# v5: rcp divisions + attention read hoisting + conv loop rewrite + removed v_cvt_pk pad nops not followed by MFMA; gate_reg pipelining dropped (no gain)
# speedup vs baseline: 1.0245x; 1.0050x over previous
; DI float sigm(float x) { return 1.f / (1.f + __expf(-x)); }
; DI u32x4 pack8(const float* f) { u32x4 o; o.x = pack2(f[0], f[1]); o.y = pack2(f[2], f[3]); o.z = pack2(f[4], f[5]); o.w = pack2(f[6], f[7]); return o; }
; DI void lds_barrier() { asm volatile("s_waitcnt lgkmcnt(0)\n\ts_barrier" ::: "memory"); }
; DI int tid512() { int t = threadIdx.x; asm volatile("" : "+v"(t)); return t; }
; template <int AI, int BJ>
; DI void stage_q(const f32x4 (&acc)[2][2][4][2], float* Cs) {
;   const int t = tid512(), wid = t >> 6, lane = t & 63, wr = wid >> 2, wc = wid & 3, fr = lane & 15, fq = lane >> 4;
;   lds_barrier();
; #pragma unroll
;   for (int m = 0; m < 4; ++m)
; #pragma unroll
;     for (int n = 0; n < 2; ++n)
; #pragma unroll
;       for (int j = 0; j < 4; ++j) Cs[(wr * 64 + m * 16 + fq * 4 + j) * CST + wc * 32 + n * 16 + fr] = acc[AI][BJ][m][n][j];
;   lds_barrier();
; }
; template <int AI, int BJ>
; DI void f3_load(PREF p, int mt, int dt, u32x4 (&g)[4]) {
;   const int t = tid512();
;   const int row0 = mt * 256 + AI * 128, col0 = dt * 256 + BJ * 128, c = (t & 15) * 8;
; #pragma unroll
;   for (int q = 0; q < 4; ++q) g[q] = *(const u32x4*)((const u16*)p.fbuf + (size_t)(row0 + (t >> 4) + 32 * q) * 1024 + col0 + c);
; }
; template <int AI, int BJ, int PASS>
; DI void f3_proc(PREF p, const f32x4 (&acc)[2][2][4][2], int mt, int dt, float* Cs, const u32x4 (&g)[4]) {
;   const int t = tid512();
;   const int row0 = mt * 256 + AI * 128, col0 = dt * 256 + BJ * 128;
;   const int c = (t & 15) * 8;
;   stage_q<AI, BJ>(acc, Cs);
; #pragma unroll
;   for (int q = 0; q < 4; ++q) {
;     int r = (t >> 4) + 32 * q;
;     float v[8]; ld8(Cs + r * CST + c, v);
;     if (PASS == 0) {
; #pragma unroll
;       for (int j = 0; j < 8; ++j) v[j] = sigm(v[j]);
;     } else {
;       float gf[8]; unpack8(g[q], gf);
; #pragma unroll
;       for (int j = 0; j < 8; ++j) v[j] *= gf[j];
;     }
;     *(u32x4*)((u16*)p.fbuf + (size_t)(row0 + r) * 1024 + col0 + c) = pack8(v);
;   }
.LBB0_36:
	s_or_b64 exec, exec, s[18:19]
	v_mov_b32_e32 v0, v168
	s_mov_b32 s18, 0x10000
	v_ashrrev_i32_e32 v102, 4, v0
	v_add_u32_e32 v102, s24, v102
	v_lshlrev_b32_e32 v0, 4, v0
	v_and_b32_e32 v0, 0xf0, v0
	v_ashrrev_i32_e32 v103, 31, v102
	v_lshl_add_u64 v[104:105], s[16:17], 0, v[0:1]
	v_lshlrev_b64 v[102:103], 11, v[102:103]
	v_lshl_add_u64 v[102:103], v[104:105], 0, v[102:103]
	v_add_co_u32_e32 v104, vcc, 0x10000, v102
	v_mov_b32_e32 v0, v168
	s_nop 0
	v_addc_co_u32_e32 v105, vcc, 0, v103, vcc
	global_load_dwordx4 v[146:149], v[102:103], off
	global_load_dwordx4 v[150:153], v[104:105], off
	v_add_co_u32_e32 v104, vcc, 0x20000, v102
	s_mov_b32 s19, 0x20000
	s_nop 0
	v_addc_co_u32_e32 v105, vcc, 0, v103, vcc
	v_add_co_u32_e32 v102, vcc, 0x30000, v102
	s_mov_b32 s20, 0x30000
	s_nop 0
	v_addc_co_u32_e32 v103, vcc, 0, v103, vcc
	global_load_dwordx4 v[154:157], v[104:105], off
	global_load_dwordx4 v[158:161], v[102:103], off
	v_mov_b32_e32 v162, v168
	v_ashrrev_i32_e32 v102, 4, v0
	v_add_u32_e32 v102, s24, v102
	v_ashrrev_i32_e32 v103, 31, v102
	v_lshlrev_b64 v[102:103], 11, v[102:103]
	v_lshlrev_b32_e32 v0, 4, v0
	v_lshl_add_u64 v[102:103], s[16:17], 0, v[102:103]
	v_and_b32_e32 v0, 0xf0, v0
	v_lshl_add_u64 v[102:103], v[102:103], 0, v[0:1]
	v_add_co_u32_e32 v104, vcc, s18, v102
	s_add_i32 s34, s34, 1
	s_nop 0
	v_addc_co_u32_e32 v105, vcc, 0, v103, vcc
	global_load_dwordx4 v[126:129], v[102:103], off offset:256
	global_load_dwordx4 v[114:117], v[104:105], off offset:256
	v_add_co_u32_e32 v104, vcc, s19, v102
	s_mov_b32 s88, 0x10000
	s_nop 0
	v_addc_co_u32_e32 v105, vcc, 0, v103, vcc
	v_add_co_u32_e32 v102, vcc, s20, v102
	s_nop 1
	v_addc_co_u32_e32 v103, vcc, 0, v103, vcc
	global_load_dwordx4 v[110:113], v[104:105], off offset:256
	s_nop 0
	global_load_dwordx4 v[102:105], v[102:103], off offset:256
	s_nop 0
	v_lshlrev_b32_e32 v0, 3, v162
	v_and_b32_e32 v166, 0x78, v0
	v_mov_b32_e32 v0, v168
	s_waitcnt lgkmcnt(0)
	s_barrier
	s_nop 0
	v_and_b32_e32 v164, 15, v0
	v_lshrrev_b32_e32 v165, 2, v0
	v_lshlrev_b32_e32 v0, 1, v0
	v_lshlrev_b32_e32 v164, 2, v164
	v_and_b32_e32 v165, 0xfffffcc, v165
	v_and_or_b32 v0, v0, s89, v164
	v_mad_u64_u32 v[164:165], s[0:1], v165, s92, v[0:1]
	v_add_u32_e32 v0, 0x400, v164
	ds_write2_b32 v164, v134, v142 offset1:16
	ds_write2_b32 v164, v135, v143 offset0:132 offset1:148
	ds_write2_b32 v0, v136, v144 offset0:8 offset1:24
	ds_write2_b32 v0, v137, v145 offset0:140 offset1:156
	v_add_u32_e32 v0, 0x2000, v164
	ds_write2_b32 v0, v130, v138 offset0:64 offset1:80
	ds_write2_b32 v0, v131, v139 offset0:196 offset1:212
	v_add_u32_e32 v0, 0x2400, v164
	ds_write2_b32 v0, v132, v140 offset0:72 offset1:88
	ds_write2_b32 v0, v133, v141 offset0:204 offset1:220
	v_add_u32_e32 v0, 0x4000, v164
	ds_write2_b32 v0, v118, v122 offset0:128 offset1:144
	v_add_u32_e32 v0, 0x4400, v164
	ds_write2_b32 v0, v119, v123 offset0:4 offset1:20
	ds_write2_b32 v0, v120, v124 offset0:136 offset1:152
	v_add_u32_e32 v0, 0x4800, v164
	ds_write2_b32 v0, v121, v125 offset0:12 offset1:28
	v_add_u32_e32 v0, 0x6000, v164
	ds_write2_b32 v0, v98, v106 offset0:192 offset1:208
	v_add_u32_e32 v0, 0x6400, v164
	ds_write2_b32 v0, v99, v107 offset0:68 offset1:84
	ds_write2_b32 v0, v100, v108 offset0:200 offset1:216
	v_add_u32_e32 v0, 0x6800, v164
	ds_write2_b32 v0, v101, v109 offset0:76 offset1:92
	v_ashrrev_i32_e32 v120, 4, v162
	v_lshlrev_b32_e32 v0, 1, v166
	v_lshl_add_u64 v[118:119], s[16:17], 0, v[0:1]
	v_mul_lo_u32 v0, v120, s92
	s_waitcnt lgkmcnt(0)
	s_barrier
	v_lshl_add_u32 v0, v166, 2, v0
	s_waitcnt vmcnt(0)
	ds_read_b128 v[98:101], v0
	ds_read_b128 v[106:109], v0 offset:16
	v_lshlrev_b32_e32 v121, 16, v146
	v_and_b32_e32 v122, 0xffff0000, v146
	v_lshlrev_b32_e32 v123, 16, v147
	v_lshlrev_b32_e32 v125, 16, v148
	v_and_b32_e32 v130, 0xffff0000, v148
	v_add_u32_e32 v120, s24, v120
	v_and_b32_e32 v124, 0xffff0000, v147
	s_waitcnt lgkmcnt(1)
	v_mul_f32_e32 v98, v98, v121
	v_mul_f32_e32 v99, v99, v122
	v_mul_f32_e32 v100, v100, v123
	s_waitcnt lgkmcnt(0)
	v_mul_f32_e32 v106, v106, v125
	v_mul_f32_e32 v107, v107, v130
	v_ashrrev_i32_e32 v121, 31, v120
	v_mul_f32_e32 v101, v101, v124
	v_cvt_pk_bf16_f32 v98, v98, v99
	v_cvt_pk_bf16_f32 v99, v100, v101
	v_cvt_pk_bf16_f32 v100, v106, v107
	v_lshlrev_b64 v[106:107], 11, v[120:121]
	v_lshlrev_b32_e32 v131, 16, v149
	v_and_b32_e32 v132, 0xffff0000, v149
	v_lshl_add_u64 v[106:107], v[118:119], 0, v[106:107]
	v_mul_f32_e32 v108, v108, v131
	v_mul_f32_e32 v109, v109, v132
	v_cvt_pk_bf16_f32 v101, v108, v109
	global_store_dwordx4 v[106:107], v[98:101], off
	ds_read_b128 v[98:101], v0 offset:16896
	ds_read_b128 v[106:109], v0 offset:16912
	v_lshlrev_b32_e32 v121, 16, v150
	v_and_b32_e32 v122, 0xffff0000, v150
	v_lshlrev_b32_e32 v123, 16, v151
	v_lshlrev_b32_e32 v125, 16, v152
	v_and_b32_e32 v124, 0xffff0000, v151
	v_and_b32_e32 v130, 0xffff0000, v152
	s_waitcnt lgkmcnt(1)
	v_mul_f32_e32 v98, v98, v121
	v_mul_f32_e32 v99, v99, v122
	v_mul_f32_e32 v100, v100, v123
	s_waitcnt lgkmcnt(0)
	v_mul_f32_e32 v106, v106, v125
	v_mul_f32_e32 v101, v101, v124
	v_mul_f32_e32 v107, v107, v130
	v_cvt_pk_bf16_f32 v98, v98, v99
	v_cvt_pk_bf16_f32 v99, v100, v101
	v_cvt_pk_bf16_f32 v100, v106, v107
	v_add_u32_e32 v106, 32, v120
	v_ashrrev_i32_e32 v107, 31, v106
	v_lshlrev_b64 v[106:107], 11, v[106:107]
	v_lshlrev_b32_e32 v131, 16, v153
	v_and_b32_e32 v132, 0xffff0000, v153
	v_lshl_add_u64 v[106:107], v[118:119], 0, v[106:107]
	v_mul_f32_e32 v108, v108, v131
	v_mul_f32_e32 v109, v109, v132
	v_cvt_pk_bf16_f32 v101, v108, v109
	global_store_dwordx4 v[106:107], v[98:101], off
	ds_read_b128 v[98:101], v0 offset:33792
	ds_read_b128 v[106:109], v0 offset:33808
	v_lshlrev_b32_e32 v121, 16, v154
	v_and_b32_e32 v122, 0xffff0000, v154
	v_lshlrev_b32_e32 v123, 16, v155
	v_lshlrev_b32_e32 v125, 16, v156
	v_and_b32_e32 v124, 0xffff0000, v155
	v_and_b32_e32 v130, 0xffff0000, v156
	s_waitcnt lgkmcnt(1)
; DI float sigm(float x) { return 1.f / (1.f + __expf(-x)); }
; DI u32x4 pack8(const float* f) { u32x4 o; o.x = pack2(f[0], f[1]); o.y = pack2(f[2], f[3]); o.z = pack2(f[4], f[5]); o.w = pack2(f[6], f[7]); return o; }
; DI int tid512() { int t = threadIdx.x; asm volatile("" : "+v"(t)); return t; }
; template <int AI, int BJ>
; DI void f3_load(PREF p, int mt, int dt, u32x4 (&g)[4]) {
;   const int t = tid512();
;   const int row0 = mt * 256 + AI * 128, col0 = dt * 256 + BJ * 128, c = (t & 15) * 8;
; #pragma unroll
;   for (int q = 0; q < 4; ++q) g[q] = *(const u32x4*)((const u16*)p.fbuf + (size_t)(row0 + (t >> 4) + 32 * q) * 1024 + col0 + c);
; }
; template <int AI, int BJ, int PASS>
; DI void f3_proc(PREF p, const f32x4 (&acc)[2][2][4][2], int mt, int dt, float* Cs, const u32x4 (&g)[4]) {
;     ...
;   for (int q = 0; q < 4; ++q) {
;     int r = (t >> 4) + 32 * q;
;     float v[8]; ld8(Cs + r * CST + c, v);
;     if (PASS == 0) {
; #pragma unroll
;       for (int j = 0; j < 8; ++j) v[j] = sigm(v[j]);
;     } else {
;       float gf[8]; unpack8(g[q], gf);
; #pragma unroll
;       for (int j = 0; j < 8; ++j) v[j] *= gf[j];
;     }
;     *(u32x4*)((u16*)p.fbuf + (size_t)(row0 + r) * 1024 + col0 + c) = pack8(v);
;   }
	v_mul_f32_e32 v98, v98, v121
	v_mul_f32_e32 v99, v99, v122
	v_mul_f32_e32 v100, v100, v123
	s_waitcnt lgkmcnt(0)
	v_mul_f32_e32 v106, v106, v125
	v_mul_f32_e32 v101, v101, v124
	v_mul_f32_e32 v107, v107, v130
	v_cvt_pk_bf16_f32 v98, v98, v99
	v_cvt_pk_bf16_f32 v99, v100, v101
	v_cvt_pk_bf16_f32 v100, v106, v107
	v_add_u32_e32 v106, 64, v120
	v_ashrrev_i32_e32 v107, 31, v106
	v_lshlrev_b64 v[106:107], 11, v[106:107]
	v_lshlrev_b32_e32 v131, 16, v157
	v_and_b32_e32 v132, 0xffff0000, v157
	v_lshl_add_u64 v[106:107], v[118:119], 0, v[106:107]
	v_mul_f32_e32 v108, v108, v131
	v_mul_f32_e32 v109, v109, v132
	v_cvt_pk_bf16_f32 v101, v108, v109
	global_store_dwordx4 v[106:107], v[98:101], off
	ds_read_b128 v[98:101], v0 offset:50688
	ds_read_b128 v[106:109], v0 offset:50704
	v_lshlrev_b32_e32 v0, 16, v158
	v_and_b32_e32 v121, 0xffff0000, v158
	v_lshlrev_b32_e32 v122, 16, v159
	v_and_b32_e32 v123, 0xffff0000, v159
	v_lshlrev_b32_e32 v124, 16, v160
	v_and_b32_e32 v125, 0xffff0000, v160
	v_lshlrev_b32_e32 v130, 16, v161
	s_waitcnt lgkmcnt(1)
	v_mul_f32_e32 v0, v98, v0
	v_mul_f32_e32 v98, v99, v121
	v_mul_f32_e32 v99, v100, v122
	v_mul_f32_e32 v100, v101, v123
	s_waitcnt lgkmcnt(0)
	v_mul_f32_e32 v101, v106, v124
	v_mul_f32_e32 v106, v107, v125
	v_and_b32_e32 v131, 0xffff0000, v161
	v_mul_f32_e32 v107, v108, v130
	v_cvt_pk_bf16_f32 v99, v99, v100
	v_cvt_pk_bf16_f32 v100, v101, v106
	v_add_u32_e32 v106, 0x60, v120
	v_mul_f32_e32 v108, v109, v131
	v_cvt_pk_bf16_f32 v101, v107, v108
	v_ashrrev_i32_e32 v107, 31, v106
	v_lshlrev_b64 v[106:107], 11, v[106:107]
	v_cvt_pk_bf16_f32 v98, v0, v98
	v_lshl_add_u64 v[106:107], v[118:119], 0, v[106:107]
	v_mov_b32_e32 v0, v168
	global_store_dwordx4 v[106:107], v[98:101], off
	v_mov_b32_e32 v132, v168
	s_nop 0
	v_ashrrev_i32_e32 v98, 4, v0
	v_add_u32_e32 v98, s25, v98
	v_lshlrev_b32_e32 v0, 4, v0
	v_and_b32_e32 v0, 0xf0, v0
	v_ashrrev_i32_e32 v99, 31, v98
	v_lshl_add_u64 v[100:101], s[16:17], 0, v[0:1]
	v_lshlrev_b64 v[98:99], 11, v[98:99]
	v_lshl_add_u64 v[98:99], v[100:101], 0, v[98:99]
	v_add_co_u32_e32 v100, vcc, s18, v98
	s_nop 1
	v_addc_co_u32_e32 v101, vcc, 0, v99, vcc
	global_load_dwordx4 v[122:125], v[98:99], off
	global_load_dwordx4 v[118:121], v[100:101], off
	v_add_co_u32_e32 v100, vcc, s19, v98
	s_nop 1
	v_addc_co_u32_e32 v101, vcc, 0, v99, vcc
	v_add_co_u32_e32 v98, vcc, s20, v98
	s_nop 1
	v_addc_co_u32_e32 v99, vcc, 0, v99, vcc
	global_load_dwordx4 v[106:109], v[100:101], off
	s_nop 0
	global_load_dwordx4 v[98:101], v[98:99], off
	s_nop 0
	v_lshlrev_b32_e32 v0, 3, v132
	v_and_b32_e32 v133, 0x78, v0
	v_mov_b32_e32 v0, v168
	s_waitcnt lgkmcnt(0)
	s_barrier
	s_nop 0
	v_and_b32_e32 v130, 15, v0
	v_lshrrev_b32_e32 v131, 2, v0
	v_lshlrev_b32_e32 v0, 1, v0
	v_lshlrev_b32_e32 v130, 2, v130
	v_and_b32_e32 v131, 0xfffffcc, v131
	v_and_or_b32 v0, v0, s89, v130
	v_mad_u64_u32 v[130:131], s[0:1], v131, s92, v[0:1]
	v_add_u32_e32 v0, 0x400, v130
	ds_write2_b32 v130, v86, v94 offset1:16
	ds_write2_b32 v130, v87, v95 offset0:132 offset1:148
	ds_write2_b32 v0, v88, v96 offset0:8 offset1:24
	ds_write2_b32 v0, v89, v97 offset0:140 offset1:156
	v_add_u32_e32 v0, 0x2000, v130
	ds_write2_b32 v0, v82, v90 offset0:64 offset1:80
	ds_write2_b32 v0, v83, v91 offset0:196 offset1:212
	v_add_u32_e32 v0, 0x2400, v130
	ds_write2_b32 v0, v84, v92 offset0:72 offset1:88
	ds_write2_b32 v0, v85, v93 offset0:204 offset1:220
	v_add_u32_e32 v0, 0x4000, v130
	ds_write2_b32 v0, v74, v78 offset0:128 offset1:144
	v_add_u32_e32 v0, 0x4400, v130
	ds_write2_b32 v0, v75, v79 offset0:4 offset1:20
	ds_write2_b32 v0, v76, v80 offset0:136 offset1:152
	v_add_u32_e32 v0, 0x4800, v130
	ds_write2_b32 v0, v77, v81 offset0:12 offset1:28
	v_add_u32_e32 v0, 0x6000, v130
	ds_write2_b32 v0, v66, v70 offset0:192 offset1:208
	v_add_u32_e32 v0, 0x6400, v130
	ds_write2_b32 v0, v67, v71 offset0:68 offset1:84
	ds_write2_b32 v0, v68, v72 offset0:200 offset1:216
	v_add_u32_e32 v0, 0x6800, v130
	ds_write2_b32 v0, v69, v73 offset0:76 offset1:92
	v_ashrrev_i32_e32 v0, 4, v132
	v_mul_lo_u32 v66, v0, s92
	s_waitcnt lgkmcnt(0)
	s_barrier
	v_lshl_add_u32 v76, v133, 2, v66
	ds_read_b128 v[66:69], v76
	ds_read_b128 v[70:73], v76 offset:16
	v_lshlrev_b32_e32 v74, 16, v126
	v_and_b32_e32 v75, 0xffff0000, v126
	v_lshlrev_b32_e32 v77, 16, v127
	v_lshlrev_b32_e32 v79, 16, v128
	v_and_b32_e32 v80, 0xffff0000, v128
	s_waitcnt lgkmcnt(1)
	v_mul_f32_e32 v66, v66, v74
	v_add_u32_e32 v74, s24, v0
	v_and_b32_e32 v78, 0xffff0000, v127
	v_mul_f32_e32 v67, v67, v75
	v_mul_f32_e32 v68, v68, v77
	s_waitcnt lgkmcnt(0)
	v_mul_f32_e32 v70, v70, v79
	v_mul_f32_e32 v71, v71, v80
	v_ashrrev_i32_e32 v75, 31, v74
	v_mul_f32_e32 v69, v69, v78
	v_cvt_pk_bf16_f32 v66, v66, v67
	v_cvt_pk_bf16_f32 v67, v68, v69
	v_cvt_pk_bf16_f32 v68, v70, v71
	v_lshlrev_b64 v[70:71], 11, v[74:75]
	v_lshl_add_u64 v[70:71], s[16:17], 0, v[70:71]
	v_lshlrev_b32_e32 v0, 1, v133
	v_lshlrev_b32_e32 v81, 16, v129
	v_and_b32_e32 v82, 0xffff0000, v129
	v_lshl_add_u64 v[70:71], v[70:71], 0, v[0:1]
	v_mul_f32_e32 v72, v72, v81
	v_mul_f32_e32 v73, v73, v82
	v_cvt_pk_bf16_f32 v69, v72, v73
	global_store_dwordx4 v[70:71], v[66:69], off offset:256
	ds_read_b128 v[66:69], v76 offset:16896
	ds_read_b128 v[70:73], v76 offset:16912
	v_lshlrev_b32_e32 v75, 16, v114
	v_and_b32_e32 v77, 0xffff0000, v114
	v_lshlrev_b32_e32 v78, 16, v115
	v_lshlrev_b32_e32 v80, 16, v116
	v_and_b32_e32 v79, 0xffff0000, v115
	v_and_b32_e32 v81, 0xffff0000, v116
	s_waitcnt lgkmcnt(1)
	v_mul_f32_e32 v66, v66, v75
	v_mul_f32_e32 v67, v67, v77
	v_mul_f32_e32 v68, v68, v78
	s_waitcnt lgkmcnt(0)
; DI float sigm(float x) { return 1.f / (1.f + __expf(-x)); }
; DI u32x4 pack8(const float* f) { u32x4 o; o.x = pack2(f[0], f[1]); o.y = pack2(f[2], f[3]); o.z = pack2(f[4], f[5]); o.w = pack2(f[6], f[7]); return o; }
; DI int tid512() { int t = threadIdx.x; asm volatile("" : "+v"(t)); return t; }
; template <int AI, int BJ>
; DI void f3_load(PREF p, int mt, int dt, u32x4 (&g)[4]) {
;   const int t = tid512();
;   const int row0 = mt * 256 + AI * 128, col0 = dt * 256 + BJ * 128, c = (t & 15) * 8;
; #pragma unroll
;   for (int q = 0; q < 4; ++q) g[q] = *(const u32x4*)((const u16*)p.fbuf + (size_t)(row0 + (t >> 4) + 32 * q) * 1024 + col0 + c);
; }
; template <int AI, int BJ, int PASS>
; DI void f3_proc(PREF p, const f32x4 (&acc)[2][2][4][2], int mt, int dt, float* Cs, const u32x4 (&g)[4]) {
;     ...
;   for (int q = 0; q < 4; ++q) {
;     int r = (t >> 4) + 32 * q;
;     float v[8]; ld8(Cs + r * CST + c, v);
;     if (PASS == 0) {
; #pragma unroll
;       for (int j = 0; j < 8; ++j) v[j] = sigm(v[j]);
;     } else {
;       float gf[8]; unpack8(g[q], gf);
; #pragma unroll
;       for (int j = 0; j < 8; ++j) v[j] *= gf[j];
;     }
;     *(u32x4*)((u16*)p.fbuf + (size_t)(row0 + r) * 1024 + col0 + c) = pack8(v);
;   }
	v_mul_f32_e32 v70, v70, v80
	v_mul_f32_e32 v69, v69, v79
	v_mul_f32_e32 v71, v71, v81
	v_cvt_pk_bf16_f32 v66, v66, v67
	v_cvt_pk_bf16_f32 v67, v68, v69
	v_cvt_pk_bf16_f32 v68, v70, v71
	v_add_u32_e32 v70, 32, v74
	v_ashrrev_i32_e32 v71, 31, v70
	v_lshlrev_b64 v[70:71], 11, v[70:71]
	v_lshl_add_u64 v[70:71], s[16:17], 0, v[70:71]
	v_lshlrev_b32_e32 v82, 16, v117
	v_and_b32_e32 v83, 0xffff0000, v117
	v_lshl_add_u64 v[70:71], v[70:71], 0, v[0:1]
	v_mul_f32_e32 v72, v72, v82
	v_mul_f32_e32 v73, v73, v83
	v_cvt_pk_bf16_f32 v69, v72, v73
	global_store_dwordx4 v[70:71], v[66:69], off offset:256
	ds_read_b128 v[66:69], v76 offset:33792
	ds_read_b128 v[70:73], v76 offset:33808
	v_lshlrev_b32_e32 v75, 16, v110
	v_and_b32_e32 v77, 0xffff0000, v110
	v_lshlrev_b32_e32 v78, 16, v111
	v_lshlrev_b32_e32 v80, 16, v112
	v_and_b32_e32 v79, 0xffff0000, v111
	v_and_b32_e32 v81, 0xffff0000, v112
	s_waitcnt lgkmcnt(1)
	v_mul_f32_e32 v66, v66, v75
	v_mul_f32_e32 v67, v67, v77
	v_mul_f32_e32 v68, v68, v78
	s_waitcnt lgkmcnt(0)
	v_mul_f32_e32 v70, v70, v80
	v_mul_f32_e32 v69, v69, v79
	v_mul_f32_e32 v71, v71, v81
	v_cvt_pk_bf16_f32 v66, v66, v67
	v_cvt_pk_bf16_f32 v67, v68, v69
	v_cvt_pk_bf16_f32 v68, v70, v71
	v_add_u32_e32 v70, 64, v74
	v_ashrrev_i32_e32 v71, 31, v70
	v_lshlrev_b64 v[70:71], 11, v[70:71]
	v_lshl_add_u64 v[70:71], s[16:17], 0, v[70:71]
	v_lshlrev_b32_e32 v82, 16, v113
	v_and_b32_e32 v83, 0xffff0000, v113
	v_lshl_add_u64 v[70:71], v[70:71], 0, v[0:1]
	v_mul_f32_e32 v72, v72, v82
	v_mul_f32_e32 v73, v73, v83
	v_cvt_pk_bf16_f32 v69, v72, v73
	global_store_dwordx4 v[70:71], v[66:69], off offset:256
	ds_read_b128 v[66:69], v76 offset:50688
	ds_read_b128 v[70:73], v76 offset:50704
	v_lshlrev_b32_e32 v75, 16, v102
	v_and_b32_e32 v76, 0xffff0000, v102
	v_lshlrev_b32_e32 v77, 16, v103
	v_lshlrev_b32_e32 v79, 16, v104
	v_and_b32_e32 v78, 0xffff0000, v103
	v_and_b32_e32 v80, 0xffff0000, v104
	s_waitcnt lgkmcnt(1)
	v_mul_f32_e32 v66, v66, v75
	v_mul_f32_e32 v67, v67, v76
	v_mul_f32_e32 v68, v68, v77
	s_waitcnt lgkmcnt(0)
	v_mul_f32_e32 v70, v70, v79
	v_mul_f32_e32 v69, v69, v78
	v_mul_f32_e32 v71, v71, v80
	v_cvt_pk_bf16_f32 v66, v66, v67
	v_cvt_pk_bf16_f32 v67, v68, v69
	v_cvt_pk_bf16_f32 v68, v70, v71
	v_add_u32_e32 v70, 0x60, v74
	v_ashrrev_i32_e32 v71, 31, v70
	v_lshlrev_b64 v[70:71], 11, v[70:71]
	v_lshl_add_u64 v[70:71], s[16:17], 0, v[70:71]
	v_lshlrev_b32_e32 v81, 16, v105
	v_and_b32_e32 v82, 0xffff0000, v105
	v_lshl_add_u64 v[70:71], v[70:71], 0, v[0:1]
	v_mov_b32_e32 v0, v168
	v_mul_f32_e32 v72, v72, v81
	v_mul_f32_e32 v73, v73, v82
	v_cvt_pk_bf16_f32 v69, v72, v73
	global_store_dwordx4 v[70:71], v[66:69], off offset:256
	v_mov_b32_e32 v84, v168
	s_nop 0
	v_ashrrev_i32_e32 v66, 4, v0
	v_add_u32_e32 v66, s25, v66
	v_ashrrev_i32_e32 v67, 31, v66
	v_lshlrev_b64 v[66:67], 11, v[66:67]
	v_lshlrev_b32_e32 v0, 4, v0
	v_lshl_add_u64 v[66:67], s[16:17], 0, v[66:67]
	v_and_b32_e32 v0, 0xf0, v0
	v_lshl_add_u64 v[66:67], v[66:67], 0, v[0:1]
	v_add_co_u32_e32 v68, vcc, s18, v66
	s_nop 1
	v_addc_co_u32_e32 v69, vcc, 0, v67, vcc
	global_load_dwordx4 v[78:81], v[66:67], off offset:256
	global_load_dwordx4 v[74:77], v[68:69], off offset:256
	v_add_co_u32_e32 v68, vcc, s19, v66
	s_nop 1
	v_addc_co_u32_e32 v69, vcc, 0, v67, vcc
	v_add_co_u32_e32 v66, vcc, s20, v66
	s_nop 1
	v_addc_co_u32_e32 v67, vcc, 0, v67, vcc
	global_load_dwordx4 v[70:73], v[68:69], off offset:256
	s_nop 0
	global_load_dwordx4 v[66:69], v[66:67], off offset:256
	s_nop 0
	v_lshlrev_b32_e32 v0, 3, v84
	v_and_b32_e32 v85, 0x78, v0
	v_mov_b32_e32 v0, v168
	s_waitcnt lgkmcnt(0)
	s_barrier
	s_nop 0
	v_and_b32_e32 v82, 15, v0
	v_lshrrev_b32_e32 v83, 2, v0
	v_lshlrev_b32_e32 v0, 1, v0
	v_lshlrev_b32_e32 v82, 2, v82
	v_and_b32_e32 v83, 0xfffffcc, v83
	v_and_or_b32 v0, v0, s89, v82
	v_mad_u64_u32 v[82:83], s[0:1], v83, s92, v[0:1]
	v_add_u32_e32 v0, 0x400, v82
	ds_write2_b32 v82, v54, v62 offset1:16
	ds_write2_b32 v82, v55, v63 offset0:132 offset1:148
	ds_write2_b32 v0, v56, v64 offset0:8 offset1:24
	ds_write2_b32 v0, v57, v65 offset0:140 offset1:156
	v_add_u32_e32 v0, 0x2000, v82
	ds_write2_b32 v0, v50, v58 offset0:64 offset1:80
	ds_write2_b32 v0, v51, v59 offset0:196 offset1:212
	v_add_u32_e32 v0, 0x2400, v82
	ds_write2_b32 v0, v52, v60 offset0:72 offset1:88
	ds_write2_b32 v0, v53, v61 offset0:204 offset1:220
	v_add_u32_e32 v0, 0x4000, v82
	ds_write2_b32 v0, v42, v46 offset0:128 offset1:144
	v_add_u32_e32 v0, 0x4400, v82
	ds_write2_b32 v0, v43, v47 offset0:4 offset1:20
	ds_write2_b32 v0, v44, v48 offset0:136 offset1:152
	v_add_u32_e32 v0, 0x4800, v82
	ds_write2_b32 v0, v45, v49 offset0:12 offset1:28
	v_add_u32_e32 v0, 0x6000, v82
	ds_write2_b32 v0, v34, v38 offset0:192 offset1:208
	v_add_u32_e32 v0, 0x6400, v82
	ds_write2_b32 v0, v35, v39 offset0:68 offset1:84
	ds_write2_b32 v0, v36, v40 offset0:200 offset1:216
	v_add_u32_e32 v0, 0x6800, v82
	ds_write2_b32 v0, v37, v41 offset0:76 offset1:92
	v_ashrrev_i32_e32 v44, 4, v84
	v_lshlrev_b32_e32 v0, 1, v85
	v_lshl_add_u64 v[42:43], s[16:17], 0, v[0:1]
	v_mul_lo_u32 v0, v44, s92
	s_waitcnt lgkmcnt(0)
	s_barrier
; DI float sigm(float x) { return 1.f / (1.f + __expf(-x)); }
; DI u32x4 pack8(const float* f) { u32x4 o; o.x = pack2(f[0], f[1]); o.y = pack2(f[2], f[3]); o.z = pack2(f[4], f[5]); o.w = pack2(f[6], f[7]); return o; }
; DI int tid512() { int t = threadIdx.x; asm volatile("" : "+v"(t)); return t; }
; template <int AI, int BJ>
; DI void f3_load(PREF p, int mt, int dt, u32x4 (&g)[4]) {
;   const int t = tid512();
;   const int row0 = mt * 256 + AI * 128, col0 = dt * 256 + BJ * 128, c = (t & 15) * 8;
; #pragma unroll
;   for (int q = 0; q < 4; ++q) g[q] = *(const u32x4*)((const u16*)p.fbuf + (size_t)(row0 + (t >> 4) + 32 * q) * 1024 + col0 + c);
; }
; template <int AI, int BJ, int PASS>
; DI void f3_proc(PREF p, const f32x4 (&acc)[2][2][4][2], int mt, int dt, float* Cs, const u32x4 (&g)[4]) {
;     ...
;   for (int q = 0; q < 4; ++q) {
;     int r = (t >> 4) + 32 * q;
;     float v[8]; ld8(Cs + r * CST + c, v);
;     if (PASS == 0) {
; #pragma unroll
;       for (int j = 0; j < 8; ++j) v[j] = sigm(v[j]);
;     } else {
;       float gf[8]; unpack8(g[q], gf);
; #pragma unroll
;       for (int j = 0; j < 8; ++j) v[j] *= gf[j];
;     }
;     *(u32x4*)((u16*)p.fbuf + (size_t)(row0 + r) * 1024 + col0 + c) = pack8(v);
;   }
	v_lshl_add_u32 v0, v85, 2, v0
	ds_read_b128 v[34:37], v0
	ds_read_b128 v[38:41], v0 offset:16
	s_waitcnt vmcnt(11)
	v_lshlrev_b32_e32 v45, 16, v122
	v_and_b32_e32 v46, 0xffff0000, v122
	v_lshlrev_b32_e32 v47, 16, v123
	v_lshlrev_b32_e32 v49, 16, v124
	v_and_b32_e32 v50, 0xffff0000, v124
	v_add_u32_e32 v44, s25, v44
	v_and_b32_e32 v48, 0xffff0000, v123
	s_waitcnt lgkmcnt(1)
	v_mul_f32_e32 v34, v34, v45
	v_mul_f32_e32 v35, v35, v46
	v_mul_f32_e32 v36, v36, v47
	s_waitcnt lgkmcnt(0)
	v_mul_f32_e32 v38, v38, v49
	v_mul_f32_e32 v39, v39, v50
	v_ashrrev_i32_e32 v45, 31, v44
	v_mul_f32_e32 v37, v37, v48
	v_cvt_pk_bf16_f32 v34, v34, v35
	v_cvt_pk_bf16_f32 v35, v36, v37
	v_cvt_pk_bf16_f32 v36, v38, v39
	v_lshlrev_b64 v[38:39], 11, v[44:45]
	v_lshlrev_b32_e32 v51, 16, v125
	v_and_b32_e32 v52, 0xffff0000, v125
	v_lshl_add_u64 v[38:39], v[42:43], 0, v[38:39]
	v_mul_f32_e32 v40, v40, v51
	v_mul_f32_e32 v41, v41, v52
	v_cvt_pk_bf16_f32 v37, v40, v41
	global_store_dwordx4 v[38:39], v[34:37], off
	ds_read_b128 v[34:37], v0 offset:16896
	ds_read_b128 v[38:41], v0 offset:16912
	s_waitcnt vmcnt(11)
	v_lshlrev_b32_e32 v45, 16, v118
	v_and_b32_e32 v46, 0xffff0000, v118
	v_lshlrev_b32_e32 v47, 16, v119
	v_lshlrev_b32_e32 v49, 16, v120
	v_and_b32_e32 v48, 0xffff0000, v119
	v_and_b32_e32 v50, 0xffff0000, v120
	s_waitcnt lgkmcnt(1)
	v_mul_f32_e32 v34, v34, v45
	v_mul_f32_e32 v35, v35, v46
	v_mul_f32_e32 v36, v36, v47
	s_waitcnt lgkmcnt(0)
	v_mul_f32_e32 v38, v38, v49
	v_mul_f32_e32 v37, v37, v48
	v_mul_f32_e32 v39, v39, v50
	v_cvt_pk_bf16_f32 v34, v34, v35
	v_cvt_pk_bf16_f32 v35, v36, v37
	v_cvt_pk_bf16_f32 v36, v38, v39
	v_add_u32_e32 v38, 32, v44
	v_ashrrev_i32_e32 v39, 31, v38
	v_lshlrev_b64 v[38:39], 11, v[38:39]
	v_lshlrev_b32_e32 v51, 16, v121
	v_and_b32_e32 v52, 0xffff0000, v121
	v_lshl_add_u64 v[38:39], v[42:43], 0, v[38:39]
	v_mul_f32_e32 v40, v40, v51
	v_mul_f32_e32 v41, v41, v52
	v_cvt_pk_bf16_f32 v37, v40, v41
	global_store_dwordx4 v[38:39], v[34:37], off
	ds_read_b128 v[34:37], v0 offset:33792
	ds_read_b128 v[38:41], v0 offset:33808
	s_waitcnt vmcnt(11)
	v_lshlrev_b32_e32 v45, 16, v106
	v_and_b32_e32 v46, 0xffff0000, v106
	v_lshlrev_b32_e32 v47, 16, v107
	v_lshlrev_b32_e32 v49, 16, v108
	v_and_b32_e32 v48, 0xffff0000, v107
	v_and_b32_e32 v50, 0xffff0000, v108
	s_waitcnt lgkmcnt(1)
	v_mul_f32_e32 v34, v34, v45
	v_mul_f32_e32 v35, v35, v46
	v_mul_f32_e32 v36, v36, v47
	s_waitcnt lgkmcnt(0)
	v_mul_f32_e32 v38, v38, v49
	v_mul_f32_e32 v37, v37, v48
	v_mul_f32_e32 v39, v39, v50
	v_cvt_pk_bf16_f32 v34, v34, v35
	v_cvt_pk_bf16_f32 v35, v36, v37
	v_cvt_pk_bf16_f32 v36, v38, v39
	v_add_u32_e32 v38, 64, v44
	v_ashrrev_i32_e32 v39, 31, v38
	v_lshlrev_b64 v[38:39], 11, v[38:39]
	v_lshlrev_b32_e32 v51, 16, v109
	v_and_b32_e32 v52, 0xffff0000, v109
	v_lshl_add_u64 v[38:39], v[42:43], 0, v[38:39]
	v_mul_f32_e32 v40, v40, v51
	v_mul_f32_e32 v41, v41, v52
	v_cvt_pk_bf16_f32 v37, v40, v41
	global_store_dwordx4 v[38:39], v[34:37], off
	ds_read_b128 v[34:37], v0 offset:50688
	ds_read_b128 v[38:41], v0 offset:50704
	s_waitcnt vmcnt(11)
	v_lshlrev_b32_e32 v0, 16, v98
	v_and_b32_e32 v45, 0xffff0000, v98
	v_lshlrev_b32_e32 v46, 16, v99
	v_and_b32_e32 v47, 0xffff0000, v99
	v_lshlrev_b32_e32 v48, 16, v100
	v_and_b32_e32 v49, 0xffff0000, v100
	v_lshlrev_b32_e32 v50, 16, v101
	s_waitcnt lgkmcnt(1)
	v_mul_f32_e32 v0, v34, v0
	v_mul_f32_e32 v34, v35, v45
	v_mul_f32_e32 v35, v36, v46
	v_mul_f32_e32 v36, v37, v47
	s_waitcnt lgkmcnt(0)
	v_mul_f32_e32 v37, v38, v48
	v_mul_f32_e32 v38, v39, v49
	v_and_b32_e32 v51, 0xffff0000, v101
	v_mul_f32_e32 v39, v40, v50
	v_cvt_pk_bf16_f32 v35, v35, v36
	v_cvt_pk_bf16_f32 v36, v37, v38
	v_add_u32_e32 v38, 0x60, v44
	v_mul_f32_e32 v40, v41, v51
	v_cvt_pk_bf16_f32 v37, v39, v40
	v_ashrrev_i32_e32 v39, 31, v38
	v_lshlrev_b64 v[38:39], 11, v[38:39]
	v_lshl_add_u64 v[38:39], v[42:43], 0, v[38:39]
	v_cvt_pk_bf16_f32 v34, v0, v34
	global_store_dwordx4 v[38:39], v[34:37], off
	s_nop 1
	v_mov_b32_e32 v36, v168
	s_nop 0
	v_lshlrev_b32_e32 v0, 3, v36
	v_and_b32_e32 v37, 0x78, v0
	v_mov_b32_e32 v0, v168
	s_waitcnt lgkmcnt(0)
	s_barrier
; DI float sigm(float x) { return 1.f / (1.f + __expf(-x)); }
; DI u32x4 pack8(const float* f) { u32x4 o; o.x = pack2(f[0], f[1]); o.y = pack2(f[2], f[3]); o.z = pack2(f[4], f[5]); o.w = pack2(f[6], f[7]); return o; }
; template <int AI, int BJ, int PASS>
; DI void f3_proc(PREF p, const f32x4 (&acc)[2][2][4][2], int mt, int dt, float* Cs, const u32x4 (&g)[4]) {
;     ...
;   stage_q<AI, BJ>(acc, Cs);
; #pragma unroll
;   for (int q = 0; q < 4; ++q) {
;     int r = (t >> 4) + 32 * q;
;     float v[8]; ld8(Cs + r * CST + c, v);
;     if (PASS == 0) {
; #pragma unroll
;       for (int j = 0; j < 8; ++j) v[j] = sigm(v[j]);
;     } else {
;       float gf[8]; unpack8(g[q], gf);
; #pragma unroll
;       for (int j = 0; j < 8; ++j) v[j] *= gf[j];
;     }
;     *(u32x4*)((u16*)p.fbuf + (size_t)(row0 + r) * 1024 + col0 + c) = pack8(v);
;   }
; DI void f3_phase(PREF p, int l, unsigned char* lds_all) {
;     ...
;   for (int k = 0;; ++k) {
;     int mt, dt;
;     if (!xcd_tile256(k, 4, mt, dt)) break;
	s_nop 0
	v_and_b32_e32 v34, 15, v0
	v_lshrrev_b32_e32 v35, 2, v0
	v_lshlrev_b32_e32 v0, 1, v0
	v_lshlrev_b32_e32 v34, 2, v34
	v_and_b32_e32 v35, 0xfffffcc, v35
	v_and_or_b32 v0, v0, s89, v34
	v_mad_u64_u32 v[34:35], s[0:1], v35, s92, v[0:1]
	v_add_u32_e32 v0, 0x400, v34
	ds_write2_b32 v34, v22, v30 offset1:16
	ds_write2_b32 v34, v23, v31 offset0:132 offset1:148
	ds_write2_b32 v0, v24, v32 offset0:8 offset1:24
	ds_write2_b32 v0, v25, v33 offset0:140 offset1:156
	v_add_u32_e32 v0, 0x2000, v34
	ds_write2_b32 v0, v18, v26 offset0:64 offset1:80
	ds_write2_b32 v0, v19, v27 offset0:196 offset1:212
	v_add_u32_e32 v0, 0x2400, v34
	ds_write2_b32 v0, v20, v28 offset0:72 offset1:88
	ds_write2_b32 v0, v21, v29 offset0:204 offset1:220
	v_add_u32_e32 v0, 0x4000, v34
	ds_write2_b32 v0, v10, v14 offset0:128 offset1:144
	v_add_u32_e32 v0, 0x4400, v34
	ds_write2_b32 v0, v11, v15 offset0:4 offset1:20
	ds_write2_b32 v0, v12, v16 offset0:136 offset1:152
	v_add_u32_e32 v0, 0x4800, v34
	ds_write2_b32 v0, v13, v17 offset0:12 offset1:28
	v_add_u32_e32 v0, 0x6000, v34
	ds_write2_b32 v0, v2, v6 offset0:192 offset1:208
	v_add_u32_e32 v0, 0x6400, v34
	ds_write2_b32 v0, v3, v7 offset0:68 offset1:84
	ds_write2_b32 v0, v4, v8 offset0:200 offset1:216
	v_add_u32_e32 v0, 0x6800, v34
	ds_write2_b32 v0, v5, v9 offset0:76 offset1:92
	v_ashrrev_i32_e32 v0, 4, v36
	v_mul_lo_u32 v2, v0, s92
	s_waitcnt lgkmcnt(0)
	s_barrier
	v_lshl_add_u32 v12, v37, 2, v2
	ds_read_b128 v[2:5], v12
	ds_read_b128 v[6:9], v12 offset:16
	s_waitcnt vmcnt(7)
	v_lshlrev_b32_e32 v10, 16, v78
	v_and_b32_e32 v11, 0xffff0000, v78
	v_lshlrev_b32_e32 v13, 16, v79
	v_lshlrev_b32_e32 v15, 16, v80
	v_and_b32_e32 v16, 0xffff0000, v80
	s_waitcnt lgkmcnt(1)
	v_mul_f32_e32 v2, v2, v10
	v_add_u32_e32 v10, s25, v0
	v_and_b32_e32 v14, 0xffff0000, v79
	v_mul_f32_e32 v3, v3, v11
	v_mul_f32_e32 v4, v4, v13
	s_waitcnt lgkmcnt(0)
	v_mul_f32_e32 v6, v6, v15
	v_mul_f32_e32 v7, v7, v16
	v_ashrrev_i32_e32 v11, 31, v10
	v_mul_f32_e32 v5, v5, v14
	v_cvt_pk_bf16_f32 v2, v2, v3
	v_cvt_pk_bf16_f32 v3, v4, v5
	v_cvt_pk_bf16_f32 v4, v6, v7
	v_lshlrev_b64 v[6:7], 11, v[10:11]
	v_lshl_add_u64 v[6:7], s[16:17], 0, v[6:7]
	v_lshlrev_b32_e32 v0, 1, v37
	v_lshlrev_b32_e32 v17, 16, v81
	v_and_b32_e32 v18, 0xffff0000, v81
	v_lshl_add_u64 v[6:7], v[6:7], 0, v[0:1]
	v_mul_f32_e32 v8, v8, v17
	v_mul_f32_e32 v9, v9, v18
	v_cvt_pk_bf16_f32 v5, v8, v9
	global_store_dwordx4 v[6:7], v[2:5], off offset:256
	ds_read_b128 v[2:5], v12 offset:16896
	ds_read_b128 v[6:9], v12 offset:16912
	s_waitcnt vmcnt(7)
	v_lshlrev_b32_e32 v11, 16, v74
	v_and_b32_e32 v13, 0xffff0000, v74
	v_lshlrev_b32_e32 v14, 16, v75
	v_lshlrev_b32_e32 v16, 16, v76
	v_and_b32_e32 v15, 0xffff0000, v75
	v_and_b32_e32 v17, 0xffff0000, v76
	s_waitcnt lgkmcnt(1)
	v_mul_f32_e32 v2, v2, v11
	v_mul_f32_e32 v3, v3, v13
	v_mul_f32_e32 v4, v4, v14
	s_waitcnt lgkmcnt(0)
	v_mul_f32_e32 v6, v6, v16
	v_mul_f32_e32 v5, v5, v15
	v_mul_f32_e32 v7, v7, v17
	v_cvt_pk_bf16_f32 v2, v2, v3
	v_cvt_pk_bf16_f32 v3, v4, v5
	v_cvt_pk_bf16_f32 v4, v6, v7
	v_add_u32_e32 v6, 32, v10
	v_ashrrev_i32_e32 v7, 31, v6
	v_lshlrev_b64 v[6:7], 11, v[6:7]
	v_lshl_add_u64 v[6:7], s[16:17], 0, v[6:7]
	v_lshlrev_b32_e32 v18, 16, v77
	v_and_b32_e32 v19, 0xffff0000, v77
	v_lshl_add_u64 v[6:7], v[6:7], 0, v[0:1]
	v_mul_f32_e32 v8, v8, v18
	v_mul_f32_e32 v9, v9, v19
	v_cvt_pk_bf16_f32 v5, v8, v9
	global_store_dwordx4 v[6:7], v[2:5], off offset:256
	ds_read_b128 v[2:5], v12 offset:33792
	ds_read_b128 v[6:9], v12 offset:33808
	s_waitcnt vmcnt(7)
	v_lshlrev_b32_e32 v11, 16, v70
	v_and_b32_e32 v13, 0xffff0000, v70
	v_lshlrev_b32_e32 v14, 16, v71
	v_lshlrev_b32_e32 v16, 16, v72
	v_and_b32_e32 v15, 0xffff0000, v71
	v_and_b32_e32 v17, 0xffff0000, v72
	s_waitcnt lgkmcnt(1)
	v_mul_f32_e32 v2, v2, v11
	v_mul_f32_e32 v3, v3, v13
	v_mul_f32_e32 v4, v4, v14
	s_waitcnt lgkmcnt(0)
	v_mul_f32_e32 v6, v6, v16
	v_mul_f32_e32 v5, v5, v15
	v_mul_f32_e32 v7, v7, v17
	v_cvt_pk_bf16_f32 v2, v2, v3
	v_cvt_pk_bf16_f32 v3, v4, v5
	v_cvt_pk_bf16_f32 v4, v6, v7
	v_add_u32_e32 v6, 64, v10
	v_ashrrev_i32_e32 v7, 31, v6
	v_lshlrev_b64 v[6:7], 11, v[6:7]
	v_lshl_add_u64 v[6:7], s[16:17], 0, v[6:7]
	v_lshlrev_b32_e32 v18, 16, v73
	v_and_b32_e32 v19, 0xffff0000, v73
	v_lshl_add_u64 v[6:7], v[6:7], 0, v[0:1]
	v_mul_f32_e32 v8, v8, v18
	v_mul_f32_e32 v9, v9, v19
	v_cvt_pk_bf16_f32 v5, v8, v9
	global_store_dwordx4 v[6:7], v[2:5], off offset:256
	ds_read_b128 v[2:5], v12 offset:50688
	ds_read_b128 v[6:9], v12 offset:50704
	s_waitcnt vmcnt(7)
	v_lshlrev_b32_e32 v11, 16, v66
	v_and_b32_e32 v12, 0xffff0000, v66
	v_lshlrev_b32_e32 v13, 16, v67
	v_lshlrev_b32_e32 v15, 16, v68
	v_and_b32_e32 v14, 0xffff0000, v67
	v_and_b32_e32 v16, 0xffff0000, v68
	s_waitcnt lgkmcnt(1)
	v_mul_f32_e32 v2, v2, v11
	v_mul_f32_e32 v3, v3, v12
	v_mul_f32_e32 v4, v4, v13
	s_waitcnt lgkmcnt(0)
	v_mul_f32_e32 v6, v6, v15
	v_mul_f32_e32 v5, v5, v14
	v_mul_f32_e32 v7, v7, v16
	v_cvt_pk_bf16_f32 v2, v2, v3
	v_cvt_pk_bf16_f32 v3, v4, v5
	v_cvt_pk_bf16_f32 v4, v6, v7
	v_add_u32_e32 v6, 0x60, v10
	v_ashrrev_i32_e32 v7, 31, v6
	v_lshlrev_b64 v[6:7], 11, v[6:7]
	s_mul_i32 s0, s34, s45
	v_lshl_add_u64 v[6:7], s[16:17], 0, v[6:7]
	s_add_i32 s16, s0, s46
	v_lshlrev_b32_e32 v17, 16, v69
	v_and_b32_e32 v18, 0xffff0000, v69
	v_lshl_add_u64 v[6:7], v[6:7], 0, v[0:1]
	s_cmp_lt_u32 s16, 64
	v_mul_f32_e32 v8, v8, v17
	v_mul_f32_e32 v9, v9, v18
	v_cvt_pk_bf16_f32 v5, v8, v9
	global_store_dwordx4 v[6:7], v[2:5], off offset:256
	s_cbranch_scc0 .LBB0_50

; DI float sigm(float x) { return 1.f / (1.f + __expf(-x)); }
; DI u32x4 pack8(const float* f) { u32x4 o; o.x = pack2(f[0], f[1]); o.y = pack2(f[2], f[3]); o.z = pack2(f[4], f[5]); o.w = pack2(f[6], f[7]); return o; }
; template <int AI, int BJ, int PASS>
; DI void f3_proc(PREF p, const f32x4 (&acc)[2][2][4][2], int mt, int dt, float* Cs, const u32x4 (&g)[4]) {
;     ...
;   stage_q<AI, BJ>(acc, Cs);
; #pragma unroll
;   for (int q = 0; q < 4; ++q) {
;     int r = (t >> 4) + 32 * q;
;     float v[8]; ld8(Cs + r * CST + c, v);
;     if (PASS == 0) {
; #pragma unroll
;       for (int j = 0; j < 8; ++j) v[j] = sigm(v[j]);
;     } else {
;       float gf[8]; unpack8(g[q], gf);
; #pragma unroll
;       for (int j = 0; j < 8; ++j) v[j] *= gf[j];
;     }
;     *(u32x4*)((u16*)p.fbuf + (size_t)(row0 + r) * 1024 + col0 + c) = pack8(v);
;   }
; DI void f3_phase(PREF p, int l, unsigned char* lds_all) {
;     ...
;       f32x4 acc[2][2][4][2]; zero_acc256(acc);
;       gemm256<1024, 1024, 1024>(acc, p.X + (size_t)mt * 256 * 1024, W + O_PLEG + (size_t)dt * 256 * 1024, shm, p);
;       u32x4 gd[4];
;       f3_proc<0, 0, 0>(p, acc, mt, dt, Cs, gd); f3_proc<0, 1, 0>(p, acc, mt, dt, Cs, gd);
;       f3_proc<1, 0, 0>(p, acc, mt, dt, Cs, gd); f3_proc<1, 1, 0>(p, acc, mt, dt, Cs, gd);
.LBB0_43:
	s_or_b64 exec, exec, s[16:17]
	v_mov_b32_e32 v132, v168
	s_lshl_b32 s24, s35, 8
	v_lshlrev_b32_e32 v0, 3, v132
	v_and_b32_e32 v133, 0x78, v0
	v_mov_b32_e32 v0, v168
	s_waitcnt lgkmcnt(0)
	s_barrier
	s_nop 0
	v_and_b32_e32 v130, 15, v0
	v_lshrrev_b32_e32 v131, 2, v0
	v_lshlrev_b32_e32 v0, 1, v0
	v_lshlrev_b32_e32 v130, 2, v130
	v_and_b32_e32 v131, 0xfffffcc, v131
	v_and_or_b32 v0, v0, s89, v130
	v_mad_u64_u32 v[130:131], s[0:1], v131, s92, v[0:1]
	v_add_u32_e32 v0, 0x400, v130
	ds_write2_b32 v130, v118, v126 offset1:16
	ds_write2_b32 v130, v119, v127 offset0:132 offset1:148
	ds_write2_b32 v0, v120, v128 offset0:8 offset1:24
	ds_write2_b32 v0, v121, v129 offset0:140 offset1:156
	v_add_u32_e32 v0, 0x2000, v130
	ds_write2_b32 v0, v114, v122 offset0:64 offset1:80
	ds_write2_b32 v0, v115, v123 offset0:196 offset1:212
	v_add_u32_e32 v0, 0x2400, v130
	ds_write2_b32 v0, v116, v124 offset0:72 offset1:88
	ds_write2_b32 v0, v117, v125 offset0:204 offset1:220
	v_add_u32_e32 v0, 0x4000, v130
	ds_write2_b32 v0, v106, v110 offset0:128 offset1:144
	v_add_u32_e32 v0, 0x4400, v130
	ds_write2_b32 v0, v107, v111 offset0:4 offset1:20
	ds_write2_b32 v0, v108, v112 offset0:136 offset1:152
	v_add_u32_e32 v0, 0x4800, v130
	ds_write2_b32 v0, v109, v113 offset0:12 offset1:28
	v_add_u32_e32 v0, 0x6000, v130
	ds_write2_b32 v0, v98, v102 offset0:192 offset1:208
	v_add_u32_e32 v0, 0x6400, v130
	ds_write2_b32 v0, v99, v103 offset0:68 offset1:84
	ds_write2_b32 v0, v100, v104 offset0:200 offset1:216
	v_add_u32_e32 v0, 0x6800, v130
	v_ashrrev_i32_e32 v100, 4, v132
	ds_write2_b32 v0, v101, v105 offset0:76 offset1:92
	v_mul_lo_u32 v0, v100, s92
	s_waitcnt lgkmcnt(0)
	s_barrier
	v_lshl_add_u32 v102, v133, 2, v0
	s_waitcnt vmcnt(0)
	ds_read_b128 v[104:107], v102
	ds_read_b128 v[108:111], v102 offset:16
	s_lshl_b32 s0, s18, 8
	s_ashr_i32 s1, s0, 31
	s_lshl_b64 s[0:1], s[0:1], 1
	s_waitcnt lgkmcnt(1)
	v_mul_f32_e32 v0, 0xbfb8aa3b, v104
	v_exp_f32_e32 v0, v0
	s_add_u32 s16, s14, s0
	s_addc_u32 s17, s15, s1
	v_mul_f32_e32 v105, 0xbfb8aa3b, v105
	v_add_f32_e32 v101, 1.0, v0
	v_lshlrev_b32_e32 v0, 1, v133
	v_lshl_add_u64 v[98:99], s[16:17], 0, v[0:1]
	v_exp_f32_e32 v105, v105
	s_nop 0
	v_add_f32_e32 v103, 1.0, v105
	v_rcp_f32_e32 v0, v101
	v_mul_f32_e32 v106, 0xbfb8aa3b, v106
	v_exp_f32_e32 v106, v106
	s_nop 0
	v_add_f32_e32 v105, 1.0, v106
	v_rcp_f32_e32 v101, v103
	v_mul_f32_e32 v107, 0xbfb8aa3b, v107
	v_exp_f32_e32 v107, v107
	s_nop 0
	v_add_f32_e32 v106, 1.0, v107
	s_waitcnt lgkmcnt(0)
	v_mul_f32_e32 v108, 0xbfb8aa3b, v108
	v_exp_f32_e32 v108, v108
	v_rcp_f32_e32 v103, v105
	v_add_f32_e32 v107, 1.0, v108
	v_rcp_f32_e32 v113, v106
	v_mul_f32_e32 v106, 0xbfb8aa3b, v109
	v_exp_f32_e32 v106, v106
	s_nop 0
	v_add_f32_e32 v106, 1.0, v106
	v_rcp_f32_e32 v112, v107
	v_mul_f32_e32 v107, 0xbfb8aa3b, v110
	v_exp_f32_e32 v107, v107
	s_nop 0
	v_add_f32_e32 v107, 1.0, v107
	v_rcp_f32_e32 v114, v106
	v_mul_f32_e32 v106, 0xbfb8aa3b, v111
	v_exp_f32_e32 v106, v106
	s_nop 0
	v_add_f32_e32 v106, 1.0, v106
	v_rcp_f32_e32 v111, v107
	v_cvt_pk_bf16_f32 v110, v112, v114
	v_rcp_f32_e32 v116, v106
	ds_read_b128 v[104:107], v102 offset:16896
	v_cvt_pk_bf16_f32 v108, v0, v101
	v_cvt_pk_bf16_f32 v109, v103, v113
	ds_read_b128 v[112:115], v102 offset:16912
	v_add_u32_e32 v100, s24, v100
	s_waitcnt lgkmcnt(1)
	v_mul_f32_e32 v0, 0xbfb8aa3b, v104
	v_exp_f32_e32 v0, v0
	v_ashrrev_i32_e32 v101, 31, v100
	v_cvt_pk_bf16_f32 v111, v111, v116
	v_lshlrev_b64 v[116:117], 11, v[100:101]
	v_add_f32_e32 v0, 1.0, v0
	v_mul_f32_e32 v105, 0xbfb8aa3b, v105
	v_lshl_add_u64 v[116:117], v[98:99], 0, v[116:117]
	v_exp_f32_e32 v105, v105
	global_store_dwordx4 v[116:117], v[108:111], off
	v_mul_f32_e32 v106, 0xbfb8aa3b, v106
	v_exp_f32_e32 v106, v106
	v_add_f32_e32 v103, 1.0, v105
	v_rcp_f32_e32 v0, v0
	v_mul_f32_e32 v107, 0xbfb8aa3b, v107
	v_add_f32_e32 v105, 1.0, v106
	v_rcp_f32_e32 v101, v103
	v_exp_f32_e32 v107, v107
	s_nop 0
	v_add_f32_e32 v106, 1.0, v107
	s_waitcnt lgkmcnt(0)
	v_mul_f32_e32 v108, 0xbfb8aa3b, v112
	v_exp_f32_e32 v108, v108
	v_rcp_f32_e32 v103, v105
	v_add_f32_e32 v107, 1.0, v108
	v_rcp_f32_e32 v109, v106
	v_mul_f32_e32 v106, 0xbfb8aa3b, v113
	v_exp_f32_e32 v106, v106
	s_nop 0
	v_add_f32_e32 v106, 1.0, v106
	v_rcp_f32_e32 v110, v107
	v_mul_f32_e32 v107, 0xbfb8aa3b, v114
	v_exp_f32_e32 v107, v107
	s_nop 0
	v_add_f32_e32 v107, 1.0, v107
	v_rcp_f32_e32 v111, v106
	v_mul_f32_e32 v106, 0xbfb8aa3b, v115
	v_exp_f32_e32 v106, v106
	s_nop 0
	v_add_f32_e32 v106, 1.0, v106
	v_rcp_f32_e32 v116, v107
	v_cvt_pk_bf16_f32 v109, v103, v109
	v_rcp_f32_e32 v117, v106
	ds_read_b128 v[104:107], v102 offset:33792
	ds_read_b128 v[112:115], v102 offset:33808
	v_cvt_pk_bf16_f32 v108, v0, v101
	v_cvt_pk_bf16_f32 v110, v110, v111
	v_cvt_pk_bf16_f32 v111, v116, v117
	s_waitcnt lgkmcnt(1)
	v_mul_f32_e32 v0, 0xbfb8aa3b, v104
	v_exp_f32_e32 v0, v0
	v_add_u32_e32 v116, 32, v100
	v_ashrrev_i32_e32 v117, 31, v116
	v_lshlrev_b64 v[116:117], 11, v[116:117]
	v_add_f32_e32 v0, 1.0, v0
	v_mul_f32_e32 v105, 0xbfb8aa3b, v105
	v_lshl_add_u64 v[116:117], v[98:99], 0, v[116:117]
	v_exp_f32_e32 v105, v105
	global_store_dwordx4 v[116:117], v[108:111], off
	v_mul_f32_e32 v106, 0xbfb8aa3b, v106
	v_exp_f32_e32 v106, v106
	v_add_f32_e32 v104, 1.0, v105
	v_rcp_f32_e32 v0, v0
	v_mul_f32_e32 v107, 0xbfb8aa3b, v107
	v_add_f32_e32 v105, 1.0, v106
	v_exp_f32_e32 v107, v107
	v_rcp_f32_e32 v101, v104
	v_add_f32_e32 v106, 1.0, v107
	s_waitcnt lgkmcnt(0)
; DI float sigm(float x) { return 1.f / (1.f + __expf(-x)); }
; DI u32x4 pack8(const float* f) { u32x4 o; o.x = pack2(f[0], f[1]); o.y = pack2(f[2], f[3]); o.z = pack2(f[4], f[5]); o.w = pack2(f[6], f[7]); return o; }
; template <int AI, int BJ, int PASS>
; DI void f3_proc(PREF p, const f32x4 (&acc)[2][2][4][2], int mt, int dt, float* Cs, const u32x4 (&g)[4]) {
;     ...
;   stage_q<AI, BJ>(acc, Cs);
; #pragma unroll
;   for (int q = 0; q < 4; ++q) {
;     int r = (t >> 4) + 32 * q;
;     float v[8]; ld8(Cs + r * CST + c, v);
;     if (PASS == 0) {
; #pragma unroll
;       for (int j = 0; j < 8; ++j) v[j] = sigm(v[j]);
;     } else {
;       float gf[8]; unpack8(g[q], gf);
; #pragma unroll
;       for (int j = 0; j < 8; ++j) v[j] *= gf[j];
;     }
;     *(u32x4*)((u16*)p.fbuf + (size_t)(row0 + r) * 1024 + col0 + c) = pack8(v);
;   }
; DI void f3_phase(PREF p, int l, unsigned char* lds_all) {
;     ...
;       f32x4 acc[2][2][4][2]; zero_acc256(acc);
;       gemm256<1024, 1024, 1024>(acc, p.X + (size_t)mt * 256 * 1024, W + O_PLEG + (size_t)dt * 256 * 1024, shm, p);
;       u32x4 gd[4];
;       f3_proc<0, 0, 0>(p, acc, mt, dt, Cs, gd); f3_proc<0, 1, 0>(p, acc, mt, dt, Cs, gd);
;       f3_proc<1, 0, 0>(p, acc, mt, dt, Cs, gd); f3_proc<1, 1, 0>(p, acc, mt, dt, Cs, gd);
	v_mul_f32_e32 v108, 0xbfb8aa3b, v112
	v_exp_f32_e32 v108, v108
	v_rcp_f32_e32 v103, v105
	v_add_f32_e32 v107, 1.0, v108
	v_rcp_f32_e32 v109, v106
	v_mul_f32_e32 v106, 0xbfb8aa3b, v113
	v_exp_f32_e32 v106, v106
	s_nop 0
	v_add_f32_e32 v106, 1.0, v106
	v_rcp_f32_e32 v110, v107
	v_mul_f32_e32 v107, 0xbfb8aa3b, v114
	v_exp_f32_e32 v107, v107
	s_nop 0
	v_add_f32_e32 v107, 1.0, v107
	v_rcp_f32_e32 v111, v106
	v_mul_f32_e32 v106, 0xbfb8aa3b, v115
	v_exp_f32_e32 v106, v106
	s_nop 0
	v_add_f32_e32 v106, 1.0, v106
	v_rcp_f32_e32 v116, v107
	v_cvt_pk_bf16_f32 v109, v103, v109
	v_rcp_f32_e32 v117, v106
	ds_read_b128 v[104:107], v102 offset:50688
	ds_read_b128 v[112:115], v102 offset:50704
	v_cvt_pk_bf16_f32 v108, v0, v101
	v_add_u32_e32 v102, 64, v100
	v_ashrrev_i32_e32 v103, 31, v102
	s_waitcnt lgkmcnt(1)
	v_mul_f32_e32 v0, 0xbfb8aa3b, v104
	v_exp_f32_e32 v0, v0
	v_lshlrev_b64 v[102:103], 11, v[102:103]
	v_lshl_add_u64 v[102:103], v[98:99], 0, v[102:103]
	v_cvt_pk_bf16_f32 v110, v110, v111
	v_add_f32_e32 v0, 1.0, v0
	v_cvt_pk_bf16_f32 v111, v116, v117
	global_store_dwordx4 v[102:103], v[108:111], off
	v_mul_f32_e32 v105, 0xbfb8aa3b, v105
	v_exp_f32_e32 v105, v105
	s_nop 0
	v_add_f32_e32 v102, 1.0, v105
	v_mul_f32_e32 v104, 0xbfb8aa3b, v106
	v_rcp_f32_e32 v0, v0
	v_exp_f32_e32 v104, v104
	s_nop 0
	v_add_f32_e32 v104, 1.0, v104
	v_rcp_f32_e32 v101, v102
	v_mul_f32_e32 v107, 0xbfb8aa3b, v107
	v_exp_f32_e32 v107, v107
	s_nop 0
	v_add_f32_e32 v105, 1.0, v107
	s_waitcnt lgkmcnt(0)
	v_mul_f32_e32 v106, 0xbfb8aa3b, v112
	v_rcp_f32_e32 v103, v104
	v_exp_f32_e32 v106, v106
	s_nop 0
	v_add_f32_e32 v106, 1.0, v106
	v_rcp_f32_e32 v104, v105
	v_mul_f32_e32 v108, 0xbfb8aa3b, v113
	v_exp_f32_e32 v108, v108
	s_nop 0
	v_add_f32_e32 v107, 1.0, v108
	v_rcp_f32_e32 v105, v106
	v_mul_f32_e32 v109, 0xbfb8aa3b, v114
	v_exp_f32_e32 v109, v109
	s_nop 0
	v_add_f32_e32 v108, 1.0, v109
	v_rcp_f32_e32 v106, v107
	v_mul_f32_e32 v110, 0xbfb8aa3b, v115
	v_exp_f32_e32 v110, v110
	s_nop 0
	v_add_f32_e32 v109, 1.0, v110
	v_rcp_f32_e32 v107, v108
	v_add_u32_e32 v100, 0x60, v100
	v_rcp_f32_e32 v108, v109
	v_cvt_pk_bf16_f32 v102, v0, v101
	v_ashrrev_i32_e32 v101, 31, v100
	v_lshlrev_b64 v[100:101], 11, v[100:101]
	v_lshl_add_u64 v[98:99], v[98:99], 0, v[100:101]
	v_mov_b32_e32 v100, v168
	v_cvt_pk_bf16_f32 v103, v103, v104
	v_cvt_pk_bf16_f32 v104, v105, v106
	v_cvt_pk_bf16_f32 v105, v107, v108
	global_store_dwordx4 v[98:99], v[102:105], off
	s_or_b32 s25, s24, 0x80
	v_lshlrev_b32_e32 v0, 3, v100
	v_and_b32_e32 v101, 0x78, v0
	v_mov_b32_e32 v0, v168
	s_waitcnt lgkmcnt(0)
	s_barrier
	s_nop 0
	v_and_b32_e32 v98, 15, v0
	v_lshrrev_b32_e32 v99, 2, v0
	v_lshlrev_b32_e32 v0, 1, v0
	v_lshlrev_b32_e32 v98, 2, v98
	v_and_b32_e32 v99, 0xfffffcc, v99
	v_and_or_b32 v0, v0, s89, v98
	v_mad_u64_u32 v[98:99], s[0:1], v99, s92, v[0:1]
	v_add_u32_e32 v0, 0x400, v98
	ds_write2_b32 v98, v86, v94 offset1:16
	ds_write2_b32 v98, v87, v95 offset0:132 offset1:148
	ds_write2_b32 v0, v88, v96 offset0:8 offset1:24
	ds_write2_b32 v0, v89, v97 offset0:140 offset1:156
	v_add_u32_e32 v0, 0x2000, v98
	ds_write2_b32 v0, v82, v90 offset0:64 offset1:80
	ds_write2_b32 v0, v83, v91 offset0:196 offset1:212
	v_add_u32_e32 v0, 0x2400, v98
	ds_write2_b32 v0, v84, v92 offset0:72 offset1:88
	ds_write2_b32 v0, v85, v93 offset0:204 offset1:220
	v_add_u32_e32 v0, 0x4000, v98
	ds_write2_b32 v0, v74, v78 offset0:128 offset1:144
	v_add_u32_e32 v0, 0x4400, v98
	ds_write2_b32 v0, v75, v79 offset0:4 offset1:20
	ds_write2_b32 v0, v76, v80 offset0:136 offset1:152
	v_add_u32_e32 v0, 0x4800, v98
	ds_write2_b32 v0, v77, v81 offset0:12 offset1:28
	v_add_u32_e32 v0, 0x6000, v98
	ds_write2_b32 v0, v66, v70 offset0:192 offset1:208
	v_add_u32_e32 v0, 0x6400, v98
	ds_write2_b32 v0, v67, v71 offset0:68 offset1:84
	ds_write2_b32 v0, v68, v72 offset0:200 offset1:216
	v_add_u32_e32 v0, 0x6800, v98
	ds_write2_b32 v0, v69, v73 offset0:76 offset1:92
	v_ashrrev_i32_e32 v0, 4, v100
	v_mul_lo_u32 v66, v0, s92
	s_waitcnt lgkmcnt(0)
	s_barrier
	v_lshl_add_u32 v68, v101, 2, v66
	ds_read_b128 v[70:73], v68
	ds_read_b128 v[74:77], v68 offset:16
	s_waitcnt lgkmcnt(1)
	v_mul_f32_e32 v66, 0xbfb8aa3b, v70
	v_exp_f32_e32 v66, v66
	v_mul_f32_e32 v71, 0xbfb8aa3b, v71
	v_exp_f32_e32 v71, v71
	v_mul_f32_e32 v72, 0xbfb8aa3b, v72
	v_add_f32_e32 v66, 1.0, v66
	v_exp_f32_e32 v72, v72
	v_mul_f32_e32 v73, 0xbfb8aa3b, v73
	v_exp_f32_e32 v73, v73
	v_add_f32_e32 v70, 1.0, v71
	v_rcp_f32_e32 v66, v66
	s_waitcnt lgkmcnt(0)
	v_mul_f32_e32 v74, 0xbfb8aa3b, v74
	v_add_f32_e32 v71, 1.0, v72
	v_rcp_f32_e32 v67, v70
	v_exp_f32_e32 v74, v74
	v_add_f32_e32 v72, 1.0, v73
	v_rcp_f32_e32 v69, v71
	v_mul_f32_e32 v75, 0xbfb8aa3b, v75
	v_add_f32_e32 v73, 1.0, v74
	v_rcp_f32_e32 v71, v72
	v_exp_f32_e32 v75, v75
	s_nop 0
	v_add_f32_e32 v74, 1.0, v75
	v_rcp_f32_e32 v72, v73
	v_mul_f32_e32 v76, 0xbfb8aa3b, v76
	v_exp_f32_e32 v76, v76
	s_nop 0
	v_add_f32_e32 v75, 1.0, v76
	v_rcp_f32_e32 v73, v74
	v_mul_f32_e32 v77, 0xbfb8aa3b, v77
	v_exp_f32_e32 v77, v77
	s_nop 0
	v_add_f32_e32 v76, 1.0, v77
	v_rcp_f32_e32 v78, v75
	v_cvt_pk_bf16_f32 v72, v72, v73
	v_rcp_f32_e32 v79, v76
	ds_read_b128 v[74:77], v68 offset:16896
	v_cvt_pk_bf16_f32 v70, v66, v67
	v_cvt_pk_bf16_f32 v73, v78, v79
	v_add_u32_e32 v66, s24, v0
	ds_read_b128 v[78:81], v68 offset:16912
	s_waitcnt lgkmcnt(1)
; DI float sigm(float x) { return 1.f / (1.f + __expf(-x)); }
; DI u32x4 pack8(const float* f) { u32x4 o; o.x = pack2(f[0], f[1]); o.y = pack2(f[2], f[3]); o.z = pack2(f[4], f[5]); o.w = pack2(f[6], f[7]); return o; }
; template <int AI, int BJ, int PASS>
; DI void f3_proc(PREF p, const f32x4 (&acc)[2][2][4][2], int mt, int dt, float* Cs, const u32x4 (&g)[4]) {
;     ...
;   stage_q<AI, BJ>(acc, Cs);
; #pragma unroll
;   for (int q = 0; q < 4; ++q) {
;     int r = (t >> 4) + 32 * q;
;     float v[8]; ld8(Cs + r * CST + c, v);
;     if (PASS == 0) {
; #pragma unroll
;       for (int j = 0; j < 8; ++j) v[j] = sigm(v[j]);
;     } else {
;       float gf[8]; unpack8(g[q], gf);
; #pragma unroll
;       for (int j = 0; j < 8; ++j) v[j] *= gf[j];
;     }
;     *(u32x4*)((u16*)p.fbuf + (size_t)(row0 + r) * 1024 + col0 + c) = pack8(v);
;   }
; DI void f3_phase(PREF p, int l, unsigned char* lds_all) {
;     ...
;       f32x4 acc[2][2][4][2]; zero_acc256(acc);
;       gemm256<1024, 1024, 1024>(acc, p.X + (size_t)mt * 256 * 1024, W + O_PLEG + (size_t)dt * 256 * 1024, shm, p);
;       u32x4 gd[4];
;       f3_proc<0, 0, 0>(p, acc, mt, dt, Cs, gd); f3_proc<0, 1, 0>(p, acc, mt, dt, Cs, gd);
;       f3_proc<1, 0, 0>(p, acc, mt, dt, Cs, gd); f3_proc<1, 1, 0>(p, acc, mt, dt, Cs, gd);
	v_mul_f32_e32 v0, 0xbfb8aa3b, v74
	v_exp_f32_e32 v0, v0
	v_ashrrev_i32_e32 v67, 31, v66
	v_lshlrev_b64 v[82:83], 11, v[66:67]
	v_cvt_pk_bf16_f32 v71, v69, v71
	v_add_f32_e32 v67, 1.0, v0
	v_lshl_add_u64 v[82:83], s[16:17], 0, v[82:83]
	v_lshlrev_b32_e32 v0, 1, v101
	v_lshl_add_u64 v[82:83], v[82:83], 0, v[0:1]
	global_store_dwordx4 v[82:83], v[70:73], off offset:256
	v_add_u32_e32 v82, 32, v66
	v_ashrrev_i32_e32 v83, 31, v82
	v_mul_f32_e32 v72, 0xbfb8aa3b, v75
	v_exp_f32_e32 v72, v72
	s_nop 0
	v_add_f32_e32 v70, 1.0, v72
	v_rcp_f32_e32 v67, v67
	v_mul_f32_e32 v74, 0xbfb8aa3b, v76
	v_exp_f32_e32 v74, v74
	s_nop 0
	v_add_f32_e32 v72, 1.0, v74
	v_mul_f32_e32 v73, 0xbfb8aa3b, v77
	v_rcp_f32_e32 v69, v70
	v_exp_f32_e32 v73, v73
	s_nop 0
	v_add_f32_e32 v73, 1.0, v73
	v_rcp_f32_e32 v71, v72
	s_waitcnt lgkmcnt(0)
	v_mul_f32_e32 v75, 0xbfb8aa3b, v78
	v_exp_f32_e32 v75, v75
	s_nop 0
	v_add_f32_e32 v74, 1.0, v75
	v_rcp_f32_e32 v72, v73
	v_mul_f32_e32 v76, 0xbfb8aa3b, v79
	v_exp_f32_e32 v76, v76
	s_nop 0
	v_add_f32_e32 v75, 1.0, v76
	v_rcp_f32_e32 v73, v74
	v_mul_f32_e32 v77, 0xbfb8aa3b, v80
	v_exp_f32_e32 v77, v77
	s_nop 0
	v_add_f32_e32 v76, 1.0, v77
	v_rcp_f32_e32 v78, v75
	v_mul_f32_e32 v75, 0xbfb8aa3b, v81
	v_exp_f32_e32 v75, v75
	s_nop 0
	v_add_f32_e32 v75, 1.0, v75
	v_rcp_f32_e32 v79, v76
	v_cvt_pk_bf16_f32 v71, v71, v72
	v_rcp_f32_e32 v80, v75
	ds_read_b128 v[74:77], v68 offset:33792
	v_cvt_pk_bf16_f32 v70, v67, v69
	v_cvt_pk_bf16_f32 v72, v73, v78
	v_cvt_pk_bf16_f32 v73, v79, v80
	ds_read_b128 v[78:81], v68 offset:33808
	s_waitcnt lgkmcnt(1)
	v_mul_f32_e32 v67, 0xbfb8aa3b, v74
	v_exp_f32_e32 v67, v67
	v_lshlrev_b64 v[82:83], 11, v[82:83]
	v_lshl_add_u64 v[82:83], s[16:17], 0, v[82:83]
	v_lshl_add_u64 v[82:83], v[82:83], 0, v[0:1]
	v_add_f32_e32 v67, 1.0, v67
	global_store_dwordx4 v[82:83], v[70:73], off offset:256
	s_nop 1
	v_mul_f32_e32 v72, 0xbfb8aa3b, v75
	v_exp_f32_e32 v72, v72
	s_nop 0
	v_add_f32_e32 v70, 1.0, v72
	v_rcp_f32_e32 v67, v67
	v_mul_f32_e32 v74, 0xbfb8aa3b, v76
	v_exp_f32_e32 v74, v74
	s_nop 0
	v_add_f32_e32 v72, 1.0, v74
	v_mul_f32_e32 v73, 0xbfb8aa3b, v77
	v_rcp_f32_e32 v69, v70
	v_exp_f32_e32 v73, v73
	s_nop 0
	v_add_f32_e32 v73, 1.0, v73
	v_rcp_f32_e32 v71, v72
	s_waitcnt lgkmcnt(0)
	v_mul_f32_e32 v75, 0xbfb8aa3b, v78
	v_exp_f32_e32 v75, v75
	s_nop 0
	v_add_f32_e32 v74, 1.0, v75
	v_rcp_f32_e32 v72, v73
	v_mul_f32_e32 v76, 0xbfb8aa3b, v79
	v_exp_f32_e32 v76, v76
	s_nop 0
	v_add_f32_e32 v75, 1.0, v76
	v_rcp_f32_e32 v73, v74
	v_mul_f32_e32 v77, 0xbfb8aa3b, v80
	v_exp_f32_e32 v77, v77
	s_nop 0
	v_add_f32_e32 v76, 1.0, v77
	v_rcp_f32_e32 v78, v75
	v_mul_f32_e32 v75, 0xbfb8aa3b, v81
	v_exp_f32_e32 v75, v75
	s_nop 0
	v_add_f32_e32 v75, 1.0, v75
	v_rcp_f32_e32 v79, v76
	v_cvt_pk_bf16_f32 v71, v71, v72
	v_rcp_f32_e32 v80, v75
	ds_read_b128 v[74:77], v68 offset:50688
	v_cvt_pk_bf16_f32 v70, v67, v69
	v_cvt_pk_bf16_f32 v72, v73, v78
	v_cvt_pk_bf16_f32 v73, v79, v80
	ds_read_b128 v[78:81], v68 offset:50704
	s_waitcnt lgkmcnt(1)
	v_mul_f32_e32 v67, 0xbfb8aa3b, v74
	v_exp_f32_e32 v67, v67
	v_add_u32_e32 v68, 64, v66
	v_ashrrev_i32_e32 v69, 31, v68
	v_lshlrev_b64 v[68:69], 11, v[68:69]
	v_add_f32_e32 v67, 1.0, v67
	v_lshl_add_u64 v[68:69], s[16:17], 0, v[68:69]
	v_lshl_add_u64 v[68:69], v[68:69], 0, v[0:1]
	global_store_dwordx4 v[68:69], v[70:73], off offset:256
	s_nop 1
	v_mul_f32_e32 v70, 0xbfb8aa3b, v75
	s_nop 0
	v_exp_f32_e32 v70, v70
	s_nop 0
	v_add_f32_e32 v70, 1.0, v70
	v_rcp_f32_e32 v67, v67
	v_mul_f32_e32 v73, 0xbfb8aa3b, v76
	v_exp_f32_e32 v73, v73
	s_nop 0
	v_add_f32_e32 v71, 1.0, v73
	v_mul_f32_e32 v72, 0xbfb8aa3b, v77
	v_exp_f32_e32 v72, v72
	v_rcp_f32_e32 v68, v70
	v_add_f32_e32 v72, 1.0, v72
	s_waitcnt lgkmcnt(0)
	v_mul_f32_e32 v74, 0xbfb8aa3b, v78
	v_exp_f32_e32 v74, v74
	v_rcp_f32_e32 v69, v71
	v_add_f32_e32 v73, 1.0, v74
	v_mul_f32_e32 v75, 0xbfb8aa3b, v79
	v_exp_f32_e32 v75, v75
	v_rcp_f32_e32 v70, v72
	v_add_f32_e32 v74, 1.0, v75
	v_mul_f32_e32 v76, 0xbfb8aa3b, v80
	v_exp_f32_e32 v76, v76
	v_rcp_f32_e32 v71, v73
	v_add_f32_e32 v75, 1.0, v76
	v_mul_f32_e32 v77, 0xbfb8aa3b, v81
	v_exp_f32_e32 v77, v77
	v_rcp_f32_e32 v72, v74
	v_add_f32_e32 v76, 1.0, v77
	v_rcp_f32_e32 v73, v75
	v_add_u32_e32 v66, 0x60, v66
	v_cvt_pk_bf16_f32 v68, v67, v68
	v_ashrrev_i32_e32 v67, 31, v66
	v_lshlrev_b64 v[66:67], 11, v[66:67]
	v_lshl_add_u64 v[66:67], s[16:17], 0, v[66:67]
	v_lshl_add_u64 v[66:67], v[66:67], 0, v[0:1]
	v_rcp_f32_e32 v74, v76
	v_cvt_pk_bf16_f32 v69, v69, v70
	v_cvt_pk_bf16_f32 v70, v71, v72
	v_cvt_pk_bf16_f32 v71, v73, v74
	global_store_dwordx4 v[66:67], v[68:71], off offset:256
	s_nop 1
	v_mov_b32_e32 v68, v168
	s_nop 0
	v_lshlrev_b32_e32 v0, 3, v68
	v_and_b32_e32 v69, 0x78, v0
	v_mov_b32_e32 v0, v168
	s_waitcnt lgkmcnt(0)
	s_barrier
	s_nop 0
	v_and_b32_e32 v66, 15, v0
	v_lshrrev_b32_e32 v67, 2, v0
	v_lshlrev_b32_e32 v0, 1, v0
	v_lshlrev_b32_e32 v66, 2, v66
	v_and_b32_e32 v67, 0xfffffcc, v67
	v_and_or_b32 v0, v0, s89, v66
	v_mad_u64_u32 v[66:67], s[0:1], v67, s92, v[0:1]
	v_add_u32_e32 v0, 0x400, v66
	ds_write2_b32 v66, v54, v62 offset1:16
	ds_write2_b32 v66, v55, v63 offset0:132 offset1:148
	ds_write2_b32 v0, v56, v64 offset0:8 offset1:24
	ds_write2_b32 v0, v57, v65 offset0:140 offset1:156
	v_add_u32_e32 v0, 0x2000, v66
	ds_write2_b32 v0, v50, v58 offset0:64 offset1:80
	ds_write2_b32 v0, v51, v59 offset0:196 offset1:212
	v_add_u32_e32 v0, 0x2400, v66
	ds_write2_b32 v0, v52, v60 offset0:72 offset1:88
	ds_write2_b32 v0, v53, v61 offset0:204 offset1:220
	v_add_u32_e32 v0, 0x4000, v66
	ds_write2_b32 v0, v42, v46 offset0:128 offset1:144
	v_add_u32_e32 v0, 0x4400, v66
	ds_write2_b32 v0, v43, v47 offset0:4 offset1:20
	ds_write2_b32 v0, v44, v48 offset0:136 offset1:152
	v_add_u32_e32 v0, 0x4800, v66
	ds_write2_b32 v0, v45, v49 offset0:12 offset1:28
	v_add_u32_e32 v0, 0x6000, v66
	ds_write2_b32 v0, v34, v38 offset0:192 offset1:208
	v_add_u32_e32 v0, 0x6400, v66
	ds_write2_b32 v0, v35, v39 offset0:68 offset1:84
	ds_write2_b32 v0, v36, v40 offset0:200 offset1:216
	v_add_u32_e32 v0, 0x6800, v66
	v_ashrrev_i32_e32 v36, 4, v68
	ds_write2_b32 v0, v37, v41 offset0:76 offset1:92
	v_mul_lo_u32 v0, v36, s92
	s_waitcnt lgkmcnt(0)
	s_barrier
; DI float sigm(float x) { return 1.f / (1.f + __expf(-x)); }
; DI u32x4 pack8(const float* f) { u32x4 o; o.x = pack2(f[0], f[1]); o.y = pack2(f[2], f[3]); o.z = pack2(f[4], f[5]); o.w = pack2(f[6], f[7]); return o; }
; template <int AI, int BJ, int PASS>
; DI void f3_proc(PREF p, const f32x4 (&acc)[2][2][4][2], int mt, int dt, float* Cs, const u32x4 (&g)[4]) {
;     ...
;   stage_q<AI, BJ>(acc, Cs);
; #pragma unroll
;   for (int q = 0; q < 4; ++q) {
;     int r = (t >> 4) + 32 * q;
;     float v[8]; ld8(Cs + r * CST + c, v);
;     if (PASS == 0) {
; #pragma unroll
;       for (int j = 0; j < 8; ++j) v[j] = sigm(v[j]);
;     } else {
;       float gf[8]; unpack8(g[q], gf);
; #pragma unroll
;       for (int j = 0; j < 8; ++j) v[j] *= gf[j];
;     }
;     *(u32x4*)((u16*)p.fbuf + (size_t)(row0 + r) * 1024 + col0 + c) = pack8(v);
;   }
; DI void f3_phase(PREF p, int l, unsigned char* lds_all) {
;     ...
;       f32x4 acc[2][2][4][2]; zero_acc256(acc);
;       gemm256<1024, 1024, 1024>(acc, p.X + (size_t)mt * 256 * 1024, W + O_PLEG + (size_t)dt * 256 * 1024, shm, p);
;       u32x4 gd[4];
;       f3_proc<0, 0, 0>(p, acc, mt, dt, Cs, gd); f3_proc<0, 1, 0>(p, acc, mt, dt, Cs, gd);
;       f3_proc<1, 0, 0>(p, acc, mt, dt, Cs, gd); f3_proc<1, 1, 0>(p, acc, mt, dt, Cs, gd);
	v_lshl_add_u32 v38, v69, 2, v0
	ds_read_b128 v[40:43], v38
	ds_read_b128 v[44:47], v38 offset:16
	v_add_u32_e32 v36, s25, v36
	s_waitcnt lgkmcnt(1)
	v_mul_f32_e32 v0, 0xbfb8aa3b, v40
	v_exp_f32_e32 v0, v0
	v_mul_f32_e32 v41, 0xbfb8aa3b, v41
	v_exp_f32_e32 v41, v41
	v_mul_f32_e32 v42, 0xbfb8aa3b, v42
	v_add_f32_e32 v37, 1.0, v0
	v_lshlrev_b32_e32 v0, 1, v69
	v_lshl_add_u64 v[34:35], s[16:17], 0, v[0:1]
	v_exp_f32_e32 v42, v42
	v_add_f32_e32 v39, 1.0, v41
	v_rcp_f32_e32 v0, v37
	v_mul_f32_e32 v43, 0xbfb8aa3b, v43
	v_add_f32_e32 v41, 1.0, v42
	v_rcp_f32_e32 v37, v39
	v_exp_f32_e32 v43, v43
	s_nop 0
	v_add_f32_e32 v42, 1.0, v43
	s_waitcnt lgkmcnt(0)
	v_mul_f32_e32 v44, 0xbfb8aa3b, v44
	v_exp_f32_e32 v44, v44
	v_rcp_f32_e32 v39, v41
	v_add_f32_e32 v43, 1.0, v44
	v_rcp_f32_e32 v49, v42
	v_mul_f32_e32 v42, 0xbfb8aa3b, v45
	v_exp_f32_e32 v42, v42
	s_nop 0
	v_add_f32_e32 v42, 1.0, v42
	v_rcp_f32_e32 v48, v43
	v_mul_f32_e32 v43, 0xbfb8aa3b, v46
	v_exp_f32_e32 v43, v43
	s_nop 0
	v_add_f32_e32 v43, 1.0, v43
	v_rcp_f32_e32 v50, v42
	v_mul_f32_e32 v42, 0xbfb8aa3b, v47
	v_exp_f32_e32 v42, v42
	s_nop 0
	v_add_f32_e32 v42, 1.0, v42
	v_rcp_f32_e32 v47, v43
	v_cvt_pk_bf16_f32 v46, v48, v50
	v_rcp_f32_e32 v52, v42
	ds_read_b128 v[40:43], v38 offset:16896
	v_cvt_pk_bf16_f32 v44, v0, v37
	v_cvt_pk_bf16_f32 v45, v39, v49
	ds_read_b128 v[48:51], v38 offset:16912
	v_ashrrev_i32_e32 v37, 31, v36
	s_waitcnt lgkmcnt(1)
	v_mul_f32_e32 v0, 0xbfb8aa3b, v40
	v_exp_f32_e32 v0, v0
	v_cvt_pk_bf16_f32 v47, v47, v52
	v_lshlrev_b64 v[52:53], 11, v[36:37]
	v_mul_f32_e32 v41, 0xbfb8aa3b, v41
	v_add_f32_e32 v0, 1.0, v0
	v_lshl_add_u64 v[52:53], v[34:35], 0, v[52:53]
	v_exp_f32_e32 v41, v41
	global_store_dwordx4 v[52:53], v[44:47], off
	v_add_f32_e32 v39, 1.0, v41
	v_rcp_f32_e32 v0, v0
	v_mul_f32_e32 v42, 0xbfb8aa3b, v42
	v_exp_f32_e32 v42, v42
	s_nop 0
	v_add_f32_e32 v41, 1.0, v42
	v_rcp_f32_e32 v37, v39
	v_mul_f32_e32 v43, 0xbfb8aa3b, v43
	v_exp_f32_e32 v43, v43
	s_nop 0
	v_add_f32_e32 v42, 1.0, v43
	s_waitcnt lgkmcnt(0)
	v_mul_f32_e32 v44, 0xbfb8aa3b, v48
	v_exp_f32_e32 v44, v44
	v_rcp_f32_e32 v39, v41
	v_add_f32_e32 v43, 1.0, v44
	v_rcp_f32_e32 v45, v42
	v_mul_f32_e32 v42, 0xbfb8aa3b, v49
	v_exp_f32_e32 v42, v42
	s_nop 0
	v_add_f32_e32 v42, 1.0, v42
	v_rcp_f32_e32 v46, v43
	v_mul_f32_e32 v43, 0xbfb8aa3b, v50
	v_exp_f32_e32 v43, v43
	s_nop 0
	v_add_f32_e32 v43, 1.0, v43
	v_rcp_f32_e32 v47, v42
	v_mul_f32_e32 v42, 0xbfb8aa3b, v51
	v_exp_f32_e32 v42, v42
	s_nop 0
	v_add_f32_e32 v42, 1.0, v42
	v_rcp_f32_e32 v52, v43
	v_cvt_pk_bf16_f32 v45, v39, v45
	v_rcp_f32_e32 v53, v42
	ds_read_b128 v[40:43], v38 offset:33792
	ds_read_b128 v[48:51], v38 offset:33808
	v_cvt_pk_bf16_f32 v44, v0, v37
	v_cvt_pk_bf16_f32 v46, v46, v47
	v_cvt_pk_bf16_f32 v47, v52, v53
	s_waitcnt lgkmcnt(1)
	v_mul_f32_e32 v0, 0xbfb8aa3b, v40
	v_exp_f32_e32 v0, v0
	v_add_u32_e32 v52, 32, v36
	v_ashrrev_i32_e32 v53, 31, v52
	v_lshlrev_b64 v[52:53], 11, v[52:53]
	v_add_f32_e32 v0, 1.0, v0
	v_mul_f32_e32 v41, 0xbfb8aa3b, v41
	v_lshl_add_u64 v[52:53], v[34:35], 0, v[52:53]
	v_exp_f32_e32 v41, v41
	global_store_dwordx4 v[52:53], v[44:47], off
	v_mul_f32_e32 v42, 0xbfb8aa3b, v42
	v_exp_f32_e32 v42, v42
	v_add_f32_e32 v40, 1.0, v41
	v_rcp_f32_e32 v0, v0
	v_mul_f32_e32 v43, 0xbfb8aa3b, v43
	v_add_f32_e32 v41, 1.0, v42
	v_exp_f32_e32 v43, v43
	v_rcp_f32_e32 v37, v40
	v_add_f32_e32 v42, 1.0, v43
	s_waitcnt lgkmcnt(0)
	v_mul_f32_e32 v44, 0xbfb8aa3b, v48
	v_exp_f32_e32 v44, v44
	v_rcp_f32_e32 v39, v41
	v_add_f32_e32 v43, 1.0, v44
	v_rcp_f32_e32 v45, v42
	v_mul_f32_e32 v42, 0xbfb8aa3b, v49
	v_exp_f32_e32 v42, v42
	s_nop 0
	v_add_f32_e32 v42, 1.0, v42
	v_rcp_f32_e32 v46, v43
	v_mul_f32_e32 v43, 0xbfb8aa3b, v50
	v_exp_f32_e32 v43, v43
	s_nop 0
	v_add_f32_e32 v43, 1.0, v43
	v_rcp_f32_e32 v47, v42
	v_mul_f32_e32 v42, 0xbfb8aa3b, v51
	v_exp_f32_e32 v42, v42
	s_nop 0
	v_add_f32_e32 v42, 1.0, v42
	v_rcp_f32_e32 v52, v43
	v_cvt_pk_bf16_f32 v45, v39, v45
	v_rcp_f32_e32 v53, v42
	ds_read_b128 v[40:43], v38 offset:50688
	ds_read_b128 v[48:51], v38 offset:50704
	v_cvt_pk_bf16_f32 v44, v0, v37
	v_add_u32_e32 v38, 64, v36
	v_ashrrev_i32_e32 v39, 31, v38
	s_waitcnt lgkmcnt(1)
	v_mul_f32_e32 v0, 0xbfb8aa3b, v40
	v_exp_f32_e32 v0, v0
	v_lshlrev_b64 v[38:39], 11, v[38:39]
	v_lshl_add_u64 v[38:39], v[34:35], 0, v[38:39]
	v_cvt_pk_bf16_f32 v46, v46, v47
	v_add_f32_e32 v0, 1.0, v0
	v_cvt_pk_bf16_f32 v47, v52, v53
	global_store_dwordx4 v[38:39], v[44:47], off
	v_mul_f32_e32 v41, 0xbfb8aa3b, v41
	v_exp_f32_e32 v41, v41
	s_nop 0
	v_add_f32_e32 v38, 1.0, v41
	v_mul_f32_e32 v40, 0xbfb8aa3b, v42
	v_rcp_f32_e32 v0, v0
	v_exp_f32_e32 v40, v40
	s_nop 0
	v_add_f32_e32 v40, 1.0, v40
	v_rcp_f32_e32 v37, v38
	v_mul_f32_e32 v43, 0xbfb8aa3b, v43
	v_exp_f32_e32 v43, v43
	s_nop 0
	v_add_f32_e32 v41, 1.0, v43
	s_waitcnt lgkmcnt(0)
	v_mul_f32_e32 v42, 0xbfb8aa3b, v48
	v_rcp_f32_e32 v39, v40
	v_exp_f32_e32 v42, v42
	s_nop 0
	v_add_f32_e32 v42, 1.0, v42
	v_rcp_f32_e32 v40, v41
	v_mul_f32_e32 v44, 0xbfb8aa3b, v49
	v_exp_f32_e32 v44, v44
	s_nop 0
	v_add_f32_e32 v43, 1.0, v44
	v_rcp_f32_e32 v41, v42
	v_mul_f32_e32 v45, 0xbfb8aa3b, v50
	v_exp_f32_e32 v45, v45
	s_nop 0
	v_add_f32_e32 v44, 1.0, v45
	v_rcp_f32_e32 v42, v43
	v_mul_f32_e32 v46, 0xbfb8aa3b, v51
	v_exp_f32_e32 v46, v46
	s_nop 0
	v_add_f32_e32 v45, 1.0, v46
	v_rcp_f32_e32 v43, v44
	v_add_u32_e32 v36, 0x60, v36
	v_rcp_f32_e32 v44, v45
	v_cvt_pk_bf16_f32 v38, v0, v37
	v_ashrrev_i32_e32 v37, 31, v36
	v_lshlrev_b64 v[36:37], 11, v[36:37]
	v_lshl_add_u64 v[34:35], v[34:35], 0, v[36:37]
	v_mov_b32_e32 v36, v168
	v_cvt_pk_bf16_f32 v39, v39, v40
	v_cvt_pk_bf16_f32 v40, v41, v42
	v_cvt_pk_bf16_f32 v41, v43, v44
	global_store_dwordx4 v[34:35], v[38:41], off
	s_nop 0
	v_lshlrev_b32_e32 v0, 3, v36
	v_and_b32_e32 v37, 0x78, v0
	v_mov_b32_e32 v0, v168
	s_waitcnt lgkmcnt(0)
	s_barrier
; DI float sigm(float x) { return 1.f / (1.f + __expf(-x)); }
; DI u32x4 pack8(const float* f) { u32x4 o; o.x = pack2(f[0], f[1]); o.y = pack2(f[2], f[3]); o.z = pack2(f[4], f[5]); o.w = pack2(f[6], f[7]); return o; }
; template <int AI, int BJ, int PASS>
; DI void f3_proc(PREF p, const f32x4 (&acc)[2][2][4][2], int mt, int dt, float* Cs, const u32x4 (&g)[4]) {
;     ...
;   stage_q<AI, BJ>(acc, Cs);
; #pragma unroll
;   for (int q = 0; q < 4; ++q) {
;     int r = (t >> 4) + 32 * q;
;     float v[8]; ld8(Cs + r * CST + c, v);
;     if (PASS == 0) {
; #pragma unroll
;       for (int j = 0; j < 8; ++j) v[j] = sigm(v[j]);
;     } else {
;       float gf[8]; unpack8(g[q], gf);
; #pragma unroll
;       for (int j = 0; j < 8; ++j) v[j] *= gf[j];
;     }
;     *(u32x4*)((u16*)p.fbuf + (size_t)(row0 + r) * 1024 + col0 + c) = pack8(v);
;   }
; DI void f3_phase(PREF p, int l, unsigned char* lds_all) {
;     ...
;       f32x4 acc[2][2][4][2]; zero_acc256(acc);
;       gemm256<1024, 1024, 1024>(acc, p.X + (size_t)mt * 256 * 1024, W + O_PLEG + (size_t)dt * 256 * 1024, shm, p);
;       u32x4 gd[4];
;       f3_proc<0, 0, 0>(p, acc, mt, dt, Cs, gd); f3_proc<0, 1, 0>(p, acc, mt, dt, Cs, gd);
;       f3_proc<1, 0, 0>(p, acc, mt, dt, Cs, gd); f3_proc<1, 1, 0>(p, acc, mt, dt, Cs, gd);
	s_nop 0
	v_and_b32_e32 v34, 15, v0
	v_lshrrev_b32_e32 v35, 2, v0
	v_lshlrev_b32_e32 v0, 1, v0
	v_lshlrev_b32_e32 v34, 2, v34
	v_and_b32_e32 v35, 0xfffffcc, v35
	v_and_or_b32 v0, v0, s89, v34
	v_mad_u64_u32 v[34:35], s[0:1], v35, s92, v[0:1]
	v_add_u32_e32 v0, 0x400, v34
	ds_write2_b32 v34, v22, v30 offset1:16
	ds_write2_b32 v34, v23, v31 offset0:132 offset1:148
	ds_write2_b32 v0, v24, v32 offset0:8 offset1:24
	ds_write2_b32 v0, v25, v33 offset0:140 offset1:156
	v_add_u32_e32 v0, 0x2000, v34
	ds_write2_b32 v0, v18, v26 offset0:64 offset1:80
	ds_write2_b32 v0, v19, v27 offset0:196 offset1:212
	v_add_u32_e32 v0, 0x2400, v34
	ds_write2_b32 v0, v20, v28 offset0:72 offset1:88
	ds_write2_b32 v0, v21, v29 offset0:204 offset1:220
	v_add_u32_e32 v0, 0x4000, v34
	ds_write2_b32 v0, v10, v14 offset0:128 offset1:144
	v_add_u32_e32 v0, 0x4400, v34
	ds_write2_b32 v0, v11, v15 offset0:4 offset1:20
	ds_write2_b32 v0, v12, v16 offset0:136 offset1:152
	v_add_u32_e32 v0, 0x4800, v34
	ds_write2_b32 v0, v13, v17 offset0:12 offset1:28
	v_add_u32_e32 v0, 0x6000, v34
	ds_write2_b32 v0, v2, v6 offset0:192 offset1:208
	v_add_u32_e32 v0, 0x6400, v34
	ds_write2_b32 v0, v3, v7 offset0:68 offset1:84
	ds_write2_b32 v0, v4, v8 offset0:200 offset1:216
	v_add_u32_e32 v0, 0x6800, v34
	ds_write2_b32 v0, v5, v9 offset0:76 offset1:92
	v_ashrrev_i32_e32 v0, 4, v36
	v_mul_lo_u32 v2, v0, s92
	s_waitcnt lgkmcnt(0)
	s_barrier
	v_lshl_add_u32 v4, v37, 2, v2
	ds_read_b128 v[6:9], v4
	ds_read_b128 v[10:13], v4 offset:16
	s_waitcnt lgkmcnt(1)
	v_mul_f32_e32 v2, 0xbfb8aa3b, v6
	v_exp_f32_e32 v2, v2
	v_mul_f32_e32 v7, 0xbfb8aa3b, v7
	v_exp_f32_e32 v7, v7
	v_mul_f32_e32 v8, 0xbfb8aa3b, v8
	v_add_f32_e32 v2, 1.0, v2
	v_exp_f32_e32 v8, v8
	v_mul_f32_e32 v9, 0xbfb8aa3b, v9
	v_exp_f32_e32 v9, v9
	v_add_f32_e32 v6, 1.0, v7
	v_rcp_f32_e32 v2, v2
	s_waitcnt lgkmcnt(0)
	v_mul_f32_e32 v10, 0xbfb8aa3b, v10
	v_add_f32_e32 v7, 1.0, v8
	v_rcp_f32_e32 v3, v6
	v_exp_f32_e32 v10, v10
	v_add_f32_e32 v8, 1.0, v9
	v_rcp_f32_e32 v5, v7
	v_mul_f32_e32 v11, 0xbfb8aa3b, v11
	v_add_f32_e32 v9, 1.0, v10
	v_rcp_f32_e32 v7, v8
	v_exp_f32_e32 v11, v11
	s_nop 0
	v_add_f32_e32 v10, 1.0, v11
	v_rcp_f32_e32 v8, v9
	v_mul_f32_e32 v12, 0xbfb8aa3b, v12
	v_exp_f32_e32 v12, v12
	s_nop 0
	v_add_f32_e32 v11, 1.0, v12
	v_rcp_f32_e32 v9, v10
	v_mul_f32_e32 v13, 0xbfb8aa3b, v13
	v_exp_f32_e32 v13, v13
	s_nop 0
	v_add_f32_e32 v12, 1.0, v13
	v_rcp_f32_e32 v14, v11
	v_cvt_pk_bf16_f32 v8, v8, v9
	v_rcp_f32_e32 v15, v12
	ds_read_b128 v[10:13], v4 offset:16896
	v_cvt_pk_bf16_f32 v6, v2, v3
	v_cvt_pk_bf16_f32 v9, v14, v15
	v_add_u32_e32 v2, s25, v0
	ds_read_b128 v[14:17], v4 offset:16912
	s_waitcnt lgkmcnt(1)
	v_mul_f32_e32 v0, 0xbfb8aa3b, v10
	v_exp_f32_e32 v0, v0
	v_ashrrev_i32_e32 v3, 31, v2
	v_lshlrev_b64 v[18:19], 11, v[2:3]
	v_cvt_pk_bf16_f32 v7, v5, v7
	v_add_f32_e32 v3, 1.0, v0
	v_lshl_add_u64 v[18:19], s[16:17], 0, v[18:19]
	v_lshlrev_b32_e32 v0, 1, v37
	v_lshl_add_u64 v[18:19], v[18:19], 0, v[0:1]
	global_store_dwordx4 v[18:19], v[6:9], off offset:256
	v_add_u32_e32 v18, 32, v2
	v_ashrrev_i32_e32 v19, 31, v18
	v_mul_f32_e32 v8, 0xbfb8aa3b, v11
	v_exp_f32_e32 v8, v8
	s_nop 0
	v_add_f32_e32 v6, 1.0, v8
	v_rcp_f32_e32 v3, v3
	v_mul_f32_e32 v10, 0xbfb8aa3b, v12
	v_exp_f32_e32 v10, v10
	s_nop 0
	v_add_f32_e32 v8, 1.0, v10
	v_mul_f32_e32 v9, 0xbfb8aa3b, v13
	v_rcp_f32_e32 v5, v6
	v_exp_f32_e32 v9, v9
	s_nop 0
	v_add_f32_e32 v9, 1.0, v9
	v_rcp_f32_e32 v7, v8
	s_waitcnt lgkmcnt(0)
	v_mul_f32_e32 v11, 0xbfb8aa3b, v14
	v_exp_f32_e32 v11, v11
	s_nop 0
	v_add_f32_e32 v10, 1.0, v11
	v_rcp_f32_e32 v8, v9
	v_mul_f32_e32 v12, 0xbfb8aa3b, v15
	v_exp_f32_e32 v12, v12
	s_nop 0
	v_add_f32_e32 v11, 1.0, v12
	v_rcp_f32_e32 v9, v10
	v_mul_f32_e32 v13, 0xbfb8aa3b, v16
	v_exp_f32_e32 v13, v13
	s_nop 0
	v_add_f32_e32 v12, 1.0, v13
	v_rcp_f32_e32 v14, v11
	v_mul_f32_e32 v11, 0xbfb8aa3b, v17
	v_exp_f32_e32 v11, v11
	s_nop 0
	v_add_f32_e32 v11, 1.0, v11
	v_rcp_f32_e32 v15, v12
	v_cvt_pk_bf16_f32 v7, v7, v8
	v_rcp_f32_e32 v16, v11
	ds_read_b128 v[10:13], v4 offset:33792
	v_cvt_pk_bf16_f32 v6, v3, v5
	v_cvt_pk_bf16_f32 v8, v9, v14
	v_cvt_pk_bf16_f32 v9, v15, v16
	ds_read_b128 v[14:17], v4 offset:33808
	s_waitcnt lgkmcnt(1)
	v_mul_f32_e32 v3, 0xbfb8aa3b, v10
	v_exp_f32_e32 v3, v3
	v_lshlrev_b64 v[18:19], 11, v[18:19]
	v_lshl_add_u64 v[18:19], s[16:17], 0, v[18:19]
	v_lshl_add_u64 v[18:19], v[18:19], 0, v[0:1]
	v_add_f32_e32 v3, 1.0, v3
	global_store_dwordx4 v[18:19], v[6:9], off offset:256
	s_nop 1
	v_mul_f32_e32 v8, 0xbfb8aa3b, v11
	v_exp_f32_e32 v8, v8
	s_nop 0
	v_add_f32_e32 v6, 1.0, v8
	v_rcp_f32_e32 v3, v3
	v_mul_f32_e32 v10, 0xbfb8aa3b, v12
	v_exp_f32_e32 v10, v10
	s_nop 0
	v_add_f32_e32 v8, 1.0, v10
	v_mul_f32_e32 v9, 0xbfb8aa3b, v13
	v_rcp_f32_e32 v5, v6
	v_exp_f32_e32 v9, v9
	s_nop 0
	v_add_f32_e32 v9, 1.0, v9
	v_rcp_f32_e32 v7, v8
	s_waitcnt lgkmcnt(0)
; DI float sigm(float x) { return 1.f / (1.f + __expf(-x)); }
; DI u32x4 pack8(const float* f) { u32x4 o; o.x = pack2(f[0], f[1]); o.y = pack2(f[2], f[3]); o.z = pack2(f[4], f[5]); o.w = pack2(f[6], f[7]); return o; }
; DI void lds_barrier() { asm volatile("s_waitcnt lgkmcnt(0)\n\ts_barrier" ::: "memory"); }
; DI int tid512() { int t = threadIdx.x; asm volatile("" : "+v"(t)); return t; }
; #define G_WAIT_V(n) asm volatile("s_waitcnt vmcnt(" #n ")" ::: "memory")
; #define G_BAR __builtin_amdgcn_s_barrier()
;     ...
;   const int t = tid512();
;   const int wid = t >> 6, lane = t & 63, wr = wid >> 2, wc = wid & 3, fr = lane & 15, fq = lane >> 4;
;   int r0, c0, r1, c1;
;   g_stage_rc(t * 16, r0, c0); g_stage_rc(t * 16 + 8192, r1, c1);
;   const int oa0 = r0 * LDA + c0, oa1 = r1 * LDA + c1, ob0 = r0 * LDB + c0, ob1 = r1 * LDB + c1;
;   const int obr = fr * 64 + fq * 16, rdo = obr ^ (((obr >> 9) & 1) << 5);
;   bf16x8 At[4][2], B0[2][2], B1[2][2];
;   constexpr int nt = K / 64;
;   lds_barrier();
;   G_STAGE(G_SB(0, 0), B, ob0, ob1, LDB, 0, KB(0)); G_STAGE(G_SA(0, 0), A, oa0, oa1, LDA, 0, KA(0));
;   G_STAGE(G_SB(0, 1), B, ob0, ob1, LDB, 128, KB(0)); G_STAGE(G_SA(0, 1), A, oa0, oa1, LDA, 128, KA(0));
;   if (wr == 1) G_BAR;
;   G_WAIT_V(4); G_BAR;
;   G_STAGE(G_SB(1, 0), B, ob0, ob1, LDB, 0, KB(1)); G_STAGE(G_SA(1, 0), A, oa0, oa1, LDA, 0, KA(1)); G_STAGE(G_SB(1, 1), B, ob0, ob1, LDB, 128, KB(1));
; template <int AI, int BJ, int PASS>
; DI void f3_proc(PREF p, const f32x4 (&acc)[2][2][4][2], int mt, int dt, float* Cs, const u32x4 (&g)[4]) {
;     ...
;   for (int q = 0; q < 4; ++q) {
;     int r = (t >> 4) + 32 * q;
;     float v[8]; ld8(Cs + r * CST + c, v);
;     if (PASS == 0) {
; #pragma unroll
;       for (int j = 0; j < 8; ++j) v[j] = sigm(v[j]);
;     } else {
;       float gf[8]; unpack8(g[q], gf);
; #pragma unroll
;       for (int j = 0; j < 8; ++j) v[j] *= gf[j];
;     }
;     *(u32x4*)((u16*)p.fbuf + (size_t)(row0 + r) * 1024 + col0 + c) = pack8(v);
;   }
	v_mul_f32_e32 v11, 0xbfb8aa3b, v14
	v_exp_f32_e32 v11, v11
	s_nop 0
	v_add_f32_e32 v10, 1.0, v11
	v_rcp_f32_e32 v8, v9
	v_mul_f32_e32 v12, 0xbfb8aa3b, v15
	v_exp_f32_e32 v12, v12
	s_nop 0
	v_add_f32_e32 v11, 1.0, v12
	v_rcp_f32_e32 v9, v10
	v_mul_f32_e32 v13, 0xbfb8aa3b, v16
	v_exp_f32_e32 v13, v13
	s_nop 0
	v_add_f32_e32 v12, 1.0, v13
	v_rcp_f32_e32 v14, v11
	v_mul_f32_e32 v11, 0xbfb8aa3b, v17
	v_exp_f32_e32 v11, v11
	s_nop 0
	v_add_f32_e32 v11, 1.0, v11
	v_rcp_f32_e32 v15, v12
	v_cvt_pk_bf16_f32 v7, v7, v8
	v_rcp_f32_e32 v16, v11
	ds_read_b128 v[10:13], v4 offset:50688
	v_cvt_pk_bf16_f32 v6, v3, v5
	v_cvt_pk_bf16_f32 v8, v9, v14
	v_cvt_pk_bf16_f32 v9, v15, v16
	ds_read_b128 v[14:17], v4 offset:50704
	s_waitcnt lgkmcnt(1)
	v_mul_f32_e32 v3, 0xbfb8aa3b, v10
	v_exp_f32_e32 v3, v3
	v_add_u32_e32 v4, 64, v2
	v_ashrrev_i32_e32 v5, 31, v4
	v_lshlrev_b64 v[4:5], 11, v[4:5]
	v_add_f32_e32 v3, 1.0, v3
	v_lshl_add_u64 v[4:5], s[16:17], 0, v[4:5]
	v_lshl_add_u64 v[4:5], v[4:5], 0, v[0:1]
	global_store_dwordx4 v[4:5], v[6:9], off offset:256
	s_nop 1
	v_mul_f32_e32 v6, 0xbfb8aa3b, v11
	s_nop 0
	v_exp_f32_e32 v6, v6
	s_nop 0
	v_add_f32_e32 v6, 1.0, v6
	v_rcp_f32_e32 v3, v3
	v_mul_f32_e32 v9, 0xbfb8aa3b, v12
	v_exp_f32_e32 v9, v9
	s_nop 0
	v_add_f32_e32 v7, 1.0, v9
	v_mul_f32_e32 v8, 0xbfb8aa3b, v13
	v_exp_f32_e32 v8, v8
	v_rcp_f32_e32 v4, v6
	v_add_f32_e32 v8, 1.0, v8
	s_waitcnt lgkmcnt(0)
	v_mul_f32_e32 v10, 0xbfb8aa3b, v14
	v_exp_f32_e32 v10, v10
	v_rcp_f32_e32 v5, v7
	v_add_f32_e32 v9, 1.0, v10
	v_mul_f32_e32 v11, 0xbfb8aa3b, v15
	v_exp_f32_e32 v11, v11
	v_rcp_f32_e32 v6, v8
	v_add_f32_e32 v10, 1.0, v11
	v_mul_f32_e32 v12, 0xbfb8aa3b, v16
	v_exp_f32_e32 v12, v12
	v_rcp_f32_e32 v7, v9
	v_add_f32_e32 v11, 1.0, v12
	v_mul_f32_e32 v13, 0xbfb8aa3b, v17
	v_exp_f32_e32 v13, v13
	v_rcp_f32_e32 v8, v10
	v_add_f32_e32 v12, 1.0, v13
	v_rcp_f32_e32 v9, v11
	v_add_u32_e32 v2, 0x60, v2
	v_cvt_pk_bf16_f32 v4, v3, v4
	v_ashrrev_i32_e32 v3, 31, v2
	v_lshlrev_b64 v[2:3], 11, v[2:3]
	v_lshl_add_u64 v[2:3], s[16:17], 0, v[2:3]
	v_lshl_add_u64 v[2:3], v[2:3], 0, v[0:1]
	s_lshl_b32 s0, s35, 17
	v_mov_b32_e32 v0, v168
	v_rcp_f32_e32 v10, v12
	v_cvt_pk_bf16_f32 v5, v5, v6
	v_cvt_pk_bf16_f32 v6, v7, v8
	v_cvt_pk_bf16_f32 v7, v9, v10
	global_store_dwordx4 v[2:3], v[4:7], off offset:256
	s_add_u32 s20, s10, s0
	s_addc_u32 s21, s11, 0
	v_lshlrev_b32_e32 v18, 4, v0
	v_and_b32_e32 v2, 32, v0
	s_lshl_b64 s[0:1], s[18:19], 17
	v_bitop3_b32 v2, v18, v2, 48 bitop3:0x6c
	s_add_u32 s18, s30, s0
	v_lshrrev_b32_e32 v3, 3, v0
	v_bfe_u32 v4, v0, 2, 4
	s_mov_b32 s0, 0xfffff0
	v_lshrrev_b32_e32 v5, 1, v0
	v_lshrrev_b32_e32 v2, 1, v2
	v_add_u32_e32 v19, 0x2000, v18
	v_and_or_b32 v3, v3, s0, v4
	v_and_or_b32 v5, v5, 32, v2
	v_lshrrev_b32_e32 v2, 7, v19
	v_and_or_b32 v4, v2, s0, v4
	v_lshl_or_b32 v2, v3, 8, v5
	v_lshl_or_b32 v4, v4, 8, v5
	v_ashrrev_i32_e32 v3, 31, v2
	v_add_u32_e32 v22, 0x10000, v18
	s_addc_u32 s19, s31, s1
	v_lshlrev_b64 v[2:3], 1, v[2:3]
	v_readfirstlane_b32 s0, v22
	v_ashrrev_i32_e32 v5, 31, v4
	v_add_u32_e32 v23, 0x12000, v18
	s_waitcnt lgkmcnt(0)
	s_barrier
	v_lshl_add_u64 v[6:7], s[18:19], 0, v[2:3]
	s_mov_b32 m0, s0
	v_lshlrev_b64 v[4:5], 1, v[4:5]
	v_readfirstlane_b32 s0, v23
	global_load_lds_dwordx4 v[6:7], off
	v_lshl_add_u64 v[8:9], s[18:19], 0, v[4:5]
	s_mov_b32 m0, s0
	v_readfirstlane_b32 s0, v18
	global_load_lds_dwordx4 v[8:9], off
	v_lshl_add_u64 v[10:11], s[20:21], 0, v[2:3]
	s_mov_b32 m0, s0
	v_readfirstlane_b32 s0, v19
	global_load_lds_dwordx4 v[10:11], off
	s_mov_b32 m0, s0
	s_add_u32 s0, s18, 0x10000
	v_add_u32_e32 v20, 0x14000, v18
	v_lshl_add_u64 v[14:15], s[20:21], 0, v[4:5]
	s_addc_u32 s1, s19, 0
	v_readfirstlane_b32 s22, v20
	global_load_lds_dwordx4 v[14:15], off
	v_lshl_add_u64 v[12:13], s[0:1], 0, v[2:3]
	s_mov_b32 m0, s22
	v_add_u32_e32 v21, 0x16000, v18
	global_load_lds_dwordx4 v[12:13], off
	v_lshl_add_u64 v[12:13], s[0:1], 0, v[4:5]
	v_readfirstlane_b32 s0, v21
	s_mov_b32 m0, s0
	s_add_u32 s0, s20, 0x10000
	v_add_u32_e32 v16, 0x4000, v18
	s_addc_u32 s1, s21, 0
	v_readfirstlane_b32 s22, v16
	global_load_lds_dwordx4 v[12:13], off
	v_lshl_add_u64 v[12:13], s[0:1], 0, v[2:3]
	s_mov_b32 m0, s22
	v_add_u32_e32 v17, 0x6000, v18
	global_load_lds_dwordx4 v[12:13], off
	v_lshl_add_u64 v[12:13], s[0:1], 0, v[4:5]
	v_readfirstlane_b32 s0, v17
	s_mov_b32 m0, s0
	s_nop 0
	global_load_lds_dwordx4 v[12:13], off
	v_ashrrev_i32_e32 v12, 8, v0
	v_cmp_eq_u32_e32 vcc, 1, v12
	s_and_saveexec_b64 s[22:23], vcc
	s_cbranch_execz .LBB0_45
	s_barrier

; DI int vbid() { return (int)blockIdx.x * 2 + half_(); }
; DI int vgrid() { return (int)gridDim.x * 2; }
; DI u32x4 pack8(const float* f) { u32x4 o; o.x = pack2(f[0], f[1]); o.y = pack2(f[2], f[3]); o.z = pack2(f[4], f[5]); o.w = pack2(f[6], f[7]); return o; }
; DI void rows_ln(PREF p, int l) {
;     ...
;   for (int row = vbid() * 4 + w; row < T_ / 2; row += vgrid() * 4) {
;     u32x4 raw[2][2];
; #pragma unroll
;     for (int k = 0; k < 2; ++k) {
;       const u16* src = (const u16*)p.fbuf + (size_t)(row + k * (T_ / 2)) * 1024;
;       raw[k][0] = *(const u32x4*)(src + lane * 8);
;       raw[k][1] = *(const u32x4*)(src + 512 + lane * 8);
;     }
; #pragma unroll
;     for (int k = 0; k < 2; ++k) {
;       float v[16];
;       unpack8(raw[k][0], v); unpack8(raw[k][1], v + 8);
;       float s = 0.f;
; #pragma unroll
;       for (int i = 0; i < 16; ++i) s += v[i];
;       const float mu = wsum(s) * (1.f / 1024.f);
;       float sq = 0.f;
; #pragma unroll
;       for (int i = 0; i < 16; ++i) { v[i] -= mu; sq += v[i] * v[i]; }
;       const float rs = rsqrtf(wsum(sq) * (1.f / 1024.f) + 1e-5f);
; #pragma unroll
;       for (int h = 0; h < 2; ++h) {
;         float y[8];
; #pragma unroll
;         for (int j = 0; j < 8; ++j) y[j] = v[h * 8 + j] * rs * gg[h * 8 + j] + bb[h * 8 + j];
;         *(u32x4*)(p.X + (size_t)(row + k * (T_ / 2)) * 1024 + h * 512 + lane * 8) = pack8(y);
;       }
;     }
;   }
.LBB0_55:
	v_lshl_add_u64 v[34:35], v[48:49], 0, v[52:53]
	global_load_dwordx4 v[54:57], v[34:35], off
	global_load_dwordx4 v[74:77], v[34:35], off offset:1024
	v_lshl_add_u64 v[34:35], v[46:47], 0, v[52:53]
	global_load_dwordx4 v[38:41], v[34:35], off offset:-1024
	s_nop 0
	global_load_dwordx4 v[34:37], v[34:35], off
	v_add_u32_e32 v42, s48, v42
	s_movk_i32 s0, 0x3fff
	s_waitcnt vmcnt(3)
	v_lshlrev_b32_e32 v73, 16, v54
	v_and_b32_e32 v72, 0xffff0000, v54
	v_add_f32_e32 v54, 0, v73
	v_lshlrev_b32_e32 v71, 16, v55
	v_add_f32_e32 v54, v54, v72
	v_and_b32_e32 v70, 0xffff0000, v55
	v_add_f32_e32 v54, v54, v71
	v_lshlrev_b32_e32 v69, 16, v56
	v_add_f32_e32 v54, v54, v70
	v_and_b32_e32 v68, 0xffff0000, v56
	v_add_f32_e32 v54, v54, v69
	v_lshlrev_b32_e32 v67, 16, v57
	v_add_f32_e32 v54, v54, v68
	v_and_b32_e32 v66, 0xffff0000, v57
	v_add_f32_e32 v54, v54, v67
	s_waitcnt vmcnt(2)
	v_lshlrev_b32_e32 v65, 16, v74
	v_add_f32_e32 v54, v54, v66
	v_and_b32_e32 v64, 0xffff0000, v74
	v_add_f32_e32 v54, v54, v65
	v_lshlrev_b32_e32 v43, 16, v75
	v_add_f32_e32 v54, v54, v64
	v_and_b32_e32 v0, 0xffff0000, v75
	v_add_f32_e32 v54, v54, v43
	v_add_f32_e32 v74, v54, v0
	v_lshlrev_b32_e32 v55, 16, v76
	v_and_b32_e32 v54, 0xffff0000, v76
	v_add_f32_e32 v74, v74, v55
	v_lshlrev_b32_e32 v57, 16, v77
	v_add_f32_e32 v74, v74, v54
	v_and_b32_e32 v56, 0xffff0000, v77
	v_add_f32_e32 v74, v74, v57
	v_add_f32_e32 v74, v74, v56
	ds_bpermute_b32 v75, v58, v74
	s_waitcnt lgkmcnt(0)
	v_add_f32_e32 v74, v74, v75
	ds_bpermute_b32 v75, v59, v74
	s_waitcnt lgkmcnt(0)
	v_add_f32_e32 v74, v74, v75
	ds_bpermute_b32 v75, v60, v74
	s_waitcnt lgkmcnt(0)
	v_add_f32_e32 v74, v74, v75
	ds_bpermute_b32 v75, v61, v74
	s_waitcnt lgkmcnt(0)
	v_add_f32_e32 v74, v74, v75
	ds_bpermute_b32 v75, v62, v74
	s_waitcnt lgkmcnt(0)
	v_add_f32_e32 v74, v74, v75
	ds_bpermute_b32 v75, v63, v74
	s_waitcnt lgkmcnt(0)
	v_add_f32_e32 v75, v74, v75
	v_fmac_f32_e32 v72, 0xba800000, v75
	v_fmac_f32_e32 v73, 0xba800000, v75
	v_mul_f32_e32 v78, v72, v72
	v_fmac_f32_e32 v78, v73, v73
	v_fmac_f32_e32 v71, 0xba800000, v75
	v_fmac_f32_e32 v78, v71, v71
	v_fmac_f32_e32 v70, 0xba800000, v75
	v_fmac_f32_e32 v78, v70, v70
	v_fmac_f32_e32 v69, 0xba800000, v75
	v_fmac_f32_e32 v78, v69, v69
	v_fmac_f32_e32 v68, 0xba800000, v75
	v_fmac_f32_e32 v78, v68, v68
	v_fmac_f32_e32 v67, 0xba800000, v75
	v_fmac_f32_e32 v78, v67, v67
	v_fmac_f32_e32 v66, 0xba800000, v75
	v_fmac_f32_e32 v78, v66, v66
	v_fmac_f32_e32 v65, 0xba800000, v75
	v_fmac_f32_e32 v78, v65, v65
	v_fmac_f32_e32 v64, 0xba800000, v75
	v_mul_f32_e32 v74, 0x3a800000, v75
	v_fmac_f32_e32 v78, v64, v64
	v_fmac_f32_e32 v43, 0xba800000, v75
	v_fmac_f32_e32 v78, v43, v43
	v_fmac_f32_e32 v0, 0xba800000, v75
	v_pk_add_f32 v[54:55], v[54:55], v[74:75] op_sel_hi:[1,0] neg_lo:[0,1] neg_hi:[0,1]
	v_fmac_f32_e32 v78, v0, v0
	v_pk_mul_f32 v[76:77], v[54:55], v[54:55]
	s_nop 0
	v_add_f32_e32 v75, v77, v78
	v_pk_add_f32 v[56:57], v[56:57], v[74:75] op_sel_hi:[1,0] neg_lo:[0,1] neg_hi:[0,1]
	v_add_f32_e32 v76, v76, v75
	v_pk_mul_f32 v[74:75], v[56:57], v[56:57]
	s_nop 0
	v_add_f32_e32 v75, v75, v76
	v_add_f32_e32 v74, v74, v75
	ds_bpermute_b32 v75, v58, v74
	s_waitcnt lgkmcnt(0)
	v_add_f32_e32 v74, v74, v75
	ds_bpermute_b32 v75, v59, v74
	s_waitcnt lgkmcnt(0)
	v_add_f32_e32 v74, v74, v75
	ds_bpermute_b32 v75, v60, v74
	s_waitcnt lgkmcnt(0)
	v_add_f32_e32 v74, v74, v75
	ds_bpermute_b32 v75, v61, v74
	s_waitcnt lgkmcnt(0)
	v_add_f32_e32 v74, v74, v75
	ds_bpermute_b32 v75, v62, v74
	s_waitcnt lgkmcnt(0)
	v_add_f32_e32 v74, v74, v75
	ds_bpermute_b32 v75, v63, v74
	s_waitcnt lgkmcnt(0)
	v_add_f32_e32 v74, v74, v75
	v_fmamk_f32 v74, v74, 0x3a800000, v171
	v_cmp_gt_f32_e32 vcc, s61, v74
	v_mul_f32_e32 v75, 0x4b800000, v74
	s_nop 0
	v_cndmask_b32_e32 v74, v74, v75, vcc
	v_rsq_f32_e32 v74, v74
	s_nop 0
	v_mul_f32_e32 v75, 0x45800000, v74
	v_cndmask_b32_e32 v76, v74, v75, vcc
	v_mul_f32_e32 v71, v71, v76
	v_mul_f32_e32 v70, v70, v76
	v_mul_f32_e32 v69, v69, v76
	v_mul_f32_e32 v68, v68, v76
	v_mul_f32_e32 v67, v67, v76
	v_lshl_add_u64 v[74:75], v[44:45], 0, v[52:53]
	v_mul_f32_e32 v73, v73, v76
	v_mul_f32_e32 v72, v72, v76
	v_fma_f32 v71, v4, v71, v12
	v_fma_f32 v70, v5, v70, v13
	v_fma_f32 v69, v6, v69, v14
	v_fma_f32 v68, v7, v68, v15
	v_fma_f32 v77, v8, v67, v16
	v_mul_f32_e32 v66, v66, v76
	v_cvt_pk_bf16_f32 v67, v71, v70
	v_mul_f32_e32 v54, v54, v76
	v_fma_f32 v73, v2, v73, v10
	v_fma_f32 v72, v3, v72, v11
	v_fma_f32 v78, v9, v66, v17
	v_cvt_pk_bf16_f32 v66, v73, v72
	v_cvt_pk_bf16_f32 v68, v69, v68
	v_cvt_pk_bf16_f32 v69, v77, v78
	global_store_dwordx4 v[74:75], v[66:69], off offset:-1024
	v_mul_f32_e32 v65, v65, v76
	v_fma_f32 v65, v18, v65, v26
	v_fma_f32 v67, v23, v54, v31
	v_mul_f32_e32 v54, v57, v76
	v_mul_f32_e32 v64, v64, v76
	v_mul_f32_e32 v43, v43, v76
	v_mul_f32_e32 v0, v0, v76
	v_mul_f32_e32 v55, v55, v76
	v_fma_f32 v57, v24, v54, v32
	v_mul_f32_e32 v54, v56, v76
	v_fma_f32 v64, v19, v64, v27
	v_fma_f32 v43, v20, v43, v28
	v_fma_f32 v0, v21, v0, v29
	v_fma_f32 v66, v22, v55, v30
	v_fma_f32 v68, v25, v54, v33
	v_cvt_pk_bf16_f32 v54, v65, v64
	v_cvt_pk_bf16_f32 v55, v43, v0
	v_cvt_pk_bf16_f32 v56, v66, v67
	v_cvt_pk_bf16_f32 v57, v57, v68
	s_waitcnt vmcnt(2)
; DI int vbid() { return (int)blockIdx.x * 2 + half_(); }
; DI int vgrid() { return (int)gridDim.x * 2; }
; DI u32x4 pack8(const float* f) { u32x4 o; o.x = pack2(f[0], f[1]); o.y = pack2(f[2], f[3]); o.z = pack2(f[4], f[5]); o.w = pack2(f[6], f[7]); return o; }
; DI void rows_ln(PREF p, int l) {
;     ...
;   for (int row = vbid() * 4 + w; row < T_ / 2; row += vgrid() * 4) {
;     u32x4 raw[2][2];
; #pragma unroll
;     for (int k = 0; k < 2; ++k) {
;       const u16* src = (const u16*)p.fbuf + (size_t)(row + k * (T_ / 2)) * 1024;
;       raw[k][0] = *(const u32x4*)(src + lane * 8);
;       raw[k][1] = *(const u32x4*)(src + 512 + lane * 8);
;     }
; #pragma unroll
;     for (int k = 0; k < 2; ++k) {
;       float v[16];
;       unpack8(raw[k][0], v); unpack8(raw[k][1], v + 8);
;       float s = 0.f;
; #pragma unroll
;       for (int i = 0; i < 16; ++i) s += v[i];
;       const float mu = wsum(s) * (1.f / 1024.f);
;       float sq = 0.f;
; #pragma unroll
;       for (int i = 0; i < 16; ++i) { v[i] -= mu; sq += v[i] * v[i]; }
;       const float rs = rsqrtf(wsum(sq) * (1.f / 1024.f) + 1e-5f);
; #pragma unroll
;       for (int h = 0; h < 2; ++h) {
;         float y[8];
; #pragma unroll
;         for (int j = 0; j < 8; ++j) y[j] = v[h * 8 + j] * rs * gg[h * 8 + j] + bb[h * 8 + j];
;         *(u32x4*)(p.X + (size_t)(row + k * (T_ / 2)) * 1024 + h * 512 + lane * 8) = pack8(y);
;       }
;     }
;   }
	v_lshlrev_b32_e32 v65, 16, v38
	global_store_dwordx4 v[74:75], v[54:57], off
	v_and_b32_e32 v64, 0xffff0000, v38
	v_lshlrev_b32_e32 v43, 16, v41
	v_lshlrev_b32_e32 v57, 16, v39
	v_and_b32_e32 v56, 0xffff0000, v39
	v_lshlrev_b32_e32 v55, 16, v40
	v_and_b32_e32 v54, 0xffff0000, v40
	s_waitcnt vmcnt(2)
	v_lshlrev_b32_e32 v40, 16, v34
	v_and_b32_e32 v39, 0xffff0000, v34
	v_add_f32_e32 v34, 0, v65
	v_add_f32_e32 v34, v34, v64
	v_add_f32_e32 v34, v34, v57
	v_add_f32_e32 v34, v34, v56
	v_add_f32_e32 v34, v34, v55
	v_add_f32_e32 v34, v34, v54
	v_and_b32_e32 v41, 0xffff0000, v41
	v_add_f32_e32 v34, v34, v43
	v_add_f32_e32 v34, v34, v41
	v_add_f32_e32 v34, v34, v40
	v_lshlrev_b32_e32 v38, 16, v35
	v_add_f32_e32 v34, v34, v39
	v_and_b32_e32 v0, 0xffff0000, v35
	v_add_f32_e32 v34, v34, v38
	v_add_f32_e32 v68, v34, v0
	v_lshlrev_b32_e32 v35, 16, v36
	v_and_b32_e32 v34, 0xffff0000, v36
	v_add_f32_e32 v36, v68, v35
	v_lshlrev_b32_e32 v67, 16, v37
	v_add_f32_e32 v36, v36, v34
	v_and_b32_e32 v66, 0xffff0000, v37
	v_add_f32_e32 v36, v36, v67
	v_add_f32_e32 v36, v36, v66
	ds_bpermute_b32 v37, v58, v36
	s_waitcnt lgkmcnt(0)
	v_add_f32_e32 v36, v36, v37
	ds_bpermute_b32 v37, v59, v36
	s_waitcnt lgkmcnt(0)
	v_add_f32_e32 v36, v36, v37
	ds_bpermute_b32 v37, v60, v36
	s_waitcnt lgkmcnt(0)
	v_add_f32_e32 v36, v36, v37
	ds_bpermute_b32 v37, v61, v36
	s_waitcnt lgkmcnt(0)
	v_add_f32_e32 v36, v36, v37
	ds_bpermute_b32 v37, v62, v36
	s_waitcnt lgkmcnt(0)
	v_add_f32_e32 v36, v36, v37
	ds_bpermute_b32 v37, v63, v36
	s_waitcnt lgkmcnt(0)
	v_add_f32_e32 v37, v36, v37
	v_fmac_f32_e32 v64, 0xba800000, v37
	v_fmac_f32_e32 v65, 0xba800000, v37
	v_mul_f32_e32 v70, v64, v64
	v_fmac_f32_e32 v70, v65, v65
	v_fmac_f32_e32 v57, 0xba800000, v37
	v_fmac_f32_e32 v70, v57, v57
	v_fmac_f32_e32 v56, 0xba800000, v37
	v_fmac_f32_e32 v70, v56, v56
	v_fmac_f32_e32 v55, 0xba800000, v37
	v_fmac_f32_e32 v70, v55, v55
	v_fmac_f32_e32 v54, 0xba800000, v37
	v_fmac_f32_e32 v70, v54, v54
	v_fmac_f32_e32 v43, 0xba800000, v37
	v_fmac_f32_e32 v70, v43, v43
	v_fmac_f32_e32 v41, 0xba800000, v37
	v_fmac_f32_e32 v70, v41, v41
	v_fmac_f32_e32 v40, 0xba800000, v37
	v_fmac_f32_e32 v70, v40, v40
	v_fmac_f32_e32 v39, 0xba800000, v37
	v_mul_f32_e32 v36, 0x3a800000, v37
	v_fmac_f32_e32 v70, v39, v39
	v_fmac_f32_e32 v38, 0xba800000, v37
	v_fmac_f32_e32 v70, v38, v38
	v_fmac_f32_e32 v0, 0xba800000, v37
	v_pk_add_f32 v[34:35], v[34:35], v[36:37] op_sel_hi:[1,0] neg_lo:[0,1] neg_hi:[0,1]
	v_fmac_f32_e32 v70, v0, v0
	v_pk_mul_f32 v[68:69], v[34:35], v[34:35]
	s_nop 0
	v_add_f32_e32 v37, v69, v70
	v_add_f32_e32 v68, v68, v37
	v_pk_add_f32 v[36:37], v[66:67], v[36:37] op_sel_hi:[1,0] neg_lo:[0,1] neg_hi:[0,1]
	s_nop 0
	v_pk_mul_f32 v[66:67], v[36:37], v[36:37]
	s_nop 0
	v_add_f32_e32 v67, v67, v68
	v_add_f32_e32 v66, v66, v67
	ds_bpermute_b32 v67, v58, v66
	v_lshl_add_u64 v[68:69], v[50:51], 0, v[52:53]
	v_lshl_add_u64 v[52:53], v[52:53], 0, s[18:19]
	s_waitcnt lgkmcnt(0)
	v_add_f32_e32 v66, v66, v67
	ds_bpermute_b32 v67, v59, v66
	s_waitcnt lgkmcnt(0)
	v_add_f32_e32 v66, v66, v67
	ds_bpermute_b32 v67, v60, v66
	s_waitcnt lgkmcnt(0)
	v_add_f32_e32 v66, v66, v67
	ds_bpermute_b32 v67, v61, v66
	s_waitcnt lgkmcnt(0)
	v_add_f32_e32 v66, v66, v67
	ds_bpermute_b32 v67, v62, v66
	s_waitcnt lgkmcnt(0)
	v_add_f32_e32 v66, v66, v67
	ds_bpermute_b32 v67, v63, v66
	s_waitcnt lgkmcnt(0)
	v_add_f32_e32 v66, v66, v67
	v_fmamk_f32 v66, v66, 0x3a800000, v171
	v_cmp_gt_f32_e32 vcc, s61, v66
	v_mul_f32_e32 v67, 0x4b800000, v66
	s_nop 0
	v_cndmask_b32_e32 v66, v66, v67, vcc
	v_rsq_f32_e32 v66, v66
	s_nop 0
	v_mul_f32_e32 v67, 0x45800000, v66
	v_cndmask_b32_e32 v66, v66, v67, vcc
	v_mul_f32_e32 v57, v57, v66
	v_mul_f32_e32 v43, v43, v66
	v_fma_f32 v57, v4, v57, v12
	v_mul_f32_e32 v56, v56, v66
	v_mul_f32_e32 v55, v55, v66
	v_fma_f32 v43, v8, v43, v16
	v_mul_f32_e32 v41, v41, v66
	v_mul_f32_e32 v34, v34, v66
	v_mul_f32_e32 v65, v65, v66
	v_mul_f32_e32 v64, v64, v66
	v_fma_f32 v56, v5, v56, v13
	v_fma_f32 v67, v6, v55, v14
	v_mul_f32_e32 v54, v54, v66
	v_fma_f32 v41, v9, v41, v17
	v_cvt_pk_bf16_f32 v55, v57, v56
	v_cvt_pk_bf16_f32 v57, v43, v41
	v_fma_f32 v43, v23, v34, v31
	v_mul_f32_e32 v34, v37, v66
	v_cmp_lt_i32_e32 vcc, s0, v42
	v_fma_f32 v65, v2, v65, v10
	v_fma_f32 v64, v3, v64, v11
	v_fma_f32 v70, v7, v54, v15
	v_cvt_pk_bf16_f32 v54, v65, v64
	v_mul_f32_e32 v40, v40, v66
	v_mul_f32_e32 v39, v39, v66
	v_mul_f32_e32 v38, v38, v66
	v_mul_f32_e32 v0, v0, v66
	v_mul_f32_e32 v35, v35, v66
	v_fma_f32 v37, v24, v34, v32
	v_mul_f32_e32 v34, v36, v66
	s_or_b64 s[12:13], vcc, s[12:13]
	v_cvt_pk_bf16_f32 v56, v67, v70
	global_store_dwordx4 v[68:69], v[54:57], off
	v_fma_f32 v40, v18, v40, v26
	v_fma_f32 v39, v19, v39, v27
	v_fma_f32 v38, v20, v38, v28
	v_fma_f32 v0, v21, v0, v29
	v_fma_f32 v41, v22, v35, v30
	v_fma_f32 v54, v25, v34, v33
	v_cvt_pk_bf16_f32 v34, v40, v39
	v_cvt_pk_bf16_f32 v35, v38, v0
	v_cvt_pk_bf16_f32 v36, v41, v43
	v_cvt_pk_bf16_f32 v37, v37, v54
	global_store_dwordx4 v[68:69], v[34:37], off offset:1024
	s_andn2_b64 exec, exec, s[12:13]
	s_cbranch_execnz .LBB0_55

; DI u32x4 pack8(const float* f) { u32x4 o; o.x = pack2(f[0], f[1]); o.y = pack2(f[2], f[3]); o.z = pack2(f[4], f[5]); o.w = pack2(f[6], f[7]); return o; }
; template <int AI, int BJ>
; DI void f1_proc(PREF p, const f32x4 (&acc)[2][2][4][2], int mt, int dt, float* Cs, const float4 (&xa)[4], const float4 (&xb)[4]) {
;     ...
;   stage_q<AI, BJ>(acc, Cs);
; #pragma unroll
;   for (int q = 0; q < 4; ++q) {
;     int r = (t >> 4) + 32 * q;
;     float v[8]; ld8(Cs + r * CST + c, v);
;     float4 a = xa[q], b = xb[q];
;     float y[8] = {alpha * a.x + v[0], alpha * a.y + v[1], alpha * a.z + v[2], alpha * a.w + v[3],
;                   alpha * b.x + v[4], alpha * b.y + v[5], alpha * b.z + v[6], alpha * b.w + v[7]};
;     *(u32x4*)((u16*)p.fbuf + (size_t)(row0 + r) * 1024 + col0 + c) = pack8(y);
;   }
; DI void f1_phase(PREF p, int l, unsigned char* lds_all) {
;     ...
;   for (int k = 0;; ++k) {
;     int mt, dt;
;     if (!xcd_tile256(k, 4, mt, dt)) break;
.LBB0_62:
	v_mov_b32_e32 v68, v168
	s_add_i32 s34, s34, 1
	v_lshlrev_b32_e32 v0, 3, v68
	v_and_b32_e32 v69, 0x78, v0
	v_mov_b32_e32 v0, v168
	s_waitcnt lgkmcnt(0)
	s_barrier
	s_nop 0
	v_and_b32_e32 v66, 15, v0
	v_lshrrev_b32_e32 v67, 2, v0
	v_lshlrev_b32_e32 v0, 1, v0
	v_lshlrev_b32_e32 v66, 2, v66
	v_and_b32_e32 v67, 0xfffffcc, v67
	v_and_or_b32 v0, v0, s89, v66
	v_mad_u64_u32 v[66:67], s[0:1], v67, s92, v[0:1]
	v_add_u32_e32 v0, 0x400, v66
	ds_write2_b32 v66, v22, v30 offset1:16
	ds_write2_b32 v66, v23, v31 offset0:132 offset1:148
	ds_write2_b32 v0, v24, v32 offset0:8 offset1:24
	ds_write2_b32 v0, v25, v33 offset0:140 offset1:156
	v_add_u32_e32 v0, 0x2000, v66
	ds_write2_b32 v0, v18, v26 offset0:64 offset1:80
	ds_write2_b32 v0, v19, v27 offset0:196 offset1:212
	v_add_u32_e32 v0, 0x2400, v66
	ds_write2_b32 v0, v20, v28 offset0:72 offset1:88
	ds_write2_b32 v0, v21, v29 offset0:204 offset1:220
	v_add_u32_e32 v0, 0x4000, v66
	ds_write2_b32 v0, v10, v14 offset0:128 offset1:144
	v_add_u32_e32 v0, 0x4400, v66
	ds_write2_b32 v0, v11, v15 offset0:4 offset1:20
	ds_write2_b32 v0, v12, v16 offset0:136 offset1:152
	v_add_u32_e32 v0, 0x4800, v66
	ds_write2_b32 v0, v13, v17 offset0:12 offset1:28
	v_add_u32_e32 v0, 0x6000, v66
	ds_write2_b32 v0, v2, v6 offset0:192 offset1:208
	v_add_u32_e32 v0, 0x6400, v66
	ds_write2_b32 v0, v3, v7 offset0:68 offset1:84
	ds_write2_b32 v0, v4, v8 offset0:200 offset1:216
	v_add_u32_e32 v0, 0x6800, v66
	ds_write2_b32 v0, v5, v9 offset0:76 offset1:92
	v_ashrrev_i32_e32 v0, 4, v68
	v_mul_lo_u32 v2, v0, s92
	s_waitcnt lgkmcnt(0)
	s_barrier
	v_lshl_add_u32 v14, v69, 2, v2
	ds_read_b128 v[2:5], v14
	ds_read_b128 v[6:9], v14 offset:16
	v_add_u32_e32 v10, s35, v0
	v_ashrrev_i32_e32 v11, 31, v10
	v_lshlrev_b32_e32 v0, 1, v69
	s_waitcnt vmcnt(6) lgkmcnt(1)
	v_fmamk_f32 v2, v62, 0x3fd744fd, v2
	v_fmamk_f32 v3, v63, 0x3fd744fd, v3
	v_fmamk_f32 v4, v64, 0x3fd744fd, v4
	s_waitcnt lgkmcnt(0)
	v_fmamk_f32 v6, v38, 0x3fd744fd, v6
	v_fmamk_f32 v7, v39, 0x3fd744fd, v7
	v_fmac_f32_e32 v5, 0x3fd744fd, v65
	v_cvt_pk_bf16_f32 v2, v2, v3
	v_cvt_pk_bf16_f32 v3, v4, v5
	v_cvt_pk_bf16_f32 v4, v6, v7
	v_lshlrev_b64 v[6:7], 11, v[10:11]
	v_fmamk_f32 v8, v40, 0x3fd744fd, v8
	v_fmac_f32_e32 v9, 0x3fd744fd, v41
	v_lshl_add_u64 v[12:13], s[22:23], 0, v[6:7]
	v_cvt_pk_bf16_f32 v5, v8, v9
	ds_read_b128 v[6:9], v14 offset:16896
	v_lshl_add_u64 v[12:13], v[12:13], 0, v[0:1]
	global_store_dwordx4 v[12:13], v[2:5], off offset:256
	ds_read_b128 v[2:5], v14 offset:16912
	s_mul_i32 s0, s34, s45
	s_waitcnt vmcnt(6) lgkmcnt(1)
	v_fmamk_f32 v6, v50, 0x3fd744fd, v6
	v_fmamk_f32 v7, v51, 0x3fd744fd, v7
	v_fmamk_f32 v8, v52, 0x3fd744fd, v8
	s_waitcnt vmcnt(5) lgkmcnt(0)
	v_fmamk_f32 v11, v34, 0x3fd744fd, v2
	v_cvt_pk_bf16_f32 v2, v6, v7
	v_add_u32_e32 v6, 32, v10
	v_fmamk_f32 v12, v35, 0x3fd744fd, v3
	v_fmamk_f32 v13, v36, 0x3fd744fd, v4
	v_fmac_f32_e32 v5, 0x3fd744fd, v37
	v_ashrrev_i32_e32 v7, 31, v6
	v_cvt_pk_bf16_f32 v4, v11, v12
	v_cvt_pk_bf16_f32 v5, v13, v5
	v_lshlrev_b64 v[12:13], 11, v[6:7]
	v_fmac_f32_e32 v9, 0x3fd744fd, v53
	v_lshl_add_u64 v[12:13], s[22:23], 0, v[12:13]
	v_cvt_pk_bf16_f32 v3, v8, v9
	ds_read_b128 v[6:9], v14 offset:33792
	v_lshl_add_u64 v[12:13], v[12:13], 0, v[0:1]
	global_store_dwordx4 v[12:13], v[2:5], off offset:256
	ds_read_b128 v[2:5], v14 offset:33808
	s_add_i32 s9, s0, s46
	s_waitcnt vmcnt(5) lgkmcnt(1)
	v_fmamk_f32 v6, v54, 0x3fd744fd, v6
	v_fmamk_f32 v7, v55, 0x3fd744fd, v7
	v_fmamk_f32 v8, v56, 0x3fd744fd, v8
	s_waitcnt vmcnt(4) lgkmcnt(0)
	v_fmamk_f32 v11, v42, 0x3fd744fd, v2
	v_cvt_pk_bf16_f32 v2, v6, v7
	v_add_u32_e32 v6, 64, v10
	v_fmamk_f32 v12, v43, 0x3fd744fd, v3
	v_fmamk_f32 v13, v44, 0x3fd744fd, v4
	v_fmac_f32_e32 v5, 0x3fd744fd, v45
	v_ashrrev_i32_e32 v7, 31, v6
	v_cvt_pk_bf16_f32 v4, v11, v12
	v_cvt_pk_bf16_f32 v5, v13, v5
	v_lshlrev_b64 v[12:13], 11, v[6:7]
	v_fmac_f32_e32 v9, 0x3fd744fd, v57
	v_lshl_add_u64 v[12:13], s[22:23], 0, v[12:13]
	v_cvt_pk_bf16_f32 v3, v8, v9
	ds_read_b128 v[6:9], v14 offset:50688
	v_lshl_add_u64 v[12:13], v[12:13], 0, v[0:1]
	global_store_dwordx4 v[12:13], v[2:5], off offset:256
	ds_read_b128 v[2:5], v14 offset:50704
	s_cmp_lt_u32 s9, 64
	s_waitcnt vmcnt(4) lgkmcnt(1)
	v_fmamk_f32 v6, v58, 0x3fd744fd, v6
	v_fmamk_f32 v7, v59, 0x3fd744fd, v7
	v_fmamk_f32 v8, v60, 0x3fd744fd, v8
	s_waitcnt vmcnt(3) lgkmcnt(0)
	v_fmamk_f32 v11, v46, 0x3fd744fd, v2
	v_cvt_pk_bf16_f32 v2, v6, v7
	v_add_u32_e32 v6, 0x60, v10
	v_ashrrev_i32_e32 v7, 31, v6
	v_lshlrev_b64 v[6:7], 11, v[6:7]
	v_lshl_add_u64 v[6:7], s[22:23], 0, v[6:7]
	v_fmac_f32_e32 v5, 0x3fd744fd, v49
	v_lshl_add_u64 v[6:7], v[6:7], 0, v[0:1]
	v_fmac_f32_e32 v9, 0x3fd744fd, v61
	v_fmamk_f32 v12, v47, 0x3fd744fd, v3
	v_fmamk_f32 v13, v48, 0x3fd744fd, v4
	v_cvt_pk_bf16_f32 v3, v8, v9
	v_cvt_pk_bf16_f32 v4, v11, v12
	v_cvt_pk_bf16_f32 v5, v13, v5
	global_store_dwordx4 v[6:7], v[2:5], off offset:256
	s_cbranch_scc0 .LBB0_84

; DI u32x4 pack8(const float* f) { u32x4 o; o.x = pack2(f[0], f[1]); o.y = pack2(f[2], f[3]); o.z = pack2(f[4], f[5]); o.w = pack2(f[6], f[7]); return o; }
; template <int AI, int BJ>
; DI void f1_load(PREF p, int l, int mt, int dt, float4 (&xa)[4], float4 (&xb)[4]) {
;     ...
;   if (l == 0) {
; #pragma unroll
;     for (int q = 0; q < 4; ++q) {
;       const float4* xs = (const float4*)(p.x + (size_t)(row0 + (t >> 4) + 32 * q) * 1024 + col0 + c);
;       xa[q] = xs[0]; xb[q] = xs[1];
;     }
;   } else {
; #pragma unroll
;     for (int q = 0; q < 4; ++q) {
;       float f[8]; unpack8(*(const u32x4*)(p.X + (size_t)(row0 + (t >> 4) + 32 * q) * 1024 + col0 + c), f);
;       xa[q] = make_float4(f[0], f[1], f[2], f[3]); xb[q] = make_float4(f[4], f[5], f[6], f[7]);
;     }
;   }
; template <int AI, int BJ>
; DI void f1_proc(PREF p, const f32x4 (&acc)[2][2][4][2], int mt, int dt, float* Cs, const float4 (&xa)[4], const float4 (&xb)[4]) {
;     ...
;   stage_q<AI, BJ>(acc, Cs);
; #pragma unroll
;   for (int q = 0; q < 4; ++q) {
;     int r = (t >> 4) + 32 * q;
;     float v[8]; ld8(Cs + r * CST + c, v);
;     float4 a = xa[q], b = xb[q];
;     float y[8] = {alpha * a.x + v[0], alpha * a.y + v[1], alpha * a.z + v[2], alpha * a.w + v[3],
;                   alpha * b.x + v[4], alpha * b.y + v[5], alpha * b.z + v[6], alpha * b.w + v[7]};
;     *(u32x4*)((u16*)p.fbuf + (size_t)(row0 + r) * 1024 + col0 + c) = pack8(y);
;   }
.LBB0_72:
	v_mov_b32_e32 v162, v168
	s_lshl_b64 s[24:25], s[20:21], 1
	v_lshlrev_b32_e32 v0, 3, v162
	v_and_b32_e32 v166, 0x78, v0
	v_mov_b32_e32 v0, v168
	s_waitcnt lgkmcnt(0)
	s_barrier
	s_add_u32 s22, s16, s24
	v_and_b32_e32 v164, 15, v0
	v_lshrrev_b32_e32 v165, 2, v0
	v_lshlrev_b32_e32 v0, 1, v0
	v_lshlrev_b32_e32 v164, 2, v164
	v_and_b32_e32 v165, 0xfffffcc, v165
	v_and_or_b32 v0, v0, s89, v164
	v_mad_u64_u32 v[164:165], s[0:1], v165, s92, v[0:1]
	v_add_u32_e32 v0, 0x400, v164
	ds_write2_b32 v164, v118, v126 offset1:16
	ds_write2_b32 v164, v119, v127 offset0:132 offset1:148
	ds_write2_b32 v0, v120, v128 offset0:8 offset1:24
	ds_write2_b32 v0, v121, v129 offset0:140 offset1:156
	v_add_u32_e32 v0, 0x2000, v164
	ds_write2_b32 v0, v114, v122 offset0:64 offset1:80
	ds_write2_b32 v0, v115, v123 offset0:196 offset1:212
	v_add_u32_e32 v0, 0x2400, v164
	ds_write2_b32 v0, v116, v124 offset0:72 offset1:88
	ds_write2_b32 v0, v117, v125 offset0:204 offset1:220
	v_add_u32_e32 v0, 0x4000, v164
	ds_write2_b32 v0, v106, v110 offset0:128 offset1:144
	v_add_u32_e32 v0, 0x4400, v164
	ds_write2_b32 v0, v107, v111 offset0:4 offset1:20
	ds_write2_b32 v0, v108, v112 offset0:136 offset1:152
	v_add_u32_e32 v0, 0x4800, v164
	ds_write2_b32 v0, v109, v113 offset0:12 offset1:28
	v_add_u32_e32 v0, 0x6000, v164
	ds_write2_b32 v0, v98, v102 offset0:192 offset1:208
	v_add_u32_e32 v0, 0x6400, v164
	ds_write2_b32 v0, v99, v103 offset0:68 offset1:84
	ds_write2_b32 v0, v100, v104 offset0:200 offset1:216
	v_add_u32_e32 v0, 0x6800, v164
	v_ashrrev_i32_e32 v108, 4, v162
	ds_write2_b32 v0, v101, v105 offset0:76 offset1:92
	v_mul_lo_u32 v0, v108, s92
	s_waitcnt lgkmcnt(0)
	s_barrier
	v_lshl_add_u32 v112, v166, 2, v0
	s_waitcnt vmcnt(0)
	ds_read_b128 v[98:101], v112
	ds_read_b128 v[102:105], v112 offset:16
	v_add_u32_e32 v108, s35, v108
	s_addc_u32 s23, s17, s25
	v_lshlrev_b32_e32 v0, 1, v166
	v_ashrrev_i32_e32 v109, 31, v108
	v_lshl_add_u64 v[106:107], s[22:23], 0, v[0:1]
	s_waitcnt lgkmcnt(1)
	v_fmamk_f32 v0, v150, 0x3fd744fd, v98
	v_fmamk_f32 v98, v151, 0x3fd744fd, v99
	v_fmamk_f32 v99, v152, 0x3fd744fd, v100
	v_fmac_f32_e32 v101, 0x3fd744fd, v153
	s_waitcnt lgkmcnt(0)
	v_fmamk_f32 v100, v130, 0x3fd744fd, v102
	v_lshlrev_b64 v[110:111], 11, v[108:109]
	v_fmamk_f32 v102, v131, 0x3fd744fd, v103
	v_fmamk_f32 v103, v132, 0x3fd744fd, v104
	v_fmac_f32_e32 v105, 0x3fd744fd, v133
	v_cvt_pk_bf16_f32 v98, v0, v98
	v_cvt_pk_bf16_f32 v99, v99, v101
	v_cvt_pk_bf16_f32 v100, v100, v102
	v_cvt_pk_bf16_f32 v101, v103, v105
	v_lshl_add_u64 v[110:111], v[106:107], 0, v[110:111]
	ds_read_b128 v[102:105], v112 offset:16896
	global_store_dwordx4 v[110:111], v[98:101], off
	ds_read_b128 v[98:101], v112 offset:16912
	s_and_b64 vcc, exec, s[8:9]
	s_waitcnt lgkmcnt(1)
	v_fmamk_f32 v0, v142, 0x3fd744fd, v102
	v_fmamk_f32 v102, v143, 0x3fd744fd, v103
	s_waitcnt lgkmcnt(0)
	v_fmamk_f32 v110, v136, 0x3fd744fd, v100
	v_fmac_f32_e32 v101, 0x3fd744fd, v137
	v_cvt_pk_bf16_f32 v101, v110, v101
	v_add_u32_e32 v110, 32, v108
	v_ashrrev_i32_e32 v111, 31, v110
	v_lshlrev_b64 v[110:111], 11, v[110:111]
	v_fmamk_f32 v103, v144, 0x3fd744fd, v104
	v_fmac_f32_e32 v105, 0x3fd744fd, v145
	v_fmamk_f32 v104, v134, 0x3fd744fd, v98
	v_fmamk_f32 v109, v135, 0x3fd744fd, v99
	v_cvt_pk_bf16_f32 v98, v0, v102
	v_cvt_pk_bf16_f32 v99, v103, v105
	v_cvt_pk_bf16_f32 v100, v104, v109
	v_lshl_add_u64 v[110:111], v[106:107], 0, v[110:111]
	ds_read_b128 v[102:105], v112 offset:33792
	global_store_dwordx4 v[110:111], v[98:101], off
	ds_read_b128 v[98:101], v112 offset:33808
	s_waitcnt lgkmcnt(1)
	v_fmamk_f32 v0, v154, 0x3fd744fd, v102
	v_fmamk_f32 v102, v155, 0x3fd744fd, v103
	s_waitcnt lgkmcnt(0)
	v_fmamk_f32 v110, v140, 0x3fd744fd, v100
	v_fmac_f32_e32 v101, 0x3fd744fd, v141
	v_cvt_pk_bf16_f32 v101, v110, v101
	v_add_u32_e32 v110, 64, v108
	v_ashrrev_i32_e32 v111, 31, v110
	v_fmamk_f32 v103, v156, 0x3fd744fd, v104
	v_fmac_f32_e32 v105, 0x3fd744fd, v157
	v_fmamk_f32 v104, v138, 0x3fd744fd, v98
	v_lshlrev_b64 v[110:111], 11, v[110:111]
	v_fmamk_f32 v109, v139, 0x3fd744fd, v99
	v_cvt_pk_bf16_f32 v98, v0, v102
	v_cvt_pk_bf16_f32 v99, v103, v105
	v_cvt_pk_bf16_f32 v100, v104, v109
	ds_read_b128 v[102:105], v112 offset:50688
	v_lshl_add_u64 v[110:111], v[106:107], 0, v[110:111]
	global_store_dwordx4 v[110:111], v[98:101], off
	ds_read_b128 v[98:101], v112 offset:50704
	s_waitcnt lgkmcnt(1)
	v_fmamk_f32 v0, v158, 0x3fd744fd, v102
	v_fmamk_f32 v102, v159, 0x3fd744fd, v103
	v_fmamk_f32 v103, v160, 0x3fd744fd, v104
	s_waitcnt lgkmcnt(0)
	v_fmamk_f32 v104, v146, 0x3fd744fd, v98
	v_cvt_pk_bf16_f32 v98, v0, v102
	v_add_u32_e32 v102, 0x60, v108
	v_fmac_f32_e32 v105, 0x3fd744fd, v161
	v_fmamk_f32 v109, v147, 0x3fd744fd, v99
	v_cvt_pk_bf16_f32 v99, v103, v105
	v_ashrrev_i32_e32 v103, 31, v102
	v_lshlrev_b64 v[102:103], 11, v[102:103]
	v_fmac_f32_e32 v101, 0x3fd744fd, v149
	v_lshl_add_u64 v[102:103], v[106:107], 0, v[102:103]
	v_mov_b32_e32 v0, v168
	v_fmamk_f32 v110, v148, 0x3fd744fd, v100
	v_cvt_pk_bf16_f32 v100, v104, v109
	v_cvt_pk_bf16_f32 v101, v110, v101
	global_store_dwordx4 v[102:103], v[98:101], off
	s_nop 1
	v_lshlrev_b32_e32 v98, 3, v0
	v_ashrrev_i32_e32 v0, 4, v0
	v_add_u32_e32 v130, s35, v0
	v_and_b32_e32 v132, 0x78, v98
	v_ashrrev_i32_e32 v131, 31, v130
	s_cbranch_vccnz .LBB0_81
; template <int AI, int BJ>
; DI void f1_load(PREF p, int l, int mt, int dt, float4 (&xa)[4], float4 (&xb)[4]) {
;     ...
;   } else {
; #pragma unroll
;     for (int q = 0; q < 4; ++q) {
;       float f[8]; unpack8(*(const u32x4*)(p.X + (size_t)(row0 + (t >> 4) + 32 * q) * 1024 + col0 + c), f);
;       xa[q] = make_float4(f[0], f[1], f[2], f[3]); xb[q] = make_float4(f[4], f[5], f[6], f[7]);
;     }
;   }
	s_add_u32 s0, s12, s24
	s_addc_u32 s1, s13, s25
	v_lshlrev_b32_e32 v0, 1, v132
	v_lshl_add_u64 v[98:99], s[0:1], 0, v[0:1]
	v_lshlrev_b64 v[100:101], 11, v[130:131]
	v_lshl_add_u64 v[102:103], v[98:99], 0, v[100:101]
	v_add_co_u32_e32 v104, vcc, s88, v102
	s_mov_b32 s0, 0x20000
	s_nop 0
	v_addc_co_u32_e32 v105, vcc, 0, v103, vcc
	global_load_dwordx4 v[98:101], v[102:103], off offset:256
	global_load_dwordx4 v[106:109], v[104:105], off offset:256
	v_add_co_u32_e32 v104, vcc, s0, v102
	s_mov_b32 s0, 0x30000
	s_nop 0
	v_addc_co_u32_e32 v105, vcc, 0, v103, vcc
	v_add_co_u32_e32 v102, vcc, s0, v102
	global_load_dwordx4 v[110:113], v[104:105], off offset:256
	s_nop 0
	v_addc_co_u32_e32 v103, vcc, 0, v103, vcc
	global_load_dwordx4 v[134:137], v[102:103], off offset:256
	s_waitcnt vmcnt(3)
	v_and_b32_e32 v127, 0xffff0000, v98
	v_lshlrev_b32_e32 v126, 16, v98
	v_and_b32_e32 v129, 0xffff0000, v99
	v_lshlrev_b32_e32 v128, 16, v99
	v_and_b32_e32 v103, 0xffff0000, v100
	v_lshlrev_b32_e32 v102, 16, v100
	v_and_b32_e32 v105, 0xffff0000, v101
	v_lshlrev_b32_e32 v104, 16, v101
	s_waitcnt vmcnt(2)
	v_and_b32_e32 v115, 0xffff0000, v106
	v_lshlrev_b32_e32 v114, 16, v106
	v_and_b32_e32 v117, 0xffff0000, v107
	v_lshlrev_b32_e32 v116, 16, v107
	v_and_b32_e32 v99, 0xffff0000, v108
	v_lshlrev_b32_e32 v98, 16, v108
	v_and_b32_e32 v101, 0xffff0000, v109
	v_lshlrev_b32_e32 v100, 16, v109
	s_waitcnt vmcnt(1)
	v_and_b32_e32 v119, 0xffff0000, v110
	v_lshlrev_b32_e32 v118, 16, v110
	v_and_b32_e32 v121, 0xffff0000, v111
	v_lshlrev_b32_e32 v120, 16, v111
	v_and_b32_e32 v107, 0xffff0000, v112
	v_lshlrev_b32_e32 v106, 16, v112
	v_and_b32_e32 v109, 0xffff0000, v113
	v_lshlrev_b32_e32 v108, 16, v113
	s_waitcnt vmcnt(0)
	v_and_b32_e32 v123, 0xffff0000, v134
	v_lshlrev_b32_e32 v122, 16, v134
	v_and_b32_e32 v125, 0xffff0000, v135
	v_lshlrev_b32_e32 v124, 16, v135
	v_and_b32_e32 v111, 0xffff0000, v136
	v_lshlrev_b32_e32 v110, 16, v136
	v_and_b32_e32 v113, 0xffff0000, v137
	v_lshlrev_b32_e32 v112, 16, v137
	s_cbranch_execnz .LBB0_75

; DI u32x4 pack8(const float* f) { u32x4 o; o.x = pack2(f[0], f[1]); o.y = pack2(f[2], f[3]); o.z = pack2(f[4], f[5]); o.w = pack2(f[6], f[7]); return o; }
; template <int AI, int BJ>
; DI void f1_load(PREF p, int l, int mt, int dt, float4 (&xa)[4], float4 (&xb)[4]) {
;     ...
;   if (l == 0) {
; #pragma unroll
;     for (int q = 0; q < 4; ++q) {
;       const float4* xs = (const float4*)(p.x + (size_t)(row0 + (t >> 4) + 32 * q) * 1024 + col0 + c);
;       xa[q] = xs[0]; xb[q] = xs[1];
;     }
;   } else {
; #pragma unroll
;     for (int q = 0; q < 4; ++q) {
;       float f[8]; unpack8(*(const u32x4*)(p.X + (size_t)(row0 + (t >> 4) + 32 * q) * 1024 + col0 + c), f);
;       xa[q] = make_float4(f[0], f[1], f[2], f[3]); xb[q] = make_float4(f[4], f[5], f[6], f[7]);
;     }
;   }
; template <int AI, int BJ>
; DI void f1_proc(PREF p, const f32x4 (&acc)[2][2][4][2], int mt, int dt, float* Cs, const float4 (&xa)[4], const float4 (&xb)[4]) {
;     ...
;   stage_q<AI, BJ>(acc, Cs);
; #pragma unroll
;   for (int q = 0; q < 4; ++q) {
;     int r = (t >> 4) + 32 * q;
;     float v[8]; ld8(Cs + r * CST + c, v);
;     float4 a = xa[q], b = xb[q];
;     float y[8] = {alpha * a.x + v[0], alpha * a.y + v[1], alpha * a.z + v[2], alpha * a.w + v[3],
;                   alpha * b.x + v[4], alpha * b.y + v[5], alpha * b.z + v[6], alpha * b.w + v[7]};
;     *(u32x4*)((u16*)p.fbuf + (size_t)(row0 + r) * 1024 + col0 + c) = pack8(y);
;   }
.LBB0_75:
	v_mov_b32_e32 v132, v168
	s_and_b64 vcc, exec, s[8:9]
	v_lshlrev_b32_e32 v0, 3, v132
	v_and_b32_e32 v133, 0x78, v0
	v_mov_b32_e32 v0, v168
	s_waitcnt lgkmcnt(0)
	s_barrier
	s_nop 0
	v_and_b32_e32 v130, 15, v0
	v_lshrrev_b32_e32 v131, 2, v0
	v_lshlrev_b32_e32 v0, 1, v0
	v_lshlrev_b32_e32 v130, 2, v130
	v_and_b32_e32 v131, 0xfffffcc, v131
	v_and_or_b32 v0, v0, s89, v130
	v_mad_u64_u32 v[130:131], s[0:1], v131, s92, v[0:1]
	v_add_u32_e32 v0, 0x400, v130
	ds_write2_b32 v130, v86, v94 offset1:16
	ds_write2_b32 v130, v87, v95 offset0:132 offset1:148
	ds_write2_b32 v0, v88, v96 offset0:8 offset1:24
	ds_write2_b32 v0, v89, v97 offset0:140 offset1:156
	v_add_u32_e32 v0, 0x2000, v130
	ds_write2_b32 v0, v82, v90 offset0:64 offset1:80
	ds_write2_b32 v0, v83, v91 offset0:196 offset1:212
	v_add_u32_e32 v0, 0x2400, v130
	ds_write2_b32 v0, v84, v92 offset0:72 offset1:88
	ds_write2_b32 v0, v85, v93 offset0:204 offset1:220
	v_add_u32_e32 v0, 0x4000, v130
	ds_write2_b32 v0, v74, v78 offset0:128 offset1:144
	v_add_u32_e32 v0, 0x4400, v130
	ds_write2_b32 v0, v75, v79 offset0:4 offset1:20
	ds_write2_b32 v0, v76, v80 offset0:136 offset1:152
	v_add_u32_e32 v0, 0x4800, v130
	ds_write2_b32 v0, v77, v81 offset0:12 offset1:28
	v_add_u32_e32 v0, 0x6000, v130
	ds_write2_b32 v0, v66, v70 offset0:192 offset1:208
	v_add_u32_e32 v0, 0x6400, v130
	ds_write2_b32 v0, v67, v71 offset0:68 offset1:84
	ds_write2_b32 v0, v68, v72 offset0:200 offset1:216
	v_add_u32_e32 v0, 0x6800, v130
	ds_write2_b32 v0, v69, v73 offset0:76 offset1:92
	v_ashrrev_i32_e32 v0, 4, v132
	v_mul_lo_u32 v66, v0, s92
	s_waitcnt lgkmcnt(0)
	s_barrier
	v_lshl_add_u32 v78, v133, 2, v66
	ds_read_b128 v[66:69], v78
	ds_read_b128 v[70:73], v78 offset:16
	v_add_u32_e32 v74, s35, v0
	v_ashrrev_i32_e32 v75, 31, v74
	v_lshlrev_b32_e32 v0, 1, v133
	s_waitcnt vmcnt(6) lgkmcnt(1)
	v_fmamk_f32 v66, v126, 0x3fd744fd, v66
	v_fmamk_f32 v67, v127, 0x3fd744fd, v67
	v_fmamk_f32 v68, v128, 0x3fd744fd, v68
	s_waitcnt lgkmcnt(0)
	v_fmamk_f32 v70, v102, 0x3fd744fd, v70
	v_fmamk_f32 v71, v103, 0x3fd744fd, v71
	v_fmac_f32_e32 v69, 0x3fd744fd, v129
	v_cvt_pk_bf16_f32 v66, v66, v67
	v_cvt_pk_bf16_f32 v67, v68, v69
	v_cvt_pk_bf16_f32 v68, v70, v71
	v_lshlrev_b64 v[70:71], 11, v[74:75]
	v_fmamk_f32 v72, v104, 0x3fd744fd, v72
	v_fmac_f32_e32 v73, 0x3fd744fd, v105
	v_lshl_add_u64 v[76:77], s[22:23], 0, v[70:71]
	v_cvt_pk_bf16_f32 v69, v72, v73
	ds_read_b128 v[70:73], v78 offset:16896
	v_lshl_add_u64 v[76:77], v[76:77], 0, v[0:1]
	global_store_dwordx4 v[76:77], v[66:69], off offset:256
	ds_read_b128 v[66:69], v78 offset:16912
	s_bitset1_b32 s35, 7
	s_waitcnt vmcnt(6) lgkmcnt(1)
	v_fmamk_f32 v70, v114, 0x3fd744fd, v70
	v_fmamk_f32 v71, v115, 0x3fd744fd, v71
	v_fmamk_f32 v72, v116, 0x3fd744fd, v72
	s_waitcnt vmcnt(5) lgkmcnt(0)
	v_fmamk_f32 v75, v98, 0x3fd744fd, v66
	v_cvt_pk_bf16_f32 v66, v70, v71
	v_add_u32_e32 v70, 32, v74
	v_fmamk_f32 v76, v99, 0x3fd744fd, v67
	v_fmamk_f32 v77, v100, 0x3fd744fd, v68
	v_fmac_f32_e32 v69, 0x3fd744fd, v101
	v_ashrrev_i32_e32 v71, 31, v70
	v_cvt_pk_bf16_f32 v68, v75, v76
	v_cvt_pk_bf16_f32 v69, v77, v69
	v_lshlrev_b64 v[76:77], 11, v[70:71]
	v_fmac_f32_e32 v73, 0x3fd744fd, v117
	v_lshl_add_u64 v[76:77], s[22:23], 0, v[76:77]
	v_cvt_pk_bf16_f32 v67, v72, v73
	ds_read_b128 v[70:73], v78 offset:33792
	v_lshl_add_u64 v[76:77], v[76:77], 0, v[0:1]
	global_store_dwordx4 v[76:77], v[66:69], off offset:256
	ds_read_b128 v[66:69], v78 offset:33808
	s_waitcnt vmcnt(5) lgkmcnt(1)
	v_fmamk_f32 v70, v118, 0x3fd744fd, v70
	v_fmamk_f32 v71, v119, 0x3fd744fd, v71
	v_fmamk_f32 v72, v120, 0x3fd744fd, v72
	s_waitcnt vmcnt(4) lgkmcnt(0)
	v_fmamk_f32 v75, v106, 0x3fd744fd, v66
	v_cvt_pk_bf16_f32 v66, v70, v71
	v_add_u32_e32 v70, 64, v74
	v_fmamk_f32 v76, v107, 0x3fd744fd, v67
	v_fmamk_f32 v77, v108, 0x3fd744fd, v68
	v_fmac_f32_e32 v69, 0x3fd744fd, v109
	v_ashrrev_i32_e32 v71, 31, v70
	v_cvt_pk_bf16_f32 v68, v75, v76
	v_cvt_pk_bf16_f32 v69, v77, v69
	v_lshlrev_b64 v[76:77], 11, v[70:71]
	v_fmac_f32_e32 v73, 0x3fd744fd, v121
	v_lshl_add_u64 v[76:77], s[22:23], 0, v[76:77]
	v_cvt_pk_bf16_f32 v67, v72, v73
	ds_read_b128 v[70:73], v78 offset:50688
	v_lshl_add_u64 v[76:77], v[76:77], 0, v[0:1]
	global_store_dwordx4 v[76:77], v[66:69], off offset:256
	ds_read_b128 v[66:69], v78 offset:50704
	s_waitcnt vmcnt(4) lgkmcnt(1)
	v_fmamk_f32 v70, v122, 0x3fd744fd, v70
	v_fmamk_f32 v71, v123, 0x3fd744fd, v71
	v_fmamk_f32 v72, v124, 0x3fd744fd, v72
	s_waitcnt vmcnt(3) lgkmcnt(0)
	v_fmamk_f32 v75, v110, 0x3fd744fd, v66
	v_cvt_pk_bf16_f32 v66, v70, v71
	v_add_u32_e32 v70, 0x60, v74
	v_ashrrev_i32_e32 v71, 31, v70
	v_lshlrev_b64 v[70:71], 11, v[70:71]
	v_lshl_add_u64 v[70:71], s[22:23], 0, v[70:71]
	v_fmac_f32_e32 v69, 0x3fd744fd, v113
	v_lshl_add_u64 v[70:71], v[70:71], 0, v[0:1]
	v_mov_b32_e32 v0, v168
	v_fmac_f32_e32 v73, 0x3fd744fd, v125
	v_fmamk_f32 v76, v111, 0x3fd744fd, v67
	v_fmamk_f32 v77, v112, 0x3fd744fd, v68
	v_cvt_pk_bf16_f32 v67, v72, v73
	v_cvt_pk_bf16_f32 v68, v75, v76
	v_cvt_pk_bf16_f32 v69, v77, v69
	global_store_dwordx4 v[70:71], v[66:69], off offset:256
	s_nop 1
	v_lshlrev_b32_e32 v66, 3, v0
	v_ashrrev_i32_e32 v0, 4, v0
	v_add_u32_e32 v98, s35, v0
	v_and_b32_e32 v100, 0x78, v66
	v_ashrrev_i32_e32 v99, 31, v98
	s_cbranch_vccnz .LBB0_82
; template <int AI, int BJ>
; DI void f1_load(PREF p, int l, int mt, int dt, float4 (&xa)[4], float4 (&xb)[4]) {
;     ...
;   } else {
; #pragma unroll
;     for (int q = 0; q < 4; ++q) {
;       float f[8]; unpack8(*(const u32x4*)(p.X + (size_t)(row0 + (t >> 4) + 32 * q) * 1024 + col0 + c), f);
;       xa[q] = make_float4(f[0], f[1], f[2], f[3]); xb[q] = make_float4(f[4], f[5], f[6], f[7]);
;     }
;   }
	s_add_u32 s0, s12, s24
	s_addc_u32 s1, s13, s25
	v_lshlrev_b32_e32 v0, 1, v100
	v_lshl_add_u64 v[66:67], s[0:1], 0, v[0:1]
	v_lshlrev_b64 v[68:69], 11, v[98:99]
	v_lshl_add_u64 v[66:67], v[66:67], 0, v[68:69]
	v_add_co_u32_e32 v72, vcc, s88, v66
	s_mov_b32 s0, 0x20000
	s_nop 0
	v_addc_co_u32_e32 v73, vcc, 0, v67, vcc
	v_add_co_u32_e32 v76, vcc, s0, v66
	s_mov_b32 s0, 0x30000
	s_nop 0
	v_addc_co_u32_e32 v77, vcc, 0, v67, vcc
	global_load_dwordx4 v[68:71], v[66:67], off
	global_load_dwordx4 v[82:85], v[76:77], off
	s_nop 0
	global_load_dwordx4 v[72:75], v[72:73], off
	v_add_co_u32_e32 v66, vcc, s0, v66
	s_waitcnt vmcnt(2)
	v_and_b32_e32 v87, 0xffff0000, v68
	v_addc_co_u32_e32 v67, vcc, 0, v67, vcc
	global_load_dwordx4 v[102:105], v[66:67], off
	v_lshlrev_b32_e32 v86, 16, v68
	v_and_b32_e32 v89, 0xffff0000, v69
	v_lshlrev_b32_e32 v88, 16, v69
	v_and_b32_e32 v67, 0xffff0000, v70
	v_lshlrev_b32_e32 v66, 16, v70
	v_and_b32_e32 v69, 0xffff0000, v71
	v_lshlrev_b32_e32 v68, 16, v71
	s_waitcnt vmcnt(1)
	v_and_b32_e32 v79, 0xffff0000, v72
	v_lshlrev_b32_e32 v78, 16, v72
	v_and_b32_e32 v81, 0xffff0000, v73
	v_lshlrev_b32_e32 v80, 16, v73
	v_and_b32_e32 v71, 0xffff0000, v74
	v_lshlrev_b32_e32 v70, 16, v74
	v_and_b32_e32 v73, 0xffff0000, v75
	v_lshlrev_b32_e32 v72, 16, v75
	v_and_b32_e32 v91, 0xffff0000, v82
	v_lshlrev_b32_e32 v90, 16, v82
	v_and_b32_e32 v93, 0xffff0000, v83
	v_lshlrev_b32_e32 v92, 16, v83
	v_and_b32_e32 v75, 0xffff0000, v84
	v_lshlrev_b32_e32 v74, 16, v84
	v_and_b32_e32 v77, 0xffff0000, v85
	v_lshlrev_b32_e32 v76, 16, v85
	s_waitcnt vmcnt(0)
	v_and_b32_e32 v95, 0xffff0000, v102
	v_lshlrev_b32_e32 v94, 16, v102
	v_and_b32_e32 v97, 0xffff0000, v103
	v_lshlrev_b32_e32 v96, 16, v103
	v_and_b32_e32 v83, 0xffff0000, v104
	v_lshlrev_b32_e32 v82, 16, v104
	v_and_b32_e32 v85, 0xffff0000, v105
	v_lshlrev_b32_e32 v84, 16, v105
	s_cbranch_execnz .LBB0_78

; DI u32x4 pack8(const float* f) { u32x4 o; o.x = pack2(f[0], f[1]); o.y = pack2(f[2], f[3]); o.z = pack2(f[4], f[5]); o.w = pack2(f[6], f[7]); return o; }
; template <int AI, int BJ>
; DI void f1_load(PREF p, int l, int mt, int dt, float4 (&xa)[4], float4 (&xb)[4]) {
;     ...
;   } else {
; #pragma unroll
;     for (int q = 0; q < 4; ++q) {
;       float f[8]; unpack8(*(const u32x4*)(p.X + (size_t)(row0 + (t >> 4) + 32 * q) * 1024 + col0 + c), f);
;       xa[q] = make_float4(f[0], f[1], f[2], f[3]); xb[q] = make_float4(f[4], f[5], f[6], f[7]);
;     }
;   }
; template <int AI, int BJ>
; DI void f1_proc(PREF p, const f32x4 (&acc)[2][2][4][2], int mt, int dt, float* Cs, const float4 (&xa)[4], const float4 (&xb)[4]) {
;     ...
;   stage_q<AI, BJ>(acc, Cs);
; #pragma unroll
;   for (int q = 0; q < 4; ++q) {
;     int r = (t >> 4) + 32 * q;
;     float v[8]; ld8(Cs + r * CST + c, v);
;     float4 a = xa[q], b = xb[q];
;     float y[8] = {alpha * a.x + v[0], alpha * a.y + v[1], alpha * a.z + v[2], alpha * a.w + v[3],
;                   alpha * b.x + v[4], alpha * b.y + v[5], alpha * b.z + v[6], alpha * b.w + v[7]};
;     *(u32x4*)((u16*)p.fbuf + (size_t)(row0 + r) * 1024 + col0 + c) = pack8(y);
;   }
.LBB0_78:
	v_mov_b32_e32 v100, v168
	s_and_b64 vcc, exec, s[8:9]
	v_lshlrev_b32_e32 v0, 3, v100
	v_and_b32_e32 v101, 0x78, v0
	v_mov_b32_e32 v0, v168
	s_waitcnt lgkmcnt(0)
	s_barrier
	s_nop 0
	v_and_b32_e32 v98, 15, v0
	v_lshrrev_b32_e32 v99, 2, v0
	v_lshlrev_b32_e32 v0, 1, v0
	v_lshlrev_b32_e32 v98, 2, v98
	v_and_b32_e32 v99, 0xfffffcc, v99
	v_and_or_b32 v0, v0, s89, v98
	v_mad_u64_u32 v[98:99], s[0:1], v99, s92, v[0:1]
	v_add_u32_e32 v0, 0x400, v98
	ds_write2_b32 v98, v54, v62 offset1:16
	ds_write2_b32 v98, v55, v63 offset0:132 offset1:148
	ds_write2_b32 v0, v56, v64 offset0:8 offset1:24
	ds_write2_b32 v0, v57, v65 offset0:140 offset1:156
	v_add_u32_e32 v0, 0x2000, v98
	ds_write2_b32 v0, v50, v58 offset0:64 offset1:80
	ds_write2_b32 v0, v51, v59 offset0:196 offset1:212
	v_add_u32_e32 v0, 0x2400, v98
	ds_write2_b32 v0, v52, v60 offset0:72 offset1:88
	ds_write2_b32 v0, v53, v61 offset0:204 offset1:220
	v_add_u32_e32 v0, 0x4000, v98
	ds_write2_b32 v0, v42, v46 offset0:128 offset1:144
	v_add_u32_e32 v0, 0x4400, v98
	ds_write2_b32 v0, v43, v47 offset0:4 offset1:20
	ds_write2_b32 v0, v44, v48 offset0:136 offset1:152
	v_add_u32_e32 v0, 0x4800, v98
	ds_write2_b32 v0, v45, v49 offset0:12 offset1:28
	v_add_u32_e32 v0, 0x6000, v98
	ds_write2_b32 v0, v34, v38 offset0:192 offset1:208
	v_add_u32_e32 v0, 0x6400, v98
	ds_write2_b32 v0, v35, v39 offset0:68 offset1:84
	ds_write2_b32 v0, v36, v40 offset0:200 offset1:216
	v_add_u32_e32 v0, 0x6800, v98
	v_ashrrev_i32_e32 v44, 4, v100
	ds_write2_b32 v0, v37, v41 offset0:76 offset1:92
	v_mul_lo_u32 v0, v44, s92
	s_waitcnt lgkmcnt(0)
	s_barrier
	v_lshl_add_u32 v48, v101, 2, v0
	ds_read_b128 v[34:37], v48
	ds_read_b128 v[38:41], v48 offset:16
	v_add_u32_e32 v44, s35, v44
	v_lshlrev_b32_e32 v0, 1, v101
	v_ashrrev_i32_e32 v45, 31, v44
	v_lshl_add_u64 v[42:43], s[22:23], 0, v[0:1]
	s_waitcnt vmcnt(6) lgkmcnt(1)
	v_fmamk_f32 v0, v86, 0x3fd744fd, v34
	v_fmamk_f32 v34, v87, 0x3fd744fd, v35
	v_fmamk_f32 v35, v88, 0x3fd744fd, v36
	v_fmac_f32_e32 v37, 0x3fd744fd, v89
	s_waitcnt lgkmcnt(0)
	v_fmamk_f32 v36, v66, 0x3fd744fd, v38
	v_lshlrev_b64 v[46:47], 11, v[44:45]
	v_fmamk_f32 v38, v67, 0x3fd744fd, v39
	v_fmamk_f32 v39, v68, 0x3fd744fd, v40
	v_fmac_f32_e32 v41, 0x3fd744fd, v69
	v_cvt_pk_bf16_f32 v34, v0, v34
	v_cvt_pk_bf16_f32 v35, v35, v37
	v_cvt_pk_bf16_f32 v36, v36, v38
	v_cvt_pk_bf16_f32 v37, v39, v41
	v_lshl_add_u64 v[46:47], v[42:43], 0, v[46:47]
	ds_read_b128 v[38:41], v48 offset:16896
	global_store_dwordx4 v[46:47], v[34:37], off
	ds_read_b128 v[34:37], v48 offset:16912
	s_waitcnt vmcnt(6) lgkmcnt(1)
	v_fmamk_f32 v0, v78, 0x3fd744fd, v38
	v_fmamk_f32 v38, v79, 0x3fd744fd, v39
	s_waitcnt vmcnt(5) lgkmcnt(0)
	v_fmamk_f32 v46, v72, 0x3fd744fd, v36
	v_fmac_f32_e32 v37, 0x3fd744fd, v73
	v_cvt_pk_bf16_f32 v37, v46, v37
	v_add_u32_e32 v46, 32, v44
	v_ashrrev_i32_e32 v47, 31, v46
	v_lshlrev_b64 v[46:47], 11, v[46:47]
	v_fmamk_f32 v39, v80, 0x3fd744fd, v40
	v_fmac_f32_e32 v41, 0x3fd744fd, v81
	v_fmamk_f32 v40, v70, 0x3fd744fd, v34
	v_fmamk_f32 v45, v71, 0x3fd744fd, v35
	v_cvt_pk_bf16_f32 v34, v0, v38
	v_cvt_pk_bf16_f32 v35, v39, v41
	v_cvt_pk_bf16_f32 v36, v40, v45
	v_lshl_add_u64 v[46:47], v[42:43], 0, v[46:47]
	ds_read_b128 v[38:41], v48 offset:33792
	global_store_dwordx4 v[46:47], v[34:37], off
	ds_read_b128 v[34:37], v48 offset:33808
	s_waitcnt vmcnt(5) lgkmcnt(1)
	v_fmamk_f32 v0, v90, 0x3fd744fd, v38
	v_fmamk_f32 v38, v91, 0x3fd744fd, v39
	s_waitcnt vmcnt(4) lgkmcnt(0)
	v_fmamk_f32 v46, v76, 0x3fd744fd, v36
	v_fmac_f32_e32 v37, 0x3fd744fd, v77
	v_cvt_pk_bf16_f32 v37, v46, v37
	v_add_u32_e32 v46, 64, v44
	v_ashrrev_i32_e32 v47, 31, v46
	v_fmamk_f32 v39, v92, 0x3fd744fd, v40
	v_fmac_f32_e32 v41, 0x3fd744fd, v93
	v_fmamk_f32 v40, v74, 0x3fd744fd, v34
	v_lshlrev_b64 v[46:47], 11, v[46:47]
	v_fmamk_f32 v45, v75, 0x3fd744fd, v35
	v_cvt_pk_bf16_f32 v34, v0, v38
	v_cvt_pk_bf16_f32 v35, v39, v41
	v_cvt_pk_bf16_f32 v36, v40, v45
	ds_read_b128 v[38:41], v48 offset:50688
	v_lshl_add_u64 v[46:47], v[42:43], 0, v[46:47]
	global_store_dwordx4 v[46:47], v[34:37], off
	ds_read_b128 v[34:37], v48 offset:50704
	s_waitcnt vmcnt(4) lgkmcnt(1)
	v_fmamk_f32 v0, v94, 0x3fd744fd, v38
	v_fmamk_f32 v38, v95, 0x3fd744fd, v39
	v_fmamk_f32 v39, v96, 0x3fd744fd, v40
	s_waitcnt vmcnt(3) lgkmcnt(0)
	v_fmamk_f32 v40, v82, 0x3fd744fd, v34
	v_cvt_pk_bf16_f32 v34, v0, v38
	v_add_u32_e32 v38, 0x60, v44
	v_fmac_f32_e32 v41, 0x3fd744fd, v97
	v_fmamk_f32 v45, v83, 0x3fd744fd, v35
	v_cvt_pk_bf16_f32 v35, v39, v41
	v_ashrrev_i32_e32 v39, 31, v38
	v_lshlrev_b64 v[38:39], 11, v[38:39]
	v_fmac_f32_e32 v37, 0x3fd744fd, v85
	v_lshl_add_u64 v[38:39], v[42:43], 0, v[38:39]
	v_mov_b32_e32 v0, v168
	v_fmamk_f32 v46, v84, 0x3fd744fd, v36
	v_cvt_pk_bf16_f32 v36, v40, v45
	v_cvt_pk_bf16_f32 v37, v46, v37
	global_store_dwordx4 v[38:39], v[34:37], off
	s_nop 1
	v_lshlrev_b32_e32 v34, 3, v0
	v_ashrrev_i32_e32 v0, 4, v0
	v_add_u32_e32 v66, s35, v0
	v_and_b32_e32 v68, 0x78, v34
	v_ashrrev_i32_e32 v67, 31, v66
	s_cbranch_vccnz .LBB0_83
	s_add_u32 s0, s12, s24
	s_addc_u32 s1, s13, s25
	v_lshlrev_b32_e32 v0, 1, v68
	v_lshl_add_u64 v[34:35], s[0:1], 0, v[0:1]
	v_lshlrev_b64 v[36:37], 11, v[66:67]
	v_lshl_add_u64 v[38:39], v[34:35], 0, v[36:37]
	v_add_co_u32_e32 v40, vcc, s88, v38
	s_mov_b32 s0, 0x20000
	s_nop 0
	v_addc_co_u32_e32 v41, vcc, 0, v39, vcc
	global_load_dwordx4 v[34:37], v[38:39], off offset:256
	global_load_dwordx4 v[42:45], v[40:41], off offset:256
	v_add_co_u32_e32 v40, vcc, s0, v38
	s_mov_b32 s0, 0x30000
	s_nop 0
	v_addc_co_u32_e32 v41, vcc, 0, v39, vcc
	v_add_co_u32_e32 v38, vcc, s0, v38
	global_load_dwordx4 v[46:49], v[40:41], off offset:256
	s_nop 0
	v_addc_co_u32_e32 v39, vcc, 0, v39, vcc
	global_load_dwordx4 v[70:73], v[38:39], off offset:256
	s_waitcnt vmcnt(3)
	v_and_b32_e32 v63, 0xffff0000, v34
	v_lshlrev_b32_e32 v62, 16, v34
	v_and_b32_e32 v65, 0xffff0000, v35
	v_lshlrev_b32_e32 v64, 16, v35
	v_and_b32_e32 v39, 0xffff0000, v36
	v_lshlrev_b32_e32 v38, 16, v36
	v_and_b32_e32 v41, 0xffff0000, v37
	v_lshlrev_b32_e32 v40, 16, v37
	s_waitcnt vmcnt(2)
	v_and_b32_e32 v51, 0xffff0000, v42
	v_lshlrev_b32_e32 v50, 16, v42
	v_and_b32_e32 v53, 0xffff0000, v43
	v_lshlrev_b32_e32 v52, 16, v43
	v_and_b32_e32 v35, 0xffff0000, v44
	v_lshlrev_b32_e32 v34, 16, v44
	v_and_b32_e32 v37, 0xffff0000, v45
	v_lshlrev_b32_e32 v36, 16, v45
	s_waitcnt vmcnt(1)
	v_and_b32_e32 v55, 0xffff0000, v46
	v_lshlrev_b32_e32 v54, 16, v46
	v_and_b32_e32 v57, 0xffff0000, v47
	v_lshlrev_b32_e32 v56, 16, v47
	v_and_b32_e32 v43, 0xffff0000, v48
	v_lshlrev_b32_e32 v42, 16, v48
	v_and_b32_e32 v45, 0xffff0000, v49
	v_lshlrev_b32_e32 v44, 16, v49
	s_waitcnt vmcnt(0)
	v_and_b32_e32 v59, 0xffff0000, v70
	v_lshlrev_b32_e32 v58, 16, v70
	v_and_b32_e32 v61, 0xffff0000, v71
	v_lshlrev_b32_e32 v60, 16, v71
	v_and_b32_e32 v47, 0xffff0000, v72
	v_lshlrev_b32_e32 v46, 16, v72
	v_and_b32_e32 v49, 0xffff0000, v73
	v_lshlrev_b32_e32 v48, 16, v73
	s_cbranch_execnz .LBB0_62
	s_branch .LBB0_61

; #define G_LDA(dst, b, h)                                                                                                  \
;   _Pragma("unroll") for (int m = 0; m < 4; ++m) _Pragma("unroll") for (int k = 0; k < 2; ++k)                             \
;       dst[m][k] = *(const bf16x8*)((const char*)G_SA(b, h) + ((wr * 4 + m) * 2 + k) * 1024 + rdo)
; #define G_LDB(dst, b, h)                                                                                                  \
;   _Pragma("unroll") for (int n = 0; n < 2; ++n) _Pragma("unroll") for (int k = 0; k < 2; ++k)                             \
;       dst[n][k] = *(const bf16x8*)((const char*)G_SB(b, h) + ((wc * 2 + n) * 2 + k) * 1024 + rdo)
; #define G_WAIT_V(n) asm volatile("s_waitcnt vmcnt(" #n ")" ::: "memory")
; #define G_WAIT_L(n) asm volatile("s_waitcnt lgkmcnt(" #n ")" ::: "memory")
; #define G_BAR __builtin_amdgcn_s_barrier()
; #define G_SCHED __builtin_amdgcn_sched_barrier(0)
;     ...
;   for (int tt = 0; tt < nt - 2; tt += 2) {
;     G_LDB(B0, 0, 0); G_SCHED; G_LDA(At, 0, 0); G_STAGE(G_SA(1, 1), A, oa0, oa1, LDA, 128, KA(tt + 1));
;     G_WAIT_L(8); G_BAR; G_WAIT_L(0); G_MMA(0, 0, At, B0); G_BAR; G_SCHED;
;     G_LDB(B1, 0, 1); G_STAGE(G_SB(0, 0), B, ob0, ob1, LDB, 0, KB(tt + 2));
;     G_BAR; G_WAIT_L(0); G_MMA(0, 1, At, B1); G_BAR;
;     G_LDA(At, 0, 1); G_STAGE(G_SA(0, 0), A, oa0, oa1, LDA, 0, KA(tt + 2));
;     G_BAR; G_WAIT_L(0); G_MMA(1, 0, At, B0); G_BAR; G_SCHED;
;     G_STAGE(G_SB(0, 1), B, ob0, ob1, LDB, 128, KB(tt + 2));
;     G_WAIT_V(6); G_BAR; G_MMA(1, 1, At, B1); G_BAR;
;     G_LDB(B0, 1, 0); G_SCHED; G_LDA(At, 1, 0); G_STAGE(G_SA(0, 1), A, oa0, oa1, LDA, 128, KA(tt + 2));
;     G_WAIT_L(8); G_BAR; G_WAIT_L(0); G_MMA(0, 0, At, B0); G_BAR; G_SCHED;
;     G_LDB(B1, 1, 1); G_STAGE(G_SB(1, 0), B, ob0, ob1, LDB, 0, KB(tt + 3));
;     G_BAR; G_WAIT_L(0); G_MMA(0, 1, At, B1); G_BAR;
;     G_LDA(At, 1, 1); G_STAGE(G_SA(1, 0), A, oa0, oa1, LDA, 0, KA(tt + 3));
.LBB0_96:
	ds_read_b128 v[182:185], v151
	ds_read_b128 v[186:189], v151 offset:1024
	ds_read_b128 v[190:193], v151 offset:2048
	ds_read_b128 v[194:197], v151 offset:3072
	v_add_u32_e32 v162, 0xc000, v147
	v_lshl_add_u64 v[166:167], s[30:31], 0, v[140:141]
	v_readfirstlane_b32 s0, v162
	v_lshl_add_u64 v[164:165], v[166:167], 0, s[78:79]
	s_mov_b32 m0, s0
	ds_read_b128 v[198:201], v143
	ds_read_b128 v[202:205], v143 offset:1024
	ds_read_b128 v[206:209], v143 offset:2048
	ds_read_b128 v[210:213], v143 offset:3072
	ds_read_b128 v[214:217], v143 offset:4096
	ds_read_b128 v[218:221], v143 offset:5120
	ds_read_b128 v[222:225], v143 offset:6144
	ds_read_b128 v[226:229], v143 offset:7168
	global_load_lds_dwordx4 v[164:165], off
	v_add_u32_e32 v164, 0xe000, v147
	v_lshl_add_u64 v[246:247], s[30:31], 0, v[138:139]
	v_readfirstlane_b32 s0, v164
	v_lshl_add_u64 v[230:231], v[246:247], 0, s[78:79]
	s_mov_b32 m0, s0
	s_add_i32 s34, s13, -1
	global_load_lds_dwordx4 v[230:231], off
	s_waitcnt lgkmcnt(8)
	s_barrier
	s_waitcnt lgkmcnt(0)
	s_setprio 1
	s_waitcnt lgkmcnt(0)
	v_mfma_f32_16x16x32_bf16 v[126:129], v[198:201], v[182:185], v[126:129]
	v_mfma_f32_16x16x32_bf16 v[122:125], v[198:201], v[190:193], v[122:125]
	v_mfma_f32_16x16x32_bf16 v[118:121], v[206:209], v[182:185], v[118:121]
	v_mfma_f32_16x16x32_bf16 v[114:117], v[206:209], v[190:193], v[114:117]
	v_mfma_f32_16x16x32_bf16 v[110:113], v[214:217], v[182:185], v[110:113]
	v_mfma_f32_16x16x32_bf16 v[106:109], v[214:217], v[190:193], v[106:109]
	v_mfma_f32_16x16x32_bf16 v[102:105], v[222:225], v[182:185], v[102:105]
	v_mfma_f32_16x16x32_bf16 v[98:101], v[222:225], v[190:193], v[98:101]
	v_mfma_f32_16x16x32_bf16 v[126:129], v[202:205], v[186:189], v[126:129]
	v_mfma_f32_16x16x32_bf16 v[122:125], v[202:205], v[194:197], v[122:125]
	v_mfma_f32_16x16x32_bf16 v[118:121], v[210:213], v[186:189], v[118:121]
	v_mfma_f32_16x16x32_bf16 v[114:117], v[210:213], v[194:197], v[114:117]
	v_mfma_f32_16x16x32_bf16 v[110:113], v[218:221], v[186:189], v[110:113]
	v_mfma_f32_16x16x32_bf16 v[106:109], v[218:221], v[194:197], v[106:109]
	v_mfma_f32_16x16x32_bf16 v[102:105], v[226:229], v[186:189], v[102:105]
	v_mfma_f32_16x16x32_bf16 v[98:101], v[226:229], v[194:197], v[98:101]
	s_setprio 0
	s_barrier
	s_add_i32 s0, s25, 0xffff0000
	s_sub_i32 s1, s23, 64
	s_and_b32 s0, s0, 0x1c0000
	s_and_b32 s1, s1, 0x80
	s_or_b32 s0, s0, s1
	s_lshl_b32 s35, s0, 1
	s_add_u32 s0, s26, s35
	s_addc_u32 s1, s27, 0
	v_readfirstlane_b32 s36, v149
	v_lshl_add_u64 v[248:249], s[0:1], 0, v[134:135]
	s_mov_b32 m0, s36
	ds_read_b128 v[230:233], v146
	ds_read_b128 v[234:237], v146 offset:1024
	ds_read_b128 v[238:241], v146 offset:2048
	ds_read_b128 v[242:245], v146 offset:3072
	global_load_lds_dwordx4 v[248:249], off
	v_lshl_add_u64 v[248:249], s[0:1], 0, v[136:137]
	v_readfirstlane_b32 s0, v150
	s_mov_b32 m0, s0
	s_nop 0
	global_load_lds_dwordx4 v[248:249], off
	s_barrier
	s_waitcnt lgkmcnt(0)
	s_setprio 1
	s_waitcnt lgkmcnt(0)
	v_mfma_f32_16x16x32_bf16 v[94:97], v[198:201], v[230:233], v[94:97]
	v_mfma_f32_16x16x32_bf16 v[90:93], v[198:201], v[238:241], v[90:93]
	v_mfma_f32_16x16x32_bf16 v[86:89], v[206:209], v[230:233], v[86:89]
	v_mfma_f32_16x16x32_bf16 v[82:85], v[206:209], v[238:241], v[82:85]
	v_mfma_f32_16x16x32_bf16 v[78:81], v[214:217], v[230:233], v[78:81]
	v_mfma_f32_16x16x32_bf16 v[74:77], v[214:217], v[238:241], v[74:77]
	v_mfma_f32_16x16x32_bf16 v[70:73], v[222:225], v[230:233], v[70:73]
	v_mfma_f32_16x16x32_bf16 v[66:69], v[222:225], v[238:241], v[66:69]
	v_mfma_f32_16x16x32_bf16 v[94:97], v[202:205], v[234:237], v[94:97]
	v_mfma_f32_16x16x32_bf16 v[90:93], v[202:205], v[242:245], v[90:93]
	v_mfma_f32_16x16x32_bf16 v[86:89], v[210:213], v[234:237], v[86:89]
	v_mfma_f32_16x16x32_bf16 v[82:85], v[210:213], v[242:245], v[82:85]
	v_mfma_f32_16x16x32_bf16 v[78:81], v[218:221], v[234:237], v[78:81]
	v_mfma_f32_16x16x32_bf16 v[74:77], v[218:221], v[242:245], v[74:77]
	v_mfma_f32_16x16x32_bf16 v[70:73], v[226:229], v[234:237], v[70:73]
	v_mfma_f32_16x16x32_bf16 v[66:69], v[226:229], v[242:245], v[66:69]
	s_setprio 0
	v_readfirstlane_b32 s0, v147
	v_lshl_add_u64 v[248:249], v[166:167], 0, s[82:83]
	s_mov_b32 m0, s0
	v_readfirstlane_b32 s0, v148
	s_barrier
	ds_read_b128 v[198:201], v143 offset:16384
	ds_read_b128 v[202:205], v143 offset:17408
	ds_read_b128 v[206:209], v143 offset:18432
	ds_read_b128 v[210:213], v143 offset:19456
	ds_read_b128 v[214:217], v143 offset:20480
	ds_read_b128 v[218:221], v143 offset:21504
	ds_read_b128 v[222:225], v143 offset:22528
	ds_read_b128 v[226:229], v143 offset:23552
	global_load_lds_dwordx4 v[248:249], off
	v_lshl_add_u64 v[248:249], v[246:247], 0, s[82:83]
	s_mov_b32 m0, s0
	s_nop 0
	global_load_lds_dwordx4 v[248:249], off
	s_barrier
	s_waitcnt lgkmcnt(0)
	s_setprio 1
	s_waitcnt lgkmcnt(0)
	v_mfma_f32_16x16x32_bf16 v[62:65], v[198:201], v[182:185], v[62:65]
	v_mfma_f32_16x16x32_bf16 v[58:61], v[198:201], v[190:193], v[58:61]
	v_mfma_f32_16x16x32_bf16 v[54:57], v[206:209], v[182:185], v[54:57]
	v_mfma_f32_16x16x32_bf16 v[50:53], v[206:209], v[190:193], v[50:53]
	v_mfma_f32_16x16x32_bf16 v[46:49], v[214:217], v[182:185], v[46:49]
	v_mfma_f32_16x16x32_bf16 v[42:45], v[214:217], v[190:193], v[42:45]
	v_mfma_f32_16x16x32_bf16 v[38:41], v[222:225], v[182:185], v[38:41]
	v_mfma_f32_16x16x32_bf16 v[34:37], v[222:225], v[190:193], v[34:37]
	v_mfma_f32_16x16x32_bf16 v[62:65], v[202:205], v[186:189], v[62:65]
	v_mfma_f32_16x16x32_bf16 v[58:61], v[202:205], v[194:197], v[58:61]
	v_mfma_f32_16x16x32_bf16 v[54:57], v[210:213], v[186:189], v[54:57]
	v_mfma_f32_16x16x32_bf16 v[50:53], v[210:213], v[194:197], v[50:53]
	v_mfma_f32_16x16x32_bf16 v[46:49], v[218:221], v[186:189], v[46:49]
	v_mfma_f32_16x16x32_bf16 v[42:45], v[218:221], v[194:197], v[42:45]
	v_mfma_f32_16x16x32_bf16 v[38:41], v[226:229], v[186:189], v[38:41]
	v_mfma_f32_16x16x32_bf16 v[34:37], v[226:229], v[194:197], v[34:37]
	s_setprio 0
	s_barrier
; #define G_LDA(dst, b, h)                                                                                                  \
;   _Pragma("unroll") for (int m = 0; m < 4; ++m) _Pragma("unroll") for (int k = 0; k < 2; ++k)                             \
;       dst[m][k] = *(const bf16x8*)((const char*)G_SA(b, h) + ((wr * 4 + m) * 2 + k) * 1024 + rdo)
; #define G_LDB(dst, b, h)                                                                                                  \
;   _Pragma("unroll") for (int n = 0; n < 2; ++n) _Pragma("unroll") for (int k = 0; k < 2; ++k)                             \
;       dst[n][k] = *(const bf16x8*)((const char*)G_SB(b, h) + ((wc * 2 + n) * 2 + k) * 1024 + rdo)
; #define G_WAIT_V(n) asm volatile("s_waitcnt vmcnt(" #n ")" ::: "memory")
; #define G_WAIT_L(n) asm volatile("s_waitcnt lgkmcnt(" #n ")" ::: "memory")
; #define G_BAR __builtin_amdgcn_s_barrier()
; #define G_SCHED __builtin_amdgcn_sched_barrier(0)
;     ...
;     G_BAR; G_WAIT_L(0); G_MMA(1, 0, At, B0); G_BAR; G_SCHED;
;     G_STAGE(G_SB(0, 1), B, ob0, ob1, LDB, 128, KB(tt + 2));
;     G_WAIT_V(6); G_BAR; G_MMA(1, 1, At, B1); G_BAR;
;     G_LDB(B0, 1, 0); G_SCHED; G_LDA(At, 1, 0); G_STAGE(G_SA(0, 1), A, oa0, oa1, LDA, 128, KA(tt + 2));
;     G_WAIT_L(8); G_BAR; G_WAIT_L(0); G_MMA(0, 0, At, B0); G_BAR; G_SCHED;
;     G_LDB(B1, 1, 1); G_STAGE(G_SB(1, 0), B, ob0, ob1, LDB, 0, KB(tt + 3));
;     G_BAR; G_WAIT_L(0); G_MMA(0, 1, At, B1); G_BAR;
;     G_LDA(At, 1, 1); G_STAGE(G_SA(1, 0), A, oa0, oa1, LDA, 0, KA(tt + 3));
;     G_BAR; G_WAIT_L(0); G_MMA(1, 0, At, B0); G_BAR; G_SCHED;
	s_add_u32 s0, s28, s35
	s_addc_u32 s1, s29, 0
	v_readfirstlane_b32 s35, v152
	v_lshl_add_u64 v[182:183], s[0:1], 0, v[134:135]
	s_mov_b32 m0, s35
	s_nop 0
	global_load_lds_dwordx4 v[182:183], off
	v_lshl_add_u64 v[182:183], s[0:1], 0, v[136:137]
	v_readfirstlane_b32 s0, v153
	s_mov_b32 m0, s0
	s_nop 0
	global_load_lds_dwordx4 v[182:183], off
	s_waitcnt vmcnt(6)
	s_barrier
	s_setprio 1
	v_mfma_f32_16x16x32_bf16 v[30:33], v[198:201], v[230:233], v[30:33]
	v_mfma_f32_16x16x32_bf16 v[26:29], v[198:201], v[238:241], v[26:29]
	v_mfma_f32_16x16x32_bf16 v[22:25], v[206:209], v[230:233], v[22:25]
	v_mfma_f32_16x16x32_bf16 v[18:21], v[206:209], v[238:241], v[18:21]
	v_mfma_f32_16x16x32_bf16 v[14:17], v[214:217], v[230:233], v[14:17]
	v_mfma_f32_16x16x32_bf16 v[10:13], v[214:217], v[238:241], v[10:13]
	v_mfma_f32_16x16x32_bf16 v[6:9], v[222:225], v[230:233], v[6:9]
	v_mfma_f32_16x16x32_bf16 v[2:5], v[222:225], v[238:241], v[2:5]
	v_mfma_f32_16x16x32_bf16 v[30:33], v[202:205], v[234:237], v[30:33]
	v_mfma_f32_16x16x32_bf16 v[26:29], v[202:205], v[242:245], v[26:29]
	v_mfma_f32_16x16x32_bf16 v[22:25], v[210:213], v[234:237], v[22:25]
	v_mfma_f32_16x16x32_bf16 v[18:21], v[210:213], v[242:245], v[18:21]
	v_mfma_f32_16x16x32_bf16 v[14:17], v[218:221], v[234:237], v[14:17]
	v_mfma_f32_16x16x32_bf16 v[10:13], v[218:221], v[242:245], v[10:13]
	v_mfma_f32_16x16x32_bf16 v[6:9], v[226:229], v[234:237], v[6:9]
	v_mfma_f32_16x16x32_bf16 v[2:5], v[226:229], v[242:245], v[2:5]
	s_setprio 0
	s_barrier
	ds_read_b128 v[182:185], v145
	ds_read_b128 v[186:189], v145 offset:1024
	ds_read_b128 v[190:193], v145 offset:2048
	ds_read_b128 v[194:197], v145 offset:3072
	v_readfirstlane_b32 s0, v154
	v_lshl_add_u64 v[230:231], v[166:167], 0, s[86:87]
	s_mov_b32 m0, s0
	v_readfirstlane_b32 s0, v155
	ds_read_b128 v[198:201], v143 offset:32768
	ds_read_b128 v[202:205], v143 offset:33792
	ds_read_b128 v[206:209], v143 offset:34816
	ds_read_b128 v[210:213], v143 offset:35840
	ds_read_b128 v[214:217], v143 offset:36864
	ds_read_b128 v[218:221], v143 offset:37888
	ds_read_b128 v[222:225], v143 offset:38912
	ds_read_b128 v[226:229], v143 offset:39936
	global_load_lds_dwordx4 v[230:231], off
	v_lshl_add_u64 v[230:231], v[246:247], 0, s[86:87]
	s_mov_b32 m0, s0
	s_nop 0
	global_load_lds_dwordx4 v[230:231], off
	s_waitcnt lgkmcnt(8)
	s_barrier
	s_waitcnt lgkmcnt(0)
	s_setprio 1
	s_waitcnt lgkmcnt(0)
	v_mfma_f32_16x16x32_bf16 v[126:129], v[198:201], v[182:185], v[126:129]
	v_mfma_f32_16x16x32_bf16 v[122:125], v[198:201], v[190:193], v[122:125]
	v_mfma_f32_16x16x32_bf16 v[118:121], v[206:209], v[182:185], v[118:121]
	v_mfma_f32_16x16x32_bf16 v[114:117], v[206:209], v[190:193], v[114:117]
	v_mfma_f32_16x16x32_bf16 v[110:113], v[214:217], v[182:185], v[110:113]
	v_mfma_f32_16x16x32_bf16 v[106:109], v[214:217], v[190:193], v[106:109]
	v_mfma_f32_16x16x32_bf16 v[102:105], v[222:225], v[182:185], v[102:105]
	v_mfma_f32_16x16x32_bf16 v[98:101], v[222:225], v[190:193], v[98:101]
	v_mfma_f32_16x16x32_bf16 v[126:129], v[202:205], v[186:189], v[126:129]
	v_mfma_f32_16x16x32_bf16 v[122:125], v[202:205], v[194:197], v[122:125]
	v_mfma_f32_16x16x32_bf16 v[118:121], v[210:213], v[186:189], v[118:121]
	v_mfma_f32_16x16x32_bf16 v[114:117], v[210:213], v[194:197], v[114:117]
	v_mfma_f32_16x16x32_bf16 v[110:113], v[218:221], v[186:189], v[110:113]
	v_mfma_f32_16x16x32_bf16 v[106:109], v[218:221], v[194:197], v[106:109]
	v_mfma_f32_16x16x32_bf16 v[102:105], v[226:229], v[186:189], v[102:105]
	v_mfma_f32_16x16x32_bf16 v[98:101], v[226:229], v[194:197], v[98:101]
	s_setprio 0
	s_barrier
	s_and_b32 s0, s25, 0x1c0000
	s_and_b32 s1, s23, 0xc0
	s_or_b32 s0, s0, s1
	s_lshl_b32 s35, s0, 1
	s_add_u32 s0, s26, s35
	s_addc_u32 s1, s27, 0
	v_readfirstlane_b32 s36, v156
	v_lshl_add_u64 v[248:249], s[0:1], 0, v[134:135]
	s_mov_b32 m0, s36
	ds_read_b128 v[230:233], v144
	ds_read_b128 v[234:237], v144 offset:1024
	ds_read_b128 v[238:241], v144 offset:2048
	ds_read_b128 v[242:245], v144 offset:3072
	global_load_lds_dwordx4 v[248:249], off
	v_lshl_add_u64 v[248:249], s[0:1], 0, v[136:137]
	v_readfirstlane_b32 s0, v157
	s_mov_b32 m0, s0
	s_nop 0
	global_load_lds_dwordx4 v[248:249], off
	s_barrier
	s_waitcnt lgkmcnt(0)
	s_setprio 1
	s_waitcnt lgkmcnt(0)
	v_mfma_f32_16x16x32_bf16 v[94:97], v[198:201], v[230:233], v[94:97]
	v_mfma_f32_16x16x32_bf16 v[90:93], v[198:201], v[238:241], v[90:93]
	v_mfma_f32_16x16x32_bf16 v[86:89], v[206:209], v[230:233], v[86:89]
	v_mfma_f32_16x16x32_bf16 v[82:85], v[206:209], v[238:241], v[82:85]
	v_mfma_f32_16x16x32_bf16 v[78:81], v[214:217], v[230:233], v[78:81]
	v_mfma_f32_16x16x32_bf16 v[74:77], v[214:217], v[238:241], v[74:77]
	v_mfma_f32_16x16x32_bf16 v[70:73], v[222:225], v[230:233], v[70:73]
	v_mfma_f32_16x16x32_bf16 v[66:69], v[222:225], v[238:241], v[66:69]
	v_mfma_f32_16x16x32_bf16 v[94:97], v[202:205], v[234:237], v[94:97]
	v_mfma_f32_16x16x32_bf16 v[90:93], v[202:205], v[242:245], v[90:93]
	v_mfma_f32_16x16x32_bf16 v[86:89], v[210:213], v[234:237], v[86:89]
	v_mfma_f32_16x16x32_bf16 v[82:85], v[210:213], v[242:245], v[82:85]
	v_mfma_f32_16x16x32_bf16 v[78:81], v[218:221], v[234:237], v[78:81]
	v_mfma_f32_16x16x32_bf16 v[74:77], v[218:221], v[242:245], v[74:77]
	v_mfma_f32_16x16x32_bf16 v[70:73], v[226:229], v[234:237], v[70:73]
	v_mfma_f32_16x16x32_bf16 v[66:69], v[226:229], v[242:245], v[66:69]
	s_setprio 0
	v_readfirstlane_b32 s0, v158
	v_lshl_add_u64 v[166:167], v[166:167], 0, s[90:91]
	s_mov_b32 m0, s0
	v_readfirstlane_b32 s0, v159
	s_barrier
; #define G_WAIT_V(n) asm volatile("s_waitcnt vmcnt(" #n ")" ::: "memory")
; #define G_WAIT_L(n) asm volatile("s_waitcnt lgkmcnt(" #n ")" ::: "memory")
; #define G_BAR __builtin_amdgcn_s_barrier()
; #define G_SCHED __builtin_amdgcn_sched_barrier(0)
; DI void br_flush(PREF p, f32x4 (&acc)[2][2][4][2], int slot) { br_store(p, acc, slot); zero_acc256(acc); }
;     ...
;     G_BAR; G_WAIT_L(0); G_MMA(1, 0, At, B0); G_BAR; G_SCHED;
;     G_STAGE(G_SB(1, 1), B, ob0, ob1, LDB, 128, KB(tt + 3));
;     G_WAIT_V(6); G_BAR; G_MMA(1, 1, At, B1); G_BAR;
;     if (MODE && ((tt + 1) & 3) == 3) br_flush(p, acc, (tt + 1) >> 2);
	ds_read_b128 v[198:201], v143 offset:49152
	ds_read_b128 v[202:205], v143 offset:50176
	ds_read_b128 v[206:209], v143 offset:51200
	ds_read_b128 v[210:213], v143 offset:52224
	ds_read_b128 v[214:217], v143 offset:53248
	ds_read_b128 v[218:221], v143 offset:54272
	ds_read_b128 v[222:225], v143 offset:55296
	ds_read_b128 v[226:229], v143 offset:56320
	global_load_lds_dwordx4 v[166:167], off
	v_lshl_add_u64 v[166:167], v[246:247], 0, s[90:91]
	s_mov_b32 m0, s0
	s_nop 0
	global_load_lds_dwordx4 v[166:167], off
	s_barrier
	s_waitcnt lgkmcnt(0)
	s_setprio 1
	s_waitcnt lgkmcnt(0)
	v_mfma_f32_16x16x32_bf16 v[62:65], v[198:201], v[182:185], v[62:65]
	v_mfma_f32_16x16x32_bf16 v[58:61], v[198:201], v[190:193], v[58:61]
	v_mfma_f32_16x16x32_bf16 v[54:57], v[206:209], v[182:185], v[54:57]
	v_mfma_f32_16x16x32_bf16 v[50:53], v[206:209], v[190:193], v[50:53]
	v_mfma_f32_16x16x32_bf16 v[46:49], v[214:217], v[182:185], v[46:49]
	v_mfma_f32_16x16x32_bf16 v[42:45], v[214:217], v[190:193], v[42:45]
	v_mfma_f32_16x16x32_bf16 v[38:41], v[222:225], v[182:185], v[38:41]
	v_mfma_f32_16x16x32_bf16 v[34:37], v[222:225], v[190:193], v[34:37]
	v_mfma_f32_16x16x32_bf16 v[62:65], v[202:205], v[186:189], v[62:65]
	v_mfma_f32_16x16x32_bf16 v[58:61], v[202:205], v[194:197], v[58:61]
	v_mfma_f32_16x16x32_bf16 v[54:57], v[210:213], v[186:189], v[54:57]
	v_mfma_f32_16x16x32_bf16 v[50:53], v[210:213], v[194:197], v[50:53]
	v_mfma_f32_16x16x32_bf16 v[46:49], v[218:221], v[186:189], v[46:49]
	v_mfma_f32_16x16x32_bf16 v[42:45], v[218:221], v[194:197], v[42:45]
	v_mfma_f32_16x16x32_bf16 v[38:41], v[226:229], v[186:189], v[38:41]
	v_mfma_f32_16x16x32_bf16 v[34:37], v[226:229], v[194:197], v[34:37]
	s_setprio 0
	s_barrier
	s_add_u32 s0, s28, s35
	s_addc_u32 s1, s29, 0
	v_readfirstlane_b32 s35, v160
	v_lshl_add_u64 v[166:167], s[0:1], 0, v[134:135]
	s_mov_b32 m0, s35
	s_nop 0
	global_load_lds_dwordx4 v[166:167], off
	v_lshl_add_u64 v[166:167], s[0:1], 0, v[136:137]
	v_readfirstlane_b32 s0, v161
	s_mov_b32 m0, s0
	s_nop 0
	global_load_lds_dwordx4 v[166:167], off
	s_waitcnt vmcnt(6)
	s_barrier
	s_setprio 1
	v_mfma_f32_16x16x32_bf16 v[30:33], v[198:201], v[230:233], v[30:33]
	v_mfma_f32_16x16x32_bf16 v[26:29], v[198:201], v[238:241], v[26:29]
	v_mfma_f32_16x16x32_bf16 v[22:25], v[206:209], v[230:233], v[22:25]
	v_mfma_f32_16x16x32_bf16 v[18:21], v[206:209], v[238:241], v[18:21]
	v_mfma_f32_16x16x32_bf16 v[14:17], v[214:217], v[230:233], v[14:17]
	v_mfma_f32_16x16x32_bf16 v[10:13], v[214:217], v[238:241], v[10:13]
	v_mfma_f32_16x16x32_bf16 v[6:9], v[222:225], v[230:233], v[6:9]
	v_mfma_f32_16x16x32_bf16 v[2:5], v[222:225], v[238:241], v[2:5]
	v_mfma_f32_16x16x32_bf16 v[30:33], v[202:205], v[234:237], v[30:33]
	v_mfma_f32_16x16x32_bf16 v[26:29], v[202:205], v[242:245], v[26:29]
	v_mfma_f32_16x16x32_bf16 v[22:25], v[210:213], v[234:237], v[22:25]
	v_mfma_f32_16x16x32_bf16 v[18:21], v[210:213], v[242:245], v[18:21]
	v_mfma_f32_16x16x32_bf16 v[14:17], v[218:221], v[234:237], v[14:17]
	v_mfma_f32_16x16x32_bf16 v[10:13], v[218:221], v[242:245], v[10:13]
	v_mfma_f32_16x16x32_bf16 v[6:9], v[226:229], v[234:237], v[6:9]
	v_mfma_f32_16x16x32_bf16 v[2:5], v[226:229], v[242:245], v[2:5]
	s_setprio 0
	s_and_b32 s0, s34, 3
	s_cmp_eq_u32 s0, 3
	s_barrier
	s_cbranch_scc0 .LBB0_95
; DI unsigned pack2(float a, float b) { unsigned r; asm("v_cvt_pk_bf16_f32 %0, %1, %2\n\ts_nop 1" : "=v"(r) : "v"(a), "v"(b)); return r; }
; DI u32x4* merge_scratch(PREF p, int region) { const int t = tid512(); return (u32x4*)p.fbuf + (size_t)blockIdx.x * 40960 + region * 8192 + (t >> 6) * 1024 + (t & 63); }
; DI void br_store(PREF p, const f32x4 (&acc)[2][2][4][2], int slot) {
;   u32x4* sb = merge_scratch(p, slot);
; #pragma unroll
;   for (int ai = 0; ai < 2; ++ai)
; #pragma unroll
;     for (int bj = 0; bj < 2; ++bj)
; #pragma unroll
;       for (int m = 0; m < 4; ++m) {
;         u32x4 o;
;         o.x = pack2(acc[ai][bj][m][0][0], acc[ai][bj][m][0][1]); o.y = pack2(acc[ai][bj][m][0][2], acc[ai][bj][m][0][3]);
;         o.z = pack2(acc[ai][bj][m][1][0], acc[ai][bj][m][1][1]); o.w = pack2(acc[ai][bj][m][1][2], acc[ai][bj][m][1][3]);
;         sb[((ai * 2 + bj) * 4 + m) * 64] = o;
;       }
; }
; DI void br_flush(PREF p, f32x4 (&acc)[2][2][4][2], int slot) { br_store(p, acc, slot); zero_acc256(acc); }
	v_mov_b32_e32 v0, v168
	s_and_b32 s0, s12, 0x6000
	s_lshl_b32 s0, s0, 4
	v_lshlrev_b32_e32 v165, 4, v0
	s_add_u32 s0, s63, s0
	v_and_b32_e32 v166, 0xfffffc00, v165
	s_addc_u32 s1, s64, 0
	v_ashrrev_i32_e32 v167, 31, v166
	v_and_b32_e32 v0, 63, v0
	v_lshl_add_u64 v[166:167], v[166:167], 4, s[0:1]
	v_lshlrev_b32_e32 v0, 4, v0
	v_lshl_add_u64 v[166:167], v[166:167], 0, v[0:1]
	v_cvt_pk_bf16_f32 v94, v94, v95
	v_cvt_pk_bf16_f32 v95, v96, v97
	v_cvt_pk_bf16_f32 v96, v90, v91
	v_add_co_u32_e32 v90, vcc, s80, v166
	v_cvt_pk_bf16_f32 v97, v92, v93
	s_movk_i32 s0, 0x3000
	s_nop 0
	v_addc_co_u32_e32 v91, vcc, 0, v167, vcc
	v_add_co_u32_e32 v92, vcc, s40, v166
	v_cvt_pk_bf16_f32 v30, v30, v31
	v_cvt_pk_bf16_f32 v31, v32, v33
	v_cvt_pk_bf16_f32 v32, v26, v27
	v_cvt_pk_bf16_f32 v126, v126, v127
	s_nop 1
	v_addc_co_u32_e32 v93, vcc, 0, v167, vcc
	v_add_co_u32_e32 v26, vcc, s0, v166
	v_cvt_pk_bf16_f32 v127, v128, v129
	v_cvt_pk_bf16_f32 v128, v122, v123
	v_cvt_pk_bf16_f32 v129, v124, v125
	v_cvt_pk_bf16_f32 v118, v118, v119
	v_cvt_pk_bf16_f32 v119, v120, v121
	v_cvt_pk_bf16_f32 v120, v114, v115
	v_cvt_pk_bf16_f32 v121, v116, v117
	v_cvt_pk_bf16_f32 v110, v110, v111
	v_cvt_pk_bf16_f32 v111, v112, v113
	v_cvt_pk_bf16_f32 v112, v106, v107
	v_cvt_pk_bf16_f32 v113, v108, v109
	v_cvt_pk_bf16_f32 v102, v102, v103
	v_cvt_pk_bf16_f32 v103, v104, v105
	v_cvt_pk_bf16_f32 v104, v98, v99
	v_cvt_pk_bf16_f32 v105, v100, v101
	v_cvt_pk_bf16_f32 v86, v86, v87
	v_cvt_pk_bf16_f32 v87, v88, v89
	v_cvt_pk_bf16_f32 v88, v82, v83
	v_cvt_pk_bf16_f32 v89, v84, v85
	v_cvt_pk_bf16_f32 v78, v78, v79
	v_cvt_pk_bf16_f32 v79, v80, v81
	v_cvt_pk_bf16_f32 v80, v74, v75
	v_cvt_pk_bf16_f32 v81, v76, v77
	v_cvt_pk_bf16_f32 v70, v70, v71
	v_cvt_pk_bf16_f32 v71, v72, v73
	v_cvt_pk_bf16_f32 v72, v66, v67
	v_cvt_pk_bf16_f32 v73, v68, v69
	v_cvt_pk_bf16_f32 v62, v62, v63
	v_cvt_pk_bf16_f32 v63, v64, v65
	v_cvt_pk_bf16_f32 v64, v58, v59
	v_cvt_pk_bf16_f32 v65, v60, v61
	v_cvt_pk_bf16_f32 v54, v54, v55
	v_cvt_pk_bf16_f32 v55, v56, v57
	v_cvt_pk_bf16_f32 v56, v50, v51
	v_cvt_pk_bf16_f32 v57, v52, v53
	v_cvt_pk_bf16_f32 v46, v46, v47
	v_cvt_pk_bf16_f32 v47, v48, v49
	v_cvt_pk_bf16_f32 v48, v42, v43
	v_cvt_pk_bf16_f32 v49, v44, v45
	v_cvt_pk_bf16_f32 v38, v38, v39
	v_cvt_pk_bf16_f32 v39, v40, v41
	v_cvt_pk_bf16_f32 v40, v34, v35
	v_cvt_pk_bf16_f32 v41, v36, v37
	v_cvt_pk_bf16_f32 v33, v28, v29
	s_nop 1
	v_addc_co_u32_e32 v27, vcc, 0, v167, vcc
	v_cvt_pk_bf16_f32 v22, v22, v23
	v_cvt_pk_bf16_f32 v23, v24, v25
	v_cvt_pk_bf16_f32 v24, v18, v19
	v_cvt_pk_bf16_f32 v25, v20, v21
	v_cvt_pk_bf16_f32 v14, v14, v15
	v_cvt_pk_bf16_f32 v15, v16, v17
	v_cvt_pk_bf16_f32 v16, v10, v11
	v_cvt_pk_bf16_f32 v17, v12, v13
	v_cvt_pk_bf16_f32 v6, v6, v7
	v_cvt_pk_bf16_f32 v7, v8, v9
	v_cvt_pk_bf16_f32 v8, v2, v3
	v_cvt_pk_bf16_f32 v9, v4, v5
	v_mov_b32_e32 v2, 0
	global_store_dwordx4 v[166:167], v[126:129], off
	global_store_dwordx4 v[166:167], v[118:121], off offset:1024
	global_store_dwordx4 v[166:167], v[110:113], off offset:2048
	global_store_dwordx4 v[166:167], v[102:105], off offset:3072
	global_store_dwordx4 v[92:93], v[94:97], off offset:-4096
	global_store_dwordx4 v[90:91], v[86:89], off offset:1024
	global_store_dwordx4 v[90:91], v[78:81], off offset:2048
	global_store_dwordx4 v[90:91], v[70:73], off offset:3072
	global_store_dwordx4 v[92:93], v[62:65], off
	global_store_dwordx4 v[92:93], v[54:57], off offset:1024
	global_store_dwordx4 v[92:93], v[46:49], off offset:2048
	global_store_dwordx4 v[92:93], v[38:41], off offset:3072
	global_store_dwordx4 v[26:27], v[30:33], off
	global_store_dwordx4 v[26:27], v[22:25], off offset:1024
	global_store_dwordx4 v[26:27], v[14:17], off offset:2048
	global_store_dwordx4 v[26:27], v[6:9], off offset:3072
	v_mov_b32_e32 v3, v2
	v_mov_b32_e32 v4, v2
	v_mov_b32_e32 v5, v2
	v_mov_b32_e32 v6, v2
	v_mov_b32_e32 v7, v2
	v_mov_b32_e32 v8, v2
	v_mov_b32_e32 v9, v2
	v_mov_b32_e32 v10, v2
	v_mov_b32_e32 v11, v2
	v_mov_b32_e32 v12, v2
	v_mov_b32_e32 v13, v2
	v_mov_b32_e32 v14, v2
	v_mov_b32_e32 v15, v2
	v_mov_b32_e32 v16, v2
	v_mov_b32_e32 v17, v2
	v_mov_b32_e32 v18, v2
	v_mov_b32_e32 v19, v2
	v_mov_b32_e32 v20, v2
	v_mov_b32_e32 v21, v2
	v_mov_b32_e32 v22, v2
	v_mov_b32_e32 v23, v2
	v_mov_b32_e32 v24, v2
	v_mov_b32_e32 v25, v2
	v_mov_b32_e32 v26, v2
	v_mov_b32_e32 v27, v2
	v_mov_b32_e32 v28, v2
	v_mov_b32_e32 v29, v2
	v_mov_b32_e32 v30, v2
	v_mov_b32_e32 v31, v2
	v_mov_b32_e32 v32, v2
	v_mov_b32_e32 v33, v2
	v_mov_b32_e32 v34, v2
	v_mov_b32_e32 v35, v2
	v_mov_b32_e32 v36, v2
	v_mov_b32_e32 v37, v2
	v_mov_b32_e32 v38, v2
	v_mov_b32_e32 v39, v2
	v_mov_b32_e32 v40, v2
	v_mov_b32_e32 v41, v2
	v_mov_b32_e32 v42, v2
	v_mov_b32_e32 v43, v2
	v_mov_b32_e32 v44, v2
	v_mov_b32_e32 v45, v2
	v_mov_b32_e32 v46, v2
	v_mov_b32_e32 v47, v2
	v_mov_b32_e32 v48, v2
	v_mov_b32_e32 v49, v2
	v_mov_b32_e32 v50, v2
	v_mov_b32_e32 v51, v2
	v_mov_b32_e32 v52, v2
	v_mov_b32_e32 v53, v2
	v_mov_b32_e32 v54, v2
	v_mov_b32_e32 v55, v2
	v_mov_b32_e32 v56, v2
	v_mov_b32_e32 v57, v2
	v_mov_b32_e32 v58, v2
	v_mov_b32_e32 v59, v2
	v_mov_b32_e32 v60, v2
	v_mov_b32_e32 v61, v2
	v_mov_b32_e32 v62, v2
	v_mov_b32_e32 v63, v2
	v_mov_b32_e32 v64, v2
	v_mov_b32_e32 v65, v2
	v_mov_b32_e32 v66, v2
	v_mov_b32_e32 v67, v2
	v_mov_b32_e32 v68, v2
	v_mov_b32_e32 v69, v2
	v_mov_b32_e32 v70, v2
	v_mov_b32_e32 v71, v2
	v_mov_b32_e32 v72, v2
	v_mov_b32_e32 v73, v2
	v_mov_b32_e32 v74, v2
	v_mov_b32_e32 v75, v2
	v_mov_b32_e32 v76, v2
	v_mov_b32_e32 v77, v2
	v_mov_b32_e32 v78, v2
	v_mov_b32_e32 v79, v2
	v_mov_b32_e32 v80, v2
	v_mov_b32_e32 v81, v2
	v_mov_b32_e32 v82, v2
	v_mov_b32_e32 v83, v2
	v_mov_b32_e32 v84, v2
	v_mov_b32_e32 v85, v2
	v_mov_b32_e32 v86, v2
	v_mov_b32_e32 v87, v2
	v_mov_b32_e32 v88, v2
	v_mov_b32_e32 v89, v2
	v_mov_b32_e32 v90, v2
	v_mov_b32_e32 v91, v2
	v_mov_b32_e32 v92, v2
	v_mov_b32_e32 v93, v2
	v_mov_b32_e32 v94, v2
	v_mov_b32_e32 v95, v2
	v_mov_b32_e32 v96, v2
	v_mov_b32_e32 v97, v2
	v_mov_b32_e32 v98, v2
	v_mov_b32_e32 v99, v2
	v_mov_b32_e32 v100, v2
	v_mov_b32_e32 v101, v2
	v_mov_b32_e32 v102, v2
	v_mov_b32_e32 v103, v2
	v_mov_b32_e32 v104, v2
	v_mov_b32_e32 v105, v2
	v_mov_b32_e32 v106, v2
	v_mov_b32_e32 v107, v2
	v_mov_b32_e32 v108, v2
	v_mov_b32_e32 v109, v2
	v_mov_b32_e32 v110, v2
	v_mov_b32_e32 v111, v2
	v_mov_b32_e32 v112, v2
	v_mov_b32_e32 v113, v2
	v_mov_b32_e32 v114, v2
	v_mov_b32_e32 v115, v2
	v_mov_b32_e32 v116, v2
	v_mov_b32_e32 v117, v2
	v_mov_b32_e32 v118, v2
	v_mov_b32_e32 v119, v2
	v_mov_b32_e32 v120, v2
	v_mov_b32_e32 v121, v2
	v_mov_b32_e32 v122, v2
	v_mov_b32_e32 v123, v2
	v_mov_b32_e32 v124, v2
	v_mov_b32_e32 v125, v2
	v_mov_b32_e32 v126, v2
	v_mov_b32_e32 v127, v2
	v_mov_b32_e32 v128, v2
	v_mov_b32_e32 v129, v2
	s_branch .LBB0_95

; DI unsigned pack2(float a, float b) { unsigned r; asm("v_cvt_pk_bf16_f32 %0, %1, %2\n\ts_nop 1" : "=v"(r) : "v"(a), "v"(b)); return r; }
; DI u32x4* merge_scratch(PREF p, int region) { const int t = tid512(); return (u32x4*)p.fbuf + (size_t)blockIdx.x * 40960 + region * 8192 + (t >> 6) * 1024 + (t & 63); }
; DI void br_store(PREF p, const f32x4 (&acc)[2][2][4][2], int slot) {
;   u32x4* sb = merge_scratch(p, slot);
; #pragma unroll
;   for (int ai = 0; ai < 2; ++ai)
; #pragma unroll
;     for (int bj = 0; bj < 2; ++bj)
; #pragma unroll
;       for (int m = 0; m < 4; ++m) {
;         u32x4 o;
;         o.x = pack2(acc[ai][bj][m][0][0], acc[ai][bj][m][0][1]); o.y = pack2(acc[ai][bj][m][0][2], acc[ai][bj][m][0][3]);
;         o.z = pack2(acc[ai][bj][m][1][0], acc[ai][bj][m][1][1]); o.w = pack2(acc[ai][bj][m][1][2], acc[ai][bj][m][1][3]);
;         sb[((ai * 2 + bj) * 4 + m) * 64] = o;
;       }
; }
; DI void merge_phase(PREF p, int l, unsigned char* lds_all) {
;     ...
;       gemm256<1024, 256, 1024, 1>(acc, p.ys + (size_t)mt * 256 * 1024, W + O_BR + (size_t)dt * 256 * 256, shm, p);
;       br_store(p, acc, 3);
;     }
; #pragma unroll 1
;     for (int n = 0; n < 4; ++n) {
;       f32x4 acc[2][2][4][2]; zero_acc256(acc);
;       gemm256<1024, 1024, 1024>(acc, p.X + (size_t)mt * 256 * 1024, W + O_WM + ((size_t)n * 1024 + dt * 256) * 1024, shm, p);
.LBB0_100:
	s_or_b64 exec, exec, s[10:11]
	v_mov_b32_e32 v0, v168
	v_cvt_pk_bf16_f32 v102, v102, v103
	v_cvt_pk_bf16_f32 v103, v104, v105
	v_cvt_pk_bf16_f32 v105, v96, v97
	v_cvt_pk_bf16_f32 v96, v90, v91
	v_cvt_pk_bf16_f32 v97, v92, v93
	s_nop 0
	v_lshlrev_b32_e32 v130, 4, v0
	v_and_b32_e32 v130, 0xfffffc00, v130
	v_ashrrev_i32_e32 v131, 31, v130
	v_and_b32_e32 v0, 63, v0
	v_lshl_add_u64 v[130:131], v[130:131], 4, s[18:19]
	v_lshlrev_b32_e32 v0, 4, v0
	v_lshl_add_u64 v[130:131], v[130:131], 0, v[0:1]
	v_add_co_u32_e32 v90, vcc, s80, v130
	s_movk_i32 s0, 0x3000
	s_nop 0
	v_addc_co_u32_e32 v91, vcc, 0, v131, vcc
	v_add_co_u32_e32 v92, vcc, s40, v130
	v_cvt_pk_bf16_f32 v30, v30, v31
	v_cvt_pk_bf16_f32 v31, v32, v33
	v_cvt_pk_bf16_f32 v32, v26, v27
	s_mov_b32 s23, 0
	s_nop 0
	v_addc_co_u32_e32 v93, vcc, 0, v131, vcc
	v_add_co_u32_e32 v26, vcc, s0, v130
	s_mov_b64 s[0:1], s[14:15]
	s_add_u32 s26, s0, s8
	s_addc_u32 s27, s1, s9
	s_lshl_b32 s28, s22, 8
	s_ashr_i32 s29, s28, 31
	s_add_u32 s30, s26, 0x40000
	s_addc_u32 s31, s27, 0
	s_add_u32 s34, s26, 0x40780
	s_addc_u32 s35, s27, 0
	s_lshl_b64 s[0:1], s[28:29], 2
	s_add_u32 s25, s49, s0
	s_addc_u32 s48, s69, s1
	s_lshl_b32 s12, s24, 8
	s_lshl_b64 s[0:1], s[28:29], 1
	s_add_u32 s36, s16, s0
	s_addc_u32 s37, s17, s1
	s_or_b32 s13, s12, 0x80
	s_lshl_b64 s[0:1], s[28:29], 11
	s_add_u32 s40, s46, s0
	v_addc_co_u32_e32 v27, vcc, 0, v131, vcc
	s_addc_u32 s41, s47, s1
	v_cvt_pk_bf16_f32 v126, v126, v127
	v_cvt_pk_bf16_f32 v127, v128, v129
	v_cvt_pk_bf16_f32 v128, v122, v123
	v_cvt_pk_bf16_f32 v129, v124, v125
	global_store_dwordx4 v[130:131], v[126:129], off
	v_cvt_pk_bf16_f32 v118, v118, v119
	v_cvt_pk_bf16_f32 v119, v120, v121
	v_cvt_pk_bf16_f32 v120, v114, v115
	v_cvt_pk_bf16_f32 v121, v116, v117
	global_store_dwordx4 v[130:131], v[118:121], off offset:1024
	v_cvt_pk_bf16_f32 v110, v110, v111
	v_cvt_pk_bf16_f32 v111, v112, v113
	v_cvt_pk_bf16_f32 v112, v106, v107
	v_cvt_pk_bf16_f32 v113, v108, v109
	global_store_dwordx4 v[130:131], v[110:113], off offset:2048
	v_cvt_pk_bf16_f32 v104, v94, v95
	global_store_dwordx4 v[130:131], v[102:105], off offset:3072
	v_cvt_pk_bf16_f32 v94, v98, v99
	v_cvt_pk_bf16_f32 v95, v100, v101
	global_store_dwordx4 v[92:93], v[94:97], off offset:-4096
	v_cvt_pk_bf16_f32 v86, v86, v87
	v_cvt_pk_bf16_f32 v87, v88, v89
	v_cvt_pk_bf16_f32 v88, v82, v83
	v_cvt_pk_bf16_f32 v89, v84, v85
	global_store_dwordx4 v[90:91], v[86:89], off offset:1024
	v_cvt_pk_bf16_f32 v78, v78, v79
	v_cvt_pk_bf16_f32 v79, v80, v81
	v_cvt_pk_bf16_f32 v80, v74, v75
	v_cvt_pk_bf16_f32 v81, v76, v77
	global_store_dwordx4 v[90:91], v[78:81], off offset:2048
	v_cvt_pk_bf16_f32 v66, v66, v67
	v_cvt_pk_bf16_f32 v67, v68, v69
	v_cvt_pk_bf16_f32 v68, v58, v59
	v_cvt_pk_bf16_f32 v69, v60, v61
	global_store_dwordx4 v[90:91], v[66:69], off offset:3072
	v_cvt_pk_bf16_f32 v58, v70, v71
	v_cvt_pk_bf16_f32 v59, v72, v73
	v_cvt_pk_bf16_f32 v60, v62, v63
	v_cvt_pk_bf16_f32 v61, v64, v65
	global_store_dwordx4 v[92:93], v[58:61], off
	v_cvt_pk_bf16_f32 v54, v54, v55
	v_cvt_pk_bf16_f32 v55, v56, v57
	v_cvt_pk_bf16_f32 v56, v50, v51
	v_cvt_pk_bf16_f32 v57, v52, v53
	global_store_dwordx4 v[92:93], v[54:57], off offset:1024
	v_cvt_pk_bf16_f32 v46, v46, v47
	v_cvt_pk_bf16_f32 v47, v48, v49
	v_cvt_pk_bf16_f32 v48, v42, v43
	v_cvt_pk_bf16_f32 v49, v44, v45
	global_store_dwordx4 v[92:93], v[46:49], off offset:2048
	v_cvt_pk_bf16_f32 v38, v38, v39
	v_cvt_pk_bf16_f32 v39, v40, v41
	v_cvt_pk_bf16_f32 v40, v34, v35
	v_cvt_pk_bf16_f32 v41, v36, v37
	global_store_dwordx4 v[92:93], v[38:41], off offset:3072
	v_cvt_pk_bf16_f32 v33, v28, v29
	global_store_dwordx4 v[26:27], v[30:33], off
	v_cvt_pk_bf16_f32 v22, v22, v23
	v_cvt_pk_bf16_f32 v23, v24, v25
	v_cvt_pk_bf16_f32 v24, v18, v19
	v_cvt_pk_bf16_f32 v25, v20, v21
	global_store_dwordx4 v[26:27], v[22:25], off offset:1024
	v_cvt_pk_bf16_f32 v14, v14, v15
	v_cvt_pk_bf16_f32 v15, v16, v17
	v_cvt_pk_bf16_f32 v16, v10, v11
	v_cvt_pk_bf16_f32 v17, v12, v13
	global_store_dwordx4 v[26:27], v[14:17], off offset:2048
	v_cvt_pk_bf16_f32 v6, v6, v7
	v_cvt_pk_bf16_f32 v7, v8, v9
	v_cvt_pk_bf16_f32 v8, v2, v3
	v_cvt_pk_bf16_f32 v9, v4, v5
	global_store_dwordx4 v[26:27], v[6:9], off offset:3072
	s_branch .LBB0_102

; DI u32x4 pack8(const float* f) { u32x4 o; o.x = pack2(f[0], f[1]); o.y = pack2(f[2], f[3]); o.z = pack2(f[4], f[5]); o.w = pack2(f[6], f[7]); return o; }
; DI void gate_reg(PREF p, int l, int n, f32x4 (&acc)[2][2][4][2], int dt) {
;     ...
;         if (n > 0) {
;           float o[8]; unpack8(pv[m], o);
; #pragma unroll
;           for (int e = 0; e < 8; ++e) v[e] += o[e];
;         }
;         if (n < 3) ssum[((ai * 2 + bj) * 4 + m) * 64] = pack8(v);
; #pragma unroll
;         for (int nn = 0; nn < 2; ++nn)
; #pragma unroll
;           for (int j = 0; j < 4; ++j) acc[ai][bj][m][nn][j] = v[nn * 4 + j];
.LBB0_118:
	s_cmp_eq_u32 s23, 3
	s_cselect_b64 s[42:43], -1, 0
	s_cmp_lg_u32 s23, 3
	s_cselect_b64 s[44:45], -1, 0
	s_and_b64 vcc, exec, s[42:43]
	s_cbranch_vccnz .LBB0_120
	v_cvt_pk_bf16_f32 v186, v158, v159
	v_cvt_pk_bf16_f32 v187, v154, v155
	v_cvt_pk_bf16_f32 v188, v150, v151
	v_cvt_pk_bf16_f32 v189, v152, v153
	global_store_dwordx4 v[164:165], v[186:189], off

; DI u32x4 pack8(const float* f) { u32x4 o; o.x = pack2(f[0], f[1]); o.y = pack2(f[2], f[3]); o.z = pack2(f[4], f[5]); o.w = pack2(f[6], f[7]); return o; }
; DI void gate_reg(PREF p, int l, int n, f32x4 (&acc)[2][2][4][2], int dt) {
;     ...
;         if (n > 0) {
;           float o[8]; unpack8(pv[m], o);
; #pragma unroll
;           for (int e = 0; e < 8; ++e) v[e] += o[e];
;         }
;         if (n < 3) ssum[((ai * 2 + bj) * 4 + m) * 64] = pack8(v);
; #pragma unroll
;         for (int nn = 0; nn < 2; ++nn)
; #pragma unroll
;           for (int j = 0; j < 4; ++j) acc[ai][bj][m][nn][j] = v[nn * 4 + j];
.LBB0_122:
	v_cndmask_b32_e64 v0, 0, 1, s[44:45]
	v_cmp_ne_u32_e64 s[10:11], 1, v0
	s_andn2_b64 vcc, exec, s[44:45]
	s_cbranch_vccnz .LBB0_124
	v_cvt_pk_bf16_f32 v186, v146, v147
	v_cvt_pk_bf16_f32 v187, v142, v143
	v_cvt_pk_bf16_f32 v188, v138, v139
	v_cvt_pk_bf16_f32 v189, v140, v141
	global_store_dwordx4 v[164:165], v[186:189], off offset:1024

; DI u32x4 pack8(const float* f) { u32x4 o; o.x = pack2(f[0], f[1]); o.y = pack2(f[2], f[3]); o.z = pack2(f[4], f[5]); o.w = pack2(f[6], f[7]); return o; }
; DI void gate_reg(PREF p, int l, int n, f32x4 (&acc)[2][2][4][2], int dt) {
;     ...
;         if (n > 0) {
;           float o[8]; unpack8(pv[m], o);
; #pragma unroll
;           for (int e = 0; e < 8; ++e) v[e] += o[e];
;         }
;         if (n < 3) ssum[((ai * 2 + bj) * 4 + m) * 64] = pack8(v);
; #pragma unroll
;         for (int nn = 0; nn < 2; ++nn)
; #pragma unroll
;           for (int j = 0; j < 4; ++j) acc[ai][bj][m][nn][j] = v[nn * 4 + j];
.LBB0_126:
	s_and_b64 vcc, exec, s[10:11]
	s_cbranch_vccnz .LBB0_128
	v_cvt_pk_bf16_f32 v126, v134, v135
	v_cvt_pk_bf16_f32 v127, v130, v131
	v_cvt_pk_bf16_f32 v128, v136, v137
	v_cvt_pk_bf16_f32 v129, v132, v133
	global_store_dwordx4 v[164:165], v[126:129], off offset:2048

; DI u32x4 pack8(const float* f) { u32x4 o; o.x = pack2(f[0], f[1]); o.y = pack2(f[2], f[3]); o.z = pack2(f[4], f[5]); o.w = pack2(f[6], f[7]); return o; }
; DI void gate_reg(PREF p, int l, int n, f32x4 (&acc)[2][2][4][2], int dt) {
;     ...
;         if (n > 0) {
;           float o[8]; unpack8(pv[m], o);
; #pragma unroll
;           for (int e = 0; e < 8; ++e) v[e] += o[e];
;         }
;         if (n < 3) ssum[((ai * 2 + bj) * 4 + m) * 64] = pack8(v);
; #pragma unroll
;         for (int nn = 0; nn < 2; ++nn)
; #pragma unroll
;           for (int j = 0; j < 4; ++j) acc[ai][bj][m][nn][j] = v[nn * 4 + j];
.LBB0_130:
	s_and_b64 vcc, exec, s[10:11]
	s_cbranch_vccnz .LBB0_132
	v_cvt_pk_bf16_f32 v114, v144, v145
	v_cvt_pk_bf16_f32 v115, v148, v149
	v_cvt_pk_bf16_f32 v116, v156, v157
	v_cvt_pk_bf16_f32 v117, v160, v161
	global_store_dwordx4 v[164:165], v[114:117], off offset:3072

; DI u32x4 pack8(const float* f) { u32x4 o; o.x = pack2(f[0], f[1]); o.y = pack2(f[2], f[3]); o.z = pack2(f[4], f[5]); o.w = pack2(f[6], f[7]); return o; }
; DI void gate_reg(PREF p, int l, int n, f32x4 (&acc)[2][2][4][2], int dt) {
;     ...
;         if (n > 0) {
;           float o[8]; unpack8(pv[m], o);
; #pragma unroll
;           for (int e = 0; e < 8; ++e) v[e] += o[e];
;         }
;         if (n < 3) ssum[((ai * 2 + bj) * 4 + m) * 64] = pack8(v);
; #pragma unroll
;         for (int nn = 0; nn < 2; ++nn)
; #pragma unroll
;           for (int j = 0; j < 4; ++j) acc[ai][bj][m][nn][j] = v[nn * 4 + j];
.LBB0_142:
	s_and_b64 vcc, exec, s[10:11]
	s_cbranch_vccnz .LBB0_144
	v_add_co_u32_e32 v186, vcc, 0x1000, v164
	v_cvt_pk_bf16_f32 v126, v110, v111
	v_cvt_pk_bf16_f32 v127, v112, v113
	v_cvt_pk_bf16_f32 v128, v106, v107
	v_cvt_pk_bf16_f32 v129, v108, v109
	s_nop 1
	v_addc_co_u32_e32 v187, vcc, 0, v165, vcc
	global_store_dwordx4 v[186:187], v[126:129], off

; DI u32x4 pack8(const float* f) { u32x4 o; o.x = pack2(f[0], f[1]); o.y = pack2(f[2], f[3]); o.z = pack2(f[4], f[5]); o.w = pack2(f[6], f[7]); return o; }
; DI void gate_reg(PREF p, int l, int n, f32x4 (&acc)[2][2][4][2], int dt) {
;     ...
;         if (n > 0) {
;           float o[8]; unpack8(pv[m], o);
; #pragma unroll
;           for (int e = 0; e < 8; ++e) v[e] += o[e];
;         }
;         if (n < 3) ssum[((ai * 2 + bj) * 4 + m) * 64] = pack8(v);
; #pragma unroll
;         for (int nn = 0; nn < 2; ++nn)
; #pragma unroll
;           for (int j = 0; j < 4; ++j) acc[ai][bj][m][nn][j] = v[nn * 4 + j];
.LBB0_146:
	s_and_b64 vcc, exec, s[10:11]
	s_cbranch_vccnz .LBB0_148
	v_add_co_u32_e32 v126, vcc, 0x1000, v164
	v_cvt_pk_bf16_f32 v122, v102, v103
	v_cvt_pk_bf16_f32 v123, v104, v105
	v_cvt_pk_bf16_f32 v124, v98, v99
	v_cvt_pk_bf16_f32 v125, v100, v101
	s_nop 1
	v_addc_co_u32_e32 v127, vcc, 0, v165, vcc
	global_store_dwordx4 v[126:127], v[122:125], off offset:1024

; DI u32x4 pack8(const float* f) { u32x4 o; o.x = pack2(f[0], f[1]); o.y = pack2(f[2], f[3]); o.z = pack2(f[4], f[5]); o.w = pack2(f[6], f[7]); return o; }
; DI void gate_reg(PREF p, int l, int n, f32x4 (&acc)[2][2][4][2], int dt) {
;     ...
;         if (n > 0) {
;           float o[8]; unpack8(pv[m], o);
; #pragma unroll
;           for (int e = 0; e < 8; ++e) v[e] += o[e];
;         }
;         if (n < 3) ssum[((ai * 2 + bj) * 4 + m) * 64] = pack8(v);
; #pragma unroll
;         for (int nn = 0; nn < 2; ++nn)
; #pragma unroll
;           for (int j = 0; j < 4; ++j) acc[ai][bj][m][nn][j] = v[nn * 4 + j];
.LBB0_150:
	s_and_b64 vcc, exec, s[10:11]
	s_cbranch_vccnz .LBB0_152
	v_add_co_u32_e32 v94, vcc, 0x1000, v164
	v_cvt_pk_bf16_f32 v90, v122, v123
	v_cvt_pk_bf16_f32 v91, v118, v119
	v_cvt_pk_bf16_f32 v92, v124, v125
	v_cvt_pk_bf16_f32 v93, v120, v121
	s_nop 1
	v_addc_co_u32_e32 v95, vcc, 0, v165, vcc
	global_store_dwordx4 v[94:95], v[90:93], off offset:2048

; DI u32x4 pack8(const float* f) { u32x4 o; o.x = pack2(f[0], f[1]); o.y = pack2(f[2], f[3]); o.z = pack2(f[4], f[5]); o.w = pack2(f[6], f[7]); return o; }
; DI void gate_reg(PREF p, int l, int n, f32x4 (&acc)[2][2][4][2], int dt) {
;     ...
;         if (n > 0) {
;           float o[8]; unpack8(pv[m], o);
; #pragma unroll
;           for (int e = 0; e < 8; ++e) v[e] += o[e];
;         }
;         if (n < 3) ssum[((ai * 2 + bj) * 4 + m) * 64] = pack8(v);
; #pragma unroll
;         for (int nn = 0; nn < 2; ++nn)
; #pragma unroll
;           for (int j = 0; j < 4; ++j) acc[ai][bj][m][nn][j] = v[nn * 4 + j];
.LBB0_154:
	s_and_b64 vcc, exec, s[10:11]
	s_cbranch_vccnz .LBB0_156
	v_add_co_u32_e32 v86, vcc, 0x1000, v164
	v_cvt_pk_bf16_f32 v82, v126, v127
	v_cvt_pk_bf16_f32 v83, v114, v115
	v_cvt_pk_bf16_f32 v84, v128, v129
	v_cvt_pk_bf16_f32 v85, v116, v117
	s_nop 1
	v_addc_co_u32_e32 v87, vcc, 0, v165, vcc
	global_store_dwordx4 v[86:87], v[82:85], off offset:3072

; DI u32x4 pack8(const float* f) { u32x4 o; o.x = pack2(f[0], f[1]); o.y = pack2(f[2], f[3]); o.z = pack2(f[4], f[5]); o.w = pack2(f[6], f[7]); return o; }
; DI void gate_reg(PREF p, int l, int n, f32x4 (&acc)[2][2][4][2], int dt) {
;     ...
;         if (n > 0) {
;           float o[8]; unpack8(pv[m], o);
; #pragma unroll
;           for (int e = 0; e < 8; ++e) v[e] += o[e];
;         }
;         if (n < 3) ssum[((ai * 2 + bj) * 4 + m) * 64] = pack8(v);
; #pragma unroll
;         for (int nn = 0; nn < 2; ++nn)
; #pragma unroll
;           for (int j = 0; j < 4; ++j) acc[ai][bj][m][nn][j] = v[nn * 4 + j];
.LBB0_166:
	s_and_b64 vcc, exec, s[10:11]
	s_cbranch_vccnz .LBB0_168
	v_add_co_u32_e32 v186, vcc, 0x2000, v164
	v_cvt_pk_bf16_f32 v94, v78, v79
	v_cvt_pk_bf16_f32 v95, v80, v81
	v_cvt_pk_bf16_f32 v96, v74, v75
	v_cvt_pk_bf16_f32 v97, v76, v77
	s_nop 1
	v_addc_co_u32_e32 v187, vcc, 0, v165, vcc
	global_store_dwordx4 v[186:187], v[94:97], off

; DI u32x4 pack8(const float* f) { u32x4 o; o.x = pack2(f[0], f[1]); o.y = pack2(f[2], f[3]); o.z = pack2(f[4], f[5]); o.w = pack2(f[6], f[7]); return o; }
; DI void gate_reg(PREF p, int l, int n, f32x4 (&acc)[2][2][4][2], int dt) {
;     ...
;         if (n > 0) {
;           float o[8]; unpack8(pv[m], o);
; #pragma unroll
;           for (int e = 0; e < 8; ++e) v[e] += o[e];
;         }
;         if (n < 3) ssum[((ai * 2 + bj) * 4 + m) * 64] = pack8(v);
; #pragma unroll
;         for (int nn = 0; nn < 2; ++nn)
; #pragma unroll
;           for (int j = 0; j < 4; ++j) acc[ai][bj][m][nn][j] = v[nn * 4 + j];
.LBB0_170:
	s_and_b64 vcc, exec, s[10:11]
	s_cbranch_vccnz .LBB0_172
	v_add_co_u32_e32 v94, vcc, 0x2000, v164
	v_cvt_pk_bf16_f32 v90, v70, v71
	v_cvt_pk_bf16_f32 v91, v72, v73
	v_cvt_pk_bf16_f32 v92, v66, v67
	v_cvt_pk_bf16_f32 v93, v68, v69
	s_nop 1
	v_addc_co_u32_e32 v95, vcc, 0, v165, vcc
	global_store_dwordx4 v[94:95], v[90:93], off offset:1024

; DI u32x4 pack8(const float* f) { u32x4 o; o.x = pack2(f[0], f[1]); o.y = pack2(f[2], f[3]); o.z = pack2(f[4], f[5]); o.w = pack2(f[6], f[7]); return o; }
; DI void gate_reg(PREF p, int l, int n, f32x4 (&acc)[2][2][4][2], int dt) {
;     ...
;         if (n > 0) {
;           float o[8]; unpack8(pv[m], o);
; #pragma unroll
;           for (int e = 0; e < 8; ++e) v[e] += o[e];
;         }
;         if (n < 3) ssum[((ai * 2 + bj) * 4 + m) * 64] = pack8(v);
; #pragma unroll
;         for (int nn = 0; nn < 2; ++nn)
; #pragma unroll
;           for (int j = 0; j < 4; ++j) acc[ai][bj][m][nn][j] = v[nn * 4 + j];
.LBB0_174:
	s_and_b64 vcc, exec, s[10:11]
	s_cbranch_vccnz .LBB0_176
	v_add_co_u32_e32 v62, vcc, 0x2000, v164
	v_cvt_pk_bf16_f32 v58, v90, v91
	v_cvt_pk_bf16_f32 v59, v86, v87
	v_cvt_pk_bf16_f32 v60, v92, v93
	v_cvt_pk_bf16_f32 v61, v88, v89
	s_nop 1
	v_addc_co_u32_e32 v63, vcc, 0, v165, vcc
	global_store_dwordx4 v[62:63], v[58:61], off offset:2048

; DI u32x4 pack8(const float* f) { u32x4 o; o.x = pack2(f[0], f[1]); o.y = pack2(f[2], f[3]); o.z = pack2(f[4], f[5]); o.w = pack2(f[6], f[7]); return o; }
; DI void gate_reg(PREF p, int l, int n, f32x4 (&acc)[2][2][4][2], int dt) {
;     ...
;         if (n > 0) {
;           float o[8]; unpack8(pv[m], o);
; #pragma unroll
;           for (int e = 0; e < 8; ++e) v[e] += o[e];
;         }
;         if (n < 3) ssum[((ai * 2 + bj) * 4 + m) * 64] = pack8(v);
; #pragma unroll
;         for (int nn = 0; nn < 2; ++nn)
; #pragma unroll
;           for (int j = 0; j < 4; ++j) acc[ai][bj][m][nn][j] = v[nn * 4 + j];
.LBB0_178:
	s_and_b64 vcc, exec, s[10:11]
	s_cbranch_vccnz .LBB0_180
	v_add_co_u32_e32 v54, vcc, 0x2000, v164
	v_cvt_pk_bf16_f32 v50, v94, v95
	v_cvt_pk_bf16_f32 v51, v82, v83
	v_cvt_pk_bf16_f32 v52, v96, v97
	v_cvt_pk_bf16_f32 v53, v84, v85
	s_nop 1
	v_addc_co_u32_e32 v55, vcc, 0, v165, vcc
	global_store_dwordx4 v[54:55], v[50:53], off offset:3072

; DI u32x4 pack8(const float* f) { u32x4 o; o.x = pack2(f[0], f[1]); o.y = pack2(f[2], f[3]); o.z = pack2(f[4], f[5]); o.w = pack2(f[6], f[7]); return o; }
; DI void gate_reg(PREF p, int l, int n, f32x4 (&acc)[2][2][4][2], int dt) {
;     ...
;         if (n > 0) {
;           float o[8]; unpack8(pv[m], o);
; #pragma unroll
;           for (int e = 0; e < 8; ++e) v[e] += o[e];
;         }
;         if (n < 3) ssum[((ai * 2 + bj) * 4 + m) * 64] = pack8(v);
; #pragma unroll
;         for (int nn = 0; nn < 2; ++nn)
; #pragma unroll
;           for (int j = 0; j < 4; ++j) acc[ai][bj][m][nn][j] = v[nn * 4 + j];
.LBB0_190:
	s_and_b64 vcc, exec, s[10:11]
	s_cbranch_vccnz .LBB0_192
	v_add_co_u32_e32 v62, vcc, 0x3000, v164
	v_cvt_pk_bf16_f32 v42, v46, v47
	v_cvt_pk_bf16_f32 v43, v48, v49
	v_cvt_pk_bf16_f32 v44, v38, v39
	v_cvt_pk_bf16_f32 v45, v40, v41
	s_nop 1
	v_addc_co_u32_e32 v63, vcc, 0, v165, vcc
	global_store_dwordx4 v[62:63], v[42:45], off

; DI u32x4 pack8(const float* f) { u32x4 o; o.x = pack2(f[0], f[1]); o.y = pack2(f[2], f[3]); o.z = pack2(f[4], f[5]); o.w = pack2(f[6], f[7]); return o; }
; DI void gate_reg(PREF p, int l, int n, f32x4 (&acc)[2][2][4][2], int dt) {
;     ...
;         if (n > 0) {
;           float o[8]; unpack8(pv[m], o);
; #pragma unroll
;           for (int e = 0; e < 8; ++e) v[e] += o[e];
;         }
;         if (n < 3) ssum[((ai * 2 + bj) * 4 + m) * 64] = pack8(v);
; #pragma unroll
;         for (int nn = 0; nn < 2; ++nn)
; #pragma unroll
;           for (int j = 0; j < 4; ++j) acc[ai][bj][m][nn][j] = v[nn * 4 + j];
.LBB0_194:
	s_and_b64 vcc, exec, s[10:11]
	s_cbranch_vccnz .LBB0_196
	v_add_co_u32_e32 v42, vcc, 0x3000, v164
	v_cvt_pk_bf16_f32 v30, v34, v35
	v_cvt_pk_bf16_f32 v31, v36, v37
	v_cvt_pk_bf16_f32 v32, v26, v27
	v_cvt_pk_bf16_f32 v33, v28, v29
	s_nop 1
	v_addc_co_u32_e32 v43, vcc, 0, v165, vcc
	global_store_dwordx4 v[42:43], v[30:33], off offset:1024

; DI float sigm(float x) { return 1.f / (1.f + __expf(-x)); }
; DI u32x4 pack8(const float* f) { u32x4 o; o.x = pack2(f[0], f[1]); o.y = pack2(f[2], f[3]); o.z = pack2(f[4], f[5]); o.w = pack2(f[6], f[7]); return o; }
; DI void gate_reg(PREF p, int l, int n, f32x4 (&acc)[2][2][4][2], int dt) {
;     ...
;       for (int m = 0; m < 4; ++m) {
;         float b[8]; unpack8(bn[m], b);
;         float v[8];
; #pragma unroll
;         for (int nn = 0; nn < 2; ++nn)
; #pragma unroll
;           for (int j = 0; j < 4; ++j) v[nn * 4 + j] = sigm(acc[ai][bj][m][nn][j] + bias[bj][nn]) * b[nn * 4 + j];
;         if (n > 0) {
;           float o[8]; unpack8(pv[m], o);
; #pragma unroll
;           for (int e = 0; e < 8; ++e) v[e] += o[e];
;         }
;         if (n < 3) ssum[((ai * 2 + bj) * 4 + m) * 64] = pack8(v);
; #pragma unroll
;         for (int nn = 0; nn < 2; ++nn)
; #pragma unroll
;           for (int j = 0; j < 4; ++j) acc[ai][bj][m][nn][j] = v[nn * 4 + j];
;       }
.LBB0_198:
	s_and_b64 vcc, exec, s[10:11]
	s_cbranch_vccnz .LBB0_200
	v_add_co_u32_e32 v30, vcc, 0x3000, v164
	v_cvt_pk_bf16_f32 v18, v22, v23
	v_cvt_pk_bf16_f32 v19, v24, v25
	v_cvt_pk_bf16_f32 v20, v14, v15
	v_cvt_pk_bf16_f32 v21, v16, v17
	s_nop 1
	v_addc_co_u32_e32 v31, vcc, 0, v165, vcc
	global_store_dwordx4 v[30:31], v[18:21], off offset:2048

; DI u32x4 pack8(const float* f) { u32x4 o; o.x = pack2(f[0], f[1]); o.y = pack2(f[2], f[3]); o.z = pack2(f[4], f[5]); o.w = pack2(f[6], f[7]); return o; }
; DI void lds_barrier() { asm volatile("s_waitcnt lgkmcnt(0)\n\ts_barrier" ::: "memory"); }
; DI int tid512() { int t = threadIdx.x; asm volatile("" : "+v"(t)); return t; }
; template <int AI, int BJ>
; DI void stage_q(const f32x4 (&acc)[2][2][4][2], float* Cs) {
;   const int t = tid512(), wid = t >> 6, lane = t & 63, wr = wid >> 2, wc = wid & 3, fr = lane & 15, fq = lane >> 4;
;   lds_barrier();
; #pragma unroll
;   for (int m = 0; m < 4; ++m)
; #pragma unroll
;     for (int n = 0; n < 2; ++n)
; #pragma unroll
;       for (int j = 0; j < 4; ++j) Cs[(wr * 64 + m * 16 + fq * 4 + j) * CST + wc * 32 + n * 16 + fr] = acc[AI][BJ][m][n][j];
;   lds_barrier();
; }
; template <int AI, int BJ>
; DI void mg_quadrant(PREF p, const f32x4 (&acc)[2][2][4][2], int mt, int dt, float* Cs) {
;   const int t = tid512();
;   const int row0 = mt * 256 + AI * 128, col0 = dt * 256 + BJ * 128;
;   stage_q<AI, BJ>(acc, Cs);
; #pragma unroll
;   for (int q = 0; q < 4; ++q) {
;     int r = (t >> 4) + 32 * q, c = (t & 15) * 8;
;     float v[8]; ld8(Cs + r * CST + c, v);
;     *(u32x4*)(p.mg + (size_t)(row0 + r) * 1024 + col0 + c) = pack8(v);
;   }
.LBB0_202:
	s_and_b64 vcc, exec, s[10:11]
	s_cbranch_vccnz .LBB0_204
	v_add_co_u32_e32 v18, vcc, 0x3000, v164
	v_cvt_pk_bf16_f32 v6, v10, v11
	v_cvt_pk_bf16_f32 v7, v12, v13
	v_cvt_pk_bf16_f32 v8, v2, v3
	v_cvt_pk_bf16_f32 v9, v4, v5
	s_nop 1
	v_addc_co_u32_e32 v19, vcc, 0, v165, vcc
	global_store_dwordx4 v[18:19], v[6:9], off offset:3072
.LBB0_204:
	s_andn2_b64 vcc, exec, s[42:43]
	s_cbranch_vccnz .LBB0_101
	v_mov_b32_e32 v8, v168
	v_mov_b32_e32 v0, v168
	s_waitcnt lgkmcnt(0)
	s_barrier
	s_nop 0
	v_and_b32_e32 v6, 15, v0
	v_lshrrev_b32_e32 v7, 2, v0
	v_lshlrev_b32_e32 v0, 1, v0
	v_lshlrev_b32_e32 v6, 2, v6
	v_and_b32_e32 v7, 0xfffffcc, v7
	v_and_or_b32 v0, v0, s89, v6
	v_mad_u64_u32 v[6:7], s[0:1], v7, s92, v[0:1]
	v_add_u32_e32 v0, 0x400, v6
	ds_write2_b32 v6, v158, v150 offset1:16
	ds_write2_b32 v6, v159, v151 offset0:132 offset1:148
	ds_write2_b32 v0, v154, v152 offset0:8 offset1:24
	ds_write2_b32 v0, v155, v153 offset0:140 offset1:156
	v_add_u32_e32 v0, 0x2000, v6
	ds_write2_b32 v0, v146, v138 offset0:64 offset1:80
	ds_write2_b32 v0, v147, v139 offset0:196 offset1:212
	v_add_u32_e32 v0, 0x2400, v6
	ds_write2_b32 v0, v142, v140 offset0:72 offset1:88
	ds_write2_b32 v0, v143, v141 offset0:204 offset1:220
	v_add_u32_e32 v0, 0x4000, v6
	ds_write2_b32 v0, v134, v136 offset0:128 offset1:144
	v_add_u32_e32 v0, 0x4400, v6
	ds_write2_b32 v0, v135, v137 offset0:4 offset1:20
	ds_write2_b32 v0, v130, v132 offset0:136 offset1:152
	v_add_u32_e32 v0, 0x4800, v6
	ds_write2_b32 v0, v131, v133 offset0:12 offset1:28
	v_add_u32_e32 v0, 0x6000, v6
	ds_write2_b32 v0, v144, v156 offset0:192 offset1:208
	v_add_u32_e32 v0, 0x6400, v6
	ds_write2_b32 v0, v145, v157 offset0:68 offset1:84
	ds_write2_b32 v0, v148, v160 offset0:200 offset1:216
	v_add_u32_e32 v0, 0x6800, v6
	ds_write2_b32 v0, v149, v161 offset0:76 offset1:92
	v_ashrrev_i32_e32 v30, 4, v8
	v_lshlrev_b32_e32 v0, 3, v8
	v_and_b32_e32 v0, 0x78, v0
	v_mul_lo_u32 v6, v30, s92
	s_waitcnt lgkmcnt(0)
	s_barrier
	v_lshl_add_u32 v52, v0, 2, v6
	ds_read_b128 v[6:9], v52
	ds_read_b128 v[18:21], v52 offset:16
	v_add_u32_e32 v44, s12, v30
	v_lshlrev_b32_e32 v0, 1, v0
	v_ashrrev_i32_e32 v45, 31, v44
	v_lshl_add_u64 v[42:43], s[36:37], 0, v[0:1]
	v_lshlrev_b64 v[50:51], 11, v[44:45]
	s_waitcnt lgkmcnt(1)
	v_cvt_pk_bf16_f32 v6, v6, v7
	v_cvt_pk_bf16_f32 v7, v8, v9
	s_waitcnt lgkmcnt(0)
	v_cvt_pk_bf16_f32 v8, v18, v19
	v_cvt_pk_bf16_f32 v9, v20, v21
	ds_read_b128 v[18:21], v52 offset:16896
	ds_read_b128 v[30:33], v52 offset:16912
	v_lshl_add_u64 v[50:51], v[42:43], 0, v[50:51]
	global_store_dwordx4 v[50:51], v[6:9], off
	v_mov_b32_e32 v0, v168
	s_waitcnt lgkmcnt(0)
	v_cvt_pk_bf16_f32 v8, v30, v31
	v_add_u32_e32 v30, 32, v44
	v_ashrrev_i32_e32 v31, 31, v30
	v_lshlrev_b64 v[50:51], 11, v[30:31]
	v_cvt_pk_bf16_f32 v6, v18, v19
	v_cvt_pk_bf16_f32 v7, v20, v21
	v_cvt_pk_bf16_f32 v9, v32, v33
	ds_read_b128 v[18:21], v52 offset:33792
	ds_read_b128 v[30:33], v52 offset:33808
	v_lshl_add_u64 v[50:51], v[42:43], 0, v[50:51]
	global_store_dwordx4 v[50:51], v[6:9], off
	s_waitcnt lgkmcnt(0)
	s_nop 0
	v_cvt_pk_bf16_f32 v8, v30, v31
	v_add_u32_e32 v30, 64, v44
	v_ashrrev_i32_e32 v31, 31, v30
	v_lshlrev_b64 v[50:51], 11, v[30:31]
	v_cvt_pk_bf16_f32 v6, v18, v19
	v_cvt_pk_bf16_f32 v7, v20, v21
	ds_read_b128 v[18:21], v52 offset:50688
	v_lshl_add_u64 v[50:51], v[42:43], 0, v[50:51]
	v_cvt_pk_bf16_f32 v9, v32, v33
	ds_read_b128 v[30:33], v52 offset:50704
	global_store_dwordx4 v[50:51], v[6:9], off
	s_waitcnt lgkmcnt(1)
	s_nop 0
	v_cvt_pk_bf16_f32 v6, v18, v19
	v_add_u32_e32 v18, 0x60, v44
	v_ashrrev_i32_e32 v19, 31, v18
	v_lshlrev_b64 v[18:19], 11, v[18:19]
	s_waitcnt lgkmcnt(0)
	v_cvt_pk_bf16_f32 v8, v30, v31
	v_lshl_add_u64 v[18:19], v[42:43], 0, v[18:19]
	v_cvt_pk_bf16_f32 v7, v20, v21
	v_cvt_pk_bf16_f32 v9, v32, v33
	global_store_dwordx4 v[18:19], v[6:9], off
	s_nop 1
	v_mov_b32_e32 v8, v168
	s_waitcnt lgkmcnt(0)
	s_barrier
	s_nop 0
	v_and_b32_e32 v6, 15, v0
	v_lshrrev_b32_e32 v7, 2, v0
	v_lshlrev_b32_e32 v0, 1, v0
	v_lshlrev_b32_e32 v6, 2, v6
	v_and_b32_e32 v7, 0xfffffcc, v7
	v_and_or_b32 v0, v0, s89, v6
	v_mad_u64_u32 v[6:7], s[0:1], v7, s92, v[0:1]
	v_add_u32_e32 v0, 0x400, v6
	ds_write2_b32 v6, v110, v106 offset1:16
	ds_write2_b32 v6, v111, v107 offset0:132 offset1:148
	ds_write2_b32 v0, v112, v108 offset0:8 offset1:24
	ds_write2_b32 v0, v113, v109 offset0:140 offset1:156
	v_add_u32_e32 v0, 0x2000, v6
	ds_write2_b32 v0, v102, v98 offset0:64 offset1:80
	ds_write2_b32 v0, v103, v99 offset0:196 offset1:212
	v_add_u32_e32 v0, 0x2400, v6
	ds_write2_b32 v0, v104, v100 offset0:72 offset1:88
	ds_write2_b32 v0, v105, v101 offset0:204 offset1:220
	v_add_u32_e32 v0, 0x4000, v6
	ds_write2_b32 v0, v122, v124 offset0:128 offset1:144
	v_add_u32_e32 v0, 0x4400, v6
	ds_write2_b32 v0, v123, v125 offset0:4 offset1:20
	ds_write2_b32 v0, v118, v120 offset0:136 offset1:152
	v_add_u32_e32 v0, 0x4800, v6
	ds_write2_b32 v0, v119, v121 offset0:12 offset1:28
	v_add_u32_e32 v0, 0x6000, v6
	ds_write2_b32 v0, v126, v128 offset0:192 offset1:208
	v_add_u32_e32 v0, 0x6400, v6
	ds_write2_b32 v0, v127, v129 offset0:68 offset1:84
	ds_write2_b32 v0, v114, v116 offset0:200 offset1:216
	v_add_u32_e32 v0, 0x6800, v6
	ds_write2_b32 v0, v115, v117 offset0:76 offset1:92
	v_ashrrev_i32_e32 v0, 4, v8
	v_lshlrev_b32_e32 v6, 3, v8
	v_and_b32_e32 v30, 0x78, v6
	v_mul_lo_u32 v6, v0, s92
	s_waitcnt lgkmcnt(0)
	s_barrier
; DI u32x4 pack8(const float* f) { u32x4 o; o.x = pack2(f[0], f[1]); o.y = pack2(f[2], f[3]); o.z = pack2(f[4], f[5]); o.w = pack2(f[6], f[7]); return o; }
; DI void lds_barrier() { asm volatile("s_waitcnt lgkmcnt(0)\n\ts_barrier" ::: "memory"); }
; DI int tid512() { int t = threadIdx.x; asm volatile("" : "+v"(t)); return t; }
; template <int AI, int BJ>
; DI void stage_q(const f32x4 (&acc)[2][2][4][2], float* Cs) {
;   const int t = tid512(), wid = t >> 6, lane = t & 63, wr = wid >> 2, wc = wid & 3, fr = lane & 15, fq = lane >> 4;
;   lds_barrier();
; #pragma unroll
;   for (int m = 0; m < 4; ++m)
; #pragma unroll
;     for (int n = 0; n < 2; ++n)
; #pragma unroll
;       for (int j = 0; j < 4; ++j) Cs[(wr * 64 + m * 16 + fq * 4 + j) * CST + wc * 32 + n * 16 + fr] = acc[AI][BJ][m][n][j];
;   lds_barrier();
; }
; template <int AI, int BJ>
; DI void mg_quadrant(PREF p, const f32x4 (&acc)[2][2][4][2], int mt, int dt, float* Cs) {
;   const int t = tid512();
;   const int row0 = mt * 256 + AI * 128, col0 = dt * 256 + BJ * 128;
;   stage_q<AI, BJ>(acc, Cs);
; #pragma unroll
;   for (int q = 0; q < 4; ++q) {
;     int r = (t >> 4) + 32 * q, c = (t & 15) * 8;
;     float v[8]; ld8(Cs + r * CST + c, v);
;     *(u32x4*)(p.mg + (size_t)(row0 + r) * 1024 + col0 + c) = pack8(v);
;   }
	v_lshl_add_u32 v50, v30, 2, v6
	ds_read_b128 v[6:9], v50
	ds_read_b128 v[18:21], v50 offset:16
	v_add_u32_e32 v42, s12, v0
	v_ashrrev_i32_e32 v43, 31, v42
	s_waitcnt lgkmcnt(1)
	v_cvt_pk_bf16_f32 v6, v6, v7
	v_cvt_pk_bf16_f32 v7, v8, v9
	s_waitcnt lgkmcnt(0)
	v_cvt_pk_bf16_f32 v8, v18, v19
	v_lshlrev_b64 v[18:19], 11, v[42:43]
	v_lshl_add_u64 v[44:45], s[36:37], 0, v[18:19]
	v_lshlrev_b32_e32 v0, 1, v30
	v_cvt_pk_bf16_f32 v9, v20, v21
	ds_read_b128 v[18:21], v50 offset:16896
	ds_read_b128 v[30:33], v50 offset:16912
	v_lshl_add_u64 v[44:45], v[44:45], 0, v[0:1]
	global_store_dwordx4 v[44:45], v[6:9], off offset:256
	s_waitcnt lgkmcnt(1)
	s_nop 0
	v_cvt_pk_bf16_f32 v6, v18, v19
	v_add_u32_e32 v18, 32, v42
	v_ashrrev_i32_e32 v19, 31, v18
	s_waitcnt lgkmcnt(0)
	v_cvt_pk_bf16_f32 v8, v30, v31
	v_lshlrev_b64 v[30:31], 11, v[18:19]
	v_lshl_add_u64 v[44:45], s[36:37], 0, v[30:31]
	v_cvt_pk_bf16_f32 v7, v20, v21
	ds_read_b128 v[18:21], v50 offset:33792
	v_lshl_add_u64 v[44:45], v[44:45], 0, v[0:1]
	v_cvt_pk_bf16_f32 v9, v32, v33
	ds_read_b128 v[30:33], v50 offset:33808
	global_store_dwordx4 v[44:45], v[6:9], off offset:256
	s_waitcnt lgkmcnt(1)
	s_nop 0
	v_cvt_pk_bf16_f32 v6, v18, v19
	v_add_u32_e32 v18, 64, v42
	v_ashrrev_i32_e32 v19, 31, v18
	s_waitcnt lgkmcnt(0)
	v_cvt_pk_bf16_f32 v8, v30, v31
	v_lshlrev_b64 v[30:31], 11, v[18:19]
	v_lshl_add_u64 v[44:45], s[36:37], 0, v[30:31]
	v_cvt_pk_bf16_f32 v7, v20, v21
	ds_read_b128 v[18:21], v50 offset:50688
	v_lshl_add_u64 v[44:45], v[44:45], 0, v[0:1]
	v_cvt_pk_bf16_f32 v9, v32, v33
	ds_read_b128 v[30:33], v50 offset:50704
	global_store_dwordx4 v[44:45], v[6:9], off offset:256
	s_waitcnt lgkmcnt(1)
	s_nop 0
	v_cvt_pk_bf16_f32 v6, v18, v19
	v_add_u32_e32 v18, 0x60, v42
	v_ashrrev_i32_e32 v19, 31, v18
	v_lshlrev_b64 v[18:19], 11, v[18:19]
	v_lshl_add_u64 v[18:19], s[36:37], 0, v[18:19]
	s_waitcnt lgkmcnt(0)
	v_cvt_pk_bf16_f32 v8, v30, v31
	v_lshl_add_u64 v[18:19], v[18:19], 0, v[0:1]
	v_cvt_pk_bf16_f32 v7, v20, v21
	v_cvt_pk_bf16_f32 v9, v32, v33
	global_store_dwordx4 v[18:19], v[6:9], off offset:256
	v_mov_b32_e32 v0, v168
	s_nop 0
	v_mov_b32_e32 v8, v168
	s_waitcnt lgkmcnt(0)
	s_barrier
	s_nop 0
	v_and_b32_e32 v6, 15, v0
	v_lshrrev_b32_e32 v7, 2, v0
	v_lshlrev_b32_e32 v0, 1, v0
	v_lshlrev_b32_e32 v6, 2, v6
	v_and_b32_e32 v7, 0xfffffcc, v7
	v_and_or_b32 v0, v0, s89, v6
	v_mad_u64_u32 v[6:7], s[0:1], v7, s92, v[0:1]
	v_add_u32_e32 v0, 0x400, v6
	ds_write2_b32 v6, v78, v74 offset1:16
	ds_write2_b32 v6, v79, v75 offset0:132 offset1:148
	ds_write2_b32 v0, v80, v76 offset0:8 offset1:24
	ds_write2_b32 v0, v81, v77 offset0:140 offset1:156
	v_add_u32_e32 v0, 0x2000, v6
	ds_write2_b32 v0, v70, v66 offset0:64 offset1:80
	ds_write2_b32 v0, v71, v67 offset0:196 offset1:212
	v_add_u32_e32 v0, 0x2400, v6
	ds_write2_b32 v0, v72, v68 offset0:72 offset1:88
	ds_write2_b32 v0, v73, v69 offset0:204 offset1:220
	v_add_u32_e32 v0, 0x4000, v6
	ds_write2_b32 v0, v90, v92 offset0:128 offset1:144
	v_add_u32_e32 v0, 0x4400, v6
	ds_write2_b32 v0, v91, v93 offset0:4 offset1:20
	ds_write2_b32 v0, v86, v88 offset0:136 offset1:152
	v_add_u32_e32 v0, 0x4800, v6
	ds_write2_b32 v0, v87, v89 offset0:12 offset1:28
	v_add_u32_e32 v0, 0x6000, v6
	ds_write2_b32 v0, v94, v96 offset0:192 offset1:208
	v_add_u32_e32 v0, 0x6400, v6
	ds_write2_b32 v0, v95, v97 offset0:68 offset1:84
	ds_write2_b32 v0, v82, v84 offset0:200 offset1:216
	v_add_u32_e32 v0, 0x6800, v6
	ds_write2_b32 v0, v83, v85 offset0:76 offset1:92
	v_ashrrev_i32_e32 v30, 4, v8
	v_lshlrev_b32_e32 v0, 3, v8
	v_and_b32_e32 v0, 0x78, v0
	v_mul_lo_u32 v6, v30, s92
	s_waitcnt lgkmcnt(0)
	s_barrier
; DI u32x4 pack8(const float* f) { u32x4 o; o.x = pack2(f[0], f[1]); o.y = pack2(f[2], f[3]); o.z = pack2(f[4], f[5]); o.w = pack2(f[6], f[7]); return o; }
; DI void lds_barrier() { asm volatile("s_waitcnt lgkmcnt(0)\n\ts_barrier" ::: "memory"); }
; DI int tid512() { int t = threadIdx.x; asm volatile("" : "+v"(t)); return t; }
; template <int AI, int BJ>
; DI void stage_q(const f32x4 (&acc)[2][2][4][2], float* Cs) {
;   const int t = tid512(), wid = t >> 6, lane = t & 63, wr = wid >> 2, wc = wid & 3, fr = lane & 15, fq = lane >> 4;
;   lds_barrier();
; #pragma unroll
;   for (int m = 0; m < 4; ++m)
; #pragma unroll
;     for (int n = 0; n < 2; ++n)
; #pragma unroll
;       for (int j = 0; j < 4; ++j) Cs[(wr * 64 + m * 16 + fq * 4 + j) * CST + wc * 32 + n * 16 + fr] = acc[AI][BJ][m][n][j];
;   lds_barrier();
; }
; template <int AI, int BJ>
; DI void mg_quadrant(PREF p, const f32x4 (&acc)[2][2][4][2], int mt, int dt, float* Cs) {
;   const int t = tid512();
;   const int row0 = mt * 256 + AI * 128, col0 = dt * 256 + BJ * 128;
;   stage_q<AI, BJ>(acc, Cs);
; #pragma unroll
;   for (int q = 0; q < 4; ++q) {
;     int r = (t >> 4) + 32 * q, c = (t & 15) * 8;
;     float v[8]; ld8(Cs + r * CST + c, v);
;     *(u32x4*)(p.mg + (size_t)(row0 + r) * 1024 + col0 + c) = pack8(v);
;   }
	v_lshl_add_u32 v52, v0, 2, v6
	ds_read_b128 v[6:9], v52
	ds_read_b128 v[18:21], v52 offset:16
	v_add_u32_e32 v44, s13, v30
	v_lshlrev_b32_e32 v0, 1, v0
	v_ashrrev_i32_e32 v45, 31, v44
	v_lshl_add_u64 v[42:43], s[36:37], 0, v[0:1]
	v_lshlrev_b64 v[50:51], 11, v[44:45]
	s_waitcnt lgkmcnt(1)
	v_cvt_pk_bf16_f32 v6, v6, v7
	v_cvt_pk_bf16_f32 v7, v8, v9
	s_waitcnt lgkmcnt(0)
	v_cvt_pk_bf16_f32 v8, v18, v19
	v_cvt_pk_bf16_f32 v9, v20, v21
	ds_read_b128 v[18:21], v52 offset:16896
	ds_read_b128 v[30:33], v52 offset:16912
	v_lshl_add_u64 v[50:51], v[42:43], 0, v[50:51]
	global_store_dwordx4 v[50:51], v[6:9], off
	v_mov_b32_e32 v0, v168
	s_waitcnt lgkmcnt(0)
	v_cvt_pk_bf16_f32 v8, v30, v31
	v_add_u32_e32 v30, 32, v44
	v_ashrrev_i32_e32 v31, 31, v30
	v_lshlrev_b64 v[50:51], 11, v[30:31]
	v_cvt_pk_bf16_f32 v6, v18, v19
	v_cvt_pk_bf16_f32 v7, v20, v21
	v_cvt_pk_bf16_f32 v9, v32, v33
	ds_read_b128 v[18:21], v52 offset:33792
	ds_read_b128 v[30:33], v52 offset:33808
	v_lshl_add_u64 v[50:51], v[42:43], 0, v[50:51]
	global_store_dwordx4 v[50:51], v[6:9], off
	s_waitcnt lgkmcnt(0)
	s_nop 0
	v_cvt_pk_bf16_f32 v8, v30, v31
	v_add_u32_e32 v30, 64, v44
	v_ashrrev_i32_e32 v31, 31, v30
	v_lshlrev_b64 v[50:51], 11, v[30:31]
	v_cvt_pk_bf16_f32 v6, v18, v19
	v_cvt_pk_bf16_f32 v7, v20, v21
	ds_read_b128 v[18:21], v52 offset:50688
	v_lshl_add_u64 v[50:51], v[42:43], 0, v[50:51]
	v_cvt_pk_bf16_f32 v9, v32, v33
	ds_read_b128 v[30:33], v52 offset:50704
	global_store_dwordx4 v[50:51], v[6:9], off
	s_waitcnt lgkmcnt(1)
	s_nop 0
	v_cvt_pk_bf16_f32 v6, v18, v19
	v_add_u32_e32 v18, 0x60, v44
	v_ashrrev_i32_e32 v19, 31, v18
	v_lshlrev_b64 v[18:19], 11, v[18:19]
	s_waitcnt lgkmcnt(0)
	v_cvt_pk_bf16_f32 v8, v30, v31
	v_lshl_add_u64 v[18:19], v[42:43], 0, v[18:19]
	v_cvt_pk_bf16_f32 v7, v20, v21
	v_cvt_pk_bf16_f32 v9, v32, v33
	global_store_dwordx4 v[18:19], v[6:9], off
	s_nop 1
	v_mov_b32_e32 v8, v168
	s_waitcnt lgkmcnt(0)
	s_barrier
	s_nop 0
	v_and_b32_e32 v6, 15, v0
	v_lshrrev_b32_e32 v7, 2, v0
	v_lshlrev_b32_e32 v0, 1, v0
	v_lshlrev_b32_e32 v6, 2, v6
	v_and_b32_e32 v7, 0xfffffcc, v7
	v_and_or_b32 v0, v0, s89, v6
	v_mad_u64_u32 v[6:7], s[0:1], v7, s92, v[0:1]
	v_add_u32_e32 v0, 0x400, v6
	ds_write2_b32 v6, v46, v38 offset1:16
	ds_write2_b32 v6, v47, v39 offset0:132 offset1:148
	ds_write2_b32 v0, v48, v40 offset0:8 offset1:24
	ds_write2_b32 v0, v49, v41 offset0:140 offset1:156
	v_add_u32_e32 v0, 0x2000, v6
	ds_write2_b32 v0, v34, v26 offset0:64 offset1:80
	ds_write2_b32 v0, v35, v27 offset0:196 offset1:212
	v_add_u32_e32 v0, 0x2400, v6
	ds_write2_b32 v0, v36, v28 offset0:72 offset1:88
	ds_write2_b32 v0, v37, v29 offset0:204 offset1:220
	v_add_u32_e32 v0, 0x4000, v6
	ds_write2_b32 v0, v22, v14 offset0:128 offset1:144
	v_add_u32_e32 v0, 0x4400, v6
	ds_write2_b32 v0, v23, v15 offset0:4 offset1:20
	ds_write2_b32 v0, v24, v16 offset0:136 offset1:152
	v_add_u32_e32 v0, 0x4800, v6
	ds_write2_b32 v0, v25, v17 offset0:12 offset1:28
	v_add_u32_e32 v0, 0x6000, v6
	ds_write2_b32 v0, v10, v2 offset0:192 offset1:208
	v_add_u32_e32 v0, 0x6400, v6
	ds_write2_b32 v0, v11, v3 offset0:68 offset1:84
	ds_write2_b32 v0, v12, v4 offset0:200 offset1:216
	v_add_u32_e32 v0, 0x6800, v6
	ds_write2_b32 v0, v13, v5 offset0:76 offset1:92
	v_ashrrev_i32_e32 v0, 4, v8
	v_lshlrev_b32_e32 v2, 3, v8
	v_and_b32_e32 v10, 0x78, v2
	v_mul_lo_u32 v2, v0, s92
	s_waitcnt lgkmcnt(0)
	s_barrier
	v_lshl_add_u32 v18, v10, 2, v2
	ds_read_b128 v[2:5], v18
	ds_read_b128 v[6:9], v18 offset:16
	v_add_u32_e32 v14, s13, v0
	v_ashrrev_i32_e32 v15, 31, v14
	s_waitcnt lgkmcnt(1)
	v_cvt_pk_bf16_f32 v2, v2, v3
	v_cvt_pk_bf16_f32 v3, v4, v5
	s_waitcnt lgkmcnt(0)
	v_cvt_pk_bf16_f32 v4, v6, v7
	v_lshlrev_b64 v[6:7], 11, v[14:15]
	v_lshl_add_u64 v[16:17], s[36:37], 0, v[6:7]
	v_lshlrev_b32_e32 v0, 1, v10
	v_cvt_pk_bf16_f32 v5, v8, v9
	ds_read_b128 v[6:9], v18 offset:16896
	ds_read_b128 v[10:13], v18 offset:16912
	v_lshl_add_u64 v[16:17], v[16:17], 0, v[0:1]
	global_store_dwordx4 v[16:17], v[2:5], off offset:256
	s_waitcnt lgkmcnt(1)
	s_nop 0
	v_cvt_pk_bf16_f32 v2, v6, v7
	v_add_u32_e32 v6, 32, v14
	v_ashrrev_i32_e32 v7, 31, v6
	s_waitcnt lgkmcnt(0)
	v_cvt_pk_bf16_f32 v4, v10, v11
	v_lshlrev_b64 v[10:11], 11, v[6:7]
	v_lshl_add_u64 v[16:17], s[36:37], 0, v[10:11]
	v_cvt_pk_bf16_f32 v3, v8, v9
	ds_read_b128 v[6:9], v18 offset:33792
	v_lshl_add_u64 v[16:17], v[16:17], 0, v[0:1]
	v_cvt_pk_bf16_f32 v5, v12, v13
	ds_read_b128 v[10:13], v18 offset:33808
	global_store_dwordx4 v[16:17], v[2:5], off offset:256
	s_waitcnt lgkmcnt(1)
	s_nop 0
	v_cvt_pk_bf16_f32 v2, v6, v7
	v_add_u32_e32 v6, 64, v14
	v_ashrrev_i32_e32 v7, 31, v6
	s_waitcnt lgkmcnt(0)
	v_cvt_pk_bf16_f32 v4, v10, v11
	v_lshlrev_b64 v[10:11], 11, v[6:7]
	v_lshl_add_u64 v[16:17], s[36:37], 0, v[10:11]
	v_cvt_pk_bf16_f32 v3, v8, v9
	ds_read_b128 v[6:9], v18 offset:50688
	v_lshl_add_u64 v[16:17], v[16:17], 0, v[0:1]
	v_cvt_pk_bf16_f32 v5, v12, v13
	ds_read_b128 v[10:13], v18 offset:50704
	global_store_dwordx4 v[16:17], v[2:5], off offset:256
	s_waitcnt lgkmcnt(1)
	s_nop 0
	v_cvt_pk_bf16_f32 v2, v6, v7
	v_add_u32_e32 v6, 0x60, v14
	v_ashrrev_i32_e32 v7, 31, v6
	v_lshlrev_b64 v[6:7], 11, v[6:7]
	v_lshl_add_u64 v[6:7], s[36:37], 0, v[6:7]
	v_lshl_add_u64 v[6:7], v[6:7], 0, v[0:1]
	v_cvt_pk_bf16_f32 v3, v8, v9
	s_waitcnt lgkmcnt(0)
	v_cvt_pk_bf16_f32 v4, v10, v11
	v_cvt_pk_bf16_f32 v5, v12, v13
	global_store_dwordx4 v[6:7], v[2:5], off offset:256
	s_branch .LBB0_101

; DI float sigm(float x) { return 1.f / (1.f + __expf(-x)); }
; DI float silu(float x) { return x / (1.f + __expf(-x)); }
; DI u32x4 pack8(const float* f) { u32x4 o; o.x = pack2(f[0], f[1]); o.y = pack2(f[2], f[3]); o.z = pack2(f[4], f[5]); o.w = pack2(f[6], f[7]); return o; }
; DI void lds_barrier() { asm volatile("s_waitcnt lgkmcnt(0)\n\ts_barrier" ::: "memory"); }
; DI int tid512() { int t = threadIdx.x; asm volatile("" : "+v"(t)); return t; }
; template <int AI, int BJ>
; DI void stage_q(const f32x4 (&acc)[2][2][4][2], float* Cs) {
;   const int t = tid512(), wid = t >> 6, lane = t & 63, wr = wid >> 2, wc = wid & 3, fr = lane & 15, fq = lane >> 4;
;   lds_barrier();
; #pragma unroll
;   for (int m = 0; m < 4; ++m)
; #pragma unroll
;     for (int n = 0; n < 2; ++n)
; #pragma unroll
;       for (int j = 0; j < 4; ++j) Cs[(wr * 64 + m * 16 + fq * 4 + j) * CST + wc * 32 + n * 16 + fr] = acc[AI][BJ][m][n][j];
;   lds_barrier();
; }
; template <int AI, int BJ>
; DI void glu_quadrant(PREF p, const f32x4 (&acc)[2][2][4][2], int mt, int nt, float* Cs) {
;   const int t = tid512();
;   const int row0 = mt * 256 + AI * 128, oc0 = (nt * 2 + BJ) * 64, c = (t & 7) * 8;
;   u32x4 zr[2];
; #pragma unroll
;   for (int q = 0; q < 2; ++q) zr[q] = *(const u32x4*)(p.hb + (size_t)(row0 + (t >> 3) + 64 * q) * HW + OFF_CZ + oc0 + c);
;   stage_q<AI, BJ>(acc, Cs);
; #pragma unroll
;   for (int q = 0; q < 2; ++q) {
;     const int r = (t >> 3) + 64 * q;
;     float v[8], g[8]; ld8(Cs + r * CST + c, v); ld8(Cs + r * CST + 64 + c, g);
;     float z[8]; unpack8(zr[q], z);
; #pragma unroll
;     for (int j = 0; j < 8; ++j) v[j] = v[j] * sigm(g[j]) * silu(z[j]);
;     *(u32x4*)(p.ys + (size_t)(row0 + r) * 1024 + 512 + oc0 + c) = pack8(v);
;   }
.LBB0_214:
	s_or_b64 exec, exec, s[16:17]
	v_mov_b32_e32 v0, v168
	s_lshl_b32 s14, s14, 8
	v_ashrrev_i32_e32 v147, 3, v0
	v_lshlrev_b32_e32 v98, 3, v0
	v_add_u32_e32 v142, s14, v147
	v_mov_b64_e32 v[138:139], s[8:9]
	v_and_b32_e32 v146, 56, v98
	v_mad_i64_i32 v[98:99], s[0:1], v142, s60, v[138:139]
	s_lshl_b32 s52, s25, 8
	v_lshl_add_u64 v[98:99], v[98:99], 0, s[52:53]
	v_lshlrev_b32_e32 v0, 1, v146
	v_lshl_add_u64 v[98:99], v[98:99], 0, v[0:1]
	global_load_dwordx4 v[118:121], v[98:99], off offset:3392
	v_add_u32_e32 v140, 64, v142
	v_mad_i64_i32 v[98:99], s[0:1], v140, s60, v[138:139]
	v_lshl_add_u64 v[98:99], v[98:99], 0, s[52:53]
	v_lshl_add_u64 v[98:99], v[98:99], 0, v[0:1]
	v_mov_b32_e32 v144, v168
	global_load_dwordx4 v[98:101], v[98:99], off offset:3392
	s_waitcnt lgkmcnt(0)
	s_barrier
	v_ashrrev_i32_e32 v143, 31, v142
	v_and_b32_e32 v145, 15, v144
	v_lshrrev_b32_e32 v148, 2, v144
	v_lshlrev_b32_e32 v144, 1, v144
	v_lshlrev_b32_e32 v145, 2, v145
	v_and_b32_e32 v148, 0xfffffcc, v148
	v_and_or_b32 v144, v144, s89, v145
	v_mad_u64_u32 v[144:145], s[0:1], v148, s92, v[144:145]
	ds_write2_b32 v144, v126, v134 offset1:16
	ds_write2_b32 v144, v127, v135 offset0:132 offset1:148
	v_add_u32_e32 v126, 0x400, v144
	ds_write2_b32 v126, v128, v136 offset0:8 offset1:24
	ds_write2_b32 v126, v129, v137 offset0:140 offset1:156
	v_add_u32_e32 v126, 0x2000, v144
	ds_write2_b32 v126, v122, v130 offset0:64 offset1:80
	ds_write2_b32 v126, v123, v131 offset0:196 offset1:212
	v_add_u32_e32 v122, 0x2400, v144
	ds_write2_b32 v122, v124, v132 offset0:72 offset1:88
	ds_write2_b32 v122, v125, v133 offset0:204 offset1:220
	v_add_u32_e32 v122, 0x4000, v144
	ds_write2_b32 v122, v110, v114 offset0:128 offset1:144
	v_add_u32_e32 v110, 0x4400, v144
	ds_write2_b32 v110, v111, v115 offset0:4 offset1:20
	ds_write2_b32 v110, v112, v116 offset0:136 offset1:152
	v_add_u32_e32 v110, 0x4800, v144
	ds_write2_b32 v110, v113, v117 offset0:12 offset1:28
	v_add_u32_e32 v110, 0x6000, v144
	ds_write2_b32 v110, v102, v106 offset0:192 offset1:208
	v_add_u32_e32 v102, 0x6400, v144
	ds_write2_b32 v102, v103, v107 offset0:68 offset1:84
	ds_write2_b32 v102, v104, v108 offset0:200 offset1:216
	v_add_u32_e32 v102, 0x6800, v144
	ds_write2_b32 v102, v105, v109 offset0:76 offset1:92
	v_mul_lo_u32 v102, v147, s92
	s_waitcnt lgkmcnt(0)
	s_barrier
	v_lshl_add_u32 v122, v146, 2, v102
	s_waitcnt vmcnt(0)
	ds_read_b128 v[110:113], v122
	ds_read_b128 v[102:105], v122 offset:16
	ds_read_b128 v[114:117], v122 offset:256
	ds_read_b128 v[106:109], v122 offset:272
	v_ashrrev_i32_e32 v141, 31, v140
	s_waitcnt lgkmcnt(1)
	v_mul_f32_e32 v114, 0xbfb8aa3b, v114
	v_exp_f32_e32 v127, v114
	s_waitcnt lgkmcnt(0)
	v_mul_f32_e32 v106, 0xbfb8aa3b, v106
	v_lshlrev_b32_e32 v125, 16, v118
	v_mul_f32_e32 v114, 0xbfb8aa3b, v125
	v_exp_f32_e32 v126, v114
	v_and_b32_e32 v128, 0xffff0000, v118
	v_lshlrev_b32_e32 v129, 16, v119
	v_and_b32_e32 v124, 0xffff0000, v119
	v_pk_add_f32 v[126:127], v[126:127], 1.0 op_sel_hi:[1,0]
	v_lshlrev_b32_e32 v119, 16, v121
	v_and_b32_e32 v118, 0xffff0000, v121
	v_lshlrev_b32_e32 v123, 16, v120
	v_and_b32_e32 v120, 0xffff0000, v120
	v_rcp_f32_e32 v114, v126
	s_nop 0
	v_mul_f32_e32 v114, v125, v114
	v_rcp_f32_e32 v121, v127
	s_nop 0
	v_mul_f32_e32 v110, v110, v121
	v_mul_f32_e32 v110, v114, v110
	v_mul_f32_e32 v114, 0xbfb8aa3b, v115
	v_exp_f32_e32 v115, v114
	v_mul_f32_e32 v114, 0xbfb8aa3b, v128
	v_exp_f32_e32 v114, v114
	s_nop 0
	v_pk_add_f32 v[114:115], v[114:115], 1.0 op_sel_hi:[1,0]
	s_nop 0
	v_rcp_f32_e32 v121, v114
	s_nop 0
	v_mul_f32_e32 v114, v128, v121
	v_rcp_f32_e32 v115, v115
	s_nop 0
	v_mul_f32_e32 v111, v111, v115
	v_mul_f32_e32 v111, v114, v111
	v_mul_f32_e32 v114, 0xbfb8aa3b, v116
	v_exp_f32_e32 v115, v114
	v_mul_f32_e32 v114, 0xbfb8aa3b, v129
	v_exp_f32_e32 v114, v114
	s_nop 0
	v_pk_add_f32 v[114:115], v[114:115], 1.0 op_sel_hi:[1,0]
	s_nop 0
	v_rcp_f32_e32 v116, v114
	s_nop 0
	v_mul_f32_e32 v114, v129, v116
	v_rcp_f32_e32 v115, v115
	s_nop 0
	v_mul_f32_e32 v112, v112, v115
	v_mul_f32_e32 v112, v114, v112
	v_mul_f32_e32 v114, 0xbfb8aa3b, v117
	v_exp_f32_e32 v115, v114
	v_mul_f32_e32 v114, 0xbfb8aa3b, v124
	v_exp_f32_e32 v114, v114
	s_nop 0
	v_pk_add_f32 v[114:115], v[114:115], 1.0 op_sel_hi:[1,0]
	s_nop 0
	v_rcp_f32_e32 v116, v114
	s_nop 0
	v_mul_f32_e32 v114, v124, v116
	v_rcp_f32_e32 v115, v115
	s_nop 0
	v_mul_f32_e32 v113, v113, v115
	v_exp_f32_e32 v115, v106
	v_mul_f32_e32 v106, 0xbfb8aa3b, v123
	v_mul_f32_e32 v113, v114, v113
	v_exp_f32_e32 v114, v106
	v_lshlrev_b32_e32 v125, 16, v100
	v_pk_add_f32 v[114:115], v[114:115], 1.0 op_sel_hi:[1,0]
	s_nop 0
	v_rcp_f32_e32 v106, v114
	s_nop 0
	v_mul_f32_e32 v106, v123, v106
	v_and_b32_e32 v124, 0xffff0000, v99
	v_rcp_f32_e32 v114, v115
	s_nop 0
	v_mul_f32_e32 v102, v102, v114
	v_mul_f32_e32 v114, v106, v102
	v_mul_f32_e32 v102, 0xbfb8aa3b, v107
	v_exp_f32_e32 v107, v102
	v_mul_f32_e32 v102, 0xbfb8aa3b, v120
	v_exp_f32_e32 v106, v102
	v_lshlrev_b32_e32 v123, 16, v99
	v_pk_add_f32 v[106:107], v[106:107], 1.0 op_sel_hi:[1,0]
	s_nop 0
	v_rcp_f32_e32 v102, v106
	s_nop 0
	v_mul_f32_e32 v102, v120, v102
	v_rcp_f32_e32 v106, v107
	s_nop 0
	v_mul_f32_e32 v103, v103, v106
	v_mul_f32_e32 v106, v102, v103
	v_mul_f32_e32 v102, 0xbfb8aa3b, v108
	v_exp_f32_e32 v103, v102
	v_mul_f32_e32 v102, 0xbfb8aa3b, v119
	v_exp_f32_e32 v102, v102
	s_nop 0
	v_pk_add_f32 v[102:103], v[102:103], 1.0 op_sel_hi:[1,0]
	s_nop 0
	v_rcp_f32_e32 v107, v102
	s_nop 0
	v_mul_f32_e32 v102, v119, v107
	v_lshlrev_b32_e32 v119, 16, v98
	v_rcp_f32_e32 v103, v103
	s_nop 0
	v_mul_f32_e32 v103, v104, v103
	v_mul_f32_e32 v107, v102, v103
	v_mul_f32_e32 v102, 0xbfb8aa3b, v109
	v_exp_f32_e32 v103, v102
	v_mul_f32_e32 v102, 0xbfb8aa3b, v118
	v_exp_f32_e32 v102, v102
	s_nop 0
	v_pk_add_f32 v[102:103], v[102:103], 1.0 op_sel_hi:[1,0]
	s_nop 0
	v_rcp_f32_e32 v104, v102
	s_nop 0
	v_mul_f32_e32 v102, v118, v104
	v_and_b32_e32 v118, 0xffff0000, v100
	v_lshlrev_b32_e32 v100, 16, v101
	v_rcp_f32_e32 v103, v103
	s_nop 0
	v_mul_f32_e32 v103, v105, v103
	v_mul_f32_e32 v105, v102, v103
	v_cvt_pk_bf16_f32 v104, v114, v106
	v_cvt_pk_bf16_f32 v105, v107, v105
	v_lshlrev_b64 v[106:107], 11, v[142:143]
	v_lshl_add_u64 v[106:107], s[10:11], 0, v[106:107]
	v_lshl_add_u64 v[106:107], v[106:107], 0, s[52:53]
	v_lshl_add_u64 v[106:107], v[106:107], 0, v[0:1]
	v_cvt_pk_bf16_f32 v102, v110, v111
	v_cvt_pk_bf16_f32 v103, v112, v113
	global_store_dwordx4 v[106:107], v[102:105], off offset:1024
	ds_read_b128 v[110:113], v122 offset:33792
	ds_read_b128 v[102:105], v122 offset:33808
	ds_read_b128 v[114:117], v122 offset:34048
	ds_read_b128 v[106:109], v122 offset:34064
	v_and_b32_e32 v122, 0xffff0000, v98
	v_and_b32_e32 v98, 0xffff0000, v101
	s_waitcnt lgkmcnt(1)
; DI float sigm(float x) { return 1.f / (1.f + __expf(-x)); }
; DI float silu(float x) { return x / (1.f + __expf(-x)); }
; DI u32x4 pack8(const float* f) { u32x4 o; o.x = pack2(f[0], f[1]); o.y = pack2(f[2], f[3]); o.z = pack2(f[4], f[5]); o.w = pack2(f[6], f[7]); return o; }
; DI void lds_barrier() { asm volatile("s_waitcnt lgkmcnt(0)\n\ts_barrier" ::: "memory"); }
; DI int tid512() { int t = threadIdx.x; asm volatile("" : "+v"(t)); return t; }
; template <int AI, int BJ>
; DI void stage_q(const f32x4 (&acc)[2][2][4][2], float* Cs) {
;   const int t = tid512(), wid = t >> 6, lane = t & 63, wr = wid >> 2, wc = wid & 3, fr = lane & 15, fq = lane >> 4;
;   lds_barrier();
; #pragma unroll
;   for (int m = 0; m < 4; ++m)
; #pragma unroll
;     for (int n = 0; n < 2; ++n)
; #pragma unroll
;       for (int j = 0; j < 4; ++j) Cs[(wr * 64 + m * 16 + fq * 4 + j) * CST + wc * 32 + n * 16 + fr] = acc[AI][BJ][m][n][j];
;   lds_barrier();
; }
; template <int AI, int BJ>
; DI void glu_quadrant(PREF p, const f32x4 (&acc)[2][2][4][2], int mt, int nt, float* Cs) {
;   const int t = tid512();
;   const int row0 = mt * 256 + AI * 128, oc0 = (nt * 2 + BJ) * 64, c = (t & 7) * 8;
;   u32x4 zr[2];
; #pragma unroll
;   for (int q = 0; q < 2; ++q) zr[q] = *(const u32x4*)(p.hb + (size_t)(row0 + (t >> 3) + 64 * q) * HW + OFF_CZ + oc0 + c);
;   stage_q<AI, BJ>(acc, Cs);
; #pragma unroll
;   for (int q = 0; q < 2; ++q) {
;     const int r = (t >> 3) + 64 * q;
;     float v[8], g[8]; ld8(Cs + r * CST + c, v); ld8(Cs + r * CST + 64 + c, g);
;     float z[8]; unpack8(zr[q], z);
; #pragma unroll
;     for (int j = 0; j < 8; ++j) v[j] = v[j] * sigm(g[j]) * silu(z[j]);
;     *(u32x4*)(p.ys + (size_t)(row0 + r) * 1024 + 512 + oc0 + c) = pack8(v);
;   }
	v_mul_f32_e32 v99, 0xbfb8aa3b, v114
	v_exp_f32_e32 v121, v99
	v_mul_f32_e32 v99, 0xbfb8aa3b, v119
	v_exp_f32_e32 v120, v99
	s_waitcnt lgkmcnt(0)
	v_mul_f32_e32 v106, 0xbfb8aa3b, v106
	v_pk_add_f32 v[120:121], v[120:121], 1.0 op_sel_hi:[1,0]
	s_nop 0
	v_rcp_f32_e32 v99, v120
	s_nop 0
	v_mul_f32_e32 v99, v119, v99
	v_rcp_f32_e32 v101, v121
	s_nop 0
	v_mul_f32_e32 v101, v110, v101
	v_mul_f32_e32 v99, v99, v101
	v_mul_f32_e32 v101, 0xbfb8aa3b, v115
	v_exp_f32_e32 v115, v101
	v_mul_f32_e32 v101, 0xbfb8aa3b, v122
	v_exp_f32_e32 v114, v101
	s_nop 0
	v_pk_add_f32 v[114:115], v[114:115], 1.0 op_sel_hi:[1,0]
	s_nop 0
	v_rcp_f32_e32 v101, v114
	s_nop 0
	v_mul_f32_e32 v101, v122, v101
	v_rcp_f32_e32 v110, v115
	s_nop 0
	v_mul_f32_e32 v110, v111, v110
	v_mul_f32_e32 v101, v101, v110
	v_mul_f32_e32 v110, 0xbfb8aa3b, v116
	v_exp_f32_e32 v111, v110
	v_mul_f32_e32 v110, 0xbfb8aa3b, v123
	v_exp_f32_e32 v110, v110
	s_nop 0
	v_pk_add_f32 v[110:111], v[110:111], 1.0 op_sel_hi:[1,0]
	s_nop 0
	v_rcp_f32_e32 v114, v110
	s_nop 0
	v_mul_f32_e32 v110, v123, v114
	v_rcp_f32_e32 v111, v111
	s_nop 0
	v_mul_f32_e32 v111, v112, v111
	v_mul_f32_e32 v110, v110, v111
	v_mul_f32_e32 v111, 0xbfb8aa3b, v117
	v_exp_f32_e32 v115, v111
	v_mul_f32_e32 v111, 0xbfb8aa3b, v124
	v_exp_f32_e32 v114, v111
	s_nop 0
	v_pk_add_f32 v[114:115], v[114:115], 1.0 op_sel_hi:[1,0]
	s_nop 0
	v_rcp_f32_e32 v111, v114
	s_nop 0
	v_mul_f32_e32 v111, v124, v111
	v_rcp_f32_e32 v112, v115
	s_nop 0
	v_mul_f32_e32 v112, v113, v112
	v_exp_f32_e32 v113, v106
	v_mul_f32_e32 v106, 0xbfb8aa3b, v125
	v_mul_f32_e32 v111, v111, v112
	v_exp_f32_e32 v112, v106
	s_nop 0
	v_pk_add_f32 v[112:113], v[112:113], 1.0 op_sel_hi:[1,0]
	s_nop 0
	v_rcp_f32_e32 v106, v112
	s_nop 0
	v_mul_f32_e32 v106, v125, v106
	v_rcp_f32_e32 v112, v113
	s_nop 0
	v_mul_f32_e32 v102, v102, v112
	v_mul_f32_e32 v112, v106, v102
	v_mul_f32_e32 v102, 0xbfb8aa3b, v107
	v_exp_f32_e32 v107, v102
	v_mul_f32_e32 v102, 0xbfb8aa3b, v118
	v_exp_f32_e32 v106, v102
	s_nop 0
	v_pk_add_f32 v[106:107], v[106:107], 1.0 op_sel_hi:[1,0]
	s_nop 0
	v_rcp_f32_e32 v102, v106
	s_nop 0
	v_mul_f32_e32 v102, v118, v102
	v_rcp_f32_e32 v106, v107
	s_nop 0
	v_mul_f32_e32 v103, v103, v106
	v_mul_f32_e32 v106, v102, v103
	v_mul_f32_e32 v102, 0xbfb8aa3b, v108
	v_exp_f32_e32 v103, v102
	v_mul_f32_e32 v102, 0xbfb8aa3b, v100
	v_exp_f32_e32 v102, v102
	s_nop 0
	v_pk_add_f32 v[102:103], v[102:103], 1.0 op_sel_hi:[1,0]
	s_nop 0
	v_rcp_f32_e32 v107, v102
	s_nop 0
	v_mul_f32_e32 v100, v100, v107
	v_rcp_f32_e32 v102, v103
	s_nop 0
	v_mul_f32_e32 v102, v104, v102
	v_mul_f32_e32 v104, v100, v102
	v_mul_f32_e32 v100, 0xbfb8aa3b, v109
	v_exp_f32_e32 v103, v100
	v_mul_f32_e32 v100, 0xbfb8aa3b, v98
	v_exp_f32_e32 v102, v100
	s_nop 0
	v_pk_add_f32 v[102:103], v[102:103], 1.0 op_sel_hi:[1,0]
	s_nop 0
	v_rcp_f32_e32 v100, v102
	s_nop 0
	v_mul_f32_e32 v98, v98, v100
	v_rcp_f32_e32 v100, v103
	s_nop 0
	v_mul_f32_e32 v100, v105, v100
	v_mul_f32_e32 v102, v98, v100
	v_cvt_pk_bf16_f32 v98, v99, v101
	v_cvt_pk_bf16_f32 v101, v104, v102
	v_lshlrev_b64 v[102:103], 11, v[140:141]
	v_lshl_add_u64 v[102:103], s[10:11], 0, v[102:103]
	v_lshl_add_u64 v[102:103], v[102:103], 0, s[52:53]
	v_lshl_add_u64 v[102:103], v[102:103], 0, v[0:1]
	v_mov_b32_e32 v0, v168
	v_cvt_pk_bf16_f32 v99, v110, v111
	v_cvt_pk_bf16_f32 v100, v112, v106
	global_store_dwordx4 v[102:103], v[98:101], off offset:1024
	v_mov_b32_e32 v110, v168
	v_ashrrev_i32_e32 v113, 3, v0
	v_lshlrev_b32_e32 v98, 3, v0
	v_add_u32_e32 v104, s14, v113
	v_and_b32_e32 v112, 56, v98
	v_mad_i64_i32 v[98:99], s[0:1], v104, s60, v[138:139]
	v_lshl_add_u64 v[98:99], v[98:99], 0, s[52:53]
	v_lshlrev_b32_e32 v0, 1, v112
	v_lshl_add_u64 v[98:99], v[98:99], 0, v[0:1]
	global_load_dwordx4 v[106:109], v[98:99], off offset:3520
	v_add_u32_e32 v102, 64, v104
	v_mad_i64_i32 v[98:99], s[0:1], v102, s60, v[138:139]
	v_lshl_add_u64 v[98:99], v[98:99], 0, s[52:53]
	v_lshl_add_u64 v[98:99], v[98:99], 0, v[0:1]
	global_load_dwordx4 v[98:101], v[98:99], off offset:3520
	s_waitcnt lgkmcnt(0)
	s_barrier
	v_ashrrev_i32_e32 v105, 31, v104
	v_and_b32_e32 v111, 15, v110
	v_lshrrev_b32_e32 v114, 2, v110
	v_lshlrev_b32_e32 v110, 1, v110
	v_lshlrev_b32_e32 v111, 2, v111
	v_and_b32_e32 v114, 0xfffffcc, v114
	v_and_or_b32 v110, v110, s89, v111
	v_mad_u64_u32 v[110:111], s[0:1], v114, s92, v[110:111]
	ds_write2_b32 v110, v86, v94 offset1:16
	ds_write2_b32 v110, v87, v95 offset0:132 offset1:148
	v_add_u32_e32 v86, 0x400, v110
	ds_write2_b32 v86, v88, v96 offset0:8 offset1:24
	ds_write2_b32 v86, v89, v97 offset0:140 offset1:156
	v_add_u32_e32 v86, 0x2000, v110
	ds_write2_b32 v86, v82, v90 offset0:64 offset1:80
	ds_write2_b32 v86, v83, v91 offset0:196 offset1:212
	v_add_u32_e32 v82, 0x2400, v110
	ds_write2_b32 v82, v84, v92 offset0:72 offset1:88
	ds_write2_b32 v82, v85, v93 offset0:204 offset1:220
	v_add_u32_e32 v82, 0x4000, v110
	ds_write2_b32 v82, v74, v78 offset0:128 offset1:144
	v_add_u32_e32 v74, 0x4400, v110
	ds_write2_b32 v74, v75, v79 offset0:4 offset1:20
	ds_write2_b32 v74, v76, v80 offset0:136 offset1:152
	v_add_u32_e32 v74, 0x4800, v110
	ds_write2_b32 v74, v77, v81 offset0:12 offset1:28
	v_add_u32_e32 v74, 0x6000, v110
	ds_write2_b32 v74, v66, v70 offset0:192 offset1:208
	v_add_u32_e32 v66, 0x6400, v110
	ds_write2_b32 v66, v67, v71 offset0:68 offset1:84
	ds_write2_b32 v66, v68, v72 offset0:200 offset1:216
	v_add_u32_e32 v66, 0x6800, v110
	ds_write2_b32 v66, v69, v73 offset0:76 offset1:92
	v_mul_lo_u32 v66, v113, s92
	s_waitcnt lgkmcnt(0)
	s_barrier
; DI float sigm(float x) { return 1.f / (1.f + __expf(-x)); }
; DI float silu(float x) { return x / (1.f + __expf(-x)); }
; DI u32x4 pack8(const float* f) { u32x4 o; o.x = pack2(f[0], f[1]); o.y = pack2(f[2], f[3]); o.z = pack2(f[4], f[5]); o.w = pack2(f[6], f[7]); return o; }
; DI int tid512() { int t = threadIdx.x; asm volatile("" : "+v"(t)); return t; }
; template <int AI, int BJ>
; DI void glu_quadrant(PREF p, const f32x4 (&acc)[2][2][4][2], int mt, int nt, float* Cs) {
;   const int t = tid512();
;   const int row0 = mt * 256 + AI * 128, oc0 = (nt * 2 + BJ) * 64, c = (t & 7) * 8;
;   u32x4 zr[2];
; #pragma unroll
;   for (int q = 0; q < 2; ++q) zr[q] = *(const u32x4*)(p.hb + (size_t)(row0 + (t >> 3) + 64 * q) * HW + OFF_CZ + oc0 + c);
;   stage_q<AI, BJ>(acc, Cs);
; #pragma unroll
;   for (int q = 0; q < 2; ++q) {
;     const int r = (t >> 3) + 64 * q;
;     float v[8], g[8]; ld8(Cs + r * CST + c, v); ld8(Cs + r * CST + 64 + c, g);
;     float z[8]; unpack8(zr[q], z);
; #pragma unroll
;     for (int j = 0; j < 8; ++j) v[j] = v[j] * sigm(g[j]) * silu(z[j]);
;     *(u32x4*)(p.ys + (size_t)(row0 + r) * 1024 + 512 + oc0 + c) = pack8(v);
;   }
	v_lshl_add_u32 v82, v112, 2, v66
	ds_read_b128 v[74:77], v82
	ds_read_b128 v[66:69], v82 offset:16
	ds_read_b128 v[78:81], v82 offset:256
	ds_read_b128 v[70:73], v82 offset:272
	v_ashrrev_i32_e32 v103, 31, v102
	s_bitset1_b32 s14, 7
	s_waitcnt lgkmcnt(1)
	v_mul_f32_e32 v78, 0xbfb8aa3b, v78
	v_exp_f32_e32 v87, v78
	s_waitcnt lgkmcnt(0)
	v_mul_f32_e32 v70, 0xbfb8aa3b, v70
	s_waitcnt vmcnt(1)
	v_lshlrev_b32_e32 v88, 16, v106
	v_mul_f32_e32 v78, 0xbfb8aa3b, v88
	v_exp_f32_e32 v86, v78
	v_and_b32_e32 v89, 0xffff0000, v106
	v_lshlrev_b32_e32 v90, 16, v107
	v_and_b32_e32 v91, 0xffff0000, v107
	v_pk_add_f32 v[86:87], v[86:87], 1.0 op_sel_hi:[1,0]
	v_lshlrev_b32_e32 v92, 16, v108
	v_and_b32_e32 v85, 0xffff0000, v108
	v_lshlrev_b32_e32 v84, 16, v109
	v_and_b32_e32 v83, 0xffff0000, v109
	v_rcp_f32_e32 v78, v86
	s_nop 0
	v_mul_f32_e32 v78, v88, v78
	v_rcp_f32_e32 v86, v87
	s_nop 0
	v_mul_f32_e32 v74, v74, v86
	v_mul_f32_e32 v74, v78, v74
	v_mul_f32_e32 v78, 0xbfb8aa3b, v79
	v_exp_f32_e32 v79, v78
	v_mul_f32_e32 v78, 0xbfb8aa3b, v89
	v_exp_f32_e32 v78, v78
	s_nop 0
	v_pk_add_f32 v[78:79], v[78:79], 1.0 op_sel_hi:[1,0]
	s_nop 0
	v_rcp_f32_e32 v86, v78
	s_nop 0
	v_mul_f32_e32 v78, v89, v86
	v_rcp_f32_e32 v79, v79
	s_nop 0
	v_mul_f32_e32 v75, v75, v79
	v_mul_f32_e32 v75, v78, v75
	v_mul_f32_e32 v78, 0xbfb8aa3b, v80
	v_exp_f32_e32 v79, v78
	v_mul_f32_e32 v78, 0xbfb8aa3b, v90
	v_exp_f32_e32 v78, v78
	s_nop 0
	v_pk_add_f32 v[78:79], v[78:79], 1.0 op_sel_hi:[1,0]
	s_nop 0
	v_rcp_f32_e32 v80, v78
	s_nop 0
	v_mul_f32_e32 v78, v90, v80
	s_waitcnt vmcnt(0)
	v_and_b32_e32 v90, 0xffff0000, v99
	v_rcp_f32_e32 v79, v79
	s_nop 0
	v_mul_f32_e32 v76, v76, v79
	v_mul_f32_e32 v76, v78, v76
	v_mul_f32_e32 v78, 0xbfb8aa3b, v81
	v_exp_f32_e32 v79, v78
	v_mul_f32_e32 v78, 0xbfb8aa3b, v91
	v_exp_f32_e32 v78, v78
	v_lshlrev_b32_e32 v89, 16, v99
	v_pk_add_f32 v[78:79], v[78:79], 1.0 op_sel_hi:[1,0]
	s_nop 0
	v_rcp_f32_e32 v80, v78
	s_nop 0
	v_mul_f32_e32 v78, v91, v80
	v_lshlrev_b32_e32 v91, 16, v100
	v_rcp_f32_e32 v79, v79
	s_nop 0
	v_mul_f32_e32 v77, v77, v79
	v_exp_f32_e32 v79, v70
	v_mul_f32_e32 v70, 0xbfb8aa3b, v92
	v_mul_f32_e32 v77, v78, v77
	v_exp_f32_e32 v78, v70
	v_and_b32_e32 v88, 0xffff0000, v98
	v_pk_add_f32 v[78:79], v[78:79], 1.0 op_sel_hi:[1,0]
	s_nop 0
	v_rcp_f32_e32 v70, v78
	s_nop 0
	v_mul_f32_e32 v70, v92, v70
	v_rcp_f32_e32 v78, v79
	s_nop 0
	v_mul_f32_e32 v66, v66, v78
	v_mul_f32_e32 v78, v70, v66
	v_mul_f32_e32 v66, 0xbfb8aa3b, v71
	v_exp_f32_e32 v71, v66
	v_mul_f32_e32 v66, 0xbfb8aa3b, v85
	v_exp_f32_e32 v70, v66
	s_nop 0
	v_pk_add_f32 v[70:71], v[70:71], 1.0 op_sel_hi:[1,0]
	s_nop 0
	v_rcp_f32_e32 v66, v70
	s_nop 0
	v_mul_f32_e32 v66, v85, v66
	v_rcp_f32_e32 v70, v71
	s_nop 0
	v_mul_f32_e32 v67, v67, v70
	v_mul_f32_e32 v70, v66, v67
	v_mul_f32_e32 v66, 0xbfb8aa3b, v72
	v_exp_f32_e32 v67, v66
	v_mul_f32_e32 v66, 0xbfb8aa3b, v84
	v_exp_f32_e32 v66, v66
	v_lshlrev_b32_e32 v85, 16, v98
	v_pk_add_f32 v[66:67], v[66:67], 1.0 op_sel_hi:[1,0]
	s_nop 0
	v_rcp_f32_e32 v71, v66
	s_nop 0
	v_mul_f32_e32 v66, v84, v71
	v_and_b32_e32 v84, 0xffff0000, v100
	v_rcp_f32_e32 v67, v67
	s_nop 0
	v_mul_f32_e32 v67, v68, v67
	v_mul_f32_e32 v71, v66, v67
	v_mul_f32_e32 v66, 0xbfb8aa3b, v73
	v_exp_f32_e32 v67, v66
	v_mul_f32_e32 v66, 0xbfb8aa3b, v83
	v_exp_f32_e32 v66, v66
	s_nop 0
	v_pk_add_f32 v[66:67], v[66:67], 1.0 op_sel_hi:[1,0]
	s_nop 0
	v_rcp_f32_e32 v68, v66
	s_nop 0
	v_mul_f32_e32 v66, v83, v68
	v_lshlrev_b32_e32 v83, 16, v101
	v_rcp_f32_e32 v67, v67
	s_nop 0
	v_mul_f32_e32 v67, v69, v67
	v_mul_f32_e32 v69, v66, v67
	v_cvt_pk_bf16_f32 v68, v78, v70
	v_cvt_pk_bf16_f32 v69, v71, v69
	v_lshlrev_b64 v[70:71], 11, v[104:105]
	v_lshl_add_u64 v[70:71], s[10:11], 0, v[70:71]
	v_lshl_add_u64 v[70:71], v[70:71], 0, s[52:53]
	v_lshl_add_u64 v[70:71], v[70:71], 0, v[0:1]
	v_cvt_pk_bf16_f32 v66, v74, v75
	v_cvt_pk_bf16_f32 v67, v76, v77
	global_store_dwordx4 v[70:71], v[66:69], off offset:1152
	ds_read_b128 v[74:77], v82 offset:33792
	ds_read_b128 v[66:69], v82 offset:33808
	ds_read_b128 v[78:81], v82 offset:34048
	ds_read_b128 v[70:73], v82 offset:34064
	v_and_b32_e32 v82, 0xffff0000, v101
	s_waitcnt lgkmcnt(1)
	v_mul_f32_e32 v78, 0xbfb8aa3b, v78
	v_exp_f32_e32 v87, v78
	v_mul_f32_e32 v78, 0xbfb8aa3b, v85
	v_exp_f32_e32 v86, v78
	s_waitcnt lgkmcnt(0)
; DI float sigm(float x) { return 1.f / (1.f + __expf(-x)); }
; DI float silu(float x) { return x / (1.f + __expf(-x)); }
; DI u32x4 pack8(const float* f) { u32x4 o; o.x = pack2(f[0], f[1]); o.y = pack2(f[2], f[3]); o.z = pack2(f[4], f[5]); o.w = pack2(f[6], f[7]); return o; }
; DI void lds_barrier() { asm volatile("s_waitcnt lgkmcnt(0)\n\ts_barrier" ::: "memory"); }
; DI int tid512() { int t = threadIdx.x; asm volatile("" : "+v"(t)); return t; }
; template <int AI, int BJ>
; DI void stage_q(const f32x4 (&acc)[2][2][4][2], float* Cs) {
;   const int t = tid512(), wid = t >> 6, lane = t & 63, wr = wid >> 2, wc = wid & 3, fr = lane & 15, fq = lane >> 4;
;   lds_barrier();
; #pragma unroll
;   for (int m = 0; m < 4; ++m)
; #pragma unroll
;     for (int n = 0; n < 2; ++n)
; #pragma unroll
;       for (int j = 0; j < 4; ++j) Cs[(wr * 64 + m * 16 + fq * 4 + j) * CST + wc * 32 + n * 16 + fr] = acc[AI][BJ][m][n][j];
;   lds_barrier();
; }
; template <int AI, int BJ>
; DI void glu_quadrant(PREF p, const f32x4 (&acc)[2][2][4][2], int mt, int nt, float* Cs) {
;   const int t = tid512();
;   const int row0 = mt * 256 + AI * 128, oc0 = (nt * 2 + BJ) * 64, c = (t & 7) * 8;
;   u32x4 zr[2];
; #pragma unroll
;   for (int q = 0; q < 2; ++q) zr[q] = *(const u32x4*)(p.hb + (size_t)(row0 + (t >> 3) + 64 * q) * HW + OFF_CZ + oc0 + c);
;   stage_q<AI, BJ>(acc, Cs);
; #pragma unroll
;   for (int q = 0; q < 2; ++q) {
;     const int r = (t >> 3) + 64 * q;
;     float v[8], g[8]; ld8(Cs + r * CST + c, v); ld8(Cs + r * CST + 64 + c, g);
;     float z[8]; unpack8(zr[q], z);
; #pragma unroll
;     for (int j = 0; j < 8; ++j) v[j] = v[j] * sigm(g[j]) * silu(z[j]);
;     *(u32x4*)(p.ys + (size_t)(row0 + r) * 1024 + 512 + oc0 + c) = pack8(v);
;   }
	v_mul_f32_e32 v70, 0xbfb8aa3b, v70
	v_pk_add_f32 v[86:87], v[86:87], 1.0 op_sel_hi:[1,0]
	s_nop 0
	v_rcp_f32_e32 v78, v86
	s_nop 0
	v_mul_f32_e32 v78, v85, v78
	v_rcp_f32_e32 v85, v87
	s_nop 0
	v_mul_f32_e32 v74, v74, v85
	v_mul_f32_e32 v74, v78, v74
	v_mul_f32_e32 v78, 0xbfb8aa3b, v79
	v_exp_f32_e32 v79, v78
	v_mul_f32_e32 v78, 0xbfb8aa3b, v88
	v_exp_f32_e32 v78, v78
	s_nop 0
	v_pk_add_f32 v[78:79], v[78:79], 1.0 op_sel_hi:[1,0]
	s_nop 0
	v_rcp_f32_e32 v85, v78
	s_nop 0
	v_mul_f32_e32 v78, v88, v85
	v_rcp_f32_e32 v79, v79
	s_nop 0
	v_mul_f32_e32 v75, v75, v79
	v_mul_f32_e32 v75, v78, v75
	v_mul_f32_e32 v78, 0xbfb8aa3b, v80
	v_exp_f32_e32 v79, v78
	v_mul_f32_e32 v78, 0xbfb8aa3b, v89
	v_exp_f32_e32 v78, v78
	s_nop 0
	v_pk_add_f32 v[78:79], v[78:79], 1.0 op_sel_hi:[1,0]
	s_nop 0
	v_rcp_f32_e32 v80, v78
	s_nop 0
	v_mul_f32_e32 v78, v89, v80
	v_rcp_f32_e32 v79, v79
	s_nop 0
	v_mul_f32_e32 v76, v76, v79
	v_mul_f32_e32 v76, v78, v76
	v_mul_f32_e32 v78, 0xbfb8aa3b, v81
	v_exp_f32_e32 v79, v78
	v_mul_f32_e32 v78, 0xbfb8aa3b, v90
	v_exp_f32_e32 v78, v78
	s_nop 0
	v_pk_add_f32 v[78:79], v[78:79], 1.0 op_sel_hi:[1,0]
	s_nop 0
	v_rcp_f32_e32 v80, v78
	s_nop 0
	v_mul_f32_e32 v78, v90, v80
	v_rcp_f32_e32 v79, v79
	s_nop 0
	v_mul_f32_e32 v77, v77, v79
	v_exp_f32_e32 v79, v70
	v_mul_f32_e32 v70, 0xbfb8aa3b, v91
	v_mul_f32_e32 v77, v78, v77
	v_exp_f32_e32 v78, v70
	s_nop 0
	v_pk_add_f32 v[78:79], v[78:79], 1.0 op_sel_hi:[1,0]
	s_nop 0
	v_rcp_f32_e32 v70, v78
	s_nop 0
	v_mul_f32_e32 v70, v91, v70
	v_rcp_f32_e32 v78, v79
	s_nop 0
	v_mul_f32_e32 v66, v66, v78
	v_mul_f32_e32 v78, v70, v66
	v_mul_f32_e32 v66, 0xbfb8aa3b, v71
	v_exp_f32_e32 v71, v66
	v_mul_f32_e32 v66, 0xbfb8aa3b, v84
	v_exp_f32_e32 v70, v66
	s_nop 0
	v_pk_add_f32 v[70:71], v[70:71], 1.0 op_sel_hi:[1,0]
	s_nop 0
	v_rcp_f32_e32 v66, v70
	s_nop 0
	v_mul_f32_e32 v66, v84, v66
	v_rcp_f32_e32 v70, v71
	s_nop 0
	v_mul_f32_e32 v67, v67, v70
	v_mul_f32_e32 v70, v66, v67
	v_mul_f32_e32 v66, 0xbfb8aa3b, v72
	v_exp_f32_e32 v67, v66
	v_mul_f32_e32 v66, 0xbfb8aa3b, v83
	v_exp_f32_e32 v66, v66
	s_nop 0
	v_pk_add_f32 v[66:67], v[66:67], 1.0 op_sel_hi:[1,0]
	s_nop 0
	v_rcp_f32_e32 v71, v66
	s_nop 0
	v_mul_f32_e32 v66, v83, v71
	v_rcp_f32_e32 v67, v67
	s_nop 0
	v_mul_f32_e32 v67, v68, v67
	v_mul_f32_e32 v71, v66, v67
	v_mul_f32_e32 v66, 0xbfb8aa3b, v73
	v_exp_f32_e32 v67, v66
	v_mul_f32_e32 v66, 0xbfb8aa3b, v82
	v_exp_f32_e32 v66, v66
	s_nop 0
	v_pk_add_f32 v[66:67], v[66:67], 1.0 op_sel_hi:[1,0]
	s_nop 0
	v_rcp_f32_e32 v68, v66
	s_nop 0
	v_mul_f32_e32 v66, v82, v68
	v_rcp_f32_e32 v67, v67
	s_nop 0
	v_mul_f32_e32 v67, v69, v67
	v_mul_f32_e32 v69, v66, v67
	v_cvt_pk_bf16_f32 v68, v78, v70
	v_cvt_pk_bf16_f32 v69, v71, v69
	v_lshlrev_b64 v[70:71], 11, v[102:103]
	v_lshl_add_u64 v[70:71], s[10:11], 0, v[70:71]
	v_lshl_add_u64 v[70:71], v[70:71], 0, s[52:53]
	v_lshl_add_u64 v[70:71], v[70:71], 0, v[0:1]
	v_mov_b32_e32 v0, v168
	v_cvt_pk_bf16_f32 v66, v74, v75
	v_cvt_pk_bf16_f32 v67, v76, v77
	global_store_dwordx4 v[70:71], v[66:69], off offset:1152
	v_mov_b32_e32 v78, v168
	v_ashrrev_i32_e32 v81, 3, v0
	v_lshlrev_b32_e32 v66, 3, v0
	v_add_u32_e32 v72, s14, v81
	v_and_b32_e32 v80, 56, v66
	v_mad_i64_i32 v[66:67], s[0:1], v72, s60, v[138:139]
	v_lshl_add_u64 v[66:67], v[66:67], 0, s[52:53]
	v_lshlrev_b32_e32 v0, 1, v80
	v_lshl_add_u64 v[66:67], v[66:67], 0, v[0:1]
	global_load_dwordx4 v[74:77], v[66:67], off offset:3392
	v_add_u32_e32 v70, 64, v72
	v_mad_i64_i32 v[66:67], s[0:1], v70, s60, v[138:139]
	v_lshl_add_u64 v[66:67], v[66:67], 0, s[52:53]
	v_lshl_add_u64 v[66:67], v[66:67], 0, v[0:1]
	global_load_dwordx4 v[66:69], v[66:67], off offset:3392
	s_waitcnt lgkmcnt(0)
	s_barrier
	v_ashrrev_i32_e32 v73, 31, v72
	v_and_b32_e32 v79, 15, v78
	v_lshrrev_b32_e32 v82, 2, v78
	v_lshlrev_b32_e32 v78, 1, v78
	v_lshlrev_b32_e32 v79, 2, v79
	v_and_b32_e32 v82, 0xfffffcc, v82
	v_and_or_b32 v78, v78, s89, v79
	v_mad_u64_u32 v[78:79], s[0:1], v82, s92, v[78:79]
	ds_write2_b32 v78, v54, v62 offset1:16
	ds_write2_b32 v78, v55, v63 offset0:132 offset1:148
	v_add_u32_e32 v54, 0x400, v78
	ds_write2_b32 v54, v56, v64 offset0:8 offset1:24
	ds_write2_b32 v54, v57, v65 offset0:140 offset1:156
	v_add_u32_e32 v54, 0x2000, v78
	ds_write2_b32 v54, v50, v58 offset0:64 offset1:80
	ds_write2_b32 v54, v51, v59 offset0:196 offset1:212
	v_add_u32_e32 v50, 0x2400, v78
	ds_write2_b32 v50, v52, v60 offset0:72 offset1:88
	ds_write2_b32 v50, v53, v61 offset0:204 offset1:220
	v_add_u32_e32 v50, 0x4000, v78
	ds_write2_b32 v50, v42, v46 offset0:128 offset1:144
	v_add_u32_e32 v42, 0x4400, v78
	ds_write2_b32 v42, v43, v47 offset0:4 offset1:20
	ds_write2_b32 v42, v44, v48 offset0:136 offset1:152
	v_add_u32_e32 v42, 0x4800, v78
	ds_write2_b32 v42, v45, v49 offset0:12 offset1:28
	v_add_u32_e32 v42, 0x6000, v78
	ds_write2_b32 v42, v34, v38 offset0:192 offset1:208
	v_add_u32_e32 v34, 0x6400, v78
	ds_write2_b32 v34, v35, v39 offset0:68 offset1:84
	ds_write2_b32 v34, v36, v40 offset0:200 offset1:216
	v_add_u32_e32 v34, 0x6800, v78
	ds_write2_b32 v34, v37, v41 offset0:76 offset1:92
	v_mul_lo_u32 v34, v81, s92
	s_waitcnt lgkmcnt(0)
	s_barrier
; DI float sigm(float x) { return 1.f / (1.f + __expf(-x)); }
; DI float silu(float x) { return x / (1.f + __expf(-x)); }
; DI u32x4 pack8(const float* f) { u32x4 o; o.x = pack2(f[0], f[1]); o.y = pack2(f[2], f[3]); o.z = pack2(f[4], f[5]); o.w = pack2(f[6], f[7]); return o; }
; DI int tid512() { int t = threadIdx.x; asm volatile("" : "+v"(t)); return t; }
; template <int AI, int BJ>
; DI void glu_quadrant(PREF p, const f32x4 (&acc)[2][2][4][2], int mt, int nt, float* Cs) {
;   const int t = tid512();
;   const int row0 = mt * 256 + AI * 128, oc0 = (nt * 2 + BJ) * 64, c = (t & 7) * 8;
;   u32x4 zr[2];
; #pragma unroll
;   for (int q = 0; q < 2; ++q) zr[q] = *(const u32x4*)(p.hb + (size_t)(row0 + (t >> 3) + 64 * q) * HW + OFF_CZ + oc0 + c);
;   stage_q<AI, BJ>(acc, Cs);
; #pragma unroll
;   for (int q = 0; q < 2; ++q) {
;     const int r = (t >> 3) + 64 * q;
;     float v[8], g[8]; ld8(Cs + r * CST + c, v); ld8(Cs + r * CST + 64 + c, g);
;     float z[8]; unpack8(zr[q], z);
; #pragma unroll
;     for (int j = 0; j < 8; ++j) v[j] = v[j] * sigm(g[j]) * silu(z[j]);
;     *(u32x4*)(p.ys + (size_t)(row0 + r) * 1024 + 512 + oc0 + c) = pack8(v);
;   }
	v_lshl_add_u32 v50, v80, 2, v34
	ds_read_b128 v[42:45], v50
	ds_read_b128 v[34:37], v50 offset:16
	ds_read_b128 v[46:49], v50 offset:256
	ds_read_b128 v[38:41], v50 offset:272
	v_ashrrev_i32_e32 v71, 31, v70
	s_waitcnt lgkmcnt(1)
	v_mul_f32_e32 v46, 0xbfb8aa3b, v46
	v_exp_f32_e32 v55, v46
	s_waitcnt lgkmcnt(0)
	v_mul_f32_e32 v38, 0xbfb8aa3b, v38
	s_waitcnt vmcnt(1)
	v_lshlrev_b32_e32 v56, 16, v74
	v_mul_f32_e32 v46, 0xbfb8aa3b, v56
	v_exp_f32_e32 v54, v46
	v_and_b32_e32 v57, 0xffff0000, v74
	v_lshlrev_b32_e32 v58, 16, v75
	v_and_b32_e32 v59, 0xffff0000, v75
	v_pk_add_f32 v[54:55], v[54:55], 1.0 op_sel_hi:[1,0]
	v_lshlrev_b32_e32 v60, 16, v76
	v_and_b32_e32 v53, 0xffff0000, v76
	v_lshlrev_b32_e32 v52, 16, v77
	v_and_b32_e32 v51, 0xffff0000, v77
	v_rcp_f32_e32 v46, v54
	s_nop 0
	v_mul_f32_e32 v46, v56, v46
	v_rcp_f32_e32 v54, v55
	s_nop 0
	v_mul_f32_e32 v42, v42, v54
	v_mul_f32_e32 v42, v46, v42
	v_mul_f32_e32 v46, 0xbfb8aa3b, v47
	v_exp_f32_e32 v47, v46
	v_mul_f32_e32 v46, 0xbfb8aa3b, v57
	v_exp_f32_e32 v46, v46
	s_nop 0
	v_pk_add_f32 v[46:47], v[46:47], 1.0 op_sel_hi:[1,0]
	s_nop 0
	v_rcp_f32_e32 v54, v46
	s_nop 0
	v_mul_f32_e32 v46, v57, v54
	v_rcp_f32_e32 v47, v47
	s_nop 0
	v_mul_f32_e32 v43, v43, v47
	v_mul_f32_e32 v43, v46, v43
	v_mul_f32_e32 v46, 0xbfb8aa3b, v48
	v_exp_f32_e32 v47, v46
	v_mul_f32_e32 v46, 0xbfb8aa3b, v58
	v_exp_f32_e32 v46, v46
	s_nop 0
	v_pk_add_f32 v[46:47], v[46:47], 1.0 op_sel_hi:[1,0]
	s_nop 0
	v_rcp_f32_e32 v48, v46
	s_nop 0
	v_mul_f32_e32 v46, v58, v48
	s_waitcnt vmcnt(0)
	v_and_b32_e32 v58, 0xffff0000, v67
	v_rcp_f32_e32 v47, v47
	s_nop 0
	v_mul_f32_e32 v44, v44, v47
	v_mul_f32_e32 v44, v46, v44
	v_mul_f32_e32 v46, 0xbfb8aa3b, v49
	v_exp_f32_e32 v47, v46
	v_mul_f32_e32 v46, 0xbfb8aa3b, v59
	v_exp_f32_e32 v46, v46
	v_lshlrev_b32_e32 v57, 16, v67
	v_pk_add_f32 v[46:47], v[46:47], 1.0 op_sel_hi:[1,0]
	s_nop 0
	v_rcp_f32_e32 v48, v46
	s_nop 0
	v_mul_f32_e32 v46, v59, v48
	v_lshlrev_b32_e32 v59, 16, v68
	v_rcp_f32_e32 v47, v47
	s_nop 0
	v_mul_f32_e32 v45, v45, v47
	v_exp_f32_e32 v47, v38
	v_mul_f32_e32 v38, 0xbfb8aa3b, v60
	v_mul_f32_e32 v45, v46, v45
	v_exp_f32_e32 v46, v38
	v_and_b32_e32 v56, 0xffff0000, v66
	v_pk_add_f32 v[46:47], v[46:47], 1.0 op_sel_hi:[1,0]
	s_nop 0
	v_rcp_f32_e32 v38, v46
	s_nop 0
	v_mul_f32_e32 v38, v60, v38
	v_rcp_f32_e32 v46, v47
	s_nop 0
	v_mul_f32_e32 v34, v34, v46
	v_mul_f32_e32 v46, v38, v34
	v_mul_f32_e32 v34, 0xbfb8aa3b, v39
	v_exp_f32_e32 v39, v34
	v_mul_f32_e32 v34, 0xbfb8aa3b, v53
	v_exp_f32_e32 v38, v34
	s_nop 0
	v_pk_add_f32 v[38:39], v[38:39], 1.0 op_sel_hi:[1,0]
	s_nop 0
	v_rcp_f32_e32 v34, v38
	s_nop 0
	v_mul_f32_e32 v34, v53, v34
	v_rcp_f32_e32 v38, v39
	s_nop 0
	v_mul_f32_e32 v35, v35, v38
	v_mul_f32_e32 v38, v34, v35
	v_mul_f32_e32 v34, 0xbfb8aa3b, v40
	v_exp_f32_e32 v35, v34
	v_mul_f32_e32 v34, 0xbfb8aa3b, v52
	v_exp_f32_e32 v34, v34
	v_lshlrev_b32_e32 v53, 16, v66
	v_pk_add_f32 v[34:35], v[34:35], 1.0 op_sel_hi:[1,0]
	s_nop 0
	v_rcp_f32_e32 v39, v34
	s_nop 0
	v_mul_f32_e32 v34, v52, v39
	v_and_b32_e32 v52, 0xffff0000, v68
	v_rcp_f32_e32 v35, v35
	s_nop 0
	v_mul_f32_e32 v35, v36, v35
	v_mul_f32_e32 v39, v34, v35
	v_mul_f32_e32 v34, 0xbfb8aa3b, v41
	v_exp_f32_e32 v35, v34
	v_mul_f32_e32 v34, 0xbfb8aa3b, v51
	v_exp_f32_e32 v34, v34
	s_nop 0
	v_pk_add_f32 v[34:35], v[34:35], 1.0 op_sel_hi:[1,0]
	s_nop 0
	v_rcp_f32_e32 v36, v34
	s_nop 0
	v_mul_f32_e32 v34, v51, v36
	v_lshlrev_b32_e32 v51, 16, v69
	v_rcp_f32_e32 v35, v35
	s_nop 0
	v_mul_f32_e32 v35, v37, v35
	v_mul_f32_e32 v37, v34, v35
	v_cvt_pk_bf16_f32 v36, v46, v38
	v_cvt_pk_bf16_f32 v37, v39, v37
	v_lshlrev_b64 v[38:39], 11, v[72:73]
	v_lshl_add_u64 v[38:39], s[10:11], 0, v[38:39]
	v_lshl_add_u64 v[38:39], v[38:39], 0, s[52:53]
	v_lshl_add_u64 v[38:39], v[38:39], 0, v[0:1]
	v_cvt_pk_bf16_f32 v34, v42, v43
	v_cvt_pk_bf16_f32 v35, v44, v45
	global_store_dwordx4 v[38:39], v[34:37], off offset:1024
	ds_read_b128 v[42:45], v50 offset:33792
	ds_read_b128 v[34:37], v50 offset:33808
	ds_read_b128 v[46:49], v50 offset:34048
	ds_read_b128 v[38:41], v50 offset:34064
	v_and_b32_e32 v50, 0xffff0000, v69
	s_waitcnt lgkmcnt(1)
	v_mul_f32_e32 v46, 0xbfb8aa3b, v46
	v_exp_f32_e32 v55, v46
	v_mul_f32_e32 v46, 0xbfb8aa3b, v53
	v_exp_f32_e32 v54, v46
	s_waitcnt lgkmcnt(0)
; DI float sigm(float x) { return 1.f / (1.f + __expf(-x)); }
; DI float silu(float x) { return x / (1.f + __expf(-x)); }
; DI u32x4 pack8(const float* f) { u32x4 o; o.x = pack2(f[0], f[1]); o.y = pack2(f[2], f[3]); o.z = pack2(f[4], f[5]); o.w = pack2(f[6], f[7]); return o; }
; DI void lds_barrier() { asm volatile("s_waitcnt lgkmcnt(0)\n\ts_barrier" ::: "memory"); }
; DI int tid512() { int t = threadIdx.x; asm volatile("" : "+v"(t)); return t; }
; template <int AI, int BJ>
; DI void stage_q(const f32x4 (&acc)[2][2][4][2], float* Cs) {
;   const int t = tid512(), wid = t >> 6, lane = t & 63, wr = wid >> 2, wc = wid & 3, fr = lane & 15, fq = lane >> 4;
;   lds_barrier();
; #pragma unroll
;   for (int m = 0; m < 4; ++m)
; #pragma unroll
;     for (int n = 0; n < 2; ++n)
; #pragma unroll
;       for (int j = 0; j < 4; ++j) Cs[(wr * 64 + m * 16 + fq * 4 + j) * CST + wc * 32 + n * 16 + fr] = acc[AI][BJ][m][n][j];
;   lds_barrier();
; }
; template <int AI, int BJ>
; DI void glu_quadrant(PREF p, const f32x4 (&acc)[2][2][4][2], int mt, int nt, float* Cs) {
;   const int t = tid512();
;   const int row0 = mt * 256 + AI * 128, oc0 = (nt * 2 + BJ) * 64, c = (t & 7) * 8;
;   u32x4 zr[2];
; #pragma unroll
;   for (int q = 0; q < 2; ++q) zr[q] = *(const u32x4*)(p.hb + (size_t)(row0 + (t >> 3) + 64 * q) * HW + OFF_CZ + oc0 + c);
;   stage_q<AI, BJ>(acc, Cs);
; #pragma unroll
;   for (int q = 0; q < 2; ++q) {
;     const int r = (t >> 3) + 64 * q;
;     float v[8], g[8]; ld8(Cs + r * CST + c, v); ld8(Cs + r * CST + 64 + c, g);
;     float z[8]; unpack8(zr[q], z);
; #pragma unroll
;     for (int j = 0; j < 8; ++j) v[j] = v[j] * sigm(g[j]) * silu(z[j]);
;     *(u32x4*)(p.ys + (size_t)(row0 + r) * 1024 + 512 + oc0 + c) = pack8(v);
;   }
	v_mul_f32_e32 v38, 0xbfb8aa3b, v38
	v_pk_add_f32 v[54:55], v[54:55], 1.0 op_sel_hi:[1,0]
	s_nop 0
	v_rcp_f32_e32 v46, v54
	s_nop 0
	v_mul_f32_e32 v46, v53, v46
	v_rcp_f32_e32 v53, v55
	s_nop 0
	v_mul_f32_e32 v42, v42, v53
	v_mul_f32_e32 v42, v46, v42
	v_mul_f32_e32 v46, 0xbfb8aa3b, v47
	v_exp_f32_e32 v47, v46
	v_mul_f32_e32 v46, 0xbfb8aa3b, v56
	v_exp_f32_e32 v46, v46
	s_nop 0
	v_pk_add_f32 v[46:47], v[46:47], 1.0 op_sel_hi:[1,0]
	s_nop 0
	v_rcp_f32_e32 v53, v46
	s_nop 0
	v_mul_f32_e32 v46, v56, v53
	v_rcp_f32_e32 v47, v47
	s_nop 0
	v_mul_f32_e32 v43, v43, v47
	v_mul_f32_e32 v43, v46, v43
	v_mul_f32_e32 v46, 0xbfb8aa3b, v48
	v_exp_f32_e32 v47, v46
	v_mul_f32_e32 v46, 0xbfb8aa3b, v57
	v_exp_f32_e32 v46, v46
	s_nop 0
	v_pk_add_f32 v[46:47], v[46:47], 1.0 op_sel_hi:[1,0]
	s_nop 0
	v_rcp_f32_e32 v48, v46
	s_nop 0
	v_mul_f32_e32 v46, v57, v48
	v_rcp_f32_e32 v47, v47
	s_nop 0
	v_mul_f32_e32 v44, v44, v47
	v_mul_f32_e32 v44, v46, v44
	v_mul_f32_e32 v46, 0xbfb8aa3b, v49
	v_exp_f32_e32 v47, v46
	v_mul_f32_e32 v46, 0xbfb8aa3b, v58
	v_exp_f32_e32 v46, v46
	s_nop 0
	v_pk_add_f32 v[46:47], v[46:47], 1.0 op_sel_hi:[1,0]
	s_nop 0
	v_rcp_f32_e32 v48, v46
	s_nop 0
	v_mul_f32_e32 v46, v58, v48
	v_rcp_f32_e32 v47, v47
	s_nop 0
	v_mul_f32_e32 v45, v45, v47
	v_exp_f32_e32 v47, v38
	v_mul_f32_e32 v38, 0xbfb8aa3b, v59
	v_mul_f32_e32 v45, v46, v45
	v_exp_f32_e32 v46, v38
	s_nop 0
	v_pk_add_f32 v[46:47], v[46:47], 1.0 op_sel_hi:[1,0]
	s_nop 0
	v_rcp_f32_e32 v38, v46
	s_nop 0
	v_mul_f32_e32 v38, v59, v38
	v_rcp_f32_e32 v46, v47
	s_nop 0
	v_mul_f32_e32 v34, v34, v46
	v_mul_f32_e32 v46, v38, v34
	v_mul_f32_e32 v34, 0xbfb8aa3b, v39
	v_exp_f32_e32 v39, v34
	v_mul_f32_e32 v34, 0xbfb8aa3b, v52
	v_exp_f32_e32 v38, v34
	s_nop 0
	v_pk_add_f32 v[38:39], v[38:39], 1.0 op_sel_hi:[1,0]
	s_nop 0
	v_rcp_f32_e32 v34, v38
	s_nop 0
	v_mul_f32_e32 v34, v52, v34
	v_rcp_f32_e32 v38, v39
	s_nop 0
	v_mul_f32_e32 v35, v35, v38
	v_mul_f32_e32 v38, v34, v35
	v_mul_f32_e32 v34, 0xbfb8aa3b, v40
	v_exp_f32_e32 v35, v34
	v_mul_f32_e32 v34, 0xbfb8aa3b, v51
	v_exp_f32_e32 v34, v34
	s_nop 0
	v_pk_add_f32 v[34:35], v[34:35], 1.0 op_sel_hi:[1,0]
	s_nop 0
	v_rcp_f32_e32 v39, v34
	s_nop 0
	v_mul_f32_e32 v34, v51, v39
	v_rcp_f32_e32 v35, v35
	s_nop 0
	v_mul_f32_e32 v35, v36, v35
	v_mul_f32_e32 v39, v34, v35
	v_mul_f32_e32 v34, 0xbfb8aa3b, v41
	v_exp_f32_e32 v35, v34
	v_mul_f32_e32 v34, 0xbfb8aa3b, v50
	v_exp_f32_e32 v34, v34
	s_nop 0
	v_pk_add_f32 v[34:35], v[34:35], 1.0 op_sel_hi:[1,0]
	s_nop 0
	v_rcp_f32_e32 v36, v34
	s_nop 0
	v_mul_f32_e32 v34, v50, v36
	v_rcp_f32_e32 v35, v35
	s_nop 0
	v_mul_f32_e32 v35, v37, v35
	v_mul_f32_e32 v37, v34, v35
	v_cvt_pk_bf16_f32 v36, v46, v38
	v_cvt_pk_bf16_f32 v37, v39, v37
	v_lshlrev_b64 v[38:39], 11, v[70:71]
	v_lshl_add_u64 v[38:39], s[10:11], 0, v[38:39]
	v_lshl_add_u64 v[38:39], v[38:39], 0, s[52:53]
	v_lshl_add_u64 v[38:39], v[38:39], 0, v[0:1]
	v_mov_b32_e32 v0, v168
	v_cvt_pk_bf16_f32 v34, v42, v43
	v_cvt_pk_bf16_f32 v35, v44, v45
	global_store_dwordx4 v[38:39], v[34:37], off offset:1024
	v_mov_b32_e32 v46, v168
	v_ashrrev_i32_e32 v49, 3, v0
	v_lshlrev_b32_e32 v34, 3, v0
	v_add_u32_e32 v40, s14, v49
	v_and_b32_e32 v48, 56, v34
	v_mad_i64_i32 v[34:35], s[0:1], v40, s60, v[138:139]
	v_lshl_add_u64 v[34:35], v[34:35], 0, s[52:53]
	v_lshlrev_b32_e32 v0, 1, v48
	v_lshl_add_u64 v[34:35], v[34:35], 0, v[0:1]
	global_load_dwordx4 v[42:45], v[34:35], off offset:3520
	v_add_u32_e32 v38, 64, v40
	v_mad_i64_i32 v[34:35], s[0:1], v38, s60, v[138:139]
	v_lshl_add_u64 v[34:35], v[34:35], 0, s[52:53]
	v_lshl_add_u64 v[34:35], v[34:35], 0, v[0:1]
	global_load_dwordx4 v[34:37], v[34:35], off offset:3520
	s_waitcnt lgkmcnt(0)
	s_barrier
	v_ashrrev_i32_e32 v41, 31, v40
	v_and_b32_e32 v47, 15, v46
	v_lshrrev_b32_e32 v50, 2, v46
	v_lshlrev_b32_e32 v46, 1, v46
	v_lshlrev_b32_e32 v47, 2, v47
	v_and_b32_e32 v50, 0xfffffcc, v50
	v_and_or_b32 v46, v46, s89, v47
	v_mad_u64_u32 v[46:47], s[0:1], v50, s92, v[46:47]
	ds_write2_b32 v46, v22, v30 offset1:16
	ds_write2_b32 v46, v23, v31 offset0:132 offset1:148
	v_add_u32_e32 v22, 0x400, v46
	ds_write2_b32 v22, v24, v32 offset0:8 offset1:24
	ds_write2_b32 v22, v25, v33 offset0:140 offset1:156
	v_add_u32_e32 v22, 0x2000, v46
	ds_write2_b32 v22, v18, v26 offset0:64 offset1:80
	ds_write2_b32 v22, v19, v27 offset0:196 offset1:212
	v_add_u32_e32 v18, 0x2400, v46
	ds_write2_b32 v18, v20, v28 offset0:72 offset1:88
	ds_write2_b32 v18, v21, v29 offset0:204 offset1:220
	v_add_u32_e32 v18, 0x4000, v46
	ds_write2_b32 v18, v10, v14 offset0:128 offset1:144
	v_add_u32_e32 v10, 0x4400, v46
	ds_write2_b32 v10, v11, v15 offset0:4 offset1:20
	ds_write2_b32 v10, v12, v16 offset0:136 offset1:152
	v_add_u32_e32 v10, 0x4800, v46
	ds_write2_b32 v10, v13, v17 offset0:12 offset1:28
	v_add_u32_e32 v10, 0x6000, v46
	ds_write2_b32 v10, v2, v6 offset0:192 offset1:208
	v_add_u32_e32 v2, 0x6400, v46
	ds_write2_b32 v2, v3, v7 offset0:68 offset1:84
	ds_write2_b32 v2, v4, v8 offset0:200 offset1:216
	v_add_u32_e32 v2, 0x6800, v46
	ds_write2_b32 v2, v5, v9 offset0:76 offset1:92
	v_mul_lo_u32 v2, v49, s92
	s_waitcnt lgkmcnt(0)
	s_barrier
; DI float sigm(float x) { return 1.f / (1.f + __expf(-x)); }
; DI float silu(float x) { return x / (1.f + __expf(-x)); }
; DI u32x4 pack8(const float* f) { u32x4 o; o.x = pack2(f[0], f[1]); o.y = pack2(f[2], f[3]); o.z = pack2(f[4], f[5]); o.w = pack2(f[6], f[7]); return o; }
; DI int tid512() { int t = threadIdx.x; asm volatile("" : "+v"(t)); return t; }
; template <int AI, int BJ>
; DI void glu_quadrant(PREF p, const f32x4 (&acc)[2][2][4][2], int mt, int nt, float* Cs) {
;   const int t = tid512();
;   const int row0 = mt * 256 + AI * 128, oc0 = (nt * 2 + BJ) * 64, c = (t & 7) * 8;
;   u32x4 zr[2];
; #pragma unroll
;   for (int q = 0; q < 2; ++q) zr[q] = *(const u32x4*)(p.hb + (size_t)(row0 + (t >> 3) + 64 * q) * HW + OFF_CZ + oc0 + c);
;   stage_q<AI, BJ>(acc, Cs);
; #pragma unroll
;   for (int q = 0; q < 2; ++q) {
;     const int r = (t >> 3) + 64 * q;
;     float v[8], g[8]; ld8(Cs + r * CST + c, v); ld8(Cs + r * CST + 64 + c, g);
;     float z[8]; unpack8(zr[q], z);
; #pragma unroll
;     for (int j = 0; j < 8; ++j) v[j] = v[j] * sigm(g[j]) * silu(z[j]);
;     *(u32x4*)(p.ys + (size_t)(row0 + r) * 1024 + 512 + oc0 + c) = pack8(v);
;   }
	v_lshl_add_u32 v18, v48, 2, v2
	ds_read_b128 v[10:13], v18
	ds_read_b128 v[2:5], v18 offset:16
	ds_read_b128 v[14:17], v18 offset:256
	ds_read_b128 v[6:9], v18 offset:272
	v_ashrrev_i32_e32 v39, 31, v38
	s_waitcnt lgkmcnt(1)
	v_mul_f32_e32 v14, 0xbfb8aa3b, v14
	v_exp_f32_e32 v23, v14
	s_waitcnt lgkmcnt(0)
	v_mul_f32_e32 v6, 0xbfb8aa3b, v6
	s_waitcnt vmcnt(1)
	v_lshlrev_b32_e32 v24, 16, v42
	v_mul_f32_e32 v14, 0xbfb8aa3b, v24
	v_exp_f32_e32 v22, v14
	v_and_b32_e32 v25, 0xffff0000, v42
	v_lshlrev_b32_e32 v26, 16, v43
	v_and_b32_e32 v27, 0xffff0000, v43
	v_pk_add_f32 v[22:23], v[22:23], 1.0 op_sel_hi:[1,0]
	v_lshlrev_b32_e32 v28, 16, v44
	v_and_b32_e32 v21, 0xffff0000, v44
	v_lshlrev_b32_e32 v20, 16, v45
	v_and_b32_e32 v19, 0xffff0000, v45
	v_rcp_f32_e32 v14, v22
	s_nop 0
	v_mul_f32_e32 v14, v24, v14
	v_rcp_f32_e32 v22, v23
	s_nop 0
	v_mul_f32_e32 v10, v10, v22
	v_mul_f32_e32 v10, v14, v10
	v_mul_f32_e32 v14, 0xbfb8aa3b, v15
	v_exp_f32_e32 v15, v14
	v_mul_f32_e32 v14, 0xbfb8aa3b, v25
	v_exp_f32_e32 v14, v14
	s_nop 0
	v_pk_add_f32 v[14:15], v[14:15], 1.0 op_sel_hi:[1,0]
	s_nop 0
	v_rcp_f32_e32 v22, v14
	s_nop 0
	v_mul_f32_e32 v14, v25, v22
	v_rcp_f32_e32 v15, v15
	s_nop 0
	v_mul_f32_e32 v11, v11, v15
	v_mul_f32_e32 v11, v14, v11
	v_mul_f32_e32 v14, 0xbfb8aa3b, v16
	v_exp_f32_e32 v15, v14
	v_mul_f32_e32 v14, 0xbfb8aa3b, v26
	v_exp_f32_e32 v14, v14
	s_nop 0
	v_pk_add_f32 v[14:15], v[14:15], 1.0 op_sel_hi:[1,0]
	s_nop 0
	v_rcp_f32_e32 v16, v14
	s_nop 0
	v_mul_f32_e32 v14, v26, v16
	s_waitcnt vmcnt(0)
	v_and_b32_e32 v26, 0xffff0000, v35
	v_rcp_f32_e32 v15, v15
	s_nop 0
	v_mul_f32_e32 v12, v12, v15
	v_mul_f32_e32 v12, v14, v12
	v_mul_f32_e32 v14, 0xbfb8aa3b, v17
	v_exp_f32_e32 v15, v14
	v_mul_f32_e32 v14, 0xbfb8aa3b, v27
	v_exp_f32_e32 v14, v14
	v_lshlrev_b32_e32 v25, 16, v35
	v_pk_add_f32 v[14:15], v[14:15], 1.0 op_sel_hi:[1,0]
	s_nop 0
	v_rcp_f32_e32 v16, v14
	s_nop 0
	v_mul_f32_e32 v14, v27, v16
	v_lshlrev_b32_e32 v27, 16, v36
	v_rcp_f32_e32 v15, v15
	s_nop 0
	v_mul_f32_e32 v13, v13, v15
	v_exp_f32_e32 v15, v6
	v_mul_f32_e32 v6, 0xbfb8aa3b, v28
	v_mul_f32_e32 v13, v14, v13
	v_exp_f32_e32 v14, v6
	v_and_b32_e32 v24, 0xffff0000, v34
	v_pk_add_f32 v[14:15], v[14:15], 1.0 op_sel_hi:[1,0]
	s_nop 0
	v_rcp_f32_e32 v6, v14
	s_nop 0
	v_mul_f32_e32 v6, v28, v6
	v_rcp_f32_e32 v14, v15
	s_nop 0
	v_mul_f32_e32 v2, v2, v14
	v_mul_f32_e32 v14, v6, v2
	v_mul_f32_e32 v2, 0xbfb8aa3b, v7
	v_exp_f32_e32 v7, v2
	v_mul_f32_e32 v2, 0xbfb8aa3b, v21
	v_exp_f32_e32 v6, v2
	s_nop 0
	v_pk_add_f32 v[6:7], v[6:7], 1.0 op_sel_hi:[1,0]
	s_nop 0
	v_rcp_f32_e32 v2, v6
	s_nop 0
	v_mul_f32_e32 v2, v21, v2
	v_rcp_f32_e32 v6, v7
	s_nop 0
	v_mul_f32_e32 v3, v3, v6
	v_mul_f32_e32 v6, v2, v3
	v_mul_f32_e32 v2, 0xbfb8aa3b, v8
	v_exp_f32_e32 v3, v2
	v_mul_f32_e32 v2, 0xbfb8aa3b, v20
	v_exp_f32_e32 v2, v2
	v_lshlrev_b32_e32 v21, 16, v34
	v_pk_add_f32 v[2:3], v[2:3], 1.0 op_sel_hi:[1,0]
	s_nop 0
	v_rcp_f32_e32 v7, v2
	s_nop 0
	v_mul_f32_e32 v2, v20, v7
	v_and_b32_e32 v20, 0xffff0000, v36
	v_rcp_f32_e32 v3, v3
	s_nop 0
	v_mul_f32_e32 v3, v4, v3
	v_mul_f32_e32 v7, v2, v3
	v_mul_f32_e32 v2, 0xbfb8aa3b, v9
	v_exp_f32_e32 v3, v2
	v_mul_f32_e32 v2, 0xbfb8aa3b, v19
	v_exp_f32_e32 v2, v2
	s_nop 0
	v_pk_add_f32 v[2:3], v[2:3], 1.0 op_sel_hi:[1,0]
	s_nop 0
	v_rcp_f32_e32 v4, v2
	s_nop 0
	v_mul_f32_e32 v2, v19, v4
	v_lshlrev_b32_e32 v19, 16, v37
	v_rcp_f32_e32 v3, v3
	s_nop 0
	v_mul_f32_e32 v3, v5, v3
	v_mul_f32_e32 v5, v2, v3
	v_cvt_pk_bf16_f32 v4, v14, v6
	v_cvt_pk_bf16_f32 v5, v7, v5
	v_lshlrev_b64 v[6:7], 11, v[40:41]
	v_lshl_add_u64 v[6:7], s[10:11], 0, v[6:7]
	v_lshl_add_u64 v[6:7], v[6:7], 0, s[52:53]
	v_lshl_add_u64 v[6:7], v[6:7], 0, v[0:1]
	v_cvt_pk_bf16_f32 v2, v10, v11
	v_cvt_pk_bf16_f32 v3, v12, v13
	global_store_dwordx4 v[6:7], v[2:5], off offset:1152
	ds_read_b128 v[10:13], v18 offset:33792
	ds_read_b128 v[2:5], v18 offset:33808
	ds_read_b128 v[14:17], v18 offset:34048
	ds_read_b128 v[6:9], v18 offset:34064
	v_and_b32_e32 v18, 0xffff0000, v37
	s_waitcnt lgkmcnt(1)
; DI float sigm(float x) { return 1.f / (1.f + __expf(-x)); }
; DI float silu(float x) { return x / (1.f + __expf(-x)); }
; DI u32x4 pack8(const float* f) { u32x4 o; o.x = pack2(f[0], f[1]); o.y = pack2(f[2], f[3]); o.z = pack2(f[4], f[5]); o.w = pack2(f[6], f[7]); return o; }
; DI int tid512() { int t = threadIdx.x; asm volatile("" : "+v"(t)); return t; }
; template <int AI, int BJ>
; DI void glu_quadrant(PREF p, const f32x4 (&acc)[2][2][4][2], int mt, int nt, float* Cs) {
;   const int t = tid512();
;   const int row0 = mt * 256 + AI * 128, oc0 = (nt * 2 + BJ) * 64, c = (t & 7) * 8;
;   u32x4 zr[2];
; #pragma unroll
;   for (int q = 0; q < 2; ++q) zr[q] = *(const u32x4*)(p.hb + (size_t)(row0 + (t >> 3) + 64 * q) * HW + OFF_CZ + oc0 + c);
;   stage_q<AI, BJ>(acc, Cs);
; #pragma unroll
;   for (int q = 0; q < 2; ++q) {
;     const int r = (t >> 3) + 64 * q;
;     float v[8], g[8]; ld8(Cs + r * CST + c, v); ld8(Cs + r * CST + 64 + c, g);
;     float z[8]; unpack8(zr[q], z);
; #pragma unroll
;     for (int j = 0; j < 8; ++j) v[j] = v[j] * sigm(g[j]) * silu(z[j]);
;     *(u32x4*)(p.ys + (size_t)(row0 + r) * 1024 + 512 + oc0 + c) = pack8(v);
;   }
	v_mul_f32_e32 v14, 0xbfb8aa3b, v14
	v_exp_f32_e32 v23, v14
	v_mul_f32_e32 v14, 0xbfb8aa3b, v21
	v_exp_f32_e32 v22, v14
	s_waitcnt lgkmcnt(0)
	v_mul_f32_e32 v6, 0xbfb8aa3b, v6
	v_pk_add_f32 v[22:23], v[22:23], 1.0 op_sel_hi:[1,0]
	s_nop 0
	v_rcp_f32_e32 v14, v22
	s_nop 0
	v_mul_f32_e32 v14, v21, v14
	v_rcp_f32_e32 v21, v23
	s_nop 0
	v_mul_f32_e32 v10, v10, v21
	v_mul_f32_e32 v10, v14, v10
	v_mul_f32_e32 v14, 0xbfb8aa3b, v15
	v_exp_f32_e32 v15, v14
	v_mul_f32_e32 v14, 0xbfb8aa3b, v24
	v_exp_f32_e32 v14, v14
	s_nop 0
	v_pk_add_f32 v[14:15], v[14:15], 1.0 op_sel_hi:[1,0]
	s_nop 0
	v_rcp_f32_e32 v21, v14
	s_nop 0
	v_mul_f32_e32 v14, v24, v21
	v_rcp_f32_e32 v15, v15
	s_nop 0
	v_mul_f32_e32 v11, v11, v15
	v_mul_f32_e32 v11, v14, v11
	v_mul_f32_e32 v14, 0xbfb8aa3b, v16
	v_exp_f32_e32 v15, v14
	v_mul_f32_e32 v14, 0xbfb8aa3b, v25
	v_exp_f32_e32 v14, v14
	s_nop 0
	v_pk_add_f32 v[14:15], v[14:15], 1.0 op_sel_hi:[1,0]
	s_nop 0
	v_rcp_f32_e32 v16, v14
	s_nop 0
	v_mul_f32_e32 v14, v25, v16
	v_rcp_f32_e32 v15, v15
	s_nop 0
	v_mul_f32_e32 v12, v12, v15
	v_mul_f32_e32 v12, v14, v12
	v_mul_f32_e32 v14, 0xbfb8aa3b, v17
	v_exp_f32_e32 v15, v14
	v_mul_f32_e32 v14, 0xbfb8aa3b, v26
	v_exp_f32_e32 v14, v14
	s_nop 0
	v_pk_add_f32 v[14:15], v[14:15], 1.0 op_sel_hi:[1,0]
	s_nop 0
	v_rcp_f32_e32 v16, v14
	s_nop 0
	v_mul_f32_e32 v14, v26, v16
	v_rcp_f32_e32 v15, v15
	s_nop 0
	v_mul_f32_e32 v13, v13, v15
	v_exp_f32_e32 v15, v6
	v_mul_f32_e32 v6, 0xbfb8aa3b, v27
	v_mul_f32_e32 v13, v14, v13
	v_exp_f32_e32 v14, v6
	s_nop 0
	v_pk_add_f32 v[14:15], v[14:15], 1.0 op_sel_hi:[1,0]
	s_nop 0
	v_rcp_f32_e32 v6, v14
	s_nop 0
	v_mul_f32_e32 v6, v27, v6
	v_rcp_f32_e32 v14, v15
	s_nop 0
	v_mul_f32_e32 v2, v2, v14
	v_mul_f32_e32 v14, v6, v2
	v_mul_f32_e32 v2, 0xbfb8aa3b, v7
	v_exp_f32_e32 v7, v2
	v_mul_f32_e32 v2, 0xbfb8aa3b, v20
	v_exp_f32_e32 v6, v2
	s_nop 0
	v_pk_add_f32 v[6:7], v[6:7], 1.0 op_sel_hi:[1,0]
	s_nop 0
	v_rcp_f32_e32 v2, v6
	s_nop 0
	v_mul_f32_e32 v2, v20, v2
	v_rcp_f32_e32 v6, v7
	s_nop 0
	v_mul_f32_e32 v3, v3, v6
	v_mul_f32_e32 v6, v2, v3
	v_mul_f32_e32 v2, 0xbfb8aa3b, v8
	v_exp_f32_e32 v3, v2
	v_mul_f32_e32 v2, 0xbfb8aa3b, v19
	v_exp_f32_e32 v2, v2
	s_nop 0
	v_pk_add_f32 v[2:3], v[2:3], 1.0 op_sel_hi:[1,0]
	s_nop 0
	v_rcp_f32_e32 v7, v2
	s_nop 0
	v_mul_f32_e32 v2, v19, v7
	v_rcp_f32_e32 v3, v3
	s_nop 0
	v_mul_f32_e32 v3, v4, v3
	v_mul_f32_e32 v7, v2, v3
	v_mul_f32_e32 v2, 0xbfb8aa3b, v9
	v_exp_f32_e32 v3, v2
	v_mul_f32_e32 v2, 0xbfb8aa3b, v18
	v_exp_f32_e32 v2, v2
	s_nop 0
	v_pk_add_f32 v[2:3], v[2:3], 1.0 op_sel_hi:[1,0]
	s_nop 0
	v_rcp_f32_e32 v4, v2
	s_nop 0
	v_mul_f32_e32 v2, v18, v4
	v_readlane_b32 s0, v254, 32
	s_add_i32 s24, s24, s0
	s_cmpk_lt_i32 s24, 0x100
	v_rcp_f32_e32 v3, v3
	s_nop 0
	v_mul_f32_e32 v3, v5, v3
	v_mul_f32_e32 v5, v2, v3
	v_cvt_pk_bf16_f32 v4, v14, v6
	v_cvt_pk_bf16_f32 v5, v7, v5
	v_lshlrev_b64 v[6:7], 11, v[38:39]
	v_lshl_add_u64 v[6:7], s[10:11], 0, v[6:7]
	v_lshl_add_u64 v[6:7], v[6:7], 0, s[52:53]
	v_lshl_add_u64 v[6:7], v[6:7], 0, v[0:1]
	v_cvt_pk_bf16_f32 v2, v10, v11
	v_cvt_pk_bf16_f32 v3, v12, v13
	global_store_dwordx4 v[6:7], v[2:5], off offset:1152
	s_cbranch_scc0 .LBB0_221

; DI unsigned pack2(float a, float b) { unsigned r; asm("v_cvt_pk_bf16_f32 %0, %1, %2\n\ts_nop 1" : "=v"(r) : "v"(a), "v"(b)); return r; }
; DI float lo2f(unsigned u) { return __uint_as_float(u << 16); }
; DI float hi2f(unsigned u) { return __uint_as_float(u & 0xffff0000u); }
; DI float silu(float x) { return x / (1.f + __expf(-x)); }
; template <int DQK, bool WIN>
; DI void attn_item(const u16* __restrict__ Qb, int ldq, const u16* __restrict__ Kb, int ldk, const u16* __restrict__ Vtb, int qb,
;                   float qscale, float sink2, const u16* __restrict__ zb, int ldz, u16* __restrict__ ob, int ldo, u16* lds) {
;     ...
;   float lt = lsum + __shfl_xor(lsum, 32);
;   float inv = 1.f / lt;
;   u32x2 zr[8];
; #pragma unroll
;   for (int e = 0; e < 8; ++e) zr[e] = *(const u32x2*)(zb + (size_t)qrow * ldz + (e >> 2) * 32 + 8 * (e & 3) + 4 * hh);
; #pragma unroll
;   for (int vb = 0; vb < 2; ++vb)
; #pragma unroll
;     for (int g4 = 0; g4 < 4; ++g4) {
;       int vd0 = vb * 32 + 8 * g4 + 4 * hh;
;       u32x2 z = zr[vb * 4 + g4];
;       float a0 = o[vb][4 * g4 + 0] * inv * silu(lo2f(z.x));
;       float a1 = o[vb][4 * g4 + 1] * inv * silu(hi2f(z.x));
;       float a2 = o[vb][4 * g4 + 2] * inv * silu(lo2f(z.y));
;       float a3 = o[vb][4 * g4 + 3] * inv * silu(hi2f(z.y));
;       u32x2 ov; ov.x = pack2(a0, a1); ov.y = pack2(a2, a3);
;       *(u32x2*)(ob + (size_t)qrow * ldo + vd0) = ov;
;     }
.LBB0_229:
	s_lshl_b32 s1, s28, 11
	s_add_u32 s8, s14, s1
	s_mul_i32 s0, s28, 0x1540
	s_addc_u32 s9, s15, 0
	s_add_u32 s0, s12, s0
	v_and_b32_e32 v34, 64, v172
	s_addc_u32 s1, s13, 0
	s_lshl_b32 s20, s27, 7
	v_xor_b32_e32 v0, 32, v172
	v_add_u32_e32 v34, 64, v34
	s_add_u32 s0, s0, s20
	v_cmp_lt_i32_e32 vcc, v0, v34
	s_addc_u32 s1, s1, 0
	v_mov_b64_e32 v[34:35], s[0:1]
	v_cndmask_b32_e32 v0, v172, v0, vcc
	v_lshlrev_b32_e32 v0, 2, v0
	ds_bpermute_b32 v162, v0, v142
	v_mad_i64_i32 v[34:35], s[0:1], v130, s60, v[34:35]
	v_lshlrev_b32_e32 v0, 1, v146
	v_lshl_add_u64 v[34:35], v[34:35], 0, v[0:1]
	global_load_dwordx2 v[50:51], v[34:35], off offset:2368
	global_load_dwordx2 v[46:47], v[34:35], off offset:2384
	global_load_dwordx2 v[44:45], v[34:35], off offset:2400
	global_load_dwordx2 v[42:43], v[34:35], off offset:2416
	global_load_dwordx2 v[40:41], v[34:35], off offset:2432
	global_load_dwordx2 v[38:39], v[34:35], off offset:2448
	global_load_dwordx2 v[36:37], v[34:35], off offset:2464
	s_nop 0
	global_load_dwordx2 v[34:35], v[34:35], off offset:2480
	s_add_u32 s8, s8, s20
	s_addc_u32 s9, s9, 0
	v_lshlrev_b64 v[48:49], 11, v[130:131]
	v_lshl_add_u64 v[48:49], s[8:9], 0, v[48:49]
	s_add_i32 s26, s26, s71
	s_cmpk_gt_i32 s26, 0x3ff
	s_waitcnt vmcnt(7)
	v_lshlrev_b32_e32 v52, 16, v50
	v_mul_f32_e32 v53, 0xbfb8aa3b, v52
	v_exp_f32_e32 v53, v53
	v_and_b32_e32 v50, 0xffff0000, v50
	v_add_f32_e32 v53, 1.0, v53
	v_rcp_f32_e32 v54, v53
	s_nop 0
	v_mul_f32_e32 v54, v52, v54
	v_mul_f32_e32 v52, 0xbfb8aa3b, v50
	v_exp_f32_e32 v52, v52
	s_nop 0
	v_add_f32_e32 v52, 1.0, v52
	v_rcp_f32_e32 v53, v52
	s_nop 0
	v_mul_f32_e32 v55, v50, v53
	v_lshlrev_b32_e32 v50, 16, v51
	v_mul_f32_e32 v52, 0xbfb8aa3b, v50
	v_exp_f32_e32 v143, v52
	s_waitcnt lgkmcnt(0)
	v_pk_add_f32 v[52:53], v[142:143], v[162:163]
	s_nop 0
	v_rcp_f32_e32 v56, v53
	s_nop 0
	v_mul_f32_e32 v53, v50, v56
	v_rcp_f32_e32 v50, v52
	s_nop 0
	v_mul_f32_e32 v20, v20, v50
	v_mul_f32_e32 v52, v20, v53
	v_mul_f32_e32 v20, v21, v50
	v_and_b32_e32 v21, 0xffff0000, v51
	v_mul_f32_e32 v51, 0xbfb8aa3b, v21
	v_exp_f32_e32 v51, v51
	v_mul_f32_e32 v18, v18, v50
	v_mul_f32_e32 v18, v18, v54
	v_mul_f32_e32 v19, v19, v50
	v_add_f32_e32 v51, 1.0, v51
	v_mul_f32_e32 v19, v19, v55
	v_rcp_f32_e32 v53, v51
	s_nop 0
	v_mul_f32_e32 v21, v21, v53
	v_mul_f32_e32 v21, v20, v21
	v_cvt_pk_bf16_f32 v20, v18, v19
	v_lshl_add_u64 v[18:19], v[48:49], 0, v[0:1]
	v_cvt_pk_bf16_f32 v21, v52, v21
	global_store_dwordx2 v[18:19], v[20:21], off offset:512
	s_waitcnt vmcnt(7)
	v_lshlrev_b32_e32 v20, 16, v46
	v_mul_f32_e32 v21, 0xbfb8aa3b, v20
	v_exp_f32_e32 v21, v21
	v_mul_f32_e32 v0, v22, v50
	v_add_f32_e32 v21, 1.0, v21
	v_rcp_f32_e32 v22, v21
	s_nop 0
	v_mul_f32_e32 v20, v20, v22
	v_and_b32_e32 v21, 0xffff0000, v46
	v_mul_f32_e32 v22, 0xbfb8aa3b, v21
	v_exp_f32_e32 v22, v22
	v_mul_f32_e32 v0, v0, v20
	v_mul_f32_e32 v20, v23, v50
	v_add_f32_e32 v22, 1.0, v22
	v_rcp_f32_e32 v23, v22
	s_nop 0
	v_mul_f32_e32 v21, v21, v23
	v_lshlrev_b32_e32 v22, 16, v47
	v_mul_f32_e32 v23, 0xbfb8aa3b, v22
	v_exp_f32_e32 v23, v23
	v_mul_f32_e32 v20, v20, v21
	v_mul_f32_e32 v21, v24, v50
	v_cvt_pk_bf16_f32 v20, v0, v20
	v_add_f32_e32 v23, 1.0, v23
	v_mul_f32_e32 v0, v26, v50
	v_rcp_f32_e32 v24, v23
	s_nop 0
	v_mul_f32_e32 v22, v22, v24
	v_and_b32_e32 v23, 0xffff0000, v47
	v_mul_f32_e32 v24, 0xbfb8aa3b, v23
	v_exp_f32_e32 v24, v24
	v_mul_f32_e32 v21, v21, v22
	v_mul_f32_e32 v22, v25, v50
	v_add_f32_e32 v24, 1.0, v24
	v_rcp_f32_e32 v25, v24
	s_nop 0
	v_mul_f32_e32 v23, v23, v25
	v_mul_f32_e32 v22, v22, v23
	v_cvt_pk_bf16_f32 v21, v21, v22
	global_store_dwordx2 v[18:19], v[20:21], off offset:528
	s_waitcnt vmcnt(7)
	v_lshlrev_b32_e32 v20, 16, v44
	v_mul_f32_e32 v21, 0xbfb8aa3b, v20
	v_exp_f32_e32 v21, v21
	s_nop 0
	v_add_f32_e32 v21, 1.0, v21
	v_rcp_f32_e32 v22, v21
	s_nop 0
	v_mul_f32_e32 v20, v20, v22
	v_and_b32_e32 v21, 0xffff0000, v44
	v_mul_f32_e32 v22, 0xbfb8aa3b, v21
	v_exp_f32_e32 v22, v22
	v_mul_f32_e32 v0, v0, v20
	v_mul_f32_e32 v20, v27, v50
	v_add_f32_e32 v22, 1.0, v22
	v_rcp_f32_e32 v23, v22
	s_nop 0
	v_mul_f32_e32 v21, v21, v23
	v_lshlrev_b32_e32 v22, 16, v45
	v_mul_f32_e32 v23, 0xbfb8aa3b, v22
	v_exp_f32_e32 v23, v23
	v_mul_f32_e32 v20, v20, v21
	v_mul_f32_e32 v21, v28, v50
	v_cvt_pk_bf16_f32 v20, v0, v20
	v_add_f32_e32 v23, 1.0, v23
	v_mul_f32_e32 v0, v30, v50
	v_rcp_f32_e32 v24, v23
	s_nop 0
	v_mul_f32_e32 v22, v22, v24
	v_and_b32_e32 v23, 0xffff0000, v45
	v_mul_f32_e32 v24, 0xbfb8aa3b, v23
	v_exp_f32_e32 v24, v24
	v_mul_f32_e32 v21, v21, v22
	v_mul_f32_e32 v22, v29, v50
	v_add_f32_e32 v24, 1.0, v24
	v_rcp_f32_e32 v25, v24
	s_nop 0
	v_mul_f32_e32 v23, v23, v25
	v_mul_f32_e32 v22, v22, v23
	v_cvt_pk_bf16_f32 v21, v21, v22
	global_store_dwordx2 v[18:19], v[20:21], off offset:544
	s_waitcnt vmcnt(7)
; DI unsigned pack2(float a, float b) { unsigned r; asm("v_cvt_pk_bf16_f32 %0, %1, %2\n\ts_nop 1" : "=v"(r) : "v"(a), "v"(b)); return r; }
; DI float lo2f(unsigned u) { return __uint_as_float(u << 16); }
; DI float hi2f(unsigned u) { return __uint_as_float(u & 0xffff0000u); }
; DI float silu(float x) { return x / (1.f + __expf(-x)); }
; template <int DQK, bool WIN>
; DI void attn_item(const u16* __restrict__ Qb, int ldq, const u16* __restrict__ Kb, int ldk, const u16* __restrict__ Vtb, int qb,
;                   float qscale, float sink2, const u16* __restrict__ zb, int ldz, u16* __restrict__ ob, int ldo, u16* lds) {
;     ...
;   for (int e = 0; e < 8; ++e) zr[e] = *(const u32x2*)(zb + (size_t)qrow * ldz + (e >> 2) * 32 + 8 * (e & 3) + 4 * hh);
; #pragma unroll
;   for (int vb = 0; vb < 2; ++vb)
; #pragma unroll
;     for (int g4 = 0; g4 < 4; ++g4) {
;       int vd0 = vb * 32 + 8 * g4 + 4 * hh;
;       u32x2 z = zr[vb * 4 + g4];
;       float a0 = o[vb][4 * g4 + 0] * inv * silu(lo2f(z.x));
;       float a1 = o[vb][4 * g4 + 1] * inv * silu(hi2f(z.x));
;       float a2 = o[vb][4 * g4 + 2] * inv * silu(lo2f(z.y));
;       float a3 = o[vb][4 * g4 + 3] * inv * silu(hi2f(z.y));
;       u32x2 ov; ov.x = pack2(a0, a1); ov.y = pack2(a2, a3);
;       *(u32x2*)(ob + (size_t)qrow * ldo + vd0) = ov;
;     }
	v_lshlrev_b32_e32 v20, 16, v42
	v_mul_f32_e32 v21, 0xbfb8aa3b, v20
	v_exp_f32_e32 v21, v21
	s_nop 0
	v_add_f32_e32 v21, 1.0, v21
	v_rcp_f32_e32 v22, v21
	s_nop 0
	v_mul_f32_e32 v20, v20, v22
	v_and_b32_e32 v21, 0xffff0000, v42
	v_mul_f32_e32 v22, 0xbfb8aa3b, v21
	v_exp_f32_e32 v22, v22
	v_mul_f32_e32 v0, v0, v20
	v_mul_f32_e32 v20, v31, v50
	v_add_f32_e32 v22, 1.0, v22
	v_rcp_f32_e32 v23, v22
	s_nop 0
	v_mul_f32_e32 v21, v21, v23
	v_lshlrev_b32_e32 v22, 16, v43
	v_mul_f32_e32 v23, 0xbfb8aa3b, v22
	v_exp_f32_e32 v23, v23
	v_mul_f32_e32 v20, v20, v21
	v_mul_f32_e32 v21, v32, v50
	v_cvt_pk_bf16_f32 v20, v0, v20
	v_add_f32_e32 v23, 1.0, v23
	v_mul_f32_e32 v0, v2, v50
	s_waitcnt vmcnt(6)
	v_lshlrev_b32_e32 v2, 16, v40
	v_rcp_f32_e32 v24, v23
	s_nop 0
	v_mul_f32_e32 v22, v22, v24
	v_and_b32_e32 v23, 0xffff0000, v43
	v_mul_f32_e32 v24, 0xbfb8aa3b, v23
	v_exp_f32_e32 v24, v24
	v_mul_f32_e32 v21, v21, v22
	v_mul_f32_e32 v22, v33, v50
	v_add_f32_e32 v24, 1.0, v24
	v_rcp_f32_e32 v25, v24
	s_nop 0
	v_mul_f32_e32 v23, v23, v25
	v_mul_f32_e32 v22, v22, v23
	v_cvt_pk_bf16_f32 v21, v21, v22
	global_store_dwordx2 v[18:19], v[20:21], off offset:560
	v_mul_f32_e32 v20, 0xbfb8aa3b, v2
	v_exp_f32_e32 v20, v20
	s_nop 0
	v_add_f32_e32 v20, 1.0, v20
	v_rcp_f32_e32 v21, v20
	s_nop 0
	v_mul_f32_e32 v2, v2, v21
	v_mul_f32_e32 v0, v0, v2
	v_mul_f32_e32 v2, v3, v50
	v_and_b32_e32 v3, 0xffff0000, v40
	v_mul_f32_e32 v20, 0xbfb8aa3b, v3
	v_exp_f32_e32 v20, v20
	s_nop 0
	v_add_f32_e32 v20, 1.0, v20
	v_rcp_f32_e32 v21, v20
	s_nop 0
	v_mul_f32_e32 v3, v3, v21
	v_mul_f32_e32 v2, v2, v3
	v_mul_f32_e32 v3, v4, v50
	v_lshlrev_b32_e32 v4, 16, v41
	v_mul_f32_e32 v20, 0xbfb8aa3b, v4
	v_exp_f32_e32 v20, v20
	v_cvt_pk_bf16_f32 v2, v0, v2
	v_mul_f32_e32 v0, v6, v50
	v_add_f32_e32 v20, 1.0, v20
	v_rcp_f32_e32 v21, v20
	s_nop 0
	v_mul_f32_e32 v4, v4, v21
	v_mul_f32_e32 v3, v3, v4
	v_mul_f32_e32 v4, v5, v50
	v_and_b32_e32 v5, 0xffff0000, v41
	v_mul_f32_e32 v20, 0xbfb8aa3b, v5
	v_exp_f32_e32 v20, v20
	s_nop 0
	v_add_f32_e32 v20, 1.0, v20
	v_rcp_f32_e32 v21, v20
	s_nop 0
	v_mul_f32_e32 v5, v5, v21
	v_mul_f32_e32 v4, v4, v5
	v_cvt_pk_bf16_f32 v3, v3, v4
	global_store_dwordx2 v[18:19], v[2:3], off offset:576
	s_waitcnt vmcnt(7)
	v_lshlrev_b32_e32 v2, 16, v38
	v_mul_f32_e32 v3, 0xbfb8aa3b, v2
	v_exp_f32_e32 v3, v3
	s_nop 0
	v_add_f32_e32 v3, 1.0, v3
	v_rcp_f32_e32 v4, v3
	s_nop 0
	v_mul_f32_e32 v2, v2, v4
	v_and_b32_e32 v3, 0xffff0000, v38
	v_mul_f32_e32 v4, 0xbfb8aa3b, v3
	v_exp_f32_e32 v4, v4
	v_mul_f32_e32 v0, v0, v2
	v_mul_f32_e32 v2, v7, v50
	v_add_f32_e32 v4, 1.0, v4
	v_rcp_f32_e32 v5, v4
	s_nop 0
	v_mul_f32_e32 v3, v3, v5
	v_lshlrev_b32_e32 v4, 16, v39
	v_mul_f32_e32 v5, 0xbfb8aa3b, v4
	v_exp_f32_e32 v5, v5
	v_mul_f32_e32 v2, v2, v3
	v_mul_f32_e32 v3, v8, v50
	v_cvt_pk_bf16_f32 v2, v0, v2
	v_add_f32_e32 v5, 1.0, v5
	v_mul_f32_e32 v0, v10, v50
	v_rcp_f32_e32 v6, v5
	s_nop 0
	v_mul_f32_e32 v4, v4, v6
	v_and_b32_e32 v5, 0xffff0000, v39
	v_mul_f32_e32 v6, 0xbfb8aa3b, v5
	v_exp_f32_e32 v6, v6
	v_mul_f32_e32 v3, v3, v4
	v_mul_f32_e32 v4, v9, v50
	v_add_f32_e32 v6, 1.0, v6
	v_rcp_f32_e32 v7, v6
	s_nop 0
	v_mul_f32_e32 v5, v5, v7
	v_mul_f32_e32 v4, v4, v5
	v_cvt_pk_bf16_f32 v3, v3, v4
	global_store_dwordx2 v[18:19], v[2:3], off offset:592
	s_waitcnt vmcnt(7)
	v_lshlrev_b32_e32 v2, 16, v36
	v_mul_f32_e32 v3, 0xbfb8aa3b, v2
	v_exp_f32_e32 v3, v3
	s_nop 0
	v_add_f32_e32 v3, 1.0, v3
	v_rcp_f32_e32 v4, v3
	s_nop 0
	v_mul_f32_e32 v2, v2, v4
	v_and_b32_e32 v3, 0xffff0000, v36
	v_mul_f32_e32 v4, 0xbfb8aa3b, v3
	v_exp_f32_e32 v4, v4
	v_mul_f32_e32 v0, v0, v2
	v_mul_f32_e32 v2, v11, v50
	v_add_f32_e32 v4, 1.0, v4
	v_rcp_f32_e32 v5, v4
	s_nop 0
	v_mul_f32_e32 v3, v3, v5
	v_lshlrev_b32_e32 v4, 16, v37
	v_mul_f32_e32 v5, 0xbfb8aa3b, v4
	v_exp_f32_e32 v5, v5
	v_mul_f32_e32 v2, v2, v3
	v_mul_f32_e32 v3, v12, v50
	v_cvt_pk_bf16_f32 v2, v0, v2
	v_add_f32_e32 v5, 1.0, v5
	v_mul_f32_e32 v0, v14, v50
	v_rcp_f32_e32 v6, v5
	s_nop 0
	v_mul_f32_e32 v4, v4, v6
	v_and_b32_e32 v5, 0xffff0000, v37
	v_mul_f32_e32 v6, 0xbfb8aa3b, v5
	v_exp_f32_e32 v6, v6
	v_mul_f32_e32 v3, v3, v4
	v_mul_f32_e32 v4, v13, v50
	v_add_f32_e32 v6, 1.0, v6
	v_rcp_f32_e32 v7, v6
	s_nop 0
	v_mul_f32_e32 v5, v5, v7
	v_mul_f32_e32 v4, v4, v5
	v_cvt_pk_bf16_f32 v3, v3, v4
	global_store_dwordx2 v[18:19], v[2:3], off offset:608
	s_waitcnt vmcnt(7)
	v_lshlrev_b32_e32 v2, 16, v34
	v_mul_f32_e32 v3, 0xbfb8aa3b, v2
	v_exp_f32_e32 v3, v3
	s_nop 0
	v_add_f32_e32 v3, 1.0, v3
	v_rcp_f32_e32 v4, v3
	s_nop 0
	v_mul_f32_e32 v2, v2, v4
	v_and_b32_e32 v3, 0xffff0000, v34
	v_mul_f32_e32 v4, 0xbfb8aa3b, v3
	v_exp_f32_e32 v4, v4
	v_mul_f32_e32 v0, v0, v2
	v_mul_f32_e32 v2, v15, v50
	v_add_f32_e32 v4, 1.0, v4
	v_rcp_f32_e32 v5, v4
	s_nop 0
	v_mul_f32_e32 v3, v3, v5
	v_lshlrev_b32_e32 v4, 16, v35
	v_mul_f32_e32 v5, 0xbfb8aa3b, v4
	v_exp_f32_e32 v5, v5
	v_mul_f32_e32 v2, v2, v3
	v_mul_f32_e32 v3, v16, v50
	v_cvt_pk_bf16_f32 v2, v0, v2
	v_add_f32_e32 v5, 1.0, v5
	v_rcp_f32_e32 v6, v5
	s_nop 0
	v_mul_f32_e32 v4, v4, v6
	v_and_b32_e32 v5, 0xffff0000, v35
	v_mul_f32_e32 v6, 0xbfb8aa3b, v5
	v_exp_f32_e32 v6, v6
	v_mul_f32_e32 v3, v3, v4
	v_mul_f32_e32 v4, v17, v50
	v_add_f32_e32 v6, 1.0, v6
	v_rcp_f32_e32 v7, v6
	s_nop 0
	v_mul_f32_e32 v5, v5, v7
	v_mul_f32_e32 v4, v4, v5
	v_cvt_pk_bf16_f32 v3, v3, v4
	global_store_dwordx2 v[18:19], v[2:3], off offset:624
	s_cbranch_scc1 .LBB0_263

; DI unsigned pack2(float a, float b) { unsigned r; asm("v_cvt_pk_bf16_f32 %0, %1, %2\n\ts_nop 1" : "=v"(r) : "v"(a), "v"(b)); return r; }
; #define MFMA32(a, b, c) __builtin_amdgcn_mfma_f32_32x32x16_bf16((a), (b), (c), 0, 0, 0)
; template <int DQK, bool WIN>
; DI void attn_item(const u16* __restrict__ Qb, int ldq, const u16* __restrict__ Kb, int ldk, const u16* __restrict__ Vtb, int qb,
;                   float qscale, float sink2, const u16* __restrict__ zb, int ldz, u16* __restrict__ ob, int ldo, u16* lds) {
;     ...
;       const float nb = -mn * qscale;
;       float ps = 0.f;
; #pragma unroll
;       for (int kb = 0; kb < 2; ++kb)
; #pragma unroll
;         for (int i = 0; i < 16; ++i) { float pv = __builtin_amdgcn_exp2f(fmaf(st[kb][i], qscale, nb)); st[kb][i] = pv; ps += pv; }
;       lsum += ps;
; #pragma unroll
;       for (int kb = 0; kb < 2; ++kb)
; #pragma unroll
;         for (int s2 = 0; s2 < 2; ++s2) {
;           union { bf16x8 v; unsigned u[4]; } pf;
; #pragma unroll
;           for (int j = 0; j < 4; ++j) pf.u[j] = pack2(st[kb][8 * s2 + 2 * j], st[kb][8 * s2 + 2 * j + 1]);
; #pragma unroll
;           for (int vb = 0; vb < 2; ++vb) {
;             const bf16x8 vf = *(const bf16x8*)(vs + (vb * 32 + r) * 72 + (kb * 2 + s2) * 16 + hh * 8);
;             o[vb] = MFMA32(vf, pf.v, o[vb]);
;           }
;         }
.LBB0_237:
	ds_read_b128 v[220:223], v156 offset:13312
	ds_read_b128 v[224:227], v156 offset:13344
	ds_read_b128 v[228:231], v156 offset:17920
	ds_read_b128 v[232:235], v156 offset:17952
	ds_read_b128 v[236:239], v156 offset:13376
	ds_read_b128 v[240:243], v156 offset:17984
	ds_read_b128 v[244:247], v156 offset:13408
	ds_read_b128 v[248:251], v156 offset:18016
	v_mul_f32_e32 v206, 0xbe16c740, v158
	v_fmamk_f32 v159, v159, 0x3e16c740, v206
	v_exp_f32_e32 v159, v159
	v_fmamk_f32 v0, v0, 0x3e16c740, v206
	v_exp_f32_e32 v208, v0
	v_fmamk_f32 v164, v164, 0x3e16c740, v206
	v_add_f32_e32 v207, 0, v159
	v_fmamk_f32 v161, v161, 0x3e16c740, v206
	v_add_f32_e32 v0, v208, v207
	v_exp_f32_e32 v207, v164
	v_fmamk_f32 v164, v165, 0x3e16c740, v206
	v_exp_f32_e32 v209, v164
	v_fmamk_f32 v164, v166, 0x3e16c740, v206
	v_exp_f32_e32 v210, v164
	v_fmamk_f32 v164, v205, 0x3e16c740, v206
	v_exp_f32_e32 v205, v164
	v_fmamk_f32 v164, v203, 0x3e16c740, v206
	v_exp_f32_e32 v203, v164
	v_fmamk_f32 v164, v204, 0x3e16c740, v206
	v_exp_f32_e32 v204, v164
	v_fmamk_f32 v164, v201, 0x3e16c740, v206
	v_exp_f32_e32 v201, v164
	v_fmamk_f32 v164, v202, 0x3e16c740, v206
	v_exp_f32_e32 v202, v164
	v_fmamk_f32 v164, v199, 0x3e16c740, v206
	v_exp_f32_e32 v199, v164
	v_fmamk_f32 v164, v200, 0x3e16c740, v206
	v_exp_f32_e32 v200, v164
	v_fmamk_f32 v164, v197, 0x3e16c740, v206
	v_exp_f32_e32 v197, v164
	v_fmamk_f32 v164, v198, 0x3e16c740, v206
	v_exp_f32_e32 v198, v164
	v_fmamk_f32 v164, v195, 0x3e16c740, v206
	v_exp_f32_e32 v195, v164
	v_fmamk_f32 v164, v194, 0x3e16c740, v206
	v_exp_f32_e32 v194, v164
	v_fmamk_f32 v164, v193, 0x3e16c740, v206
	v_exp_f32_e32 v193, v164
	v_fmamk_f32 v164, v192, 0x3e16c740, v206
	v_exp_f32_e32 v192, v164
	v_fmamk_f32 v164, v167, 0x3e16c740, v206
	v_exp_f32_e32 v211, v164
	v_fmamk_f32 v164, v182, 0x3e16c740, v206
	v_exp_f32_e32 v212, v164
	v_fmamk_f32 v164, v183, 0x3e16c740, v206
	v_exp_f32_e32 v213, v164
	v_fmamk_f32 v164, v184, 0x3e16c740, v206
	v_exp_f32_e32 v214, v164
	v_fmamk_f32 v164, v185, 0x3e16c740, v206
	v_exp_f32_e32 v215, v164
	v_fmamk_f32 v164, v186, 0x3e16c740, v206
	v_exp_f32_e32 v216, v164
	v_fmamk_f32 v164, v187, 0x3e16c740, v206
	v_exp_f32_e32 v217, v164
	v_fmamk_f32 v164, v188, 0x3e16c740, v206
	v_exp_f32_e32 v218, v164
	v_fmamk_f32 v164, v189, 0x3e16c740, v206
	v_fmamk_f32 v160, v160, 0x3e16c740, v206
	v_fmamk_f32 v162, v162, 0x3e16c740, v206
	v_exp_f32_e32 v219, v164
	v_fmamk_f32 v164, v190, 0x3e16c740, v206
	v_exp_f32_e32 v161, v161
	v_exp_f32_e32 v160, v160
	v_exp_f32_e32 v162, v162
	v_exp_f32_e32 v190, v164
	v_cvt_pk_bf16_f32 v164, v159, v208
	v_cvt_pk_bf16_f32 v165, v161, v160
	v_cvt_pk_bf16_f32 v166, v207, v162
	v_cvt_pk_bf16_f32 v167, v209, v210
	v_add_f32_e32 v0, v161, v0
	s_waitcnt lgkmcnt(7)
	v_mfma_f32_32x32x16_bf16 v[34:49], v[220:223], v[164:167], v[34:49]
	v_add_f32_e32 v0, v160, v0
	v_add_f32_e32 v0, v207, v0
	v_add_f32_e32 v0, v162, v0
	v_add_f32_e32 v0, v209, v0
	v_add_f32_e32 v0, v210, v0
	v_add_f32_e32 v0, v205, v0
	s_waitcnt lgkmcnt(5)
	v_mfma_f32_32x32x16_bf16 v[50:65], v[228:231], v[164:167], v[50:65]
	v_cvt_pk_bf16_f32 v164, v205, v203
	v_cvt_pk_bf16_f32 v165, v204, v201
	v_cvt_pk_bf16_f32 v166, v202, v199
	v_cvt_pk_bf16_f32 v167, v200, v197
	v_add_f32_e32 v0, v203, v0
	v_add_f32_e32 v0, v204, v0
	s_waitcnt lgkmcnt(4)
	v_mfma_f32_32x32x16_bf16 v[50:65], v[232:235], v[164:167], v[50:65]
	v_add_f32_e32 v0, v201, v0
	v_add_f32_e32 v0, v202, v0
	v_add_f32_e32 v0, v199, v0
	v_add_f32_e32 v0, v200, v0
	v_add_f32_e32 v0, v197, v0
	v_fmac_f32_e32 v206, 0x3e16c740, v191
	v_mfma_f32_32x32x16_bf16 v[34:49], v[224:227], v[164:167], v[34:49]
	v_cvt_pk_bf16_f32 v164, v198, v195
	v_cvt_pk_bf16_f32 v165, v194, v193
	v_cvt_pk_bf16_f32 v166, v192, v211
	v_cvt_pk_bf16_f32 v167, v212, v213
	v_add_f32_e32 v0, v198, v0
	v_exp_f32_e32 v191, v206
	v_add_f32_e32 v0, v195, v0
	s_waitcnt lgkmcnt(3)
	v_mfma_f32_32x32x16_bf16 v[34:49], v[236:239], v[164:167], v[34:49]
	v_add_f32_e32 v0, v194, v0
	v_add_f32_e32 v0, v193, v0
	v_add_f32_e32 v0, v192, v0
	v_add_f32_e32 v0, v211, v0
	v_add_f32_e32 v0, v212, v0
	v_add_f32_e32 v0, v213, v0
	s_waitcnt lgkmcnt(2)
	v_mfma_f32_32x32x16_bf16 v[50:65], v[240:243], v[164:167], v[50:65]
	v_cvt_pk_bf16_f32 v164, v214, v215
	v_cvt_pk_bf16_f32 v165, v216, v217
	v_cvt_pk_bf16_f32 v166, v218, v219
	v_cvt_pk_bf16_f32 v167, v190, v191
	v_add_f32_e32 v0, v214, v0
	v_add_f32_e32 v0, v215, v0
	s_waitcnt lgkmcnt(1)
	v_mfma_f32_32x32x16_bf16 v[34:49], v[244:247], v[164:167], v[34:49]
	v_add_f32_e32 v0, v216, v0
	v_add_f32_e32 v0, v217, v0
	v_add_f32_e32 v0, v218, v0
	v_add_f32_e32 v0, v219, v0
	v_add_f32_e32 v0, v190, v0
	v_add_f32_e32 v0, v191, v0
	s_waitcnt lgkmcnt(0)
	v_mfma_f32_32x32x16_bf16 v[50:65], v[248:251], v[164:167], v[50:65]
	v_add_f32_e32 v0, v0, v196

; DI unsigned pack2(float a, float b) { unsigned r; asm("v_cvt_pk_bf16_f32 %0, %1, %2\n\ts_nop 1" : "=v"(r) : "v"(a), "v"(b)); return r; }
; #define MFMA32(a, b, c) __builtin_amdgcn_mfma_f32_32x32x16_bf16((a), (b), (c), 0, 0, 0)
; template <int DQK, bool WIN>
; DI void attn_item(const u16* __restrict__ Qb, int ldq, const u16* __restrict__ Kb, int ldk, const u16* __restrict__ Vtb, int qb,
;                   float qscale, float sink2, const u16* __restrict__ zb, int ldz, u16* __restrict__ ob, int ldo, u16* lds) {
;     ...
;       const float nb = -mn * qscale;
;       float ps = 0.f;
; #pragma unroll
;       for (int kb = 0; kb < 2; ++kb)
; #pragma unroll
;         for (int i = 0; i < 16; ++i) { float pv = __builtin_amdgcn_exp2f(fmaf(st[kb][i], qscale, nb)); st[kb][i] = pv; ps += pv; }
;       lsum += ps;
; #pragma unroll
;       for (int kb = 0; kb < 2; ++kb)
; #pragma unroll
;         for (int s2 = 0; s2 < 2; ++s2) {
;           union { bf16x8 v; unsigned u[4]; } pf;
; #pragma unroll
;           for (int j = 0; j < 4; ++j) pf.u[j] = pack2(st[kb][8 * s2 + 2 * j], st[kb][8 * s2 + 2 * j + 1]);
; #pragma unroll
;           for (int vb = 0; vb < 2; ++vb) {
;             const bf16x8 vf = *(const bf16x8*)(vs + (vb * 32 + r) * 72 + (kb * 2 + s2) * 16 + hh * 8);
;             o[vb] = MFMA32(vf, pf.v, o[vb]);
;           }
;         }
.LBB0_243:
	ds_read_b128 v[186:189], v156 offset:13312
	ds_read_b128 v[190:193], v156 offset:13344
	ds_read_b128 v[194:197], v156 offset:17920
	ds_read_b128 v[198:201], v156 offset:17952
	ds_read_b128 v[202:205], v156 offset:13376
	ds_read_b128 v[206:209], v156 offset:17984
	ds_read_b128 v[210:213], v156 offset:13408
	ds_read_b128 v[214:217], v156 offset:18016
	v_mul_f32_e32 v157, 0xbe16c740, v0
	v_fmamk_f32 v50, v50, 0x3e16c740, v157
	v_exp_f32_e32 v50, v50
	v_fmamk_f32 v51, v51, 0x3e16c740, v157
	v_exp_f32_e32 v51, v51
	v_fmamk_f32 v52, v52, 0x3e16c740, v157
	v_exp_f32_e32 v52, v52
	v_fmamk_f32 v53, v53, 0x3e16c740, v157
	v_exp_f32_e32 v53, v53
	v_fmamk_f32 v54, v54, 0x3e16c740, v157
	v_add_f32_e32 v158, 0, v50
	v_exp_f32_e32 v54, v54
	v_fmamk_f32 v55, v55, 0x3e16c740, v157
	v_add_f32_e32 v158, v51, v158
	v_exp_f32_e32 v55, v55
	v_fmamk_f32 v56, v56, 0x3e16c740, v157
	v_add_f32_e32 v158, v52, v158
	v_exp_f32_e32 v56, v56
	v_fmamk_f32 v57, v57, 0x3e16c740, v157
	v_add_f32_e32 v158, v53, v158
	v_exp_f32_e32 v57, v57
	v_fmamk_f32 v58, v58, 0x3e16c740, v157
	v_add_f32_e32 v158, v54, v158
	v_exp_f32_e32 v58, v58
	v_fmamk_f32 v59, v59, 0x3e16c740, v157
	v_add_f32_e32 v158, v55, v158
	v_exp_f32_e32 v59, v59
	v_fmamk_f32 v60, v60, 0x3e16c740, v157
	v_add_f32_e32 v158, v56, v158
	v_exp_f32_e32 v60, v60
	v_fmamk_f32 v61, v61, 0x3e16c740, v157
	v_add_f32_e32 v158, v57, v158
	v_exp_f32_e32 v61, v61
	v_fmamk_f32 v62, v62, 0x3e16c740, v157
	v_add_f32_e32 v158, v58, v158
	v_exp_f32_e32 v62, v62
	v_fmamk_f32 v63, v63, 0x3e16c740, v157
	v_add_f32_e32 v158, v59, v158
	v_exp_f32_e32 v63, v63
	v_fmamk_f32 v64, v64, 0x3e16c740, v157
	v_add_f32_e32 v158, v60, v158
	v_exp_f32_e32 v64, v64
	v_fmamk_f32 v65, v65, 0x3e16c740, v157
	v_add_f32_e32 v158, v61, v158
	v_exp_f32_e32 v65, v65
	v_fmamk_f32 v34, v34, 0x3e16c740, v157
	v_add_f32_e32 v158, v62, v158
	v_exp_f32_e32 v159, v34
	v_add_f32_e32 v158, v63, v158
	v_add_f32_e32 v158, v64, v158
	v_add_f32_e32 v158, v65, v158
	v_fmamk_f32 v35, v35, 0x3e16c740, v157
	v_add_f32_e32 v34, v159, v158
	v_exp_f32_e32 v158, v35
	v_fmamk_f32 v35, v36, 0x3e16c740, v157
	v_exp_f32_e32 v160, v35
	v_fmamk_f32 v35, v37, 0x3e16c740, v157
	v_exp_f32_e32 v161, v35
	v_fmamk_f32 v35, v38, 0x3e16c740, v157
	v_exp_f32_e32 v162, v35
	v_fmamk_f32 v35, v39, 0x3e16c740, v157
	v_add_f32_e32 v34, v158, v34
	v_exp_f32_e32 v164, v35
	v_fmamk_f32 v35, v40, 0x3e16c740, v157
	v_add_f32_e32 v34, v160, v34
	v_exp_f32_e32 v165, v35
	v_fmamk_f32 v35, v41, 0x3e16c740, v157
	v_add_f32_e32 v34, v161, v34
	v_exp_f32_e32 v166, v35
	v_fmamk_f32 v35, v42, 0x3e16c740, v157
	v_add_f32_e32 v34, v162, v34
	v_exp_f32_e32 v167, v35
	v_fmamk_f32 v35, v43, 0x3e16c740, v157
	v_add_f32_e32 v34, v164, v34
	v_exp_f32_e32 v182, v35
	v_fmamk_f32 v35, v44, 0x3e16c740, v157
	v_add_f32_e32 v34, v165, v34
	v_exp_f32_e32 v183, v35
	v_fmamk_f32 v35, v45, 0x3e16c740, v157
	v_add_f32_e32 v34, v166, v34
	v_exp_f32_e32 v184, v35
	v_fmamk_f32 v35, v46, 0x3e16c740, v157
	v_add_f32_e32 v34, v167, v34
	v_exp_f32_e32 v46, v35
	v_fmamk_f32 v35, v47, 0x3e16c740, v157
	v_add_f32_e32 v34, v182, v34
	v_exp_f32_e32 v47, v35
	v_fmamk_f32 v35, v48, 0x3e16c740, v157
	v_add_f32_e32 v34, v183, v34
	v_exp_f32_e32 v48, v35
	v_fmac_f32_e32 v157, 0x3e16c740, v49
	v_add_f32_e32 v34, v184, v34
	v_exp_f32_e32 v49, v157
	v_add_f32_e32 v34, v46, v34
	v_add_f32_e32 v34, v47, v34
	v_add_f32_e32 v34, v48, v34
	v_add_f32_e32 v34, v49, v34
	v_add_f32_e32 v142, v34, v142
	v_cvt_pk_bf16_f32 v34, v50, v51
	v_cvt_pk_bf16_f32 v35, v52, v53
	v_cvt_pk_bf16_f32 v36, v54, v55
	v_cvt_pk_bf16_f32 v37, v56, v57
	v_mov_b32_e32 v157, v0
	s_waitcnt lgkmcnt(7)
	v_mfma_f32_32x32x16_bf16 v[18:33], v[186:189], v[34:37], v[18:33]
	s_waitcnt lgkmcnt(5)
	v_mfma_f32_32x32x16_bf16 v[2:17], v[194:197], v[34:37], v[2:17]
	v_cvt_pk_bf16_f32 v34, v58, v59
	v_cvt_pk_bf16_f32 v35, v60, v61
	v_cvt_pk_bf16_f32 v36, v62, v63
	v_cvt_pk_bf16_f32 v37, v64, v65
	s_waitcnt lgkmcnt(4)
	s_nop 0
	v_mfma_f32_32x32x16_bf16 v[2:17], v[198:201], v[34:37], v[2:17]
	v_mfma_f32_32x32x16_bf16 v[18:33], v[190:193], v[34:37], v[18:33]
	v_cvt_pk_bf16_f32 v34, v159, v158
	v_cvt_pk_bf16_f32 v35, v160, v161
	v_cvt_pk_bf16_f32 v36, v162, v164
	v_cvt_pk_bf16_f32 v37, v165, v166
	s_waitcnt lgkmcnt(3)
	s_nop 0
	v_mfma_f32_32x32x16_bf16 v[18:33], v[202:205], v[34:37], v[18:33]
	s_waitcnt lgkmcnt(2)
	v_mfma_f32_32x32x16_bf16 v[2:17], v[206:209], v[34:37], v[2:17]
	v_cvt_pk_bf16_f32 v34, v167, v182
	v_cvt_pk_bf16_f32 v35, v183, v184
	v_cvt_pk_bf16_f32 v36, v46, v47
	v_cvt_pk_bf16_f32 v37, v48, v49
	s_waitcnt lgkmcnt(1)
	s_nop 0
	v_mfma_f32_32x32x16_bf16 v[18:33], v[210:213], v[34:37], v[18:33]
	s_waitcnt lgkmcnt(0)
	v_mfma_f32_32x32x16_bf16 v[2:17], v[214:217], v[34:37], v[2:17]

; DI unsigned pack2(float a, float b) { unsigned r; asm("v_cvt_pk_bf16_f32 %0, %1, %2\n\ts_nop 1" : "=v"(r) : "v"(a), "v"(b)); return r; }
; #define MFMA32(a, b, c) __builtin_amdgcn_mfma_f32_32x32x16_bf16((a), (b), (c), 0, 0, 0)
; template <int DQK, bool WIN>
; DI void attn_item(const u16* __restrict__ Qb, int ldq, const u16* __restrict__ Kb, int ldk, const u16* __restrict__ Vtb, int qb,
;                   float qscale, float sink2, const u16* __restrict__ zb, int ldz, u16* __restrict__ ob, int ldo, u16* lds) {
;     ...
;       const float nb = -mn * qscale;
;       float ps = 0.f;
; #pragma unroll
;       for (int kb = 0; kb < 2; ++kb)
; #pragma unroll
;         for (int i = 0; i < 16; ++i) { float pv = __builtin_amdgcn_exp2f(fmaf(st[kb][i], qscale, nb)); st[kb][i] = pv; ps += pv; }
;       lsum += ps;
; #pragma unroll
;       for (int kb = 0; kb < 2; ++kb)
; #pragma unroll
;         for (int s2 = 0; s2 < 2; ++s2) {
;           union { bf16x8 v; unsigned u[4]; } pf;
; #pragma unroll
;           for (int j = 0; j < 4; ++j) pf.u[j] = pack2(st[kb][8 * s2 + 2 * j], st[kb][8 * s2 + 2 * j + 1]);
; #pragma unroll
;           for (int vb = 0; vb < 2; ++vb) {
;             const bf16x8 vf = *(const bf16x8*)(vs + (vb * 32 + r) * 72 + (kb * 2 + s2) * 16 + hh * 8);
;             o[vb] = MFMA32(vf, pf.v, o[vb]);
;           }
;         }
.LBB0_251:
	ds_read_b128 v[220:223], v156 offset:35840
	ds_read_b128 v[224:227], v156 offset:40448
	ds_read_b128 v[228:231], v156 offset:35872
	ds_read_b128 v[232:235], v156 offset:40480
	ds_read_b128 v[236:239], v156 offset:35904
	ds_read_b128 v[240:243], v156 offset:40512
	ds_read_b128 v[244:247], v156 offset:35936
	ds_read_b128 v[248:251], v156 offset:40544
	v_mul_f32_e32 v206, 0xbe16c740, v157
	v_fmamk_f32 v167, v167, 0x3e16c740, v206
	v_exp_f32_e32 v167, v167
	v_fmamk_f32 v166, v166, 0x3e16c740, v206
	v_exp_f32_e32 v166, v166
	v_fmamk_f32 v182, v182, 0x3e16c740, v206
	v_exp_f32_e32 v182, v182
	v_fmamk_f32 v183, v183, 0x3e16c740, v206
	v_exp_f32_e32 v183, v183
	v_fmamk_f32 v185, v185, 0x3e16c740, v206
	v_add_f32_e32 v207, 0, v167
	v_exp_f32_e32 v185, v185
	v_fmamk_f32 v186, v186, 0x3e16c740, v206
	v_add_f32_e32 v207, v166, v207
	v_exp_f32_e32 v186, v186
	v_fmamk_f32 v190, v190, 0x3e16c740, v206
	v_add_f32_e32 v207, v182, v207
	v_exp_f32_e32 v208, v190
	v_fmamk_f32 v191, v191, 0x3e16c740, v206
	v_add_f32_e32 v190, v183, v207
	v_exp_f32_e32 v207, v191
	v_fmamk_f32 v191, v201, 0x3e16c740, v206
	v_add_f32_e32 v190, v185, v190
	v_exp_f32_e32 v209, v191
	v_fmamk_f32 v191, v195, 0x3e16c740, v206
	v_add_f32_e32 v190, v186, v190
	v_exp_f32_e32 v210, v191
	v_fmamk_f32 v191, v202, 0x3e16c740, v206
	v_add_f32_e32 v190, v208, v190
	v_exp_f32_e32 v202, v191
	v_fmamk_f32 v191, v196, 0x3e16c740, v206
	v_add_f32_e32 v190, v207, v190
	v_exp_f32_e32 v211, v191
	v_fmamk_f32 v191, v203, 0x3e16c740, v206
	v_add_f32_e32 v190, v209, v190
	v_exp_f32_e32 v203, v191
	v_fmamk_f32 v191, v197, 0x3e16c740, v206
	v_add_f32_e32 v190, v210, v190
	v_exp_f32_e32 v212, v191
	v_fmamk_f32 v191, v204, 0x3e16c740, v206
	v_add_f32_e32 v190, v202, v190
	v_exp_f32_e32 v204, v191
	v_fmamk_f32 v191, v198, 0x3e16c740, v206
	v_add_f32_e32 v190, v211, v190
	v_exp_f32_e32 v213, v191
	v_fmamk_f32 v191, v205, 0x3e16c740, v206
	v_add_f32_e32 v190, v203, v190
	v_exp_f32_e32 v205, v191
	v_fmamk_f32 v191, v199, 0x3e16c740, v206
	v_add_f32_e32 v190, v212, v190
	v_exp_f32_e32 v214, v191
	v_fmamk_f32 v191, v200, 0x3e16c740, v206
	v_add_f32_e32 v190, v204, v190
	v_exp_f32_e32 v215, v191
	v_add_f32_e32 v190, v213, v190
	v_add_f32_e32 v190, v205, v190
	v_add_f32_e32 v190, v214, v190
	v_add_f32_e32 v195, v215, v190
	v_fmamk_f32 v190, v193, 0x3e16c740, v206
	v_exp_f32_e32 v216, v190
	v_fmamk_f32 v190, v194, 0x3e16c740, v206
	v_exp_f32_e32 v217, v190
	v_fmamk_f32 v190, v192, 0x3e16c740, v206
	v_exp_f32_e32 v218, v190
	v_add_f32_e32 v194, v216, v195
	v_add_f32_e32 v194, v217, v194
	v_add_f32_e32 v219, v218, v194
	v_cvt_pk_bf16_f32 v194, v167, v166
	v_fmamk_f32 v166, v187, 0x3e16c740, v206
	v_exp_f32_e32 v167, v166
	v_fmamk_f32 v166, v188, 0x3e16c740, v206
	v_cvt_pk_bf16_f32 v196, v185, v186
	v_cvt_pk_bf16_f32 v197, v208, v207
	v_exp_f32_e32 v207, v166
	v_fmamk_f32 v166, v189, 0x3e16c740, v206
	v_cvt_pk_bf16_f32 v195, v182, v183
	v_exp_f32_e32 v208, v166
	s_waitcnt lgkmcnt(7)
	v_mfma_f32_32x32x16_bf16 v[18:33], v[220:223], v[194:197], v[18:33]
	v_fmamk_f32 v166, v184, 0x3e16c740, v206
	v_cvt_pk_bf16_f32 v182, v209, v210
	v_cvt_pk_bf16_f32 v183, v202, v211
	v_cvt_pk_bf16_f32 v184, v203, v212
	v_cvt_pk_bf16_f32 v185, v204, v213
	v_fmamk_f32 v165, v165, 0x3e16c740, v206
	s_waitcnt lgkmcnt(5)
	v_mfma_f32_32x32x16_bf16 v[18:33], v[228:231], v[182:185], v[18:33]
	v_fmamk_f32 v164, v164, 0x3e16c740, v206
	v_fmamk_f32 v160, v160, 0x3e16c740, v206
	v_exp_f32_e32 v160, v160
	v_fmamk_f32 v161, v161, 0x3e16c740, v206
	v_fmamk_f32 v162, v162, 0x3e16c740, v206
	v_fmac_f32_e32 v206, 0x3e16c740, v159
	v_mfma_f32_32x32x16_bf16 v[2:17], v[224:227], v[194:197], v[2:17]
	v_exp_f32_e32 v194, v166
	v_add_f32_e32 v166, v167, v219
	v_add_f32_e32 v166, v207, v166
	v_add_f32_e32 v166, v208, v166
	v_add_f32_e32 v195, v194, v166
	v_exp_f32_e32 v196, v165
	v_cvt_pk_bf16_f32 v165, v215, v216
	s_waitcnt lgkmcnt(4)
	v_mfma_f32_32x32x16_bf16 v[2:17], v[232:235], v[182:185], v[2:17]
	v_exp_f32_e32 v190, v164
	v_cvt_pk_bf16_f32 v164, v205, v214
	v_cvt_pk_bf16_f32 v166, v217, v218
	v_cvt_pk_bf16_f32 v167, v167, v207
	v_exp_f32_e32 v161, v161
	v_exp_f32_e32 v162, v162
	s_waitcnt lgkmcnt(3)
	v_mfma_f32_32x32x16_bf16 v[18:33], v[236:239], v[164:167], v[18:33]
	v_exp_f32_e32 v159, v206
	s_waitcnt lgkmcnt(2)
	v_mfma_f32_32x32x16_bf16 v[2:17], v[240:243], v[164:167], v[2:17]
	v_cvt_pk_bf16_f32 v164, v208, v194
	v_cvt_pk_bf16_f32 v165, v196, v190
	v_cvt_pk_bf16_f32 v166, v160, v161
	v_cvt_pk_bf16_f32 v167, v162, v159
	s_waitcnt lgkmcnt(1)
	s_nop 0
	v_mfma_f32_32x32x16_bf16 v[18:33], v[244:247], v[164:167], v[18:33]
	v_add_f32_e32 v186, v196, v195
	v_add_f32_e32 v186, v190, v186
	v_add_f32_e32 v160, v160, v186
	v_add_f32_e32 v160, v161, v160
	v_add_f32_e32 v160, v162, v160
	v_add_f32_e32 v159, v159, v160
	v_add_f32_e32 v142, v159, v142
	s_waitcnt lgkmcnt(0)
	v_mfma_f32_32x32x16_bf16 v[2:17], v[248:251], v[164:167], v[2:17]

; DI unsigned pack2(float a, float b) { unsigned r; asm("v_cvt_pk_bf16_f32 %0, %1, %2\n\ts_nop 1" : "=v"(r) : "v"(a), "v"(b)); return r; }
; #define MFMA32(a, b, c) __builtin_amdgcn_mfma_f32_32x32x16_bf16((a), (b), (c), 0, 0, 0)
; template <int DQK, bool WIN>
; DI void attn_item(const u16* __restrict__ Qb, int ldq, const u16* __restrict__ Kb, int ldk, const u16* __restrict__ Vtb, int qb,
;                   float qscale, float sink2, const u16* __restrict__ zb, int ldz, u16* __restrict__ ob, int ldo, u16* lds) {
;     ...
;       const float nb = -mn * qscale;
;       float ps = 0.f;
; #pragma unroll
;       for (int kb = 0; kb < 2; ++kb)
; #pragma unroll
;         for (int i = 0; i < 16; ++i) { float pv = __builtin_amdgcn_exp2f(fmaf(st[kb][i], qscale, nb)); st[kb][i] = pv; ps += pv; }
;       lsum += ps;
; #pragma unroll
;       for (int kb = 0; kb < 2; ++kb)
; #pragma unroll
;         for (int s2 = 0; s2 < 2; ++s2) {
;           union { bf16x8 v; unsigned u[4]; } pf;
; #pragma unroll
;           for (int j = 0; j < 4; ++j) pf.u[j] = pack2(st[kb][8 * s2 + 2 * j], st[kb][8 * s2 + 2 * j + 1]);
; #pragma unroll
;           for (int vb = 0; vb < 2; ++vb) {
;             const bf16x8 vf = *(const bf16x8*)(vs + (vb * 32 + r) * 72 + (kb * 2 + s2) * 16 + hh * 8);
;             o[vb] = MFMA32(vf, pf.v, o[vb]);
;           }
;         }
.LBB0_261:
	ds_read_b128 v[186:189], v156 offset:35840
	ds_read_b128 v[190:193], v156 offset:35872
	ds_read_b128 v[194:197], v156 offset:40448
	ds_read_b128 v[198:201], v156 offset:40480
	ds_read_b128 v[202:205], v156 offset:35904
	ds_read_b128 v[206:209], v156 offset:40512
	ds_read_b128 v[210:213], v156 offset:35936
	ds_read_b128 v[214:217], v156 offset:40544
	v_mul_f32_e32 v157, 0xbe16c740, v142
	v_fmamk_f32 v18, v18, 0x3e16c740, v157
	v_exp_f32_e32 v18, v18
	v_fmamk_f32 v19, v19, 0x3e16c740, v157
	v_exp_f32_e32 v19, v19
	v_fmamk_f32 v20, v20, 0x3e16c740, v157
	v_exp_f32_e32 v20, v20
	v_fmamk_f32 v21, v21, 0x3e16c740, v157
	v_exp_f32_e32 v21, v21
	v_fmamk_f32 v22, v22, 0x3e16c740, v157
	v_add_f32_e32 v158, 0, v18
	v_exp_f32_e32 v22, v22
	v_fmamk_f32 v23, v23, 0x3e16c740, v157
	v_add_f32_e32 v158, v19, v158
	v_exp_f32_e32 v23, v23
	v_fmamk_f32 v24, v24, 0x3e16c740, v157
	v_add_f32_e32 v158, v20, v158
	v_exp_f32_e32 v24, v24
	v_fmamk_f32 v25, v25, 0x3e16c740, v157
	v_add_f32_e32 v158, v21, v158
	v_exp_f32_e32 v25, v25
	v_fmamk_f32 v26, v26, 0x3e16c740, v157
	v_add_f32_e32 v158, v22, v158
	v_exp_f32_e32 v26, v26
	v_fmamk_f32 v27, v27, 0x3e16c740, v157
	v_add_f32_e32 v158, v23, v158
	v_exp_f32_e32 v27, v27
	v_fmamk_f32 v28, v28, 0x3e16c740, v157
	v_add_f32_e32 v158, v24, v158
	v_exp_f32_e32 v28, v28
	v_fmamk_f32 v29, v29, 0x3e16c740, v157
	v_add_f32_e32 v158, v25, v158
	v_exp_f32_e32 v29, v29
	v_fmamk_f32 v30, v30, 0x3e16c740, v157
	v_add_f32_e32 v158, v26, v158
	v_exp_f32_e32 v30, v30
	v_fmamk_f32 v31, v31, 0x3e16c740, v157
	v_add_f32_e32 v158, v27, v158
	v_exp_f32_e32 v31, v31
	v_fmamk_f32 v32, v32, 0x3e16c740, v157
	v_add_f32_e32 v158, v28, v158
	v_exp_f32_e32 v32, v32
	v_fmamk_f32 v33, v33, 0x3e16c740, v157
	v_add_f32_e32 v158, v29, v158
	v_exp_f32_e32 v33, v33
	v_fmamk_f32 v2, v2, 0x3e16c740, v157
	v_add_f32_e32 v158, v30, v158
	v_exp_f32_e32 v159, v2
	v_add_f32_e32 v158, v31, v158
	v_add_f32_e32 v158, v32, v158
	v_add_f32_e32 v158, v33, v158
	v_fmamk_f32 v3, v3, 0x3e16c740, v157
	v_add_f32_e32 v2, v159, v158
	v_exp_f32_e32 v158, v3
	v_fmamk_f32 v3, v4, 0x3e16c740, v157
	v_exp_f32_e32 v160, v3
	v_fmamk_f32 v3, v5, 0x3e16c740, v157
	v_exp_f32_e32 v161, v3
	v_fmamk_f32 v3, v6, 0x3e16c740, v157
	v_exp_f32_e32 v162, v3
	v_fmamk_f32 v3, v7, 0x3e16c740, v157
	v_add_f32_e32 v2, v158, v2
	v_exp_f32_e32 v164, v3
	v_fmamk_f32 v3, v8, 0x3e16c740, v157
	v_add_f32_e32 v2, v160, v2
	v_exp_f32_e32 v165, v3
	v_fmamk_f32 v3, v9, 0x3e16c740, v157
	v_add_f32_e32 v2, v161, v2
	v_exp_f32_e32 v166, v3
	v_fmamk_f32 v3, v10, 0x3e16c740, v157
	v_add_f32_e32 v2, v162, v2
	v_exp_f32_e32 v167, v3
	v_fmamk_f32 v3, v11, 0x3e16c740, v157
	v_add_f32_e32 v2, v164, v2
	v_exp_f32_e32 v182, v3
	v_fmamk_f32 v3, v12, 0x3e16c740, v157
	v_add_f32_e32 v2, v165, v2
	v_exp_f32_e32 v183, v3
	v_fmamk_f32 v3, v13, 0x3e16c740, v157
	v_add_f32_e32 v2, v166, v2
	v_exp_f32_e32 v184, v3
	v_fmamk_f32 v3, v14, 0x3e16c740, v157
	v_add_f32_e32 v2, v167, v2
	v_exp_f32_e32 v14, v3
	v_fmamk_f32 v3, v15, 0x3e16c740, v157
	v_add_f32_e32 v2, v182, v2
	v_exp_f32_e32 v15, v3
	v_fmamk_f32 v3, v16, 0x3e16c740, v157
	v_add_f32_e32 v2, v183, v2
	v_exp_f32_e32 v16, v3
	v_fmac_f32_e32 v157, 0x3e16c740, v17
	v_add_f32_e32 v2, v184, v2
	v_exp_f32_e32 v17, v157
	v_add_f32_e32 v2, v14, v2
	v_add_f32_e32 v2, v15, v2
	v_add_f32_e32 v2, v16, v2
	v_add_f32_e32 v2, v17, v2
	v_add_f32_e32 v0, v2, v0
	v_cvt_pk_bf16_f32 v2, v18, v19
	v_cvt_pk_bf16_f32 v3, v20, v21
	v_cvt_pk_bf16_f32 v4, v22, v23
	v_cvt_pk_bf16_f32 v5, v24, v25
	s_waitcnt lgkmcnt(7)
	s_nop 0
	v_mfma_f32_32x32x16_bf16 v[34:49], v[186:189], v[2:5], v[34:49]
	s_waitcnt lgkmcnt(5)
	v_mfma_f32_32x32x16_bf16 v[50:65], v[194:197], v[2:5], v[50:65]
	v_cvt_pk_bf16_f32 v2, v26, v27
	v_cvt_pk_bf16_f32 v3, v28, v29
	v_cvt_pk_bf16_f32 v4, v30, v31
	v_cvt_pk_bf16_f32 v5, v32, v33
	s_waitcnt lgkmcnt(4)
	s_nop 0
	v_mfma_f32_32x32x16_bf16 v[50:65], v[198:201], v[2:5], v[50:65]
	v_mfma_f32_32x32x16_bf16 v[34:49], v[190:193], v[2:5], v[34:49]
	v_cvt_pk_bf16_f32 v2, v159, v158
	v_cvt_pk_bf16_f32 v3, v160, v161
	v_cvt_pk_bf16_f32 v4, v162, v164
	v_cvt_pk_bf16_f32 v5, v165, v166
	v_mov_b32_e32 v158, v142
	s_waitcnt lgkmcnt(3)
	v_mfma_f32_32x32x16_bf16 v[34:49], v[202:205], v[2:5], v[34:49]
	s_waitcnt lgkmcnt(2)
	v_mfma_f32_32x32x16_bf16 v[50:65], v[206:209], v[2:5], v[50:65]
	v_cvt_pk_bf16_f32 v2, v167, v182
	v_cvt_pk_bf16_f32 v3, v183, v184
	v_cvt_pk_bf16_f32 v4, v14, v15
	v_cvt_pk_bf16_f32 v5, v16, v17
	s_waitcnt lgkmcnt(1)
	s_nop 0
	v_mfma_f32_32x32x16_bf16 v[34:49], v[210:213], v[2:5], v[34:49]
	s_waitcnt lgkmcnt(0)
	v_mfma_f32_32x32x16_bf16 v[50:65], v[214:217], v[2:5], v[50:65]

; DI int tidx() { int t = threadIdx.x & 255; asm volatile("" : "+v"(t)); return t; }
; #define GM_LOAD(RA, RB, KT)                                                                 \
;   _Pragma("unroll") for (int i = 0; i < 4; ++i) {                                           \
;     RA[i] = *(const u32x4*)(ag + (size_t)(32 * i) * lda + (KT) * 64);                       \
;     RB[i] = *(const u32x4*)(bg + (size_t)(32 * i) * ldb + (KT) * 64);                       \
;   }
; template <bool DEEP = true>
; DI void gemm_main(f32x4 (&acc)[4][4], const u16* __restrict__ A, int lda, const u16* __restrict__ B, int ldb, int K, u16* lds) {
;   const int tid = tidx(), lane = tid & 63, w = tid >> 6;
;   const int wm = w >> 1, wn = w & 1, fr = lane & 15, fq = lane >> 4;
;   const int lrow = tid >> 3, lch = (tid & 7) * 8, lsw = ((tid & 7) ^ (lrow & 7)) * 8;
;   const u16* ag = A + (size_t)lrow * lda + lch;
;   const u16* bg = B + (size_t)lrow * ldb + lch;
;   const int nk = K >> 6;
;   if (DEEP) {
;     u32x4 ra0[4], rb0[4], ra1[4], rb1[4];
;     GM_LOAD(ra0, rb0, 0)
;     GM_LOAD(ra1, rb1, 1)
;     __syncthreads();
;     GM_STORE(ra0, rb0, 0)
;     __syncthreads();
;     for (int kt = 0; kt < nk; kt += 2) {
;       if (kt + 2 < nk) { GM_LOAD(ra0, rb0, kt + 2) }
;       GM_COMPUTE(0)
;       __builtin_amdgcn_sched_barrier(0);
;       GM_STORE(ra1, rb1, 1)
;       __syncthreads();
;       if (kt + 3 < nk) { GM_LOAD(ra1, rb1, kt + 3) }
;       GM_COMPUTE(1)
;       __builtin_amdgcn_sched_barrier(0);
;       if (kt + 2 < nk) { GM_STORE(ra0, rb0, 0) }
.LBB0_265:
	s_and_b32 s14, s20, 0xffffff80
	v_mov_b32_e32 v82, v169
	s_ashr_i32 s15, s14, 31
	v_mov_b32_e32 v83, v169
	s_and_b32 s21, s19, 0x80
	s_lshl_b64 s[0:1], s[14:15], 9
	s_add_u32 s0, s12, s0
	v_ashrrev_i32_e32 v34, 3, v83
	v_ashrrev_i32_e32 v35, 31, v34
	s_addc_u32 s1, s13, s1
	s_lshl_b32 s15, s21, 9
	v_lshlrev_b64 v[2:3], 9, v[34:35]
	v_lshlrev_b32_e32 v0, 4, v83
	s_add_u32 s22, s17, s15
	v_lshl_add_u64 v[4:5], s[0:1], 0, v[2:3]
	v_and_b32_e32 v0, 0x70, v0
	s_addc_u32 s23, s18, 0
	v_lshl_add_u64 v[66:67], v[4:5], 0, v[0:1]
	v_lshl_add_u64 v[2:3], s[22:23], 0, v[2:3]
	v_add_co_u32_e32 v70, vcc, s35, v66
	v_lshl_add_u64 v[68:69], v[2:3], 0, v[0:1]
	s_nop 0
	v_addc_co_u32_e32 v71, vcc, 0, v67, vcc
	v_add_co_u32_e32 v72, vcc, s35, v68
	global_load_dwordx4 v[2:5], v[66:67], off
	global_load_dwordx4 v[6:9], v[68:69], off
	v_addc_co_u32_e32 v73, vcc, 0, v69, vcc
	v_add_co_u32_e32 v74, vcc, s37, v66
	global_load_dwordx4 v[10:13], v[70:71], off
	s_nop 0
	v_addc_co_u32_e32 v75, vcc, 0, v67, vcc
	v_add_co_u32_e32 v76, vcc, s37, v68
	global_load_dwordx4 v[18:21], v[74:75], off
	s_nop 0
	v_addc_co_u32_e32 v77, vcc, 0, v69, vcc
	v_add_co_u32_e32 v78, vcc, s40, v66
	global_load_dwordx4 v[14:17], v[72:73], off
	s_nop 0
	v_addc_co_u32_e32 v79, vcc, 0, v67, vcc
	global_load_dwordx4 v[26:29], v[78:79], off
	v_add_co_u32_e32 v80, vcc, s40, v68
	global_load_dwordx4 v[22:25], v[76:77], off
	s_nop 0
	v_addc_co_u32_e32 v81, vcc, 0, v69, vcc
	global_load_dwordx4 v[30:33], v[80:81], off
	v_xor_b32_e32 v0, v34, v83
	v_lshlrev_b32_e32 v0, 4, v0
	v_lshlrev_b32_e32 v34, 7, v34
	v_and_b32_e32 v0, 0x70, v0
	v_add3_u32 v85, s33, v0, v34
	global_load_dwordx4 v[46:49], v[66:67], off offset:128
	global_load_dwordx4 v[42:45], v[70:71], off offset:128
	global_load_dwordx4 v[38:41], v[74:75], off offset:128
	global_load_dwordx4 v[34:37], v[78:79], off offset:128
	global_load_dwordx4 v[62:65], v[68:69], off offset:128
	global_load_dwordx4 v[58:61], v[72:73], off offset:128
	global_load_dwordx4 v[54:57], v[76:77], off offset:128
	global_load_dwordx4 v[50:53], v[80:81], off offset:128
	s_barrier
	v_and_b32_e32 v84, 15, v83
	v_lshrrev_b32_e32 v86, 1, v83
	v_and_or_b32 v84, v86, s41, v84
	v_lshrrev_b32_e32 v0, 4, v83
	v_bfe_u32 v87, v83, 4, 2
	v_lshl_add_u32 v88, v84, 7, s33
	v_lshlrev_b32_e32 v84, 7, v83
	v_and_b32_e32 v83, 7, v83
	v_and_b32_e32 v84, 0x2780, v84
	v_bitop3_b32 v0, v0, v83, 3 bitop3:0x6c
	v_add_u32_e32 v89, s33, v84
	v_lshlrev_b32_e32 v0, 4, v0
	v_add_u32_e32 v86, v88, v0
	v_add_u32_e32 v84, v89, v0
	v_bitop3_b32 v0, v87, v83, 4 bitop3:0x36
	v_lshlrev_b32_e32 v0, 4, v0
	v_add_u32_e32 v83, v88, v0
	v_add_u32_e32 v0, v89, v0
	s_waitcnt vmcnt(15)
	ds_write_b128 v85, v[2:5]
	s_waitcnt vmcnt(13)
	ds_write_b128 v85, v[10:13] offset:4096
	s_waitcnt vmcnt(12)
	ds_write_b128 v85, v[18:21] offset:8192
	s_waitcnt vmcnt(10)
	ds_write_b128 v85, v[26:29] offset:12288
	ds_write_b128 v85, v[6:9] offset:16384
	ds_write_b128 v85, v[14:17] offset:20480
	s_waitcnt vmcnt(9)
	ds_write_b128 v85, v[22:25] offset:24576
	s_waitcnt vmcnt(8)
	ds_write_b128 v85, v[30:33] offset:28672
	s_waitcnt lgkmcnt(0)
	s_barrier
	global_load_dwordx4 v[2:5], v[66:67], off offset:256
	global_load_dwordx4 v[6:9], v[68:69], off offset:256
	global_load_dwordx4 v[10:13], v[70:71], off offset:256
	global_load_dwordx4 v[14:17], v[72:73], off offset:256
	global_load_dwordx4 v[18:21], v[74:75], off offset:256
	global_load_dwordx4 v[22:25], v[76:77], off offset:256
	global_load_dwordx4 v[26:29], v[78:79], off offset:256
	global_load_dwordx4 v[30:33], v[80:81], off offset:256
	s_setprio 1
	ds_read_b128 v[88:91], v86
	ds_read_b128 v[92:95], v86 offset:2048
	ds_read_b128 v[96:99], v86 offset:4096
	ds_read_b128 v[100:103], v86 offset:6144
	ds_read_b128 v[104:107], v84 offset:16384
	ds_read_b128 v[120:123], v84 offset:18432
	ds_read_b128 v[136:139], v84 offset:20480
	ds_read_b128 v[152:155], v84 offset:22528
	s_waitcnt lgkmcnt(3)
	v_mfma_f32_16x16x32_bf16 v[108:111], v[88:91], v[104:107], 0
	v_mfma_f32_16x16x32_bf16 v[112:115], v[92:95], v[104:107], 0
	v_mfma_f32_16x16x32_bf16 v[116:119], v[96:99], v[104:107], 0
	v_mfma_f32_16x16x32_bf16 v[104:107], v[100:103], v[104:107], 0
	s_waitcnt lgkmcnt(2)
	v_mfma_f32_16x16x32_bf16 v[124:127], v[88:91], v[120:123], 0
	v_mfma_f32_16x16x32_bf16 v[128:131], v[92:95], v[120:123], 0
	v_mfma_f32_16x16x32_bf16 v[132:135], v[96:99], v[120:123], 0
	v_mfma_f32_16x16x32_bf16 v[120:123], v[100:103], v[120:123], 0
	s_waitcnt lgkmcnt(1)
	v_mfma_f32_16x16x32_bf16 v[140:143], v[88:91], v[136:139], 0
	v_mfma_f32_16x16x32_bf16 v[144:147], v[92:95], v[136:139], 0
	v_mfma_f32_16x16x32_bf16 v[148:151], v[96:99], v[136:139], 0
	v_mfma_f32_16x16x32_bf16 v[136:139], v[100:103], v[136:139], 0
	s_waitcnt lgkmcnt(0)
	v_mfma_f32_16x16x32_bf16 v[88:91], v[88:91], v[152:155], 0
	v_mfma_f32_16x16x32_bf16 v[92:95], v[92:95], v[152:155], 0
	v_mfma_f32_16x16x32_bf16 v[96:99], v[96:99], v[152:155], 0
	v_mfma_f32_16x16x32_bf16 v[100:103], v[100:103], v[152:155], 0
	ds_read_b128 v[152:155], v83
	ds_read_b128 v[156:159], v83 offset:2048
	ds_read_b128 v[164:167], v83 offset:4096
	ds_read_b128 v[182:185], v83 offset:6144
	ds_read_b128 v[186:189], v0 offset:16384
	s_waitcnt lgkmcnt(0)
	v_mfma_f32_16x16x32_bf16 v[108:111], v[152:155], v[186:189], v[108:111]
	v_mfma_f32_16x16x32_bf16 v[112:115], v[156:159], v[186:189], v[112:115]
	v_mfma_f32_16x16x32_bf16 v[116:119], v[164:167], v[186:189], v[116:119]
	v_mfma_f32_16x16x32_bf16 v[104:107], v[182:185], v[186:189], v[104:107]
	ds_read_b128 v[186:189], v0 offset:18432
	s_waitcnt lgkmcnt(0)
	v_mfma_f32_16x16x32_bf16 v[124:127], v[152:155], v[186:189], v[124:127]
	v_mfma_f32_16x16x32_bf16 v[128:131], v[156:159], v[186:189], v[128:131]
	v_mfma_f32_16x16x32_bf16 v[132:135], v[164:167], v[186:189], v[132:135]
	v_mfma_f32_16x16x32_bf16 v[120:123], v[182:185], v[186:189], v[120:123]
	ds_read_b128 v[186:189], v0 offset:20480
	s_waitcnt lgkmcnt(0)
	v_mfma_f32_16x16x32_bf16 v[140:143], v[152:155], v[186:189], v[140:143]
	v_mfma_f32_16x16x32_bf16 v[144:147], v[156:159], v[186:189], v[144:147]
	v_mfma_f32_16x16x32_bf16 v[148:151], v[164:167], v[186:189], v[148:151]
	v_mfma_f32_16x16x32_bf16 v[136:139], v[182:185], v[186:189], v[136:139]
	ds_read_b128 v[186:189], v0 offset:22528
	s_waitcnt lgkmcnt(0)
	v_mfma_f32_16x16x32_bf16 v[88:91], v[152:155], v[186:189], v[88:91]
	v_mfma_f32_16x16x32_bf16 v[92:95], v[156:159], v[186:189], v[92:95]
	v_mfma_f32_16x16x32_bf16 v[96:99], v[164:167], v[186:189], v[96:99]
	v_mfma_f32_16x16x32_bf16 v[100:103], v[182:185], v[186:189], v[100:103]
	s_setprio 0
	s_waitcnt vmcnt(15)
	ds_write_b128 v85, v[46:49] offset:32768
	s_waitcnt vmcnt(11)
	ds_write_b128 v85, v[62:65] offset:49152
	ds_write_b128 v85, v[42:45] offset:36864
	s_waitcnt vmcnt(10)
	ds_write_b128 v85, v[58:61] offset:53248
	ds_write_b128 v85, v[38:41] offset:40960
	s_waitcnt vmcnt(9)
	ds_write_b128 v85, v[54:57] offset:57344
	ds_write_b128 v85, v[34:37] offset:45056
	s_waitcnt vmcnt(8)
	ds_write_b128 v85, v[50:53] offset:61440
	s_waitcnt lgkmcnt(0)
	s_barrier
; DI int tidx() { int t = threadIdx.x & 255; asm volatile("" : "+v"(t)); return t; }
; #define GM_LOAD(RA, RB, KT)                                                                 \
;   _Pragma("unroll") for (int i = 0; i < 4; ++i) {                                           \
;     RA[i] = *(const u32x4*)(ag + (size_t)(32 * i) * lda + (KT) * 64);                       \
;     RB[i] = *(const u32x4*)(bg + (size_t)(32 * i) * ldb + (KT) * 64);                       \
;   }
; template <bool DEEP = true>
; DI void gemm_main(f32x4 (&acc)[4][4], const u16* __restrict__ A, int lda, const u16* __restrict__ B, int ldb, int K, u16* lds) {
;   const int tid = tidx(), lane = tid & 63, w = tid >> 6;
;   const int wm = w >> 1, wn = w & 1, fr = lane & 15, fq = lane >> 4;
;   const int lrow = tid >> 3, lch = (tid & 7) * 8, lsw = ((tid & 7) ^ (lrow & 7)) * 8;
;   const u16* ag = A + (size_t)lrow * lda + lch;
;   const u16* bg = B + (size_t)lrow * ldb + lch;
;   const int nk = K >> 6;
;   if (DEEP) {
;     u32x4 ra0[4], rb0[4], ra1[4], rb1[4];
;     GM_LOAD(ra0, rb0, 0)
;     GM_LOAD(ra1, rb1, 1)
;     __syncthreads();
;     GM_STORE(ra0, rb0, 0)
;     __syncthreads();
;     for (int kt = 0; kt < nk; kt += 2) {
;       if (kt + 2 < nk) { GM_LOAD(ra0, rb0, kt + 2) }
;       GM_COMPUTE(0)
;       __builtin_amdgcn_sched_barrier(0);
;       GM_STORE(ra1, rb1, 1)
;       __syncthreads();
;       if (kt + 3 < nk) { GM_LOAD(ra1, rb1, kt + 3) }
;       GM_COMPUTE(1)
;       __builtin_amdgcn_sched_barrier(0);
;       if (kt + 2 < nk) { GM_STORE(ra0, rb0, 0) }
	global_load_dwordx4 v[34:37], v[66:67], off offset:384
	global_load_dwordx4 v[38:41], v[68:69], off offset:384
	global_load_dwordx4 v[42:45], v[70:71], off offset:384
	global_load_dwordx4 v[46:49], v[72:73], off offset:384
	global_load_dwordx4 v[50:53], v[74:75], off offset:384
	global_load_dwordx4 v[54:57], v[76:77], off offset:384
	global_load_dwordx4 v[58:61], v[78:79], off offset:384
	global_load_dwordx4 v[62:65], v[80:81], off offset:384
	s_setprio 1
	ds_read_b128 v[66:69], v86 offset:32768
	ds_read_b128 v[70:73], v86 offset:34816
	ds_read_b128 v[74:77], v86 offset:36864
	ds_read_b128 v[78:81], v86 offset:38912
	ds_read_b128 v[152:155], v84 offset:49152
	s_waitcnt lgkmcnt(0)
	v_mfma_f32_16x16x32_bf16 v[108:111], v[66:69], v[152:155], v[108:111]
	v_mfma_f32_16x16x32_bf16 v[112:115], v[70:73], v[152:155], v[112:115]
	v_mfma_f32_16x16x32_bf16 v[116:119], v[74:77], v[152:155], v[116:119]
	v_mfma_f32_16x16x32_bf16 v[104:107], v[78:81], v[152:155], v[104:107]
	ds_read_b128 v[152:155], v84 offset:51200
	s_waitcnt lgkmcnt(0)
	v_mfma_f32_16x16x32_bf16 v[124:127], v[66:69], v[152:155], v[124:127]
	v_mfma_f32_16x16x32_bf16 v[128:131], v[70:73], v[152:155], v[128:131]
	v_mfma_f32_16x16x32_bf16 v[132:135], v[74:77], v[152:155], v[132:135]
	v_mfma_f32_16x16x32_bf16 v[120:123], v[78:81], v[152:155], v[120:123]
	ds_read_b128 v[152:155], v84 offset:53248
	s_waitcnt lgkmcnt(0)
	v_mfma_f32_16x16x32_bf16 v[140:143], v[66:69], v[152:155], v[140:143]
	v_mfma_f32_16x16x32_bf16 v[144:147], v[70:73], v[152:155], v[144:147]
	v_mfma_f32_16x16x32_bf16 v[148:151], v[74:77], v[152:155], v[148:151]
	v_mfma_f32_16x16x32_bf16 v[136:139], v[78:81], v[152:155], v[136:139]
	ds_read_b128 v[152:155], v84 offset:55296
	s_waitcnt lgkmcnt(0)
	v_mfma_f32_16x16x32_bf16 v[66:69], v[66:69], v[152:155], v[88:91]
	v_mfma_f32_16x16x32_bf16 v[70:73], v[70:73], v[152:155], v[92:95]
	v_mfma_f32_16x16x32_bf16 v[74:77], v[74:77], v[152:155], v[96:99]
	v_mfma_f32_16x16x32_bf16 v[78:81], v[78:81], v[152:155], v[100:103]
	ds_read_b128 v[88:91], v83 offset:32768
	ds_read_b128 v[92:95], v83 offset:34816
	ds_read_b128 v[96:99], v83 offset:36864
	ds_read_b128 v[100:103], v83 offset:38912
	ds_read_b128 v[152:155], v0 offset:49152
	s_waitcnt lgkmcnt(0)
	v_mfma_f32_16x16x32_bf16 v[108:111], v[88:91], v[152:155], v[108:111]
	v_mfma_f32_16x16x32_bf16 v[112:115], v[92:95], v[152:155], v[112:115]
	v_mfma_f32_16x16x32_bf16 v[116:119], v[96:99], v[152:155], v[116:119]
	v_mfma_f32_16x16x32_bf16 v[104:107], v[100:103], v[152:155], v[104:107]
	ds_read_b128 v[152:155], v0 offset:51200
	s_waitcnt lgkmcnt(0)
	v_mfma_f32_16x16x32_bf16 v[124:127], v[88:91], v[152:155], v[124:127]
	v_mfma_f32_16x16x32_bf16 v[128:131], v[92:95], v[152:155], v[128:131]
	v_mfma_f32_16x16x32_bf16 v[132:135], v[96:99], v[152:155], v[132:135]
	v_mfma_f32_16x16x32_bf16 v[120:123], v[100:103], v[152:155], v[120:123]
	ds_read_b128 v[152:155], v0 offset:53248
	s_waitcnt lgkmcnt(0)
	v_mfma_f32_16x16x32_bf16 v[140:143], v[88:91], v[152:155], v[140:143]
	v_mfma_f32_16x16x32_bf16 v[144:147], v[92:95], v[152:155], v[144:147]
	v_mfma_f32_16x16x32_bf16 v[148:151], v[96:99], v[152:155], v[148:151]
	v_mfma_f32_16x16x32_bf16 v[136:139], v[100:103], v[152:155], v[136:139]
	ds_read_b128 v[152:155], v0 offset:55296
	s_waitcnt lgkmcnt(0)
	v_mfma_f32_16x16x32_bf16 v[66:69], v[88:91], v[152:155], v[66:69]
	v_mfma_f32_16x16x32_bf16 v[70:73], v[92:95], v[152:155], v[70:73]
	v_mfma_f32_16x16x32_bf16 v[74:77], v[96:99], v[152:155], v[74:77]
	v_mfma_f32_16x16x32_bf16 v[78:81], v[100:103], v[152:155], v[78:81]
	s_setprio 0
	s_waitcnt vmcnt(15)
	ds_write_b128 v85, v[2:5]
	s_waitcnt vmcnt(14)
	ds_write_b128 v85, v[6:9] offset:16384
	s_waitcnt vmcnt(13)
	ds_write_b128 v85, v[10:13] offset:4096
	s_waitcnt vmcnt(12)
	ds_write_b128 v85, v[14:17] offset:20480
	s_waitcnt vmcnt(11)
	ds_write_b128 v85, v[18:21] offset:8192
	s_waitcnt vmcnt(10)
	ds_write_b128 v85, v[22:25] offset:24576
	s_waitcnt vmcnt(9)
	ds_write_b128 v85, v[26:29] offset:12288
	s_waitcnt vmcnt(8)
	ds_write_b128 v85, v[30:33] offset:28672
	s_waitcnt lgkmcnt(0)
	s_barrier
	s_setprio 1
	ds_read_b128 v[2:5], v86
	ds_read_b128 v[6:9], v86 offset:2048
	ds_read_b128 v[10:13], v86 offset:4096
	ds_read_b128 v[14:17], v86 offset:6144
	ds_read_b128 v[18:21], v84 offset:16384
	ds_read_b128 v[88:91], v84 offset:18432
	s_waitcnt lgkmcnt(1)
	v_mfma_f32_16x16x32_bf16 v[22:25], v[2:5], v[18:21], v[108:111]
	v_mfma_f32_16x16x32_bf16 v[26:29], v[6:9], v[18:21], v[112:115]
	v_mfma_f32_16x16x32_bf16 v[30:33], v[10:13], v[18:21], v[116:119]
	v_mfma_f32_16x16x32_bf16 v[18:21], v[14:17], v[18:21], v[104:107]
	s_nop 2
	ds_read_b128 v[104:107], v84 offset:20480
	s_waitcnt lgkmcnt(1)
	v_mfma_f32_16x16x32_bf16 v[92:95], v[2:5], v[88:91], v[124:127]
	v_mfma_f32_16x16x32_bf16 v[96:99], v[6:9], v[88:91], v[128:131]
	v_mfma_f32_16x16x32_bf16 v[100:103], v[10:13], v[88:91], v[132:135]
	v_mfma_f32_16x16x32_bf16 v[88:91], v[14:17], v[88:91], v[120:123]
	s_nop 2
	ds_read_b128 v[120:123], v84 offset:22528
	s_waitcnt lgkmcnt(1)
	v_mfma_f32_16x16x32_bf16 v[108:111], v[2:5], v[104:107], v[140:143]
	v_mfma_f32_16x16x32_bf16 v[112:115], v[6:9], v[104:107], v[144:147]
	v_mfma_f32_16x16x32_bf16 v[116:119], v[10:13], v[104:107], v[148:151]
	v_mfma_f32_16x16x32_bf16 v[104:107], v[14:17], v[104:107], v[136:139]
	s_waitcnt lgkmcnt(0)
	v_mfma_f32_16x16x32_bf16 v[2:5], v[2:5], v[120:123], v[66:69]
	v_mfma_f32_16x16x32_bf16 v[6:9], v[6:9], v[120:123], v[70:73]
	v_mfma_f32_16x16x32_bf16 v[10:13], v[10:13], v[120:123], v[74:77]
	v_mfma_f32_16x16x32_bf16 v[14:17], v[14:17], v[120:123], v[78:81]
	ds_read_b128 v[66:69], v83
	ds_read_b128 v[70:73], v83 offset:2048
	ds_read_b128 v[74:77], v83 offset:4096
	ds_read_b128 v[78:81], v83 offset:6144
	ds_read_b128 v[120:123], v0 offset:16384
	s_waitcnt lgkmcnt(0)
; DI int tidx() { int t = threadIdx.x & 255; asm volatile("" : "+v"(t)); return t; }
; #define GM_LOAD(RA, RB, KT)                                                                 \
;   _Pragma("unroll") for (int i = 0; i < 4; ++i) {                                           \
;     RA[i] = *(const u32x4*)(ag + (size_t)(32 * i) * lda + (KT) * 64);                       \
;     RB[i] = *(const u32x4*)(bg + (size_t)(32 * i) * ldb + (KT) * 64);                       \
;   }
; template <bool DEEP = true>
; DI void gemm_main(f32x4 (&acc)[4][4], const u16* __restrict__ A, int lda, const u16* __restrict__ B, int ldb, int K, u16* lds) {
;   const int tid = tidx(), lane = tid & 63, w = tid >> 6;
;   const int wm = w >> 1, wn = w & 1, fr = lane & 15, fq = lane >> 4;
;   const int lrow = tid >> 3, lch = (tid & 7) * 8, lsw = ((tid & 7) ^ (lrow & 7)) * 8;
;   const u16* ag = A + (size_t)lrow * lda + lch;
;   const u16* bg = B + (size_t)lrow * ldb + lch;
;   const int nk = K >> 6;
;   if (DEEP) {
;     u32x4 ra0[4], rb0[4], ra1[4], rb1[4];
;     GM_LOAD(ra0, rb0, 0)
;     GM_LOAD(ra1, rb1, 1)
;     __syncthreads();
;     GM_STORE(ra0, rb0, 0)
;     __syncthreads();
;     for (int kt = 0; kt < nk; kt += 2) {
;       if (kt + 2 < nk) { GM_LOAD(ra0, rb0, kt + 2) }
;       GM_COMPUTE(0)
;       __builtin_amdgcn_sched_barrier(0);
;       GM_STORE(ra1, rb1, 1)
;       __syncthreads();
;       if (kt + 3 < nk) { GM_LOAD(ra1, rb1, kt + 3) }
;       GM_COMPUTE(1)
;       __builtin_amdgcn_sched_barrier(0);
;       if (kt + 2 < nk) { GM_STORE(ra0, rb0, 0) }
;       __syncthreads();
;     }
	v_mfma_f32_16x16x32_bf16 v[22:25], v[66:69], v[120:123], v[22:25]
	v_mfma_f32_16x16x32_bf16 v[26:29], v[70:73], v[120:123], v[26:29]
	v_mfma_f32_16x16x32_bf16 v[30:33], v[74:77], v[120:123], v[30:33]
	v_mfma_f32_16x16x32_bf16 v[18:21], v[78:81], v[120:123], v[18:21]
	ds_read_b128 v[120:123], v0 offset:18432
	s_waitcnt lgkmcnt(0)
	v_mfma_f32_16x16x32_bf16 v[92:95], v[66:69], v[120:123], v[92:95]
	v_mfma_f32_16x16x32_bf16 v[96:99], v[70:73], v[120:123], v[96:99]
	v_mfma_f32_16x16x32_bf16 v[100:103], v[74:77], v[120:123], v[100:103]
	v_mfma_f32_16x16x32_bf16 v[88:91], v[78:81], v[120:123], v[88:91]
	ds_read_b128 v[120:123], v0 offset:20480
	s_waitcnt lgkmcnt(0)
	v_mfma_f32_16x16x32_bf16 v[108:111], v[66:69], v[120:123], v[108:111]
	v_mfma_f32_16x16x32_bf16 v[112:115], v[70:73], v[120:123], v[112:115]
	v_mfma_f32_16x16x32_bf16 v[116:119], v[74:77], v[120:123], v[116:119]
	v_mfma_f32_16x16x32_bf16 v[104:107], v[78:81], v[120:123], v[104:107]
	ds_read_b128 v[120:123], v0 offset:22528
	s_waitcnt lgkmcnt(0)
	v_mfma_f32_16x16x32_bf16 v[2:5], v[66:69], v[120:123], v[2:5]
	v_mfma_f32_16x16x32_bf16 v[6:9], v[70:73], v[120:123], v[6:9]
	v_mfma_f32_16x16x32_bf16 v[10:13], v[74:77], v[120:123], v[10:13]
	v_mfma_f32_16x16x32_bf16 v[14:17], v[78:81], v[120:123], v[14:17]
	s_setprio 0
	s_waitcnt vmcnt(7)
	ds_write_b128 v85, v[34:37] offset:32768
	s_waitcnt vmcnt(6)
	ds_write_b128 v85, v[38:41] offset:49152
	s_waitcnt vmcnt(5)
	ds_write_b128 v85, v[42:45] offset:36864
	s_waitcnt vmcnt(4)
	ds_write_b128 v85, v[46:49] offset:53248
	s_waitcnt vmcnt(3)
	ds_write_b128 v85, v[50:53] offset:40960
	s_waitcnt vmcnt(2)
	ds_write_b128 v85, v[54:57] offset:57344
	s_waitcnt vmcnt(1)
	ds_write_b128 v85, v[58:61] offset:45056
	s_waitcnt vmcnt(0)
	ds_write_b128 v85, v[62:65] offset:61440
	s_waitcnt lgkmcnt(0)
	s_barrier
	s_setprio 1
	ds_read_b128 v[34:37], v86 offset:32768
	ds_read_b128 v[38:41], v86 offset:34816
	ds_read_b128 v[42:45], v86 offset:36864
	ds_read_b128 v[46:49], v86 offset:38912
	ds_read_b128 v[50:53], v84 offset:49152
	s_waitcnt lgkmcnt(0)
	v_mfma_f32_16x16x32_bf16 v[22:25], v[34:37], v[50:53], v[22:25]
	ds_read_b128 v[66:69], v84 offset:53248
	v_mfma_f32_16x16x32_bf16 v[26:29], v[38:41], v[50:53], v[26:29]
	v_mfma_f32_16x16x32_bf16 v[30:33], v[42:45], v[50:53], v[30:33]
	v_mfma_f32_16x16x32_bf16 v[18:21], v[46:49], v[50:53], v[18:21]
	ds_read_b128 v[50:53], v84 offset:51200
	ds_read_b128 v[84:87], v84 offset:55296
	s_waitcnt lgkmcnt(1)
	v_mfma_f32_16x16x32_bf16 v[54:57], v[34:37], v[50:53], v[92:95]
	v_mfma_f32_16x16x32_bf16 v[58:61], v[38:41], v[50:53], v[96:99]
	v_mfma_f32_16x16x32_bf16 v[62:65], v[42:45], v[50:53], v[100:103]
	v_mfma_f32_16x16x32_bf16 v[50:53], v[46:49], v[50:53], v[88:91]
	v_mfma_f32_16x16x32_bf16 v[70:73], v[34:37], v[66:69], v[108:111]
	v_mfma_f32_16x16x32_bf16 v[74:77], v[38:41], v[66:69], v[112:115]
	v_mfma_f32_16x16x32_bf16 v[78:81], v[42:45], v[66:69], v[116:119]
	v_mfma_f32_16x16x32_bf16 v[66:69], v[46:49], v[66:69], v[104:107]
	s_waitcnt lgkmcnt(0)
	v_mfma_f32_16x16x32_bf16 v[2:5], v[34:37], v[84:87], v[2:5]
	v_mfma_f32_16x16x32_bf16 v[6:9], v[38:41], v[84:87], v[6:9]
	v_mfma_f32_16x16x32_bf16 v[10:13], v[42:45], v[84:87], v[10:13]
	v_mfma_f32_16x16x32_bf16 v[14:17], v[46:49], v[84:87], v[14:17]
	ds_read_b128 v[34:37], v83 offset:32768
	ds_read_b128 v[38:41], v83 offset:34816
	ds_read_b128 v[42:45], v83 offset:36864
	ds_read_b128 v[46:49], v83 offset:38912
	ds_read_b128 v[84:87], v0 offset:49152
	s_waitcnt lgkmcnt(0)
	v_mfma_f32_16x16x32_bf16 v[22:25], v[34:37], v[84:87], v[22:25]
	v_mfma_f32_16x16x32_bf16 v[26:29], v[38:41], v[84:87], v[26:29]
	v_mfma_f32_16x16x32_bf16 v[30:33], v[42:45], v[84:87], v[30:33]
	v_mfma_f32_16x16x32_bf16 v[18:21], v[46:49], v[84:87], v[18:21]
	ds_read_b128 v[84:87], v0 offset:51200
	s_waitcnt lgkmcnt(0)
	v_mfma_f32_16x16x32_bf16 v[54:57], v[34:37], v[84:87], v[54:57]
	v_mfma_f32_16x16x32_bf16 v[58:61], v[38:41], v[84:87], v[58:61]
	v_mfma_f32_16x16x32_bf16 v[62:65], v[42:45], v[84:87], v[62:65]
	v_mfma_f32_16x16x32_bf16 v[50:53], v[46:49], v[84:87], v[50:53]
	ds_read_b128 v[84:87], v0 offset:53248
	s_waitcnt lgkmcnt(0)
	v_mfma_f32_16x16x32_bf16 v[70:73], v[34:37], v[84:87], v[70:73]
	v_mfma_f32_16x16x32_bf16 v[74:77], v[38:41], v[84:87], v[74:77]
	v_mfma_f32_16x16x32_bf16 v[78:81], v[42:45], v[84:87], v[78:81]
	v_mfma_f32_16x16x32_bf16 v[66:69], v[46:49], v[84:87], v[66:69]
	ds_read_b128 v[84:87], v0 offset:55296
	s_waitcnt lgkmcnt(0)
	v_mfma_f32_16x16x32_bf16 v[2:5], v[34:37], v[84:87], v[2:5]
	v_mfma_f32_16x16x32_bf16 v[6:9], v[38:41], v[84:87], v[6:9]
	v_mfma_f32_16x16x32_bf16 v[10:13], v[42:45], v[84:87], v[10:13]
	v_mfma_f32_16x16x32_bf16 v[14:17], v[46:49], v[84:87], v[14:17]
	s_setprio 0
	v_mov_b32_e32 v0, v169
	s_barrier
; DI int tidx() { int t = threadIdx.x & 255; asm volatile("" : "+v"(t)); return t; }
; DI float silu(float x) { return x / (1.f + __expf(-x)); }
; DI u32x4 pack8(const float* f) { u32x4 o; o.x = pack2(f[0], f[1]); o.y = pack2(f[2], f[3]); o.z = pack2(f[4], f[5]); o.w = pack2(f[6], f[7]); return o; }
; DI void stage_c(const f32x4 (&acc)[4][4], float* Cs) {
;   const int tid = tidx(), lane = tid & 63, w = tid >> 6;
;   const int wm = w >> 1, wn = w & 1, fr = lane & 15, fq = lane >> 4;
; #pragma unroll
;   for (int m = 0; m < 4; ++m)
; #pragma unroll
;     for (int n = 0; n < 4; ++n)
; #pragma unroll
;       for (int j = 0; j < 4; ++j) Cs[(wm * 64 + m * 16 + fq * 4 + j) * CST + wn * 64 + n * 16 + fr] = acc[m][n][j];
;   __syncthreads();
; }
; DI void pw2_tile(PREF p, int l, int idx, unsigned char* ldsb) {
;     ...
;   u32x4 zr[8];
; #pragma unroll
;   for (int q = 0; q < 8; ++q) zr[q] = *(const u32x4*)(p.hb + (size_t)(row0 + (tid >> 4) + 16 * q) * HW + OFF_AZ + col0 + (tid & 15) * 8);
; #pragma unroll
;   for (int q = 0; q < 8; ++q) {
;     int r = (tid >> 4) + 16 * q, c = (tid & 15) * 8;
;     float v[8]; ld8(Cs + r * CST + c, v);
;     float z[8]; unpack8(zr[q], z);
; #pragma unroll
;     for (int j = 0; j < 8; ++j) v[j] *= silu(z[j]);
;     *(u32x4*)(p.ys + (size_t)(row0 + r) * 1024 + col0 + c) = pack8(v);
;   }
	s_lshl_b32 s52, s21, 1
	v_lshrrev_b32_e32 v35, 2, v0
	v_lshrrev_b32_e32 v34, 1, v0
	v_and_b32_e32 v35, 12, v35
	v_and_or_b32 v34, v34, s42, v35
	v_and_b32_e32 v0, 0x4f, v0
	v_mul_lo_u32 v34, v34, s92
	v_lshlrev_b32_e32 v0, 2, v0
	v_add3_u32 v0, s33, v34, v0
	ds_write2_b32 v0, v22, v54 offset1:16
	ds_write2_b32 v0, v23, v55 offset0:132 offset1:148
	v_add_u32_e32 v22, 0x400, v0
	ds_write2_b32 v22, v24, v56 offset0:8 offset1:24
	ds_write2_b32 v22, v25, v57 offset0:140 offset1:156
	ds_write2_b32 v0, v70, v2 offset0:32 offset1:48
	ds_write2_b32 v0, v71, v3 offset0:164 offset1:180
	ds_write2_b32 v22, v72, v4 offset0:40 offset1:56
	ds_write2_b32 v22, v73, v5 offset0:172 offset1:188
	v_add_u32_e32 v2, 0x2000, v0
	v_add_u32_e32 v3, 0x2400, v0
	ds_write2_b32 v2, v26, v58 offset0:64 offset1:80
	ds_write2_b32 v2, v27, v59 offset0:196 offset1:212
	ds_write2_b32 v3, v28, v60 offset0:72 offset1:88
	ds_write2_b32 v3, v29, v61 offset0:204 offset1:220
	ds_write2_b32 v2, v74, v6 offset0:96 offset1:112
	ds_write2_b32 v2, v75, v7 offset0:228 offset1:244
	ds_write2_b32 v3, v76, v8 offset0:104 offset1:120
	ds_write2_b32 v3, v77, v9 offset0:236 offset1:252
	v_add_u32_e32 v2, 0x4000, v0
	v_add_u32_e32 v3, 0x4400, v0
	v_add_u32_e32 v4, 0x4800, v0
	ds_write2_b32 v2, v30, v62 offset0:128 offset1:144
	ds_write2_b32 v3, v31, v63 offset0:4 offset1:20
	ds_write2_b32 v3, v32, v64 offset0:136 offset1:152
	ds_write2_b32 v4, v33, v65 offset0:12 offset1:28
	ds_write2_b32 v2, v78, v10 offset0:160 offset1:176
	ds_write2_b32 v3, v79, v11 offset0:36 offset1:52
	ds_write2_b32 v3, v80, v12 offset0:168 offset1:184
	ds_write2_b32 v4, v81, v13 offset0:44 offset1:60
	v_add_u32_e32 v2, 0x6000, v0
	v_add_u32_e32 v3, 0x6400, v0
	v_add_u32_e32 v0, 0x6800, v0
	v_ashrrev_i32_e32 v30, 4, v82
	ds_write2_b32 v2, v18, v50 offset0:192 offset1:208
	ds_write2_b32 v3, v19, v51 offset0:68 offset1:84
	ds_write2_b32 v3, v20, v52 offset0:200 offset1:216
	ds_write2_b32 v0, v21, v53 offset0:76 offset1:92
	ds_write2_b32 v2, v66, v14 offset0:224 offset1:240
	ds_write2_b32 v3, v67, v15 offset0:100 offset1:116
	ds_write2_b32 v3, v68, v16 offset0:232 offset1:248
	ds_write2_b32 v0, v69, v17 offset0:108 offset1:124
	v_add_u32_e32 v54, s14, v30
	v_lshlrev_b32_e32 v0, 3, v82
	v_mov_b64_e32 v[2:3], s[8:9]
	v_and_b32_e32 v31, 0x78, v0
	v_mad_i64_i32 v[4:5], s[0:1], v54, s60, v[2:3]
	v_lshl_add_u64 v[4:5], v[4:5], 0, s[52:53]
	v_lshlrev_b32_e32 v0, 1, v31
	v_lshl_add_u64 v[4:5], v[4:5], 0, v[0:1]
	s_waitcnt lgkmcnt(0)
	s_barrier
	global_load_dwordx4 v[56:59], v[4:5], off offset:1024
	v_add_u32_e32 v52, 16, v54
	v_mad_i64_i32 v[4:5], s[0:1], v52, s60, v[2:3]
	v_lshl_add_u64 v[4:5], v[4:5], 0, s[52:53]
	v_lshl_add_u64 v[4:5], v[4:5], 0, v[0:1]
	v_add_u32_e32 v50, 32, v54
	global_load_dwordx4 v[26:29], v[4:5], off offset:1024
	v_mad_i64_i32 v[4:5], s[0:1], v50, s60, v[2:3]
	v_lshl_add_u64 v[4:5], v[4:5], 0, s[52:53]
	v_lshl_add_u64 v[4:5], v[4:5], 0, v[0:1]
	v_add_u32_e32 v48, 48, v54
	global_load_dwordx4 v[22:25], v[4:5], off offset:1024
	v_mad_i64_i32 v[4:5], s[0:1], v48, s60, v[2:3]
	v_lshl_add_u64 v[4:5], v[4:5], 0, s[52:53]
	v_lshl_add_u64 v[4:5], v[4:5], 0, v[0:1]
	v_add_u32_e32 v46, 64, v54
	global_load_dwordx4 v[18:21], v[4:5], off offset:1024
	v_mad_i64_i32 v[4:5], s[0:1], v46, s60, v[2:3]
	v_lshl_add_u64 v[4:5], v[4:5], 0, s[52:53]
	v_lshl_add_u64 v[4:5], v[4:5], 0, v[0:1]
	v_add_u32_e32 v44, 0x50, v54
	global_load_dwordx4 v[14:17], v[4:5], off offset:1024
	v_mad_i64_i32 v[4:5], s[0:1], v44, s60, v[2:3]
	v_lshl_add_u64 v[4:5], v[4:5], 0, s[52:53]
	v_lshl_add_u64 v[4:5], v[4:5], 0, v[0:1]
	v_add_u32_e32 v42, 0x60, v54
	v_add_u32_e32 v38, 0x70, v54
	global_load_dwordx4 v[10:13], v[4:5], off offset:1024
	v_mad_i64_i32 v[4:5], s[0:1], v42, s60, v[2:3]
	v_mad_i64_i32 v[2:3], s[0:1], v38, s60, v[2:3]
	s_add_u32 s0, s10, s52
	s_addc_u32 s1, s11, 0
	v_lshl_add_u64 v[40:41], s[0:1], 0, v[0:1]
	v_lshl_add_u64 v[4:5], v[4:5], 0, s[52:53]
	v_lshl_add_u64 v[2:3], v[2:3], 0, s[52:53]
	v_lshl_add_u64 v[4:5], v[4:5], 0, v[0:1]
	v_lshl_add_u64 v[2:3], v[2:3], 0, v[0:1]
	v_lshlrev_b32_e32 v31, 2, v31
	v_mul_lo_u32 v0, v30, s92
	v_add3_u32 v0, s33, v31, v0
	global_load_dwordx4 v[6:9], v[4:5], off offset:1024
	v_ashrrev_i32_e32 v55, 31, v54
	global_load_dwordx4 v[2:5], v[2:3], off offset:1024
	ds_read_b128 v[34:37], v0
	ds_read_b128 v[30:33], v0 offset:16
	v_ashrrev_i32_e32 v53, 31, v52
	v_ashrrev_i32_e32 v51, 31, v50
	v_ashrrev_i32_e32 v49, 31, v48
	v_ashrrev_i32_e32 v47, 31, v46
	v_ashrrev_i32_e32 v45, 31, v44
	v_ashrrev_i32_e32 v43, 31, v42
	v_ashrrev_i32_e32 v39, 31, v38
	s_add_i32 s16, s16, s71
	s_add_i32 s19, s19, s36
	s_add_i32 s20, s20, s84
	s_cmpk_gt_i32 s16, 0x1ff
	s_waitcnt vmcnt(7)
	v_lshlrev_b32_e32 v60, 16, v56
	v_and_b32_e32 v61, 0xffff0000, v56
	v_lshlrev_b32_e32 v64, 16, v59
	v_and_b32_e32 v56, 0xffff0000, v59
	v_mul_f32_e32 v59, 0xbfb8aa3b, v60
	v_exp_f32_e32 v59, v59
	v_lshlrev_b32_e32 v62, 16, v57
	v_and_b32_e32 v57, 0xffff0000, v57
	v_lshlrev_b32_e32 v63, 16, v58
	v_add_f32_e32 v59, 1.0, v59
	v_and_b32_e32 v58, 0xffff0000, v58
	v_rcp_f32_e32 v65, v59
	s_nop 0
	v_mul_f32_e32 v59, v60, v65
	s_waitcnt lgkmcnt(1)
	v_mul_f32_e32 v34, v59, v34
	v_mul_f32_e32 v59, 0xbfb8aa3b, v61
	v_exp_f32_e32 v59, v59
	s_nop 0
	v_add_f32_e32 v59, 1.0, v59
	v_rcp_f32_e32 v60, v59
	s_nop 0
	v_mul_f32_e32 v59, v61, v60
	v_mul_f32_e32 v35, v59, v35
	v_mul_f32_e32 v59, 0xbfb8aa3b, v62
	v_exp_f32_e32 v59, v59
	s_nop 0
	v_add_f32_e32 v59, 1.0, v59
	v_rcp_f32_e32 v60, v59
	s_nop 0
	v_mul_f32_e32 v59, v62, v60
	v_mul_f32_e32 v36, v59, v36
	v_mul_f32_e32 v59, 0xbfb8aa3b, v57
	v_exp_f32_e32 v59, v59
	s_nop 0
	v_add_f32_e32 v59, 1.0, v59
	v_rcp_f32_e32 v60, v59
	s_nop 0
	v_mul_f32_e32 v57, v57, v60
	v_mul_f32_e32 v37, v57, v37
	v_mul_f32_e32 v57, 0xbfb8aa3b, v63
	v_exp_f32_e32 v57, v57
	s_nop 0
	v_add_f32_e32 v57, 1.0, v57
	v_rcp_f32_e32 v59, v57
	s_nop 0
	v_mul_f32_e32 v57, v63, v59
	s_waitcnt lgkmcnt(0)
; DI float silu(float x) { return x / (1.f + __expf(-x)); }
; DI u32x4 pack8(const float* f) { u32x4 o; o.x = pack2(f[0], f[1]); o.y = pack2(f[2], f[3]); o.z = pack2(f[4], f[5]); o.w = pack2(f[6], f[7]); return o; }
; DI void pw2_tile(PREF p, int l, int idx, unsigned char* ldsb) {
;     ...
;   u32x4 zr[8];
; #pragma unroll
;   for (int q = 0; q < 8; ++q) zr[q] = *(const u32x4*)(p.hb + (size_t)(row0 + (tid >> 4) + 16 * q) * HW + OFF_AZ + col0 + (tid & 15) * 8);
; #pragma unroll
;   for (int q = 0; q < 8; ++q) {
;     int r = (tid >> 4) + 16 * q, c = (tid & 15) * 8;
;     float v[8]; ld8(Cs + r * CST + c, v);
;     float z[8]; unpack8(zr[q], z);
; #pragma unroll
;     for (int j = 0; j < 8; ++j) v[j] *= silu(z[j]);
;     *(u32x4*)(p.ys + (size_t)(row0 + r) * 1024 + col0 + c) = pack8(v);
;   }
	v_mul_f32_e32 v57, v57, v30
	v_mul_f32_e32 v30, 0xbfb8aa3b, v58
	v_exp_f32_e32 v30, v30
	s_nop 0
	v_add_f32_e32 v30, 1.0, v30
	v_rcp_f32_e32 v59, v30
	s_nop 0
	v_mul_f32_e32 v30, v58, v59
	v_mul_f32_e32 v58, v30, v31
	v_mul_f32_e32 v30, 0xbfb8aa3b, v64
	v_exp_f32_e32 v30, v30
	s_nop 0
	v_add_f32_e32 v30, 1.0, v30
	v_rcp_f32_e32 v31, v30
	s_nop 0
	v_mul_f32_e32 v30, v64, v31
	v_mul_f32_e32 v59, v30, v32
	v_mul_f32_e32 v30, 0xbfb8aa3b, v56
	v_exp_f32_e32 v30, v30
	s_nop 0
	v_add_f32_e32 v30, 1.0, v30
	v_rcp_f32_e32 v31, v30
	s_nop 0
	v_mul_f32_e32 v30, v56, v31
	v_mul_f32_e32 v33, v30, v33
	v_cvt_pk_bf16_f32 v30, v34, v35
	v_lshlrev_b64 v[34:35], 11, v[54:55]
	s_waitcnt vmcnt(6)
	v_lshlrev_b32_e32 v54, 16, v26
	v_cvt_pk_bf16_f32 v32, v57, v58
	v_lshlrev_b32_e32 v56, 16, v27
	v_and_b32_e32 v57, 0xffff0000, v27
	v_mul_f32_e32 v27, 0xbfb8aa3b, v54
	v_exp_f32_e32 v27, v27
	v_cvt_pk_bf16_f32 v33, v59, v33
	v_and_b32_e32 v55, 0xffff0000, v26
	v_lshlrev_b32_e32 v59, 16, v29
	v_add_f32_e32 v27, 1.0, v27
	v_and_b32_e32 v26, 0xffff0000, v29
	v_lshl_add_u64 v[34:35], v[40:41], 0, v[34:35]
	v_cvt_pk_bf16_f32 v31, v36, v37
	global_store_dwordx4 v[34:35], v[30:33], off
	v_rcp_f32_e32 v29, v27
	s_nop 0
	v_mul_f32_e32 v27, v54, v29
	v_mul_f32_e32 v29, 0xbfb8aa3b, v55
	v_exp_f32_e32 v29, v29
	ds_read_b128 v[34:37], v0 offset:8448
	ds_read_b128 v[30:33], v0 offset:8464
	v_lshlrev_b32_e32 v58, 16, v28
	v_and_b32_e32 v28, 0xffff0000, v28
	v_add_f32_e32 v29, 1.0, v29
	s_waitcnt lgkmcnt(1)
	v_mul_f32_e32 v27, v27, v34
	v_rcp_f32_e32 v34, v29
	s_nop 0
	v_mul_f32_e32 v29, v55, v34
	v_mul_f32_e32 v34, 0xbfb8aa3b, v56
	v_exp_f32_e32 v34, v34
	v_mul_f32_e32 v29, v29, v35
	v_add_f32_e32 v34, 1.0, v34
	v_rcp_f32_e32 v35, v34
	s_nop 0
	v_mul_f32_e32 v34, v56, v35
	v_mul_f32_e32 v35, 0xbfb8aa3b, v57
	v_exp_f32_e32 v35, v35
	v_mul_f32_e32 v34, v34, v36
	v_add_f32_e32 v35, 1.0, v35
	v_rcp_f32_e32 v36, v35
	s_nop 0
	v_mul_f32_e32 v35, v57, v36
	v_mul_f32_e32 v36, 0xbfb8aa3b, v58
	v_exp_f32_e32 v36, v36
	v_mul_f32_e32 v35, v35, v37
	v_add_f32_e32 v36, 1.0, v36
	v_rcp_f32_e32 v37, v36
	s_nop 0
	v_mul_f32_e32 v36, v58, v37
	s_waitcnt lgkmcnt(0)
	v_mul_f32_e32 v30, v36, v30
	v_mul_f32_e32 v36, 0xbfb8aa3b, v28
	v_exp_f32_e32 v36, v36
	s_nop 0
	v_add_f32_e32 v36, 1.0, v36
	v_rcp_f32_e32 v37, v36
	s_nop 0
	v_mul_f32_e32 v28, v28, v37
	v_mul_f32_e32 v28, v28, v31
	v_mul_f32_e32 v31, 0xbfb8aa3b, v59
	v_exp_f32_e32 v31, v31
	v_cvt_pk_bf16_f32 v28, v30, v28
	s_nop 0
	v_add_f32_e32 v31, 1.0, v31
	v_rcp_f32_e32 v36, v31
	s_nop 0
	v_mul_f32_e32 v31, v59, v36
	v_mul_f32_e32 v31, v31, v32
	v_mul_f32_e32 v32, 0xbfb8aa3b, v26
	v_exp_f32_e32 v32, v32
	s_nop 0
	v_add_f32_e32 v32, 1.0, v32
	v_rcp_f32_e32 v36, v32
	s_nop 0
	v_mul_f32_e32 v26, v26, v36
	v_mul_f32_e32 v32, v26, v33
	v_cvt_pk_bf16_f32 v26, v27, v29
	v_cvt_pk_bf16_f32 v27, v34, v35
	s_waitcnt vmcnt(6)
	v_lshlrev_b32_e32 v34, 16, v22
	v_lshlrev_b32_e32 v36, 16, v23
	v_and_b32_e32 v37, 0xffff0000, v23
	v_mul_f32_e32 v23, 0xbfb8aa3b, v34
	v_exp_f32_e32 v23, v23
	v_cvt_pk_bf16_f32 v29, v31, v32
	v_lshlrev_b64 v[30:31], 11, v[52:53]
	v_and_b32_e32 v35, 0xffff0000, v22
	v_add_f32_e32 v23, 1.0, v23
	v_lshlrev_b32_e32 v53, 16, v25
	v_and_b32_e32 v22, 0xffff0000, v25
	v_lshl_add_u64 v[30:31], v[40:41], 0, v[30:31]
	global_store_dwordx4 v[30:31], v[26:29], off
	ds_read_b128 v[30:33], v0 offset:16896
	ds_read_b128 v[26:29], v0 offset:16912
	v_rcp_f32_e32 v25, v23
	s_nop 0
	v_mul_f32_e32 v23, v34, v25
	v_mul_f32_e32 v25, 0xbfb8aa3b, v35
	v_exp_f32_e32 v25, v25
	s_waitcnt lgkmcnt(1)
	v_mul_f32_e32 v23, v23, v30
	v_lshlrev_b32_e32 v52, 16, v24
	v_and_b32_e32 v24, 0xffff0000, v24
	v_add_f32_e32 v25, 1.0, v25
	v_rcp_f32_e32 v30, v25
	s_nop 0
	v_mul_f32_e32 v25, v35, v30
	v_mul_f32_e32 v30, 0xbfb8aa3b, v36
	v_exp_f32_e32 v30, v30
	v_mul_f32_e32 v25, v25, v31
	v_add_f32_e32 v30, 1.0, v30
	v_rcp_f32_e32 v31, v30
	s_nop 0
	v_mul_f32_e32 v30, v36, v31
	v_mul_f32_e32 v31, 0xbfb8aa3b, v37
	v_exp_f32_e32 v31, v31
	v_mul_f32_e32 v30, v30, v32
	v_add_f32_e32 v31, 1.0, v31
	v_rcp_f32_e32 v32, v31
	s_nop 0
	v_mul_f32_e32 v31, v37, v32
	v_mul_f32_e32 v32, 0xbfb8aa3b, v52
	v_exp_f32_e32 v32, v32
	v_mul_f32_e32 v31, v31, v33
	v_add_f32_e32 v32, 1.0, v32
	v_rcp_f32_e32 v33, v32
	s_nop 0
	v_mul_f32_e32 v32, v52, v33
	s_waitcnt lgkmcnt(0)
	v_mul_f32_e32 v26, v32, v26
	v_mul_f32_e32 v32, 0xbfb8aa3b, v24
	v_exp_f32_e32 v32, v32
	s_nop 0
	v_add_f32_e32 v32, 1.0, v32
	v_rcp_f32_e32 v33, v32
	s_nop 0
	v_mul_f32_e32 v24, v24, v33
	v_mul_f32_e32 v24, v24, v27
	v_mul_f32_e32 v27, 0xbfb8aa3b, v53
	v_exp_f32_e32 v27, v27
	v_cvt_pk_bf16_f32 v24, v26, v24
	s_nop 0
	v_add_f32_e32 v27, 1.0, v27
	v_rcp_f32_e32 v32, v27
	s_nop 0
	v_mul_f32_e32 v27, v53, v32
	v_mul_f32_e32 v27, v27, v28
	v_mul_f32_e32 v28, 0xbfb8aa3b, v22
	v_exp_f32_e32 v28, v28
	s_nop 0
	v_add_f32_e32 v28, 1.0, v28
	v_rcp_f32_e32 v32, v28
	s_nop 0
	v_mul_f32_e32 v22, v22, v32
	v_mul_f32_e32 v28, v22, v29
	v_cvt_pk_bf16_f32 v22, v23, v25
	v_cvt_pk_bf16_f32 v23, v30, v31
	s_waitcnt vmcnt(6)
	v_lshlrev_b32_e32 v30, 16, v18
	v_lshlrev_b32_e32 v32, 16, v19
	v_and_b32_e32 v33, 0xffff0000, v19
	v_mul_f32_e32 v19, 0xbfb8aa3b, v30
	v_exp_f32_e32 v19, v19
	v_and_b32_e32 v31, 0xffff0000, v18
	v_lshlrev_b32_e32 v35, 16, v21
	v_and_b32_e32 v18, 0xffff0000, v21
	v_add_f32_e32 v19, 1.0, v19
	v_cvt_pk_bf16_f32 v25, v27, v28
	v_lshlrev_b64 v[26:27], 11, v[50:51]
	v_lshl_add_u64 v[26:27], v[40:41], 0, v[26:27]
	v_rcp_f32_e32 v21, v19
	s_nop 0
	v_mul_f32_e32 v19, v30, v21
	v_mul_f32_e32 v21, 0xbfb8aa3b, v31
	global_store_dwordx4 v[26:27], v[22:25], off
	v_exp_f32_e32 v21, v21
	ds_read_b128 v[26:29], v0 offset:25344
	ds_read_b128 v[22:25], v0 offset:25360
	v_lshlrev_b32_e32 v34, 16, v20
	v_and_b32_e32 v20, 0xffff0000, v20
	v_add_f32_e32 v21, 1.0, v21
	s_waitcnt lgkmcnt(1)
; DI float silu(float x) { return x / (1.f + __expf(-x)); }
; DI u32x4 pack8(const float* f) { u32x4 o; o.x = pack2(f[0], f[1]); o.y = pack2(f[2], f[3]); o.z = pack2(f[4], f[5]); o.w = pack2(f[6], f[7]); return o; }
; DI void pw2_tile(PREF p, int l, int idx, unsigned char* ldsb) {
;     ...
;   u32x4 zr[8];
; #pragma unroll
;   for (int q = 0; q < 8; ++q) zr[q] = *(const u32x4*)(p.hb + (size_t)(row0 + (tid >> 4) + 16 * q) * HW + OFF_AZ + col0 + (tid & 15) * 8);
; #pragma unroll
;   for (int q = 0; q < 8; ++q) {
;     int r = (tid >> 4) + 16 * q, c = (tid & 15) * 8;
;     float v[8]; ld8(Cs + r * CST + c, v);
;     float z[8]; unpack8(zr[q], z);
; #pragma unroll
;     for (int j = 0; j < 8; ++j) v[j] *= silu(z[j]);
;     *(u32x4*)(p.ys + (size_t)(row0 + r) * 1024 + col0 + c) = pack8(v);
;   }
	v_mul_f32_e32 v19, v19, v26
	v_rcp_f32_e32 v26, v21
	s_nop 0
	v_mul_f32_e32 v21, v31, v26
	v_mul_f32_e32 v26, 0xbfb8aa3b, v32
	v_exp_f32_e32 v26, v26
	v_mul_f32_e32 v21, v21, v27
	v_add_f32_e32 v26, 1.0, v26
	v_rcp_f32_e32 v27, v26
	s_nop 0
	v_mul_f32_e32 v26, v32, v27
	v_mul_f32_e32 v27, 0xbfb8aa3b, v33
	v_exp_f32_e32 v27, v27
	v_mul_f32_e32 v26, v26, v28
	v_add_f32_e32 v27, 1.0, v27
	v_rcp_f32_e32 v28, v27
	s_nop 0
	v_mul_f32_e32 v27, v33, v28
	v_mul_f32_e32 v28, 0xbfb8aa3b, v34
	v_exp_f32_e32 v28, v28
	v_mul_f32_e32 v27, v27, v29
	v_add_f32_e32 v28, 1.0, v28
	v_rcp_f32_e32 v29, v28
	s_nop 0
	v_mul_f32_e32 v28, v34, v29
	s_waitcnt lgkmcnt(0)
	v_mul_f32_e32 v22, v28, v22
	v_mul_f32_e32 v28, 0xbfb8aa3b, v20
	v_exp_f32_e32 v28, v28
	s_nop 0
	v_add_f32_e32 v28, 1.0, v28
	v_rcp_f32_e32 v29, v28
	s_nop 0
	v_mul_f32_e32 v20, v20, v29
	v_mul_f32_e32 v20, v20, v23
	v_mul_f32_e32 v23, 0xbfb8aa3b, v35
	v_exp_f32_e32 v23, v23
	v_cvt_pk_bf16_f32 v20, v22, v20
	s_nop 0
	v_add_f32_e32 v23, 1.0, v23
	v_rcp_f32_e32 v28, v23
	s_nop 0
	v_mul_f32_e32 v23, v35, v28
	v_mul_f32_e32 v23, v23, v24
	v_mul_f32_e32 v24, 0xbfb8aa3b, v18
	v_exp_f32_e32 v24, v24
	s_nop 0
	v_add_f32_e32 v24, 1.0, v24
	v_rcp_f32_e32 v28, v24
	s_nop 0
	v_mul_f32_e32 v18, v18, v28
	v_mul_f32_e32 v24, v18, v25
	v_cvt_pk_bf16_f32 v18, v19, v21
	v_cvt_pk_bf16_f32 v19, v26, v27
	s_waitcnt vmcnt(6)
	v_lshlrev_b32_e32 v26, 16, v14
	v_lshlrev_b32_e32 v28, 16, v15
	v_and_b32_e32 v29, 0xffff0000, v15
	v_mul_f32_e32 v15, 0xbfb8aa3b, v26
	v_exp_f32_e32 v15, v15
	v_and_b32_e32 v27, 0xffff0000, v14
	v_lshlrev_b32_e32 v31, 16, v17
	v_and_b32_e32 v14, 0xffff0000, v17
	v_add_f32_e32 v15, 1.0, v15
	v_cvt_pk_bf16_f32 v21, v23, v24
	v_lshlrev_b64 v[22:23], 11, v[48:49]
	v_lshl_add_u64 v[22:23], v[40:41], 0, v[22:23]
	v_rcp_f32_e32 v17, v15
	s_nop 0
	v_mul_f32_e32 v15, v26, v17
	v_mul_f32_e32 v17, 0xbfb8aa3b, v27
	global_store_dwordx4 v[22:23], v[18:21], off
	v_exp_f32_e32 v17, v17
	ds_read_b128 v[22:25], v0 offset:33792
	ds_read_b128 v[18:21], v0 offset:33808
	v_lshlrev_b32_e32 v30, 16, v16
	v_and_b32_e32 v16, 0xffff0000, v16
	v_add_f32_e32 v17, 1.0, v17
	s_waitcnt lgkmcnt(1)
	v_mul_f32_e32 v15, v15, v22
	v_rcp_f32_e32 v22, v17
	s_nop 0
	v_mul_f32_e32 v17, v27, v22
	v_mul_f32_e32 v22, 0xbfb8aa3b, v28
	v_exp_f32_e32 v22, v22
	v_mul_f32_e32 v17, v17, v23
	v_add_f32_e32 v22, 1.0, v22
	v_rcp_f32_e32 v23, v22
	s_nop 0
	v_mul_f32_e32 v22, v28, v23
	v_mul_f32_e32 v23, 0xbfb8aa3b, v29
	v_exp_f32_e32 v23, v23
	v_mul_f32_e32 v22, v22, v24
	v_add_f32_e32 v23, 1.0, v23
	v_rcp_f32_e32 v24, v23
	s_nop 0
	v_mul_f32_e32 v23, v29, v24
	v_mul_f32_e32 v24, 0xbfb8aa3b, v30
	v_exp_f32_e32 v24, v24
	v_mul_f32_e32 v23, v23, v25
	v_add_f32_e32 v24, 1.0, v24
	v_rcp_f32_e32 v25, v24
	s_nop 0
	v_mul_f32_e32 v24, v30, v25
	s_waitcnt lgkmcnt(0)
	v_mul_f32_e32 v18, v24, v18
	v_mul_f32_e32 v24, 0xbfb8aa3b, v16
	v_exp_f32_e32 v24, v24
	s_nop 0
	v_add_f32_e32 v24, 1.0, v24
	v_rcp_f32_e32 v25, v24
	s_nop 0
	v_mul_f32_e32 v16, v16, v25
	v_mul_f32_e32 v16, v16, v19
	v_mul_f32_e32 v19, 0xbfb8aa3b, v31
	v_exp_f32_e32 v19, v19
	v_cvt_pk_bf16_f32 v16, v18, v16
	s_nop 0
	v_add_f32_e32 v19, 1.0, v19
	v_rcp_f32_e32 v24, v19
	s_nop 0
	v_mul_f32_e32 v19, v31, v24
	v_mul_f32_e32 v19, v19, v20
	v_mul_f32_e32 v20, 0xbfb8aa3b, v14
	v_exp_f32_e32 v20, v20
	s_nop 0
	v_add_f32_e32 v20, 1.0, v20
	v_rcp_f32_e32 v24, v20
	s_nop 0
	v_mul_f32_e32 v14, v14, v24
	v_mul_f32_e32 v20, v14, v21
	v_cvt_pk_bf16_f32 v14, v15, v17
	v_cvt_pk_bf16_f32 v15, v22, v23
	s_waitcnt vmcnt(6)
	v_lshlrev_b32_e32 v22, 16, v10
	v_lshlrev_b32_e32 v24, 16, v11
	v_and_b32_e32 v25, 0xffff0000, v11
	v_mul_f32_e32 v11, 0xbfb8aa3b, v22
	v_exp_f32_e32 v11, v11
	v_and_b32_e32 v23, 0xffff0000, v10
	v_lshlrev_b32_e32 v27, 16, v13
	v_and_b32_e32 v10, 0xffff0000, v13
	v_add_f32_e32 v11, 1.0, v11
	v_cvt_pk_bf16_f32 v17, v19, v20
	v_lshlrev_b64 v[18:19], 11, v[46:47]
	v_lshl_add_u64 v[18:19], v[40:41], 0, v[18:19]
	v_rcp_f32_e32 v13, v11
	s_nop 0
	v_mul_f32_e32 v11, v22, v13
	v_mul_f32_e32 v13, 0xbfb8aa3b, v23
	global_store_dwordx4 v[18:19], v[14:17], off
	v_exp_f32_e32 v13, v13
	ds_read_b128 v[18:21], v0 offset:42240
	ds_read_b128 v[14:17], v0 offset:42256
	v_lshlrev_b32_e32 v26, 16, v12
	v_and_b32_e32 v12, 0xffff0000, v12
	v_add_f32_e32 v13, 1.0, v13
	s_waitcnt lgkmcnt(1)
	v_mul_f32_e32 v11, v11, v18
	v_rcp_f32_e32 v18, v13
	s_nop 0
	v_mul_f32_e32 v13, v23, v18
	v_mul_f32_e32 v18, 0xbfb8aa3b, v24
	v_exp_f32_e32 v18, v18
	v_mul_f32_e32 v13, v13, v19
	v_add_f32_e32 v18, 1.0, v18
	v_rcp_f32_e32 v19, v18
	s_nop 0
	v_mul_f32_e32 v18, v24, v19
	v_mul_f32_e32 v19, 0xbfb8aa3b, v25
	v_exp_f32_e32 v19, v19
	v_mul_f32_e32 v18, v18, v20
	v_add_f32_e32 v19, 1.0, v19
	v_rcp_f32_e32 v20, v19
	s_nop 0
	v_mul_f32_e32 v19, v25, v20
	v_mul_f32_e32 v20, 0xbfb8aa3b, v26
	v_exp_f32_e32 v20, v20
	v_mul_f32_e32 v19, v19, v21
	v_add_f32_e32 v20, 1.0, v20
	v_rcp_f32_e32 v21, v20
	s_nop 0
	v_mul_f32_e32 v20, v26, v21
	s_waitcnt lgkmcnt(0)
; DI float silu(float x) { return x / (1.f + __expf(-x)); }
; DI u32x4 pack8(const float* f) { u32x4 o; o.x = pack2(f[0], f[1]); o.y = pack2(f[2], f[3]); o.z = pack2(f[4], f[5]); o.w = pack2(f[6], f[7]); return o; }
; DI void pw2_tile(PREF p, int l, int idx, unsigned char* ldsb) {
;     ...
;   u32x4 zr[8];
; #pragma unroll
;   for (int q = 0; q < 8; ++q) zr[q] = *(const u32x4*)(p.hb + (size_t)(row0 + (tid >> 4) + 16 * q) * HW + OFF_AZ + col0 + (tid & 15) * 8);
; #pragma unroll
;   for (int q = 0; q < 8; ++q) {
;     int r = (tid >> 4) + 16 * q, c = (tid & 15) * 8;
;     float v[8]; ld8(Cs + r * CST + c, v);
;     float z[8]; unpack8(zr[q], z);
; #pragma unroll
;     for (int j = 0; j < 8; ++j) v[j] *= silu(z[j]);
;     *(u32x4*)(p.ys + (size_t)(row0 + r) * 1024 + col0 + c) = pack8(v);
;   }
	v_mul_f32_e32 v14, v20, v14
	v_mul_f32_e32 v20, 0xbfb8aa3b, v12
	v_exp_f32_e32 v20, v20
	s_nop 0
	v_add_f32_e32 v20, 1.0, v20
	v_rcp_f32_e32 v21, v20
	s_nop 0
	v_mul_f32_e32 v12, v12, v21
	v_mul_f32_e32 v12, v12, v15
	v_mul_f32_e32 v15, 0xbfb8aa3b, v27
	v_exp_f32_e32 v15, v15
	v_cvt_pk_bf16_f32 v12, v14, v12
	s_nop 0
	v_add_f32_e32 v15, 1.0, v15
	v_rcp_f32_e32 v20, v15
	s_nop 0
	v_mul_f32_e32 v15, v27, v20
	v_mul_f32_e32 v15, v15, v16
	v_mul_f32_e32 v16, 0xbfb8aa3b, v10
	v_exp_f32_e32 v16, v16
	s_nop 0
	v_add_f32_e32 v16, 1.0, v16
	v_rcp_f32_e32 v20, v16
	s_nop 0
	v_mul_f32_e32 v10, v10, v20
	v_mul_f32_e32 v16, v10, v17
	v_cvt_pk_bf16_f32 v10, v11, v13
	v_cvt_pk_bf16_f32 v11, v18, v19
	s_waitcnt vmcnt(6)
	v_lshlrev_b32_e32 v18, 16, v6
	v_lshlrev_b32_e32 v20, 16, v7
	v_and_b32_e32 v21, 0xffff0000, v7
	v_mul_f32_e32 v7, 0xbfb8aa3b, v18
	v_exp_f32_e32 v7, v7
	v_and_b32_e32 v19, 0xffff0000, v6
	v_lshlrev_b32_e32 v23, 16, v9
	v_and_b32_e32 v6, 0xffff0000, v9
	v_add_f32_e32 v7, 1.0, v7
	v_cvt_pk_bf16_f32 v13, v15, v16
	v_lshlrev_b64 v[14:15], 11, v[44:45]
	v_lshl_add_u64 v[14:15], v[40:41], 0, v[14:15]
	v_rcp_f32_e32 v9, v7
	s_nop 0
	v_mul_f32_e32 v7, v18, v9
	v_mul_f32_e32 v9, 0xbfb8aa3b, v19
	global_store_dwordx4 v[14:15], v[10:13], off
	v_exp_f32_e32 v9, v9
	ds_read_b128 v[14:17], v0 offset:50688
	ds_read_b128 v[10:13], v0 offset:50704
	v_lshlrev_b32_e32 v22, 16, v8
	v_and_b32_e32 v8, 0xffff0000, v8
	v_add_f32_e32 v9, 1.0, v9
	s_waitcnt lgkmcnt(1)
	v_mul_f32_e32 v7, v7, v14
	v_rcp_f32_e32 v14, v9
	s_nop 0
	v_mul_f32_e32 v9, v19, v14
	v_mul_f32_e32 v14, 0xbfb8aa3b, v20
	v_exp_f32_e32 v14, v14
	v_mul_f32_e32 v9, v9, v15
	v_add_f32_e32 v14, 1.0, v14
	v_rcp_f32_e32 v15, v14
	s_nop 0
	v_mul_f32_e32 v14, v20, v15
	v_mul_f32_e32 v15, 0xbfb8aa3b, v21
	v_exp_f32_e32 v15, v15
	v_mul_f32_e32 v14, v14, v16
	v_add_f32_e32 v15, 1.0, v15
	v_rcp_f32_e32 v16, v15
	s_nop 0
	v_mul_f32_e32 v15, v21, v16
	v_mul_f32_e32 v16, 0xbfb8aa3b, v22
	v_exp_f32_e32 v16, v16
	v_mul_f32_e32 v15, v15, v17
	v_add_f32_e32 v16, 1.0, v16
	v_rcp_f32_e32 v17, v16
	s_nop 0
	v_mul_f32_e32 v16, v22, v17
	s_waitcnt lgkmcnt(0)
	v_mul_f32_e32 v10, v16, v10
	v_mul_f32_e32 v16, 0xbfb8aa3b, v8
	v_exp_f32_e32 v16, v16
	s_nop 0
	v_add_f32_e32 v16, 1.0, v16
	v_rcp_f32_e32 v17, v16
	s_nop 0
	v_mul_f32_e32 v8, v8, v17
	v_mul_f32_e32 v8, v8, v11
	v_mul_f32_e32 v11, 0xbfb8aa3b, v23
	v_exp_f32_e32 v11, v11
	v_cvt_pk_bf16_f32 v8, v10, v8
	s_nop 0
	v_add_f32_e32 v11, 1.0, v11
	v_rcp_f32_e32 v16, v11
	s_nop 0
	v_mul_f32_e32 v11, v23, v16
	v_mul_f32_e32 v11, v11, v12
	v_mul_f32_e32 v12, 0xbfb8aa3b, v6
	v_exp_f32_e32 v12, v12
	s_nop 0
	v_add_f32_e32 v12, 1.0, v12
	v_rcp_f32_e32 v16, v12
	s_nop 0
	v_mul_f32_e32 v6, v6, v16
	v_mul_f32_e32 v12, v6, v13
	v_cvt_pk_bf16_f32 v6, v7, v9
	v_cvt_pk_bf16_f32 v7, v14, v15
	s_waitcnt vmcnt(6)
	v_lshlrev_b32_e32 v14, 16, v2
	v_and_b32_e32 v15, 0xffff0000, v2
	v_mul_f32_e32 v2, 0xbfb8aa3b, v14
	v_exp_f32_e32 v2, v2
	v_cvt_pk_bf16_f32 v9, v11, v12
	v_lshlrev_b64 v[10:11], 11, v[42:43]
	v_lshl_add_u64 v[10:11], v[40:41], 0, v[10:11]
	global_store_dwordx4 v[10:11], v[6:9], off
	v_add_f32_e32 v2, 1.0, v2
	ds_read_b128 v[10:13], v0 offset:59136
	ds_read_b128 v[6:9], v0 offset:59152
	v_lshlrev_b32_e32 v18, 16, v5
	v_and_b32_e32 v0, 0xffff0000, v5
	v_lshlrev_b32_e32 v16, 16, v3
	v_and_b32_e32 v3, 0xffff0000, v3
	v_lshlrev_b32_e32 v17, 16, v4
	v_rcp_f32_e32 v5, v2
	s_nop 0
	v_mul_f32_e32 v2, v14, v5
	v_mul_f32_e32 v5, 0xbfb8aa3b, v15
	v_exp_f32_e32 v5, v5
	s_waitcnt lgkmcnt(1)
	v_mul_f32_e32 v2, v2, v10
	v_and_b32_e32 v4, 0xffff0000, v4
	v_add_f32_e32 v5, 1.0, v5
	v_rcp_f32_e32 v10, v5
	s_nop 0
	v_mul_f32_e32 v5, v15, v10
	v_mul_f32_e32 v10, 0xbfb8aa3b, v16
	v_exp_f32_e32 v10, v10
	v_mul_f32_e32 v5, v5, v11
	v_cvt_pk_bf16_f32 v2, v2, v5
	v_add_f32_e32 v10, 1.0, v10
	v_rcp_f32_e32 v11, v10
	s_nop 0
	v_mul_f32_e32 v10, v16, v11
	v_mul_f32_e32 v11, 0xbfb8aa3b, v3
	v_exp_f32_e32 v11, v11
	v_mul_f32_e32 v10, v10, v12
	v_add_f32_e32 v11, 1.0, v11
	v_rcp_f32_e32 v12, v11
	s_nop 0
	v_mul_f32_e32 v3, v3, v12
	v_mul_f32_e32 v11, 0xbfb8aa3b, v17
	v_exp_f32_e32 v11, v11
	v_mul_f32_e32 v3, v3, v13
	v_cvt_pk_bf16_f32 v3, v10, v3
	v_add_f32_e32 v11, 1.0, v11
	v_rcp_f32_e32 v12, v11
	s_nop 0
	v_mul_f32_e32 v11, v17, v12
	s_waitcnt lgkmcnt(0)
	v_mul_f32_e32 v6, v11, v6
	v_mul_f32_e32 v11, 0xbfb8aa3b, v4
	v_exp_f32_e32 v11, v11
	s_nop 0
	v_add_f32_e32 v11, 1.0, v11
	v_rcp_f32_e32 v12, v11
	s_nop 0
	v_mul_f32_e32 v4, v4, v12
	v_mul_f32_e32 v4, v4, v7
	v_mul_f32_e32 v7, 0xbfb8aa3b, v18
	v_exp_f32_e32 v7, v7
	v_cvt_pk_bf16_f32 v4, v6, v4
	s_nop 0
	v_add_f32_e32 v7, 1.0, v7
	v_rcp_f32_e32 v11, v7
	s_nop 0
	v_mul_f32_e32 v7, v18, v11
	v_mul_f32_e32 v7, v7, v8
	v_mul_f32_e32 v8, 0xbfb8aa3b, v0
	v_exp_f32_e32 v8, v8
	s_nop 0
	v_add_f32_e32 v8, 1.0, v8
	v_rcp_f32_e32 v11, v8
	s_nop 0
	v_mul_f32_e32 v0, v0, v11
	v_mul_f32_e32 v0, v0, v9
	v_cvt_pk_bf16_f32 v5, v7, v0
	v_lshlrev_b64 v[6:7], 11, v[38:39]
	v_lshl_add_u64 v[6:7], v[40:41], 0, v[6:7]
	global_store_dwordx4 v[6:7], v[2:5], off
	s_cbranch_scc0 .LBB0_265

; DI u32x4 pack8(const float* f) { u32x4 o; o.x = pack2(f[0], f[1]); o.y = pack2(f[2], f[3]); o.z = pack2(f[4], f[5]); o.w = pack2(f[6], f[7]); return o; }
; DI void ssm2_item(PREF p, int l, int item, unsigned char* ldsb) {
;     ...
;   const int hcol = lane & 15, q4 = lane >> 4;
;   bf16x8 cf[4];
;   {
;     const float* cre = p.c_re + ((size_t)(l * 16 + g) * 16 + hcol) * 64;
;     const float* cim = p.c_im + ((size_t)(l * 16 + g) * 16 + hcol) * 64;
; #pragma unroll
;     for (int ks = 0; ks < 4; ++ks) {
;       float v[8];
; #pragma unroll
;       for (int j = 0; j < 8; ++j) {
;         int k = 32 * ks + 8 * q4 + j;
;         v[j] = (k & 1) ? -cim[k >> 1] : cre[k >> 1];
;       }
;       union { bf16x8 v8; u32x4 u; } cv; cv.u = pack8(v); cf[ks] = cv.v8;
;     }
;   }
;   const float dch = p.ssm_d[l * 256 + g * 16 + hcol];
.LBB0_303:
	v_and_b32_e32 v62, 15, v79
	v_lshlrev_b64 v[22:23], 12, v[22:23]
	v_lshrrev_b32_e32 v0, 2, v79
	v_lshl_or_b32 v22, v62, 8, v22
	v_and_b32_e32 v64, 12, v0
	v_lshl_add_u64 v[26:27], s[46:47], 0, v[22:23]
	v_lshlrev_b32_e32 v0, 2, v64
	v_lshl_add_u64 v[58:59], v[26:27], 0, v[0:1]
	global_load_dwordx4 v[26:29], v[58:59], off
	v_lshl_add_u64 v[24:25], s[44:45], 0, v[22:23]
	v_lshl_add_u64 v[54:55], v[24:25], 0, v[0:1]
	global_load_dwordx4 v[22:25], v[54:55], off
	s_movk_i32 s0, 0x1100
	v_mul_lo_u32 v66, v80, s0
	v_add_u32_e32 v56, s33, v66
	v_and_b32_e32 v68, 48, v79
	s_waitcnt vmcnt(4)
	v_mov_b32_e32 v63, v14
	v_mov_b32_e32 v14, v3
	s_mov_b32 s8, 0
	s_waitcnt vmcnt(1)
	v_xor_b32_e32 v0, 0x80000000, v26
	v_xor_b32_e32 v26, 0x80000000, v27
	v_xor_b32_e32 v27, 0x80000000, v28
	v_xor_b32_e32 v28, 0x80000000, v29
	s_waitcnt vmcnt(0)
	v_cvt_pk_bf16_f32 v23, v23, v26
	v_cvt_pk_bf16_f32 v24, v24, v27
	v_cvt_pk_bf16_f32 v25, v25, v28
	global_load_dwordx4 v[26:29], v[54:55], off offset:64
	global_load_dwordx4 v[30:33], v[58:59], off offset:64
	v_cvt_pk_bf16_f32 v22, v22, v0
	s_waitcnt vmcnt(0)
	v_xor_b32_e32 v0, 0x80000000, v30
	v_xor_b32_e32 v30, 0x80000000, v31
	v_xor_b32_e32 v31, 0x80000000, v32
	v_xor_b32_e32 v32, 0x80000000, v33
	v_cvt_pk_bf16_f32 v27, v27, v30
	v_cvt_pk_bf16_f32 v28, v28, v31
	v_cvt_pk_bf16_f32 v29, v29, v32
	global_load_dwordx4 v[30:33], v[54:55], off offset:128
	global_load_dwordx4 v[34:37], v[58:59], off offset:128
	v_cvt_pk_bf16_f32 v26, v26, v0
	s_waitcnt vmcnt(0)
	v_xor_b32_e32 v0, 0x80000000, v34
	v_xor_b32_e32 v34, 0x80000000, v35
	v_xor_b32_e32 v35, 0x80000000, v36
	v_xor_b32_e32 v36, 0x80000000, v37
	v_cvt_pk_bf16_f32 v31, v31, v34
	v_cvt_pk_bf16_f32 v32, v32, v35
	v_cvt_pk_bf16_f32 v33, v33, v36
	global_load_dwordx4 v[34:37], v[54:55], off offset:192
	s_nop 0
	global_load_dwordx4 v[58:61], v[58:59], off offset:192
	s_load_dwordx2 s[0:1], s[10:11], 0xa8
	v_cvt_pk_bf16_f32 v30, v30, v0
	s_waitcnt vmcnt(0)
	v_xor_b32_e32 v0, 0x80000000, v58
	v_lshlrev_b32_e32 v58, 4, v81
	v_xor_b32_e32 v54, 0x80000000, v59
	v_cvt_pk_bf16_f32 v34, v34, v0
	v_add_u32_e32 v0, s56, v58
	v_xor_b32_e32 v55, 0x80000000, v60
	v_cvt_pk_bf16_f32 v35, v35, v54
	v_or_b32_e32 v54, v0, v62
	v_cvt_pk_bf16_f32 v36, v36, v55
	v_ashrrev_i32_e32 v55, 31, v54
	s_waitcnt lgkmcnt(0)
	v_lshl_add_u64 v[54:55], v[54:55], 2, s[0:1]
	global_load_dword v65, v[54:55], off
	v_xor_b32_e32 v57, 0x80000000, v61
	s_movk_i32 s0, 0xef40
	v_mad_u64_u32 v[54:55], s[0:1], v80, s0, v[56:57]
	s_movk_i32 s0, 0x110
	s_nop 0
	v_mad_u32_u24 v67, v62, s0, v56
	s_load_dwordx2 s[0:1], s[10:11], 0x178
	v_ashrrev_i32_e32 v59, 31, v58
	v_cvt_pk_bf16_f32 v37, v37, v57
	v_lshlrev_b32_e32 v0, 1, v62
	v_mov_b32_e32 v60, v46
	s_waitcnt lgkmcnt(0)
	v_lshl_add_u64 v[56:57], v[58:59], 1, s[0:1]
	v_mov_b32_e32 v58, v5
	v_mov_b32_e32 v5, v16
	v_mov_b32_e32 v16, v38
	v_lshl_or_b32 v38, v78, 2, v66
	v_readlane_b32 s0, v254, 24
	v_lshl_add_u64 v[56:57], v[56:57], 0, v[0:1]
	v_lshl_add_u32 v0, v62, 2, v54
	v_mov_b32_e32 v59, v17
	v_mov_b32_e32 v61, v10
	v_mov_b32_e32 v10, v47
	v_mov_b32_e32 v46, v48
	v_mov_b32_e32 v47, v12
	v_mov_b32_e32 v12, v49
	v_mov_b32_e32 v48, v42
	v_mov_b32_e32 v49, v6
	v_mov_b32_e32 v6, v43
	v_mov_b32_e32 v42, v44
	v_mov_b32_e32 v43, v8
	v_mov_b32_e32 v8, v45
	v_mov_b32_e32 v17, v18
	v_mov_b32_e32 v18, v39
	v_mov_b32_e32 v44, v40
	v_mov_b32_e32 v45, v20
	v_mov_b32_e32 v20, v41
	v_mov_b32_e32 v62, v2
	v_pk_mov_b32 v[2:3], v[50:51], v[50:51] op_sel:[1,0]
	v_add_u32_e32 v55, s0, v38
	v_add_u32_e32 v66, v67, v68
	s_waitcnt vmcnt(0)

; DI unsigned pack2(float a, float b) { unsigned r; asm("v_cvt_pk_bf16_f32 %0, %1, %2\n\ts_nop 1" : "=v"(r) : "v"(a), "v"(b)); return r; }
; DI void ssm2_item(PREF p, int l, int item, unsigned char* ldsb) {
;     ...
;   for (int sub = 0; sub < 4; ++sub) {
;     for (int tt = 0; tt < 16; ++tt) {
;       SSM_STEP(sub * 16 + tt)
;       *(unsigned*)(Hs + tt * 136 + 2 * lane) = pack2(hr, hi);
;     }
.LBB0_305:
	v_add_u32_e32 v39, s9, v54
	ds_read_b128 v[68:71], v39
	ds_read_b128 v[72:75], v39 offset:16
	ds_read_b128 v[76:79], v39 offset:32
	ds_read_b128 v[80:83], v39 offset:48
	s_addk_i32 s9, 0x200
	s_waitcnt lgkmcnt(3)
	v_pk_fma_f32 v[40:41], v[16:17], v[68:69], 0 op_sel_hi:[1,0,0]
	s_cmpk_eq_i32 s9, 0x1000
	v_pk_fma_f32 v[40:41], v[18:19], v[68:69], v[40:41] op_sel:[0,1,0]
	v_mov_b32_e32 v68, v71
	v_pk_fma_f32 v[40:41], v[44:45], v[70:71], v[40:41] op_sel_hi:[1,0,1]
	s_waitcnt lgkmcnt(2)
	v_mov_b32_e32 v70, v75
	v_pk_fma_f32 v[40:41], v[20:21], v[68:69], v[40:41] op_sel_hi:[1,0,1]
	v_pk_mul_f32 v[68:69], v[2:3], v[52:53] op_sel:[0,1]
	v_pk_fma_f32 v[40:41], v[62:63], v[72:73], v[40:41] op_sel_hi:[1,0,1]
	s_nop 0
	v_pk_fma_f32 v[40:41], v[14:15], v[72:73], v[40:41] op_sel:[0,1,0]
	s_nop 0
	v_pk_fma_f32 v[40:41], v[4:5], v[74:75], v[40:41] op_sel_hi:[1,0,1]
	s_nop 0
	v_pk_fma_f32 v[40:41], v[58:59], v[70:71], v[40:41] op_sel_hi:[1,0,1]
	s_waitcnt lgkmcnt(1)
	v_mov_b32_e32 v70, v79
	v_pk_fma_f32 v[40:41], v[60:61], v[76:77], v[40:41] op_sel_hi:[1,0,1]
	s_nop 0
	v_pk_fma_f32 v[40:41], v[10:11], v[76:77], v[40:41] op_sel:[0,1,0]
	s_nop 0
	v_pk_fma_f32 v[40:41], v[46:47], v[78:79], v[40:41] op_sel_hi:[1,0,1]
	s_nop 0
	v_pk_fma_f32 v[40:41], v[12:13], v[70:71], v[40:41] op_sel_hi:[1,0,1]
	s_waitcnt lgkmcnt(0)
	v_mov_b32_e32 v70, v83
	v_pk_fma_f32 v[40:41], v[48:49], v[80:81], v[40:41] op_sel_hi:[1,0,1]
	s_nop 0
	v_pk_fma_f32 v[40:41], v[6:7], v[80:81], v[40:41] op_sel:[0,1,0]
	s_nop 0
	v_pk_fma_f32 v[40:41], v[42:43], v[82:83], v[40:41] op_sel_hi:[1,0,1]
	s_nop 0
	v_pk_fma_f32 v[40:41], v[8:9], v[70:71], v[40:41] op_sel_hi:[1,0,1]
	v_pk_fma_f32 v[70:71], v[50:51], v[52:53], v[68:69] neg_lo:[0,0,1] neg_hi:[0,0,1]
	v_pk_fma_f32 v[52:53], v[50:51], v[52:53], v[68:69] op_sel_hi:[1,0,1]
	s_nop 0
	v_mov_b32_e32 v71, v53
	v_pk_add_f32 v[40:41], v[70:71], v[40:41]
	s_nop 0
	v_cvt_pk_bf16_f32 v52, v40, v41
	ds_write_b32 v38, v52
	ds_read_b128 v[68:71], v39 offset:256
	ds_read_b128 v[72:75], v39 offset:272
	ds_read_b128 v[76:79], v39 offset:288
	ds_read_b128 v[80:83], v39 offset:304
	s_waitcnt lgkmcnt(3)
	v_pk_fma_f32 v[52:53], v[16:17], v[68:69], 0 op_sel_hi:[1,0,0]
	s_nop 0
	v_pk_fma_f32 v[52:53], v[18:19], v[68:69], v[52:53] op_sel:[0,1,0]
	v_mov_b32_e32 v68, v71
	v_pk_fma_f32 v[52:53], v[44:45], v[70:71], v[52:53] op_sel_hi:[1,0,1]
	s_waitcnt lgkmcnt(2)
	v_mov_b32_e32 v70, v75
	v_pk_fma_f32 v[52:53], v[20:21], v[68:69], v[52:53] op_sel_hi:[1,0,1]
	v_pk_mul_f32 v[68:69], v[2:3], v[40:41] op_sel:[0,1]
	v_pk_fma_f32 v[52:53], v[62:63], v[72:73], v[52:53] op_sel_hi:[1,0,1]
	s_nop 0
	v_pk_fma_f32 v[52:53], v[14:15], v[72:73], v[52:53] op_sel:[0,1,0]
	s_nop 0
	v_pk_fma_f32 v[52:53], v[4:5], v[74:75], v[52:53] op_sel_hi:[1,0,1]
	s_nop 0
	v_pk_fma_f32 v[52:53], v[58:59], v[70:71], v[52:53] op_sel_hi:[1,0,1]
	s_waitcnt lgkmcnt(1)
	v_mov_b32_e32 v70, v79
	v_pk_fma_f32 v[52:53], v[60:61], v[76:77], v[52:53] op_sel_hi:[1,0,1]
	s_nop 0
	v_pk_fma_f32 v[52:53], v[10:11], v[76:77], v[52:53] op_sel:[0,1,0]
	s_nop 0
	v_pk_fma_f32 v[52:53], v[46:47], v[78:79], v[52:53] op_sel_hi:[1,0,1]
	s_nop 0
	v_pk_fma_f32 v[52:53], v[12:13], v[70:71], v[52:53] op_sel_hi:[1,0,1]
	s_waitcnt lgkmcnt(0)
	v_mov_b32_e32 v70, v83
	v_pk_fma_f32 v[52:53], v[48:49], v[80:81], v[52:53] op_sel_hi:[1,0,1]
	s_nop 0
	v_pk_fma_f32 v[52:53], v[6:7], v[80:81], v[52:53] op_sel:[0,1,0]
	s_nop 0
	v_pk_fma_f32 v[52:53], v[42:43], v[82:83], v[52:53] op_sel_hi:[1,0,1]
	s_nop 0
	v_pk_fma_f32 v[52:53], v[8:9], v[70:71], v[52:53] op_sel_hi:[1,0,1]
	v_pk_fma_f32 v[70:71], v[50:51], v[40:41], v[68:69] neg_lo:[0,0,1] neg_hi:[0,0,1]
	v_pk_fma_f32 v[40:41], v[50:51], v[40:41], v[68:69] op_sel_hi:[1,0,1]
	s_nop 0
	v_mov_b32_e32 v71, v41
	v_pk_add_f32 v[52:53], v[70:71], v[52:53]
	s_nop 0
	v_cvt_pk_bf16_f32 v39, v52, v53
	ds_write_b32 v38, v39 offset:272
	v_add_u32_e32 v38, 0x220, v38
	s_cbranch_scc0 .LBB0_305
; DI u16 f2bf(float x) { return (u16)(pack2(x, x) & 0xffffu); }
; DI float gelu_t(float x) { float u = 0.7978845608028654f * (x + 0.044715f * x * x * x); return x / (1.f + __expf(-2.f * u)); }
; #define MFMA16(a, b, c) __builtin_amdgcn_mfma_f32_16x16x32_bf16((a), (b), (c), 0, 0, 0)
; DI void ssm2_item(PREF p, int l, int item, unsigned char* ldsb) {
;     ...
;     __syncthreads();
;     f32x4 acc = {0.f, 0.f, 0.f, 0.f};
; #pragma unroll
;     for (int ks = 0; ks < 4; ++ks) {
;       bf16x8 a = *(const bf16x8*)(Hs + hcol * 136 + 32 * ks + 8 * q4);
;       acc = MFMA16(a, cf[ks], acc);
;     }
; #pragma unroll
;     for (int j = 0; j < 4; ++j) {
;       int t = sub * 16 + 4 * q4 + j;
;       float uu = uS[t * 64 + w * 16 + hcol];
;       float yv = gelu_t(acc[j] + dch * uu);
;       p.yss[(size_t)(b * S_ + c * 64 + t) * 256 + g * 16 + hcol] = f2bf(yv);
;     }
;     __syncthreads();
;   }
	s_waitcnt lgkmcnt(0)
	s_barrier
	ds_read_b128 v[38:41], v66 offset:16384
	ds_read_b128 v[68:71], v66 offset:16448
	v_lshl_or_b32 v67, s8, 4, v64
	s_add_i32 s8, s8, 1
	v_add_u32_e32 v54, 0x1000, v54
	s_cmp_eq_u32 s8, 4
	s_waitcnt lgkmcnt(1)
	v_mfma_f32_16x16x32_bf16 v[38:41], v[38:41], v[22:25], 0
	s_waitcnt lgkmcnt(0)
	v_mfma_f32_16x16x32_bf16 v[38:41], v[68:71], v[26:29], v[38:41]
	ds_read_b128 v[68:71], v66 offset:16512
	s_waitcnt lgkmcnt(0)
	v_mfma_f32_16x16x32_bf16 v[38:41], v[68:71], v[30:33], v[38:41]
	ds_read_b128 v[68:71], v66 offset:16576
	s_waitcnt lgkmcnt(0)
	v_mfma_f32_16x16x32_bf16 v[38:41], v[68:71], v[34:37], v[38:41]
	v_lshl_add_u32 v68, v67, 8, v0
	ds_read_b32 v68, v68
	s_waitcnt lgkmcnt(0)
	s_nop 4
	v_fma_f32 v38, v65, v68, v38
	v_mul_f32_e32 v68, 0x3d372713, v38
	v_mul_f32_e32 v68, v38, v68
	v_fma_f32 v68, v38, v68, v38
	v_mul_f32_e32 v68, 0x3f4c422a, v68
	v_mul_f32_e32 v68, -2.0, v68
	v_mul_f32_e32 v68, 0x3fb8aa3b, v68
	v_exp_f32_e32 v68, v68
	s_nop 0
	v_add_f32_e32 v68, 1.0, v68
	v_rcp_f32_e32 v69, v68
	s_nop 0
	v_mul_f32_e32 v38, v38, v69
	v_or_b32_e32 v68, s62, v67
	v_ashrrev_i32_e32 v69, 31, v68
	v_lshlrev_b64 v[68:69], 9, v[68:69]
	v_cvt_pk_bf16_f32 v38, v38, v38
	v_lshl_add_u64 v[68:69], v[56:57], 0, v[68:69]
	global_store_short v[68:69], v38, off
	v_or_b32_e32 v38, 1, v67
	v_lshl_add_u32 v68, v38, 8, v0
	ds_read_b32 v68, v68
	v_or_b32_e32 v38, s62, v38
	s_waitcnt lgkmcnt(0)
	v_fma_f32 v39, v65, v68, v39
	v_mul_f32_e32 v68, 0x3d372713, v39
	v_mul_f32_e32 v68, v39, v68
	v_fma_f32 v68, v39, v68, v39
	v_mul_f32_e32 v68, 0x3f4c422a, v68
	v_mul_f32_e32 v68, -2.0, v68
	v_mul_f32_e32 v68, 0x3fb8aa3b, v68
	v_exp_f32_e32 v68, v68
	s_nop 0
	v_add_f32_e32 v68, 1.0, v68
	v_rcp_f32_e32 v69, v68
	s_nop 0
	v_mul_f32_e32 v39, v39, v69
	v_cvt_pk_bf16_f32 v68, v39, v39
	v_ashrrev_i32_e32 v39, 31, v38
	v_lshlrev_b64 v[38:39], 9, v[38:39]
	v_lshl_add_u64 v[38:39], v[56:57], 0, v[38:39]
	global_store_short v[38:39], v68, off
	v_or_b32_e32 v38, 2, v67
	v_lshl_add_u32 v39, v38, 8, v0
	ds_read_b32 v39, v39
	v_or_b32_e32 v38, s62, v38
	s_waitcnt lgkmcnt(0)
	v_fma_f32 v39, v65, v39, v40
	v_mul_f32_e32 v40, 0x3d372713, v39
	v_mul_f32_e32 v40, v39, v40
	v_fma_f32 v40, v39, v40, v39
	v_mul_f32_e32 v40, 0x3f4c422a, v40
	v_mul_f32_e32 v40, -2.0, v40
	v_mul_f32_e32 v40, 0x3fb8aa3b, v40
	v_exp_f32_e32 v40, v40
	s_nop 0
	v_add_f32_e32 v40, 1.0, v40
	v_rcp_f32_e32 v68, v40
	s_nop 0
	v_mul_f32_e32 v39, v39, v68
	v_cvt_pk_bf16_f32 v40, v39, v39
	v_ashrrev_i32_e32 v39, 31, v38
	v_lshlrev_b64 v[38:39], 9, v[38:39]
	v_lshl_add_u64 v[38:39], v[56:57], 0, v[38:39]
	global_store_short v[38:39], v40, off
	v_or_b32_e32 v38, 3, v67
	v_lshl_add_u32 v39, v38, 8, v0
	ds_read_b32 v39, v39
	v_or_b32_e32 v38, s62, v38
	s_waitcnt lgkmcnt(0)
	v_fmac_f32_e32 v41, v65, v39
	v_mul_f32_e32 v39, 0x3d372713, v41
	v_mul_f32_e32 v39, v41, v39
	v_fma_f32 v39, v41, v39, v41
	v_mul_f32_e32 v39, 0x3f4c422a, v39
	v_mul_f32_e32 v39, -2.0, v39
	v_mul_f32_e32 v39, 0x3fb8aa3b, v39
	v_exp_f32_e32 v39, v39
	s_nop 0
	v_add_f32_e32 v39, 1.0, v39
	v_rcp_f32_e32 v40, v39
	s_nop 0
	v_mul_f32_e32 v39, v41, v40
	v_cvt_pk_bf16_f32 v40, v39, v39
	v_ashrrev_i32_e32 v39, 31, v38
	v_lshlrev_b64 v[38:39], 9, v[38:39]
	v_lshl_add_u64 v[38:39], v[56:57], 0, v[38:39]
	global_store_short v[38:39], v40, off
	s_barrier
	s_cbranch_scc0 .LBB0_304
	s_add_i32 s48, s48, s71
	s_sub_i32 s57, s57, s71
	s_cmpk_gt_i32 s48, 0x7ff
	s_cbranch_scc0 .LBB0_268

; DI unsigned pack2(float a, float b) { unsigned r; asm("v_cvt_pk_bf16_f32 %0, %1, %2\n\ts_nop 1" : "=v"(r) : "v"(a), "v"(b)); return r; }
; DI float lo2f(unsigned u) { return __uint_as_float(u << 16); }
; DI float hi2f(unsigned u) { return __uint_as_float(u & 0xffff0000u); }
; DI float silu(float x) { return x / (1.f + __expf(-x)); }
; template <int DQK, bool WIN>
; DI void attn_item(const u16* __restrict__ Qb, int ldq, const u16* __restrict__ Kb, int ldk, const u16* __restrict__ Vtb, int qb,
;                   float qscale, float sink2, const u16* __restrict__ zb, int ldz, u16* __restrict__ ob, int ldo, u16* lds) {
;     ...
;   float lt = lsum + __shfl_xor(lsum, 32);
;   float inv = 1.f / lt;
;   u32x2 zr[8];
; #pragma unroll
;   for (int e = 0; e < 8; ++e) zr[e] = *(const u32x2*)(zb + (size_t)qrow * ldz + (e >> 2) * 32 + 8 * (e & 3) + 4 * hh);
; #pragma unroll
;   for (int vb = 0; vb < 2; ++vb)
; #pragma unroll
;     for (int g4 = 0; g4 < 4; ++g4) {
;       int vd0 = vb * 32 + 8 * g4 + 4 * hh;
;       u32x2 z = zr[vb * 4 + g4];
;       float a0 = o[vb][4 * g4 + 0] * inv * silu(lo2f(z.x));
;       float a1 = o[vb][4 * g4 + 1] * inv * silu(hi2f(z.x));
;       float a2 = o[vb][4 * g4 + 2] * inv * silu(lo2f(z.y));
;       float a3 = o[vb][4 * g4 + 3] * inv * silu(hi2f(z.y));
;       u32x2 ov; ov.x = pack2(a0, a1); ov.y = pack2(a2, a3);
;       *(u32x2*)(ob + (size_t)qrow * ldo + vd0) = ov;
;     }
.LBB0_312:
	v_mad_i64_i32 v[34:35], s[0:1], v114, s60, 0
	s_lshl_b32 s24, s8, 1
	s_add_u32 s0, s41, s24
	s_addc_u32 s1, s42, 0
	v_and_b32_e32 v37, 64, v172
	v_xor_b32_e32 v36, 32, v172
	v_add_u32_e32 v37, 64, v37
	v_lshl_add_u64 v[34:35], s[0:1], 0, v[34:35]
	v_lshlrev_b64 v[48:49], 1, v[0:1]
	v_cmp_lt_i32_e32 vcc, v36, v37
	v_lshl_add_u64 v[34:35], v[34:35], 0, v[48:49]
	s_mov_b64 s[0:1], 0x1340
	v_cndmask_b32_e32 v36, v172, v36, vcc
	v_lshl_add_u64 v[50:51], v[34:35], 0, s[0:1]
	v_add_co_u32_e32 v34, vcc, s80, v34
	v_lshlrev_b32_e32 v36, 2, v36
	s_nop 0
	v_addc_co_u32_e32 v35, vcc, 0, v35, vcc
	ds_bpermute_b32 v162, v36, v116
	global_load_dwordx2 v[52:53], v[34:35], off offset:832
	global_load_dwordx2 v[46:47], v[50:51], off offset:16
	global_load_dwordx2 v[44:45], v[50:51], off offset:32
	global_load_dwordx2 v[42:43], v[50:51], off offset:48
	global_load_dwordx2 v[40:41], v[50:51], off offset:64
	global_load_dwordx2 v[38:39], v[50:51], off offset:80
	global_load_dwordx2 v[36:37], v[50:51], off offset:96
	global_load_dwordx2 v[34:35], v[50:51], off offset:112
	s_lshl_b64 s[8:9], s[22:23], 23
	s_add_u32 s8, s14, s8
	s_addc_u32 s9, s15, s9
	s_add_u32 s8, s8, s24
	s_addc_u32 s9, s9, 0
	v_lshlrev_b64 v[50:51], 11, v[114:115]
	v_lshl_add_u64 v[50:51], s[8:9], 0, v[50:51]
	s_add_i32 s36, s36, s71
	s_cmpk_gt_i32 s36, 0x3ff
	s_waitcnt vmcnt(7)
	v_lshlrev_b32_e32 v0, 16, v52
	v_mul_f32_e32 v54, 0xbfb8aa3b, v0
	v_exp_f32_e32 v54, v54
	s_nop 0
	v_add_f32_e32 v54, 1.0, v54
	v_rcp_f32_e32 v55, v54
	s_nop 0
	v_mul_f32_e32 v56, v0, v55
	v_and_b32_e32 v0, 0xffff0000, v52
	v_mul_f32_e32 v52, 0xbfb8aa3b, v0
	v_exp_f32_e32 v52, v52
	s_nop 0
	v_add_f32_e32 v52, 1.0, v52
	v_rcp_f32_e32 v54, v52
	s_nop 0
	v_mul_f32_e32 v52, v0, v54
	v_lshlrev_b32_e32 v0, 16, v53
	v_mul_f32_e32 v54, 0xbfb8aa3b, v0
	v_exp_f32_e32 v117, v54
	s_waitcnt lgkmcnt(0)
	v_pk_add_f32 v[54:55], v[116:117], v[162:163]
	s_nop 0
	v_rcp_f32_e32 v57, v55
	s_nop 0
	v_mul_f32_e32 v55, v0, v57
	v_rcp_f32_e32 v0, v54
	s_nop 0
	v_mul_f32_e32 v19, v19, v0
	v_mul_f32_e32 v20, v20, v0
	v_mul_f32_e32 v19, v19, v52
	v_mul_f32_e32 v52, v20, v55
	v_mul_f32_e32 v20, v21, v0
	v_and_b32_e32 v21, 0xffff0000, v53
	v_mul_f32_e32 v53, 0xbfb8aa3b, v21
	v_exp_f32_e32 v53, v53
	v_mul_f32_e32 v18, v18, v0
	v_mul_f32_e32 v18, v18, v56
	v_mul_f32_e32 v2, v2, v0
	v_add_f32_e32 v53, 1.0, v53
	v_mul_f32_e32 v3, v3, v0
	v_mul_f32_e32 v4, v4, v0
	v_mul_f32_e32 v5, v5, v0
	v_rcp_f32_e32 v54, v53
	s_nop 0
	v_mul_f32_e32 v21, v21, v54
	v_mul_f32_e32 v21, v20, v21
	v_cvt_pk_bf16_f32 v20, v18, v19
	v_cvt_pk_bf16_f32 v21, v52, v21
	v_lshl_add_u64 v[18:19], v[50:51], 0, v[48:49]
	global_store_dwordx2 v[18:19], v[20:21], off offset:1536
	s_waitcnt vmcnt(7)
	v_lshlrev_b32_e32 v21, 16, v46
	v_mul_f32_e32 v20, v22, v0
	v_mul_f32_e32 v22, 0xbfb8aa3b, v21
	v_exp_f32_e32 v22, v22
	s_nop 0
	v_add_f32_e32 v22, 1.0, v22
	v_rcp_f32_e32 v48, v22
	s_nop 0
	v_mul_f32_e32 v21, v21, v48
	v_and_b32_e32 v22, 0xffff0000, v46
	v_mul_f32_e32 v20, v20, v21
	v_mul_f32_e32 v21, v23, v0
	v_mul_f32_e32 v23, 0xbfb8aa3b, v22
	v_exp_f32_e32 v23, v23
	s_nop 0
	v_add_f32_e32 v23, 1.0, v23
	v_rcp_f32_e32 v46, v23
	s_nop 0
	v_mul_f32_e32 v22, v22, v46
	v_lshlrev_b32_e32 v23, 16, v47
	v_mul_f32_e32 v21, v21, v22
	v_mul_f32_e32 v22, v24, v0
	v_mul_f32_e32 v24, 0xbfb8aa3b, v23
	v_exp_f32_e32 v24, v24
	v_cvt_pk_bf16_f32 v20, v20, v21
	s_nop 0
	v_add_f32_e32 v24, 1.0, v24
	v_rcp_f32_e32 v46, v24
	s_nop 0
	v_mul_f32_e32 v23, v23, v46
	v_and_b32_e32 v24, 0xffff0000, v47
	v_mul_f32_e32 v22, v22, v23
	v_mul_f32_e32 v23, v25, v0
	v_mul_f32_e32 v25, 0xbfb8aa3b, v24
	v_exp_f32_e32 v25, v25
	s_nop 0
	v_add_f32_e32 v25, 1.0, v25
	v_rcp_f32_e32 v46, v25
	s_nop 0
	v_mul_f32_e32 v24, v24, v46
	v_mul_f32_e32 v23, v23, v24
	v_cvt_pk_bf16_f32 v21, v22, v23
	global_store_dwordx2 v[18:19], v[20:21], off offset:1552
	s_waitcnt vmcnt(7)
	v_lshlrev_b32_e32 v21, 16, v44
	v_mul_f32_e32 v22, 0xbfb8aa3b, v21
	v_exp_f32_e32 v22, v22
	v_mul_f32_e32 v20, v26, v0
	v_add_f32_e32 v22, 1.0, v22
	v_rcp_f32_e32 v23, v22
	s_nop 0
	v_mul_f32_e32 v21, v21, v23
	v_and_b32_e32 v22, 0xffff0000, v44
	v_mul_f32_e32 v23, 0xbfb8aa3b, v22
	v_exp_f32_e32 v23, v23
	v_mul_f32_e32 v20, v20, v21
	v_mul_f32_e32 v21, v27, v0
	v_add_f32_e32 v23, 1.0, v23
	v_rcp_f32_e32 v24, v23
	s_nop 0
	v_mul_f32_e32 v22, v22, v24
	v_lshlrev_b32_e32 v23, 16, v45
	v_mul_f32_e32 v24, 0xbfb8aa3b, v23
	v_exp_f32_e32 v24, v24
	v_mul_f32_e32 v21, v21, v22
	v_mul_f32_e32 v22, v28, v0
	v_cvt_pk_bf16_f32 v20, v20, v21
	v_add_f32_e32 v24, 1.0, v24
	v_rcp_f32_e32 v25, v24
	s_nop 0
	v_mul_f32_e32 v23, v23, v25
	v_and_b32_e32 v24, 0xffff0000, v45
	v_mul_f32_e32 v25, 0xbfb8aa3b, v24
	v_exp_f32_e32 v25, v25
	v_mul_f32_e32 v22, v22, v23
	v_mul_f32_e32 v23, v29, v0
	v_add_f32_e32 v25, 1.0, v25
	v_rcp_f32_e32 v26, v25
	s_nop 0
	v_mul_f32_e32 v24, v24, v26
	v_mul_f32_e32 v23, v23, v24
	v_cvt_pk_bf16_f32 v21, v22, v23
	global_store_dwordx2 v[18:19], v[20:21], off offset:1568
	s_waitcnt vmcnt(7)
; DI unsigned pack2(float a, float b) { unsigned r; asm("v_cvt_pk_bf16_f32 %0, %1, %2\n\ts_nop 1" : "=v"(r) : "v"(a), "v"(b)); return r; }
; DI float lo2f(unsigned u) { return __uint_as_float(u << 16); }
; DI float hi2f(unsigned u) { return __uint_as_float(u & 0xffff0000u); }
; DI float silu(float x) { return x / (1.f + __expf(-x)); }
; template <int DQK, bool WIN>
; DI void attn_item(const u16* __restrict__ Qb, int ldq, const u16* __restrict__ Kb, int ldk, const u16* __restrict__ Vtb, int qb,
;                   float qscale, float sink2, const u16* __restrict__ zb, int ldz, u16* __restrict__ ob, int ldo, u16* lds) {
;     ...
;   for (int e = 0; e < 8; ++e) zr[e] = *(const u32x2*)(zb + (size_t)qrow * ldz + (e >> 2) * 32 + 8 * (e & 3) + 4 * hh);
; #pragma unroll
;   for (int vb = 0; vb < 2; ++vb)
; #pragma unroll
;     for (int g4 = 0; g4 < 4; ++g4) {
;       int vd0 = vb * 32 + 8 * g4 + 4 * hh;
;       u32x2 z = zr[vb * 4 + g4];
;       float a0 = o[vb][4 * g4 + 0] * inv * silu(lo2f(z.x));
;       float a1 = o[vb][4 * g4 + 1] * inv * silu(hi2f(z.x));
;       float a2 = o[vb][4 * g4 + 2] * inv * silu(lo2f(z.y));
;       float a3 = o[vb][4 * g4 + 3] * inv * silu(hi2f(z.y));
;       u32x2 ov; ov.x = pack2(a0, a1); ov.y = pack2(a2, a3);
;       *(u32x2*)(ob + (size_t)qrow * ldo + vd0) = ov;
;     }
	v_lshlrev_b32_e32 v21, 16, v42
	v_mul_f32_e32 v22, 0xbfb8aa3b, v21
	v_exp_f32_e32 v22, v22
	v_mul_f32_e32 v20, v30, v0
	v_add_f32_e32 v22, 1.0, v22
	v_rcp_f32_e32 v23, v22
	s_nop 0
	v_mul_f32_e32 v21, v21, v23
	v_and_b32_e32 v22, 0xffff0000, v42
	v_mul_f32_e32 v23, 0xbfb8aa3b, v22
	v_exp_f32_e32 v23, v23
	v_mul_f32_e32 v20, v20, v21
	v_mul_f32_e32 v21, v31, v0
	v_add_f32_e32 v23, 1.0, v23
	v_rcp_f32_e32 v24, v23
	s_nop 0
	v_mul_f32_e32 v22, v22, v24
	v_lshlrev_b32_e32 v23, 16, v43
	v_mul_f32_e32 v24, 0xbfb8aa3b, v23
	v_exp_f32_e32 v24, v24
	v_mul_f32_e32 v21, v21, v22
	v_mul_f32_e32 v22, v32, v0
	v_cvt_pk_bf16_f32 v20, v20, v21
	v_add_f32_e32 v24, 1.0, v24
	v_rcp_f32_e32 v25, v24
	s_nop 0
	v_mul_f32_e32 v23, v23, v25
	v_and_b32_e32 v24, 0xffff0000, v43
	v_mul_f32_e32 v25, 0xbfb8aa3b, v24
	v_exp_f32_e32 v25, v25
	v_mul_f32_e32 v22, v22, v23
	v_mul_f32_e32 v23, v33, v0
	v_add_f32_e32 v25, 1.0, v25
	v_rcp_f32_e32 v26, v25
	s_nop 0
	v_mul_f32_e32 v24, v24, v26
	v_mul_f32_e32 v23, v23, v24
	v_cvt_pk_bf16_f32 v21, v22, v23
	global_store_dwordx2 v[18:19], v[20:21], off offset:1584
	s_waitcnt vmcnt(7)
	v_lshlrev_b32_e32 v20, 16, v40
	v_mul_f32_e32 v21, 0xbfb8aa3b, v20
	v_exp_f32_e32 v21, v21
	s_nop 0
	v_add_f32_e32 v21, 1.0, v21
	v_rcp_f32_e32 v22, v21
	s_nop 0
	v_mul_f32_e32 v20, v20, v22
	v_mul_f32_e32 v2, v2, v20
	v_and_b32_e32 v20, 0xffff0000, v40
	v_mul_f32_e32 v21, 0xbfb8aa3b, v20
	v_exp_f32_e32 v21, v21
	s_nop 0
	v_add_f32_e32 v21, 1.0, v21
	v_rcp_f32_e32 v22, v21
	s_nop 0
	v_mul_f32_e32 v20, v20, v22
	v_mul_f32_e32 v3, v3, v20
	v_lshlrev_b32_e32 v20, 16, v41
	v_mul_f32_e32 v21, 0xbfb8aa3b, v20
	v_exp_f32_e32 v21, v21
	v_cvt_pk_bf16_f32 v2, v2, v3
	s_nop 0
	v_add_f32_e32 v21, 1.0, v21
	v_rcp_f32_e32 v22, v21
	s_nop 0
	v_mul_f32_e32 v20, v20, v22
	v_mul_f32_e32 v4, v4, v20
	v_and_b32_e32 v20, 0xffff0000, v41
	v_mul_f32_e32 v21, 0xbfb8aa3b, v20
	v_exp_f32_e32 v21, v21
	s_nop 0
	v_add_f32_e32 v21, 1.0, v21
	v_rcp_f32_e32 v22, v21
	s_nop 0
	v_mul_f32_e32 v20, v20, v22
	v_mul_f32_e32 v5, v5, v20
	v_cvt_pk_bf16_f32 v3, v4, v5
	global_store_dwordx2 v[18:19], v[2:3], off offset:1600
	s_waitcnt vmcnt(7)
	v_lshlrev_b32_e32 v3, 16, v38
	v_mul_f32_e32 v4, 0xbfb8aa3b, v3
	v_exp_f32_e32 v4, v4
	v_mul_f32_e32 v2, v6, v0
	v_add_f32_e32 v4, 1.0, v4
	v_rcp_f32_e32 v5, v4
	s_nop 0
	v_mul_f32_e32 v3, v3, v5
	v_and_b32_e32 v4, 0xffff0000, v38
	v_mul_f32_e32 v5, 0xbfb8aa3b, v4
	v_exp_f32_e32 v5, v5
	v_mul_f32_e32 v2, v2, v3
	v_mul_f32_e32 v3, v7, v0
	v_add_f32_e32 v5, 1.0, v5
	v_rcp_f32_e32 v6, v5
	s_nop 0
	v_mul_f32_e32 v4, v4, v6
	v_lshlrev_b32_e32 v5, 16, v39
	v_mul_f32_e32 v6, 0xbfb8aa3b, v5
	v_exp_f32_e32 v6, v6
	v_mul_f32_e32 v3, v3, v4
	v_mul_f32_e32 v4, v8, v0
	v_cvt_pk_bf16_f32 v2, v2, v3
	v_add_f32_e32 v6, 1.0, v6
	v_rcp_f32_e32 v7, v6
	s_nop 0
	v_mul_f32_e32 v5, v5, v7
	v_and_b32_e32 v6, 0xffff0000, v39
	v_mul_f32_e32 v7, 0xbfb8aa3b, v6
	v_exp_f32_e32 v7, v7
	v_mul_f32_e32 v4, v4, v5
	v_mul_f32_e32 v5, v9, v0
	v_add_f32_e32 v7, 1.0, v7
	v_rcp_f32_e32 v8, v7
	s_nop 0
	v_mul_f32_e32 v6, v6, v8
	v_mul_f32_e32 v5, v5, v6
	v_cvt_pk_bf16_f32 v3, v4, v5
	global_store_dwordx2 v[18:19], v[2:3], off offset:1616
	s_waitcnt vmcnt(7)
	v_lshlrev_b32_e32 v3, 16, v36
	v_mul_f32_e32 v4, 0xbfb8aa3b, v3
	v_exp_f32_e32 v4, v4
	v_mul_f32_e32 v2, v10, v0
	v_add_f32_e32 v4, 1.0, v4
	v_rcp_f32_e32 v5, v4
	s_nop 0
	v_mul_f32_e32 v3, v3, v5
	v_and_b32_e32 v4, 0xffff0000, v36
	v_mul_f32_e32 v5, 0xbfb8aa3b, v4
	v_exp_f32_e32 v5, v5
	v_mul_f32_e32 v2, v2, v3
	v_mul_f32_e32 v3, v11, v0
	v_add_f32_e32 v5, 1.0, v5
	v_rcp_f32_e32 v6, v5
	s_nop 0
	v_mul_f32_e32 v4, v4, v6
	v_lshlrev_b32_e32 v5, 16, v37
	v_mul_f32_e32 v6, 0xbfb8aa3b, v5
	v_exp_f32_e32 v6, v6
	v_mul_f32_e32 v3, v3, v4
	v_mul_f32_e32 v4, v12, v0
	v_cvt_pk_bf16_f32 v2, v2, v3
	v_add_f32_e32 v6, 1.0, v6
	v_rcp_f32_e32 v7, v6
	s_nop 0
	v_mul_f32_e32 v5, v5, v7
	v_and_b32_e32 v6, 0xffff0000, v37
	v_mul_f32_e32 v7, 0xbfb8aa3b, v6
	v_exp_f32_e32 v7, v7
	v_mul_f32_e32 v4, v4, v5
	v_mul_f32_e32 v5, v13, v0
	v_add_f32_e32 v7, 1.0, v7
	v_rcp_f32_e32 v8, v7
	s_nop 0
	v_mul_f32_e32 v6, v6, v8
	v_mul_f32_e32 v5, v5, v6
	v_cvt_pk_bf16_f32 v3, v4, v5
	global_store_dwordx2 v[18:19], v[2:3], off offset:1632
	s_waitcnt vmcnt(7)
	v_lshlrev_b32_e32 v3, 16, v34
	v_mul_f32_e32 v4, 0xbfb8aa3b, v3
	v_exp_f32_e32 v4, v4
	v_mul_f32_e32 v2, v14, v0
	v_add_f32_e32 v4, 1.0, v4
	v_rcp_f32_e32 v5, v4
	s_nop 0
	v_mul_f32_e32 v3, v3, v5
	v_and_b32_e32 v4, 0xffff0000, v34
	v_mul_f32_e32 v5, 0xbfb8aa3b, v4
	v_exp_f32_e32 v5, v5
	v_mul_f32_e32 v2, v2, v3
	v_mul_f32_e32 v3, v15, v0
	v_add_f32_e32 v5, 1.0, v5
	v_rcp_f32_e32 v6, v5
	s_nop 0
	v_mul_f32_e32 v4, v4, v6
	v_lshlrev_b32_e32 v5, 16, v35
	v_mul_f32_e32 v6, 0xbfb8aa3b, v5
	v_exp_f32_e32 v6, v6
	v_mul_f32_e32 v3, v3, v4
	v_mul_f32_e32 v4, v16, v0
	v_mul_f32_e32 v0, v17, v0
	v_add_f32_e32 v6, 1.0, v6
	v_cvt_pk_bf16_f32 v2, v2, v3
	s_nop 0
	v_rcp_f32_e32 v7, v6
	s_nop 0
	v_mul_f32_e32 v5, v5, v7
	v_mul_f32_e32 v4, v4, v5
	v_and_b32_e32 v5, 0xffff0000, v35
	v_mul_f32_e32 v6, 0xbfb8aa3b, v5
	v_exp_f32_e32 v6, v6
	s_nop 0
	v_add_f32_e32 v6, 1.0, v6
	v_rcp_f32_e32 v7, v6
	s_nop 0
	v_mul_f32_e32 v5, v5, v7
	v_mul_f32_e32 v0, v0, v5
	v_cvt_pk_bf16_f32 v3, v4, v0
	global_store_dwordx2 v[18:19], v[2:3], off offset:1648
	s_cbranch_scc1 .LBB0_335

; DI unsigned pack2(float a, float b) { unsigned r; asm("v_cvt_pk_bf16_f32 %0, %1, %2\n\ts_nop 1" : "=v"(r) : "v"(a), "v"(b)); return r; }
; #define MFMA32(a, b, c) __builtin_amdgcn_mfma_f32_32x32x16_bf16((a), (b), (c), 0, 0, 0)
; template <int DQK, bool WIN>
; DI void attn_item(const u16* __restrict__ Qb, int ldq, const u16* __restrict__ Kb, int ldk, const u16* __restrict__ Vtb, int qb,
;                   float qscale, float sink2, const u16* __restrict__ zb, int ldz, u16* __restrict__ ob, int ldo, u16* lds) {
;     ...
;       const float nb = -mn * qscale;
;       float ps = 0.f;
; #pragma unroll
;       for (int kb = 0; kb < 2; ++kb)
; #pragma unroll
;         for (int i = 0; i < 16; ++i) { float pv = __builtin_amdgcn_exp2f(fmaf(st[kb][i], qscale, nb)); st[kb][i] = pv; ps += pv; }
;       lsum += ps;
; #pragma unroll
;       for (int kb = 0; kb < 2; ++kb)
; #pragma unroll
;         for (int s2 = 0; s2 < 2; ++s2) {
;           union { bf16x8 v; unsigned u[4]; } pf;
; #pragma unroll
;           for (int j = 0; j < 4; ++j) pf.u[j] = pack2(st[kb][8 * s2 + 2 * j], st[kb][8 * s2 + 2 * j + 1]);
; #pragma unroll
;           for (int vb = 0; vb < 2; ++vb) {
;             const bf16x8 vf = *(const bf16x8*)(vs + (vb * 32 + r) * 72 + (kb * 2 + s2) * 16 + hh * 8);
;             o[vb] = MFMA32(vf, pf.v, o[vb]);
;           }
;         }
.LBB0_320:
	ds_read_b128 v[164:167], v140 offset:9216
	ds_read_b128 v[182:185], v140 offset:9248
	ds_read_b128 v[186:189], v140 offset:13824
	ds_read_b128 v[190:193], v140 offset:13856
	ds_read_b128 v[194:197], v140 offset:9280
	ds_read_b128 v[198:201], v140 offset:13888
	ds_read_b128 v[202:205], v140 offset:9312
	ds_read_b128 v[206:209], v140 offset:13920
	v_mul_f32_e32 v48, 0xbe38aa3b, v34
	v_fmamk_f32 v49, v50, 0x3e38aa3b, v48
	v_exp_f32_e32 v49, v49
	v_fmamk_f32 v51, v51, 0x3e38aa3b, v48
	v_exp_f32_e32 v51, v51
	v_fmamk_f32 v52, v52, 0x3e38aa3b, v48
	v_exp_f32_e32 v52, v52
	v_fmamk_f32 v53, v53, 0x3e38aa3b, v48
	v_exp_f32_e32 v53, v53
	v_fmamk_f32 v62, v148, 0x3e38aa3b, v48
	v_add_f32_e32 v50, 0, v49
	v_exp_f32_e32 v62, v62
	v_fmamk_f32 v63, v147, 0x3e38aa3b, v48
	v_add_f32_e32 v50, v51, v50
	v_exp_f32_e32 v63, v63
	v_fmamk_f32 v64, v149, 0x3e38aa3b, v48
	v_add_f32_e32 v50, v52, v50
	v_exp_f32_e32 v64, v64
	v_fmamk_f32 v65, v150, 0x3e38aa3b, v48
	v_add_f32_e32 v50, v53, v50
	v_exp_f32_e32 v65, v65
	v_fmamk_f32 v144, v151, 0x3e38aa3b, v48
	v_add_f32_e32 v50, v62, v50
	v_exp_f32_e32 v144, v144
	v_fmamk_f32 v145, v145, 0x3e38aa3b, v48
	v_add_f32_e32 v50, v63, v50
	v_exp_f32_e32 v145, v145
	v_fmamk_f32 v146, v146, 0x3e38aa3b, v48
	v_add_f32_e32 v50, v64, v50
	v_exp_f32_e32 v146, v146
	v_fmamk_f32 v60, v60, 0x3e38aa3b, v48
	v_add_f32_e32 v50, v65, v50
	v_exp_f32_e32 v60, v60
	v_fmamk_f32 v61, v61, 0x3e38aa3b, v48
	v_add_f32_e32 v50, v144, v50
	v_exp_f32_e32 v61, v61
	v_fmamk_f32 v58, v58, 0x3e38aa3b, v48
	v_add_f32_e32 v50, v145, v50
	v_exp_f32_e32 v58, v58
	v_fmamk_f32 v59, v59, 0x3e38aa3b, v48
	v_add_f32_e32 v50, v146, v50
	v_exp_f32_e32 v59, v59
	v_fmamk_f32 v56, v56, 0x3e38aa3b, v48
	v_add_f32_e32 v50, v60, v50
	v_exp_f32_e32 v56, v56
	v_fmamk_f32 v57, v57, 0x3e38aa3b, v48
	v_add_f32_e32 v50, v61, v50
	v_exp_f32_e32 v57, v57
	v_fmamk_f32 v54, v54, 0x3e38aa3b, v48
	v_add_f32_e32 v50, v58, v50
	v_exp_f32_e32 v54, v54
	v_fmamk_f32 v55, v55, 0x3e38aa3b, v48
	v_add_f32_e32 v50, v59, v50
	v_exp_f32_e32 v55, v55
	v_fmamk_f32 v36, v36, 0x3e38aa3b, v48
	v_add_f32_e32 v50, v56, v50
	v_exp_f32_e32 v147, v36
	v_add_f32_e32 v50, v57, v50
	v_add_f32_e32 v50, v54, v50
	v_add_f32_e32 v50, v55, v50
	v_fmamk_f32 v37, v37, 0x3e38aa3b, v48
	v_add_f32_e32 v36, v147, v50
	v_exp_f32_e32 v50, v37
	v_fmamk_f32 v35, v35, 0x3e38aa3b, v48
	v_exp_f32_e32 v35, v35
	v_fmamk_f32 v37, v38, 0x3e38aa3b, v48
	v_exp_f32_e32 v148, v37
	v_fmamk_f32 v37, v39, 0x3e38aa3b, v48
	v_exp_f32_e32 v149, v37
	v_fmamk_f32 v37, v40, 0x3e38aa3b, v48
	v_add_f32_e32 v36, v50, v36
	v_exp_f32_e32 v150, v37
	v_fmamk_f32 v37, v41, 0x3e38aa3b, v48
	v_add_f32_e32 v36, v35, v36
	v_exp_f32_e32 v151, v37
	v_fmamk_f32 v37, v42, 0x3e38aa3b, v48
	v_add_f32_e32 v36, v148, v36
	v_exp_f32_e32 v152, v37
	v_fmamk_f32 v37, v43, 0x3e38aa3b, v48
	v_add_f32_e32 v36, v149, v36
	v_exp_f32_e32 v153, v37
	v_fmamk_f32 v37, v44, 0x3e38aa3b, v48
	v_add_f32_e32 v36, v150, v36
	v_exp_f32_e32 v154, v37
	v_fmamk_f32 v37, v45, 0x3e38aa3b, v48
	v_add_f32_e32 v36, v151, v36
	v_exp_f32_e32 v155, v37
	v_fmamk_f32 v37, v46, 0x3e38aa3b, v48
	v_add_f32_e32 v36, v152, v36
	v_exp_f32_e32 v156, v37
	v_fmac_f32_e32 v48, 0x3e38aa3b, v47
	v_add_f32_e32 v36, v153, v36
	v_exp_f32_e32 v48, v48
	v_add_f32_e32 v36, v154, v36
	v_add_f32_e32 v36, v155, v36
	v_add_f32_e32 v36, v156, v36
	v_add_f32_e32 v36, v48, v36
	v_add_f32_e32 v116, v36, v116
	v_cvt_pk_bf16_f32 v36, v49, v51
	v_cvt_pk_bf16_f32 v37, v52, v53
	v_cvt_pk_bf16_f32 v38, v62, v63
	v_cvt_pk_bf16_f32 v39, v64, v65
	s_waitcnt lgkmcnt(7)
	s_nop 0
	v_mfma_f32_32x32x16_bf16 v[18:33], v[164:167], v[36:39], v[18:33]
	s_waitcnt lgkmcnt(5)
	v_mfma_f32_32x32x16_bf16 v[2:17], v[186:189], v[36:39], v[2:17]
	v_cvt_pk_bf16_f32 v36, v144, v145
	v_cvt_pk_bf16_f32 v37, v146, v60
	v_cvt_pk_bf16_f32 v38, v61, v58
	v_cvt_pk_bf16_f32 v39, v59, v56
	v_mov_b32_e32 v144, v34
	s_waitcnt lgkmcnt(4)
	v_mfma_f32_32x32x16_bf16 v[2:17], v[190:193], v[36:39], v[2:17]
	v_mfma_f32_32x32x16_bf16 v[18:33], v[182:185], v[36:39], v[18:33]
	v_cvt_pk_bf16_f32 v36, v57, v54
	v_cvt_pk_bf16_f32 v37, v55, v147
	v_cvt_pk_bf16_f32 v38, v50, v35
	v_cvt_pk_bf16_f32 v39, v148, v149
	s_waitcnt lgkmcnt(3)
	s_nop 0
	v_mfma_f32_32x32x16_bf16 v[18:33], v[194:197], v[36:39], v[18:33]
	s_waitcnt lgkmcnt(2)
	v_mfma_f32_32x32x16_bf16 v[2:17], v[198:201], v[36:39], v[2:17]
	v_cvt_pk_bf16_f32 v36, v150, v151
	v_cvt_pk_bf16_f32 v37, v152, v153
	v_cvt_pk_bf16_f32 v38, v154, v155
	v_cvt_pk_bf16_f32 v39, v156, v48
	s_waitcnt lgkmcnt(1)
	s_nop 0
	v_mfma_f32_32x32x16_bf16 v[18:33], v[202:205], v[36:39], v[18:33]
	s_waitcnt lgkmcnt(0)
	v_mfma_f32_32x32x16_bf16 v[2:17], v[206:209], v[36:39], v[2:17]

; DI unsigned pack2(float a, float b) { unsigned r; asm("v_cvt_pk_bf16_f32 %0, %1, %2\n\ts_nop 1" : "=v"(r) : "v"(a), "v"(b)); return r; }
; #define MFMA32(a, b, c) __builtin_amdgcn_mfma_f32_32x32x16_bf16((a), (b), (c), 0, 0, 0)
; template <int DQK, bool WIN>
; DI void attn_item(const u16* __restrict__ Qb, int ldq, const u16* __restrict__ Kb, int ldk, const u16* __restrict__ Vtb, int qb,
;                   float qscale, float sink2, const u16* __restrict__ zb, int ldz, u16* __restrict__ ob, int ldo, u16* lds) {
;     ...
;       const float nb = -mn * qscale;
;       float ps = 0.f;
; #pragma unroll
;       for (int kb = 0; kb < 2; ++kb)
; #pragma unroll
;         for (int i = 0; i < 16; ++i) { float pv = __builtin_amdgcn_exp2f(fmaf(st[kb][i], qscale, nb)); st[kb][i] = pv; ps += pv; }
;       lsum += ps;
; #pragma unroll
;       for (int kb = 0; kb < 2; ++kb)
; #pragma unroll
;         for (int s2 = 0; s2 < 2; ++s2) {
;           union { bf16x8 v; unsigned u[4]; } pf;
; #pragma unroll
;           for (int j = 0; j < 4; ++j) pf.u[j] = pack2(st[kb][8 * s2 + 2 * j], st[kb][8 * s2 + 2 * j + 1]);
; #pragma unroll
;           for (int vb = 0; vb < 2; ++vb) {
;             const bf16x8 vf = *(const bf16x8*)(vs + (vb * 32 + r) * 72 + (kb * 2 + s2) * 16 + hh * 8);
;             o[vb] = MFMA32(vf, pf.v, o[vb]);
;           }
;         }
.LBB0_326:
	ds_read_b128 v[164:167], v140 offset:27648
	ds_read_b128 v[182:185], v140 offset:27680
	ds_read_b128 v[186:189], v140 offset:32256
	ds_read_b128 v[190:193], v140 offset:32288
	ds_read_b128 v[194:197], v140 offset:27712
	ds_read_b128 v[198:201], v140 offset:32320
	ds_read_b128 v[202:205], v140 offset:27744
	ds_read_b128 v[206:209], v140 offset:32352
	v_mul_f32_e32 v48, 0xbe38aa3b, v34
	v_fmamk_f32 v49, v50, 0x3e38aa3b, v48
	v_exp_f32_e32 v49, v49
	v_fmamk_f32 v51, v51, 0x3e38aa3b, v48
	v_exp_f32_e32 v51, v51
	v_fmamk_f32 v52, v52, 0x3e38aa3b, v48
	v_exp_f32_e32 v52, v52
	v_fmamk_f32 v53, v53, 0x3e38aa3b, v48
	v_exp_f32_e32 v53, v53
	v_fmamk_f32 v62, v148, 0x3e38aa3b, v48
	v_add_f32_e32 v50, 0, v49
	v_exp_f32_e32 v62, v62
	v_fmamk_f32 v63, v147, 0x3e38aa3b, v48
	v_add_f32_e32 v50, v51, v50
	v_exp_f32_e32 v63, v63
	v_fmamk_f32 v64, v149, 0x3e38aa3b, v48
	v_add_f32_e32 v50, v52, v50
	v_exp_f32_e32 v64, v64
	v_fmamk_f32 v65, v150, 0x3e38aa3b, v48
	v_add_f32_e32 v50, v53, v50
	v_exp_f32_e32 v65, v65
	v_fmamk_f32 v143, v151, 0x3e38aa3b, v48
	v_add_f32_e32 v50, v62, v50
	v_exp_f32_e32 v143, v143
	v_fmamk_f32 v144, v145, 0x3e38aa3b, v48
	v_add_f32_e32 v50, v63, v50
	v_exp_f32_e32 v144, v144
	v_fmamk_f32 v145, v146, 0x3e38aa3b, v48
	v_add_f32_e32 v50, v64, v50
	v_exp_f32_e32 v145, v145
	v_fmamk_f32 v60, v60, 0x3e38aa3b, v48
	v_add_f32_e32 v50, v65, v50
	v_exp_f32_e32 v60, v60
	v_fmamk_f32 v61, v61, 0x3e38aa3b, v48
	v_add_f32_e32 v50, v143, v50
	v_exp_f32_e32 v61, v61
	v_fmamk_f32 v58, v58, 0x3e38aa3b, v48
	v_add_f32_e32 v50, v144, v50
	v_exp_f32_e32 v58, v58
	v_fmamk_f32 v59, v59, 0x3e38aa3b, v48
	v_add_f32_e32 v50, v145, v50
	v_exp_f32_e32 v59, v59
	v_fmamk_f32 v56, v56, 0x3e38aa3b, v48
	v_add_f32_e32 v50, v60, v50
	v_exp_f32_e32 v56, v56
	v_fmamk_f32 v57, v57, 0x3e38aa3b, v48
	v_add_f32_e32 v50, v61, v50
	v_exp_f32_e32 v57, v57
	v_fmamk_f32 v54, v54, 0x3e38aa3b, v48
	v_add_f32_e32 v50, v58, v50
	v_exp_f32_e32 v54, v54
	v_fmamk_f32 v55, v55, 0x3e38aa3b, v48
	v_add_f32_e32 v50, v59, v50
	v_exp_f32_e32 v55, v55
	v_fmamk_f32 v36, v36, 0x3e38aa3b, v48
	v_add_f32_e32 v50, v56, v50
	v_exp_f32_e32 v146, v36
	v_add_f32_e32 v50, v57, v50
	v_add_f32_e32 v50, v54, v50
	v_add_f32_e32 v50, v55, v50
	v_fmamk_f32 v37, v37, 0x3e38aa3b, v48
	v_add_f32_e32 v36, v146, v50
	v_exp_f32_e32 v50, v37
	v_fmamk_f32 v35, v35, 0x3e38aa3b, v48
	v_exp_f32_e32 v35, v35
	v_fmamk_f32 v37, v38, 0x3e38aa3b, v48
	v_exp_f32_e32 v147, v37
	v_fmamk_f32 v37, v39, 0x3e38aa3b, v48
	v_exp_f32_e32 v148, v37
	v_fmamk_f32 v37, v40, 0x3e38aa3b, v48
	v_add_f32_e32 v36, v50, v36
	v_exp_f32_e32 v149, v37
	v_fmamk_f32 v37, v41, 0x3e38aa3b, v48
	v_add_f32_e32 v36, v35, v36
	v_exp_f32_e32 v150, v37
	v_fmamk_f32 v37, v42, 0x3e38aa3b, v48
	v_add_f32_e32 v36, v147, v36
	v_exp_f32_e32 v151, v37
	v_fmamk_f32 v37, v43, 0x3e38aa3b, v48
	v_add_f32_e32 v36, v148, v36
	v_exp_f32_e32 v152, v37
	v_fmamk_f32 v37, v44, 0x3e38aa3b, v48
	v_add_f32_e32 v36, v149, v36
	v_exp_f32_e32 v153, v37
	v_fmamk_f32 v37, v45, 0x3e38aa3b, v48
	v_add_f32_e32 v36, v150, v36
	v_exp_f32_e32 v154, v37
	v_fmamk_f32 v37, v46, 0x3e38aa3b, v48
	v_add_f32_e32 v36, v151, v36
	v_exp_f32_e32 v155, v37
	v_fmac_f32_e32 v48, 0x3e38aa3b, v47
	v_add_f32_e32 v36, v152, v36
	v_exp_f32_e32 v48, v48
	v_add_f32_e32 v36, v153, v36
	v_add_f32_e32 v36, v154, v36
	v_add_f32_e32 v36, v155, v36
	v_add_f32_e32 v36, v48, v36
	v_add_f32_e32 v116, v36, v116
	v_cvt_pk_bf16_f32 v36, v49, v51
	v_cvt_pk_bf16_f32 v37, v52, v53
	v_cvt_pk_bf16_f32 v38, v62, v63
	v_cvt_pk_bf16_f32 v39, v64, v65
	s_waitcnt lgkmcnt(7)
	s_nop 0
	v_mfma_f32_32x32x16_bf16 v[18:33], v[164:167], v[36:39], v[18:33]
	s_waitcnt lgkmcnt(5)
	v_mfma_f32_32x32x16_bf16 v[2:17], v[186:189], v[36:39], v[2:17]
	v_cvt_pk_bf16_f32 v36, v143, v144
	v_cvt_pk_bf16_f32 v37, v145, v60
	v_cvt_pk_bf16_f32 v38, v61, v58
	v_cvt_pk_bf16_f32 v39, v59, v56
	v_mov_b32_e32 v144, v34
	s_waitcnt lgkmcnt(4)
	v_mfma_f32_32x32x16_bf16 v[2:17], v[190:193], v[36:39], v[2:17]
	v_mfma_f32_32x32x16_bf16 v[18:33], v[182:185], v[36:39], v[18:33]
	v_cvt_pk_bf16_f32 v36, v57, v54
	v_cvt_pk_bf16_f32 v37, v55, v146
	v_cvt_pk_bf16_f32 v38, v50, v35
	v_cvt_pk_bf16_f32 v39, v147, v148
	s_waitcnt lgkmcnt(3)
	s_nop 0
	v_mfma_f32_32x32x16_bf16 v[18:33], v[194:197], v[36:39], v[18:33]
	s_waitcnt lgkmcnt(2)
	v_mfma_f32_32x32x16_bf16 v[2:17], v[198:201], v[36:39], v[2:17]
	v_cvt_pk_bf16_f32 v36, v149, v150
	v_cvt_pk_bf16_f32 v37, v151, v152
	v_cvt_pk_bf16_f32 v38, v153, v154
	v_cvt_pk_bf16_f32 v39, v155, v48
	s_waitcnt lgkmcnt(1)
	s_nop 0
	v_mfma_f32_32x32x16_bf16 v[18:33], v[202:205], v[36:39], v[18:33]
	s_waitcnt lgkmcnt(0)
	v_mfma_f32_32x32x16_bf16 v[2:17], v[206:209], v[36:39], v[2:17]

; #define GM_LOAD(RA, RB, KT)                                                                 \
;   _Pragma("unroll") for (int i = 0; i < 4; ++i) {                                           \
;     RA[i] = *(const u32x4*)(ag + (size_t)(32 * i) * lda + (KT) * 64);                       \
;     RB[i] = *(const u32x4*)(bg + (size_t)(32 * i) * ldb + (KT) * 64);                       \
;   }
; template <bool DEEP = true>
; DI void gemm_main(f32x4 (&acc)[4][4], const u16* __restrict__ A, int lda, const u16* __restrict__ B, int ldb, int K, u16* lds) {
;     ...
;   if (DEEP) {
;     u32x4 ra0[4], rb0[4], ra1[4], rb1[4];
;     GM_LOAD(ra0, rb0, 0)
;     GM_LOAD(ra1, rb1, 1)
;     __syncthreads();
;     GM_STORE(ra0, rb0, 0)
;     __syncthreads();
;     for (int kt = 0; kt < nk; kt += 2) {
;       if (kt + 2 < nk) { GM_LOAD(ra0, rb0, kt + 2) }
;       GM_COMPUTE(0)
;       __builtin_amdgcn_sched_barrier(0);
;       GM_STORE(ra1, rb1, 1)
;       __syncthreads();
;       if (kt + 3 < nk) { GM_LOAD(ra1, rb1, kt + 3) }
;       GM_COMPUTE(1)
.LBB0_337:
	s_or_b64 exec, exec, s[18:19]
	s_and_b32 s18, s20, 3
	s_mul_i32 s0, s24, 0x1540
	s_mul_hi_i32 s1, s24, 0x1540
	s_add_u32 s0, s16, s0
	s_addc_u32 s1, s17, s1
	v_mov_b32_e32 v35, v169
	s_lshl_b32 s19, s18, 15
	v_mov_b64_e32 v[2:3], s[0:1]
	v_ashrrev_i32_e32 v68, 3, v35
	v_lshlrev_b32_e32 v0, 4, v35
	s_add_u32 s26, s21, s19
	v_ashrrev_i32_e32 v69, 31, v68
	v_mad_i64_i32 v[2:3], s[0:1], v68, s60, v[2:3]
	v_and_b32_e32 v0, 0x70, v0
	s_addc_u32 s27, s22, 0
	v_lshl_add_u64 v[2:3], v[2:3], 0, v[0:1]
	v_lshlrev_b64 v[4:5], 8, v[68:69]
	s_mov_b32 s0, 0x2b000
	v_lshl_add_u64 v[4:5], s[26:27], 0, v[4:5]
	v_add_co_u32_e32 v10, vcc, s0, v2
	v_lshl_add_u64 v[6:7], v[4:5], 0, v[0:1]
	s_nop 0
	v_addc_co_u32_e32 v11, vcc, 0, v3, vcc
	s_movk_i32 s0, 0x2000
	v_add_co_u32_e32 v14, vcc, s0, v6
	global_load_dwordx4 v[36:39], v[2:3], off offset:2048
	global_load_dwordx4 v[40:43], v[6:7], off
	v_addc_co_u32_e32 v15, vcc, 0, v7, vcc
	v_add_co_u32_e32 v18, vcc, s28, v2
	s_movk_i32 s0, 0x4000
	s_nop 0
	v_addc_co_u32_e32 v19, vcc, 0, v3, vcc
	global_load_dwordx4 v[44:47], v[10:11], off
	v_add_co_u32_e32 v22, vcc, s0, v6
	global_load_dwordx4 v[48:51], v[14:15], off
	s_nop 0
	v_addc_co_u32_e32 v23, vcc, 0, v7, vcc
	s_mov_b32 s0, 0x80000
	global_load_dwordx4 v[52:55], v[18:19], off offset:2048
	v_add_co_u32_e32 v26, vcc, s0, v2
	global_load_dwordx4 v[56:59], v[22:23], off
	s_nop 0
	v_addc_co_u32_e32 v27, vcc, 0, v3, vcc
	s_movk_i32 s0, 0x6000
	global_load_dwordx4 v[60:63], v[26:27], off
	v_add_co_u32_e32 v30, vcc, s0, v6
	v_xor_b32_e32 v71, v68, v35
	s_nop 0
	v_addc_co_u32_e32 v31, vcc, 0, v7, vcc
	global_load_dwordx4 v[64:67], v[30:31], off
	s_nop 0
	global_load_dwordx4 v[2:5], v[2:3], off offset:2176
	s_nop 0
	global_load_dwordx4 v[6:9], v[6:7], off offset:128
	s_nop 0
	global_load_dwordx4 v[10:13], v[10:11], off offset:128
	s_nop 0
	global_load_dwordx4 v[14:17], v[14:15], off offset:128
	s_nop 0
	global_load_dwordx4 v[18:21], v[18:19], off offset:2176
	s_nop 0
	global_load_dwordx4 v[22:25], v[22:23], off offset:128
	s_nop 0
	global_load_dwordx4 v[26:29], v[26:27], off offset:128
	s_nop 0
	global_load_dwordx4 v[30:33], v[30:31], off offset:128
	v_lshlrev_b32_e32 v69, 4, v71
	v_and_b32_e32 v69, 0x70, v69
	v_lshlrev_b32_e32 v68, 7, v68
	v_add3_u32 v120, s33, v69, v68
	s_waitcnt lgkmcnt(0)
	s_barrier
	s_mov_b32 s0, 0x1ffffc0
	v_lshrrev_b32_e32 v70, 4, v35
	v_bfe_u32 v0, v35, 4, 2
	s_waitcnt vmcnt(15)
	ds_write_b128 v120, v[36:39]
	s_waitcnt vmcnt(14)
	ds_write_b128 v120, v[40:43] offset:16384
	s_waitcnt vmcnt(13)
	ds_write_b128 v120, v[44:47] offset:4096
	s_waitcnt vmcnt(12)
	ds_write_b128 v120, v[48:51] offset:20480
	s_waitcnt vmcnt(11)
	ds_write_b128 v120, v[52:55] offset:8192
	s_waitcnt vmcnt(10)
	ds_write_b128 v120, v[56:59] offset:24576
	s_waitcnt vmcnt(9)
	ds_write_b128 v120, v[60:63] offset:12288
	s_waitcnt vmcnt(8)
	ds_write_b128 v120, v[64:67] offset:28672
	v_and_b32_e32 v36, 15, v35
	v_lshrrev_b32_e32 v37, 1, v35
	v_and_or_b32 v36, v37, s0, v36
	v_lshlrev_b32_e32 v37, 7, v35
	v_and_b32_e32 v35, 7, v35
	v_and_b32_e32 v37, 0x2780, v37
	v_bitop3_b32 v38, v70, v35, 3 bitop3:0x6c
	v_bitop3_b32 v0, v0, v35, 4 bitop3:0x36
	v_lshl_add_u32 v36, v36, 7, s33
	v_add_u32_e32 v37, s33, v37
	v_lshlrev_b32_e32 v38, 4, v38
	v_lshlrev_b32_e32 v0, 4, v0
	s_waitcnt lgkmcnt(0)
	s_barrier
	v_add_u32_e32 v121, v36, v38
	v_add_u32_e32 v122, v37, v38
	v_add_u32_e32 v35, v36, v0
	v_add_u32_e32 v0, v37, v0
	s_setprio 1
	ds_read_b128 v[36:39], v121
	ds_read_b128 v[40:43], v121 offset:2048
	ds_read_b128 v[44:47], v121 offset:4096
	ds_read_b128 v[48:51], v121 offset:6144
	ds_read_b128 v[52:55], v122 offset:16384
	ds_read_b128 v[68:71], v122 offset:18432
	ds_read_b128 v[84:87], v122 offset:20480
	ds_read_b128 v[100:103], v122 offset:22528
	s_waitcnt lgkmcnt(3)
	v_mfma_f32_16x16x32_bf16 v[56:59], v[36:39], v[52:55], 0
	v_mfma_f32_16x16x32_bf16 v[60:63], v[40:43], v[52:55], 0
	v_mfma_f32_16x16x32_bf16 v[64:67], v[44:47], v[52:55], 0
	v_mfma_f32_16x16x32_bf16 v[52:55], v[48:51], v[52:55], 0
	s_waitcnt lgkmcnt(2)
	v_mfma_f32_16x16x32_bf16 v[72:75], v[36:39], v[68:71], 0
	v_mfma_f32_16x16x32_bf16 v[76:79], v[40:43], v[68:71], 0
	v_mfma_f32_16x16x32_bf16 v[80:83], v[44:47], v[68:71], 0
	v_mfma_f32_16x16x32_bf16 v[68:71], v[48:51], v[68:71], 0
	s_waitcnt lgkmcnt(1)
	v_mfma_f32_16x16x32_bf16 v[88:91], v[36:39], v[84:87], 0
	v_mfma_f32_16x16x32_bf16 v[92:95], v[40:43], v[84:87], 0
	v_mfma_f32_16x16x32_bf16 v[96:99], v[44:47], v[84:87], 0
	v_mfma_f32_16x16x32_bf16 v[84:87], v[48:51], v[84:87], 0
	s_waitcnt lgkmcnt(0)
	v_mfma_f32_16x16x32_bf16 v[36:39], v[36:39], v[100:103], 0
	v_mfma_f32_16x16x32_bf16 v[40:43], v[40:43], v[100:103], 0
	v_mfma_f32_16x16x32_bf16 v[44:47], v[44:47], v[100:103], 0
	v_mfma_f32_16x16x32_bf16 v[48:51], v[48:51], v[100:103], 0
	ds_read_b128 v[100:103], v35
	ds_read_b128 v[104:107], v35 offset:2048
	ds_read_b128 v[108:111], v35 offset:4096
	ds_read_b128 v[112:115], v35 offset:6144
	ds_read_b128 v[116:119], v0 offset:16384
	s_waitcnt lgkmcnt(0)
	v_mfma_f32_16x16x32_bf16 v[56:59], v[100:103], v[116:119], v[56:59]
	v_mfma_f32_16x16x32_bf16 v[60:63], v[104:107], v[116:119], v[60:63]
	v_mfma_f32_16x16x32_bf16 v[64:67], v[108:111], v[116:119], v[64:67]
	v_mfma_f32_16x16x32_bf16 v[52:55], v[112:115], v[116:119], v[52:55]
	ds_read_b128 v[116:119], v0 offset:18432
	s_waitcnt lgkmcnt(0)
	v_mfma_f32_16x16x32_bf16 v[72:75], v[100:103], v[116:119], v[72:75]
	v_mfma_f32_16x16x32_bf16 v[76:79], v[104:107], v[116:119], v[76:79]
	v_mfma_f32_16x16x32_bf16 v[80:83], v[108:111], v[116:119], v[80:83]
	v_mfma_f32_16x16x32_bf16 v[68:71], v[112:115], v[116:119], v[68:71]
	ds_read_b128 v[116:119], v0 offset:20480
	s_waitcnt lgkmcnt(0)
	v_mfma_f32_16x16x32_bf16 v[88:91], v[100:103], v[116:119], v[88:91]
	v_mfma_f32_16x16x32_bf16 v[92:95], v[104:107], v[116:119], v[92:95]
	v_mfma_f32_16x16x32_bf16 v[96:99], v[108:111], v[116:119], v[96:99]
	v_mfma_f32_16x16x32_bf16 v[84:87], v[112:115], v[116:119], v[84:87]
	ds_read_b128 v[116:119], v0 offset:22528
	s_waitcnt lgkmcnt(0)
	v_mfma_f32_16x16x32_bf16 v[36:39], v[100:103], v[116:119], v[36:39]
	v_mfma_f32_16x16x32_bf16 v[40:43], v[104:107], v[116:119], v[40:43]
	v_mfma_f32_16x16x32_bf16 v[44:47], v[108:111], v[116:119], v[44:47]
	v_mfma_f32_16x16x32_bf16 v[48:51], v[112:115], v[116:119], v[48:51]
	s_setprio 0
	s_waitcnt vmcnt(7)
	ds_write_b128 v120, v[2:5] offset:32768
	s_waitcnt vmcnt(6)
	ds_write_b128 v120, v[6:9] offset:49152
	s_waitcnt vmcnt(5)
	ds_write_b128 v120, v[10:13] offset:36864
	s_waitcnt vmcnt(4)
	ds_write_b128 v120, v[14:17] offset:53248
	s_waitcnt vmcnt(3)
	ds_write_b128 v120, v[18:21] offset:40960
	s_waitcnt vmcnt(2)
	ds_write_b128 v120, v[22:25] offset:57344
	s_waitcnt vmcnt(1)
	ds_write_b128 v120, v[26:29] offset:45056
	s_waitcnt vmcnt(0)
	ds_write_b128 v120, v[30:33] offset:61440
	s_waitcnt lgkmcnt(0)
	s_barrier
; DI int tidx() { int t = threadIdx.x & 255; asm volatile("" : "+v"(t)); return t; }
; template <bool DEEP = true>
; DI void gemm_main(f32x4 (&acc)[4][4], const u16* __restrict__ A, int lda, const u16* __restrict__ B, int ldb, int K, u16* lds) {
;     ...
;       GM_COMPUTE(1)
;       __builtin_amdgcn_sched_barrier(0);
;       if (kt + 2 < nk) { GM_STORE(ra0, rb0, 0) }
;       __syncthreads();
; DI void stage_c(const f32x4 (&acc)[4][4], float* Cs) {
;   const int tid = tidx(), lane = tid & 63, w = tid >> 6;
;   const int wm = w >> 1, wn = w & 1, fr = lane & 15, fq = lane >> 4;
; #pragma unroll
;   for (int m = 0; m < 4; ++m)
; #pragma unroll
;     for (int n = 0; n < 4; ++n)
; #pragma unroll
;       for (int j = 0; j < 4; ++j) Cs[(wm * 64 + m * 16 + fq * 4 + j) * CST + wn * 64 + n * 16 + fr] = acc[m][n][j];
;   __syncthreads();
	s_setprio 1
	ds_read_b128 v[2:5], v121 offset:32768
	ds_read_b128 v[6:9], v121 offset:34816
	ds_read_b128 v[10:13], v121 offset:36864
	ds_read_b128 v[14:17], v121 offset:38912
	ds_read_b128 v[18:21], v122 offset:49152
	s_waitcnt lgkmcnt(0)
	v_mfma_f32_16x16x32_bf16 v[22:25], v[2:5], v[18:21], v[56:59]
	v_mfma_f32_16x16x32_bf16 v[26:29], v[6:9], v[18:21], v[60:63]
	v_mfma_f32_16x16x32_bf16 v[30:33], v[10:13], v[18:21], v[64:67]
	v_mfma_f32_16x16x32_bf16 v[18:21], v[14:17], v[18:21], v[52:55]
	s_nop 2
	ds_read_b128 v[52:55], v122 offset:51200
	s_waitcnt lgkmcnt(0)
	v_mfma_f32_16x16x32_bf16 v[56:59], v[2:5], v[52:55], v[72:75]
	v_mfma_f32_16x16x32_bf16 v[60:63], v[6:9], v[52:55], v[76:79]
	v_mfma_f32_16x16x32_bf16 v[64:67], v[10:13], v[52:55], v[80:83]
	v_mfma_f32_16x16x32_bf16 v[52:55], v[14:17], v[52:55], v[68:71]
	s_nop 2
	ds_read_b128 v[68:71], v122 offset:53248
	s_waitcnt lgkmcnt(0)
	v_mfma_f32_16x16x32_bf16 v[72:75], v[2:5], v[68:71], v[88:91]
	v_mfma_f32_16x16x32_bf16 v[76:79], v[6:9], v[68:71], v[92:95]
	v_mfma_f32_16x16x32_bf16 v[80:83], v[10:13], v[68:71], v[96:99]
	v_mfma_f32_16x16x32_bf16 v[68:71], v[14:17], v[68:71], v[84:87]
	s_nop 2
	ds_read_b128 v[84:87], v122 offset:55296
	s_waitcnt lgkmcnt(0)
	v_mfma_f32_16x16x32_bf16 v[2:5], v[2:5], v[84:87], v[36:39]
	v_mfma_f32_16x16x32_bf16 v[6:9], v[6:9], v[84:87], v[40:43]
	v_mfma_f32_16x16x32_bf16 v[10:13], v[10:13], v[84:87], v[44:47]
	v_mfma_f32_16x16x32_bf16 v[14:17], v[14:17], v[84:87], v[48:51]
	ds_read_b128 v[36:39], v35 offset:32768
	ds_read_b128 v[40:43], v35 offset:34816
	ds_read_b128 v[44:47], v35 offset:36864
	ds_read_b128 v[48:51], v35 offset:38912
	ds_read_b128 v[84:87], v0 offset:49152
	s_waitcnt lgkmcnt(0)
	v_mfma_f32_16x16x32_bf16 v[22:25], v[36:39], v[84:87], v[22:25]
	v_mfma_f32_16x16x32_bf16 v[26:29], v[40:43], v[84:87], v[26:29]
	v_mfma_f32_16x16x32_bf16 v[30:33], v[44:47], v[84:87], v[30:33]
	v_mfma_f32_16x16x32_bf16 v[18:21], v[48:51], v[84:87], v[18:21]
	ds_read_b128 v[84:87], v0 offset:51200
	s_waitcnt lgkmcnt(0)
	v_mfma_f32_16x16x32_bf16 v[56:59], v[36:39], v[84:87], v[56:59]
	v_mfma_f32_16x16x32_bf16 v[60:63], v[40:43], v[84:87], v[60:63]
	v_mfma_f32_16x16x32_bf16 v[64:67], v[44:47], v[84:87], v[64:67]
	v_mfma_f32_16x16x32_bf16 v[52:55], v[48:51], v[84:87], v[52:55]
	ds_read_b128 v[84:87], v0 offset:53248
	s_waitcnt lgkmcnt(0)
	v_mfma_f32_16x16x32_bf16 v[72:75], v[36:39], v[84:87], v[72:75]
	v_mfma_f32_16x16x32_bf16 v[76:79], v[40:43], v[84:87], v[76:79]
	v_mfma_f32_16x16x32_bf16 v[80:83], v[44:47], v[84:87], v[80:83]
	v_mfma_f32_16x16x32_bf16 v[68:71], v[48:51], v[84:87], v[68:71]
	ds_read_b128 v[84:87], v0 offset:55296
	s_waitcnt lgkmcnt(0)
	v_mfma_f32_16x16x32_bf16 v[2:5], v[36:39], v[84:87], v[2:5]
	v_mfma_f32_16x16x32_bf16 v[6:9], v[40:43], v[84:87], v[6:9]
	v_mfma_f32_16x16x32_bf16 v[10:13], v[44:47], v[84:87], v[10:13]
	v_mfma_f32_16x16x32_bf16 v[14:17], v[48:51], v[84:87], v[14:17]
	s_setprio 0
	v_mov_b32_e32 v0, v169
	s_barrier
	s_mov_b32 s0, 0xfffffc0
	v_lshrrev_b32_e32 v36, 2, v0
	v_lshrrev_b32_e32 v35, 1, v0
	v_and_b32_e32 v36, 12, v36
	v_and_or_b32 v35, v35, s0, v36
	v_and_b32_e32 v0, 0x4f, v0
	v_mul_lo_u32 v35, v35, s92
	v_lshlrev_b32_e32 v0, 2, v0
	v_add3_u32 v0, s33, v35, v0
	ds_write2_b32 v0, v22, v56 offset1:16
	ds_write2_b32 v0, v23, v57 offset0:132 offset1:148
	v_add_u32_e32 v22, 0x400, v0
	ds_write2_b32 v22, v24, v58 offset0:8 offset1:24
	ds_write2_b32 v22, v25, v59 offset0:140 offset1:156
	ds_write2_b32 v0, v72, v2 offset0:32 offset1:48
	ds_write2_b32 v0, v73, v3 offset0:164 offset1:180
	ds_write2_b32 v22, v74, v4 offset0:40 offset1:56
	ds_write2_b32 v22, v75, v5 offset0:172 offset1:188
	v_add_u32_e32 v2, 0x2000, v0
	v_add_u32_e32 v3, 0x2400, v0
	ds_write2_b32 v2, v26, v60 offset0:64 offset1:80
	ds_write2_b32 v2, v27, v61 offset0:196 offset1:212
	ds_write2_b32 v3, v28, v62 offset0:72 offset1:88
	ds_write2_b32 v3, v29, v63 offset0:204 offset1:220
	ds_write2_b32 v2, v76, v6 offset0:96 offset1:112
	ds_write2_b32 v2, v77, v7 offset0:228 offset1:244
	ds_write2_b32 v3, v78, v8 offset0:104 offset1:120
	ds_write2_b32 v3, v79, v9 offset0:236 offset1:252
	v_add_u32_e32 v2, 0x4000, v0
	v_add_u32_e32 v3, 0x4400, v0
	v_add_u32_e32 v4, 0x4800, v0
	ds_write2_b32 v2, v30, v64 offset0:128 offset1:144
	ds_write2_b32 v3, v31, v65 offset0:4 offset1:20
	ds_write2_b32 v3, v32, v66 offset0:136 offset1:152
	ds_write2_b32 v4, v33, v67 offset0:12 offset1:28
	ds_write2_b32 v2, v80, v10 offset0:160 offset1:176
	ds_write2_b32 v3, v81, v11 offset0:36 offset1:52
	ds_write2_b32 v3, v82, v12 offset0:168 offset1:184
	ds_write2_b32 v4, v83, v13 offset0:44 offset1:60
	v_add_u32_e32 v2, 0x6000, v0
	v_add_u32_e32 v3, 0x6400, v0
	v_add_u32_e32 v0, 0x6800, v0
	ds_write2_b32 v2, v18, v52 offset0:192 offset1:208
	ds_write2_b32 v3, v19, v53 offset0:68 offset1:84
	ds_write2_b32 v3, v20, v54 offset0:200 offset1:216
	ds_write2_b32 v0, v21, v55 offset0:76 offset1:92
	ds_write2_b32 v2, v68, v14 offset0:224 offset1:240
	ds_write2_b32 v3, v69, v15 offset0:100 offset1:116
	ds_write2_b32 v3, v70, v16 offset0:232 offset1:248
	ds_write2_b32 v0, v71, v17 offset0:108 offset1:124
	v_lshlrev_b32_e32 v0, 3, v34
	v_ashrrev_i32_e32 v18, 3, v34
	v_and_b32_e32 v0, 56, v0
	v_lshlrev_b32_e32 v2, 2, v0
	v_readlane_b32 s25, v254, 16
	v_mul_lo_u32 v3, v18, s92
	v_add3_u32 v17, s33, v2, v3
	v_lshl_add_u32 v16, v18, 2, s25
	s_waitcnt lgkmcnt(0)
	s_barrier
; DI u32x4 pack8(const float* f) { u32x4 o; o.x = pack2(f[0], f[1]); o.y = pack2(f[2], f[3]); o.z = pack2(f[4], f[5]); o.w = pack2(f[6], f[7]); return o; }
; DI void kv_tile(PREF p, int l, int idx, unsigned char* ldsb) {
;     ...
; #pragma unroll
;   for (int q = 0; q < 4; ++q) {
;     int r = (tid >> 3) + 32 * q, c = (tid & 7) * 8;
;     float rs = aux[r];
;     float v[8]; ld8(Cs + r * CST + c, v);
; #pragma unroll
;     for (int j = 0; j < 8; ++j) v[j] *= rs;
;     *(u32x4*)(p.Km + (size_t)(row0 + r) * 384 + head * 96 + c) = pack8(v);
;   }
;   {
;     int b = row0 >> 12, s0 = row0 & 4095;
; #pragma unroll
;     for (int q = 0; q < 4; ++q) {
;       int item = tid + 256 * q; int c = item & 63, rg = item >> 6;
;       float v[8];
; #pragma unroll
;       for (int j = 0; j < 8; ++j) v[j] = Cs[(rg * 8 + j) * CST + 64 + c] * aux[rg * 8 + j];
;       *(u32x4*)(p.Vmt + ((size_t)(b * 4 + head) * 64 + c) * S_ + s0 + rg * 8) = pack8(v);
;     }
	ds_read2_b32 v[10:11], v16 offset1:32
	ds_read_b128 v[2:5], v17
	ds_read_b128 v[6:9], v17 offset:16
	s_mul_i32 s52, s18, 0xc0
	s_add_u32 s0, s12, s52
	s_addc_u32 s1, s13, 0
	v_lshlrev_b32_e32 v0, 1, v0
	v_lshl_add_u64 v[12:13], s[0:1], 0, v[0:1]
	s_waitcnt lgkmcnt(1)
	v_mul_f32_e32 v0, v10, v2
	v_mul_f32_e32 v2, v10, v3
	v_mul_f32_e32 v3, v10, v4
	v_mul_f32_e32 v4, v10, v5
	s_waitcnt lgkmcnt(0)
	v_mul_f32_e32 v5, v10, v6
	v_cvt_pk_bf16_f32 v2, v0, v2
	v_add_u32_e32 v0, s24, v18
	v_mul_f32_e32 v6, v10, v7
	v_mul_f32_e32 v7, v10, v8
	v_mul_f32_e32 v8, v10, v9
	v_cvt_pk_bf16_f32 v3, v3, v4
	v_cvt_pk_bf16_f32 v4, v5, v6
	v_cvt_pk_bf16_f32 v5, v7, v8
	v_mad_i64_i32 v[14:15], s[0:1], v0, s96, v[12:13]
	ds_read_b128 v[6:9], v17 offset:16896
	global_store_dwordx4 v[14:15], v[2:5], off
	ds_read_b128 v[2:5], v17 offset:16912
	s_and_b32 s19, s23, 0xf80
	v_and_b32_e32 v54, 1, v34
	s_waitcnt lgkmcnt(1)
	v_mul_f32_e32 v6, v11, v6
	v_mul_f32_e32 v7, v11, v7
	s_waitcnt lgkmcnt(0)
	v_mul_f32_e32 v14, v11, v3
	v_mul_f32_e32 v10, v11, v2
	v_mul_f32_e32 v15, v11, v4
	v_mul_f32_e32 v5, v11, v5
	v_cvt_pk_bf16_f32 v4, v10, v14
	v_add_u32_e32 v14, 32, v0
	v_mul_f32_e32 v8, v11, v8
	v_mul_f32_e32 v9, v11, v9
	v_cvt_pk_bf16_f32 v2, v6, v7
	v_cvt_pk_bf16_f32 v3, v8, v9
	v_cvt_pk_bf16_f32 v5, v15, v5
	v_mad_i64_i32 v[14:15], s[0:1], v14, s96, v[12:13]
	ds_read2_b32 v[10:11], v16 offset0:64 offset1:96
	ds_read_b128 v[6:9], v17 offset:33792
	global_store_dwordx4 v[14:15], v[2:5], off
	ds_read_b128 v[2:5], v17 offset:33808
	v_cmp_eq_u32_e32 vcc, 0, v54
	s_waitcnt lgkmcnt(1)
	v_mul_f32_e32 v6, v10, v6
	v_mul_f32_e32 v7, v10, v7
	v_mul_f32_e32 v8, v10, v8
	v_mul_f32_e32 v9, v10, v9
	s_waitcnt lgkmcnt(0)
	v_mul_f32_e32 v14, v10, v2
	v_mul_f32_e32 v15, v10, v3
	v_mul_f32_e32 v16, v10, v4
	v_mul_f32_e32 v5, v10, v5
	v_add_u32_e32 v10, 64, v0
	v_cvt_pk_bf16_f32 v2, v6, v7
	v_cvt_pk_bf16_f32 v3, v8, v9
	v_cvt_pk_bf16_f32 v4, v14, v15
	v_cvt_pk_bf16_f32 v5, v16, v5
	ds_read_b128 v[6:9], v17 offset:50688
	v_mad_i64_i32 v[14:15], s[0:1], v10, s96, v[12:13]
	global_store_dwordx4 v[14:15], v[2:5], off
	ds_read_b128 v[2:5], v17 offset:50704
	s_waitcnt lgkmcnt(1)
	v_mul_f32_e32 v6, v11, v6
	v_mul_f32_e32 v7, v11, v7
	v_add_u32_e32 v0, 0x60, v0
	v_mul_f32_e32 v8, v11, v8
	s_waitcnt lgkmcnt(0)
	v_mul_f32_e32 v10, v11, v2
	v_cvt_pk_bf16_f32 v2, v6, v7
	v_mad_i64_i32 v[6:7], s[0:1], v0, s96, v[12:13]
	s_ashr_i32 s0, s20, 5
	s_and_b32 s0, s0, -4
	s_or_b32 s0, s0, s18
	s_ashr_i32 s1, s0, 31
	v_mul_f32_e32 v14, v11, v3
	v_mul_f32_e32 v15, v11, v4
	v_mul_f32_e32 v5, v11, v5
	v_cvt_pk_bf16_f32 v4, v10, v14
	s_lshl_b64 s[0:1], s[0:1], 19
	v_mul_f32_e32 v9, v11, v9
	v_cvt_pk_bf16_f32 v3, v8, v9
	v_cvt_pk_bf16_f32 v5, v15, v5
	global_store_dwordx4 v[6:7], v[2:5], off
	s_add_u32 s0, s14, s0
	s_addc_u32 s1, s15, s1
	v_and_b32_e32 v4, 63, v34
	v_lshlrev_b32_e32 v0, 13, v4
	v_and_b32_e32 v12, -8, v18
	v_lshl_add_u64 v[2:3], s[0:1], 0, v[0:1]
	v_mul_lo_u32 v0, v12, s92
	v_lshlrev_b32_e32 v20, 2, v4
	s_lshl_b32 s0, s19, 1
	s_mov_b32 s1, s53
	v_add3_u32 v0, s33, v0, v20
	v_lshl_add_u32 v6, v12, 2, s25
	v_lshl_add_u64 v[10:11], v[2:3], 0, s[0:1]
	ds_read2_b32 v[14:15], v0 offset0:64 offset1:196
	ds_read_b128 v[2:5], v6
	v_add_u32_e32 v7, 0x400, v0
	ds_read2_b32 v[16:17], v7 offset0:72 offset1:204
	ds_read_b96 v[6:8], v6 offset:16
	ds_read_b32 v9, v0 offset:3424
	v_add_u32_e32 v0, 0x800, v0
	v_ashrrev_i32_e32 v13, 31, v12
	s_waitcnt lgkmcnt(3)
	v_mul_f32_e32 v19, v14, v2
	v_mul_f32_e32 v15, v15, v3
	ds_read2_b32 v[2:3], v0 offset0:80 offset1:212
	v_or_b32_e32 v0, 7, v18
	v_mul_lo_u32 v14, v0, s92
	s_waitcnt lgkmcnt(3)
	v_mul_f32_e32 v4, v16, v4
	v_add3_u32 v16, s33, v14, v20
	v_add_u32_e32 v14, 0x100, v34
	v_ashrrev_i32_e32 v21, 3, v14
	v_and_b32_e32 v14, -8, v21
	v_mul_f32_e32 v5, v17, v5
	v_lshl_add_u32 v0, v0, 2, s25
	v_mul_lo_u32 v17, v14, s92
	v_add3_u32 v18, s33, v17, v20
	ds_read_b32 v16, v16 offset:256
	ds_read_b32 v0, v0
	ds_read_b32 v22, v18 offset:3424
	s_waitcnt lgkmcnt(3)
	v_mul_f32_e32 v6, v2, v6
	v_mul_f32_e32 v7, v3, v7
	v_cvt_pk_bf16_f32 v3, v4, v5
	s_waitcnt lgkmcnt(1)
	v_mul_f32_e32 v0, v16, v0
	v_cvt_pk_bf16_f32 v4, v6, v7
	v_lshl_add_u64 v[6:7], v[12:13], 1, v[10:11]
	v_mul_f32_e32 v8, v9, v8
	v_cvt_pk_bf16_f32 v2, v19, v15
	v_cvt_pk_bf16_f32 v5, v8, v0
	global_store_dwordx4 v[6:7], v[2:5], off
	ds_read2_b32 v[12:13], v18 offset0:64 offset1:196
	v_lshl_add_u32 v0, v14, 2, s25
	ds_read_b128 v[2:5], v0
	ds_read_b96 v[6:8], v0 offset:16
	v_add_u32_e32 v0, 0x400, v18
	ds_read2_b32 v[16:17], v0 offset0:72 offset1:204
	v_add_u32_e32 v0, 0x800, v18
	ds_read2_b32 v[18:19], v0 offset0:80 offset1:212
	s_waitcnt lgkmcnt(3)
	v_mul_f32_e32 v0, v12, v2
	v_or_b32_e32 v2, 7, v21
	v_mul_f32_e32 v9, v13, v3
	v_mul_lo_u32 v3, v2, s92
	v_add3_u32 v3, s33, v3, v20
	v_lshl_add_u32 v2, v2, 2, s25
	s_waitcnt lgkmcnt(1)
	v_mul_f32_e32 v13, v16, v4
	v_mul_f32_e32 v16, v17, v5
	s_waitcnt lgkmcnt(0)
	v_mul_f32_e32 v17, v18, v6
	v_mul_f32_e32 v18, v19, v7
	ds_read_b32 v6, v3 offset:256
	ds_read_b32 v7, v2
	v_add_u32_e32 v2, 0x200, v34
	v_ashrrev_i32_e32 v21, 3, v2
	v_and_b32_e32 v12, -8, v21
	v_ashrrev_i32_e32 v15, 31, v14
	v_mul_lo_u32 v2, v12, s92
	v_mul_f32_e32 v19, v22, v8
	v_add3_u32 v22, s33, v2, v20
	v_lshl_add_u32 v23, v12, 2, s25
	v_lshl_add_u64 v[14:15], v[14:15], 1, v[10:11]
	ds_read_b128 v[2:5], v23
	ds_read_b32 v24, v22 offset:3424
	s_waitcnt lgkmcnt(2)
	v_mul_f32_e32 v25, v6, v7
	v_cvt_pk_bf16_f32 v6, v0, v9
	v_cvt_pk_bf16_f32 v7, v13, v16
	v_cvt_pk_bf16_f32 v8, v17, v18
	v_cvt_pk_bf16_f32 v9, v19, v25
	global_store_dwordx4 v[14:15], v[6:9], off
	ds_read2_b32 v[14:15], v22 offset0:64 offset1:196
	v_add_u32_e32 v0, 0x400, v22
	ds_read2_b32 v[16:17], v0 offset0:72 offset1:204
	ds_read_b96 v[6:8], v23 offset:16
	v_ashrrev_i32_e32 v13, 31, v12
	s_waitcnt lgkmcnt(2)
; DI u32x4 pack8(const float* f) { u32x4 o; o.x = pack2(f[0], f[1]); o.y = pack2(f[2], f[3]); o.z = pack2(f[4], f[5]); o.w = pack2(f[6], f[7]); return o; }
; DI void kv_tile(PREF p, int l, int idx, unsigned char* ldsb) {
;     ...
;   {
;     int b = row0 >> 12, s0 = row0 & 4095;
; #pragma unroll
;     for (int q = 0; q < 4; ++q) {
;       int item = tid + 256 * q; int c = item & 63, rg = item >> 6;
;       float v[8];
; #pragma unroll
;       for (int j = 0; j < 8; ++j) v[j] = Cs[(rg * 8 + j) * CST + 64 + c] * aux[rg * 8 + j];
;       *(u32x4*)(p.Vmt + ((size_t)(b * 4 + head) * 64 + c) * S_ + s0 + rg * 8) = pack8(v);
;     }
;   }
;   {
;     int r = tid >> 1, half = tid & 1;
;     int t = row0 + r, s = t & 4095;
;     const u16* src = p.hb + (size_t)t * HW + OFF_KR;
;     float x1[16], x2[16];
;     unpack8(*(const u32x4*)(src), x1); unpack8(*(const u32x4*)(src + 8), x1 + 8);
;     unpack8(*(const u32x4*)(src + 16), x2); unpack8(*(const u32x4*)(src + 24), x2 + 8);
;     const float* cs = p.rcos + s * 16; const float* sn = p.rsin + s * 16;
;     float ov[16];
; #pragma unroll
;     for (int i = 0; i < 16; ++i) ov[i] = half ? (x2[i] * cs[i] + x1[i] * sn[i]) : (x1[i] * cs[i] - x2[i] * sn[i]);
	v_mul_f32_e32 v0, v14, v2
	v_or_b32_e32 v14, 7, v21
	v_mul_f32_e32 v9, v15, v3
	s_waitcnt lgkmcnt(1)
	v_mul_f32_e32 v4, v16, v4
	v_mul_lo_u32 v15, v14, s92
	v_lshl_add_u32 v16, v14, 2, s25
	v_add_u32_e32 v14, 0x300, v34
	v_add_u32_e32 v2, 0x800, v22
	v_ashrrev_i32_e32 v18, 3, v14
	ds_read2_b32 v[2:3], v2 offset0:80 offset1:212
	v_and_b32_e32 v14, -8, v18
	v_mul_f32_e32 v5, v17, v5
	v_add3_u32 v15, s33, v15, v20
	v_mul_lo_u32 v17, v14, s92
	v_add3_u32 v19, s33, v17, v20
	ds_read_b32 v15, v15 offset:256
	ds_read_b32 v16, v16
	ds_read_b32 v21, v19 offset:3424
	s_waitcnt lgkmcnt(3)
	v_mul_f32_e32 v6, v2, v6
	v_mul_f32_e32 v7, v3, v7
	v_mul_f32_e32 v8, v24, v8
	s_waitcnt lgkmcnt(1)
	v_mul_f32_e32 v15, v15, v16
	v_cvt_pk_bf16_f32 v2, v0, v9
	v_cvt_pk_bf16_f32 v3, v4, v5
	v_cvt_pk_bf16_f32 v4, v6, v7
	v_cvt_pk_bf16_f32 v5, v8, v15
	v_lshl_add_u64 v[6:7], v[12:13], 1, v[10:11]
	v_lshl_add_u32 v0, v14, 2, s25
	global_store_dwordx4 v[6:7], v[2:5], off
	ds_read2_b32 v[12:13], v19 offset0:64 offset1:196
	ds_read_b128 v[2:5], v0
	v_add_u32_e32 v6, 0x400, v19
	ds_read2_b32 v[16:17], v6 offset0:72 offset1:204
	ds_read_b96 v[6:8], v0 offset:16
	v_ashrrev_i32_e32 v15, 31, v14
	s_waitcnt lgkmcnt(2)
	v_mul_f32_e32 v0, v12, v2
	v_add_u32_e32 v2, 0x800, v19
	v_or_b32_e32 v12, 7, v18
	v_mul_f32_e32 v9, v13, v3
	ds_read2_b32 v[2:3], v2 offset0:80 offset1:212
	v_mul_lo_u32 v13, v12, s92
	v_add3_u32 v13, s33, v13, v20
	v_lshl_add_u32 v12, v12, 2, s25
	ds_read_b32 v13, v13 offset:256
	ds_read_b32 v12, v12
	s_waitcnt lgkmcnt(4)
	v_mul_f32_e32 v4, v16, v4
	s_waitcnt lgkmcnt(2)
	v_mul_f32_e32 v6, v2, v6
	v_mul_f32_e32 v7, v3, v7
	v_mul_f32_e32 v5, v17, v5
	v_cvt_pk_bf16_f32 v2, v0, v9
	v_cvt_pk_bf16_f32 v3, v4, v5
	v_cvt_pk_bf16_f32 v4, v6, v7
	v_lshl_add_u64 v[6:7], v[14:15], 1, v[10:11]
	v_ashrrev_i32_e32 v0, 1, v34
	v_mul_f32_e32 v8, v21, v8
	s_waitcnt lgkmcnt(0)
	v_mul_f32_e32 v12, v13, v12
	v_cvt_pk_bf16_f32 v5, v8, v12
	global_store_dwordx4 v[6:7], v[2:5], off
	v_add_u32_e32 v0, s24, v0
	v_lshlrev_b32_e32 v10, 6, v0
	v_mov_b64_e32 v[2:3], s[16:17]
	v_mad_i64_i32 v[30:31], s[0:1], v0, s60, v[2:3]
	global_load_dwordx4 v[2:5], v[30:31], off offset:2304
	global_load_dwordx4 v[6:9], v[30:31], off offset:2336
	v_and_b32_e32 v46, 0x3ffc0, v10
	global_load_dwordx4 v[10:13], v46, s[10:11]
	global_load_dwordx4 v[14:17], v46, s[8:9]
	global_load_dwordx4 v[18:21], v46, s[10:11] offset:16
	global_load_dwordx4 v[22:25], v46, s[8:9] offset:16
	global_load_dwordx4 v[26:29], v[30:31], off offset:2320
	s_nop 0
	global_load_dwordx4 v[30:33], v[30:31], off offset:2352
	s_nop 0
	global_load_dwordx4 v[34:37], v46, s[8:9] offset:48
	global_load_dwordx4 v[38:41], v46, s[10:11] offset:48
	global_load_dwordx4 v[42:45], v46, s[8:9] offset:32
	s_nop 0
	global_load_dwordx4 v[46:49], v46, s[10:11] offset:32
	s_add_i32 s20, s20, s71
	s_add_i32 s23, s23, s85
	s_cmpk_gt_i32 s20, 0x3ff
	s_waitcnt vmcnt(9)
	v_mov_b32_e32 v52, v10
	s_waitcnt vmcnt(8)
	v_mov_b32_e32 v53, v14
	v_lshlrev_b32_e32 v50, 16, v2
	v_lshlrev_b32_e32 v51, 16, v6
	v_pk_mul_f32 v[52:53], v[52:53], v[50:51]
	s_nop 0
	v_add_f32_e32 v55, v53, v52
	v_mov_b32_e32 v52, v14
	v_mov_b32_e32 v53, v10
	v_pk_mul_f32 v[50:51], v[52:53], v[50:51]
	v_mov_b32_e32 v14, v11
	v_sub_f32_e32 v10, v50, v51
	v_cndmask_b32_e32 v55, v55, v10, vcc
	v_and_b32_e32 v51, 0xffff0000, v6
	v_and_b32_e32 v50, 0xffff0000, v2
	v_mov_b32_e32 v10, v15
	v_pk_mul_f32 v[10:11], v[10:11], v[50:51]
	v_pk_mul_f32 v[52:53], v[14:15], v[50:51]
	v_sub_f32_e32 v6, v10, v11
	v_lshlrev_b32_e32 v11, 16, v7
	v_lshlrev_b32_e32 v10, 16, v3
	v_mov_b32_e32 v14, v12
	v_mov_b32_e32 v15, v16
	v_add_f32_e32 v2, v53, v52
	v_pk_mul_f32 v[14:15], v[14:15], v[10:11]
	v_cndmask_b32_e32 v50, v2, v6, vcc
	v_add_f32_e32 v2, v15, v14
	v_mov_b32_e32 v14, v16
	v_mov_b32_e32 v15, v12
	v_pk_mul_f32 v[10:11], v[14:15], v[10:11]
	v_and_b32_e32 v7, 0xffff0000, v7
	v_sub_f32_e32 v6, v10, v11
	v_cndmask_b32_e32 v10, v2, v6, vcc
	v_and_b32_e32 v6, 0xffff0000, v3
	v_mov_b32_e32 v16, v13
	v_pk_mul_f32 v[2:3], v[16:17], v[6:7]
	v_mov_b32_e32 v12, v17
	v_add_f32_e32 v11, v3, v2
	v_pk_mul_f32 v[2:3], v[12:13], v[6:7]
	s_waitcnt vmcnt(7)
	v_mov_b32_e32 v6, v18
	v_sub_f32_e32 v2, v2, v3
	v_cndmask_b32_e32 v11, v11, v2, vcc
	v_lshlrev_b32_e32 v3, 16, v8
	v_lshlrev_b32_e32 v2, 16, v4
	s_waitcnt vmcnt(6)
; DI u32x4 pack8(const float* f) { u32x4 o; o.x = pack2(f[0], f[1]); o.y = pack2(f[2], f[3]); o.z = pack2(f[4], f[5]); o.w = pack2(f[6], f[7]); return o; }
; DI void kv_tile(PREF p, int l, int idx, unsigned char* ldsb) {
;     ...
;   {
;     int r = tid >> 1, half = tid & 1;
;     int t = row0 + r, s = t & 4095;
;     const u16* src = p.hb + (size_t)t * HW + OFF_KR;
;     float x1[16], x2[16];
;     unpack8(*(const u32x4*)(src), x1); unpack8(*(const u32x4*)(src + 8), x1 + 8);
;     unpack8(*(const u32x4*)(src + 16), x2); unpack8(*(const u32x4*)(src + 24), x2 + 8);
;     const float* cs = p.rcos + s * 16; const float* sn = p.rsin + s * 16;
;     float ov[16];
; #pragma unroll
;     for (int i = 0; i < 16; ++i) ov[i] = half ? (x2[i] * cs[i] + x1[i] * sn[i]) : (x1[i] * cs[i] - x2[i] * sn[i]);
;     u16* dst = p.Km + (size_t)t * 384 + head * 96 + 64 + half * 16;
;     *(u32x4*)dst = pack8(ov); *(u32x4*)(dst + 8) = pack8(ov + 8);
	v_mov_b32_e32 v7, v22
	v_pk_mul_f32 v[6:7], v[6:7], v[2:3]
	s_nop 0
	v_add_f32_e32 v12, v7, v6
	v_mov_b32_e32 v6, v22
	v_mov_b32_e32 v7, v18
	v_pk_mul_f32 v[2:3], v[6:7], v[2:3]
	v_mov_b32_e32 v22, v19
	v_sub_f32_e32 v2, v2, v3
	v_cndmask_b32_e32 v12, v12, v2, vcc
	v_and_b32_e32 v3, 0xffff0000, v8
	v_and_b32_e32 v2, 0xffff0000, v4
	v_mov_b32_e32 v18, v23
	v_pk_mul_f32 v[6:7], v[22:23], v[2:3]
	v_pk_mul_f32 v[2:3], v[18:19], v[2:3]
	v_add_f32_e32 v4, v7, v6
	v_sub_f32_e32 v2, v2, v3
	v_cndmask_b32_e32 v8, v4, v2, vcc
	v_lshlrev_b32_e32 v3, 16, v9
	v_lshlrev_b32_e32 v2, 16, v5
	v_mov_b32_e32 v6, v20
	v_mov_b32_e32 v7, v24
	v_pk_mul_f32 v[6:7], v[6:7], v[2:3]
	s_nop 0
	v_add_f32_e32 v4, v7, v6
	v_mov_b32_e32 v6, v24
	v_mov_b32_e32 v7, v20
	v_pk_mul_f32 v[2:3], v[6:7], v[2:3]
	v_mov_b32_e32 v24, v21
	v_sub_f32_e32 v2, v2, v3
	v_cndmask_b32_e32 v13, v4, v2, vcc
	v_and_b32_e32 v3, 0xffff0000, v9
	v_and_b32_e32 v2, 0xffff0000, v5
	v_mov_b32_e32 v20, v25
	v_pk_mul_f32 v[4:5], v[24:25], v[2:3]
	v_pk_mul_f32 v[2:3], v[20:21], v[2:3]
	v_add_f32_e32 v4, v5, v4
	v_sub_f32_e32 v2, v2, v3
	v_cndmask_b32_e32 v9, v4, v2, vcc
	s_waitcnt vmcnt(4)
	v_lshlrev_b32_e32 v3, 16, v30
	v_lshlrev_b32_e32 v2, 16, v26
	s_waitcnt vmcnt(0)
	v_mov_b32_e32 v4, v46
	v_mov_b32_e32 v5, v42
	v_pk_mul_f32 v[4:5], v[4:5], v[2:3]
	s_nop 0
	v_add_f32_e32 v6, v5, v4
	v_mov_b32_e32 v4, v42
	v_mov_b32_e32 v5, v46
	v_pk_mul_f32 v[2:3], v[4:5], v[2:3]
	v_mov_b32_e32 v42, v47
	v_sub_f32_e32 v2, v2, v3
	v_cndmask_b32_e32 v14, v6, v2, vcc
	v_and_b32_e32 v3, 0xffff0000, v30
	v_and_b32_e32 v2, 0xffff0000, v26
	v_mov_b32_e32 v46, v43
	v_pk_mul_f32 v[4:5], v[42:43], v[2:3]
	v_pk_mul_f32 v[2:3], v[46:47], v[2:3]
	v_add_f32_e32 v4, v5, v4
	v_sub_f32_e32 v2, v2, v3
	v_cndmask_b32_e32 v15, v4, v2, vcc
	v_lshlrev_b32_e32 v3, 16, v31
	v_lshlrev_b32_e32 v2, 16, v27
	v_mov_b32_e32 v4, v48
	v_mov_b32_e32 v5, v44
	v_pk_mul_f32 v[4:5], v[4:5], v[2:3]
	s_nop 0
	v_add_f32_e32 v6, v5, v4
	v_mov_b32_e32 v4, v44
	v_mov_b32_e32 v5, v48
	v_pk_mul_f32 v[2:3], v[4:5], v[2:3]
	v_mov_b32_e32 v44, v49
	v_sub_f32_e32 v2, v2, v3
	v_cndmask_b32_e32 v16, v6, v2, vcc
	v_and_b32_e32 v3, 0xffff0000, v31
	v_and_b32_e32 v2, 0xffff0000, v27
	v_mov_b32_e32 v48, v45
	v_pk_mul_f32 v[4:5], v[44:45], v[2:3]
	v_pk_mul_f32 v[2:3], v[48:49], v[2:3]
	v_add_f32_e32 v4, v5, v4
	v_sub_f32_e32 v2, v2, v3
	v_cndmask_b32_e32 v17, v4, v2, vcc
	v_lshlrev_b32_e32 v3, 16, v32
	v_lshlrev_b32_e32 v2, 16, v28
	v_mov_b32_e32 v4, v38
	v_mov_b32_e32 v5, v34
	v_pk_mul_f32 v[4:5], v[4:5], v[2:3]
	s_nop 0
	v_add_f32_e32 v6, v5, v4
	v_mov_b32_e32 v4, v34
	v_mov_b32_e32 v5, v38
	v_pk_mul_f32 v[2:3], v[4:5], v[2:3]
	v_mov_b32_e32 v34, v39
	v_sub_f32_e32 v2, v2, v3
	v_cndmask_b32_e32 v18, v6, v2, vcc
	v_and_b32_e32 v3, 0xffff0000, v32
	v_and_b32_e32 v2, 0xffff0000, v28
	v_mov_b32_e32 v38, v35
	v_pk_mul_f32 v[4:5], v[34:35], v[2:3]
	v_pk_mul_f32 v[2:3], v[38:39], v[2:3]
	v_add_f32_e32 v4, v5, v4
	v_sub_f32_e32 v2, v2, v3
	v_cndmask_b32_e32 v19, v4, v2, vcc
	v_lshlrev_b32_e32 v3, 16, v33
	v_lshlrev_b32_e32 v2, 16, v29
	v_mov_b32_e32 v4, v40
	v_mov_b32_e32 v5, v36
	v_pk_mul_f32 v[4:5], v[4:5], v[2:3]
	s_nop 0
	v_add_f32_e32 v6, v5, v4
	v_mov_b32_e32 v4, v36
	v_mov_b32_e32 v5, v40
	v_pk_mul_f32 v[2:3], v[4:5], v[2:3]
	v_mov_b32_e32 v36, v41
	v_sub_f32_e32 v2, v2, v3
	v_cndmask_b32_e32 v20, v6, v2, vcc
	v_and_b32_e32 v3, 0xffff0000, v33
	v_and_b32_e32 v2, 0xffff0000, v29
	v_mov_b32_e32 v40, v37
	v_pk_mul_f32 v[4:5], v[36:37], v[2:3]
	v_pk_mul_f32 v[2:3], v[40:41], v[2:3]
	v_add_f32_e32 v4, v5, v4
	v_sub_f32_e32 v2, v2, v3
	v_cndmask_b32_e32 v21, v4, v2, vcc
	v_mov_b64_e32 v[2:3], s[12:13]
	v_mad_i64_i32 v[2:3], s[0:1], v0, s96, v[2:3]
	v_lshl_add_u64 v[2:3], v[2:3], 0, s[52:53]
	v_lshlrev_b32_e32 v0, 5, v54
	v_lshl_add_u64 v[6:7], v[2:3], 0, v[0:1]
	v_cvt_pk_bf16_f32 v2, v55, v50
	v_cvt_pk_bf16_f32 v3, v10, v11
	v_cvt_pk_bf16_f32 v4, v12, v8
	v_cvt_pk_bf16_f32 v5, v13, v9
	global_store_dwordx4 v[6:7], v[2:5], off offset:128
	s_nop 1
	v_cvt_pk_bf16_f32 v2, v14, v15
	v_cvt_pk_bf16_f32 v3, v16, v17
	v_cvt_pk_bf16_f32 v4, v18, v19
	v_cvt_pk_bf16_f32 v5, v20, v21
	global_store_dwordx4 v[6:7], v[2:5], off offset:144
	s_cbranch_scc1 .LBB0_340

; DI u32x4 pack8(const float* f) { u32x4 o; o.x = pack2(f[0], f[1]); o.y = pack2(f[2], f[3]); o.z = pack2(f[4], f[5]); o.w = pack2(f[6], f[7]); return o; }
; DI void q_tile(PREF p, int l, int idx, unsigned char* ldsb) {
;     ...
;   for (int q = 0; q < 8; ++q) {
;     int r = (tid >> 4) + 16 * q, c = (tid & 15) * 8;
;     int n = col0 + c; int dd = n % 96;
;     float rs = aux[r];
;     float v[8]; ld8(Cs + r * CST + c, v);
; #pragma unroll
;     for (int j = 0; j < 8; ++j) v[j] *= rs;
;     if (dd >= 64) {
;       int ri0 = dd - 64; int s = (row0 + r) & 4095;
;       float pv[8];
;       if (ri0 < 16) {
;         ld8(Cs + r * CST + c + 16, pv);
;         const float* cs = p.rcos + s * 16 + ri0; const float* sn = p.rsin + s * 16 + ri0;
; #pragma unroll
;         for (int j = 0; j < 8; ++j) v[j] = v[j] * cs[j] - pv[j] * rs * sn[j];
;       } else {
;         ld8(Cs + r * CST + c - 16, pv);
;         const float* cs = p.rcos + s * 16 + ri0 - 16; const float* sn = p.rsin + s * 16 + ri0 - 16;
; #pragma unroll
;         for (int j = 0; j < 8; ++j) v[j] = v[j] * cs[j] + pv[j] * rs * sn[j];
;       }
;     }
;     *(u32x4*)(p.Qm + (size_t)(row0 + r) * 384 + n) = pack8(v);
;   }
.LBB0_343:
	s_or_b64 exec, exec, s[16:17]
	s_add_i32 s20, s20, s71
	v_mad_i64_i32 v[6:7], s[0:1], v18, s96, v[6:7]
	s_cmpk_gt_i32 s20, 0x2ff
	v_cvt_pk_bf16_f32 v2, v14, v15
	v_cvt_pk_bf16_f32 v3, v12, v13
	v_cvt_pk_bf16_f32 v4, v10, v11
	v_cvt_pk_bf16_f32 v5, v8, v9
	global_store_dwordx4 v[6:7], v[2:5], off
	s_cbranch_scc1 .LBB0_395

; DI u32x4 pack8(const float* f) { u32x4 o; o.x = pack2(f[0], f[1]); o.y = pack2(f[2], f[3]); o.z = pack2(f[4], f[5]); o.w = pack2(f[6], f[7]); return o; }
; DI void q_tile(PREF p, int l, int idx, unsigned char* ldsb) {
;     ...
;   for (int q = 0; q < 8; ++q) {
;     int r = (tid >> 4) + 16 * q, c = (tid & 15) * 8;
;     int n = col0 + c; int dd = n % 96;
;     float rs = aux[r];
;     float v[8]; ld8(Cs + r * CST + c, v);
; #pragma unroll
;     for (int j = 0; j < 8; ++j) v[j] *= rs;
;     if (dd >= 64) {
;       int ri0 = dd - 64; int s = (row0 + r) & 4095;
;       float pv[8];
;       if (ri0 < 16) {
;         ld8(Cs + r * CST + c + 16, pv);
;         const float* cs = p.rcos + s * 16 + ri0; const float* sn = p.rsin + s * 16 + ri0;
; #pragma unroll
;         for (int j = 0; j < 8; ++j) v[j] = v[j] * cs[j] - pv[j] * rs * sn[j];
;       } else {
;         ld8(Cs + r * CST + c - 16, pv);
;         const float* cs = p.rcos + s * 16 + ri0 - 16; const float* sn = p.rsin + s * 16 + ri0 - 16;
; #pragma unroll
;         for (int j = 0; j < 8; ++j) v[j] = v[j] * cs[j] + pv[j] * rs * sn[j];
;       }
;     }
;     *(u32x4*)(p.Qm + (size_t)(row0 + r) * 384 + n) = pack8(v);
.LBB0_354:
	s_or_b64 exec, exec, s[16:17]
	v_readlane_b32 s0, v254, 46
	v_readlane_b32 s1, v254, 47
	s_load_dwordx2 s[0:1], s[0:1], 0x158
	v_ashrrev_i32_e32 v7, 31, v6
	v_cvt_pk_bf16_f32 v17, v8, v9
	v_add_u32_e32 v23, 0x2100, v23
	v_cvt_pk_bf16_f32 v14, v14, v15
	s_waitcnt lgkmcnt(0)
	v_lshl_add_u64 v[6:7], v[6:7], 1, s[0:1]
	v_mad_i64_i32 v[8:9], s[0:1], v20, s96, v[6:7]
	v_cvt_pk_bf16_f32 v15, v12, v13
	v_cvt_pk_bf16_f32 v16, v10, v11
	global_store_dwordx4 v[8:9], v[14:17], off
	v_add_u32_e32 v25, v22, v23
	ds_read_b32 v16, v21 offset:64
	ds_read_b128 v[8:11], v25
	ds_read_b128 v[26:29], v25 offset:16
	v_add_u32_e32 v24, 16, v20
	s_waitcnt lgkmcnt(1)
	v_pk_mul_f32 v[14:15], v[16:17], v[8:9] op_sel_hi:[0,1]
	v_pk_mul_f32 v[12:13], v[16:17], v[10:11] op_sel_hi:[0,1]
	s_waitcnt lgkmcnt(0)
	v_pk_mul_f32 v[10:11], v[16:17], v[26:27] op_sel_hi:[0,1]
	v_pk_mul_f32 v[8:9], v[16:17], v[28:29] op_sel_hi:[0,1]
	s_and_saveexec_b64 s[16:17], s[8:9]
	s_cbranch_execz .LBB0_360
	v_lshlrev_b32_e32 v0, 4, v24
	v_and_b32_e32 v0, 0xfff0, v0
	v_lshlrev_b32_e32 v0, 2, v0
	v_mov_b32_e32 v17, v16
	v_lshl_add_u64 v[18:19], v[4:5], 0, v[0:1]
	s_and_saveexec_b64 s[0:1], vcc
	s_xor_b64 s[18:19], exec, s[0:1]
	s_cbranch_execz .LBB0_357
	v_subrev_u32_e32 v26, 64, v25
	v_lshl_add_u64 v[42:43], v[2:3], 0, v[0:1]
	ds_read_b128 v[26:29], v26
	global_load_dwordx4 v[30:33], v[18:19], off offset:-48
	global_load_dwordx4 v[34:37], v[18:19], off offset:-64
	global_load_dwordx4 v[38:41], v[42:43], off offset:-48
	s_nop 0
	global_load_dwordx4 v[42:45], v[42:43], off offset:-64
	v_subrev_u32_e32 v25, 48, v25
	s_waitcnt lgkmcnt(0)
	v_pk_mul_f32 v[18:19], v[16:17], v[26:27]
	s_waitcnt vmcnt(0)
	v_pk_mul_f32 v[18:19], v[18:19], v[42:43]
	s_nop 0
	v_pk_fma_f32 v[14:15], v[14:15], v[34:35], v[18:19]
	v_pk_mul_f32 v[18:19], v[16:17], v[28:29]
	ds_read_b128 v[26:29], v25
	v_pk_mul_f32 v[18:19], v[18:19], v[44:45]
	s_nop 0
	v_pk_fma_f32 v[12:13], v[12:13], v[36:37], v[18:19]
	s_waitcnt lgkmcnt(0)
	v_pk_mul_f32 v[18:19], v[16:17], v[26:27]
	v_pk_mul_f32 v[16:17], v[16:17], v[28:29]
	v_pk_mul_f32 v[18:19], v[18:19], v[38:39]
	v_pk_mul_f32 v[16:17], v[16:17], v[40:41]
	v_pk_fma_f32 v[10:11], v[10:11], v[30:31], v[18:19]
	v_pk_fma_f32 v[8:9], v[8:9], v[32:33], v[16:17]

; DI u32x4 pack8(const float* f) { u32x4 o; o.x = pack2(f[0], f[1]); o.y = pack2(f[2], f[3]); o.z = pack2(f[4], f[5]); o.w = pack2(f[6], f[7]); return o; }
; DI void q_tile(PREF p, int l, int idx, unsigned char* ldsb) {
;     ...
;   for (int q = 0; q < 8; ++q) {
;     int r = (tid >> 4) + 16 * q, c = (tid & 15) * 8;
;     int n = col0 + c; int dd = n % 96;
;     float rs = aux[r];
;     float v[8]; ld8(Cs + r * CST + c, v);
; #pragma unroll
;     for (int j = 0; j < 8; ++j) v[j] *= rs;
;     if (dd >= 64) {
;       int ri0 = dd - 64; int s = (row0 + r) & 4095;
;       float pv[8];
;       if (ri0 < 16) {
;         ld8(Cs + r * CST + c + 16, pv);
;         const float* cs = p.rcos + s * 16 + ri0; const float* sn = p.rsin + s * 16 + ri0;
; #pragma unroll
;         for (int j = 0; j < 8; ++j) v[j] = v[j] * cs[j] - pv[j] * rs * sn[j];
;       } else {
;         ld8(Cs + r * CST + c - 16, pv);
;         const float* cs = p.rcos + s * 16 + ri0 - 16; const float* sn = p.rsin + s * 16 + ri0 - 16;
; #pragma unroll
;         for (int j = 0; j < 8; ++j) v[j] = v[j] * cs[j] + pv[j] * rs * sn[j];
;       }
;     }
;     *(u32x4*)(p.Qm + (size_t)(row0 + r) * 384 + n) = pack8(v);
.LBB0_360:
	s_or_b64 exec, exec, s[16:17]
	v_cvt_pk_bf16_f32 v17, v8, v9
	v_mad_i64_i32 v[8:9], s[0:1], v24, s96, v[6:7]
	v_add_u32_e32 v23, 0x2100, v23
	v_cvt_pk_bf16_f32 v14, v14, v15
	v_cvt_pk_bf16_f32 v15, v12, v13
	v_cvt_pk_bf16_f32 v16, v10, v11
	global_store_dwordx4 v[8:9], v[14:17], off
	v_add_u32_e32 v25, v22, v23
	ds_read_b32 v16, v21 offset:128
	ds_read_b128 v[8:11], v25
	ds_read_b128 v[26:29], v25 offset:16
	v_add_u32_e32 v24, 32, v20
	s_waitcnt lgkmcnt(1)
	v_pk_mul_f32 v[14:15], v[16:17], v[8:9] op_sel_hi:[0,1]
	v_pk_mul_f32 v[12:13], v[16:17], v[10:11] op_sel_hi:[0,1]
	s_waitcnt lgkmcnt(0)
	v_pk_mul_f32 v[10:11], v[16:17], v[26:27] op_sel_hi:[0,1]
	v_pk_mul_f32 v[8:9], v[16:17], v[28:29] op_sel_hi:[0,1]
	s_and_saveexec_b64 s[16:17], s[8:9]
	s_cbranch_execz .LBB0_366
	v_lshlrev_b32_e32 v0, 4, v24
	v_and_b32_e32 v0, 0xfff0, v0
	v_lshlrev_b32_e32 v0, 2, v0
	v_mov_b32_e32 v17, v16
	v_lshl_add_u64 v[18:19], v[4:5], 0, v[0:1]
	s_and_saveexec_b64 s[0:1], vcc
	s_xor_b64 s[18:19], exec, s[0:1]
	s_cbranch_execz .LBB0_363
	v_subrev_u32_e32 v26, 64, v25
	v_lshl_add_u64 v[42:43], v[2:3], 0, v[0:1]
	ds_read_b128 v[26:29], v26
	global_load_dwordx4 v[30:33], v[18:19], off offset:-48
	global_load_dwordx4 v[34:37], v[18:19], off offset:-64
	global_load_dwordx4 v[38:41], v[42:43], off offset:-48
	s_nop 0
	global_load_dwordx4 v[42:45], v[42:43], off offset:-64
	v_subrev_u32_e32 v25, 48, v25
	s_waitcnt lgkmcnt(0)
	v_pk_mul_f32 v[18:19], v[16:17], v[26:27]
	s_waitcnt vmcnt(0)
	v_pk_mul_f32 v[18:19], v[18:19], v[42:43]
	s_nop 0
	v_pk_fma_f32 v[14:15], v[14:15], v[34:35], v[18:19]
	v_pk_mul_f32 v[18:19], v[16:17], v[28:29]
	ds_read_b128 v[26:29], v25
	v_pk_mul_f32 v[18:19], v[18:19], v[44:45]
	s_nop 0
	v_pk_fma_f32 v[12:13], v[12:13], v[36:37], v[18:19]
	s_waitcnt lgkmcnt(0)
	v_pk_mul_f32 v[18:19], v[16:17], v[26:27]
	v_pk_mul_f32 v[16:17], v[16:17], v[28:29]
	v_pk_mul_f32 v[18:19], v[18:19], v[38:39]
	v_pk_mul_f32 v[16:17], v[16:17], v[40:41]
	v_pk_fma_f32 v[10:11], v[10:11], v[30:31], v[18:19]
	v_pk_fma_f32 v[8:9], v[8:9], v[32:33], v[16:17]

; DI u32x4 pack8(const float* f) { u32x4 o; o.x = pack2(f[0], f[1]); o.y = pack2(f[2], f[3]); o.z = pack2(f[4], f[5]); o.w = pack2(f[6], f[7]); return o; }
; DI void q_tile(PREF p, int l, int idx, unsigned char* ldsb) {
;     ...
;   for (int q = 0; q < 8; ++q) {
;     int r = (tid >> 4) + 16 * q, c = (tid & 15) * 8;
;     int n = col0 + c; int dd = n % 96;
;     float rs = aux[r];
;     float v[8]; ld8(Cs + r * CST + c, v);
; #pragma unroll
;     for (int j = 0; j < 8; ++j) v[j] *= rs;
;     if (dd >= 64) {
;       int ri0 = dd - 64; int s = (row0 + r) & 4095;
;       float pv[8];
;       if (ri0 < 16) {
;         ld8(Cs + r * CST + c + 16, pv);
;         const float* cs = p.rcos + s * 16 + ri0; const float* sn = p.rsin + s * 16 + ri0;
; #pragma unroll
;         for (int j = 0; j < 8; ++j) v[j] = v[j] * cs[j] - pv[j] * rs * sn[j];
;       } else {
;         ld8(Cs + r * CST + c - 16, pv);
;         const float* cs = p.rcos + s * 16 + ri0 - 16; const float* sn = p.rsin + s * 16 + ri0 - 16;
; #pragma unroll
;         for (int j = 0; j < 8; ++j) v[j] = v[j] * cs[j] + pv[j] * rs * sn[j];
;       }
;     }
;     *(u32x4*)(p.Qm + (size_t)(row0 + r) * 384 + n) = pack8(v);
.LBB0_366:
	s_or_b64 exec, exec, s[16:17]
	v_cvt_pk_bf16_f32 v17, v8, v9
	v_mad_i64_i32 v[8:9], s[0:1], v24, s96, v[6:7]
	v_add_u32_e32 v0, 0x2100, v23
	v_cvt_pk_bf16_f32 v14, v14, v15
	v_cvt_pk_bf16_f32 v15, v12, v13
	v_cvt_pk_bf16_f32 v16, v10, v11
	global_store_dwordx4 v[8:9], v[14:17], off
	v_add_u32_e32 v22, v22, v0
	ds_read_b32 v16, v21 offset:192
	ds_read_b128 v[8:11], v22
	ds_read_b128 v[24:27], v22 offset:16
	v_add_u32_e32 v23, 48, v20
	s_waitcnt lgkmcnt(1)
	v_pk_mul_f32 v[14:15], v[16:17], v[8:9] op_sel_hi:[0,1]
	v_pk_mul_f32 v[12:13], v[16:17], v[10:11] op_sel_hi:[0,1]
	s_waitcnt lgkmcnt(0)
	v_pk_mul_f32 v[10:11], v[16:17], v[24:25] op_sel_hi:[0,1]
	v_pk_mul_f32 v[8:9], v[16:17], v[26:27] op_sel_hi:[0,1]
	s_and_saveexec_b64 s[16:17], s[8:9]
	s_cbranch_execz .LBB0_372
	v_lshlrev_b32_e32 v0, 4, v23
	v_and_b32_e32 v0, 0xfff0, v0
	v_lshlrev_b32_e32 v0, 2, v0
	v_mov_b32_e32 v17, v16
	v_lshl_add_u64 v[18:19], v[4:5], 0, v[0:1]
	s_and_saveexec_b64 s[0:1], vcc
	s_xor_b64 s[18:19], exec, s[0:1]
	s_cbranch_execz .LBB0_369
	v_subrev_u32_e32 v24, 64, v22
	v_lshl_add_u64 v[40:41], v[2:3], 0, v[0:1]
	ds_read_b128 v[24:27], v24
	global_load_dwordx4 v[28:31], v[18:19], off offset:-48
	global_load_dwordx4 v[32:35], v[18:19], off offset:-64
	global_load_dwordx4 v[36:39], v[40:41], off offset:-48
	s_nop 0
	global_load_dwordx4 v[40:43], v[40:41], off offset:-64
	v_subrev_u32_e32 v44, 48, v22
	s_waitcnt lgkmcnt(0)
	v_pk_mul_f32 v[18:19], v[16:17], v[24:25]
	s_waitcnt vmcnt(0)
	v_pk_mul_f32 v[18:19], v[18:19], v[40:41]
	s_nop 0
	v_pk_fma_f32 v[14:15], v[14:15], v[32:33], v[18:19]
	v_pk_mul_f32 v[18:19], v[16:17], v[26:27]
	ds_read_b128 v[24:27], v44
	v_pk_mul_f32 v[18:19], v[18:19], v[42:43]
	s_nop 0
	v_pk_fma_f32 v[12:13], v[12:13], v[34:35], v[18:19]
	s_waitcnt lgkmcnt(0)
	v_pk_mul_f32 v[18:19], v[16:17], v[24:25]
	v_pk_mul_f32 v[16:17], v[16:17], v[26:27]
	v_pk_mul_f32 v[18:19], v[18:19], v[36:37]
	v_pk_mul_f32 v[16:17], v[16:17], v[38:39]
	v_pk_fma_f32 v[10:11], v[10:11], v[28:29], v[18:19]
	v_pk_fma_f32 v[8:9], v[8:9], v[30:31], v[16:17]

; DI u32x4 pack8(const float* f) { u32x4 o; o.x = pack2(f[0], f[1]); o.y = pack2(f[2], f[3]); o.z = pack2(f[4], f[5]); o.w = pack2(f[6], f[7]); return o; }
; DI void q_tile(PREF p, int l, int idx, unsigned char* ldsb) {
;     ...
;   for (int q = 0; q < 8; ++q) {
;     int r = (tid >> 4) + 16 * q, c = (tid & 15) * 8;
;     int n = col0 + c; int dd = n % 96;
;     float rs = aux[r];
;     float v[8]; ld8(Cs + r * CST + c, v);
; #pragma unroll
;     for (int j = 0; j < 8; ++j) v[j] *= rs;
;     if (dd >= 64) {
;       int ri0 = dd - 64; int s = (row0 + r) & 4095;
;       float pv[8];
;       if (ri0 < 16) {
;         ld8(Cs + r * CST + c + 16, pv);
;         const float* cs = p.rcos + s * 16 + ri0; const float* sn = p.rsin + s * 16 + ri0;
; #pragma unroll
;         for (int j = 0; j < 8; ++j) v[j] = v[j] * cs[j] - pv[j] * rs * sn[j];
;       } else {
;         ld8(Cs + r * CST + c - 16, pv);
;         const float* cs = p.rcos + s * 16 + ri0 - 16; const float* sn = p.rsin + s * 16 + ri0 - 16;
; #pragma unroll
;         for (int j = 0; j < 8; ++j) v[j] = v[j] * cs[j] + pv[j] * rs * sn[j];
;       }
;     }
;     *(u32x4*)(p.Qm + (size_t)(row0 + r) * 384 + n) = pack8(v);
.LBB0_372:
	s_or_b64 exec, exec, s[16:17]
	v_cvt_pk_bf16_f32 v17, v8, v9
	v_mad_i64_i32 v[8:9], s[0:1], v23, s96, v[6:7]
	v_cvt_pk_bf16_f32 v14, v14, v15
	v_cvt_pk_bf16_f32 v15, v12, v13
	v_cvt_pk_bf16_f32 v16, v10, v11
	global_store_dwordx4 v[8:9], v[14:17], off
	ds_read_b32 v16, v21 offset:256
	ds_read_b128 v[8:11], v22 offset:8448
	ds_read_b128 v[24:27], v22 offset:8464
	v_add_u32_e32 v23, 64, v20
	s_waitcnt lgkmcnt(1)
	v_pk_mul_f32 v[14:15], v[16:17], v[8:9] op_sel_hi:[0,1]
	v_pk_mul_f32 v[12:13], v[16:17], v[10:11] op_sel_hi:[0,1]
	s_waitcnt lgkmcnt(0)
	v_pk_mul_f32 v[10:11], v[16:17], v[24:25] op_sel_hi:[0,1]
	v_pk_mul_f32 v[8:9], v[16:17], v[26:27] op_sel_hi:[0,1]
	s_and_saveexec_b64 s[16:17], s[8:9]
	s_cbranch_execz .LBB0_378
	v_lshlrev_b32_e32 v0, 4, v23
	v_and_b32_e32 v0, 0xfff0, v0
	v_lshlrev_b32_e32 v0, 2, v0
	v_mov_b32_e32 v17, v16
	v_lshl_add_u64 v[18:19], v[4:5], 0, v[0:1]
	s_and_saveexec_b64 s[0:1], vcc
	s_xor_b64 s[18:19], exec, s[0:1]
	s_cbranch_execz .LBB0_375
	v_lshl_add_u64 v[28:29], v[2:3], 0, v[0:1]
	global_load_dwordx4 v[24:27], v[28:29], off offset:-64
	s_nop 0
	global_load_dwordx4 v[28:31], v[28:29], off offset:-48
	s_nop 0
	global_load_dwordx4 v[32:35], v[18:19], off offset:-64
	global_load_dwordx4 v[36:39], v[18:19], off offset:-48
	ds_read_b128 v[40:43], v22 offset:8384
	ds_read_b128 v[44:47], v22 offset:8400
	s_waitcnt lgkmcnt(1)
	v_pk_mul_f32 v[18:19], v[16:17], v[40:41]
	v_pk_mul_f32 v[40:41], v[16:17], v[42:43]
	s_waitcnt lgkmcnt(0)
	v_pk_mul_f32 v[42:43], v[16:17], v[44:45]
	v_pk_mul_f32 v[16:17], v[16:17], v[46:47]
	s_waitcnt vmcnt(3)
	v_pk_mul_f32 v[18:19], v[18:19], v[24:25]
	v_pk_mul_f32 v[24:25], v[40:41], v[26:27]
	s_waitcnt vmcnt(2)
	v_pk_mul_f32 v[26:27], v[42:43], v[28:29]
	v_pk_mul_f32 v[16:17], v[16:17], v[30:31]
	s_waitcnt vmcnt(1)
	v_pk_fma_f32 v[14:15], v[14:15], v[32:33], v[18:19]
	v_pk_fma_f32 v[12:13], v[12:13], v[34:35], v[24:25]
	s_waitcnt vmcnt(0)
	v_pk_fma_f32 v[10:11], v[10:11], v[36:37], v[26:27]
	v_pk_fma_f32 v[8:9], v[8:9], v[38:39], v[16:17]

; DI u32x4 pack8(const float* f) { u32x4 o; o.x = pack2(f[0], f[1]); o.y = pack2(f[2], f[3]); o.z = pack2(f[4], f[5]); o.w = pack2(f[6], f[7]); return o; }
; DI void q_tile(PREF p, int l, int idx, unsigned char* ldsb) {
;     ...
;   for (int q = 0; q < 8; ++q) {
;     int r = (tid >> 4) + 16 * q, c = (tid & 15) * 8;
;     int n = col0 + c; int dd = n % 96;
;     float rs = aux[r];
;     float v[8]; ld8(Cs + r * CST + c, v);
; #pragma unroll
;     for (int j = 0; j < 8; ++j) v[j] *= rs;
;     if (dd >= 64) {
;       int ri0 = dd - 64; int s = (row0 + r) & 4095;
;       float pv[8];
;       if (ri0 < 16) {
;         ld8(Cs + r * CST + c + 16, pv);
;         const float* cs = p.rcos + s * 16 + ri0; const float* sn = p.rsin + s * 16 + ri0;
; #pragma unroll
;         for (int j = 0; j < 8; ++j) v[j] = v[j] * cs[j] - pv[j] * rs * sn[j];
;       } else {
;         ld8(Cs + r * CST + c - 16, pv);
;         const float* cs = p.rcos + s * 16 + ri0 - 16; const float* sn = p.rsin + s * 16 + ri0 - 16;
; #pragma unroll
;         for (int j = 0; j < 8; ++j) v[j] = v[j] * cs[j] + pv[j] * rs * sn[j];
;       }
;     }
;     *(u32x4*)(p.Qm + (size_t)(row0 + r) * 384 + n) = pack8(v);
.LBB0_378:
	s_or_b64 exec, exec, s[16:17]
	v_cvt_pk_bf16_f32 v17, v8, v9
	v_mad_i64_i32 v[8:9], s[0:1], v23, s96, v[6:7]
	v_cvt_pk_bf16_f32 v14, v14, v15
	v_cvt_pk_bf16_f32 v15, v12, v13
	v_cvt_pk_bf16_f32 v16, v10, v11
	global_store_dwordx4 v[8:9], v[14:17], off
	ds_read_b32 v16, v21 offset:320
	ds_read_b128 v[8:11], v22 offset:16896
	ds_read_b128 v[24:27], v22 offset:16912
	v_add_u32_e32 v23, 0x50, v20
	s_waitcnt lgkmcnt(1)
	v_pk_mul_f32 v[14:15], v[16:17], v[8:9] op_sel_hi:[0,1]
	v_pk_mul_f32 v[12:13], v[16:17], v[10:11] op_sel_hi:[0,1]
	s_waitcnt lgkmcnt(0)
	v_pk_mul_f32 v[10:11], v[16:17], v[24:25] op_sel_hi:[0,1]
	v_pk_mul_f32 v[8:9], v[16:17], v[26:27] op_sel_hi:[0,1]
	s_and_saveexec_b64 s[16:17], s[8:9]
	s_cbranch_execz .LBB0_384
	v_lshlrev_b32_e32 v0, 4, v23
	v_and_b32_e32 v0, 0xfff0, v0
	v_lshlrev_b32_e32 v0, 2, v0
	v_mov_b32_e32 v17, v16
	v_lshl_add_u64 v[18:19], v[4:5], 0, v[0:1]
	s_and_saveexec_b64 s[0:1], vcc
	s_xor_b64 s[18:19], exec, s[0:1]
	s_cbranch_execz .LBB0_381
	v_lshl_add_u64 v[28:29], v[2:3], 0, v[0:1]
	global_load_dwordx4 v[24:27], v[28:29], off offset:-64
	s_nop 0
	global_load_dwordx4 v[28:31], v[28:29], off offset:-48
	s_nop 0
	global_load_dwordx4 v[32:35], v[18:19], off offset:-64
	global_load_dwordx4 v[36:39], v[18:19], off offset:-48
	ds_read_b128 v[40:43], v22 offset:16832
	ds_read_b128 v[44:47], v22 offset:16848
	s_waitcnt lgkmcnt(1)
	v_pk_mul_f32 v[18:19], v[16:17], v[40:41]
	v_pk_mul_f32 v[40:41], v[16:17], v[42:43]
	s_waitcnt lgkmcnt(0)
	v_pk_mul_f32 v[42:43], v[16:17], v[44:45]
	v_pk_mul_f32 v[16:17], v[16:17], v[46:47]
	s_waitcnt vmcnt(3)
	v_pk_mul_f32 v[18:19], v[18:19], v[24:25]
	v_pk_mul_f32 v[24:25], v[40:41], v[26:27]
	s_waitcnt vmcnt(2)
	v_pk_mul_f32 v[26:27], v[42:43], v[28:29]
	v_pk_mul_f32 v[16:17], v[16:17], v[30:31]
	s_waitcnt vmcnt(1)
	v_pk_fma_f32 v[14:15], v[14:15], v[32:33], v[18:19]
	v_pk_fma_f32 v[12:13], v[12:13], v[34:35], v[24:25]
	s_waitcnt vmcnt(0)
	v_pk_fma_f32 v[10:11], v[10:11], v[36:37], v[26:27]
	v_pk_fma_f32 v[8:9], v[8:9], v[38:39], v[16:17]

; DI u32x4 pack8(const float* f) { u32x4 o; o.x = pack2(f[0], f[1]); o.y = pack2(f[2], f[3]); o.z = pack2(f[4], f[5]); o.w = pack2(f[6], f[7]); return o; }
; DI void q_tile(PREF p, int l, int idx, unsigned char* ldsb) {
;     ...
;   for (int q = 0; q < 8; ++q) {
;     int r = (tid >> 4) + 16 * q, c = (tid & 15) * 8;
;     int n = col0 + c; int dd = n % 96;
;     float rs = aux[r];
;     float v[8]; ld8(Cs + r * CST + c, v);
; #pragma unroll
;     for (int j = 0; j < 8; ++j) v[j] *= rs;
;     if (dd >= 64) {
;       int ri0 = dd - 64; int s = (row0 + r) & 4095;
;       float pv[8];
;       if (ri0 < 16) {
;         ld8(Cs + r * CST + c + 16, pv);
;         const float* cs = p.rcos + s * 16 + ri0; const float* sn = p.rsin + s * 16 + ri0;
; #pragma unroll
;         for (int j = 0; j < 8; ++j) v[j] = v[j] * cs[j] - pv[j] * rs * sn[j];
;       } else {
;         ld8(Cs + r * CST + c - 16, pv);
;         const float* cs = p.rcos + s * 16 + ri0 - 16; const float* sn = p.rsin + s * 16 + ri0 - 16;
; #pragma unroll
;         for (int j = 0; j < 8; ++j) v[j] = v[j] * cs[j] + pv[j] * rs * sn[j];
;       }
;     }
;     *(u32x4*)(p.Qm + (size_t)(row0 + r) * 384 + n) = pack8(v);
.LBB0_384:
	s_or_b64 exec, exec, s[16:17]
	v_cvt_pk_bf16_f32 v17, v8, v9
	v_mad_i64_i32 v[8:9], s[0:1], v23, s96, v[6:7]
	v_cvt_pk_bf16_f32 v14, v14, v15
	v_cvt_pk_bf16_f32 v15, v12, v13
	v_cvt_pk_bf16_f32 v16, v10, v11
	global_store_dwordx4 v[8:9], v[14:17], off
	ds_read_b32 v16, v21 offset:384
	ds_read_b128 v[8:11], v22 offset:25344
	ds_read_b128 v[24:27], v22 offset:25360
	v_add_u32_e32 v23, 0x60, v20
	s_waitcnt lgkmcnt(1)
	v_pk_mul_f32 v[14:15], v[16:17], v[8:9] op_sel_hi:[0,1]
	v_pk_mul_f32 v[12:13], v[16:17], v[10:11] op_sel_hi:[0,1]
	s_waitcnt lgkmcnt(0)
	v_pk_mul_f32 v[10:11], v[16:17], v[24:25] op_sel_hi:[0,1]
	v_pk_mul_f32 v[8:9], v[16:17], v[26:27] op_sel_hi:[0,1]
	s_and_saveexec_b64 s[16:17], s[8:9]
	s_cbranch_execz .LBB0_390
	v_lshlrev_b32_e32 v0, 4, v23
	v_and_b32_e32 v0, 0xfff0, v0
	v_lshlrev_b32_e32 v0, 2, v0
	v_mov_b32_e32 v17, v16
	v_lshl_add_u64 v[18:19], v[4:5], 0, v[0:1]
	s_and_saveexec_b64 s[0:1], vcc
	s_xor_b64 s[18:19], exec, s[0:1]
	s_cbranch_execz .LBB0_387
	v_lshl_add_u64 v[28:29], v[2:3], 0, v[0:1]
	global_load_dwordx4 v[24:27], v[28:29], off offset:-64
	s_nop 0
	global_load_dwordx4 v[28:31], v[28:29], off offset:-48
	s_nop 0
	global_load_dwordx4 v[32:35], v[18:19], off offset:-64
	global_load_dwordx4 v[36:39], v[18:19], off offset:-48
	ds_read_b128 v[40:43], v22 offset:25280
	ds_read_b128 v[44:47], v22 offset:25296
	s_waitcnt lgkmcnt(1)
	v_pk_mul_f32 v[18:19], v[16:17], v[40:41]
	v_pk_mul_f32 v[40:41], v[16:17], v[42:43]
	s_waitcnt lgkmcnt(0)
	v_pk_mul_f32 v[42:43], v[16:17], v[44:45]
	v_pk_mul_f32 v[16:17], v[16:17], v[46:47]
	s_waitcnt vmcnt(3)
	v_pk_mul_f32 v[18:19], v[18:19], v[24:25]
	v_pk_mul_f32 v[24:25], v[40:41], v[26:27]
	s_waitcnt vmcnt(2)
	v_pk_mul_f32 v[26:27], v[42:43], v[28:29]
	v_pk_mul_f32 v[16:17], v[16:17], v[30:31]
	s_waitcnt vmcnt(1)
	v_pk_fma_f32 v[14:15], v[14:15], v[32:33], v[18:19]
	v_pk_fma_f32 v[12:13], v[12:13], v[34:35], v[24:25]
	s_waitcnt vmcnt(0)
	v_pk_fma_f32 v[10:11], v[10:11], v[36:37], v[26:27]
	v_pk_fma_f32 v[8:9], v[8:9], v[38:39], v[16:17]

; DI u32x4 pack8(const float* f) { u32x4 o; o.x = pack2(f[0], f[1]); o.y = pack2(f[2], f[3]); o.z = pack2(f[4], f[5]); o.w = pack2(f[6], f[7]); return o; }
; DI void q_tile(PREF p, int l, int idx, unsigned char* ldsb) {
;     ...
;   for (int q = 0; q < 8; ++q) {
;     int r = (tid >> 4) + 16 * q, c = (tid & 15) * 8;
;     int n = col0 + c; int dd = n % 96;
;     float rs = aux[r];
;     float v[8]; ld8(Cs + r * CST + c, v);
; #pragma unroll
;     for (int j = 0; j < 8; ++j) v[j] *= rs;
;     if (dd >= 64) {
;       int ri0 = dd - 64; int s = (row0 + r) & 4095;
;       float pv[8];
;       if (ri0 < 16) {
;         ld8(Cs + r * CST + c + 16, pv);
;         const float* cs = p.rcos + s * 16 + ri0; const float* sn = p.rsin + s * 16 + ri0;
; #pragma unroll
;         for (int j = 0; j < 8; ++j) v[j] = v[j] * cs[j] - pv[j] * rs * sn[j];
;       } else {
;         ld8(Cs + r * CST + c - 16, pv);
;         const float* cs = p.rcos + s * 16 + ri0 - 16; const float* sn = p.rsin + s * 16 + ri0 - 16;
; #pragma unroll
;         for (int j = 0; j < 8; ++j) v[j] = v[j] * cs[j] + pv[j] * rs * sn[j];
;       }
;     }
;     *(u32x4*)(p.Qm + (size_t)(row0 + r) * 384 + n) = pack8(v);
.LBB0_390:
	s_or_b64 exec, exec, s[16:17]
	v_cvt_pk_bf16_f32 v17, v8, v9
	v_mad_i64_i32 v[8:9], s[0:1], v23, s96, v[6:7]
	v_cvt_pk_bf16_f32 v14, v14, v15
	v_cvt_pk_bf16_f32 v15, v12, v13
	v_cvt_pk_bf16_f32 v16, v10, v11
	global_store_dwordx4 v[8:9], v[14:17], off
	ds_read_b32 v16, v21 offset:448
	ds_read_b128 v[8:11], v22 offset:33792
	ds_read_b128 v[24:27], v22 offset:33808
	v_add_u32_e32 v18, 0x70, v20
	s_waitcnt lgkmcnt(1)
	v_pk_mul_f32 v[14:15], v[16:17], v[8:9] op_sel_hi:[0,1]
	v_pk_mul_f32 v[12:13], v[16:17], v[10:11] op_sel_hi:[0,1]
	s_waitcnt lgkmcnt(0)
	v_pk_mul_f32 v[10:11], v[16:17], v[24:25] op_sel_hi:[0,1]
	v_pk_mul_f32 v[8:9], v[16:17], v[26:27] op_sel_hi:[0,1]
	s_and_saveexec_b64 s[16:17], s[8:9]
	s_cbranch_execz .LBB0_343
	v_lshlrev_b32_e32 v0, 4, v18
	v_and_b32_e32 v0, 0xfff0, v0
	v_lshlrev_b32_e32 v0, 2, v0
	v_mov_b32_e32 v17, v16
	v_lshl_add_u64 v[4:5], v[4:5], 0, v[0:1]
	s_and_saveexec_b64 s[0:1], vcc
	s_xor_b64 s[8:9], exec, s[0:1]
	s_cbranch_execz .LBB0_393
	v_lshl_add_u64 v[2:3], v[2:3], 0, v[0:1]
	global_load_dwordx4 v[24:27], v[2:3], off offset:-64
	global_load_dwordx4 v[28:31], v[2:3], off offset:-48
	global_load_dwordx4 v[32:35], v[4:5], off offset:-64
	s_nop 0
	global_load_dwordx4 v[2:5], v[4:5], off offset:-48
	ds_read_b128 v[36:39], v22 offset:33728
	ds_read_b128 v[20:23], v22 offset:33744
	s_waitcnt lgkmcnt(1)
	v_pk_mul_f32 v[36:37], v[16:17], v[36:37]
	v_pk_mul_f32 v[38:39], v[16:17], v[38:39]
	s_waitcnt lgkmcnt(0)
	v_pk_mul_f32 v[20:21], v[16:17], v[20:21]
	v_pk_mul_f32 v[16:17], v[16:17], v[22:23]
	s_waitcnt vmcnt(3)
	v_pk_mul_f32 v[22:23], v[36:37], v[24:25]
	v_pk_mul_f32 v[24:25], v[38:39], v[26:27]
	s_waitcnt vmcnt(2)
	v_pk_mul_f32 v[20:21], v[20:21], v[28:29]
	v_pk_mul_f32 v[16:17], v[16:17], v[30:31]
	s_waitcnt vmcnt(1)
	v_pk_fma_f32 v[14:15], v[14:15], v[32:33], v[22:23]
	v_pk_fma_f32 v[12:13], v[12:13], v[34:35], v[24:25]
	s_waitcnt vmcnt(0)
	v_pk_fma_f32 v[10:11], v[10:11], v[2:3], v[20:21]
	v_pk_fma_f32 v[8:9], v[8:9], v[4:5], v[16:17]

; DI int tidx() { int t = threadIdx.x & 255; asm volatile("" : "+v"(t)); return t; }
; DI int vbid() { return (int)blockIdx.x * 2 + half_(); }
; DI int vgrid() { return (int)gridDim.x * 2; }
; DI u32x4 pack8(const float* f) { u32x4 o; o.x = pack2(f[0], f[1]); o.y = pack2(f[2], f[3]); o.z = pack2(f[4], f[5]); o.w = pack2(f[6], f[7]); return o; }
; DI void rows_ple(PREF p, int l) {
;   const int tid = tidx(), lane = tid & 63, w = tid >> 6;
;   for (int row = vbid() * 4 + w; row < T_; row += vgrid() * 4) {
;     const u16* src = (const u16*)p.fbuf + (size_t)row * 1024;
;     float v[16];
;     unpack8(*(const u32x4*)(src + lane * 8), v);
;     unpack8(*(const u32x4*)(src + 512 + lane * 8), v + 8);
;     float xv[16];
;     unpack8(*(const u32x4*)(p.X + (size_t)row * 1024 + lane * 8), xv);
;     unpack8(*(const u32x4*)(p.X + (size_t)row * 1024 + 512 + lane * 8), xv + 8);
;     float sq = 0.f;
; #pragma unroll
;     for (int i = 0; i < 16; ++i) sq += v[i] * v[i];
;     const float rs = rsqrtf(wsum(sq) * (1.f / 1024.f) + 1e-6f);
; #pragma unroll
;     for (int h = 0; h < 2; ++h) {
;       const int c = h * 512 + lane * 8;
;       const float4 g0 = *(const float4*)(p.ple_ng + l * 1024 + c), g1 = *(const float4*)(p.ple_ng + l * 1024 + c + 4);
;       float y[8];
;       y[0] = xv[h * 8 + 0] + v[h * 8 + 0] * rs * g0.x; y[1] = xv[h * 8 + 1] + v[h * 8 + 1] * rs * g0.y;
;       y[2] = xv[h * 8 + 2] + v[h * 8 + 2] * rs * g0.z; y[3] = xv[h * 8 + 3] + v[h * 8 + 3] * rs * g0.w;
;       y[4] = xv[h * 8 + 4] + v[h * 8 + 4] * rs * g1.x; y[5] = xv[h * 8 + 5] + v[h * 8 + 5] * rs * g1.y;
;       y[6] = xv[h * 8 + 6] + v[h * 8 + 6] * rs * g1.z; y[7] = xv[h * 8 + 7] + v[h * 8 + 7] * rs * g1.w;
;       if (l == NL - 1) {
;         float4* od = (float4*)(p.out + (size_t)row * 1024 + c);
;         od[0] = make_float4(y[0], y[1], y[2], y[3]); od[1] = make_float4(y[4], y[5], y[6], y[7]);
;       } else {
;         *(u32x4*)(p.X + (size_t)row * 1024 + c) = pack8(y);
.LBB0_433:
	v_readlane_b32 s14, v254, 46
	v_readlane_b32 s15, v254, 47
	s_load_dwordx2 s[0:1], s[14:15], 0x190
	s_waitcnt lgkmcnt(0)
	v_lshl_add_u64 v[2:3], s[0:1], 0, v[20:21]
	global_load_dwordx4 v[10:13], v[2:3], off offset:-1024
	global_load_dwordx4 v[6:9], v[2:3], off
	s_load_dwordx2 s[0:1], s[14:15], 0x130
	s_mov_b64 s[14:15], -1
	s_waitcnt lgkmcnt(0)
	v_lshl_add_u64 v[22:23], s[0:1], 0, v[20:21]
	global_load_dwordx4 v[40:43], v[22:23], off offset:-1024
	global_load_dwordx4 v[2:5], v[22:23], off
	global_load_dwordx4 v[44:47], v[16:17], off offset:16
	global_load_dwordx4 v[48:51], v[16:17], off
	s_waitcnt vmcnt(5)
	v_lshlrev_b32_e32 v60, 16, v11
	s_waitcnt vmcnt(4)
	v_lshlrev_b32_e32 v24, 16, v6
	v_and_b32_e32 v25, 0xffff0000, v6
	v_lshlrev_b32_e32 v26, 16, v7
	v_and_b32_e32 v27, 0xffff0000, v7
	v_lshlrev_b32_e32 v6, 16, v10
	v_and_b32_e32 v7, 0xffff0000, v10
	v_pk_mul_f32 v[58:59], v[6:7], v[6:7]
	v_and_b32_e32 v61, 0xffff0000, v11
	v_pk_mul_f32 v[10:11], v[60:61], v[60:61]
	v_add_f32_e32 v0, v58, v59
	v_lshlrev_b32_e32 v62, 16, v12
	v_and_b32_e32 v63, 0xffff0000, v12
	v_add_f32_e32 v0, v10, v0
	v_pk_mul_f32 v[66:67], v[62:63], v[62:63]
	v_add_f32_e32 v0, v11, v0
	v_lshlrev_b32_e32 v68, 16, v13
	v_and_b32_e32 v69, 0xffff0000, v13
	v_add_f32_e32 v0, v66, v0
	v_pk_mul_f32 v[12:13], v[68:69], v[68:69]
	v_add_f32_e32 v0, v67, v0
	v_add_f32_e32 v0, v12, v0
	v_pk_mul_f32 v[32:33], v[24:25], v[24:25]
	v_add_f32_e32 v0, v13, v0
	v_add_f32_e32 v0, v32, v0
	v_pk_mul_f32 v[52:53], v[26:27], v[26:27]
	v_add_f32_e32 v0, v33, v0
	v_lshlrev_b32_e32 v28, 16, v8
	v_and_b32_e32 v29, 0xffff0000, v8
	v_add_f32_e32 v0, v52, v0
	v_pk_mul_f32 v[54:55], v[28:29], v[28:29]
	v_add_f32_e32 v0, v53, v0
	v_lshlrev_b32_e32 v30, 16, v9
	v_and_b32_e32 v31, 0xffff0000, v9
	v_add_f32_e32 v0, v54, v0
	v_pk_mul_f32 v[56:57], v[30:31], v[30:31]
	v_add_f32_e32 v0, v55, v0
	v_add_f32_e32 v0, v56, v0
	v_add_f32_e32 v0, v57, v0
	ds_bpermute_b32 v10, v34, v0
	s_waitcnt vmcnt(3)
	v_lshlrev_b32_e32 v8, 16, v40
	v_and_b32_e32 v9, 0xffff0000, v40
	v_lshlrev_b32_e32 v40, 16, v41
	v_and_b32_e32 v41, 0xffff0000, v41
	s_waitcnt lgkmcnt(0)
	v_add_f32_e32 v0, v0, v10
	ds_bpermute_b32 v10, v35, v0
	v_lshlrev_b32_e32 v64, 16, v42
	v_and_b32_e32 v65, 0xffff0000, v42
	v_lshlrev_b32_e32 v42, 16, v43
	v_and_b32_e32 v43, 0xffff0000, v43
	s_waitcnt lgkmcnt(0)
	v_add_f32_e32 v0, v0, v10
	ds_bpermute_b32 v10, v36, v0
	s_waitcnt lgkmcnt(0)
	v_add_f32_e32 v0, v0, v10
	ds_bpermute_b32 v10, v37, v0
	s_waitcnt lgkmcnt(0)
	v_add_f32_e32 v0, v0, v10
	ds_bpermute_b32 v10, v38, v0
	s_waitcnt lgkmcnt(0)
	v_add_f32_e32 v0, v0, v10
	ds_bpermute_b32 v10, v39, v0
	s_waitcnt lgkmcnt(0)
	v_add_f32_e32 v0, v0, v10
	v_fmamk_f32 v0, v0, 0x3a800000, v173
	v_cmp_gt_f32_e32 vcc, s61, v0
	v_mul_f32_e32 v10, 0x4b800000, v0
	s_nop 0
	v_cndmask_b32_e32 v0, v0, v10, vcc
	v_rsq_f32_e32 v0, v0
	s_nop 0
	v_mul_f32_e32 v10, 0x45800000, v0
	v_cndmask_b32_e32 v32, v0, v10, vcc
	v_pk_mul_f32 v[6:7], v[32:33], v[6:7] op_sel_hi:[0,1]
	s_waitcnt vmcnt(0)
	v_pk_fma_f32 v[10:11], v[48:49], v[6:7], v[8:9]
	v_pk_mul_f32 v[6:7], v[32:33], v[60:61] op_sel_hi:[0,1]
	v_pk_fma_f32 v[12:13], v[50:51], v[6:7], v[40:41]
	v_pk_mul_f32 v[6:7], v[32:33], v[62:63] op_sel_hi:[0,1]
	v_pk_mul_f32 v[8:9], v[32:33], v[68:69] op_sel_hi:[0,1]
	v_pk_fma_f32 v[6:7], v[44:45], v[6:7], v[64:65]
	v_pk_fma_f32 v[8:9], v[46:47], v[8:9], v[42:43]
	s_and_b64 vcc, exec, s[10:11]
	s_cbranch_vccz .LBB0_435
	v_cvt_pk_bf16_f32 v40, v10, v11
	v_cvt_pk_bf16_f32 v41, v12, v13
	v_cvt_pk_bf16_f32 v42, v6, v7
	v_cvt_pk_bf16_f32 v43, v8, v9
	global_store_dwordx4 v[22:23], v[40:43], off offset:-1024
	s_mov_b64 s[14:15], 0

; DI u32x4 pack8(const float* f) { u32x4 o; o.x = pack2(f[0], f[1]); o.y = pack2(f[2], f[3]); o.z = pack2(f[4], f[5]); o.w = pack2(f[6], f[7]); return o; }
; DI void rows_ple(PREF p, int l) {
;     ...
; #pragma unroll
;     for (int h = 0; h < 2; ++h) {
;       const int c = h * 512 + lane * 8;
;       const float4 g0 = *(const float4*)(p.ple_ng + l * 1024 + c), g1 = *(const float4*)(p.ple_ng + l * 1024 + c + 4);
;       float y[8];
;       y[0] = xv[h * 8 + 0] + v[h * 8 + 0] * rs * g0.x; y[1] = xv[h * 8 + 1] + v[h * 8 + 1] * rs * g0.y;
;       y[2] = xv[h * 8 + 2] + v[h * 8 + 2] * rs * g0.z; y[3] = xv[h * 8 + 3] + v[h * 8 + 3] * rs * g0.w;
;       y[4] = xv[h * 8 + 4] + v[h * 8 + 4] * rs * g1.x; y[5] = xv[h * 8 + 5] + v[h * 8 + 5] * rs * g1.y;
;       y[6] = xv[h * 8 + 6] + v[h * 8 + 6] * rs * g1.z; y[7] = xv[h * 8 + 7] + v[h * 8 + 7] * rs * g1.w;
;       if (l == NL - 1) {
;         float4* od = (float4*)(p.out + (size_t)row * 1024 + c);
;         od[0] = make_float4(y[0], y[1], y[2], y[3]); od[1] = make_float4(y[4], y[5], y[6], y[7]);
;       } else {
;         *(u32x4*)(p.X + (size_t)row * 1024 + c) = pack8(y);
;       }
;     }
.LBB0_437:
	global_load_dwordx4 v[6:9], v[16:17], off offset:2048
	s_nop 0
	global_load_dwordx4 v[10:13], v[16:17], off offset:2064
	v_mov_b32_e32 v33, v32
	v_lshlrev_b32_e32 v40, 16, v2
	v_and_b32_e32 v41, 0xffff0000, v2
	v_lshlrev_b32_e32 v2, 16, v3
	v_and_b32_e32 v3, 0xffff0000, v3
	v_lshlrev_b32_e32 v42, 16, v4
	v_and_b32_e32 v43, 0xffff0000, v4
	v_lshlrev_b32_e32 v4, 16, v5
	v_and_b32_e32 v5, 0xffff0000, v5
	v_pk_mul_f32 v[24:25], v[32:33], v[24:25]
	v_pk_mul_f32 v[26:27], v[32:33], v[26:27]
	v_pk_mul_f32 v[28:29], v[32:33], v[28:29]
	v_pk_mul_f32 v[30:31], v[32:33], v[30:31]
	s_andn2_b64 vcc, exec, s[10:11]
	s_mov_b64 s[14:15], -1
	s_waitcnt vmcnt(1)
	v_pk_fma_f32 v[6:7], v[24:25], v[6:7], v[40:41]
	v_pk_fma_f32 v[8:9], v[26:27], v[8:9], v[2:3]
	s_waitcnt vmcnt(0)
	v_pk_fma_f32 v[2:3], v[28:29], v[10:11], v[42:43]
	v_pk_fma_f32 v[4:5], v[30:31], v[12:13], v[4:5]
	s_cbranch_vccnz .LBB0_439
	s_mov_b64 s[14:15], 0
	v_cvt_pk_bf16_f32 v10, v6, v7
	v_cvt_pk_bf16_f32 v11, v8, v9
	v_cvt_pk_bf16_f32 v12, v2, v3
	v_cvt_pk_bf16_f32 v13, v4, v5
	global_store_dwordx4 v[22:23], v[10:13], off

; DI u32x4 pack8(const float* f) { u32x4 o; o.x = pack2(f[0], f[1]); o.y = pack2(f[2], f[3]); o.z = pack2(f[4], f[5]); o.w = pack2(f[6], f[7]); return o; }
; DI void lds_barrier() { asm volatile("s_waitcnt lgkmcnt(0)\n\ts_barrier" ::: "memory"); }
; DI int tid512() { int t = threadIdx.x; asm volatile("" : "+v"(t)); return t; }
; template <int AI, int BJ>
; DI void stage_q(const f32x4 (&acc)[2][2][4][2], float* Cs) {
;   const int t = tid512(), wid = t >> 6, lane = t & 63, wr = wid >> 2, wc = wid & 3, fr = lane & 15, fq = lane >> 4;
;   lds_barrier();
; #pragma unroll
;   for (int m = 0; m < 4; ++m)
; #pragma unroll
;     for (int n = 0; n < 2; ++n)
; #pragma unroll
;       for (int j = 0; j < 4; ++j) Cs[(wr * 64 + m * 16 + fq * 4 + j) * CST + wc * 32 + n * 16 + fr] = acc[AI][BJ][m][n][j];
;   lds_barrier();
; }
; template <int AI, int BJ>
; DI void in_quadrant(PREF p, const f32x4 (&acc)[2][2][4][2], int mt, int nt, float* Cs) {
;   const int t = tid512();
;   const int row0 = mt * 256 + AI * 128, col0 = nt * 256 + BJ * 128;
;   if (col0 >= HW) return;
;   stage_q<AI, BJ>(acc, Cs);
; #pragma unroll
;   for (int q = 0; q < 4; ++q) {
;     int r = (t >> 4) + 32 * q, c = (t & 15) * 8;
;     if (col0 + c < HW) {
;       float v[8]; ld8(Cs + r * CST + c, v);
;       *(u32x4*)(p.hb + (size_t)(row0 + r) * HW + col0 + c) = pack8(v);
;     }
;   }
.LBB0_456:
	s_or_b64 exec, exec, s[18:19]
	s_lshl_b32 s17, s16, 8
	s_lshl_b32 s18, s14, 8
	s_cmp_lt_i32 s14, 11
	v_mov_b32_e32 v130, v168
	s_cselect_b64 s[20:21], -1, 0
	s_cmp_gt_i32 s14, 10
	s_cbranch_scc1 .LBB0_463
	v_mov_b32_e32 v0, v168
	s_waitcnt lgkmcnt(0)
	s_barrier
	s_nop 0
	v_and_b32_e32 v131, 15, v0
	v_lshrrev_b32_e32 v132, 2, v0
	v_lshlrev_b32_e32 v0, 1, v0
	v_lshlrev_b32_e32 v131, 2, v131
	v_and_b32_e32 v132, 0xfffffcc, v132
	v_and_or_b32 v0, v0, s89, v131
	v_mad_u64_u32 v[132:133], s[0:1], v132, s92, v[0:1]
	v_add_u32_e32 v0, 0x400, v132
	ds_write2_b32 v132, v118, v126 offset1:16
	ds_write2_b32 v132, v119, v127 offset0:132 offset1:148
	ds_write2_b32 v0, v120, v128 offset0:8 offset1:24
	ds_write2_b32 v0, v121, v129 offset0:140 offset1:156
	v_add_u32_e32 v0, 0x2000, v132
	ds_write2_b32 v0, v114, v122 offset0:64 offset1:80
	ds_write2_b32 v0, v115, v123 offset0:196 offset1:212
	v_add_u32_e32 v0, 0x2400, v132
	ds_write2_b32 v0, v116, v124 offset0:72 offset1:88
	ds_write2_b32 v0, v117, v125 offset0:204 offset1:220
	v_add_u32_e32 v0, 0x4000, v132
	ds_write2_b32 v0, v106, v110 offset0:128 offset1:144
	v_add_u32_e32 v0, 0x4400, v132
	ds_write2_b32 v0, v107, v111 offset0:4 offset1:20
	ds_write2_b32 v0, v108, v112 offset0:136 offset1:152
	v_add_u32_e32 v0, 0x4800, v132
	ds_write2_b32 v0, v109, v113 offset0:12 offset1:28
	v_add_u32_e32 v0, 0x6000, v132
	ds_write2_b32 v0, v98, v102 offset0:192 offset1:208
	v_add_u32_e32 v0, 0x6400, v132
	ds_write2_b32 v0, v99, v103 offset0:68 offset1:84
	ds_write2_b32 v0, v100, v104 offset0:200 offset1:216
	v_add_u32_e32 v0, 0x6800, v132
	ds_write2_b32 v0, v101, v105 offset0:76 offset1:92
	v_lshlrev_b32_e32 v0, 3, v130
	s_waitcnt lgkmcnt(0)
	s_barrier
	v_and_b32_e32 v98, 0x78, v0
	v_or_b32_e32 v0, s18, v98
	v_cmp_gt_i32_e32 vcc, s58, v0
	s_and_saveexec_b64 s[22:23], vcc
	s_cbranch_execz .LBB0_459
	s_ashr_i32 s19, s18, 31
	s_lshl_b64 s[0:1], s[18:19], 1
	s_add_u32 s0, s10, s0
	s_addc_u32 s1, s11, s1
	v_lshlrev_b32_e32 v0, 1, v98
	v_lshl_add_u64 v[106:107], s[0:1], 0, v[0:1]
	v_ashrrev_i32_e32 v0, 4, v130
	v_mul_lo_u32 v99, v0, s92
	v_lshl_add_u32 v108, v98, 2, v99
	s_waitcnt vmcnt(0)
	ds_read_b128 v[98:101], v108
	ds_read_b128 v[102:105], v108 offset:16
	v_add_u32_e32 v0, s17, v0
	s_waitcnt lgkmcnt(1)
	v_cvt_pk_bf16_f32 v98, v98, v99
	v_cvt_pk_bf16_f32 v99, v100, v101
	s_waitcnt lgkmcnt(0)
	v_cvt_pk_bf16_f32 v100, v102, v103
	v_mad_i64_i32 v[102:103], s[0:1], v0, s60, v[106:107]
	v_cvt_pk_bf16_f32 v101, v104, v105
	global_store_dwordx4 v[102:103], v[98:101], off
	ds_read_b128 v[98:101], v108 offset:16896
	ds_read_b128 v[102:105], v108 offset:16912
	s_waitcnt lgkmcnt(1)
	v_cvt_pk_bf16_f32 v98, v98, v99
	v_cvt_pk_bf16_f32 v99, v100, v101
	s_waitcnt lgkmcnt(0)
	v_cvt_pk_bf16_f32 v100, v102, v103
	v_add_u32_e32 v102, 32, v0
	v_mad_i64_i32 v[102:103], s[0:1], v102, s60, v[106:107]
	v_cvt_pk_bf16_f32 v101, v104, v105
	global_store_dwordx4 v[102:103], v[98:101], off
	ds_read_b128 v[98:101], v108 offset:33792
	ds_read_b128 v[102:105], v108 offset:33808
	s_waitcnt lgkmcnt(1)
	v_cvt_pk_bf16_f32 v98, v98, v99
	v_cvt_pk_bf16_f32 v99, v100, v101
	s_waitcnt lgkmcnt(0)
	v_cvt_pk_bf16_f32 v100, v102, v103
	v_add_u32_e32 v102, 64, v0
	v_mad_i64_i32 v[102:103], s[0:1], v102, s60, v[106:107]
	v_cvt_pk_bf16_f32 v101, v104, v105
	global_store_dwordx4 v[102:103], v[98:101], off
	ds_read_b128 v[98:101], v108 offset:50688
	ds_read_b128 v[102:105], v108 offset:50704
	v_add_u32_e32 v0, 0x60, v0
	s_waitcnt lgkmcnt(1)
	v_cvt_pk_bf16_f32 v98, v98, v99
	v_cvt_pk_bf16_f32 v99, v100, v101
	s_waitcnt lgkmcnt(0)
	v_cvt_pk_bf16_f32 v100, v102, v103
	v_mad_i64_i32 v[102:103], s[0:1], v0, s60, v[106:107]
	v_cvt_pk_bf16_f32 v101, v104, v105
	global_store_dwordx4 v[102:103], v[98:101], off
; DI u32x4 pack8(const float* f) { u32x4 o; o.x = pack2(f[0], f[1]); o.y = pack2(f[2], f[3]); o.z = pack2(f[4], f[5]); o.w = pack2(f[6], f[7]); return o; }
; template <int AI, int BJ>
; DI void in_quadrant(PREF p, const f32x4 (&acc)[2][2][4][2], int mt, int nt, float* Cs) {
;     ...
;   if (col0 + 128 > OFF_SV && col0 < OFF_SV + 128) {
;     int b = row0 >> 12, s0 = row0 & 4095;
; #pragma unroll
;     for (int q = 0; q < 4; ++q) {
;       int item = t + 512 * q; int c = item & 127, rg = item >> 7;
;       int vc = col0 + c - OFF_SV;
;       if (vc >= 0 && vc < 128) {
;         float v[8];
; #pragma unroll
;         for (int j = 0; j < 8; ++j) v[j] = Cs[(rg * 8 + j) * CST + c];
;         *(u32x4*)(p.Vst + ((size_t)(b * 2 + (vc >> 6)) * 64 + (vc & 63)) * S_ + s0 + rg * 8) = pack8(v);
;       }
;     }
;   }
.LBB0_459:
	s_or_b64 exec, exec, s[22:23]
	s_cmp_lt_i32 s14, 9
	s_cselect_b64 s[0:1], -1, 0
	s_cmp_eq_u32 s14, 10
	s_cselect_b64 s[22:23], -1, 0
	s_or_b64 s[0:1], s[0:1], s[22:23]
	s_and_b64 vcc, exec, s[0:1]
	s_cbranch_vccnz .LBB0_463
	v_and_b32_e32 v100, 0x7f, v130
	v_or_b32_e32 v0, s18, v100
	v_add_u32_e32 v0, 0xfffff6e0, v0
	v_cmp_gt_u32_e32 vcc, s93, v0
	s_and_saveexec_b64 s[22:23], vcc
	s_cbranch_execz .LBB0_462
	v_lshrrev_b32_e32 v98, 6, v0
	s_ashr_i32 s0, s16, 3
	v_and_or_b32 v98, s0, -2, v98
	v_ashrrev_i32_e32 v99, 31, v98
	v_lshlrev_b64 v[98:99], 19, v[98:99]
	v_lshlrev_b32_e32 v0, 13, v0
	v_lshl_add_u64 v[98:99], s[12:13], 0, v[98:99]
	v_and_b32_e32 v0, 0x7e000, v0
	v_lshl_add_u64 v[98:99], v[98:99], 0, v[0:1]
	v_lshlrev_b32_e32 v0, 2, v100
	v_ashrrev_i32_e32 v100, 4, v130
	s_and_b32 s0, s17, 0xf00
	v_and_b32_e32 v104, -8, v100
	s_lshl_b32 s52, s0, 1
	v_mad_u64_u32 v[106:107], s[0:1], v104, s92, v[0:1]
	v_or_b32_e32 v100, 7, v100
	v_mad_u64_u32 v[108:109], s[0:1], v100, s92, v[0:1]
	ds_read2_b32 v[100:101], v106 offset1:132
	s_waitcnt lgkmcnt(0)
	v_cvt_pk_bf16_f32 v100, v100, v101
	v_add_u32_e32 v101, 0x400, v106
	ds_read2_b32 v[102:103], v101 offset0:8 offset1:140
	s_waitcnt lgkmcnt(0)
	v_cvt_pk_bf16_f32 v101, v102, v103
	v_add_u32_e32 v102, 0x800, v106
	ds_read2_b32 v[102:103], v102 offset0:16 offset1:148
	s_waitcnt lgkmcnt(0)
	v_cvt_pk_bf16_f32 v102, v102, v103
	ds_read_b32 v103, v106 offset:3168
	ds_read_b32 v105, v108
	v_lshl_add_u64 v[98:99], v[98:99], 0, s[52:53]
	s_waitcnt lgkmcnt(0)
	v_cvt_pk_bf16_f32 v103, v103, v105
	v_ashrrev_i32_e32 v105, 31, v104
	v_lshl_add_u64 v[104:105], v[104:105], 1, v[98:99]
	global_store_dwordx4 v[104:105], v[100:103], off
	s_nop 1
	v_add_u32_e32 v100, 0x200, v130
	v_ashrrev_i32_e32 v100, 4, v100
	v_and_b32_e32 v104, -8, v100
	v_mad_u64_u32 v[106:107], s[0:1], v104, s92, v[0:1]
	v_or_b32_e32 v100, 7, v100
	v_mad_u64_u32 v[108:109], s[0:1], v100, s92, v[0:1]
	ds_read2_b32 v[100:101], v106 offset1:132
	s_waitcnt lgkmcnt(0)
	v_cvt_pk_bf16_f32 v100, v100, v101
	v_add_u32_e32 v101, 0x400, v106
	ds_read2_b32 v[102:103], v101 offset0:8 offset1:140
	s_waitcnt lgkmcnt(0)
	v_cvt_pk_bf16_f32 v101, v102, v103
	v_add_u32_e32 v102, 0x800, v106
	ds_read2_b32 v[102:103], v102 offset0:16 offset1:148
	s_waitcnt lgkmcnt(0)
	v_cvt_pk_bf16_f32 v102, v102, v103
	ds_read_b32 v103, v106 offset:3168
	ds_read_b32 v105, v108
	s_waitcnt lgkmcnt(0)
	v_cvt_pk_bf16_f32 v103, v103, v105
	v_ashrrev_i32_e32 v105, 31, v104
	v_lshl_add_u64 v[104:105], v[104:105], 1, v[98:99]
	global_store_dwordx4 v[104:105], v[100:103], off
	s_nop 1
	v_add_u32_e32 v100, 0x400, v130
	v_ashrrev_i32_e32 v100, 4, v100
	v_and_b32_e32 v104, -8, v100
	v_mad_u64_u32 v[106:107], s[0:1], v104, s92, v[0:1]
	v_or_b32_e32 v100, 7, v100
	v_mad_u64_u32 v[108:109], s[0:1], v100, s92, v[0:1]
	ds_read2_b32 v[100:101], v106 offset1:132
	s_waitcnt lgkmcnt(0)
	v_cvt_pk_bf16_f32 v100, v100, v101
	v_add_u32_e32 v101, 0x400, v106
	ds_read2_b32 v[102:103], v101 offset0:8 offset1:140
	s_waitcnt lgkmcnt(0)
	v_cvt_pk_bf16_f32 v101, v102, v103
	v_add_u32_e32 v102, 0x800, v106
	ds_read2_b32 v[102:103], v102 offset0:16 offset1:148
	s_waitcnt lgkmcnt(0)
	v_cvt_pk_bf16_f32 v102, v102, v103
	ds_read_b32 v103, v106 offset:3168
	ds_read_b32 v105, v108
	s_waitcnt lgkmcnt(0)
	v_cvt_pk_bf16_f32 v103, v103, v105
	v_ashrrev_i32_e32 v105, 31, v104
	v_lshl_add_u64 v[104:105], v[104:105], 1, v[98:99]
	global_store_dwordx4 v[104:105], v[100:103], off
	s_nop 1
	v_add_u32_e32 v100, 0x600, v130
	v_ashrrev_i32_e32 v100, 4, v100
	v_and_b32_e32 v104, -8, v100
	v_mad_u64_u32 v[106:107], s[0:1], v104, s92, v[0:1]
	v_or_b32_e32 v100, 7, v100
	v_mad_u64_u32 v[108:109], s[0:1], v100, s92, v[0:1]
	v_add_u32_e32 v0, 0x400, v106
	ds_read2_b32 v[100:101], v106 offset1:132
	ds_read2_b32 v[102:103], v0 offset0:8 offset1:140
	v_add_u32_e32 v0, 0x800, v106
	s_waitcnt lgkmcnt(0)
	v_cvt_pk_bf16_f32 v100, v100, v101
	v_cvt_pk_bf16_f32 v101, v102, v103
	ds_read2_b32 v[102:103], v0 offset0:16 offset1:148
	s_waitcnt lgkmcnt(0)
	v_cvt_pk_bf16_f32 v102, v102, v103
	ds_read_b32 v0, v106 offset:3168
	ds_read_b32 v103, v108
	v_ashrrev_i32_e32 v105, 31, v104
	v_lshl_add_u64 v[98:99], v[104:105], 1, v[98:99]
	s_waitcnt lgkmcnt(0)
	v_cvt_pk_bf16_f32 v103, v0, v103
	global_store_dwordx4 v[98:99], v[100:103], off

; DI u32x4 pack8(const float* f) { u32x4 o; o.x = pack2(f[0], f[1]); o.y = pack2(f[2], f[3]); o.z = pack2(f[4], f[5]); o.w = pack2(f[6], f[7]); return o; }
; DI void lds_barrier() { asm volatile("s_waitcnt lgkmcnt(0)\n\ts_barrier" ::: "memory"); }
; DI int tid512() { int t = threadIdx.x; asm volatile("" : "+v"(t)); return t; }
; template <int AI, int BJ>
; DI void stage_q(const f32x4 (&acc)[2][2][4][2], float* Cs) {
;   const int t = tid512(), wid = t >> 6, lane = t & 63, wr = wid >> 2, wc = wid & 3, fr = lane & 15, fq = lane >> 4;
;   lds_barrier();
; #pragma unroll
;   for (int m = 0; m < 4; ++m)
; #pragma unroll
;     for (int n = 0; n < 2; ++n)
; #pragma unroll
;       for (int j = 0; j < 4; ++j) Cs[(wr * 64 + m * 16 + fq * 4 + j) * CST + wc * 32 + n * 16 + fr] = acc[AI][BJ][m][n][j];
;   lds_barrier();
; }
; template <int AI, int BJ>
; DI void in_quadrant(PREF p, const f32x4 (&acc)[2][2][4][2], int mt, int nt, float* Cs) {
;   const int t = tid512();
;   const int row0 = mt * 256 + AI * 128, col0 = nt * 256 + BJ * 128;
;   if (col0 >= HW) return;
;   stage_q<AI, BJ>(acc, Cs);
; #pragma unroll
;   for (int q = 0; q < 4; ++q) {
;     int r = (t >> 4) + 32 * q, c = (t & 15) * 8;
;     if (col0 + c < HW) {
;       float v[8]; ld8(Cs + r * CST + c, v);
;       *(u32x4*)(p.hb + (size_t)(row0 + r) * HW + col0 + c) = pack8(v);
;     }
;   }
.LBB0_463:
	s_or_b32 s15, s18, 0x80
	s_cmpk_lt_i32 s15, 0xaa0
	v_mov_b32_e32 v98, v168
	s_cselect_b64 s[22:23], -1, 0
	s_cmpk_gt_i32 s15, 0xa9f
	s_cbranch_scc1 .LBB0_470
	v_mov_b32_e32 v0, v168
	s_waitcnt lgkmcnt(0)
	s_barrier
	s_nop 0
	v_and_b32_e32 v99, 15, v0
	v_lshrrev_b32_e32 v100, 2, v0
	v_lshlrev_b32_e32 v0, 1, v0
	v_lshlrev_b32_e32 v99, 2, v99
	v_and_b32_e32 v100, 0xfffffcc, v100
	v_and_or_b32 v0, v0, s89, v99
	v_mad_u64_u32 v[100:101], s[0:1], v100, s92, v[0:1]
	v_add_u32_e32 v0, 0x400, v100
	ds_write2_b32 v100, v86, v94 offset1:16
	ds_write2_b32 v100, v87, v95 offset0:132 offset1:148
	ds_write2_b32 v0, v88, v96 offset0:8 offset1:24
	ds_write2_b32 v0, v89, v97 offset0:140 offset1:156
	v_add_u32_e32 v0, 0x2000, v100
	ds_write2_b32 v0, v82, v90 offset0:64 offset1:80
	ds_write2_b32 v0, v83, v91 offset0:196 offset1:212
	v_add_u32_e32 v0, 0x2400, v100
	ds_write2_b32 v0, v84, v92 offset0:72 offset1:88
	ds_write2_b32 v0, v85, v93 offset0:204 offset1:220
	v_add_u32_e32 v0, 0x4000, v100
	ds_write2_b32 v0, v74, v78 offset0:128 offset1:144
	v_add_u32_e32 v0, 0x4400, v100
	ds_write2_b32 v0, v75, v79 offset0:4 offset1:20
	ds_write2_b32 v0, v76, v80 offset0:136 offset1:152
	v_add_u32_e32 v0, 0x4800, v100
	ds_write2_b32 v0, v77, v81 offset0:12 offset1:28
	v_add_u32_e32 v0, 0x6000, v100
	ds_write2_b32 v0, v66, v70 offset0:192 offset1:208
	v_add_u32_e32 v0, 0x6400, v100
	ds_write2_b32 v0, v67, v71 offset0:68 offset1:84
	ds_write2_b32 v0, v68, v72 offset0:200 offset1:216
	v_add_u32_e32 v0, 0x6800, v100
	ds_write2_b32 v0, v69, v73 offset0:76 offset1:92
	v_lshlrev_b32_e32 v0, 3, v98
	s_waitcnt lgkmcnt(0)
	s_barrier
	v_and_b32_e32 v66, 0x78, v0
	v_or_b32_e32 v0, s15, v66
	v_cmp_gt_i32_e32 vcc, s58, v0
	s_and_saveexec_b64 s[24:25], vcc
	s_cbranch_execz .LBB0_466
	s_ashr_i32 s19, s18, 31
	s_lshl_b64 s[0:1], s[18:19], 1
	s_add_u32 s0, s10, s0
	s_addc_u32 s1, s11, s1
	v_lshlrev_b32_e32 v0, 1, v66
	v_lshl_add_u64 v[74:75], s[0:1], 0, v[0:1]
	v_ashrrev_i32_e32 v0, 4, v98
	v_mul_lo_u32 v67, v0, s92
	v_lshl_add_u32 v76, v66, 2, v67
	s_waitcnt vmcnt(0)
	ds_read_b128 v[66:69], v76
	ds_read_b128 v[70:73], v76 offset:16
	v_add_u32_e32 v0, s17, v0
	s_waitcnt lgkmcnt(1)
	v_cvt_pk_bf16_f32 v66, v66, v67
	v_cvt_pk_bf16_f32 v67, v68, v69
	s_waitcnt lgkmcnt(0)
	v_cvt_pk_bf16_f32 v68, v70, v71
	v_mad_i64_i32 v[70:71], s[0:1], v0, s60, v[74:75]
	v_cvt_pk_bf16_f32 v69, v72, v73
	global_store_dwordx4 v[70:71], v[66:69], off offset:256
	ds_read_b128 v[66:69], v76 offset:16896
	ds_read_b128 v[70:73], v76 offset:16912
	s_waitcnt lgkmcnt(1)
	v_cvt_pk_bf16_f32 v66, v66, v67
	v_cvt_pk_bf16_f32 v67, v68, v69
	s_waitcnt lgkmcnt(0)
	v_cvt_pk_bf16_f32 v68, v70, v71
	v_add_u32_e32 v70, 32, v0
	v_mad_i64_i32 v[70:71], s[0:1], v70, s60, v[74:75]
	v_cvt_pk_bf16_f32 v69, v72, v73
	global_store_dwordx4 v[70:71], v[66:69], off offset:256
	ds_read_b128 v[66:69], v76 offset:33792
	ds_read_b128 v[70:73], v76 offset:33808
	s_waitcnt lgkmcnt(1)
	v_cvt_pk_bf16_f32 v66, v66, v67
	v_cvt_pk_bf16_f32 v67, v68, v69
	s_waitcnt lgkmcnt(0)
	v_cvt_pk_bf16_f32 v68, v70, v71
	v_add_u32_e32 v70, 64, v0
	v_mad_i64_i32 v[70:71], s[0:1], v70, s60, v[74:75]
	v_cvt_pk_bf16_f32 v69, v72, v73
	global_store_dwordx4 v[70:71], v[66:69], off offset:256
	ds_read_b128 v[66:69], v76 offset:50688
	ds_read_b128 v[70:73], v76 offset:50704
	v_add_u32_e32 v0, 0x60, v0
	s_waitcnt lgkmcnt(1)
	v_cvt_pk_bf16_f32 v66, v66, v67
	v_cvt_pk_bf16_f32 v67, v68, v69
	s_waitcnt lgkmcnt(0)
	v_cvt_pk_bf16_f32 v68, v70, v71
	v_mad_i64_i32 v[70:71], s[0:1], v0, s60, v[74:75]
	v_cvt_pk_bf16_f32 v69, v72, v73
	global_store_dwordx4 v[70:71], v[66:69], off offset:256
; DI u32x4 pack8(const float* f) { u32x4 o; o.x = pack2(f[0], f[1]); o.y = pack2(f[2], f[3]); o.z = pack2(f[4], f[5]); o.w = pack2(f[6], f[7]); return o; }
; template <int AI, int BJ>
; DI void in_quadrant(PREF p, const f32x4 (&acc)[2][2][4][2], int mt, int nt, float* Cs) {
;     ...
;   if (col0 + 128 > OFF_SV && col0 < OFF_SV + 128) {
;     int b = row0 >> 12, s0 = row0 & 4095;
; #pragma unroll
;     for (int q = 0; q < 4; ++q) {
;       int item = t + 512 * q; int c = item & 127, rg = item >> 7;
;       int vc = col0 + c - OFF_SV;
;       if (vc >= 0 && vc < 128) {
;         float v[8];
; #pragma unroll
;         for (int j = 0; j < 8; ++j) v[j] = Cs[(rg * 8 + j) * CST + c];
;         *(u32x4*)(p.Vst + ((size_t)(b * 2 + (vc >> 6)) * 64 + (vc & 63)) * S_ + s0 + rg * 8) = pack8(v);
;       }
;     }
;   }
.LBB0_466:
	s_or_b64 exec, exec, s[24:25]
	s_cmp_lt_i32 s14, 9
	s_cselect_b64 s[0:1], -1, 0
	s_cmpk_gt_i32 s15, 0x99f
	s_cselect_b64 s[24:25], -1, 0
	s_or_b64 s[0:1], s[0:1], s[24:25]
	s_and_b64 vcc, exec, s[0:1]
	s_cbranch_vccnz .LBB0_470
	v_and_b32_e32 v68, 0x7f, v98
	v_or_b32_e32 v0, s15, v68
	v_add_u32_e32 v0, 0xfffff6e0, v0
	v_cmp_gt_u32_e32 vcc, s93, v0
	s_and_saveexec_b64 s[24:25], vcc
	s_cbranch_execz .LBB0_469
	v_lshrrev_b32_e32 v66, 6, v0
	s_ashr_i32 s0, s16, 3
	v_and_or_b32 v66, s0, -2, v66
	v_ashrrev_i32_e32 v67, 31, v66
	v_lshlrev_b64 v[66:67], 19, v[66:67]
	v_lshlrev_b32_e32 v0, 13, v0
	v_lshl_add_u64 v[66:67], s[12:13], 0, v[66:67]
	v_and_b32_e32 v0, 0x7e000, v0
	v_lshl_add_u64 v[66:67], v[66:67], 0, v[0:1]
	v_lshlrev_b32_e32 v0, 2, v68
	v_ashrrev_i32_e32 v68, 4, v98
	s_and_b32 s0, s17, 0xf00
	v_and_b32_e32 v72, -8, v68
	s_lshl_b32 s52, s0, 1
	v_mad_u64_u32 v[74:75], s[0:1], v72, s92, v[0:1]
	v_or_b32_e32 v68, 7, v68
	v_mad_u64_u32 v[76:77], s[0:1], v68, s92, v[0:1]
	ds_read2_b32 v[68:69], v74 offset1:132
	s_waitcnt lgkmcnt(0)
	v_cvt_pk_bf16_f32 v68, v68, v69
	v_add_u32_e32 v69, 0x400, v74
	ds_read2_b32 v[70:71], v69 offset0:8 offset1:140
	s_waitcnt lgkmcnt(0)
	v_cvt_pk_bf16_f32 v69, v70, v71
	v_add_u32_e32 v70, 0x800, v74
	ds_read2_b32 v[70:71], v70 offset0:16 offset1:148
	s_waitcnt lgkmcnt(0)
	v_cvt_pk_bf16_f32 v70, v70, v71
	ds_read_b32 v71, v74 offset:3168
	ds_read_b32 v73, v76
	v_lshl_add_u64 v[66:67], v[66:67], 0, s[52:53]
	s_waitcnt lgkmcnt(0)
	v_cvt_pk_bf16_f32 v71, v71, v73
	v_ashrrev_i32_e32 v73, 31, v72
	v_lshl_add_u64 v[72:73], v[72:73], 1, v[66:67]
	global_store_dwordx4 v[72:73], v[68:71], off
	s_nop 1
	v_add_u32_e32 v68, 0x200, v98
	v_ashrrev_i32_e32 v68, 4, v68
	v_and_b32_e32 v72, -8, v68
	v_mad_u64_u32 v[74:75], s[0:1], v72, s92, v[0:1]
	v_or_b32_e32 v68, 7, v68
	v_mad_u64_u32 v[76:77], s[0:1], v68, s92, v[0:1]
	ds_read2_b32 v[68:69], v74 offset1:132
	s_waitcnt lgkmcnt(0)
	v_cvt_pk_bf16_f32 v68, v68, v69
	v_add_u32_e32 v69, 0x400, v74
	ds_read2_b32 v[70:71], v69 offset0:8 offset1:140
	s_waitcnt lgkmcnt(0)
	v_cvt_pk_bf16_f32 v69, v70, v71
	v_add_u32_e32 v70, 0x800, v74
	ds_read2_b32 v[70:71], v70 offset0:16 offset1:148
	s_waitcnt lgkmcnt(0)
	v_cvt_pk_bf16_f32 v70, v70, v71
	ds_read_b32 v71, v74 offset:3168
	ds_read_b32 v73, v76
	s_waitcnt lgkmcnt(0)
	v_cvt_pk_bf16_f32 v71, v71, v73
	v_ashrrev_i32_e32 v73, 31, v72
	v_lshl_add_u64 v[72:73], v[72:73], 1, v[66:67]
	global_store_dwordx4 v[72:73], v[68:71], off
	s_nop 1
	v_add_u32_e32 v68, 0x400, v98
	v_ashrrev_i32_e32 v68, 4, v68
	v_and_b32_e32 v72, -8, v68
	v_mad_u64_u32 v[74:75], s[0:1], v72, s92, v[0:1]
	v_or_b32_e32 v68, 7, v68
	v_mad_u64_u32 v[76:77], s[0:1], v68, s92, v[0:1]
	ds_read2_b32 v[68:69], v74 offset1:132
	s_waitcnt lgkmcnt(0)
	v_cvt_pk_bf16_f32 v68, v68, v69
	v_add_u32_e32 v69, 0x400, v74
	ds_read2_b32 v[70:71], v69 offset0:8 offset1:140
	s_waitcnt lgkmcnt(0)
	v_cvt_pk_bf16_f32 v69, v70, v71
	v_add_u32_e32 v70, 0x800, v74
	ds_read2_b32 v[70:71], v70 offset0:16 offset1:148
	s_waitcnt lgkmcnt(0)
	v_cvt_pk_bf16_f32 v70, v70, v71
	ds_read_b32 v71, v74 offset:3168
	ds_read_b32 v73, v76
	s_waitcnt lgkmcnt(0)
	v_cvt_pk_bf16_f32 v71, v71, v73
	v_ashrrev_i32_e32 v73, 31, v72
	v_lshl_add_u64 v[72:73], v[72:73], 1, v[66:67]
	global_store_dwordx4 v[72:73], v[68:71], off
	s_nop 1
	v_add_u32_e32 v68, 0x600, v98
	v_ashrrev_i32_e32 v68, 4, v68
	v_and_b32_e32 v72, -8, v68
	v_mad_u64_u32 v[74:75], s[0:1], v72, s92, v[0:1]
	v_or_b32_e32 v68, 7, v68
	v_mad_u64_u32 v[76:77], s[0:1], v68, s92, v[0:1]
	v_add_u32_e32 v0, 0x400, v74
	ds_read2_b32 v[68:69], v74 offset1:132
	ds_read2_b32 v[70:71], v0 offset0:8 offset1:140
	v_add_u32_e32 v0, 0x800, v74
	s_waitcnt lgkmcnt(0)
	v_cvt_pk_bf16_f32 v68, v68, v69
	v_cvt_pk_bf16_f32 v69, v70, v71
	ds_read2_b32 v[70:71], v0 offset0:16 offset1:148
	s_waitcnt lgkmcnt(0)
	v_cvt_pk_bf16_f32 v70, v70, v71
	ds_read_b32 v0, v74 offset:3168
	ds_read_b32 v71, v76
	v_ashrrev_i32_e32 v73, 31, v72
	v_lshl_add_u64 v[66:67], v[72:73], 1, v[66:67]
	s_waitcnt lgkmcnt(0)
	v_cvt_pk_bf16_f32 v71, v0, v71
	global_store_dwordx4 v[66:67], v[68:71], off

; DI u32x4 pack8(const float* f) { u32x4 o; o.x = pack2(f[0], f[1]); o.y = pack2(f[2], f[3]); o.z = pack2(f[4], f[5]); o.w = pack2(f[6], f[7]); return o; }
; DI void lds_barrier() { asm volatile("s_waitcnt lgkmcnt(0)\n\ts_barrier" ::: "memory"); }
; DI int tid512() { int t = threadIdx.x; asm volatile("" : "+v"(t)); return t; }
; template <int AI, int BJ>
; DI void stage_q(const f32x4 (&acc)[2][2][4][2], float* Cs) {
;   const int t = tid512(), wid = t >> 6, lane = t & 63, wr = wid >> 2, wc = wid & 3, fr = lane & 15, fq = lane >> 4;
;   lds_barrier();
; #pragma unroll
;   for (int m = 0; m < 4; ++m)
; #pragma unroll
;     for (int n = 0; n < 2; ++n)
; #pragma unroll
;       for (int j = 0; j < 4; ++j) Cs[(wr * 64 + m * 16 + fq * 4 + j) * CST + wc * 32 + n * 16 + fr] = acc[AI][BJ][m][n][j];
;   lds_barrier();
; }
; template <int AI, int BJ>
; DI void in_quadrant(PREF p, const f32x4 (&acc)[2][2][4][2], int mt, int nt, float* Cs) {
;   const int t = tid512();
;   const int row0 = mt * 256 + AI * 128, col0 = nt * 256 + BJ * 128;
;   if (col0 >= HW) return;
;   stage_q<AI, BJ>(acc, Cs);
; #pragma unroll
;   for (int q = 0; q < 4; ++q) {
;     int r = (t >> 4) + 32 * q, c = (t & 15) * 8;
;     if (col0 + c < HW) {
;       float v[8]; ld8(Cs + r * CST + c, v);
;       *(u32x4*)(p.hb + (size_t)(row0 + r) * HW + col0 + c) = pack8(v);
;     }
;   }
.LBB0_470:
	v_mov_b32_e32 v66, v168
	s_andn2_b64 vcc, exec, s[20:21]
	s_bitset1_b32 s17, 7
	s_cbranch_vccnz .LBB0_477
	v_mov_b32_e32 v0, v168
	s_waitcnt lgkmcnt(0)
	s_barrier
	s_nop 0
	v_and_b32_e32 v67, 15, v0
	v_lshrrev_b32_e32 v68, 2, v0
	v_lshlrev_b32_e32 v0, 1, v0
	v_lshlrev_b32_e32 v67, 2, v67
	v_and_b32_e32 v68, 0xfffffcc, v68
	v_and_or_b32 v0, v0, s89, v67
	v_mad_u64_u32 v[68:69], s[0:1], v68, s92, v[0:1]
	v_add_u32_e32 v0, 0x400, v68
	ds_write2_b32 v68, v54, v62 offset1:16
	ds_write2_b32 v68, v55, v63 offset0:132 offset1:148
	ds_write2_b32 v0, v56, v64 offset0:8 offset1:24
	ds_write2_b32 v0, v57, v65 offset0:140 offset1:156
	v_add_u32_e32 v0, 0x2000, v68
	ds_write2_b32 v0, v50, v58 offset0:64 offset1:80
	ds_write2_b32 v0, v51, v59 offset0:196 offset1:212
	v_add_u32_e32 v0, 0x2400, v68
	ds_write2_b32 v0, v52, v60 offset0:72 offset1:88
	ds_write2_b32 v0, v53, v61 offset0:204 offset1:220
	v_add_u32_e32 v0, 0x4000, v68
	ds_write2_b32 v0, v42, v46 offset0:128 offset1:144
	v_add_u32_e32 v0, 0x4400, v68
	ds_write2_b32 v0, v43, v47 offset0:4 offset1:20
	ds_write2_b32 v0, v44, v48 offset0:136 offset1:152
	v_add_u32_e32 v0, 0x4800, v68
	ds_write2_b32 v0, v45, v49 offset0:12 offset1:28
	v_add_u32_e32 v0, 0x6000, v68
	ds_write2_b32 v0, v34, v38 offset0:192 offset1:208
	v_add_u32_e32 v0, 0x6400, v68
	ds_write2_b32 v0, v35, v39 offset0:68 offset1:84
	ds_write2_b32 v0, v36, v40 offset0:200 offset1:216
	v_add_u32_e32 v0, 0x6800, v68
	ds_write2_b32 v0, v37, v41 offset0:76 offset1:92
	v_lshlrev_b32_e32 v0, 3, v66
	s_waitcnt lgkmcnt(0)
	s_barrier
	v_and_b32_e32 v34, 0x78, v0
	v_or_b32_e32 v0, s18, v34
	v_cmp_gt_i32_e32 vcc, s58, v0
	s_and_saveexec_b64 s[20:21], vcc
	s_cbranch_execz .LBB0_473
	s_ashr_i32 s19, s18, 31
	s_lshl_b64 s[0:1], s[18:19], 1
	s_add_u32 s0, s10, s0
	s_addc_u32 s1, s11, s1
	v_lshlrev_b32_e32 v0, 1, v34
	v_lshl_add_u64 v[42:43], s[0:1], 0, v[0:1]
	v_ashrrev_i32_e32 v0, 4, v66
	v_mul_lo_u32 v35, v0, s92
	v_lshl_add_u32 v44, v34, 2, v35
	s_waitcnt vmcnt(0)
	ds_read_b128 v[34:37], v44
	ds_read_b128 v[38:41], v44 offset:16
	v_add_u32_e32 v0, s17, v0
	s_waitcnt lgkmcnt(1)
	v_cvt_pk_bf16_f32 v34, v34, v35
	v_cvt_pk_bf16_f32 v35, v36, v37
	s_waitcnt lgkmcnt(0)
	v_cvt_pk_bf16_f32 v36, v38, v39
	v_mad_i64_i32 v[38:39], s[0:1], v0, s60, v[42:43]
	v_cvt_pk_bf16_f32 v37, v40, v41
	global_store_dwordx4 v[38:39], v[34:37], off
	ds_read_b128 v[34:37], v44 offset:16896
	ds_read_b128 v[38:41], v44 offset:16912
	s_waitcnt lgkmcnt(1)
	v_cvt_pk_bf16_f32 v34, v34, v35
	v_cvt_pk_bf16_f32 v35, v36, v37
	s_waitcnt lgkmcnt(0)
	v_cvt_pk_bf16_f32 v36, v38, v39
	v_add_u32_e32 v38, 32, v0
	v_mad_i64_i32 v[38:39], s[0:1], v38, s60, v[42:43]
	v_cvt_pk_bf16_f32 v37, v40, v41
	global_store_dwordx4 v[38:39], v[34:37], off
	ds_read_b128 v[34:37], v44 offset:33792
	ds_read_b128 v[38:41], v44 offset:33808
	s_waitcnt lgkmcnt(1)
	v_cvt_pk_bf16_f32 v34, v34, v35
	v_cvt_pk_bf16_f32 v35, v36, v37
	s_waitcnt lgkmcnt(0)
	v_cvt_pk_bf16_f32 v36, v38, v39
	v_add_u32_e32 v38, 64, v0
	v_mad_i64_i32 v[38:39], s[0:1], v38, s60, v[42:43]
	v_cvt_pk_bf16_f32 v37, v40, v41
	global_store_dwordx4 v[38:39], v[34:37], off
	ds_read_b128 v[34:37], v44 offset:50688
	ds_read_b128 v[38:41], v44 offset:50704
	v_add_u32_e32 v0, 0x60, v0
	s_waitcnt lgkmcnt(1)
	v_cvt_pk_bf16_f32 v34, v34, v35
	v_cvt_pk_bf16_f32 v35, v36, v37
	s_waitcnt lgkmcnt(0)
	v_cvt_pk_bf16_f32 v36, v38, v39
	v_mad_i64_i32 v[38:39], s[0:1], v0, s60, v[42:43]
	v_cvt_pk_bf16_f32 v37, v40, v41
	global_store_dwordx4 v[38:39], v[34:37], off
; DI u32x4 pack8(const float* f) { u32x4 o; o.x = pack2(f[0], f[1]); o.y = pack2(f[2], f[3]); o.z = pack2(f[4], f[5]); o.w = pack2(f[6], f[7]); return o; }
; template <int AI, int BJ>
; DI void in_quadrant(PREF p, const f32x4 (&acc)[2][2][4][2], int mt, int nt, float* Cs) {
;     ...
;   if (col0 + 128 > OFF_SV && col0 < OFF_SV + 128) {
;     int b = row0 >> 12, s0 = row0 & 4095;
; #pragma unroll
;     for (int q = 0; q < 4; ++q) {
;       int item = t + 512 * q; int c = item & 127, rg = item >> 7;
;       int vc = col0 + c - OFF_SV;
;       if (vc >= 0 && vc < 128) {
;         float v[8];
; #pragma unroll
;         for (int j = 0; j < 8; ++j) v[j] = Cs[(rg * 8 + j) * CST + c];
;         *(u32x4*)(p.Vst + ((size_t)(b * 2 + (vc >> 6)) * 64 + (vc & 63)) * S_ + s0 + rg * 8) = pack8(v);
;       }
;     }
;   }
.LBB0_473:
	s_or_b64 exec, exec, s[20:21]
	s_cmp_lt_i32 s14, 9
	s_cselect_b64 s[0:1], -1, 0
	s_cmp_eq_u32 s14, 10
	s_cselect_b64 s[20:21], -1, 0
	s_or_b64 s[0:1], s[0:1], s[20:21]
	s_and_b64 vcc, exec, s[0:1]
	s_cbranch_vccnz .LBB0_477
	v_and_b32_e32 v36, 0x7f, v66
	v_or_b32_e32 v0, s18, v36
	v_add_u32_e32 v0, 0xfffff6e0, v0
	v_cmp_gt_u32_e32 vcc, s93, v0
	s_and_saveexec_b64 s[20:21], vcc
	s_cbranch_execz .LBB0_476
	v_lshrrev_b32_e32 v34, 6, v0
	s_ashr_i32 s0, s16, 3
	v_and_or_b32 v34, s0, -2, v34
	v_ashrrev_i32_e32 v35, 31, v34
	v_lshlrev_b64 v[34:35], 19, v[34:35]
	v_lshlrev_b32_e32 v0, 13, v0
	v_lshl_add_u64 v[34:35], s[12:13], 0, v[34:35]
	v_and_b32_e32 v0, 0x7e000, v0
	v_lshl_add_u64 v[34:35], v[34:35], 0, v[0:1]
	v_lshlrev_b32_e32 v0, 2, v36
	v_ashrrev_i32_e32 v36, 4, v66
	s_and_b32 s0, s17, 0xf80
	v_and_b32_e32 v40, -8, v36
	s_lshl_b32 s52, s0, 1
	v_mad_u64_u32 v[42:43], s[0:1], v40, s92, v[0:1]
	v_or_b32_e32 v36, 7, v36
	v_mad_u64_u32 v[44:45], s[0:1], v36, s92, v[0:1]
	ds_read2_b32 v[36:37], v42 offset1:132
	s_waitcnt lgkmcnt(0)
	v_cvt_pk_bf16_f32 v36, v36, v37
	v_add_u32_e32 v37, 0x400, v42
	ds_read2_b32 v[38:39], v37 offset0:8 offset1:140
	s_waitcnt lgkmcnt(0)
	v_cvt_pk_bf16_f32 v37, v38, v39
	v_add_u32_e32 v38, 0x800, v42
	ds_read2_b32 v[38:39], v38 offset0:16 offset1:148
	s_waitcnt lgkmcnt(0)
	v_cvt_pk_bf16_f32 v38, v38, v39
	ds_read_b32 v39, v42 offset:3168
	ds_read_b32 v41, v44
	v_lshl_add_u64 v[34:35], v[34:35], 0, s[52:53]
	s_waitcnt lgkmcnt(0)
	v_cvt_pk_bf16_f32 v39, v39, v41
	v_ashrrev_i32_e32 v41, 31, v40
	v_lshl_add_u64 v[40:41], v[40:41], 1, v[34:35]
	global_store_dwordx4 v[40:41], v[36:39], off
	s_nop 1
	v_add_u32_e32 v36, 0x200, v66
	v_ashrrev_i32_e32 v36, 4, v36
	v_and_b32_e32 v40, -8, v36
	v_mad_u64_u32 v[42:43], s[0:1], v40, s92, v[0:1]
	v_or_b32_e32 v36, 7, v36
	v_mad_u64_u32 v[44:45], s[0:1], v36, s92, v[0:1]
	ds_read2_b32 v[36:37], v42 offset1:132
	s_waitcnt lgkmcnt(0)
	v_cvt_pk_bf16_f32 v36, v36, v37
	v_add_u32_e32 v37, 0x400, v42
	ds_read2_b32 v[38:39], v37 offset0:8 offset1:140
	s_waitcnt lgkmcnt(0)
	v_cvt_pk_bf16_f32 v37, v38, v39
	v_add_u32_e32 v38, 0x800, v42
	ds_read2_b32 v[38:39], v38 offset0:16 offset1:148
	s_waitcnt lgkmcnt(0)
	v_cvt_pk_bf16_f32 v38, v38, v39
	ds_read_b32 v39, v42 offset:3168
	ds_read_b32 v41, v44
	s_waitcnt lgkmcnt(0)
	v_cvt_pk_bf16_f32 v39, v39, v41
	v_ashrrev_i32_e32 v41, 31, v40
	v_lshl_add_u64 v[40:41], v[40:41], 1, v[34:35]
	global_store_dwordx4 v[40:41], v[36:39], off
	s_nop 1
	v_add_u32_e32 v36, 0x400, v66
	v_ashrrev_i32_e32 v36, 4, v36
	v_and_b32_e32 v40, -8, v36
	v_mad_u64_u32 v[42:43], s[0:1], v40, s92, v[0:1]
	v_or_b32_e32 v36, 7, v36
	v_mad_u64_u32 v[44:45], s[0:1], v36, s92, v[0:1]
	ds_read2_b32 v[36:37], v42 offset1:132
	s_waitcnt lgkmcnt(0)
	v_cvt_pk_bf16_f32 v36, v36, v37
	v_add_u32_e32 v37, 0x400, v42
	ds_read2_b32 v[38:39], v37 offset0:8 offset1:140
	s_waitcnt lgkmcnt(0)
	v_cvt_pk_bf16_f32 v37, v38, v39
	v_add_u32_e32 v38, 0x800, v42
	ds_read2_b32 v[38:39], v38 offset0:16 offset1:148
	s_waitcnt lgkmcnt(0)
	v_cvt_pk_bf16_f32 v38, v38, v39
	ds_read_b32 v39, v42 offset:3168
	ds_read_b32 v41, v44
	s_waitcnt lgkmcnt(0)
	v_cvt_pk_bf16_f32 v39, v39, v41
	v_ashrrev_i32_e32 v41, 31, v40
	v_lshl_add_u64 v[40:41], v[40:41], 1, v[34:35]
	global_store_dwordx4 v[40:41], v[36:39], off
	s_nop 1
	v_add_u32_e32 v36, 0x600, v66
	v_ashrrev_i32_e32 v36, 4, v36
	v_and_b32_e32 v40, -8, v36
	v_mad_u64_u32 v[42:43], s[0:1], v40, s92, v[0:1]
	v_or_b32_e32 v36, 7, v36
	v_mad_u64_u32 v[44:45], s[0:1], v36, s92, v[0:1]
	v_add_u32_e32 v0, 0x400, v42
	ds_read2_b32 v[36:37], v42 offset1:132
	ds_read2_b32 v[38:39], v0 offset0:8 offset1:140
	v_add_u32_e32 v0, 0x800, v42
	s_waitcnt lgkmcnt(0)
	v_cvt_pk_bf16_f32 v36, v36, v37
	v_cvt_pk_bf16_f32 v37, v38, v39
	ds_read2_b32 v[38:39], v0 offset0:16 offset1:148
	s_waitcnt lgkmcnt(0)
	v_cvt_pk_bf16_f32 v38, v38, v39
	ds_read_b32 v0, v42 offset:3168
	ds_read_b32 v39, v44
	v_ashrrev_i32_e32 v41, 31, v40
	v_lshl_add_u64 v[34:35], v[40:41], 1, v[34:35]
	s_waitcnt lgkmcnt(0)
	v_cvt_pk_bf16_f32 v39, v0, v39
	global_store_dwordx4 v[34:35], v[36:39], off

; DI u32x4 pack8(const float* f) { u32x4 o; o.x = pack2(f[0], f[1]); o.y = pack2(f[2], f[3]); o.z = pack2(f[4], f[5]); o.w = pack2(f[6], f[7]); return o; }
; DI void lds_barrier() { asm volatile("s_waitcnt lgkmcnt(0)\n\ts_barrier" ::: "memory"); }
; DI int tid512() { int t = threadIdx.x; asm volatile("" : "+v"(t)); return t; }
; template <int AI, int BJ>
; DI void stage_q(const f32x4 (&acc)[2][2][4][2], float* Cs) {
;   const int t = tid512(), wid = t >> 6, lane = t & 63, wr = wid >> 2, wc = wid & 3, fr = lane & 15, fq = lane >> 4;
;   lds_barrier();
; #pragma unroll
;   for (int m = 0; m < 4; ++m)
; #pragma unroll
;     for (int n = 0; n < 2; ++n)
; #pragma unroll
;       for (int j = 0; j < 4; ++j) Cs[(wr * 64 + m * 16 + fq * 4 + j) * CST + wc * 32 + n * 16 + fr] = acc[AI][BJ][m][n][j];
;   lds_barrier();
; }
; template <int AI, int BJ>
; DI void in_quadrant(PREF p, const f32x4 (&acc)[2][2][4][2], int mt, int nt, float* Cs) {
;   const int t = tid512();
;   const int row0 = mt * 256 + AI * 128, col0 = nt * 256 + BJ * 128;
;   if (col0 >= HW) return;
;   stage_q<AI, BJ>(acc, Cs);
; #pragma unroll
;   for (int q = 0; q < 4; ++q) {
;     int r = (t >> 4) + 32 * q, c = (t & 15) * 8;
;     if (col0 + c < HW) {
;       float v[8]; ld8(Cs + r * CST + c, v);
;       *(u32x4*)(p.hb + (size_t)(row0 + r) * HW + col0 + c) = pack8(v);
;     }
;   }
.LBB0_477:
	v_mov_b32_e32 v34, v168
	s_andn2_b64 vcc, exec, s[22:23]
	s_cbranch_vccnz .LBB0_445
	v_mov_b32_e32 v0, v168
	s_waitcnt lgkmcnt(0)
	s_barrier
	s_nop 0
	v_and_b32_e32 v35, 15, v0
	v_lshrrev_b32_e32 v36, 2, v0
	v_lshlrev_b32_e32 v0, 1, v0
	v_lshlrev_b32_e32 v35, 2, v35
	v_and_b32_e32 v36, 0xfffffcc, v36
	v_and_or_b32 v0, v0, s89, v35
	v_mad_u64_u32 v[36:37], s[0:1], v36, s92, v[0:1]
	v_add_u32_e32 v0, 0x400, v36
	ds_write2_b32 v36, v22, v30 offset1:16
	ds_write2_b32 v36, v23, v31 offset0:132 offset1:148
	ds_write2_b32 v0, v24, v32 offset0:8 offset1:24
	ds_write2_b32 v0, v25, v33 offset0:140 offset1:156
	v_add_u32_e32 v0, 0x2000, v36
	ds_write2_b32 v0, v18, v26 offset0:64 offset1:80
	ds_write2_b32 v0, v19, v27 offset0:196 offset1:212
	v_add_u32_e32 v0, 0x2400, v36
	ds_write2_b32 v0, v20, v28 offset0:72 offset1:88
	ds_write2_b32 v0, v21, v29 offset0:204 offset1:220
	v_add_u32_e32 v0, 0x4000, v36
	ds_write2_b32 v0, v10, v14 offset0:128 offset1:144
	v_add_u32_e32 v0, 0x4400, v36
	ds_write2_b32 v0, v11, v15 offset0:4 offset1:20
	ds_write2_b32 v0, v12, v16 offset0:136 offset1:152
	v_add_u32_e32 v0, 0x4800, v36
	ds_write2_b32 v0, v13, v17 offset0:12 offset1:28
	v_add_u32_e32 v0, 0x6000, v36
	ds_write2_b32 v0, v2, v6 offset0:192 offset1:208
	v_add_u32_e32 v0, 0x6400, v36
	ds_write2_b32 v0, v3, v7 offset0:68 offset1:84
	ds_write2_b32 v0, v4, v8 offset0:200 offset1:216
	v_add_u32_e32 v0, 0x6800, v36
	ds_write2_b32 v0, v5, v9 offset0:76 offset1:92
	v_lshlrev_b32_e32 v0, 3, v34
	s_waitcnt lgkmcnt(0)
	s_barrier
	v_and_b32_e32 v2, 0x78, v0
	v_or_b32_e32 v0, s15, v2
	v_cmp_gt_i32_e32 vcc, s58, v0
	s_and_saveexec_b64 s[20:21], vcc
	s_cbranch_execz .LBB0_480
	s_ashr_i32 s19, s18, 31
	s_lshl_b64 s[0:1], s[18:19], 1
	s_add_u32 s0, s10, s0
	s_addc_u32 s1, s11, s1
	v_lshlrev_b32_e32 v0, 1, v2
	v_lshl_add_u64 v[10:11], s[0:1], 0, v[0:1]
	v_ashrrev_i32_e32 v0, 4, v34
	v_mul_lo_u32 v3, v0, s92
	v_lshl_add_u32 v12, v2, 2, v3
	s_waitcnt vmcnt(0)
	ds_read_b128 v[2:5], v12
	ds_read_b128 v[6:9], v12 offset:16
	v_add_u32_e32 v0, s17, v0
	s_waitcnt lgkmcnt(1)
	v_cvt_pk_bf16_f32 v2, v2, v3
	v_cvt_pk_bf16_f32 v3, v4, v5
	s_waitcnt lgkmcnt(0)
	v_cvt_pk_bf16_f32 v4, v6, v7
	v_mad_i64_i32 v[6:7], s[0:1], v0, s60, v[10:11]
	v_cvt_pk_bf16_f32 v5, v8, v9
	global_store_dwordx4 v[6:7], v[2:5], off offset:256
	ds_read_b128 v[2:5], v12 offset:16896
	ds_read_b128 v[6:9], v12 offset:16912
	s_waitcnt lgkmcnt(1)
	v_cvt_pk_bf16_f32 v2, v2, v3
	v_cvt_pk_bf16_f32 v3, v4, v5
	s_waitcnt lgkmcnt(0)
	v_cvt_pk_bf16_f32 v4, v6, v7
	v_add_u32_e32 v6, 32, v0
	v_mad_i64_i32 v[6:7], s[0:1], v6, s60, v[10:11]
	v_cvt_pk_bf16_f32 v5, v8, v9
	global_store_dwordx4 v[6:7], v[2:5], off offset:256
	ds_read_b128 v[2:5], v12 offset:33792
	ds_read_b128 v[6:9], v12 offset:33808
	s_waitcnt lgkmcnt(1)
	v_cvt_pk_bf16_f32 v2, v2, v3
	v_cvt_pk_bf16_f32 v3, v4, v5
	s_waitcnt lgkmcnt(0)
	v_cvt_pk_bf16_f32 v4, v6, v7
	v_add_u32_e32 v6, 64, v0
	v_mad_i64_i32 v[6:7], s[0:1], v6, s60, v[10:11]
	v_cvt_pk_bf16_f32 v5, v8, v9
	global_store_dwordx4 v[6:7], v[2:5], off offset:256
	ds_read_b128 v[2:5], v12 offset:50688
	ds_read_b128 v[6:9], v12 offset:50704
	v_add_u32_e32 v0, 0x60, v0
	s_waitcnt lgkmcnt(1)
	v_cvt_pk_bf16_f32 v2, v2, v3
	v_cvt_pk_bf16_f32 v3, v4, v5
	s_waitcnt lgkmcnt(0)
	v_cvt_pk_bf16_f32 v4, v6, v7
	v_mad_i64_i32 v[6:7], s[0:1], v0, s60, v[10:11]
	v_cvt_pk_bf16_f32 v5, v8, v9
	global_store_dwordx4 v[6:7], v[2:5], off offset:256
; DI u32x4 pack8(const float* f) { u32x4 o; o.x = pack2(f[0], f[1]); o.y = pack2(f[2], f[3]); o.z = pack2(f[4], f[5]); o.w = pack2(f[6], f[7]); return o; }
; template <int AI, int BJ>
; DI void in_quadrant(PREF p, const f32x4 (&acc)[2][2][4][2], int mt, int nt, float* Cs) {
;     ...
;   if (col0 + 128 > OFF_SV && col0 < OFF_SV + 128) {
;     int b = row0 >> 12, s0 = row0 & 4095;
; #pragma unroll
;     for (int q = 0; q < 4; ++q) {
;       int item = t + 512 * q; int c = item & 127, rg = item >> 7;
;       int vc = col0 + c - OFF_SV;
;       if (vc >= 0 && vc < 128) {
;         float v[8];
; #pragma unroll
;         for (int j = 0; j < 8; ++j) v[j] = Cs[(rg * 8 + j) * CST + c];
;         *(u32x4*)(p.Vst + ((size_t)(b * 2 + (vc >> 6)) * 64 + (vc & 63)) * S_ + s0 + rg * 8) = pack8(v);
;       }
;     }
;   }
.LBB0_480:
	s_or_b64 exec, exec, s[20:21]
	s_cmp_lt_i32 s14, 9
	s_cselect_b64 s[0:1], -1, 0
	s_cmpk_gt_i32 s15, 0x99f
	s_cselect_b64 s[18:19], -1, 0
	s_or_b64 s[0:1], s[0:1], s[18:19]
	s_and_b64 vcc, exec, s[0:1]
	s_cbranch_vccnz .LBB0_445
	v_and_b32_e32 v4, 0x7f, v34
	v_or_b32_e32 v0, s15, v4
	v_add_u32_e32 v0, 0xfffff6e0, v0
	v_cmp_gt_u32_e32 vcc, s93, v0
	s_and_saveexec_b64 s[18:19], vcc
	s_cbranch_execz .LBB0_444
	v_lshrrev_b32_e32 v2, 6, v0
	s_ashr_i32 s0, s16, 3
	v_and_or_b32 v2, s0, -2, v2
	v_ashrrev_i32_e32 v3, 31, v2
	v_lshlrev_b64 v[2:3], 19, v[2:3]
	v_lshlrev_b32_e32 v0, 13, v0
	v_lshl_add_u64 v[2:3], s[12:13], 0, v[2:3]
	v_and_b32_e32 v0, 0x7e000, v0
	v_lshl_add_u64 v[2:3], v[2:3], 0, v[0:1]
	v_lshlrev_b32_e32 v0, 2, v4
	v_ashrrev_i32_e32 v4, 4, v34
	s_and_b32 s0, s17, 0xf80
	v_and_b32_e32 v8, -8, v4
	s_lshl_b32 s52, s0, 1
	v_mad_u64_u32 v[10:11], s[0:1], v8, s92, v[0:1]
	v_or_b32_e32 v4, 7, v4
	v_mad_u64_u32 v[12:13], s[0:1], v4, s92, v[0:1]
	ds_read2_b32 v[4:5], v10 offset1:132
	s_waitcnt lgkmcnt(0)
	v_cvt_pk_bf16_f32 v4, v4, v5
	v_add_u32_e32 v5, 0x400, v10
	ds_read2_b32 v[6:7], v5 offset0:8 offset1:140
	s_waitcnt lgkmcnt(0)
	v_cvt_pk_bf16_f32 v5, v6, v7
	v_add_u32_e32 v6, 0x800, v10
	ds_read2_b32 v[6:7], v6 offset0:16 offset1:148
	s_waitcnt lgkmcnt(0)
	v_cvt_pk_bf16_f32 v6, v6, v7
	ds_read_b32 v7, v10 offset:3168
	ds_read_b32 v9, v12
	v_lshl_add_u64 v[2:3], v[2:3], 0, s[52:53]
	s_waitcnt lgkmcnt(0)
	v_cvt_pk_bf16_f32 v7, v7, v9
	v_ashrrev_i32_e32 v9, 31, v8
	v_lshl_add_u64 v[8:9], v[8:9], 1, v[2:3]
	global_store_dwordx4 v[8:9], v[4:7], off
	s_nop 1
	v_add_u32_e32 v4, 0x200, v34
	v_ashrrev_i32_e32 v4, 4, v4
	v_and_b32_e32 v8, -8, v4
	v_mad_u64_u32 v[10:11], s[0:1], v8, s92, v[0:1]
	v_or_b32_e32 v4, 7, v4
	v_mad_u64_u32 v[12:13], s[0:1], v4, s92, v[0:1]
	ds_read2_b32 v[4:5], v10 offset1:132
	s_waitcnt lgkmcnt(0)
	v_cvt_pk_bf16_f32 v4, v4, v5
	v_add_u32_e32 v5, 0x400, v10
	ds_read2_b32 v[6:7], v5 offset0:8 offset1:140
	s_waitcnt lgkmcnt(0)
	v_cvt_pk_bf16_f32 v5, v6, v7
	v_add_u32_e32 v6, 0x800, v10
	ds_read2_b32 v[6:7], v6 offset0:16 offset1:148
	s_waitcnt lgkmcnt(0)
	v_cvt_pk_bf16_f32 v6, v6, v7
	ds_read_b32 v7, v10 offset:3168
	ds_read_b32 v9, v12
	s_waitcnt lgkmcnt(0)
	v_cvt_pk_bf16_f32 v7, v7, v9
	v_ashrrev_i32_e32 v9, 31, v8
	v_lshl_add_u64 v[8:9], v[8:9], 1, v[2:3]
	global_store_dwordx4 v[8:9], v[4:7], off
	s_nop 1
	v_add_u32_e32 v4, 0x400, v34
	v_ashrrev_i32_e32 v4, 4, v4
	v_and_b32_e32 v8, -8, v4
	v_mad_u64_u32 v[10:11], s[0:1], v8, s92, v[0:1]
	v_or_b32_e32 v4, 7, v4
	v_mad_u64_u32 v[12:13], s[0:1], v4, s92, v[0:1]
	ds_read2_b32 v[4:5], v10 offset1:132
	s_waitcnt lgkmcnt(0)
	v_cvt_pk_bf16_f32 v4, v4, v5
	v_add_u32_e32 v5, 0x400, v10
	ds_read2_b32 v[6:7], v5 offset0:8 offset1:140
	s_waitcnt lgkmcnt(0)
	v_cvt_pk_bf16_f32 v5, v6, v7
	v_add_u32_e32 v6, 0x800, v10
	ds_read2_b32 v[6:7], v6 offset0:16 offset1:148
	s_waitcnt lgkmcnt(0)
	v_cvt_pk_bf16_f32 v6, v6, v7
	ds_read_b32 v7, v10 offset:3168
	ds_read_b32 v9, v12
	s_waitcnt lgkmcnt(0)
	v_cvt_pk_bf16_f32 v7, v7, v9
	v_ashrrev_i32_e32 v9, 31, v8
	v_lshl_add_u64 v[8:9], v[8:9], 1, v[2:3]
	global_store_dwordx4 v[8:9], v[4:7], off
	s_nop 1
	v_add_u32_e32 v4, 0x600, v34
	v_ashrrev_i32_e32 v4, 4, v4
	v_and_b32_e32 v8, -8, v4
	v_mad_u64_u32 v[10:11], s[0:1], v8, s92, v[0:1]
	v_or_b32_e32 v4, 7, v4
	v_mad_u64_u32 v[12:13], s[0:1], v4, s92, v[0:1]
	v_add_u32_e32 v0, 0x400, v10
	ds_read2_b32 v[4:5], v10 offset1:132
	ds_read2_b32 v[6:7], v0 offset0:8 offset1:140
	v_add_u32_e32 v0, 0x800, v10
	s_waitcnt lgkmcnt(0)
	v_cvt_pk_bf16_f32 v4, v4, v5
	v_cvt_pk_bf16_f32 v5, v6, v7
	ds_read2_b32 v[6:7], v0 offset0:16 offset1:148
	s_waitcnt lgkmcnt(0)
	v_cvt_pk_bf16_f32 v6, v6, v7
	ds_read_b32 v0, v10 offset:3168
	ds_read_b32 v7, v12
	v_ashrrev_i32_e32 v9, 31, v8
	v_lshl_add_u64 v[2:3], v[8:9], 1, v[2:3]
	s_waitcnt lgkmcnt(0)
	v_cvt_pk_bf16_f32 v7, v0, v7
	global_store_dwordx4 v[2:3], v[4:7], off
	s_branch .LBB0_444

; DI int vbid() { return (int)blockIdx.x * 2 + half_(); }
; DI int vgrid() { return (int)gridDim.x * 2; }
; DI u32x4 pack8(const float* f) { u32x4 o; o.x = pack2(f[0], f[1]); o.y = pack2(f[2], f[3]); o.z = pack2(f[4], f[5]); o.w = pack2(f[6], f[7]); return o; }
; DI void phase_in(PREF p, int l, unsigned char* lds_all) {
;     ...
;   const int gtid = vbid() * 256 + tid, gsz = vgrid() * 256;
;   const float* ps = p.p + (size_t)l * T_ * 256;
;   for (int idx = gtid; idx < T_ * 256 / 8; idx += gsz) {
;     const float4* s = (const float4*)(ps + (size_t)idx * 8);
;     float4 a = s[0], b = s[1];
;     float v[8] = {a.x, a.y, a.z, a.w, b.x, b.y, b.z, b.w};
;     *(u32x4*)(p.pb + (size_t)idx * 8) = pack8(v);
;   }
.LBB0_485:
	global_load_dwordx4 v[8:11], v[6:7], off offset:-28
	global_load_dwordx4 v[12:15], v[6:7], off offset:-12
	v_add_u32_e32 v2, s64, v2
	s_mov_b32 s0, 0xfffff
	v_cmp_lt_i32_e32 vcc, s0, v2
	v_lshl_add_u64 v[6:7], v[6:7], 0, s[16:17]
	s_or_b64 s[10:11], vcc, s[10:11]
	s_waitcnt vmcnt(1)
	v_cvt_pk_bf16_f32 v8, v8, v9
	v_cvt_pk_bf16_f32 v9, v10, v11
	s_waitcnt vmcnt(0)
	v_cvt_pk_bf16_f32 v10, v12, v13
	v_cvt_pk_bf16_f32 v11, v14, v15
	global_store_dwordx4 v[4:5], v[8:11], off
	v_lshl_add_u64 v[4:5], v[4:5], 0, s[14:15]
	s_andn2_b64 exec, exec, s[10:11]
	s_cbranch_execnz .LBB0_485

; DI int tidx() { int t = threadIdx.x & 255; asm volatile("" : "+v"(t)); return t; }
; DI int vbid() { return (int)blockIdx.x * 2 + half_(); }
; DI int vgrid() { return (int)gridDim.x * 2; }
; DI u16 f2bf(float x) { return (u16)(pack2(x, x) & 0xffffu); }
; DI void prep_w(const float* __restrict__ src, int K, int N, u16* __restrict__ dst, int Npad, const float* __restrict__ g, int perm,
;                u16* T) {
;   const int tid = tidx();
;   const int ntn = Npad >> 6, ntiles = (K >> 6) * ntn;
;   for (int it = vbid(); it < ntiles; it += vgrid()) {
;     const int kt = it / ntn, k0 = kt * 64, n0 = (it - kt * ntn) * 64;
;     int sn0 = n0;
;     if (perm) { int tl = n0 >> 7, rr = n0 & 127; sn0 = (rr < 64) ? (tl * 64 + rr) : (256 + tl * 64 + rr - 64); }
;     __syncthreads();
;     {
;       const int nn = tid & 63, kq = tid >> 6;
;       const bool valid = (n0 + nn) < N;
;       float v[16];
; #pragma unroll
;       for (int i = 0; i < 16; ++i) v[i] = valid ? src[(size_t)(k0 + kq + 4 * i) * N + sn0 + nn] : 0.f;
;       if (g) {
; #pragma unroll
;         for (int i = 0; i < 16; ++i) v[i] *= g[k0 + kq + 4 * i];
;       }
; #pragma unroll
;       for (int i = 0; i < 16; ++i) T[(kq + 4 * i) * 72 + nn] = f2bf(v[i]);
;     }
;     __syncthreads();
;     {
;       const int nn = tid >> 2, kc = (tid & 3) * 16;
;       unsigned w[8];
; #pragma unroll
;       for (int j = 0; j < 8; ++j) w[j] = (unsigned)T[(kc + 2 * j) * 72 + nn] | ((unsigned)T[(kc + 2 * j + 1) * 72 + nn] << 16);
;       u32x4 o0 = {w[0], w[1], w[2], w[3]}, o1 = {w[4], w[5], w[6], w[7]};
;       u16* d = dst + (size_t)(n0 + nn) * K + k0 + kc;
;       *(u32x4*)d = o0; *(u32x4*)(d + 8) = o1;
;     }
;   }
.LBB0_492:
	s_or_b64 exec, exec, s[56:57]
	s_waitcnt vmcnt(0)
	v_cvt_pk_bf16_f32 v6, v14, v14
	ds_write_b16 v11, v6
	v_cvt_pk_bf16_f32 v6, v12, v12
	ds_write_b16 v11, v6 offset:576
	v_cvt_pk_bf16_f32 v6, v16, v16
	ds_write_b16 v11, v6 offset:1152
	v_cvt_pk_bf16_f32 v6, v15, v15
	ds_write_b16 v11, v6 offset:1728
	v_cvt_pk_bf16_f32 v6, v18, v18
	ds_write_b16 v11, v6 offset:2304
	v_cvt_pk_bf16_f32 v6, v17, v17
	ds_write_b16 v11, v6 offset:2880
	v_cvt_pk_bf16_f32 v6, v20, v20
	ds_write_b16 v11, v6 offset:3456
	v_cvt_pk_bf16_f32 v6, v19, v19
	ds_write_b16 v11, v6 offset:4032
	v_cvt_pk_bf16_f32 v6, v22, v22
	ds_write_b16 v11, v6 offset:4608
	v_cvt_pk_bf16_f32 v6, v21, v21
	ds_write_b16 v11, v6 offset:5184
	v_cvt_pk_bf16_f32 v6, v24, v24
	ds_write_b16 v11, v6 offset:5760
	v_cvt_pk_bf16_f32 v6, v23, v23
	ds_write_b16 v11, v6 offset:6336
	v_cvt_pk_bf16_f32 v6, v26, v26
	ds_write_b16 v11, v6 offset:6912
	v_cvt_pk_bf16_f32 v6, v25, v25
	ds_write_b16 v11, v6 offset:7488
	v_cvt_pk_bf16_f32 v6, v28, v28
	ds_write_b16 v11, v6 offset:8064
	v_cvt_pk_bf16_f32 v6, v27, v27
	ds_write_b16 v11, v6 offset:8640
	s_waitcnt lgkmcnt(0)
	s_barrier
	ds_read_u16 v6, v10
	ds_read_u16 v7, v10 offset:144
	ds_read_u16 v13, v10 offset:288
	ds_read_u16 v14, v10 offset:432
	ds_read_u16 v15, v10 offset:576
	ds_read_u16 v16, v10 offset:720
	ds_read_u16 v17, v10 offset:864
	ds_read_u16 v18, v10 offset:1008
	s_waitcnt lgkmcnt(6)
	v_lshl_or_b32 v12, v7, 16, v6
	ds_read_u16 v6, v10 offset:1152
	ds_read_u16 v7, v10 offset:1296
	ds_read_u16 v19, v10 offset:1440
	ds_read_u16 v20, v10 offset:1584
	ds_read_u16 v21, v10 offset:1728
	ds_read_u16 v22, v10 offset:1872
	ds_read_u16 v23, v10 offset:2016
	ds_read_u16 v24, v10 offset:2160
	s_waitcnt lgkmcnt(12)
	v_lshl_or_b32 v13, v14, 16, v13
	s_waitcnt lgkmcnt(10)
	v_lshl_or_b32 v14, v16, 16, v15
	s_waitcnt lgkmcnt(6)
	v_lshl_or_b32 v16, v7, 16, v6
	v_add_u32_e32 v6, s48, v9
	v_ashrrev_i32_e32 v7, 31, v6
	v_lshlrev_b64 v[6:7], 11, v[6:7]
	v_lshl_add_u64 v[6:7], s[46:47], 0, v[6:7]
	s_ashr_i32 s9, s8, 31
	v_lshl_add_u64 v[6:7], s[8:9], 1, v[6:7]
	s_add_i32 s52, s52, s71
	s_add_i32 s55, s55, s84
	v_lshl_or_b32 v15, v18, 16, v17
	s_waitcnt lgkmcnt(4)
	v_lshl_or_b32 v17, v20, 16, v19
	s_waitcnt lgkmcnt(2)
	v_lshl_or_b32 v18, v22, 16, v21
	s_waitcnt lgkmcnt(0)
	v_lshl_or_b32 v19, v24, 16, v23
	v_lshl_add_u64 v[6:7], v[6:7], 0, v[0:1]
	s_cmpk_lt_i32 s52, 0x2c0
	global_store_dwordx4 v[6:7], v[12:15], off
	global_store_dwordx4 v[6:7], v[16:19], off offset:16
	s_cbranch_scc0 .LBB0_525

; DI int tidx() { int t = threadIdx.x & 255; asm volatile("" : "+v"(t)); return t; }
; DI int vbid() { return (int)blockIdx.x * 2 + half_(); }
; DI int vgrid() { return (int)gridDim.x * 2; }
; DI u16 f2bf(float x) { return (u16)(pack2(x, x) & 0xffffu); }
; DI void prep_w(const float* __restrict__ src, int K, int N, u16* __restrict__ dst, int Npad, const float* __restrict__ g, int perm,
;                u16* T) {
;   const int tid = tidx();
;   const int ntn = Npad >> 6, ntiles = (K >> 6) * ntn;
;   for (int it = vbid(); it < ntiles; it += vgrid()) {
;     const int kt = it / ntn, k0 = kt * 64, n0 = (it - kt * ntn) * 64;
;     int sn0 = n0;
;     if (perm) { int tl = n0 >> 7, rr = n0 & 127; sn0 = (rr < 64) ? (tl * 64 + rr) : (256 + tl * 64 + rr - 64); }
;     __syncthreads();
;     {
;       const int nn = tid & 63, kq = tid >> 6;
;       const bool valid = (n0 + nn) < N;
;       float v[16];
; #pragma unroll
;       for (int i = 0; i < 16; ++i) v[i] = valid ? src[(size_t)(k0 + kq + 4 * i) * N + sn0 + nn] : 0.f;
;       if (g) {
; #pragma unroll
;         for (int i = 0; i < 16; ++i) v[i] *= g[k0 + kq + 4 * i];
;       }
; #pragma unroll
;       for (int i = 0; i < 16; ++i) T[(kq + 4 * i) * 72 + nn] = f2bf(v[i]);
;     }
;     __syncthreads();
;     {
;       const int nn = tid >> 2, kc = (tid & 3) * 16;
;       unsigned w[8];
; #pragma unroll
;       for (int j = 0; j < 8; ++j) w[j] = (unsigned)T[(kc + 2 * j) * 72 + nn] | ((unsigned)T[(kc + 2 * j + 1) * 72 + nn] << 16);
;       u32x4 o0 = {w[0], w[1], w[2], w[3]}, o1 = {w[4], w[5], w[6], w[7]};
;       u16* d = dst + (size_t)(n0 + nn) * K + k0 + kc;
;       *(u32x4*)d = o0; *(u32x4*)(d + 8) = o1;
;     }
;   }
.LBB0_527:
	s_or_b64 exec, exec, s[56:57]
	s_waitcnt vmcnt(0)
	v_cvt_pk_bf16_f32 v6, v14, v14
	ds_write_b16 v13, v6
	v_cvt_pk_bf16_f32 v6, v15, v15
	ds_write_b16 v13, v6 offset:576
	v_cvt_pk_bf16_f32 v6, v17, v17
	ds_write_b16 v13, v6 offset:1152
	v_cvt_pk_bf16_f32 v6, v16, v16
	ds_write_b16 v13, v6 offset:1728
	v_cvt_pk_bf16_f32 v6, v19, v19
	ds_write_b16 v13, v6 offset:2304
	v_cvt_pk_bf16_f32 v6, v18, v18
	ds_write_b16 v13, v6 offset:2880
	v_cvt_pk_bf16_f32 v6, v21, v21
	ds_write_b16 v13, v6 offset:3456
	v_cvt_pk_bf16_f32 v6, v20, v20
	ds_write_b16 v13, v6 offset:4032
	v_cvt_pk_bf16_f32 v6, v23, v23
	ds_write_b16 v13, v6 offset:4608
	v_cvt_pk_bf16_f32 v6, v22, v22
	ds_write_b16 v13, v6 offset:5184
	v_cvt_pk_bf16_f32 v6, v25, v25
	ds_write_b16 v13, v6 offset:5760
	v_cvt_pk_bf16_f32 v6, v24, v24
	ds_write_b16 v13, v6 offset:6336
	v_cvt_pk_bf16_f32 v6, v27, v27
	ds_write_b16 v13, v6 offset:6912
	v_cvt_pk_bf16_f32 v6, v26, v26
	ds_write_b16 v13, v6 offset:7488
	v_cvt_pk_bf16_f32 v6, v29, v29
	ds_write_b16 v13, v6 offset:8064
	v_cvt_pk_bf16_f32 v6, v28, v28
	ds_write_b16 v13, v6 offset:8640
	s_waitcnt lgkmcnt(0)
	s_barrier
	ds_read_u16 v6, v12
	ds_read_u16 v7, v12 offset:144
	ds_read_u16 v8, v12 offset:288
	ds_read_u16 v9, v12 offset:432
	ds_read_u16 v14, v12 offset:576
	ds_read_u16 v15, v12 offset:720
	ds_read_u16 v16, v12 offset:864
	ds_read_u16 v17, v12 offset:1008
	s_sub_i32 s0, 0, s61
	s_waitcnt lgkmcnt(6)
	v_lshl_or_b32 v6, v7, 16, v6
	s_waitcnt lgkmcnt(4)
	v_lshl_or_b32 v7, v9, 16, v8
	s_waitcnt lgkmcnt(2)
	v_lshl_or_b32 v8, v15, 16, v14
	ds_read_u16 v14, v12 offset:1152
	ds_read_u16 v15, v12 offset:1296
	ds_read_u16 v18, v12 offset:1440
	ds_read_u16 v19, v12 offset:1584
	ds_read_u16 v20, v12 offset:1728
	ds_read_u16 v21, v12 offset:1872
	ds_read_u16 v22, v12 offset:2016
	ds_read_u16 v23, v12 offset:2160
	s_add_i32 s0, s0, s55
	s_waitcnt lgkmcnt(6)
	v_lshl_or_b32 v14, v15, 16, v14
	s_waitcnt lgkmcnt(4)
	v_lshl_or_b32 v15, v19, 16, v18
	v_add_u32_e32 v18, s0, v11
	v_ashrrev_i32_e32 v19, 31, v18
	v_lshlrev_b64 v[18:19], 11, v[18:19]
	v_lshl_add_u64 v[18:19], s[48:49], 0, v[18:19]
	s_ashr_i32 s63, s62, 31
	v_lshl_add_u64 v[18:19], s[62:63], 1, v[18:19]
	s_add_i32 s52, s52, s71
	s_add_i32 s55, s55, s84
	v_lshl_or_b32 v9, v17, 16, v16
	s_waitcnt lgkmcnt(2)
	v_lshl_or_b32 v16, v21, 16, v20
	s_waitcnt lgkmcnt(0)
	v_lshl_or_b32 v17, v23, 16, v22
	v_lshl_add_u64 v[18:19], v[18:19], 0, v[0:1]
	s_cmpk_lt_i32 s52, 0x400
	global_store_dwordx4 v[18:19], v[6:9], off
	global_store_dwordx4 v[18:19], v[14:17], off offset:16
	s_cbranch_scc0 .LBB0_560

; DI u16 f2bf(float x) { return (u16)(pack2(x, x) & 0xffffu); }
; DI void prep_w(const float* __restrict__ src, int K, int N, u16* __restrict__ dst, int Npad, const float* __restrict__ g, int perm,
;                u16* T) {
;     ...
;       for (int i = 0; i < 16; ++i) T[(kq + 4 * i) * 72 + nn] = f2bf(v[i]);
;     }
;     __syncthreads();
;     {
;       const int nn = tid >> 2, kc = (tid & 3) * 16;
;       unsigned w[8];
; #pragma unroll
;       for (int j = 0; j < 8; ++j) w[j] = (unsigned)T[(kc + 2 * j) * 72 + nn] | ((unsigned)T[(kc + 2 * j + 1) * 72 + nn] << 16);
;       u32x4 o0 = {w[0], w[1], w[2], w[3]}, o1 = {w[4], w[5], w[6], w[7]};
;       u16* d = dst + (size_t)(n0 + nn) * K + k0 + kc;
;       *(u32x4*)d = o0; *(u32x4*)(d + 8) = o1;
.LBB0_562:
	s_or_b64 exec, exec, s[56:57]
	s_waitcnt vmcnt(0)
	v_cvt_pk_bf16_f32 v6, v14, v14
	ds_write_b16 v13, v6
	v_cvt_pk_bf16_f32 v6, v15, v15
	ds_write_b16 v13, v6 offset:576
	v_cvt_pk_bf16_f32 v6, v17, v17
	ds_write_b16 v13, v6 offset:1152
	v_cvt_pk_bf16_f32 v6, v16, v16
	ds_write_b16 v13, v6 offset:1728
	v_cvt_pk_bf16_f32 v6, v19, v19
	ds_write_b16 v13, v6 offset:2304
	v_cvt_pk_bf16_f32 v6, v18, v18
	ds_write_b16 v13, v6 offset:2880
	v_cvt_pk_bf16_f32 v6, v21, v21
	ds_write_b16 v13, v6 offset:3456
	v_cvt_pk_bf16_f32 v6, v20, v20
	ds_write_b16 v13, v6 offset:4032
	v_cvt_pk_bf16_f32 v6, v23, v23
	ds_write_b16 v13, v6 offset:4608
	v_cvt_pk_bf16_f32 v6, v22, v22
	ds_write_b16 v13, v6 offset:5184
	v_cvt_pk_bf16_f32 v6, v25, v25
	ds_write_b16 v13, v6 offset:5760
	v_cvt_pk_bf16_f32 v6, v24, v24
	ds_write_b16 v13, v6 offset:6336
	v_cvt_pk_bf16_f32 v6, v27, v27
	ds_write_b16 v13, v6 offset:6912
	v_cvt_pk_bf16_f32 v6, v26, v26
	ds_write_b16 v13, v6 offset:7488
	v_cvt_pk_bf16_f32 v6, v29, v29
	ds_write_b16 v13, v6 offset:8064
	v_cvt_pk_bf16_f32 v6, v28, v28
	ds_write_b16 v13, v6 offset:8640
	s_waitcnt lgkmcnt(0)
	s_barrier
	ds_read_u16 v6, v12
	ds_read_u16 v7, v12 offset:144
	ds_read_u16 v8, v12 offset:288
	ds_read_u16 v9, v12 offset:432
	ds_read_u16 v14, v12 offset:576
	ds_read_u16 v15, v12 offset:720
	ds_read_u16 v16, v12 offset:864
	ds_read_u16 v17, v12 offset:1008
	s_sub_i32 s0, 0, s61
	s_waitcnt lgkmcnt(6)
	v_lshl_or_b32 v6, v7, 16, v6
	s_waitcnt lgkmcnt(4)
	v_lshl_or_b32 v7, v9, 16, v8
	s_waitcnt lgkmcnt(2)
	v_lshl_or_b32 v8, v15, 16, v14
	ds_read_u16 v14, v12 offset:1152
	ds_read_u16 v15, v12 offset:1296
	ds_read_u16 v18, v12 offset:1440
	ds_read_u16 v19, v12 offset:1584
	ds_read_u16 v20, v12 offset:1728
	ds_read_u16 v21, v12 offset:1872
	ds_read_u16 v22, v12 offset:2016
	ds_read_u16 v23, v12 offset:2160
	s_add_i32 s0, s0, s55
	s_waitcnt lgkmcnt(6)
	v_lshl_or_b32 v14, v15, 16, v14
	s_waitcnt lgkmcnt(4)
	v_lshl_or_b32 v15, v19, 16, v18
	v_add_u32_e32 v18, s0, v11
	v_ashrrev_i32_e32 v19, 31, v18
	v_lshlrev_b64 v[18:19], 9, v[18:19]
	v_lshl_add_u64 v[18:19], s[62:63], 0, v[18:19]
	s_ashr_i32 s69, s68, 31
	v_lshl_add_u64 v[18:19], s[68:69], 1, v[18:19]
	s_add_i32 s52, s52, s71
	s_add_i32 s55, s55, s84
	v_lshl_or_b32 v9, v17, 16, v16
	s_waitcnt lgkmcnt(2)
	v_lshl_or_b32 v16, v21, 16, v20
	s_waitcnt lgkmcnt(0)
	v_lshl_or_b32 v17, v23, 16, v22
	v_lshl_add_u64 v[18:19], v[18:19], 0, v[0:1]
	s_cmp_lt_i32 s52, 16
	global_store_dwordx4 v[18:19], v[6:9], off
	global_store_dwordx4 v[18:19], v[14:17], off offset:16
	s_cbranch_scc0 .LBB0_595

; DI u16 f2bf(float x) { return (u16)(pack2(x, x) & 0xffffu); }
; DI void prep_w(const float* __restrict__ src, int K, int N, u16* __restrict__ dst, int Npad, const float* __restrict__ g, int perm,
;                u16* T) {
;     ...
;       for (int i = 0; i < 16; ++i) T[(kq + 4 * i) * 72 + nn] = f2bf(v[i]);
;     }
;     __syncthreads();
;     {
;       const int nn = tid >> 2, kc = (tid & 3) * 16;
;       unsigned w[8];
; #pragma unroll
;       for (int j = 0; j < 8; ++j) w[j] = (unsigned)T[(kc + 2 * j) * 72 + nn] | ((unsigned)T[(kc + 2 * j + 1) * 72 + nn] << 16);
;       u32x4 o0 = {w[0], w[1], w[2], w[3]}, o1 = {w[4], w[5], w[6], w[7]};
;       u16* d = dst + (size_t)(n0 + nn) * K + k0 + kc;
;       *(u32x4*)d = o0; *(u32x4*)(d + 8) = o1;
.LBB0_597:
	s_waitcnt vmcnt(0)
	v_cvt_pk_bf16_f32 v6, v6, v6
	ds_write_b16 v29, v6
	v_cvt_pk_bf16_f32 v6, v7, v7
	ds_write_b16 v29, v6 offset:576
	v_cvt_pk_bf16_f32 v6, v8, v8
	ds_write_b16 v29, v6 offset:1152
	v_cvt_pk_bf16_f32 v6, v9, v9
	ds_write_b16 v29, v6 offset:1728
	v_cvt_pk_bf16_f32 v6, v10, v10
	ds_write_b16 v29, v6 offset:2304
	v_cvt_pk_bf16_f32 v6, v11, v11
	ds_write_b16 v29, v6 offset:2880
	v_cvt_pk_bf16_f32 v6, v12, v12
	ds_write_b16 v29, v6 offset:3456
	v_cvt_pk_bf16_f32 v6, v13, v13
	ds_write_b16 v29, v6 offset:4032
	v_cvt_pk_bf16_f32 v6, v14, v14
	ds_write_b16 v29, v6 offset:4608
	v_cvt_pk_bf16_f32 v6, v15, v15
	ds_write_b16 v29, v6 offset:5184
	v_cvt_pk_bf16_f32 v6, v16, v16
	ds_write_b16 v29, v6 offset:5760
	v_cvt_pk_bf16_f32 v6, v17, v17
	ds_write_b16 v29, v6 offset:6336
	v_cvt_pk_bf16_f32 v6, v20, v20
	ds_write_b16 v29, v6 offset:6912
	v_cvt_pk_bf16_f32 v6, v21, v21
	ds_write_b16 v29, v6 offset:7488
	v_cvt_pk_bf16_f32 v6, v24, v24
	ds_write_b16 v29, v6 offset:8064
	v_cvt_pk_bf16_f32 v6, v25, v25
	ds_write_b16 v29, v6 offset:8640
	s_waitcnt lgkmcnt(0)
	s_barrier
	ds_read_u16 v6, v28
	ds_read_u16 v7, v28 offset:144
	ds_read_u16 v8, v28 offset:288
	ds_read_u16 v9, v28 offset:432
	ds_read_u16 v10, v28 offset:576
	ds_read_u16 v11, v28 offset:720
	ds_read_u16 v12, v28 offset:864
	ds_read_u16 v13, v28 offset:1008
	s_waitcnt lgkmcnt(6)
	v_lshl_or_b32 v6, v7, 16, v6
	s_waitcnt lgkmcnt(4)
	v_lshl_or_b32 v7, v9, 16, v8
	s_waitcnt lgkmcnt(2)
	v_lshl_or_b32 v8, v11, 16, v10
	ds_read_u16 v10, v28 offset:1152
	ds_read_u16 v11, v28 offset:1296
	ds_read_u16 v14, v28 offset:1440
	ds_read_u16 v15, v28 offset:1584
	ds_read_u16 v16, v28 offset:1728
	ds_read_u16 v17, v28 offset:1872
	ds_read_u16 v18, v28 offset:2016
	ds_read_u16 v19, v28 offset:2160
	s_waitcnt lgkmcnt(6)
	v_lshl_or_b32 v10, v11, 16, v10
	s_waitcnt lgkmcnt(4)
	v_lshl_or_b32 v11, v15, 16, v14
	v_add_u32_e32 v14, s56, v27
	v_ashrrev_i32_e32 v15, 31, v14
	v_lshlrev_b64 v[14:15], 9, v[14:15]
	v_lshl_add_u64 v[14:15], s[8:9], 0, v[14:15]
	s_ashr_i32 s69, s68, 31
	v_lshl_add_u64 v[14:15], s[68:69], 1, v[14:15]
	s_add_i32 s55, s55, s71
	s_add_i32 s52, s52, s84
	v_lshl_or_b32 v9, v13, 16, v12
	s_waitcnt lgkmcnt(2)
	v_lshl_or_b32 v12, v17, 16, v16
	s_waitcnt lgkmcnt(0)
	v_lshl_or_b32 v13, v19, 16, v18
	v_lshl_add_u64 v[14:15], v[14:15], 0, v[0:1]
	s_cmp_lt_i32 s55, 24
	global_store_dwordx4 v[14:15], v[6:9], off
	global_store_dwordx4 v[14:15], v[10:13], off offset:16
	s_cbranch_scc0 .LBB0_632

; DI u16 f2bf(float x) { return (u16)(pack2(x, x) & 0xffffu); }
; DI void prep_w(const float* __restrict__ src, int K, int N, u16* __restrict__ dst, int Npad, const float* __restrict__ g, int perm,
;                u16* T) {
;     ...
;       for (int i = 0; i < 16; ++i) T[(kq + 4 * i) * 72 + nn] = f2bf(v[i]);
;     }
;     __syncthreads();
;     {
;       const int nn = tid >> 2, kc = (tid & 3) * 16;
;       unsigned w[8];
; #pragma unroll
;       for (int j = 0; j < 8; ++j) w[j] = (unsigned)T[(kc + 2 * j) * 72 + nn] | ((unsigned)T[(kc + 2 * j + 1) * 72 + nn] << 16);
;       u32x4 o0 = {w[0], w[1], w[2], w[3]}, o1 = {w[4], w[5], w[6], w[7]};
;       u16* d = dst + (size_t)(n0 + nn) * K + k0 + kc;
;       *(u32x4*)d = o0; *(u32x4*)(d + 8) = o1;
.LBB0_634:
	s_waitcnt vmcnt(0)
	v_cvt_pk_bf16_f32 v6, v6, v6
	ds_write_b16 v29, v6
	v_cvt_pk_bf16_f32 v6, v7, v7
	ds_write_b16 v29, v6 offset:576
	v_cvt_pk_bf16_f32 v6, v8, v8
	ds_write_b16 v29, v6 offset:1152
	v_cvt_pk_bf16_f32 v6, v9, v9
	ds_write_b16 v29, v6 offset:1728
	v_cvt_pk_bf16_f32 v6, v10, v10
	ds_write_b16 v29, v6 offset:2304
	v_cvt_pk_bf16_f32 v6, v11, v11
	ds_write_b16 v29, v6 offset:2880
	v_cvt_pk_bf16_f32 v6, v12, v12
	ds_write_b16 v29, v6 offset:3456
	v_cvt_pk_bf16_f32 v6, v13, v13
	ds_write_b16 v29, v6 offset:4032
	v_cvt_pk_bf16_f32 v6, v18, v18
	ds_write_b16 v29, v6 offset:4608
	v_cvt_pk_bf16_f32 v6, v19, v19
	ds_write_b16 v29, v6 offset:5184
	v_cvt_pk_bf16_f32 v6, v20, v20
	ds_write_b16 v29, v6 offset:5760
	v_cvt_pk_bf16_f32 v6, v21, v21
	ds_write_b16 v29, v6 offset:6336
	v_cvt_pk_bf16_f32 v6, v22, v22
	ds_write_b16 v29, v6 offset:6912
	v_cvt_pk_bf16_f32 v6, v23, v23
	ds_write_b16 v29, v6 offset:7488
	v_cvt_pk_bf16_f32 v6, v24, v24
	ds_write_b16 v29, v6 offset:8064
	v_cvt_pk_bf16_f32 v6, v25, v25
	ds_write_b16 v29, v6 offset:8640
	s_waitcnt lgkmcnt(0)
	s_barrier
	ds_read_u16 v6, v28
	ds_read_u16 v7, v28 offset:144
	ds_read_u16 v8, v28 offset:288
	ds_read_u16 v9, v28 offset:432
	ds_read_u16 v10, v28 offset:576
	ds_read_u16 v11, v28 offset:720
	ds_read_u16 v12, v28 offset:864
	ds_read_u16 v13, v28 offset:1008
	s_sub_i32 s0, 0, s49
	s_waitcnt lgkmcnt(6)
	v_lshl_or_b32 v6, v7, 16, v6
	s_waitcnt lgkmcnt(4)
	v_lshl_or_b32 v7, v9, 16, v8
	s_waitcnt lgkmcnt(2)
	v_lshl_or_b32 v8, v11, 16, v10
	ds_read_u16 v10, v28 offset:1152
	ds_read_u16 v11, v28 offset:1296
	ds_read_u16 v14, v28 offset:1440
	ds_read_u16 v15, v28 offset:1584
	ds_read_u16 v16, v28 offset:1728
	ds_read_u16 v17, v28 offset:1872
	ds_read_u16 v18, v28 offset:2016
	ds_read_u16 v19, v28 offset:2160
	s_add_i32 s0, s0, s52
	s_waitcnt lgkmcnt(6)
	v_lshl_or_b32 v10, v11, 16, v10
	s_waitcnt lgkmcnt(4)
	v_lshl_or_b32 v11, v15, 16, v14
	v_add_u32_e32 v14, s0, v27
	v_ashrrev_i32_e32 v15, 31, v14
	v_lshlrev_b64 v[14:15], 8, v[14:15]
	v_lshl_add_u64 v[14:15], s[68:69], 0, v[14:15]
	s_ashr_i32 s49, s48, 31
	v_lshl_add_u64 v[14:15], s[48:49], 1, v[14:15]
	s_add_i32 s64, s64, s71
	s_add_i32 s52, s52, s84
	v_lshl_or_b32 v9, v13, 16, v12
	s_waitcnt lgkmcnt(2)
	v_lshl_or_b32 v12, v17, 16, v16
	s_waitcnt lgkmcnt(0)
	v_lshl_or_b32 v13, v19, 16, v18
	v_lshl_add_u64 v[14:15], v[14:15], 0, v[0:1]
	s_cmp_lt_i32 s64, 16
	global_store_dwordx4 v[14:15], v[6:9], off
	global_store_dwordx4 v[14:15], v[10:13], off offset:16
	s_cbranch_scc0 .LBB0_669

; DI u16 f2bf(float x) { return (u16)(pack2(x, x) & 0xffffu); }
; DI void prep_w(const float* __restrict__ src, int K, int N, u16* __restrict__ dst, int Npad, const float* __restrict__ g, int perm,
;                u16* T) {
;     ...
;       for (int i = 0; i < 16; ++i) T[(kq + 4 * i) * 72 + nn] = f2bf(v[i]);
;     }
;     __syncthreads();
;     {
;       const int nn = tid >> 2, kc = (tid & 3) * 16;
;       unsigned w[8];
; #pragma unroll
;       for (int j = 0; j < 8; ++j) w[j] = (unsigned)T[(kc + 2 * j) * 72 + nn] | ((unsigned)T[(kc + 2 * j + 1) * 72 + nn] << 16);
;       u32x4 o0 = {w[0], w[1], w[2], w[3]}, o1 = {w[4], w[5], w[6], w[7]};
;       u16* d = dst + (size_t)(n0 + nn) * K + k0 + kc;
;       *(u32x4*)d = o0; *(u32x4*)(d + 8) = o1;
.LBB0_671:
	s_or_b64 exec, exec, s[56:57]
	s_waitcnt vmcnt(0)
	v_cvt_pk_bf16_f32 v6, v14, v14
	ds_write_b16 v13, v6
	v_cvt_pk_bf16_f32 v6, v15, v15
	ds_write_b16 v13, v6 offset:576
	v_cvt_pk_bf16_f32 v6, v17, v17
	ds_write_b16 v13, v6 offset:1152
	v_cvt_pk_bf16_f32 v6, v16, v16
	ds_write_b16 v13, v6 offset:1728
	v_cvt_pk_bf16_f32 v6, v19, v19
	ds_write_b16 v13, v6 offset:2304
	v_cvt_pk_bf16_f32 v6, v18, v18
	ds_write_b16 v13, v6 offset:2880
	v_cvt_pk_bf16_f32 v6, v21, v21
	ds_write_b16 v13, v6 offset:3456
	v_cvt_pk_bf16_f32 v6, v20, v20
	ds_write_b16 v13, v6 offset:4032
	v_cvt_pk_bf16_f32 v6, v23, v23
	ds_write_b16 v13, v6 offset:4608
	v_cvt_pk_bf16_f32 v6, v22, v22
	ds_write_b16 v13, v6 offset:5184
	v_cvt_pk_bf16_f32 v6, v25, v25
	ds_write_b16 v13, v6 offset:5760
	v_cvt_pk_bf16_f32 v6, v24, v24
	ds_write_b16 v13, v6 offset:6336
	v_cvt_pk_bf16_f32 v6, v27, v27
	ds_write_b16 v13, v6 offset:6912
	v_cvt_pk_bf16_f32 v6, v26, v26
	ds_write_b16 v13, v6 offset:7488
	v_cvt_pk_bf16_f32 v6, v29, v29
	ds_write_b16 v13, v6 offset:8064
	v_cvt_pk_bf16_f32 v6, v28, v28
	ds_write_b16 v13, v6 offset:8640
	s_waitcnt lgkmcnt(0)
	s_barrier
	ds_read_u16 v6, v12
	ds_read_u16 v7, v12 offset:144
	ds_read_u16 v8, v12 offset:288
	ds_read_u16 v9, v12 offset:432
	ds_read_u16 v14, v12 offset:576
	ds_read_u16 v15, v12 offset:720
	ds_read_u16 v16, v12 offset:864
	ds_read_u16 v17, v12 offset:1008
	s_sub_i32 s0, 0, s61
	s_waitcnt lgkmcnt(6)
	v_lshl_or_b32 v6, v7, 16, v6
	s_waitcnt lgkmcnt(4)
	v_lshl_or_b32 v7, v9, 16, v8
	s_waitcnt lgkmcnt(2)
	v_lshl_or_b32 v8, v15, 16, v14
	ds_read_u16 v14, v12 offset:1152
	ds_read_u16 v15, v12 offset:1296
	ds_read_u16 v18, v12 offset:1440
	ds_read_u16 v19, v12 offset:1584
	ds_read_u16 v20, v12 offset:1728
	ds_read_u16 v21, v12 offset:1872
	ds_read_u16 v22, v12 offset:2016
	ds_read_u16 v23, v12 offset:2160
	s_add_i32 s0, s0, s64
	s_waitcnt lgkmcnt(6)
	v_lshl_or_b32 v14, v15, 16, v14
	s_waitcnt lgkmcnt(4)
	v_lshl_or_b32 v15, v19, 16, v18
	v_add_u32_e32 v18, s0, v11
	v_ashrrev_i32_e32 v19, 31, v18
	v_lshlrev_b64 v[18:19], 9, v[18:19]
	v_lshl_add_u64 v[18:19], s[48:49], 0, v[18:19]
	s_ashr_i32 s63, s62, 31
	v_lshl_add_u64 v[18:19], s[62:63], 1, v[18:19]
	s_add_i32 s52, s52, s71
	s_add_i32 s55, s55, s85
	s_add_i32 s64, s64, s84
	v_lshl_or_b32 v9, v17, 16, v16
	s_waitcnt lgkmcnt(2)
	v_lshl_or_b32 v16, v21, 16, v20
	s_waitcnt lgkmcnt(0)
	v_lshl_or_b32 v17, v23, 16, v22
	v_lshl_add_u64 v[18:19], v[18:19], 0, v[0:1]
	s_cmp_lt_i32 s52, 32
	global_store_dwordx4 v[18:19], v[6:9], off
	global_store_dwordx4 v[18:19], v[14:17], off offset:16
	s_cbranch_scc0 .LBB0_704

; DI u16 f2bf(float x) { return (u16)(pack2(x, x) & 0xffffu); }
; DI void prep_w(const float* __restrict__ src, int K, int N, u16* __restrict__ dst, int Npad, const float* __restrict__ g, int perm,
;                u16* T) {
;     ...
;       for (int i = 0; i < 16; ++i) T[(kq + 4 * i) * 72 + nn] = f2bf(v[i]);
;     }
;     __syncthreads();
;     {
;       const int nn = tid >> 2, kc = (tid & 3) * 16;
;       unsigned w[8];
; #pragma unroll
;       for (int j = 0; j < 8; ++j) w[j] = (unsigned)T[(kc + 2 * j) * 72 + nn] | ((unsigned)T[(kc + 2 * j + 1) * 72 + nn] << 16);
;       u32x4 o0 = {w[0], w[1], w[2], w[3]}, o1 = {w[4], w[5], w[6], w[7]};
;       u16* d = dst + (size_t)(n0 + nn) * K + k0 + kc;
;       *(u32x4*)d = o0; *(u32x4*)(d + 8) = o1;
.LBB0_708:
	s_or_b64 exec, exec, s[56:57]
	s_waitcnt vmcnt(0)
	v_cvt_pk_bf16_f32 v6, v14, v14
	ds_write_b16 v13, v6
	v_cvt_pk_bf16_f32 v6, v15, v15
	ds_write_b16 v13, v6 offset:576
	v_cvt_pk_bf16_f32 v6, v17, v17
	ds_write_b16 v13, v6 offset:1152
	v_cvt_pk_bf16_f32 v6, v16, v16
	ds_write_b16 v13, v6 offset:1728
	v_cvt_pk_bf16_f32 v6, v19, v19
	ds_write_b16 v13, v6 offset:2304
	v_cvt_pk_bf16_f32 v6, v18, v18
	ds_write_b16 v13, v6 offset:2880
	v_cvt_pk_bf16_f32 v6, v21, v21
	ds_write_b16 v13, v6 offset:3456
	v_cvt_pk_bf16_f32 v6, v20, v20
	ds_write_b16 v13, v6 offset:4032
	v_cvt_pk_bf16_f32 v6, v23, v23
	ds_write_b16 v13, v6 offset:4608
	v_cvt_pk_bf16_f32 v6, v22, v22
	ds_write_b16 v13, v6 offset:5184
	v_cvt_pk_bf16_f32 v6, v25, v25
	ds_write_b16 v13, v6 offset:5760
	v_cvt_pk_bf16_f32 v6, v24, v24
	ds_write_b16 v13, v6 offset:6336
	v_cvt_pk_bf16_f32 v6, v27, v27
	ds_write_b16 v13, v6 offset:6912
	v_cvt_pk_bf16_f32 v6, v26, v26
	ds_write_b16 v13, v6 offset:7488
	v_cvt_pk_bf16_f32 v6, v29, v29
	ds_write_b16 v13, v6 offset:8064
	v_cvt_pk_bf16_f32 v6, v28, v28
	ds_write_b16 v13, v6 offset:8640
	s_waitcnt lgkmcnt(0)
	s_barrier
	ds_read_u16 v6, v12
	ds_read_u16 v7, v12 offset:144
	ds_read_u16 v8, v12 offset:288
	ds_read_u16 v9, v12 offset:432
	ds_read_u16 v14, v12 offset:576
	ds_read_u16 v15, v12 offset:720
	ds_read_u16 v16, v12 offset:864
	ds_read_u16 v17, v12 offset:1008
	s_sub_i32 s0, 0, s63
	s_waitcnt lgkmcnt(6)
	v_lshl_or_b32 v6, v7, 16, v6
	s_waitcnt lgkmcnt(4)
	v_lshl_or_b32 v7, v9, 16, v8
	s_waitcnt lgkmcnt(2)
	v_lshl_or_b32 v8, v15, 16, v14
	ds_read_u16 v14, v12 offset:1152
	ds_read_u16 v15, v12 offset:1296
	ds_read_u16 v18, v12 offset:1440
	ds_read_u16 v19, v12 offset:1584
	ds_read_u16 v20, v12 offset:1728
	ds_read_u16 v21, v12 offset:1872
	ds_read_u16 v22, v12 offset:2016
	ds_read_u16 v23, v12 offset:2160
	s_add_i32 s0, s0, s61
	s_waitcnt lgkmcnt(6)
	v_lshl_or_b32 v14, v15, 16, v14
	s_waitcnt lgkmcnt(4)
	v_lshl_or_b32 v15, v19, 16, v18
	v_add_u32_e32 v18, s0, v11
	v_ashrrev_i32_e32 v19, 31, v18
	v_lshlrev_b64 v[18:19], 9, v[18:19]
	v_lshl_add_u64 v[18:19], s[48:49], 0, v[18:19]
	s_ashr_i32 s63, s62, 31
	v_lshl_add_u64 v[18:19], s[62:63], 1, v[18:19]
	s_add_i32 s55, s55, s71
	s_add_i32 s61, s61, s84
	v_lshl_or_b32 v9, v17, 16, v16
	s_waitcnt lgkmcnt(2)
	v_lshl_or_b32 v16, v21, 16, v20
	s_waitcnt lgkmcnt(0)
	v_lshl_or_b32 v17, v23, 16, v22
	v_lshl_add_u64 v[18:19], v[18:19], 0, v[0:1]
	s_cmp_lt_i32 s55, 64
	global_store_dwordx4 v[18:19], v[6:9], off
	global_store_dwordx4 v[18:19], v[14:17], off offset:16
	s_cbranch_scc0 .LBB0_705

; DI u16 f2bf(float x) { return (u16)(pack2(x, x) & 0xffffu); }
; DI void prep_w(const float* __restrict__ src, int K, int N, u16* __restrict__ dst, int Npad, const float* __restrict__ g, int perm,
;                u16* T) {
;     ...
;       for (int i = 0; i < 16; ++i) T[(kq + 4 * i) * 72 + nn] = f2bf(v[i]);
;     }
;     __syncthreads();
;     {
;       const int nn = tid >> 2, kc = (tid & 3) * 16;
;       unsigned w[8];
; #pragma unroll
;       for (int j = 0; j < 8; ++j) w[j] = (unsigned)T[(kc + 2 * j) * 72 + nn] | ((unsigned)T[(kc + 2 * j + 1) * 72 + nn] << 16);
;       u32x4 o0 = {w[0], w[1], w[2], w[3]}, o1 = {w[4], w[5], w[6], w[7]};
;       u16* d = dst + (size_t)(n0 + nn) * K + k0 + kc;
;       *(u32x4*)d = o0; *(u32x4*)(d + 8) = o1;
.LBB0_743:
	s_or_b64 exec, exec, s[56:57]
	s_waitcnt vmcnt(0)
	v_cvt_pk_bf16_f32 v6, v14, v14
	ds_write_b16 v13, v6
	v_cvt_pk_bf16_f32 v6, v15, v15
	ds_write_b16 v13, v6 offset:576
	v_cvt_pk_bf16_f32 v6, v17, v17
	ds_write_b16 v13, v6 offset:1152
	v_cvt_pk_bf16_f32 v6, v16, v16
	ds_write_b16 v13, v6 offset:1728
	v_cvt_pk_bf16_f32 v6, v19, v19
	ds_write_b16 v13, v6 offset:2304
	v_cvt_pk_bf16_f32 v6, v18, v18
	ds_write_b16 v13, v6 offset:2880
	v_cvt_pk_bf16_f32 v6, v21, v21
	ds_write_b16 v13, v6 offset:3456
	v_cvt_pk_bf16_f32 v6, v20, v20
	ds_write_b16 v13, v6 offset:4032
	v_cvt_pk_bf16_f32 v6, v23, v23
	ds_write_b16 v13, v6 offset:4608
	v_cvt_pk_bf16_f32 v6, v22, v22
	ds_write_b16 v13, v6 offset:5184
	v_cvt_pk_bf16_f32 v6, v25, v25
	ds_write_b16 v13, v6 offset:5760
	v_cvt_pk_bf16_f32 v6, v24, v24
	ds_write_b16 v13, v6 offset:6336
	v_cvt_pk_bf16_f32 v6, v27, v27
	ds_write_b16 v13, v6 offset:6912
	v_cvt_pk_bf16_f32 v6, v26, v26
	ds_write_b16 v13, v6 offset:7488
	v_cvt_pk_bf16_f32 v6, v29, v29
	ds_write_b16 v13, v6 offset:8064
	v_cvt_pk_bf16_f32 v6, v28, v28
	ds_write_b16 v13, v6 offset:8640
	s_waitcnt lgkmcnt(0)
	s_barrier
	ds_read_u16 v6, v12
	ds_read_u16 v7, v12 offset:144
	ds_read_u16 v8, v12 offset:288
	ds_read_u16 v9, v12 offset:432
	ds_read_u16 v14, v12 offset:576
	ds_read_u16 v15, v12 offset:720
	ds_read_u16 v16, v12 offset:864
	ds_read_u16 v17, v12 offset:1008
	s_sub_i32 s0, 0, s55
	s_waitcnt lgkmcnt(6)
	v_lshl_or_b32 v6, v7, 16, v6
	s_waitcnt lgkmcnt(4)
	v_lshl_or_b32 v7, v9, 16, v8
	s_waitcnt lgkmcnt(2)
	v_lshl_or_b32 v8, v15, 16, v14
	ds_read_u16 v14, v12 offset:1152
	ds_read_u16 v15, v12 offset:1296
	ds_read_u16 v18, v12 offset:1440
	ds_read_u16 v19, v12 offset:1584
	ds_read_u16 v20, v12 offset:1728
	ds_read_u16 v21, v12 offset:1872
	ds_read_u16 v22, v12 offset:2016
	ds_read_u16 v23, v12 offset:2160
	s_add_i32 s0, s0, s52
	s_waitcnt lgkmcnt(6)
	v_lshl_or_b32 v14, v15, 16, v14
	s_waitcnt lgkmcnt(4)
	v_lshl_or_b32 v15, v19, 16, v18
	v_add_u32_e32 v18, s0, v11
	v_ashrrev_i32_e32 v19, 31, v18
	v_lshlrev_b64 v[18:19], 11, v[18:19]
	v_lshl_add_u64 v[18:19], s[62:63], 0, v[18:19]
	s_ashr_i32 s69, s68, 31
	v_lshl_add_u64 v[18:19], s[68:69], 1, v[18:19]
	s_add_i32 s45, s45, s71
	s_add_i32 s52, s52, s84
	v_lshl_or_b32 v9, v17, 16, v16
	s_waitcnt lgkmcnt(2)
	v_lshl_or_b32 v16, v21, 16, v20
	s_waitcnt lgkmcnt(0)
	v_lshl_or_b32 v17, v23, 16, v22
	v_lshl_add_u64 v[18:19], v[18:19], 0, v[0:1]
	s_cmpk_lt_i32 s45, 0x100
	global_store_dwordx4 v[18:19], v[6:9], off
	global_store_dwordx4 v[18:19], v[14:17], off offset:16
	s_cbranch_scc0 .LBB0_776

; DI u16 f2bf(float x) { return (u16)(pack2(x, x) & 0xffffu); }
; DI void prep_w(const float* __restrict__ src, int K, int N, u16* __restrict__ dst, int Npad, const float* __restrict__ g, int perm,
;                u16* T) {
;     ...
;       for (int i = 0; i < 16; ++i) T[(kq + 4 * i) * 72 + nn] = f2bf(v[i]);
;     }
;     __syncthreads();
;     {
;       const int nn = tid >> 2, kc = (tid & 3) * 16;
;       unsigned w[8];
; #pragma unroll
;       for (int j = 0; j < 8; ++j) w[j] = (unsigned)T[(kc + 2 * j) * 72 + nn] | ((unsigned)T[(kc + 2 * j + 1) * 72 + nn] << 16);
;       u32x4 o0 = {w[0], w[1], w[2], w[3]}, o1 = {w[4], w[5], w[6], w[7]};
;       u16* d = dst + (size_t)(n0 + nn) * K + k0 + kc;
;       *(u32x4*)d = o0; *(u32x4*)(d + 8) = o1;
.LBB0_778:
	s_or_b64 exec, exec, s[56:57]
	s_waitcnt vmcnt(0)
	v_cvt_pk_bf16_f32 v6, v14, v14
	ds_write_b16 v13, v6
	v_cvt_pk_bf16_f32 v6, v15, v15
	ds_write_b16 v13, v6 offset:576
	v_cvt_pk_bf16_f32 v6, v17, v17
	ds_write_b16 v13, v6 offset:1152
	v_cvt_pk_bf16_f32 v6, v16, v16
	ds_write_b16 v13, v6 offset:1728
	v_cvt_pk_bf16_f32 v6, v19, v19
	ds_write_b16 v13, v6 offset:2304
	v_cvt_pk_bf16_f32 v6, v18, v18
	ds_write_b16 v13, v6 offset:2880
	v_cvt_pk_bf16_f32 v6, v21, v21
	ds_write_b16 v13, v6 offset:3456
	v_cvt_pk_bf16_f32 v6, v20, v20
	ds_write_b16 v13, v6 offset:4032
	v_cvt_pk_bf16_f32 v6, v23, v23
	ds_write_b16 v13, v6 offset:4608
	v_cvt_pk_bf16_f32 v6, v22, v22
	ds_write_b16 v13, v6 offset:5184
	v_cvt_pk_bf16_f32 v6, v25, v25
	ds_write_b16 v13, v6 offset:5760
	v_cvt_pk_bf16_f32 v6, v24, v24
	ds_write_b16 v13, v6 offset:6336
	v_cvt_pk_bf16_f32 v6, v27, v27
	ds_write_b16 v13, v6 offset:6912
	v_cvt_pk_bf16_f32 v6, v26, v26
	ds_write_b16 v13, v6 offset:7488
	v_cvt_pk_bf16_f32 v6, v29, v29
	ds_write_b16 v13, v6 offset:8064
	v_cvt_pk_bf16_f32 v6, v28, v28
	ds_write_b16 v13, v6 offset:8640
	s_waitcnt lgkmcnt(0)
	s_barrier
	ds_read_u16 v6, v12
	ds_read_u16 v7, v12 offset:144
	ds_read_u16 v8, v12 offset:288
	ds_read_u16 v9, v12 offset:432
	ds_read_u16 v14, v12 offset:576
	ds_read_u16 v15, v12 offset:720
	ds_read_u16 v16, v12 offset:864
	ds_read_u16 v17, v12 offset:1008
	s_sub_i32 s0, 0, s55
	s_waitcnt lgkmcnt(6)
	v_lshl_or_b32 v6, v7, 16, v6
	s_waitcnt lgkmcnt(4)
	v_lshl_or_b32 v7, v9, 16, v8
	s_waitcnt lgkmcnt(2)
	v_lshl_or_b32 v8, v15, 16, v14
	ds_read_u16 v14, v12 offset:1152
	ds_read_u16 v15, v12 offset:1296
	ds_read_u16 v18, v12 offset:1440
	ds_read_u16 v19, v12 offset:1584
	ds_read_u16 v20, v12 offset:1728
	ds_read_u16 v21, v12 offset:1872
	ds_read_u16 v22, v12 offset:2016
	ds_read_u16 v23, v12 offset:2160
	s_add_i32 s0, s0, s52
	s_waitcnt lgkmcnt(6)
	v_lshl_or_b32 v14, v15, 16, v14
	s_waitcnt lgkmcnt(4)
	v_lshl_or_b32 v15, v19, 16, v18
	v_add_u32_e32 v18, s0, v11
	v_ashrrev_i32_e32 v19, 31, v18
	v_lshlrev_b64 v[18:19], 9, v[18:19]
	v_lshl_add_u64 v[18:19], s[62:63], 0, v[18:19]
	s_ashr_i32 s69, s68, 31
	v_lshl_add_u64 v[18:19], s[68:69], 1, v[18:19]
	s_add_i32 s45, s45, s71
	s_add_i32 s52, s52, s84
	v_lshl_or_b32 v9, v17, 16, v16
	s_waitcnt lgkmcnt(2)
	v_lshl_or_b32 v16, v21, 16, v20
	s_waitcnt lgkmcnt(0)
	v_lshl_or_b32 v17, v23, 16, v22
	v_lshl_add_u64 v[18:19], v[18:19], 0, v[0:1]
	s_cmp_lt_i32 s45, 64
	global_store_dwordx4 v[18:19], v[6:9], off
	global_store_dwordx4 v[18:19], v[14:17], off offset:16
	s_cbranch_scc0 .LBB0_811

; DI u16 f2bf(float x) { return (u16)(pack2(x, x) & 0xffffu); }
; DI void prep_w(const float* __restrict__ src, int K, int N, u16* __restrict__ dst, int Npad, const float* __restrict__ g, int perm,
;                u16* T) {
;     ...
;       for (int i = 0; i < 16; ++i) T[(kq + 4 * i) * 72 + nn] = f2bf(v[i]);
;     }
;     __syncthreads();
;     {
;       const int nn = tid >> 2, kc = (tid & 3) * 16;
;       unsigned w[8];
; #pragma unroll
;       for (int j = 0; j < 8; ++j) w[j] = (unsigned)T[(kc + 2 * j) * 72 + nn] | ((unsigned)T[(kc + 2 * j + 1) * 72 + nn] << 16);
;       u32x4 o0 = {w[0], w[1], w[2], w[3]}, o1 = {w[4], w[5], w[6], w[7]};
;       u16* d = dst + (size_t)(n0 + nn) * K + k0 + kc;
;       *(u32x4*)d = o0; *(u32x4*)(d + 8) = o1;
.LBB0_813:
	s_or_b64 exec, exec, s[56:57]
	s_waitcnt vmcnt(0)
	v_cvt_pk_bf16_f32 v6, v14, v14
	ds_write_b16 v13, v6
	v_cvt_pk_bf16_f32 v6, v15, v15
	ds_write_b16 v13, v6 offset:576
	v_cvt_pk_bf16_f32 v6, v17, v17
	ds_write_b16 v13, v6 offset:1152
	v_cvt_pk_bf16_f32 v6, v16, v16
	ds_write_b16 v13, v6 offset:1728
	v_cvt_pk_bf16_f32 v6, v19, v19
	ds_write_b16 v13, v6 offset:2304
	v_cvt_pk_bf16_f32 v6, v18, v18
	ds_write_b16 v13, v6 offset:2880
	v_cvt_pk_bf16_f32 v6, v21, v21
	ds_write_b16 v13, v6 offset:3456
	v_cvt_pk_bf16_f32 v6, v20, v20
	ds_write_b16 v13, v6 offset:4032
	v_cvt_pk_bf16_f32 v6, v23, v23
	ds_write_b16 v13, v6 offset:4608
	v_cvt_pk_bf16_f32 v6, v22, v22
	ds_write_b16 v13, v6 offset:5184
	v_cvt_pk_bf16_f32 v6, v25, v25
	ds_write_b16 v13, v6 offset:5760
	v_cvt_pk_bf16_f32 v6, v24, v24
	ds_write_b16 v13, v6 offset:6336
	v_cvt_pk_bf16_f32 v6, v27, v27
	ds_write_b16 v13, v6 offset:6912
	v_cvt_pk_bf16_f32 v6, v26, v26
	ds_write_b16 v13, v6 offset:7488
	v_cvt_pk_bf16_f32 v6, v29, v29
	ds_write_b16 v13, v6 offset:8064
	v_cvt_pk_bf16_f32 v6, v28, v28
	ds_write_b16 v13, v6 offset:8640
	s_waitcnt lgkmcnt(0)
	s_barrier
	ds_read_u16 v6, v12
	ds_read_u16 v7, v12 offset:144
	ds_read_u16 v8, v12 offset:288
	ds_read_u16 v9, v12 offset:432
	ds_read_u16 v14, v12 offset:576
	ds_read_u16 v15, v12 offset:720
	ds_read_u16 v16, v12 offset:864
	ds_read_u16 v17, v12 offset:1008
	s_sub_i32 s0, 0, s49
	s_waitcnt lgkmcnt(6)
	v_lshl_or_b32 v6, v7, 16, v6
	s_waitcnt lgkmcnt(4)
	v_lshl_or_b32 v7, v9, 16, v8
	s_waitcnt lgkmcnt(2)
	v_lshl_or_b32 v8, v15, 16, v14
	ds_read_u16 v14, v12 offset:1152
	ds_read_u16 v15, v12 offset:1296
	ds_read_u16 v18, v12 offset:1440
	ds_read_u16 v19, v12 offset:1584
	ds_read_u16 v20, v12 offset:1728
	ds_read_u16 v21, v12 offset:1872
	ds_read_u16 v22, v12 offset:2016
	ds_read_u16 v23, v12 offset:2160
	s_add_i32 s0, s0, s52
	s_waitcnt lgkmcnt(6)
	v_lshl_or_b32 v14, v15, 16, v14
	s_waitcnt lgkmcnt(4)
	v_lshl_or_b32 v15, v19, 16, v18
	v_add_u32_e32 v18, s0, v11
	v_ashrrev_i32_e32 v19, 31, v18
	v_lshlrev_b64 v[18:19], 11, v[18:19]
	v_lshl_add_u64 v[18:19], s[46:47], 0, v[18:19]
	s_ashr_i32 s49, s48, 31
	v_lshl_add_u64 v[18:19], s[48:49], 1, v[18:19]
	s_add_i32 s45, s45, s71
	s_add_i32 s52, s52, s84
	v_lshl_or_b32 v9, v17, 16, v16
	s_waitcnt lgkmcnt(2)
	v_lshl_or_b32 v16, v21, 16, v20
	s_waitcnt lgkmcnt(0)
	v_lshl_or_b32 v17, v23, 16, v22
	v_lshl_add_u64 v[18:19], v[18:19], 0, v[0:1]
	s_cmpk_lt_i32 s45, 0x100
	global_store_dwordx4 v[18:19], v[6:9], off
	global_store_dwordx4 v[18:19], v[14:17], off offset:16
	s_cbranch_scc0 .LBB0_489

; DI u32x4 pack8(const float* f) { u32x4 o; o.x = pack2(f[0], f[1]); o.y = pack2(f[2], f[3]); o.z = pack2(f[4], f[5]); o.w = pack2(f[6], f[7]); return o; }
; DI void phase_prep(PREF p, unsigned char* ldsb) {
;     ...
;   for (int idx = gtid; idx < T_ * D_ / 8; idx += gsz) {
;     const float4* s = (const float4*)(p.x + (size_t)idx * 8);
;     float4 a = s[0], b = s[1];
;     float v[8] = {a.x, a.y, a.z, a.w, b.x, b.y, b.z, b.w};
;     *(u32x4*)(p.X + (size_t)idx * 8) = pack8(v);
;   }
.LBB0_870:
	global_load_dwordx4 v[6:9], v[4:5], off offset:-28
	global_load_dwordx4 v[10:13], v[4:5], off offset:-12
	v_add_u32_e32 v18, s64, v18
	v_lshl_add_u64 v[4:5], v[4:5], 0, s[10:11]
	s_mov_b32 s10, 0x3fffff
	v_cmp_lt_i32_e32 vcc, s10, v18
	v_readlane_b32 s10, v254, 26
	v_readlane_b32 s11, v254, 27
	s_or_b64 s[0:1], vcc, s[0:1]
	s_waitcnt vmcnt(1)
	v_cvt_pk_bf16_f32 v6, v6, v7
	v_cvt_pk_bf16_f32 v7, v8, v9
	s_waitcnt vmcnt(0)
	v_cvt_pk_bf16_f32 v8, v10, v11
	v_cvt_pk_bf16_f32 v9, v12, v13
	global_store_dwordx4 v[2:3], v[6:9], off
	v_lshl_add_u64 v[2:3], v[2:3], 0, s[10:11]
	v_readlane_b32 s10, v254, 28
	v_readlane_b32 s11, v254, 29
	s_andn2_b64 exec, exec, s[0:1]
	s_cbranch_execnz .LBB0_870
	s_getpc_b64 s[98:99]
